# SSD scan: X^T row fragments preloaded into registers per chunk (no per-MFMA global loads), state update regenerated with pipelined LDS reads, cvt wrapper nops trimmed
# speedup vs baseline: 1.0377x; 1.0377x over previous
; __device__ __forceinline__ unsigned cvt_pk_bf16(float lo, float hi) { unsigned r; asm volatile("s_nop 0\n\tv_cvt_pk_bf16_f32 %0, %1, %2\n\ts_nop 1" : "=v"(r) : "v"(lo), "v"(hi)); return r; }
; #define LAS __attribute__((address_space(3)))
; #define LDS_FENCE() asm volatile("s_waitcnt lgkmcnt(0)" ::: "memory")
; __device__ __forceinline__ void tr_item(const float* W, int ldw, int col0, const float* kscale, bf16_t* WT, int K, int row0, LAS float* scr, int item, int nblk, int lane) {
;     const int kb = item / nblk, nb = item % nblk, k0 = 64 * kb, n0 = 32 * nb;
; #pragma unroll 8
;     for (int i = 0; i < 32; ++i) { const int kk = 2 * i + (lane >> 5); float v = W[(size_t)(k0 + kk) * ldw + col0 + n0 + (lane & 31)]; if (kscale) v *= kscale[k0 + kk]; scr[kk * 33 + (lane & 31)] = v; }
;     LDS_FENCE();
;     const int c = lane & 7;
; #pragma unroll
;     for (int j = 0; j < 4; ++j) { const int n = (lane >> 3) + 8 * j; const LAS float* s = scr + (8 * c) * 33 + n;
;         u32x4 o; o.x = cvt_pk_bf16(s[0 * 33], s[1 * 33]); o.y = cvt_pk_bf16(s[2 * 33], s[3 * 33]); o.z = cvt_pk_bf16(s[4 * 33], s[5 * 33]); o.w = cvt_pk_bf16(s[6 * 33], s[7 * 33]);
;         *(u32x4*)(WT + (size_t)(row0 + n0 + n) * K + k0 + 8 * c) = o; }
;     LDS_FENCE();
; }
.LBB0_9:
	s_lshl_b32 s36, s23, 1
	s_lshl_b32 s37, s1, 1
	v_or_b32_e32 v21, s36, v3
	v_or_b32_e32 v22, s37, v16
	s_add_i32 s38, s36, 4
	s_add_i32 s39, s37, 4
	s_add_i32 s40, s36, 8
	s_add_i32 s41, s37, 8
	s_add_i32 s42, s36, 12
	s_add_i32 s43, s37, 12
	s_add_i32 s44, s36, 16
	s_add_i32 s45, s37, 16
	s_add_i32 s46, s36, 20
	s_add_i32 s47, s37, 20
	s_add_i32 s48, s36, 24
	s_add_i32 s49, s37, 24
	s_add_i32 s50, s36, 28
	s_add_i32 s51, s37, 28
	v_mad_i64_i32 v[22:23], s[24:25], v22, s22, v[14:15]
	v_mad_i64_i32 v[24:25], s[24:25], v21, s22, v[14:15]
	v_or_b32_e32 v21, s38, v3
	v_or_b32_e32 v26, s39, v16
	v_or_b32_e32 v32, s40, v3
	v_or_b32_e32 v30, s41, v16
	v_or_b32_e32 v36, s42, v3
	v_or_b32_e32 v34, s43, v16
	v_or_b32_e32 v40, s44, v3
	v_or_b32_e32 v38, s45, v16
	v_or_b32_e32 v44, s46, v3
	v_or_b32_e32 v42, s47, v16
	v_or_b32_e32 v46, s48, v3
	v_or_b32_e32 v48, s49, v16
	v_or_b32_e32 v56, s50, v3
	v_or_b32_e32 v54, s51, v16
	v_mad_i64_i32 v[26:27], s[24:25], v26, s22, v[14:15]
	v_mad_i64_i32 v[28:29], s[24:25], v21, s22, v[14:15]
	v_mad_i64_i32 v[30:31], s[24:25], v30, s22, v[14:15]
	v_mad_i64_i32 v[32:33], s[24:25], v32, s22, v[14:15]
	v_mad_i64_i32 v[34:35], s[24:25], v34, s22, v[14:15]
	v_mad_i64_i32 v[36:37], s[24:25], v36, s22, v[14:15]
	v_mad_i64_i32 v[38:39], s[24:25], v38, s22, v[14:15]
	v_mad_i64_i32 v[40:41], s[24:25], v40, s22, v[14:15]
	v_mad_i64_i32 v[42:43], s[24:25], v42, s22, v[14:15]
	v_mad_i64_i32 v[44:45], s[24:25], v44, s22, v[14:15]
	v_mad_i64_i32 v[50:51], s[24:25], v48, s22, v[14:15]
	v_mad_i64_i32 v[52:53], s[24:25], v46, s22, v[14:15]
	v_mad_i64_i32 v[54:55], s[24:25], v54, s22, v[14:15]
	v_mad_i64_i32 v[56:57], s[24:25], v56, s22, v[14:15]
	global_load_dword v21, v[22:23], off
	global_load_dword v46, v[24:25], off
	global_load_dword v48, v[26:27], off
	global_load_dword v58, v[28:29], off
	global_load_dword v59, v[30:31], off
	global_load_dword v60, v[32:33], off
	global_load_dword v61, v[34:35], off
	global_load_dword v62, v[36:37], off
	global_load_dword v63, v[38:39], off
	global_load_dword v64, v[40:41], off
	global_load_dword v65, v[42:43], off
	global_load_dword v66, v[44:45], off
	global_load_dword v67, v[50:51], off
	global_load_dword v68, v[52:53], off
	global_load_dword v69, v[54:55], off
	global_load_dword v70, v[56:57], off
	v_or_b32_e32 v24, s36, v1
	v_or_b32_e32 v22, s37, v6
	s_add_i32 s1, s1, 16
	s_add_i32 s23, s23, 16
	s_add_i32 s5, s5, -16
	v_mad_u64_u32 v[22:23], s[24:25], v22, s7, v[10:11]
	v_mad_u64_u32 v[24:25], s[24:25], v24, s7, v[10:11]
	v_or_b32_e32 v23, s38, v1
	v_or_b32_e32 v25, s39, v6
	v_or_b32_e32 v32, s40, v1
	v_or_b32_e32 v30, s41, v6
	v_or_b32_e32 v36, s42, v1
	v_or_b32_e32 v34, s43, v6
	v_or_b32_e32 v40, s44, v1
	v_or_b32_e32 v38, s45, v6
	v_or_b32_e32 v44, s46, v1
	v_or_b32_e32 v42, s47, v6
	v_or_b32_e32 v52, s48, v1
	v_or_b32_e32 v50, s49, v6
	v_or_b32_e32 v56, s50, v1
	v_or_b32_e32 v54, s51, v6
	s_cmp_lg_u32 s5, 0
	v_mad_u64_u32 v[26:27], s[24:25], v25, s7, v[10:11]
	v_mad_u64_u32 v[28:29], s[24:25], v23, s7, v[10:11]
	v_mad_u64_u32 v[30:31], s[24:25], v30, s7, v[10:11]
	v_mad_u64_u32 v[32:33], s[24:25], v32, s7, v[10:11]
	v_mad_u64_u32 v[34:35], s[24:25], v34, s7, v[10:11]
	v_mad_u64_u32 v[36:37], s[24:25], v36, s7, v[10:11]
	v_mad_u64_u32 v[38:39], s[24:25], v38, s7, v[10:11]
	v_mad_u64_u32 v[40:41], s[24:25], v40, s7, v[10:11]
	v_mad_u64_u32 v[42:43], s[24:25], v42, s7, v[10:11]
	v_mad_u64_u32 v[44:45], s[24:25], v44, s7, v[10:11]
	v_mad_u64_u32 v[50:51], s[24:25], v50, s7, v[10:11]
	v_mad_u64_u32 v[52:53], s[24:25], v52, s7, v[10:11]
	v_mad_u64_u32 v[54:55], s[24:25], v54, s7, v[10:11]
	v_mad_u64_u32 v[56:57], s[24:25], v56, s7, v[10:11]
	s_waitcnt vmcnt(15)
	ds_write_b32 v22, v21
	s_waitcnt vmcnt(14)
	ds_write_b32 v24, v46
	s_waitcnt vmcnt(13)
	ds_write_b32 v26, v48
	s_waitcnt vmcnt(12)
	ds_write_b32 v28, v58
	s_waitcnt vmcnt(11)
	ds_write_b32 v30, v59
	s_waitcnt vmcnt(10)
	ds_write_b32 v32, v60
	s_waitcnt vmcnt(9)
	ds_write_b32 v34, v61
	s_waitcnt vmcnt(8)
	ds_write_b32 v36, v62
	s_waitcnt vmcnt(7)
	ds_write_b32 v38, v63
	s_waitcnt vmcnt(6)
	ds_write_b32 v40, v64
	s_waitcnt vmcnt(5)
	ds_write_b32 v42, v65
	s_waitcnt vmcnt(4)
	ds_write_b32 v44, v66
	s_waitcnt vmcnt(3)
	ds_write_b32 v50, v67
	s_waitcnt vmcnt(2)
	ds_write_b32 v52, v68
	s_waitcnt vmcnt(1)
	ds_write_b32 v54, v69
	s_waitcnt vmcnt(0)
	ds_write_b32 v56, v70
	s_cbranch_scc1 .LBB0_9
	s_waitcnt lgkmcnt(0)
	v_or_b32_e32 v26, s0, v7
	ds_read2_b32 v[14:15], v11 offset1:33
	s_ashr_i32 s5, s4, 31
	v_ashrrev_i32_e32 v27, 31, v26
	s_waitcnt lgkmcnt(0)
	v_cvt_pk_bf16_f32 v22, v14, v15
	ds_read2_b32 v[14:15], v11 offset0:66 offset1:99
	v_lshl_add_u64 v[28:29], s[4:5], 1, v[12:13]
	v_lshlrev_b64 v[26:27], 11, v[26:27]
	s_waitcnt lgkmcnt(0)
	v_cvt_pk_bf16_f32 v23, v14, v15
	ds_read2_b32 v[14:15], v11 offset0:132 offset1:165
	v_lshl_add_u64 v[26:27], v[28:29], 0, v[26:27]
	s_waitcnt lgkmcnt(0)
	v_cvt_pk_bf16_f32 v24, v14, v15
	ds_read2_b32 v[14:15], v11 offset0:198 offset1:231
	s_waitcnt lgkmcnt(0)
	v_cvt_pk_bf16_f32 v25, v14, v15
	global_store_dwordx4 v[26:27], v[22:25], off
	v_or_b32_e32 v26, s0, v17
	ds_read2_b32 v[14:15], v11 offset0:8 offset1:41
	v_ashrrev_i32_e32 v27, 31, v26
	s_waitcnt lgkmcnt(0)
	v_cvt_pk_bf16_f32 v22, v14, v15
	ds_read2_b32 v[14:15], v11 offset0:74 offset1:107
	v_lshlrev_b64 v[26:27], 11, v[26:27]
	s_waitcnt lgkmcnt(0)
	v_cvt_pk_bf16_f32 v23, v14, v15
	ds_read2_b32 v[14:15], v11 offset0:140 offset1:173
	v_lshl_add_u64 v[26:27], v[28:29], 0, v[26:27]
	s_waitcnt lgkmcnt(0)
	v_cvt_pk_bf16_f32 v24, v14, v15
	ds_read2_b32 v[14:15], v11 offset0:206 offset1:239
	s_waitcnt lgkmcnt(0)
	v_cvt_pk_bf16_f32 v25, v14, v15
	global_store_dwordx4 v[26:27], v[22:25], off
	v_or_b32_e32 v26, s0, v18
	ds_read2_b32 v[14:15], v11 offset0:16 offset1:49
	v_ashrrev_i32_e32 v27, 31, v26
	s_waitcnt lgkmcnt(0)
	v_cvt_pk_bf16_f32 v22, v14, v15
	ds_read2_b32 v[14:15], v11 offset0:82 offset1:115
	v_lshlrev_b64 v[26:27], 11, v[26:27]
	s_waitcnt lgkmcnt(0)
	v_cvt_pk_bf16_f32 v23, v14, v15
	ds_read2_b32 v[14:15], v11 offset0:148 offset1:181
	v_lshl_add_u64 v[26:27], v[28:29], 0, v[26:27]
	s_waitcnt lgkmcnt(0)
	v_cvt_pk_bf16_f32 v24, v14, v15
	ds_read2_b32 v[14:15], v11 offset0:214 offset1:247
	s_waitcnt lgkmcnt(0)
	v_cvt_pk_bf16_f32 v25, v14, v15
	global_store_dwordx4 v[26:27], v[22:25], off
	v_or_b32_e32 v26, s0, v19
	ds_read2_b32 v[14:15], v11 offset0:24 offset1:57
	v_ashrrev_i32_e32 v27, 31, v26
	s_waitcnt lgkmcnt(0)
	v_cvt_pk_bf16_f32 v22, v14, v15
	ds_read2_b32 v[14:15], v11 offset0:90 offset1:123
	v_lshlrev_b64 v[26:27], 11, v[26:27]
	s_waitcnt lgkmcnt(0)
	v_cvt_pk_bf16_f32 v23, v14, v15
	ds_read2_b32 v[14:15], v11 offset0:156 offset1:189
	v_lshl_add_u64 v[26:27], v[28:29], 0, v[26:27]
	s_waitcnt lgkmcnt(0)
	v_cvt_pk_bf16_f32 v24, v14, v15
	ds_read2_b32 v[14:15], v11 offset0:222 offset1:255
	s_waitcnt lgkmcnt(0)
	v_cvt_pk_bf16_f32 v25, v14, v15
	global_store_dwordx4 v[26:27], v[22:25], off
	s_waitcnt lgkmcnt(0)
	s_add_i32 s6, s6, s28
	s_cmpk_lt_i32 s6, 0x600
	s_cbranch_scc1 .LBB0_8

; __device__ __forceinline__ unsigned cvt_pk_bf16(float lo, float hi) { unsigned r; asm volatile("s_nop 0\n\tv_cvt_pk_bf16_f32 %0, %1, %2\n\ts_nop 1" : "=v"(r) : "v"(lo), "v"(hi)); return r; }
; #define LAS __attribute__((address_space(3)))
; #define LDS_FENCE() asm volatile("s_waitcnt lgkmcnt(0)" ::: "memory")
; __device__ __forceinline__ void tr_item(const float* W, int ldw, int col0, const float* kscale, bf16_t* WT, int K, int row0, LAS float* scr, int item, int nblk, int lane) {
;     const int kb = item / nblk, nb = item % nblk, k0 = 64 * kb, n0 = 32 * nb;
; #pragma unroll 8
;     for (int i = 0; i < 32; ++i) { const int kk = 2 * i + (lane >> 5); float v = W[(size_t)(k0 + kk) * ldw + col0 + n0 + (lane & 31)]; if (kscale) v *= kscale[k0 + kk]; scr[kk * 33 + (lane & 31)] = v; }
;     LDS_FENCE();
;     const int c = lane & 7;
; #pragma unroll
;     for (int j = 0; j < 4; ++j) { const int n = (lane >> 3) + 8 * j; const LAS float* s = scr + (8 * c) * 33 + n;
;         u32x4 o; o.x = cvt_pk_bf16(s[0 * 33], s[1 * 33]); o.y = cvt_pk_bf16(s[2 * 33], s[3 * 33]); o.z = cvt_pk_bf16(s[4 * 33], s[5 * 33]); o.w = cvt_pk_bf16(s[6 * 33], s[7 * 33]);
;         *(u32x4*)(WT + (size_t)(row0 + n0 + n) * K + k0 + 8 * c) = o; }
;     LDS_FENCE();
; }
.LBB0_14:
	s_lshl_b32 s36, s23, 1
	s_lshl_b32 s37, s5, 1
	v_or_b32_e32 v22, s37, v8
	s_add_i32 s38, s36, 4
	s_add_i32 s39, s37, 4
	s_add_i32 s40, s36, 8
	s_add_i32 s41, s37, 8
	s_add_i32 s42, s36, 12
	s_add_i32 s43, s37, 12
	s_add_i32 s44, s36, 16
	s_add_i32 s45, s37, 16
	s_add_i32 s46, s36, 20
	s_add_i32 s47, s37, 20
	s_add_i32 s48, s36, 24
	s_add_i32 s49, s37, 24
	s_add_i32 s50, s36, 28
	s_add_i32 s51, s37, 28
	v_or_b32_e32 v24, s36, v3
	v_mad_i64_i32 v[22:23], s[24:25], v22, s22, v[16:17]
	v_or_b32_e32 v28, s38, v3
	v_or_b32_e32 v26, s39, v8
	v_or_b32_e32 v32, s40, v3
	v_or_b32_e32 v30, s41, v8
	v_or_b32_e32 v36, s42, v3
	v_or_b32_e32 v34, s43, v8
	v_or_b32_e32 v40, s44, v3
	v_or_b32_e32 v38, s45, v8
	v_or_b32_e32 v44, s46, v3
	v_or_b32_e32 v42, s47, v8
	v_or_b32_e32 v46, s48, v3
	v_or_b32_e32 v48, s49, v8
	v_or_b32_e32 v56, s50, v3
	v_or_b32_e32 v54, s51, v8
	v_mad_i64_i32 v[24:25], s[24:25], v24, s22, v[16:17]
	v_mad_i64_i32 v[26:27], s[24:25], v26, s22, v[16:17]
	v_mad_i64_i32 v[28:29], s[24:25], v28, s22, v[16:17]
	v_mad_i64_i32 v[30:31], s[24:25], v30, s22, v[16:17]
	v_mad_i64_i32 v[32:33], s[24:25], v32, s22, v[16:17]
	v_mad_i64_i32 v[34:35], s[24:25], v34, s22, v[16:17]
	v_mad_i64_i32 v[36:37], s[24:25], v36, s22, v[16:17]
	v_mad_i64_i32 v[38:39], s[24:25], v38, s22, v[16:17]
	v_mad_i64_i32 v[40:41], s[24:25], v40, s22, v[16:17]
	v_mad_i64_i32 v[42:43], s[24:25], v42, s22, v[16:17]
	v_mad_i64_i32 v[44:45], s[24:25], v44, s22, v[16:17]
	v_mad_i64_i32 v[50:51], s[24:25], v48, s22, v[16:17]
	v_mad_i64_i32 v[52:53], s[24:25], v46, s22, v[16:17]
	v_mad_i64_i32 v[54:55], s[24:25], v54, s22, v[16:17]
	v_mad_i64_i32 v[56:57], s[24:25], v56, s22, v[16:17]
	global_load_dword v46, v[22:23], off
	global_load_dword v48, v[24:25], off
	global_load_dword v58, v[26:27], off
	global_load_dword v59, v[28:29], off
	global_load_dword v60, v[30:31], off
	global_load_dword v61, v[32:33], off
	global_load_dword v62, v[34:35], off
	global_load_dword v63, v[36:37], off
	global_load_dword v64, v[38:39], off
	global_load_dword v65, v[40:41], off
	global_load_dword v66, v[42:43], off
	global_load_dword v67, v[44:45], off
	global_load_dword v68, v[50:51], off
	global_load_dword v69, v[52:53], off
	global_load_dword v70, v[54:55], off
	global_load_dword v71, v[56:57], off
	v_or_b32_e32 v24, s36, v1
	v_or_b32_e32 v22, s37, v6
	s_add_i32 s5, s5, 16
	s_add_i32 s23, s23, 16
	s_add_i32 s1, s1, -16
	v_mad_u64_u32 v[22:23], s[24:25], v22, s7, v[12:13]
	v_mad_u64_u32 v[24:25], s[24:25], v24, s7, v[12:13]
	v_or_b32_e32 v23, s38, v1
	v_or_b32_e32 v25, s39, v6
	v_or_b32_e32 v32, s40, v1
	v_or_b32_e32 v30, s41, v6
	v_or_b32_e32 v36, s42, v1
	v_or_b32_e32 v34, s43, v6
	v_or_b32_e32 v40, s44, v1
	v_or_b32_e32 v38, s45, v6
	v_or_b32_e32 v44, s46, v1
	v_or_b32_e32 v42, s47, v6
	v_or_b32_e32 v52, s48, v1
	v_or_b32_e32 v50, s49, v6
	v_or_b32_e32 v56, s50, v1
	v_or_b32_e32 v54, s51, v6
	s_cmp_lg_u32 s1, 0
	v_mad_u64_u32 v[26:27], s[24:25], v25, s7, v[12:13]
	v_mad_u64_u32 v[28:29], s[24:25], v23, s7, v[12:13]
	v_mad_u64_u32 v[30:31], s[24:25], v30, s7, v[12:13]
	v_mad_u64_u32 v[32:33], s[24:25], v32, s7, v[12:13]
	v_mad_u64_u32 v[34:35], s[24:25], v34, s7, v[12:13]
	v_mad_u64_u32 v[36:37], s[24:25], v36, s7, v[12:13]
	v_mad_u64_u32 v[38:39], s[24:25], v38, s7, v[12:13]
	v_mad_u64_u32 v[40:41], s[24:25], v40, s7, v[12:13]
	v_mad_u64_u32 v[42:43], s[24:25], v42, s7, v[12:13]
	v_mad_u64_u32 v[44:45], s[24:25], v44, s7, v[12:13]
	v_mad_u64_u32 v[50:51], s[24:25], v50, s7, v[12:13]
	v_mad_u64_u32 v[52:53], s[24:25], v52, s7, v[12:13]
	v_mad_u64_u32 v[54:55], s[24:25], v54, s7, v[12:13]
	v_mad_u64_u32 v[56:57], s[24:25], v56, s7, v[12:13]
	s_waitcnt vmcnt(15)
	ds_write_b32 v22, v46
	s_waitcnt vmcnt(14)
	ds_write_b32 v24, v48
	s_waitcnt vmcnt(13)
	ds_write_b32 v26, v58
	s_waitcnt vmcnt(12)
	ds_write_b32 v28, v59
	s_waitcnt vmcnt(11)
	ds_write_b32 v30, v60
	s_waitcnt vmcnt(10)
	ds_write_b32 v32, v61
	s_waitcnt vmcnt(9)
	ds_write_b32 v34, v62
	s_waitcnt vmcnt(8)
	ds_write_b32 v36, v63
	s_waitcnt vmcnt(7)
	ds_write_b32 v38, v64
	s_waitcnt vmcnt(6)
	ds_write_b32 v40, v65
	s_waitcnt vmcnt(5)
	ds_write_b32 v42, v66
	s_waitcnt vmcnt(4)
	ds_write_b32 v44, v67
	s_waitcnt vmcnt(3)
	ds_write_b32 v50, v68
	s_waitcnt vmcnt(2)
	ds_write_b32 v52, v69
	s_waitcnt vmcnt(1)
	ds_write_b32 v54, v70
	s_waitcnt vmcnt(0)
	ds_write_b32 v56, v71
	s_cbranch_scc1 .LBB0_14
	s_waitcnt lgkmcnt(0)
	ds_read2_b32 v[16:17], v13 offset1:33
	s_waitcnt lgkmcnt(0)
	v_cvt_pk_bf16_f32 v22, v16, v17
	ds_read2_b32 v[16:17], v13 offset0:66 offset1:99
	s_addk_i32 s4, 0xc00
	s_waitcnt lgkmcnt(0)
	v_cvt_pk_bf16_f32 v23, v16, v17
	ds_read2_b32 v[16:17], v13 offset0:132 offset1:165
	s_ashr_i32 s1, s0, 31
	v_or_b32_e32 v8, s4, v7
	s_waitcnt lgkmcnt(0)
	v_cvt_pk_bf16_f32 v24, v16, v17
	ds_read2_b32 v[16:17], v13 offset0:198 offset1:231
	v_lshl_add_u64 v[26:27], s[0:1], 1, v[14:15]
	v_lshlrev_b64 v[28:29], 11, v[8:9]
	s_waitcnt lgkmcnt(0)
	v_cvt_pk_bf16_f32 v25, v16, v17
	ds_read2_b32 v[16:17], v13 offset0:8 offset1:41
	v_lshl_add_u64 v[28:29], v[26:27], 0, v[28:29]
	global_store_dwordx4 v[28:29], v[22:25], off
	v_or_b32_e32 v8, s4, v18
	v_lshlrev_b64 v[28:29], 11, v[8:9]
	s_waitcnt lgkmcnt(0)
	v_cvt_pk_bf16_f32 v22, v16, v17
	ds_read2_b32 v[16:17], v13 offset0:74 offset1:107
	s_waitcnt lgkmcnt(0)
	v_cvt_pk_bf16_f32 v23, v16, v17
	ds_read2_b32 v[16:17], v13 offset0:140 offset1:173
	s_waitcnt lgkmcnt(0)
	v_cvt_pk_bf16_f32 v24, v16, v17
	ds_read2_b32 v[16:17], v13 offset0:206 offset1:239
	s_waitcnt lgkmcnt(0)
	v_cvt_pk_bf16_f32 v25, v16, v17
	ds_read2_b32 v[16:17], v13 offset0:16 offset1:49
	v_lshl_add_u64 v[28:29], v[26:27], 0, v[28:29]
	global_store_dwordx4 v[28:29], v[22:25], off
	v_or_b32_e32 v8, s4, v19
	v_lshlrev_b64 v[28:29], 11, v[8:9]
	s_waitcnt lgkmcnt(0)
	v_cvt_pk_bf16_f32 v22, v16, v17
	ds_read2_b32 v[16:17], v13 offset0:82 offset1:115
	s_waitcnt lgkmcnt(0)
	v_cvt_pk_bf16_f32 v23, v16, v17
	ds_read2_b32 v[16:17], v13 offset0:148 offset1:181
	s_waitcnt lgkmcnt(0)
	v_cvt_pk_bf16_f32 v24, v16, v17
	ds_read2_b32 v[16:17], v13 offset0:214 offset1:247
	s_waitcnt lgkmcnt(0)
	v_cvt_pk_bf16_f32 v25, v16, v17
	ds_read2_b32 v[16:17], v13 offset0:24 offset1:57
	v_lshl_add_u64 v[28:29], v[26:27], 0, v[28:29]
	v_or_b32_e32 v8, s4, v21
	global_store_dwordx4 v[28:29], v[22:25], off
	v_lshlrev_b64 v[28:29], 11, v[8:9]
	v_lshl_add_u64 v[26:27], v[26:27], 0, v[28:29]
	s_waitcnt lgkmcnt(0)
	v_cvt_pk_bf16_f32 v22, v16, v17
	ds_read2_b32 v[16:17], v13 offset0:90 offset1:123
	s_waitcnt lgkmcnt(0)
	v_cvt_pk_bf16_f32 v23, v16, v17
	ds_read2_b32 v[16:17], v13 offset0:156 offset1:189
	s_waitcnt lgkmcnt(0)
	v_cvt_pk_bf16_f32 v24, v16, v17
	ds_read2_b32 v[16:17], v13 offset0:222 offset1:255
	s_waitcnt lgkmcnt(0)
	v_cvt_pk_bf16_f32 v25, v16, v17
	global_store_dwordx4 v[26:27], v[22:25], off
	s_waitcnt lgkmcnt(0)
	s_add_i32 s6, s6, s28
	s_cmpk_lt_i32 s6, 0x200
	s_cbranch_scc1 .LBB0_13

; __device__ __forceinline__ unsigned cvt_pk_bf16(float lo, float hi) { unsigned r; asm volatile("s_nop 0\n\tv_cvt_pk_bf16_f32 %0, %1, %2\n\ts_nop 1" : "=v"(r) : "v"(lo), "v"(hi)); return r; }
; #define LAS __attribute__((address_space(3)))
; #define LDS_FENCE() asm volatile("s_waitcnt lgkmcnt(0)" ::: "memory")
; __device__ __forceinline__ void tr_item(const float* W, int ldw, int col0, const float* kscale, bf16_t* WT, int K, int row0, LAS float* scr, int item, int nblk, int lane) {
;     const int kb = item / nblk, nb = item % nblk, k0 = 64 * kb, n0 = 32 * nb;
; #pragma unroll 8
;     for (int i = 0; i < 32; ++i) { const int kk = 2 * i + (lane >> 5); float v = W[(size_t)(k0 + kk) * ldw + col0 + n0 + (lane & 31)]; if (kscale) v *= kscale[k0 + kk]; scr[kk * 33 + (lane & 31)] = v; }
;     LDS_FENCE();
;     const int c = lane & 7;
; #pragma unroll
;     for (int j = 0; j < 4; ++j) { const int n = (lane >> 3) + 8 * j; const LAS float* s = scr + (8 * c) * 33 + n;
;         u32x4 o; o.x = cvt_pk_bf16(s[0 * 33], s[1 * 33]); o.y = cvt_pk_bf16(s[2 * 33], s[3 * 33]); o.z = cvt_pk_bf16(s[4 * 33], s[5 * 33]); o.w = cvt_pk_bf16(s[6 * 33], s[7 * 33]);
;         *(u32x4*)(WT + (size_t)(row0 + n0 + n) * K + k0 + 8 * c) = o; }
;     LDS_FENCE();
; }
.LBB0_19:
	s_lshl_b32 s36, s23, 1
	s_lshl_b32 s37, s5, 1
	v_or_b32_e32 v22, s37, v8
	s_add_i32 s38, s36, 4
	s_add_i32 s39, s37, 4
	s_add_i32 s40, s36, 8
	s_add_i32 s41, s37, 8
	s_add_i32 s42, s36, 12
	s_add_i32 s43, s37, 12
	s_add_i32 s44, s36, 16
	s_add_i32 s45, s37, 16
	s_add_i32 s46, s36, 20
	s_add_i32 s47, s37, 20
	s_add_i32 s48, s36, 24
	s_add_i32 s49, s37, 24
	s_add_i32 s50, s36, 28
	s_add_i32 s51, s37, 28
	v_or_b32_e32 v24, s36, v3
	v_mad_i64_i32 v[22:23], s[24:25], v22, s22, v[16:17]
	v_or_b32_e32 v28, s38, v3
	v_or_b32_e32 v26, s39, v8
	v_or_b32_e32 v32, s40, v3
	v_or_b32_e32 v30, s41, v8
	v_or_b32_e32 v36, s42, v3
	v_or_b32_e32 v34, s43, v8
	v_or_b32_e32 v40, s44, v3
	v_or_b32_e32 v38, s45, v8
	v_or_b32_e32 v44, s46, v3
	v_or_b32_e32 v42, s47, v8
	v_or_b32_e32 v46, s48, v3
	v_or_b32_e32 v48, s49, v8
	v_or_b32_e32 v56, s50, v3
	v_or_b32_e32 v54, s51, v8
	v_mad_i64_i32 v[24:25], s[24:25], v24, s22, v[16:17]
	v_mad_i64_i32 v[26:27], s[24:25], v26, s22, v[16:17]
	v_mad_i64_i32 v[28:29], s[24:25], v28, s22, v[16:17]
	v_mad_i64_i32 v[30:31], s[24:25], v30, s22, v[16:17]
	v_mad_i64_i32 v[32:33], s[24:25], v32, s22, v[16:17]
	v_mad_i64_i32 v[34:35], s[24:25], v34, s22, v[16:17]
	v_mad_i64_i32 v[36:37], s[24:25], v36, s22, v[16:17]
	v_mad_i64_i32 v[38:39], s[24:25], v38, s22, v[16:17]
	v_mad_i64_i32 v[40:41], s[24:25], v40, s22, v[16:17]
	v_mad_i64_i32 v[42:43], s[24:25], v42, s22, v[16:17]
	v_mad_i64_i32 v[44:45], s[24:25], v44, s22, v[16:17]
	v_mad_i64_i32 v[50:51], s[24:25], v48, s22, v[16:17]
	v_mad_i64_i32 v[52:53], s[24:25], v46, s22, v[16:17]
	v_mad_i64_i32 v[54:55], s[24:25], v54, s22, v[16:17]
	v_mad_i64_i32 v[56:57], s[24:25], v56, s22, v[16:17]
	global_load_dword v46, v[22:23], off
	global_load_dword v48, v[24:25], off
	global_load_dword v58, v[26:27], off
	global_load_dword v59, v[28:29], off
	global_load_dword v60, v[30:31], off
	global_load_dword v61, v[32:33], off
	global_load_dword v62, v[34:35], off
	global_load_dword v63, v[36:37], off
	global_load_dword v64, v[38:39], off
	global_load_dword v65, v[40:41], off
	global_load_dword v66, v[42:43], off
	global_load_dword v67, v[44:45], off
	global_load_dword v68, v[50:51], off
	global_load_dword v69, v[52:53], off
	global_load_dword v70, v[54:55], off
	global_load_dword v71, v[56:57], off
	v_or_b32_e32 v24, s36, v1
	v_or_b32_e32 v22, s37, v6
	s_add_i32 s5, s5, 16
	s_add_i32 s23, s23, 16
	s_add_i32 s1, s1, -16
	v_mad_u64_u32 v[22:23], s[24:25], v22, s7, v[12:13]
	v_mad_u64_u32 v[24:25], s[24:25], v24, s7, v[12:13]
	v_or_b32_e32 v23, s38, v1
	v_or_b32_e32 v25, s39, v6
	v_or_b32_e32 v32, s40, v1
	v_or_b32_e32 v30, s41, v6
	v_or_b32_e32 v36, s42, v1
	v_or_b32_e32 v34, s43, v6
	v_or_b32_e32 v40, s44, v1
	v_or_b32_e32 v38, s45, v6
	v_or_b32_e32 v44, s46, v1
	v_or_b32_e32 v42, s47, v6
	v_or_b32_e32 v52, s48, v1
	v_or_b32_e32 v50, s49, v6
	v_or_b32_e32 v56, s50, v1
	v_or_b32_e32 v54, s51, v6
	s_cmp_lg_u32 s1, 0
	v_mad_u64_u32 v[26:27], s[24:25], v25, s7, v[12:13]
	v_mad_u64_u32 v[28:29], s[24:25], v23, s7, v[12:13]
	v_mad_u64_u32 v[30:31], s[24:25], v30, s7, v[12:13]
	v_mad_u64_u32 v[32:33], s[24:25], v32, s7, v[12:13]
	v_mad_u64_u32 v[34:35], s[24:25], v34, s7, v[12:13]
	v_mad_u64_u32 v[36:37], s[24:25], v36, s7, v[12:13]
	v_mad_u64_u32 v[38:39], s[24:25], v38, s7, v[12:13]
	v_mad_u64_u32 v[40:41], s[24:25], v40, s7, v[12:13]
	v_mad_u64_u32 v[42:43], s[24:25], v42, s7, v[12:13]
	v_mad_u64_u32 v[44:45], s[24:25], v44, s7, v[12:13]
	v_mad_u64_u32 v[50:51], s[24:25], v50, s7, v[12:13]
	v_mad_u64_u32 v[52:53], s[24:25], v52, s7, v[12:13]
	v_mad_u64_u32 v[54:55], s[24:25], v54, s7, v[12:13]
	v_mad_u64_u32 v[56:57], s[24:25], v56, s7, v[12:13]
	s_waitcnt vmcnt(15)
	ds_write_b32 v22, v46
	s_waitcnt vmcnt(14)
	ds_write_b32 v24, v48
	s_waitcnt vmcnt(13)
	ds_write_b32 v26, v58
	s_waitcnt vmcnt(12)
	ds_write_b32 v28, v59
	s_waitcnt vmcnt(11)
	ds_write_b32 v30, v60
	s_waitcnt vmcnt(10)
	ds_write_b32 v32, v61
	s_waitcnt vmcnt(9)
	ds_write_b32 v34, v62
	s_waitcnt vmcnt(8)
	ds_write_b32 v36, v63
	s_waitcnt vmcnt(7)
	ds_write_b32 v38, v64
	s_waitcnt vmcnt(6)
	ds_write_b32 v40, v65
	s_waitcnt vmcnt(5)
	ds_write_b32 v42, v66
	s_waitcnt vmcnt(4)
	ds_write_b32 v44, v67
	s_waitcnt vmcnt(3)
	ds_write_b32 v50, v68
	s_waitcnt vmcnt(2)
	ds_write_b32 v52, v69
	s_waitcnt vmcnt(1)
	ds_write_b32 v54, v70
	s_waitcnt vmcnt(0)
	ds_write_b32 v56, v71
	s_cbranch_scc1 .LBB0_19
	s_waitcnt lgkmcnt(0)
	ds_read2_b32 v[16:17], v13 offset1:33
	s_waitcnt lgkmcnt(0)
	v_cvt_pk_bf16_f32 v22, v16, v17
	ds_read2_b32 v[16:17], v13 offset0:66 offset1:99
	s_addk_i32 s4, 0x1000
	s_waitcnt lgkmcnt(0)
	v_cvt_pk_bf16_f32 v23, v16, v17
	ds_read2_b32 v[16:17], v13 offset0:132 offset1:165
	s_ashr_i32 s1, s0, 31
	v_or_b32_e32 v8, s4, v7
	s_waitcnt lgkmcnt(0)
	v_cvt_pk_bf16_f32 v24, v16, v17
	ds_read2_b32 v[16:17], v13 offset0:198 offset1:231
	v_lshl_add_u64 v[26:27], s[0:1], 1, v[14:15]
	v_lshlrev_b64 v[28:29], 11, v[8:9]
	s_waitcnt lgkmcnt(0)
	v_cvt_pk_bf16_f32 v25, v16, v17
	ds_read2_b32 v[16:17], v13 offset0:8 offset1:41
	v_lshl_add_u64 v[28:29], v[26:27], 0, v[28:29]
	global_store_dwordx4 v[28:29], v[22:25], off
	v_or_b32_e32 v8, s4, v18
	v_lshlrev_b64 v[28:29], 11, v[8:9]
	s_waitcnt lgkmcnt(0)
	v_cvt_pk_bf16_f32 v22, v16, v17
	ds_read2_b32 v[16:17], v13 offset0:74 offset1:107
	s_waitcnt lgkmcnt(0)
	v_cvt_pk_bf16_f32 v23, v16, v17
	ds_read2_b32 v[16:17], v13 offset0:140 offset1:173
	s_waitcnt lgkmcnt(0)
	v_cvt_pk_bf16_f32 v24, v16, v17
	ds_read2_b32 v[16:17], v13 offset0:206 offset1:239
	s_waitcnt lgkmcnt(0)
	v_cvt_pk_bf16_f32 v25, v16, v17
	ds_read2_b32 v[16:17], v13 offset0:16 offset1:49
	v_lshl_add_u64 v[28:29], v[26:27], 0, v[28:29]
	global_store_dwordx4 v[28:29], v[22:25], off
	v_or_b32_e32 v8, s4, v19
	v_lshlrev_b64 v[28:29], 11, v[8:9]
	s_waitcnt lgkmcnt(0)
	v_cvt_pk_bf16_f32 v22, v16, v17
	ds_read2_b32 v[16:17], v13 offset0:82 offset1:115
	s_waitcnt lgkmcnt(0)
	v_cvt_pk_bf16_f32 v23, v16, v17
	ds_read2_b32 v[16:17], v13 offset0:148 offset1:181
	s_waitcnt lgkmcnt(0)
	v_cvt_pk_bf16_f32 v24, v16, v17
	ds_read2_b32 v[16:17], v13 offset0:214 offset1:247
	s_waitcnt lgkmcnt(0)
	v_cvt_pk_bf16_f32 v25, v16, v17
	ds_read2_b32 v[16:17], v13 offset0:24 offset1:57
	v_lshl_add_u64 v[28:29], v[26:27], 0, v[28:29]
	v_or_b32_e32 v8, s4, v21
	global_store_dwordx4 v[28:29], v[22:25], off
	v_lshlrev_b64 v[28:29], 11, v[8:9]
	v_lshl_add_u64 v[26:27], v[26:27], 0, v[28:29]
	s_waitcnt lgkmcnt(0)
	v_cvt_pk_bf16_f32 v22, v16, v17
	ds_read2_b32 v[16:17], v13 offset0:90 offset1:123
	s_waitcnt lgkmcnt(0)
	v_cvt_pk_bf16_f32 v23, v16, v17
	ds_read2_b32 v[16:17], v13 offset0:156 offset1:189
	s_waitcnt lgkmcnt(0)
	v_cvt_pk_bf16_f32 v24, v16, v17
	ds_read2_b32 v[16:17], v13 offset0:222 offset1:255
	s_waitcnt lgkmcnt(0)
	v_cvt_pk_bf16_f32 v25, v16, v17
	global_store_dwordx4 v[26:27], v[22:25], off
	s_waitcnt lgkmcnt(0)
	s_add_i32 s6, s6, s28
	s_cmpk_lt_i32 s6, 0x200
	s_cbranch_scc1 .LBB0_18

; __device__ __forceinline__ unsigned cvt_pk_bf16(float lo, float hi) { unsigned r; asm volatile("s_nop 0\n\tv_cvt_pk_bf16_f32 %0, %1, %2\n\ts_nop 1" : "=v"(r) : "v"(lo), "v"(hi)); return r; }
; #define LAS __attribute__((address_space(3)))
; #define LDS_FENCE() asm volatile("s_waitcnt lgkmcnt(0)" ::: "memory")
; __device__ __forceinline__ void tr_item(const float* W, int ldw, int col0, const float* kscale, bf16_t* WT, int K, int row0, LAS float* scr, int item, int nblk, int lane) {
;     const int kb = item / nblk, nb = item % nblk, k0 = 64 * kb, n0 = 32 * nb;
; #pragma unroll 8
;     for (int i = 0; i < 32; ++i) { const int kk = 2 * i + (lane >> 5); float v = W[(size_t)(k0 + kk) * ldw + col0 + n0 + (lane & 31)]; if (kscale) v *= kscale[k0 + kk]; scr[kk * 33 + (lane & 31)] = v; }
;     LDS_FENCE();
;     const int c = lane & 7;
; #pragma unroll
;     for (int j = 0; j < 4; ++j) { const int n = (lane >> 3) + 8 * j; const LAS float* s = scr + (8 * c) * 33 + n;
;         u32x4 o; o.x = cvt_pk_bf16(s[0 * 33], s[1 * 33]); o.y = cvt_pk_bf16(s[2 * 33], s[3 * 33]); o.z = cvt_pk_bf16(s[4 * 33], s[5 * 33]); o.w = cvt_pk_bf16(s[6 * 33], s[7 * 33]);
;         *(u32x4*)(WT + (size_t)(row0 + n0 + n) * K + k0 + 8 * c) = o; }
;     LDS_FENCE();
; }
.LBB0_24:
	s_lshl_b32 s40, s37, 1
	s_lshl_b32 s41, s23, 1
	v_or_b32_e32 v22, s41, v8
	s_add_i32 s42, s40, 4
	s_add_i32 s43, s41, 4
	s_add_i32 s44, s40, 8
	s_add_i32 s45, s41, 8
	s_add_i32 s46, s40, 12
	s_add_i32 s47, s41, 12
	s_add_i32 s48, s40, 16
	s_add_i32 s49, s41, 16
	s_add_i32 s50, s40, 20
	s_add_i32 s51, s41, 20
	s_add_i32 s52, s40, 24
	s_add_i32 s53, s41, 24
	s_add_i32 s54, s40, 28
	s_add_i32 s55, s41, 28
	v_or_b32_e32 v24, s40, v3
	v_mad_i64_i32 v[22:23], s[38:39], v22, s36, v[16:17]
	v_or_b32_e32 v28, s42, v3
	v_or_b32_e32 v26, s43, v8
	v_or_b32_e32 v32, s44, v3
	v_or_b32_e32 v30, s45, v8
	v_or_b32_e32 v36, s46, v3
	v_or_b32_e32 v34, s47, v8
	v_or_b32_e32 v40, s48, v3
	v_or_b32_e32 v38, s49, v8
	v_or_b32_e32 v44, s50, v3
	v_or_b32_e32 v42, s51, v8
	v_or_b32_e32 v46, s52, v3
	v_or_b32_e32 v48, s53, v8
	v_or_b32_e32 v56, s54, v3
	v_or_b32_e32 v54, s55, v8
	v_mad_i64_i32 v[24:25], s[38:39], v24, s36, v[16:17]
	v_mad_i64_i32 v[26:27], s[38:39], v26, s36, v[16:17]
	v_mad_i64_i32 v[28:29], s[38:39], v28, s36, v[16:17]
	v_mad_i64_i32 v[30:31], s[38:39], v30, s36, v[16:17]
	v_mad_i64_i32 v[32:33], s[38:39], v32, s36, v[16:17]
	v_mad_i64_i32 v[34:35], s[38:39], v34, s36, v[16:17]
	v_mad_i64_i32 v[36:37], s[38:39], v36, s36, v[16:17]
	v_mad_i64_i32 v[38:39], s[38:39], v38, s36, v[16:17]
	v_mad_i64_i32 v[40:41], s[38:39], v40, s36, v[16:17]
	v_mad_i64_i32 v[42:43], s[38:39], v42, s36, v[16:17]
	v_mad_i64_i32 v[44:45], s[38:39], v44, s36, v[16:17]
	v_mad_i64_i32 v[50:51], s[38:39], v48, s36, v[16:17]
	v_mad_i64_i32 v[52:53], s[38:39], v46, s36, v[16:17]
	v_mad_i64_i32 v[54:55], s[38:39], v54, s36, v[16:17]
	v_mad_i64_i32 v[56:57], s[38:39], v56, s36, v[16:17]
	global_load_dword v46, v[22:23], off
	global_load_dword v48, v[24:25], off
	global_load_dword v58, v[26:27], off
	global_load_dword v59, v[28:29], off
	global_load_dword v60, v[30:31], off
	global_load_dword v61, v[32:33], off
	global_load_dword v62, v[34:35], off
	global_load_dword v63, v[36:37], off
	global_load_dword v64, v[38:39], off
	global_load_dword v65, v[40:41], off
	global_load_dword v66, v[42:43], off
	global_load_dword v67, v[44:45], off
	global_load_dword v68, v[50:51], off
	global_load_dword v69, v[52:53], off
	global_load_dword v70, v[54:55], off
	global_load_dword v71, v[56:57], off
	v_or_b32_e32 v24, s40, v1
	v_or_b32_e32 v22, s41, v6
	s_add_i32 s23, s23, 16
	s_add_i32 s37, s37, 16
	s_add_i32 s21, s21, -16
	v_mad_u64_u32 v[22:23], s[38:39], v22, s25, v[12:13]
	v_mad_u64_u32 v[24:25], s[38:39], v24, s25, v[12:13]
	v_or_b32_e32 v23, s42, v1
	v_or_b32_e32 v25, s43, v6
	v_or_b32_e32 v32, s44, v1
	v_or_b32_e32 v30, s45, v6
	v_or_b32_e32 v36, s46, v1
	v_or_b32_e32 v34, s47, v6
	v_or_b32_e32 v40, s48, v1
	v_or_b32_e32 v38, s49, v6
	v_or_b32_e32 v44, s50, v1
	v_or_b32_e32 v42, s51, v6
	v_or_b32_e32 v52, s52, v1
	v_or_b32_e32 v50, s53, v6
	v_or_b32_e32 v56, s54, v1
	v_or_b32_e32 v54, s55, v6
	s_cmp_lg_u32 s21, 0
	v_mad_u64_u32 v[26:27], s[38:39], v25, s25, v[12:13]
	v_mad_u64_u32 v[28:29], s[38:39], v23, s25, v[12:13]
	v_mad_u64_u32 v[30:31], s[38:39], v30, s25, v[12:13]
	v_mad_u64_u32 v[32:33], s[38:39], v32, s25, v[12:13]
	v_mad_u64_u32 v[34:35], s[38:39], v34, s25, v[12:13]
	v_mad_u64_u32 v[36:37], s[38:39], v36, s25, v[12:13]
	v_mad_u64_u32 v[38:39], s[38:39], v38, s25, v[12:13]
	v_mad_u64_u32 v[40:41], s[38:39], v40, s25, v[12:13]
	v_mad_u64_u32 v[42:43], s[38:39], v42, s25, v[12:13]
	v_mad_u64_u32 v[44:45], s[38:39], v44, s25, v[12:13]
	v_mad_u64_u32 v[50:51], s[38:39], v50, s25, v[12:13]
	v_mad_u64_u32 v[52:53], s[38:39], v52, s25, v[12:13]
	v_mad_u64_u32 v[54:55], s[38:39], v54, s25, v[12:13]
	v_mad_u64_u32 v[56:57], s[38:39], v56, s25, v[12:13]
	s_waitcnt vmcnt(15)
	ds_write_b32 v22, v46
	s_waitcnt vmcnt(14)
	ds_write_b32 v24, v48
	s_waitcnt vmcnt(13)
	ds_write_b32 v26, v58
	s_waitcnt vmcnt(12)
	ds_write_b32 v28, v59
	s_waitcnt vmcnt(11)
	ds_write_b32 v30, v60
	s_waitcnt vmcnt(10)
	ds_write_b32 v32, v61
	s_waitcnt vmcnt(9)
	ds_write_b32 v34, v62
	s_waitcnt vmcnt(8)
	ds_write_b32 v36, v63
	s_waitcnt vmcnt(7)
	ds_write_b32 v38, v64
	s_waitcnt vmcnt(6)
	ds_write_b32 v40, v65
	s_waitcnt vmcnt(5)
	ds_write_b32 v42, v66
	s_waitcnt vmcnt(4)
	ds_write_b32 v44, v67
	s_waitcnt vmcnt(3)
	ds_write_b32 v50, v68
	s_waitcnt vmcnt(2)
	ds_write_b32 v52, v69
	s_waitcnt vmcnt(1)
	ds_write_b32 v54, v70
	s_waitcnt vmcnt(0)
	ds_write_b32 v56, v71
	s_cbranch_scc1 .LBB0_24
	s_waitcnt lgkmcnt(0)
	ds_read2_b32 v[16:17], v13 offset1:33
	s_waitcnt lgkmcnt(0)
	v_cvt_pk_bf16_f32 v22, v16, v17
	ds_read2_b32 v[16:17], v13 offset0:66 offset1:99
	s_addk_i32 s22, 0x1400
	s_waitcnt lgkmcnt(0)
	v_cvt_pk_bf16_f32 v23, v16, v17
	ds_read2_b32 v[16:17], v13 offset0:132 offset1:165
	s_ashr_i32 s21, s20, 31
	v_or_b32_e32 v8, s22, v7
	s_waitcnt lgkmcnt(0)
	v_cvt_pk_bf16_f32 v24, v16, v17
	ds_read2_b32 v[16:17], v13 offset0:198 offset1:231
	v_lshl_add_u64 v[26:27], s[20:21], 1, v[14:15]
	v_lshlrev_b64 v[28:29], 11, v[8:9]
	s_waitcnt lgkmcnt(0)
	v_cvt_pk_bf16_f32 v25, v16, v17
	ds_read2_b32 v[16:17], v13 offset0:8 offset1:41
	v_lshl_add_u64 v[28:29], v[26:27], 0, v[28:29]
	global_store_dwordx4 v[28:29], v[22:25], off
	v_or_b32_e32 v8, s22, v18
	v_lshlrev_b64 v[28:29], 11, v[8:9]
	s_waitcnt lgkmcnt(0)
	v_cvt_pk_bf16_f32 v22, v16, v17
	ds_read2_b32 v[16:17], v13 offset0:74 offset1:107
	s_waitcnt lgkmcnt(0)
	v_cvt_pk_bf16_f32 v23, v16, v17
	ds_read2_b32 v[16:17], v13 offset0:140 offset1:173
	s_waitcnt lgkmcnt(0)
	v_cvt_pk_bf16_f32 v24, v16, v17
	ds_read2_b32 v[16:17], v13 offset0:206 offset1:239
	s_waitcnt lgkmcnt(0)
	v_cvt_pk_bf16_f32 v25, v16, v17
	ds_read2_b32 v[16:17], v13 offset0:16 offset1:49
	v_lshl_add_u64 v[28:29], v[26:27], 0, v[28:29]
	global_store_dwordx4 v[28:29], v[22:25], off
	v_or_b32_e32 v8, s22, v19
	v_lshlrev_b64 v[28:29], 11, v[8:9]
	s_waitcnt lgkmcnt(0)
	v_cvt_pk_bf16_f32 v22, v16, v17
	ds_read2_b32 v[16:17], v13 offset0:82 offset1:115
	s_waitcnt lgkmcnt(0)
	v_cvt_pk_bf16_f32 v23, v16, v17
	ds_read2_b32 v[16:17], v13 offset0:148 offset1:181
	s_waitcnt lgkmcnt(0)
	v_cvt_pk_bf16_f32 v24, v16, v17
	ds_read2_b32 v[16:17], v13 offset0:214 offset1:247
	s_waitcnt lgkmcnt(0)
	v_cvt_pk_bf16_f32 v25, v16, v17
	ds_read2_b32 v[16:17], v13 offset0:24 offset1:57
	v_lshl_add_u64 v[28:29], v[26:27], 0, v[28:29]
	v_or_b32_e32 v8, s22, v21
	global_store_dwordx4 v[28:29], v[22:25], off
	v_lshlrev_b64 v[28:29], 11, v[8:9]
	v_lshl_add_u64 v[26:27], v[26:27], 0, v[28:29]
	s_waitcnt lgkmcnt(0)
	v_cvt_pk_bf16_f32 v22, v16, v17
	ds_read2_b32 v[16:17], v13 offset0:90 offset1:123
	s_waitcnt lgkmcnt(0)
	v_cvt_pk_bf16_f32 v23, v16, v17
	ds_read2_b32 v[16:17], v13 offset0:156 offset1:189
	s_waitcnt lgkmcnt(0)
	v_cvt_pk_bf16_f32 v24, v16, v17
	ds_read2_b32 v[16:17], v13 offset0:222 offset1:255
	s_waitcnt lgkmcnt(0)
	v_cvt_pk_bf16_f32 v25, v16, v17
	global_store_dwordx4 v[26:27], v[22:25], off
	s_waitcnt lgkmcnt(0)
	s_add_i32 s24, s24, s28
	s_cmp_lt_i32 s24, 32
	s_cbranch_scc1 .LBB0_23

; #define LAS __attribute__((address_space(3)))
; __device__ __forceinline__ void tr_item(const float* W, int ldw, int col0, const float* kscale, bf16_t* WT, int K, int row0, LAS float* scr, int item, int nblk, int lane) {
;     const int kb = item / nblk, nb = item % nblk, k0 = 64 * kb, n0 = 32 * nb;
; #pragma unroll 8
;     for (int i = 0; i < 32; ++i) { const int kk = 2 * i + (lane >> 5); float v = W[(size_t)(k0 + kk) * ldw + col0 + n0 + (lane & 31)]; if (kscale) v *= kscale[k0 + kk]; scr[kk * 33 + (lane & 31)] = v; }
.LBB0_29:
	s_lshl_b32 s38, s25, 1
	s_lshl_b32 s39, s21, 1
	v_or_b32_e32 v21, s38, v3
	v_or_b32_e32 v22, s39, v16
	s_add_i32 s40, s38, 4
	s_add_i32 s41, s39, 4
	s_add_i32 s42, s38, 8
	s_add_i32 s43, s39, 8
	s_add_i32 s44, s38, 12
	s_add_i32 s45, s39, 12
	s_add_i32 s46, s38, 16
	s_add_i32 s47, s39, 16
	s_add_i32 s48, s38, 20
	s_add_i32 s49, s39, 20
	s_add_i32 s50, s38, 24
	s_add_i32 s51, s39, 24
	s_add_i32 s52, s38, 28
	s_add_i32 s53, s39, 28
	v_mad_i64_i32 v[22:23], s[36:37], v22, s24, v[14:15]
	v_mad_i64_i32 v[24:25], s[36:37], v21, s24, v[14:15]
	v_or_b32_e32 v21, s40, v3
	v_or_b32_e32 v26, s41, v16
	v_or_b32_e32 v32, s42, v3
	v_or_b32_e32 v30, s43, v16
	v_or_b32_e32 v36, s44, v3
	v_or_b32_e32 v34, s45, v16
	v_or_b32_e32 v40, s46, v3
	v_or_b32_e32 v38, s47, v16
	v_or_b32_e32 v44, s48, v3
	v_or_b32_e32 v42, s49, v16
	v_or_b32_e32 v46, s50, v3
	v_or_b32_e32 v48, s51, v16
	v_or_b32_e32 v56, s52, v3
	v_or_b32_e32 v54, s53, v16
	v_mad_i64_i32 v[26:27], s[36:37], v26, s24, v[14:15]
	v_mad_i64_i32 v[28:29], s[36:37], v21, s24, v[14:15]
	v_mad_i64_i32 v[30:31], s[36:37], v30, s24, v[14:15]
	v_mad_i64_i32 v[32:33], s[36:37], v32, s24, v[14:15]
	v_mad_i64_i32 v[34:35], s[36:37], v34, s24, v[14:15]
	v_mad_i64_i32 v[36:37], s[36:37], v36, s24, v[14:15]
	v_mad_i64_i32 v[38:39], s[36:37], v38, s24, v[14:15]
	v_mad_i64_i32 v[40:41], s[36:37], v40, s24, v[14:15]
	v_mad_i64_i32 v[42:43], s[36:37], v42, s24, v[14:15]
	v_mad_i64_i32 v[44:45], s[36:37], v44, s24, v[14:15]
	v_mad_i64_i32 v[50:51], s[36:37], v48, s24, v[14:15]
	v_mad_i64_i32 v[52:53], s[36:37], v46, s24, v[14:15]
	v_mad_i64_i32 v[54:55], s[36:37], v54, s24, v[14:15]
	v_mad_i64_i32 v[56:57], s[36:37], v56, s24, v[14:15]
	global_load_dword v21, v[22:23], off
	global_load_dword v46, v[24:25], off
	global_load_dword v48, v[26:27], off
	global_load_dword v58, v[28:29], off
	global_load_dword v59, v[30:31], off
	global_load_dword v60, v[32:33], off
	global_load_dword v61, v[34:35], off
	global_load_dword v62, v[36:37], off
	global_load_dword v63, v[38:39], off
	global_load_dword v64, v[40:41], off
	global_load_dword v65, v[42:43], off
	global_load_dword v66, v[44:45], off
	global_load_dword v67, v[50:51], off
	global_load_dword v68, v[52:53], off
	global_load_dword v69, v[54:55], off
	global_load_dword v70, v[56:57], off
	v_or_b32_e32 v24, s38, v1
	v_or_b32_e32 v22, s39, v6
	s_add_i32 s21, s21, 16
	s_add_i32 s25, s25, 16
	s_add_i32 s15, s15, -16
	v_mad_u64_u32 v[22:23], s[36:37], v22, s23, v[10:11]
	v_mad_u64_u32 v[24:25], s[36:37], v24, s23, v[10:11]
	v_or_b32_e32 v23, s40, v1
	v_or_b32_e32 v25, s41, v6
	v_or_b32_e32 v32, s42, v1
	v_or_b32_e32 v30, s43, v6
	v_or_b32_e32 v36, s44, v1
	v_or_b32_e32 v34, s45, v6
	v_or_b32_e32 v40, s46, v1
	v_or_b32_e32 v38, s47, v6
	v_or_b32_e32 v44, s48, v1
	v_or_b32_e32 v42, s49, v6
	v_or_b32_e32 v52, s50, v1
	v_or_b32_e32 v50, s51, v6
	v_or_b32_e32 v56, s52, v1
	v_or_b32_e32 v54, s53, v6
	s_cmp_lg_u32 s15, 0
	v_mad_u64_u32 v[26:27], s[36:37], v25, s23, v[10:11]
	v_mad_u64_u32 v[28:29], s[36:37], v23, s23, v[10:11]
	v_mad_u64_u32 v[30:31], s[36:37], v30, s23, v[10:11]
	v_mad_u64_u32 v[32:33], s[36:37], v32, s23, v[10:11]
	v_mad_u64_u32 v[34:35], s[36:37], v34, s23, v[10:11]
	v_mad_u64_u32 v[36:37], s[36:37], v36, s23, v[10:11]
	v_mad_u64_u32 v[38:39], s[36:37], v38, s23, v[10:11]
	v_mad_u64_u32 v[40:41], s[36:37], v40, s23, v[10:11]
	v_mad_u64_u32 v[42:43], s[36:37], v42, s23, v[10:11]
	v_mad_u64_u32 v[44:45], s[36:37], v44, s23, v[10:11]
	v_mad_u64_u32 v[50:51], s[36:37], v50, s23, v[10:11]
	v_mad_u64_u32 v[52:53], s[36:37], v52, s23, v[10:11]
	v_mad_u64_u32 v[54:55], s[36:37], v54, s23, v[10:11]
	v_mad_u64_u32 v[56:57], s[36:37], v56, s23, v[10:11]
	s_waitcnt vmcnt(15)
	ds_write_b32 v22, v21
	s_waitcnt vmcnt(14)
	ds_write_b32 v24, v46
	s_waitcnt vmcnt(13)
	ds_write_b32 v26, v48
	s_waitcnt vmcnt(12)
	ds_write_b32 v28, v58
	s_waitcnt vmcnt(11)
	ds_write_b32 v30, v59
	s_waitcnt vmcnt(10)
	ds_write_b32 v32, v60
	s_waitcnt vmcnt(9)
	ds_write_b32 v34, v61
	s_waitcnt vmcnt(8)
	ds_write_b32 v36, v62
	s_waitcnt vmcnt(7)
	ds_write_b32 v38, v63
	s_waitcnt vmcnt(6)
	ds_write_b32 v40, v64
	s_waitcnt vmcnt(5)
	ds_write_b32 v42, v65
	s_waitcnt vmcnt(4)
	ds_write_b32 v44, v66
	s_waitcnt vmcnt(3)
	ds_write_b32 v50, v67
	s_waitcnt vmcnt(2)
	ds_write_b32 v52, v68
	s_waitcnt vmcnt(1)
	ds_write_b32 v54, v69
	s_waitcnt vmcnt(0)
	ds_write_b32 v56, v70
	s_cbranch_scc1 .LBB0_29
; __device__ __forceinline__ unsigned cvt_pk_bf16(float lo, float hi) { unsigned r; asm volatile("s_nop 0\n\tv_cvt_pk_bf16_f32 %0, %1, %2\n\ts_nop 1" : "=v"(r) : "v"(lo), "v"(hi)); return r; }
; #define LAS __attribute__((address_space(3)))
; #define LDS_FENCE() asm volatile("s_waitcnt lgkmcnt(0)" ::: "memory")
; __device__ __forceinline__ void tr_item(const float* W, int ldw, int col0, const float* kscale, bf16_t* WT, int K, int row0, LAS float* scr, int item, int nblk, int lane) {
;     ...
;     LDS_FENCE();
;     const int c = lane & 7;
; #pragma unroll
;     for (int j = 0; j < 4; ++j) { const int n = (lane >> 3) + 8 * j; const LAS float* s = scr + (8 * c) * 33 + n;
;         u32x4 o; o.x = cvt_pk_bf16(s[0 * 33], s[1 * 33]); o.y = cvt_pk_bf16(s[2 * 33], s[3 * 33]); o.z = cvt_pk_bf16(s[4 * 33], s[5 * 33]); o.w = cvt_pk_bf16(s[6 * 33], s[7 * 33]);
;         *(u32x4*)(WT + (size_t)(row0 + n0 + n) * K + k0 + 8 * c) = o; }
;     LDS_FENCE();
	s_waitcnt lgkmcnt(0)
	v_or_b32_e32 v26, s14, v7
	ds_read2_b32 v[14:15], v11 offset1:33
	s_ashr_i32 s21, s20, 31
	v_ashrrev_i32_e32 v27, 31, v26
	s_waitcnt lgkmcnt(0)
	v_cvt_pk_bf16_f32 v22, v14, v15
	ds_read2_b32 v[14:15], v11 offset0:66 offset1:99
	v_lshl_add_u64 v[28:29], s[20:21], 1, v[12:13]
	v_lshlrev_b64 v[26:27], 11, v[26:27]
	s_waitcnt lgkmcnt(0)
	v_cvt_pk_bf16_f32 v23, v14, v15
	ds_read2_b32 v[14:15], v11 offset0:132 offset1:165
	v_lshl_add_u64 v[26:27], v[28:29], 0, v[26:27]
	s_waitcnt lgkmcnt(0)
	v_cvt_pk_bf16_f32 v24, v14, v15
	ds_read2_b32 v[14:15], v11 offset0:198 offset1:231
	s_waitcnt lgkmcnt(0)
	v_cvt_pk_bf16_f32 v25, v14, v15
	global_store_dwordx4 v[26:27], v[22:25], off
	v_or_b32_e32 v26, s14, v17
	ds_read2_b32 v[14:15], v11 offset0:8 offset1:41
	v_ashrrev_i32_e32 v27, 31, v26
	s_waitcnt lgkmcnt(0)
	v_cvt_pk_bf16_f32 v22, v14, v15
	ds_read2_b32 v[14:15], v11 offset0:74 offset1:107
	v_lshlrev_b64 v[26:27], 11, v[26:27]
	s_waitcnt lgkmcnt(0)
	v_cvt_pk_bf16_f32 v23, v14, v15
	ds_read2_b32 v[14:15], v11 offset0:140 offset1:173
	v_lshl_add_u64 v[26:27], v[28:29], 0, v[26:27]
	s_waitcnt lgkmcnt(0)
	v_cvt_pk_bf16_f32 v24, v14, v15
	ds_read2_b32 v[14:15], v11 offset0:206 offset1:239
	s_waitcnt lgkmcnt(0)
	v_cvt_pk_bf16_f32 v25, v14, v15
	global_store_dwordx4 v[26:27], v[22:25], off
	v_or_b32_e32 v26, s14, v18
	ds_read2_b32 v[14:15], v11 offset0:16 offset1:49
	v_ashrrev_i32_e32 v27, 31, v26
	s_waitcnt lgkmcnt(0)
	v_cvt_pk_bf16_f32 v22, v14, v15
	ds_read2_b32 v[14:15], v11 offset0:82 offset1:115
	v_lshlrev_b64 v[26:27], 11, v[26:27]
	s_waitcnt lgkmcnt(0)
	v_cvt_pk_bf16_f32 v23, v14, v15
	ds_read2_b32 v[14:15], v11 offset0:148 offset1:181
	v_lshl_add_u64 v[26:27], v[28:29], 0, v[26:27]
	s_waitcnt lgkmcnt(0)
	v_cvt_pk_bf16_f32 v24, v14, v15
	ds_read2_b32 v[14:15], v11 offset0:214 offset1:247
	s_waitcnt lgkmcnt(0)
	v_cvt_pk_bf16_f32 v25, v14, v15
	global_store_dwordx4 v[26:27], v[22:25], off
	v_or_b32_e32 v26, s14, v19
	ds_read2_b32 v[14:15], v11 offset0:24 offset1:57
	v_ashrrev_i32_e32 v27, 31, v26
	s_waitcnt lgkmcnt(0)
	v_cvt_pk_bf16_f32 v22, v14, v15
	ds_read2_b32 v[14:15], v11 offset0:90 offset1:123
	v_lshlrev_b64 v[26:27], 11, v[26:27]
	s_waitcnt lgkmcnt(0)
	v_cvt_pk_bf16_f32 v23, v14, v15
	ds_read2_b32 v[14:15], v11 offset0:156 offset1:189
	v_lshl_add_u64 v[26:27], v[28:29], 0, v[26:27]
	s_waitcnt lgkmcnt(0)
	v_cvt_pk_bf16_f32 v24, v14, v15
	ds_read2_b32 v[14:15], v11 offset0:222 offset1:255
	s_waitcnt lgkmcnt(0)
	v_cvt_pk_bf16_f32 v25, v14, v15
	global_store_dwordx4 v[26:27], v[22:25], off
	s_waitcnt lgkmcnt(0)
	s_add_i32 s22, s22, s28
	s_cmpk_lt_i32 s22, 0xa00
	s_cbranch_scc1 .LBB0_28

; __device__ __forceinline__ unsigned cvt_pk_bf16(float lo, float hi) { unsigned r; asm volatile("s_nop 0\n\tv_cvt_pk_bf16_f32 %0, %1, %2\n\ts_nop 1" : "=v"(r) : "v"(lo), "v"(hi)); return r; }
; #define LAS __attribute__((address_space(3)))
; #define LDS_FENCE() asm volatile("s_waitcnt lgkmcnt(0)" ::: "memory")
; __device__ __forceinline__ void tr_item(const float* W, int ldw, int col0, const float* kscale, bf16_t* WT, int K, int row0, LAS float* scr, int item, int nblk, int lane) {
;     ...
;     LDS_FENCE();
;     const int c = lane & 7;
; #pragma unroll
;     for (int j = 0; j < 4; ++j) { const int n = (lane >> 3) + 8 * j; const LAS float* s = scr + (8 * c) * 33 + n;
;         u32x4 o; o.x = cvt_pk_bf16(s[0 * 33], s[1 * 33]); o.y = cvt_pk_bf16(s[2 * 33], s[3 * 33]); o.z = cvt_pk_bf16(s[4 * 33], s[5 * 33]); o.w = cvt_pk_bf16(s[6 * 33], s[7 * 33]);
;         *(u32x4*)(WT + (size_t)(row0 + n0 + n) * K + k0 + 8 * c) = o; }
;     LDS_FENCE();
.LBB0_33:
	s_waitcnt lgkmcnt(0)
	v_or_b32_e32 v24, s22, v1
	ds_read2_b32 v[12:13], v3 offset1:33
	v_ashrrev_i32_e32 v25, 31, v24
	s_waitcnt lgkmcnt(0)
	s_nop 0
	v_cvt_pk_bf16_f32 v12, v12, v13
	ds_read2_b32 v[14:15], v3 offset0:66 offset1:99
	v_lshl_add_u64 v[18:19], s[24:25], 1, v[10:11]
	v_lshlrev_b64 v[24:25], 12, v[24:25]
	s_waitcnt lgkmcnt(0)
	s_nop 0
	v_cvt_pk_bf16_f32 v13, v14, v15
	ds_read2_b32 v[14:15], v3 offset0:132 offset1:165
	v_lshl_add_u64 v[24:25], v[18:19], 0, v[24:25]
	s_waitcnt lgkmcnt(0)
	v_cvt_pk_bf16_f32 v14, v14, v15
	ds_read2_b32 v[16:17], v3 offset0:198 offset1:231
	s_waitcnt lgkmcnt(0)
	v_cvt_pk_bf16_f32 v15, v16, v17
	global_store_dwordx4 v[24:25], v[12:15], off
	v_or_b32_e32 v24, s22, v7
	ds_read2_b32 v[16:17], v3 offset0:8 offset1:41
	s_waitcnt lgkmcnt(0)
	v_cvt_pk_bf16_f32 v12, v16, v17
	ds_read2_b32 v[14:15], v3 offset0:74 offset1:107
	v_ashrrev_i32_e32 v25, 31, v24
	s_waitcnt lgkmcnt(0)
	v_cvt_pk_bf16_f32 v13, v14, v15
	ds_read2_b32 v[14:15], v3 offset0:140 offset1:173
	v_lshlrev_b64 v[24:25], 12, v[24:25]
	s_waitcnt lgkmcnt(0)
	v_cvt_pk_bf16_f32 v14, v14, v15
	ds_read2_b32 v[16:17], v3 offset0:206 offset1:239
	s_waitcnt lgkmcnt(0)
	v_cvt_pk_bf16_f32 v15, v16, v17
	v_lshl_add_u64 v[24:25], v[18:19], 0, v[24:25]
	ds_read2_b32 v[16:17], v3 offset0:16 offset1:49
	global_store_dwordx4 v[24:25], v[12:15], off
	v_or_b32_e32 v24, s22, v21
	v_ashrrev_i32_e32 v25, 31, v24
	s_waitcnt lgkmcnt(0)
	v_cvt_pk_bf16_f32 v12, v16, v17
	ds_read2_b32 v[14:15], v3 offset0:82 offset1:115
	s_waitcnt lgkmcnt(0)
	v_cvt_pk_bf16_f32 v13, v14, v15
	ds_read2_b32 v[14:15], v3 offset0:148 offset1:181
	s_waitcnt lgkmcnt(0)
	v_cvt_pk_bf16_f32 v14, v14, v15
	ds_read2_b32 v[16:17], v3 offset0:214 offset1:247
	v_lshlrev_b64 v[24:25], 12, v[24:25]
	s_waitcnt lgkmcnt(0)
	v_cvt_pk_bf16_f32 v15, v16, v17
	ds_read2_b32 v[16:17], v3 offset0:24 offset1:57
	v_lshl_add_u64 v[24:25], v[18:19], 0, v[24:25]
	global_store_dwordx4 v[24:25], v[12:15], off
	s_add_i32 s36, s36, s28
	s_cmpk_lt_i32 s36, 0x400
	s_waitcnt lgkmcnt(0)
	v_cvt_pk_bf16_f32 v12, v16, v17
	v_or_b32_e32 v16, s22, v22
	v_ashrrev_i32_e32 v17, 31, v16
	ds_read2_b32 v[14:15], v3 offset0:90 offset1:123
	v_lshlrev_b64 v[16:17], 12, v[16:17]
	s_waitcnt lgkmcnt(0)
	v_cvt_pk_bf16_f32 v13, v14, v15
	ds_read2_b32 v[14:15], v3 offset0:156 offset1:189
	v_lshl_add_u64 v[16:17], v[18:19], 0, v[16:17]
	s_waitcnt lgkmcnt(0)
	v_cvt_pk_bf16_f32 v14, v14, v15
	ds_read2_b32 v[24:25], v3 offset0:222 offset1:255
	s_waitcnt lgkmcnt(0)
	v_cvt_pk_bf16_f32 v15, v24, v25
	global_store_dwordx4 v[16:17], v[12:15], off
	s_waitcnt lgkmcnt(0)
	s_cbranch_scc0 .LBB0_52

; #define LAS __attribute__((address_space(3)))
; __device__ __forceinline__ void tr_item(const float* W, int ldw, int col0, const float* kscale, bf16_t* WT, int K, int row0, LAS float* scr, int item, int nblk, int lane) {
;     const int kb = item / nblk, nb = item % nblk, k0 = 64 * kb, n0 = 32 * nb;
; #pragma unroll 8
;     for (int i = 0; i < 32; ++i) { const int kk = 2 * i + (lane >> 5); float v = W[(size_t)(k0 + kk) * ldw + col0 + n0 + (lane & 31)]; if (kscale) v *= kscale[k0 + kk]; scr[kk * 33 + (lane & 31)] = v; }
.LBB0_55:
	s_lshl_b32 s21, s20, 1
	s_lshl_b32 s22, s7, 1
	v_or_b32_e32 v24, s22, v16
	s_add_i32 s23, s21, 4
	s_add_i32 s24, s22, 4
	s_add_i32 s25, s21, 8
	s_add_i32 s36, s22, 8
	s_add_i32 s37, s21, 12
	s_add_i32 s40, s22, 12
	s_add_i32 s41, s21, 16
	s_add_i32 s42, s22, 16
	s_add_i32 s43, s21, 20
	s_add_i32 s44, s22, 20
	s_add_i32 s45, s21, 24
	s_add_i32 s46, s22, 24
	s_add_i32 s47, s21, 28
	s_add_i32 s48, s22, 28
	v_or_b32_e32 v22, s21, v3
	v_ashrrev_i32_e32 v25, 31, v24
	v_or_b32_e32 v26, s23, v3
	v_or_b32_e32 v28, s24, v16
	v_or_b32_e32 v30, s25, v3
	v_or_b32_e32 v32, s36, v16
	v_or_b32_e32 v34, s37, v3
	v_or_b32_e32 v36, s40, v16
	v_or_b32_e32 v38, s41, v3
	v_or_b32_e32 v40, s42, v16
	v_or_b32_e32 v42, s43, v3
	v_or_b32_e32 v44, s44, v16
	v_or_b32_e32 v50, s45, v3
	v_or_b32_e32 v52, s46, v16
	v_or_b32_e32 v54, s47, v3
	v_or_b32_e32 v56, s48, v16
	v_ashrrev_i32_e32 v23, 31, v22
	v_lshlrev_b64 v[24:25], 12, v[24:25]
	v_ashrrev_i32_e32 v29, 31, v28
	v_ashrrev_i32_e32 v27, 31, v26
	v_ashrrev_i32_e32 v33, 31, v32
	v_ashrrev_i32_e32 v31, 31, v30
	v_ashrrev_i32_e32 v37, 31, v36
	v_ashrrev_i32_e32 v35, 31, v34
	v_ashrrev_i32_e32 v41, 31, v40
	v_ashrrev_i32_e32 v39, 31, v38
	v_ashrrev_i32_e32 v45, 31, v44
	v_ashrrev_i32_e32 v43, 31, v42
	v_ashrrev_i32_e32 v53, 31, v52
	v_ashrrev_i32_e32 v51, 31, v50
	v_ashrrev_i32_e32 v57, 31, v56
	v_ashrrev_i32_e32 v55, 31, v54
	v_lshlrev_b64 v[22:23], 12, v[22:23]
	v_lshl_add_u64 v[24:25], v[14:15], 0, v[24:25]
	v_lshlrev_b64 v[26:27], 12, v[26:27]
	v_lshlrev_b64 v[28:29], 12, v[28:29]
	v_lshlrev_b64 v[30:31], 12, v[30:31]
	v_lshlrev_b64 v[32:33], 12, v[32:33]
	v_lshlrev_b64 v[34:35], 12, v[34:35]
	v_lshlrev_b64 v[36:37], 12, v[36:37]
	v_lshlrev_b64 v[38:39], 12, v[38:39]
	v_lshlrev_b64 v[40:41], 12, v[40:41]
	v_lshlrev_b64 v[42:43], 12, v[42:43]
	v_lshlrev_b64 v[44:45], 12, v[44:45]
	v_lshlrev_b64 v[50:51], 12, v[50:51]
	v_lshlrev_b64 v[52:53], 12, v[52:53]
	v_lshlrev_b64 v[54:55], 12, v[54:55]
	v_lshlrev_b64 v[56:57], 12, v[56:57]
	v_lshl_add_u64 v[22:23], v[14:15], 0, v[22:23]
	v_lshl_add_u64 v[28:29], v[14:15], 0, v[28:29]
	v_lshl_add_u64 v[26:27], v[14:15], 0, v[26:27]
	v_lshl_add_u64 v[32:33], v[14:15], 0, v[32:33]
	v_lshl_add_u64 v[30:31], v[14:15], 0, v[30:31]
	v_lshl_add_u64 v[36:37], v[14:15], 0, v[36:37]
	v_lshl_add_u64 v[34:35], v[14:15], 0, v[34:35]
	v_lshl_add_u64 v[40:41], v[14:15], 0, v[40:41]
	v_lshl_add_u64 v[38:39], v[14:15], 0, v[38:39]
	v_lshl_add_u64 v[44:45], v[14:15], 0, v[44:45]
	v_lshl_add_u64 v[42:43], v[14:15], 0, v[42:43]
	v_lshl_add_u64 v[52:53], v[14:15], 0, v[52:53]
	v_lshl_add_u64 v[50:51], v[14:15], 0, v[50:51]
	v_lshl_add_u64 v[56:57], v[14:15], 0, v[56:57]
	v_lshl_add_u64 v[54:55], v[14:15], 0, v[54:55]
	global_load_dword v21, v[24:25], off
	global_load_dword v46, v[22:23], off
	global_load_dword v48, v[28:29], off
	global_load_dword v58, v[26:27], off
	global_load_dword v59, v[32:33], off
	global_load_dword v60, v[30:31], off
	global_load_dword v61, v[36:37], off
	global_load_dword v62, v[34:35], off
	global_load_dword v63, v[40:41], off
	global_load_dword v64, v[38:39], off
	global_load_dword v65, v[44:45], off
	global_load_dword v66, v[42:43], off
	global_load_dword v67, v[52:53], off
	global_load_dword v68, v[50:51], off
	global_load_dword v69, v[56:57], off
	global_load_dword v70, v[54:55], off
	v_or_b32_e32 v24, s21, v1
	v_or_b32_e32 v22, s22, v6
	s_add_i32 s7, s7, 16
	s_add_i32 s20, s20, 16
	s_add_i32 s5, s5, -16
	v_mad_u64_u32 v[22:23], s[38:39], v22, s15, v[10:11]
	v_mad_u64_u32 v[24:25], s[38:39], v24, s15, v[10:11]
	v_or_b32_e32 v23, s23, v1
	v_or_b32_e32 v25, s24, v6
	v_or_b32_e32 v32, s25, v1
	v_or_b32_e32 v30, s36, v6
	v_or_b32_e32 v36, s37, v1
	v_or_b32_e32 v34, s40, v6
	v_or_b32_e32 v40, s41, v1
	v_or_b32_e32 v38, s42, v6
	v_or_b32_e32 v44, s43, v1
	v_or_b32_e32 v42, s44, v6
	v_or_b32_e32 v52, s45, v1
	v_or_b32_e32 v50, s46, v6
	v_or_b32_e32 v56, s47, v1
	v_or_b32_e32 v54, s48, v6
	s_cmp_lg_u32 s5, 0
	v_mad_u64_u32 v[26:27], s[22:23], v25, s15, v[10:11]
	v_mad_u64_u32 v[28:29], s[22:23], v23, s15, v[10:11]
	v_mad_u64_u32 v[30:31], s[22:23], v30, s15, v[10:11]
	v_mad_u64_u32 v[32:33], s[22:23], v32, s15, v[10:11]
	v_mad_u64_u32 v[34:35], s[22:23], v34, s15, v[10:11]
	v_mad_u64_u32 v[36:37], s[22:23], v36, s15, v[10:11]
	v_mad_u64_u32 v[38:39], s[22:23], v38, s15, v[10:11]
	v_mad_u64_u32 v[40:41], s[22:23], v40, s15, v[10:11]
	v_mad_u64_u32 v[42:43], s[22:23], v42, s15, v[10:11]
	v_mad_u64_u32 v[44:45], s[22:23], v44, s15, v[10:11]
	v_mad_u64_u32 v[50:51], s[22:23], v50, s15, v[10:11]
	v_mad_u64_u32 v[52:53], s[22:23], v52, s15, v[10:11]
	v_mad_u64_u32 v[54:55], s[22:23], v54, s15, v[10:11]
	v_mad_u64_u32 v[56:57], s[22:23], v56, s15, v[10:11]
	s_waitcnt vmcnt(15)
	ds_write_b32 v22, v21
	s_waitcnt vmcnt(14)
	ds_write_b32 v24, v46
	s_waitcnt vmcnt(13)
	ds_write_b32 v26, v48
	s_waitcnt vmcnt(12)
	ds_write_b32 v28, v58
	s_waitcnt vmcnt(11)
	ds_write_b32 v30, v59
	s_waitcnt vmcnt(10)
	ds_write_b32 v32, v60
	s_waitcnt vmcnt(9)
	ds_write_b32 v34, v61
	s_waitcnt vmcnt(8)
	ds_write_b32 v36, v62
	s_waitcnt vmcnt(7)
	ds_write_b32 v38, v63
	s_waitcnt vmcnt(6)
	ds_write_b32 v40, v64
	s_waitcnt vmcnt(5)
	ds_write_b32 v42, v65
	s_waitcnt vmcnt(4)
	ds_write_b32 v44, v66
	s_waitcnt vmcnt(3)
	ds_write_b32 v50, v67
	s_waitcnt vmcnt(2)
	ds_write_b32 v52, v68
	s_waitcnt vmcnt(1)
	ds_write_b32 v54, v69
	s_waitcnt vmcnt(0)
	ds_write_b32 v56, v70
	s_cbranch_scc1 .LBB0_55
; __device__ __forceinline__ unsigned cvt_pk_bf16(float lo, float hi) { unsigned r; asm volatile("s_nop 0\n\tv_cvt_pk_bf16_f32 %0, %1, %2\n\ts_nop 1" : "=v"(r) : "v"(lo), "v"(hi)); return r; }
; #define LAS __attribute__((address_space(3)))
; #define LDS_FENCE() asm volatile("s_waitcnt lgkmcnt(0)" ::: "memory")
; __device__ __forceinline__ void tr_item(const float* W, int ldw, int col0, const float* kscale, bf16_t* WT, int K, int row0, LAS float* scr, int item, int nblk, int lane) {
;     ...
;     LDS_FENCE();
;     const int c = lane & 7;
; #pragma unroll
;     for (int j = 0; j < 4; ++j) { const int n = (lane >> 3) + 8 * j; const LAS float* s = scr + (8 * c) * 33 + n;
;         u32x4 o; o.x = cvt_pk_bf16(s[0 * 33], s[1 * 33]); o.y = cvt_pk_bf16(s[2 * 33], s[3 * 33]); o.z = cvt_pk_bf16(s[4 * 33], s[5 * 33]); o.w = cvt_pk_bf16(s[6 * 33], s[7 * 33]);
;         *(u32x4*)(WT + (size_t)(row0 + n0 + n) * K + k0 + 8 * c) = o; }
;     LDS_FENCE();
	s_waitcnt lgkmcnt(0)
	v_or_b32_e32 v26, s4, v7
	ds_read2_b32 v[14:15], v11 offset1:33
	s_ashr_i32 s7, s6, 31
	v_ashrrev_i32_e32 v27, 31, v26
	s_waitcnt lgkmcnt(0)
	v_cvt_pk_bf16_f32 v22, v14, v15
	ds_read2_b32 v[14:15], v11 offset0:66 offset1:99
	v_lshl_add_u64 v[28:29], s[6:7], 1, v[12:13]
	v_lshlrev_b64 v[26:27], 11, v[26:27]
	s_waitcnt lgkmcnt(0)
	v_cvt_pk_bf16_f32 v23, v14, v15
	ds_read2_b32 v[14:15], v11 offset0:132 offset1:165
	v_lshl_add_u64 v[26:27], v[28:29], 0, v[26:27]
	s_waitcnt lgkmcnt(0)
	v_cvt_pk_bf16_f32 v24, v14, v15
	ds_read2_b32 v[14:15], v11 offset0:198 offset1:231
	s_waitcnt lgkmcnt(0)
	v_cvt_pk_bf16_f32 v25, v14, v15
	global_store_dwordx4 v[26:27], v[22:25], off
	v_or_b32_e32 v26, s4, v17
	ds_read2_b32 v[14:15], v11 offset0:8 offset1:41
	v_ashrrev_i32_e32 v27, 31, v26
	s_waitcnt lgkmcnt(0)
	v_cvt_pk_bf16_f32 v22, v14, v15
	ds_read2_b32 v[14:15], v11 offset0:74 offset1:107
	v_lshlrev_b64 v[26:27], 11, v[26:27]
	s_waitcnt lgkmcnt(0)
	v_cvt_pk_bf16_f32 v23, v14, v15
	ds_read2_b32 v[14:15], v11 offset0:140 offset1:173
	v_lshl_add_u64 v[26:27], v[28:29], 0, v[26:27]
	s_waitcnt lgkmcnt(0)
	v_cvt_pk_bf16_f32 v24, v14, v15
	ds_read2_b32 v[14:15], v11 offset0:206 offset1:239
	s_waitcnt lgkmcnt(0)
	v_cvt_pk_bf16_f32 v25, v14, v15
	global_store_dwordx4 v[26:27], v[22:25], off
	v_or_b32_e32 v26, s4, v18
	ds_read2_b32 v[14:15], v11 offset0:16 offset1:49
	v_ashrrev_i32_e32 v27, 31, v26
	s_waitcnt lgkmcnt(0)
	v_cvt_pk_bf16_f32 v22, v14, v15
	ds_read2_b32 v[14:15], v11 offset0:82 offset1:115
	v_lshlrev_b64 v[26:27], 11, v[26:27]
	s_waitcnt lgkmcnt(0)
	v_cvt_pk_bf16_f32 v23, v14, v15
	ds_read2_b32 v[14:15], v11 offset0:148 offset1:181
	v_lshl_add_u64 v[26:27], v[28:29], 0, v[26:27]
	s_waitcnt lgkmcnt(0)
	v_cvt_pk_bf16_f32 v24, v14, v15
	ds_read2_b32 v[14:15], v11 offset0:214 offset1:247
	s_waitcnt lgkmcnt(0)
	v_cvt_pk_bf16_f32 v25, v14, v15
	global_store_dwordx4 v[26:27], v[22:25], off
	v_or_b32_e32 v26, s4, v19
	ds_read2_b32 v[14:15], v11 offset0:24 offset1:57
	v_ashrrev_i32_e32 v27, 31, v26
	s_waitcnt lgkmcnt(0)
	v_cvt_pk_bf16_f32 v22, v14, v15
	ds_read2_b32 v[14:15], v11 offset0:90 offset1:123
	v_lshlrev_b64 v[26:27], 11, v[26:27]
	s_waitcnt lgkmcnt(0)
	v_cvt_pk_bf16_f32 v23, v14, v15
	ds_read2_b32 v[14:15], v11 offset0:156 offset1:189
	v_lshl_add_u64 v[26:27], v[28:29], 0, v[26:27]
	s_waitcnt lgkmcnt(0)
	v_cvt_pk_bf16_f32 v24, v14, v15
	ds_read2_b32 v[14:15], v11 offset0:222 offset1:255
	s_waitcnt lgkmcnt(0)
	v_cvt_pk_bf16_f32 v25, v14, v15
	global_store_dwordx4 v[26:27], v[22:25], off
	s_waitcnt lgkmcnt(0)
	s_add_i32 s14, s14, s28
	s_cmpk_lt_i32 s14, 0x200
	s_cbranch_scc1 .LBB0_54

; #define LAS __attribute__((address_space(3)))
; __device__ __forceinline__ void tr_item(const float* W, int ldw, int col0, const float* kscale, bf16_t* WT, int K, int row0, LAS float* scr, int item, int nblk, int lane) {
;     const int kb = item / nblk, nb = item % nblk, k0 = 64 * kb, n0 = 32 * nb;
; #pragma unroll 8
;     for (int i = 0; i < 32; ++i) { const int kk = 2 * i + (lane >> 5); float v = W[(size_t)(k0 + kk) * ldw + col0 + n0 + (lane & 31)]; if (kscale) v *= kscale[k0 + kk]; scr[kk * 33 + (lane & 31)] = v; }
.LBB0_60:
	s_lshl_b32 s15, s14, 1
	s_lshl_b32 s20, s5, 1
	v_or_b32_e32 v24, s20, v16
	s_add_i32 s21, s15, 4
	s_add_i32 s22, s20, 4
	s_add_i32 s23, s15, 8
	s_add_i32 s24, s20, 8
	s_add_i32 s25, s15, 12
	s_add_i32 s36, s20, 12
	s_add_i32 s37, s15, 16
	s_add_i32 s40, s20, 16
	s_add_i32 s41, s15, 20
	s_add_i32 s42, s20, 20
	s_add_i32 s43, s15, 24
	s_add_i32 s44, s20, 24
	s_add_i32 s45, s15, 28
	s_add_i32 s46, s20, 28
	v_or_b32_e32 v22, s15, v3
	v_ashrrev_i32_e32 v25, 31, v24
	v_or_b32_e32 v26, s21, v3
	v_or_b32_e32 v28, s22, v16
	v_or_b32_e32 v30, s23, v3
	v_or_b32_e32 v32, s24, v16
	v_or_b32_e32 v34, s25, v3
	v_or_b32_e32 v36, s36, v16
	v_or_b32_e32 v38, s37, v3
	v_or_b32_e32 v40, s40, v16
	v_or_b32_e32 v42, s41, v3
	v_or_b32_e32 v44, s42, v16
	v_or_b32_e32 v50, s43, v3
	v_or_b32_e32 v52, s44, v16
	v_or_b32_e32 v54, s45, v3
	v_or_b32_e32 v56, s46, v16
	v_ashrrev_i32_e32 v23, 31, v22
	v_lshlrev_b64 v[24:25], 12, v[24:25]
	v_ashrrev_i32_e32 v29, 31, v28
	v_ashrrev_i32_e32 v27, 31, v26
	v_ashrrev_i32_e32 v33, 31, v32
	v_ashrrev_i32_e32 v31, 31, v30
	v_ashrrev_i32_e32 v37, 31, v36
	v_ashrrev_i32_e32 v35, 31, v34
	v_ashrrev_i32_e32 v41, 31, v40
	v_ashrrev_i32_e32 v39, 31, v38
	v_ashrrev_i32_e32 v45, 31, v44
	v_ashrrev_i32_e32 v43, 31, v42
	v_ashrrev_i32_e32 v53, 31, v52
	v_ashrrev_i32_e32 v51, 31, v50
	v_ashrrev_i32_e32 v57, 31, v56
	v_ashrrev_i32_e32 v55, 31, v54
	v_lshlrev_b64 v[22:23], 12, v[22:23]
	v_lshl_add_u64 v[24:25], v[14:15], 0, v[24:25]
	v_lshlrev_b64 v[26:27], 12, v[26:27]
	v_lshlrev_b64 v[28:29], 12, v[28:29]
	v_lshlrev_b64 v[30:31], 12, v[30:31]
	v_lshlrev_b64 v[32:33], 12, v[32:33]
	v_lshlrev_b64 v[34:35], 12, v[34:35]
	v_lshlrev_b64 v[36:37], 12, v[36:37]
	v_lshlrev_b64 v[38:39], 12, v[38:39]
	v_lshlrev_b64 v[40:41], 12, v[40:41]
	v_lshlrev_b64 v[42:43], 12, v[42:43]
	v_lshlrev_b64 v[44:45], 12, v[44:45]
	v_lshlrev_b64 v[50:51], 12, v[50:51]
	v_lshlrev_b64 v[52:53], 12, v[52:53]
	v_lshlrev_b64 v[54:55], 12, v[54:55]
	v_lshlrev_b64 v[56:57], 12, v[56:57]
	v_lshl_add_u64 v[22:23], v[14:15], 0, v[22:23]
	v_lshl_add_u64 v[28:29], v[14:15], 0, v[28:29]
	v_lshl_add_u64 v[26:27], v[14:15], 0, v[26:27]
	v_lshl_add_u64 v[32:33], v[14:15], 0, v[32:33]
	v_lshl_add_u64 v[30:31], v[14:15], 0, v[30:31]
	v_lshl_add_u64 v[36:37], v[14:15], 0, v[36:37]
	v_lshl_add_u64 v[34:35], v[14:15], 0, v[34:35]
	v_lshl_add_u64 v[40:41], v[14:15], 0, v[40:41]
	v_lshl_add_u64 v[38:39], v[14:15], 0, v[38:39]
	v_lshl_add_u64 v[44:45], v[14:15], 0, v[44:45]
	v_lshl_add_u64 v[42:43], v[14:15], 0, v[42:43]
	v_lshl_add_u64 v[52:53], v[14:15], 0, v[52:53]
	v_lshl_add_u64 v[50:51], v[14:15], 0, v[50:51]
	v_lshl_add_u64 v[56:57], v[14:15], 0, v[56:57]
	v_lshl_add_u64 v[54:55], v[14:15], 0, v[54:55]
	global_load_dword v21, v[24:25], off
	global_load_dword v46, v[22:23], off
	global_load_dword v48, v[28:29], off
	global_load_dword v58, v[26:27], off
	global_load_dword v59, v[32:33], off
	global_load_dword v60, v[30:31], off
	global_load_dword v61, v[36:37], off
	global_load_dword v62, v[34:35], off
	global_load_dword v63, v[40:41], off
	global_load_dword v64, v[38:39], off
	global_load_dword v65, v[44:45], off
	global_load_dword v66, v[42:43], off
	global_load_dword v67, v[52:53], off
	global_load_dword v68, v[50:51], off
	global_load_dword v69, v[56:57], off
	global_load_dword v70, v[54:55], off
	v_or_b32_e32 v24, s15, v1
	v_or_b32_e32 v22, s20, v6
	s_add_i32 s5, s5, 16
	s_add_i32 s14, s14, 16
	s_add_i32 s1, s1, -16
	v_mad_u64_u32 v[22:23], s[38:39], v22, s7, v[10:11]
	v_mad_u64_u32 v[24:25], s[38:39], v24, s7, v[10:11]
	v_or_b32_e32 v23, s21, v1
	v_or_b32_e32 v25, s22, v6
	v_or_b32_e32 v32, s23, v1
	v_or_b32_e32 v30, s24, v6
	v_or_b32_e32 v36, s25, v1
	v_or_b32_e32 v34, s36, v6
	v_or_b32_e32 v40, s37, v1
	v_or_b32_e32 v38, s40, v6
	v_or_b32_e32 v44, s41, v1
	v_or_b32_e32 v42, s42, v6
	v_or_b32_e32 v52, s43, v1
	v_or_b32_e32 v50, s44, v6
	v_or_b32_e32 v56, s45, v1
	v_or_b32_e32 v54, s46, v6
	s_cmp_lg_u32 s1, 0
	v_mad_u64_u32 v[26:27], s[20:21], v25, s7, v[10:11]
	v_mad_u64_u32 v[28:29], s[20:21], v23, s7, v[10:11]
	v_mad_u64_u32 v[30:31], s[20:21], v30, s7, v[10:11]
	v_mad_u64_u32 v[32:33], s[20:21], v32, s7, v[10:11]
	v_mad_u64_u32 v[34:35], s[20:21], v34, s7, v[10:11]
	v_mad_u64_u32 v[36:37], s[20:21], v36, s7, v[10:11]
	v_mad_u64_u32 v[38:39], s[20:21], v38, s7, v[10:11]
	v_mad_u64_u32 v[40:41], s[20:21], v40, s7, v[10:11]
	v_mad_u64_u32 v[42:43], s[20:21], v42, s7, v[10:11]
	v_mad_u64_u32 v[44:45], s[20:21], v44, s7, v[10:11]
	v_mad_u64_u32 v[50:51], s[20:21], v50, s7, v[10:11]
	v_mad_u64_u32 v[52:53], s[20:21], v52, s7, v[10:11]
	v_mad_u64_u32 v[54:55], s[20:21], v54, s7, v[10:11]
	v_mad_u64_u32 v[56:57], s[20:21], v56, s7, v[10:11]
	s_waitcnt vmcnt(15)
	ds_write_b32 v22, v21
	s_waitcnt vmcnt(14)
	ds_write_b32 v24, v46
	s_waitcnt vmcnt(13)
	ds_write_b32 v26, v48
	s_waitcnt vmcnt(12)
	ds_write_b32 v28, v58
	s_waitcnt vmcnt(11)
	ds_write_b32 v30, v59
	s_waitcnt vmcnt(10)
	ds_write_b32 v32, v60
	s_waitcnt vmcnt(9)
	ds_write_b32 v34, v61
	s_waitcnt vmcnt(8)
	ds_write_b32 v36, v62
	s_waitcnt vmcnt(7)
	ds_write_b32 v38, v63
	s_waitcnt vmcnt(6)
	ds_write_b32 v40, v64
	s_waitcnt vmcnt(5)
	ds_write_b32 v42, v65
	s_waitcnt vmcnt(4)
	ds_write_b32 v44, v66
	s_waitcnt vmcnt(3)
	ds_write_b32 v50, v67
	s_waitcnt vmcnt(2)
	ds_write_b32 v52, v68
	s_waitcnt vmcnt(1)
	ds_write_b32 v54, v69
	s_waitcnt vmcnt(0)
	ds_write_b32 v56, v70
	s_cbranch_scc1 .LBB0_60
; __device__ __forceinline__ unsigned cvt_pk_bf16(float lo, float hi) { unsigned r; asm volatile("s_nop 0\n\tv_cvt_pk_bf16_f32 %0, %1, %2\n\ts_nop 1" : "=v"(r) : "v"(lo), "v"(hi)); return r; }
; #define LAS __attribute__((address_space(3)))
; #define LDS_FENCE() asm volatile("s_waitcnt lgkmcnt(0)" ::: "memory")
; __device__ __forceinline__ void tr_item(const float* W, int ldw, int col0, const float* kscale, bf16_t* WT, int K, int row0, LAS float* scr, int item, int nblk, int lane) {
;     ...
;     LDS_FENCE();
;     const int c = lane & 7;
; #pragma unroll
;     for (int j = 0; j < 4; ++j) { const int n = (lane >> 3) + 8 * j; const LAS float* s = scr + (8 * c) * 33 + n;
;         u32x4 o; o.x = cvt_pk_bf16(s[0 * 33], s[1 * 33]); o.y = cvt_pk_bf16(s[2 * 33], s[3 * 33]); o.z = cvt_pk_bf16(s[4 * 33], s[5 * 33]); o.w = cvt_pk_bf16(s[6 * 33], s[7 * 33]);
;         *(u32x4*)(WT + (size_t)(row0 + n0 + n) * K + k0 + 8 * c) = o; }
;     LDS_FENCE();
	s_waitcnt lgkmcnt(0)
	v_or_b32_e32 v26, s0, v7
	ds_read2_b32 v[14:15], v11 offset1:33
	s_ashr_i32 s5, s4, 31
	v_ashrrev_i32_e32 v27, 31, v26
	s_waitcnt lgkmcnt(0)
	v_cvt_pk_bf16_f32 v22, v14, v15
	ds_read2_b32 v[14:15], v11 offset0:66 offset1:99
	v_lshl_add_u64 v[28:29], s[4:5], 1, v[12:13]
	v_lshlrev_b64 v[26:27], 11, v[26:27]
	s_waitcnt lgkmcnt(0)
	v_cvt_pk_bf16_f32 v23, v14, v15
	ds_read2_b32 v[14:15], v11 offset0:132 offset1:165
	v_lshl_add_u64 v[26:27], v[28:29], 0, v[26:27]
	s_waitcnt lgkmcnt(0)
	v_cvt_pk_bf16_f32 v24, v14, v15
	ds_read2_b32 v[14:15], v11 offset0:198 offset1:231
	s_waitcnt lgkmcnt(0)
	v_cvt_pk_bf16_f32 v25, v14, v15
	global_store_dwordx4 v[26:27], v[22:25], off
	v_or_b32_e32 v26, s0, v17
	ds_read2_b32 v[14:15], v11 offset0:8 offset1:41
	v_ashrrev_i32_e32 v27, 31, v26
	s_waitcnt lgkmcnt(0)
	v_cvt_pk_bf16_f32 v22, v14, v15
	ds_read2_b32 v[14:15], v11 offset0:74 offset1:107
	v_lshlrev_b64 v[26:27], 11, v[26:27]
	s_waitcnt lgkmcnt(0)
	v_cvt_pk_bf16_f32 v23, v14, v15
	ds_read2_b32 v[14:15], v11 offset0:140 offset1:173
	v_lshl_add_u64 v[26:27], v[28:29], 0, v[26:27]
	s_waitcnt lgkmcnt(0)
	v_cvt_pk_bf16_f32 v24, v14, v15
	ds_read2_b32 v[14:15], v11 offset0:206 offset1:239
	s_waitcnt lgkmcnt(0)
	v_cvt_pk_bf16_f32 v25, v14, v15
	global_store_dwordx4 v[26:27], v[22:25], off
	v_or_b32_e32 v26, s0, v18
	ds_read2_b32 v[14:15], v11 offset0:16 offset1:49
	v_ashrrev_i32_e32 v27, 31, v26
	s_waitcnt lgkmcnt(0)
	v_cvt_pk_bf16_f32 v22, v14, v15
	ds_read2_b32 v[14:15], v11 offset0:82 offset1:115
	v_lshlrev_b64 v[26:27], 11, v[26:27]
	s_waitcnt lgkmcnt(0)
	v_cvt_pk_bf16_f32 v23, v14, v15
	ds_read2_b32 v[14:15], v11 offset0:148 offset1:181
	v_lshl_add_u64 v[26:27], v[28:29], 0, v[26:27]
	s_waitcnt lgkmcnt(0)
	v_cvt_pk_bf16_f32 v24, v14, v15
	ds_read2_b32 v[14:15], v11 offset0:214 offset1:247
	s_waitcnt lgkmcnt(0)
	v_cvt_pk_bf16_f32 v25, v14, v15
	global_store_dwordx4 v[26:27], v[22:25], off
	v_or_b32_e32 v26, s0, v19
	ds_read2_b32 v[14:15], v11 offset0:24 offset1:57
	v_ashrrev_i32_e32 v27, 31, v26
	s_waitcnt lgkmcnt(0)
	v_cvt_pk_bf16_f32 v22, v14, v15
	ds_read2_b32 v[14:15], v11 offset0:90 offset1:123
	v_lshlrev_b64 v[26:27], 11, v[26:27]
	s_waitcnt lgkmcnt(0)
	v_cvt_pk_bf16_f32 v23, v14, v15
	ds_read2_b32 v[14:15], v11 offset0:156 offset1:189
	v_lshl_add_u64 v[26:27], v[28:29], 0, v[26:27]
	s_waitcnt lgkmcnt(0)
	v_cvt_pk_bf16_f32 v24, v14, v15
	ds_read2_b32 v[14:15], v11 offset0:222 offset1:255
	s_waitcnt lgkmcnt(0)
	v_cvt_pk_bf16_f32 v25, v14, v15
	global_store_dwordx4 v[26:27], v[22:25], off
	s_waitcnt lgkmcnt(0)
	s_add_i32 s6, s6, s28
	s_cmpk_lt_i32 s6, 0x200
	s_cbranch_scc1 .LBB0_59

; #define LAS __attribute__((address_space(3)))
; __device__ __forceinline__ void tr_item(const float* W, int ldw, int col0, const float* kscale, bf16_t* WT, int K, int row0, LAS float* scr, int item, int nblk, int lane) {
;     const int kb = item / nblk, nb = item % nblk, k0 = 64 * kb, n0 = 32 * nb;
; #pragma unroll 8
;     for (int i = 0; i < 32; ++i) { const int kk = 2 * i + (lane >> 5); float v = W[(size_t)(k0 + kk) * ldw + col0 + n0 + (lane & 31)]; if (kscale) v *= kscale[k0 + kk]; scr[kk * 33 + (lane & 31)] = v; }
.LBB0_65:
	s_lshl_b32 s15, s14, 1
	s_lshl_b32 s20, s5, 1
	v_or_b32_e32 v24, s20, v16
	s_add_i32 s21, s15, 4
	s_add_i32 s22, s20, 4
	s_add_i32 s23, s15, 8
	s_add_i32 s24, s20, 8
	s_add_i32 s25, s15, 12
	s_add_i32 s36, s20, 12
	s_add_i32 s37, s15, 16
	s_add_i32 s40, s20, 16
	s_add_i32 s41, s15, 20
	s_add_i32 s42, s20, 20
	s_add_i32 s43, s15, 24
	s_add_i32 s44, s20, 24
	s_add_i32 s45, s15, 28
	s_add_i32 s46, s20, 28
	v_or_b32_e32 v22, s15, v3
	v_ashrrev_i32_e32 v25, 31, v24
	v_or_b32_e32 v26, s21, v3
	v_or_b32_e32 v28, s22, v16
	v_or_b32_e32 v30, s23, v3
	v_or_b32_e32 v32, s24, v16
	v_or_b32_e32 v34, s25, v3
	v_or_b32_e32 v36, s36, v16
	v_or_b32_e32 v38, s37, v3
	v_or_b32_e32 v40, s40, v16
	v_or_b32_e32 v42, s41, v3
	v_or_b32_e32 v44, s42, v16
	v_or_b32_e32 v50, s43, v3
	v_or_b32_e32 v52, s44, v16
	v_or_b32_e32 v54, s45, v3
	v_or_b32_e32 v56, s46, v16
	v_ashrrev_i32_e32 v23, 31, v22
	v_lshlrev_b64 v[24:25], 14, v[24:25]
	v_ashrrev_i32_e32 v29, 31, v28
	v_ashrrev_i32_e32 v27, 31, v26
	v_ashrrev_i32_e32 v33, 31, v32
	v_ashrrev_i32_e32 v31, 31, v30
	v_ashrrev_i32_e32 v37, 31, v36
	v_ashrrev_i32_e32 v35, 31, v34
	v_ashrrev_i32_e32 v41, 31, v40
	v_ashrrev_i32_e32 v39, 31, v38
	v_ashrrev_i32_e32 v45, 31, v44
	v_ashrrev_i32_e32 v43, 31, v42
	v_ashrrev_i32_e32 v53, 31, v52
	v_ashrrev_i32_e32 v51, 31, v50
	v_ashrrev_i32_e32 v57, 31, v56
	v_ashrrev_i32_e32 v55, 31, v54
	v_lshlrev_b64 v[22:23], 14, v[22:23]
	v_lshl_add_u64 v[24:25], v[14:15], 0, v[24:25]
	v_lshlrev_b64 v[26:27], 14, v[26:27]
	v_lshlrev_b64 v[28:29], 14, v[28:29]
	v_lshlrev_b64 v[30:31], 14, v[30:31]
	v_lshlrev_b64 v[32:33], 14, v[32:33]
	v_lshlrev_b64 v[34:35], 14, v[34:35]
	v_lshlrev_b64 v[36:37], 14, v[36:37]
	v_lshlrev_b64 v[38:39], 14, v[38:39]
	v_lshlrev_b64 v[40:41], 14, v[40:41]
	v_lshlrev_b64 v[42:43], 14, v[42:43]
	v_lshlrev_b64 v[44:45], 14, v[44:45]
	v_lshlrev_b64 v[50:51], 14, v[50:51]
	v_lshlrev_b64 v[52:53], 14, v[52:53]
	v_lshlrev_b64 v[54:55], 14, v[54:55]
	v_lshlrev_b64 v[56:57], 14, v[56:57]
	v_lshl_add_u64 v[22:23], v[14:15], 0, v[22:23]
	v_lshl_add_u64 v[28:29], v[14:15], 0, v[28:29]
	v_lshl_add_u64 v[26:27], v[14:15], 0, v[26:27]
	v_lshl_add_u64 v[32:33], v[14:15], 0, v[32:33]
	v_lshl_add_u64 v[30:31], v[14:15], 0, v[30:31]
	v_lshl_add_u64 v[36:37], v[14:15], 0, v[36:37]
	v_lshl_add_u64 v[34:35], v[14:15], 0, v[34:35]
	v_lshl_add_u64 v[40:41], v[14:15], 0, v[40:41]
	v_lshl_add_u64 v[38:39], v[14:15], 0, v[38:39]
	v_lshl_add_u64 v[44:45], v[14:15], 0, v[44:45]
	v_lshl_add_u64 v[42:43], v[14:15], 0, v[42:43]
	v_lshl_add_u64 v[52:53], v[14:15], 0, v[52:53]
	v_lshl_add_u64 v[50:51], v[14:15], 0, v[50:51]
	v_lshl_add_u64 v[56:57], v[14:15], 0, v[56:57]
	v_lshl_add_u64 v[54:55], v[14:15], 0, v[54:55]
	global_load_dword v21, v[24:25], off
	global_load_dword v46, v[22:23], off
	global_load_dword v48, v[28:29], off
	global_load_dword v58, v[26:27], off
	global_load_dword v59, v[32:33], off
	global_load_dword v60, v[30:31], off
	global_load_dword v61, v[36:37], off
	global_load_dword v62, v[34:35], off
	global_load_dword v63, v[40:41], off
	global_load_dword v64, v[38:39], off
	global_load_dword v65, v[44:45], off
	global_load_dword v66, v[42:43], off
	global_load_dword v67, v[52:53], off
	global_load_dword v68, v[50:51], off
	global_load_dword v69, v[56:57], off
	global_load_dword v70, v[54:55], off
	v_or_b32_e32 v24, s15, v1
	v_or_b32_e32 v22, s20, v6
	s_add_i32 s5, s5, 16
	s_add_i32 s14, s14, 16
	s_add_i32 s1, s1, -16
	v_mad_u64_u32 v[22:23], s[38:39], v22, s7, v[10:11]
	v_mad_u64_u32 v[24:25], s[38:39], v24, s7, v[10:11]
	v_or_b32_e32 v23, s21, v1
	v_or_b32_e32 v25, s22, v6
	v_or_b32_e32 v32, s23, v1
	v_or_b32_e32 v30, s24, v6
	v_or_b32_e32 v36, s25, v1
	v_or_b32_e32 v34, s36, v6
	v_or_b32_e32 v40, s37, v1
	v_or_b32_e32 v38, s40, v6
	v_or_b32_e32 v44, s41, v1
	v_or_b32_e32 v42, s42, v6
	v_or_b32_e32 v52, s43, v1
	v_or_b32_e32 v50, s44, v6
	v_or_b32_e32 v56, s45, v1
	v_or_b32_e32 v54, s46, v6
	s_cmp_lg_u32 s1, 0
	v_mad_u64_u32 v[26:27], s[20:21], v25, s7, v[10:11]
	v_mad_u64_u32 v[28:29], s[20:21], v23, s7, v[10:11]
	v_mad_u64_u32 v[30:31], s[20:21], v30, s7, v[10:11]
	v_mad_u64_u32 v[32:33], s[20:21], v32, s7, v[10:11]
	v_mad_u64_u32 v[34:35], s[20:21], v34, s7, v[10:11]
	v_mad_u64_u32 v[36:37], s[20:21], v36, s7, v[10:11]
	v_mad_u64_u32 v[38:39], s[20:21], v38, s7, v[10:11]
	v_mad_u64_u32 v[40:41], s[20:21], v40, s7, v[10:11]
	v_mad_u64_u32 v[42:43], s[20:21], v42, s7, v[10:11]
	v_mad_u64_u32 v[44:45], s[20:21], v44, s7, v[10:11]
	v_mad_u64_u32 v[50:51], s[20:21], v50, s7, v[10:11]
	v_mad_u64_u32 v[52:53], s[20:21], v52, s7, v[10:11]
	v_mad_u64_u32 v[54:55], s[20:21], v54, s7, v[10:11]
	v_mad_u64_u32 v[56:57], s[20:21], v56, s7, v[10:11]
	s_waitcnt vmcnt(15)
	ds_write_b32 v22, v21
	s_waitcnt vmcnt(14)
	ds_write_b32 v24, v46
	s_waitcnt vmcnt(13)
	ds_write_b32 v26, v48
	s_waitcnt vmcnt(12)
	ds_write_b32 v28, v58
	s_waitcnt vmcnt(11)
	ds_write_b32 v30, v59
	s_waitcnt vmcnt(10)
	ds_write_b32 v32, v60
	s_waitcnt vmcnt(9)
	ds_write_b32 v34, v61
	s_waitcnt vmcnt(8)
	ds_write_b32 v36, v62
	s_waitcnt vmcnt(7)
	ds_write_b32 v38, v63
	s_waitcnt vmcnt(6)
	ds_write_b32 v40, v64
	s_waitcnt vmcnt(5)
	ds_write_b32 v42, v65
	s_waitcnt vmcnt(4)
	ds_write_b32 v44, v66
	s_waitcnt vmcnt(3)
	ds_write_b32 v50, v67
	s_waitcnt vmcnt(2)
	ds_write_b32 v52, v68
	s_waitcnt vmcnt(1)
	ds_write_b32 v54, v69
	s_waitcnt vmcnt(0)
	ds_write_b32 v56, v70
	s_cbranch_scc1 .LBB0_65
; __device__ __forceinline__ unsigned cvt_pk_bf16(float lo, float hi) { unsigned r; asm volatile("s_nop 0\n\tv_cvt_pk_bf16_f32 %0, %1, %2\n\ts_nop 1" : "=v"(r) : "v"(lo), "v"(hi)); return r; }
; #define LAS __attribute__((address_space(3)))
; #define LDS_FENCE() asm volatile("s_waitcnt lgkmcnt(0)" ::: "memory")
; __device__ __forceinline__ void tr_item(const float* W, int ldw, int col0, const float* kscale, bf16_t* WT, int K, int row0, LAS float* scr, int item, int nblk, int lane) {
;     ...
;     LDS_FENCE();
;     const int c = lane & 7;
; #pragma unroll
;     for (int j = 0; j < 4; ++j) { const int n = (lane >> 3) + 8 * j; const LAS float* s = scr + (8 * c) * 33 + n;
;         u32x4 o; o.x = cvt_pk_bf16(s[0 * 33], s[1 * 33]); o.y = cvt_pk_bf16(s[2 * 33], s[3 * 33]); o.z = cvt_pk_bf16(s[4 * 33], s[5 * 33]); o.w = cvt_pk_bf16(s[6 * 33], s[7 * 33]);
;         *(u32x4*)(WT + (size_t)(row0 + n0 + n) * K + k0 + 8 * c) = o; }
;     LDS_FENCE();
	s_waitcnt lgkmcnt(0)
	v_or_b32_e32 v26, s0, v7
	ds_read2_b32 v[14:15], v11 offset1:33
	s_ashr_i32 s5, s4, 31
	v_ashrrev_i32_e32 v27, 31, v26
	s_waitcnt lgkmcnt(0)
	v_cvt_pk_bf16_f32 v22, v14, v15
	ds_read2_b32 v[14:15], v11 offset0:66 offset1:99
	v_lshl_add_u64 v[28:29], s[4:5], 1, v[12:13]
	v_lshlrev_b64 v[26:27], 11, v[26:27]
	s_waitcnt lgkmcnt(0)
	v_cvt_pk_bf16_f32 v23, v14, v15
	ds_read2_b32 v[14:15], v11 offset0:132 offset1:165
	v_lshl_add_u64 v[26:27], v[28:29], 0, v[26:27]
	s_waitcnt lgkmcnt(0)
	v_cvt_pk_bf16_f32 v24, v14, v15
	ds_read2_b32 v[14:15], v11 offset0:198 offset1:231
	s_waitcnt lgkmcnt(0)
	v_cvt_pk_bf16_f32 v25, v14, v15
	global_store_dwordx4 v[26:27], v[22:25], off
	v_or_b32_e32 v26, s0, v17
	ds_read2_b32 v[14:15], v11 offset0:8 offset1:41
	v_ashrrev_i32_e32 v27, 31, v26
	s_waitcnt lgkmcnt(0)
	v_cvt_pk_bf16_f32 v22, v14, v15
	ds_read2_b32 v[14:15], v11 offset0:74 offset1:107
	v_lshlrev_b64 v[26:27], 11, v[26:27]
	s_waitcnt lgkmcnt(0)
	v_cvt_pk_bf16_f32 v23, v14, v15
	ds_read2_b32 v[14:15], v11 offset0:140 offset1:173
	v_lshl_add_u64 v[26:27], v[28:29], 0, v[26:27]
	s_waitcnt lgkmcnt(0)
	v_cvt_pk_bf16_f32 v24, v14, v15
	ds_read2_b32 v[14:15], v11 offset0:206 offset1:239
	s_waitcnt lgkmcnt(0)
	v_cvt_pk_bf16_f32 v25, v14, v15
	global_store_dwordx4 v[26:27], v[22:25], off
	v_or_b32_e32 v26, s0, v18
	ds_read2_b32 v[14:15], v11 offset0:16 offset1:49
	v_ashrrev_i32_e32 v27, 31, v26
	s_waitcnt lgkmcnt(0)
	v_cvt_pk_bf16_f32 v22, v14, v15
	ds_read2_b32 v[14:15], v11 offset0:82 offset1:115
	v_lshlrev_b64 v[26:27], 11, v[26:27]
	s_waitcnt lgkmcnt(0)
	v_cvt_pk_bf16_f32 v23, v14, v15
	ds_read2_b32 v[14:15], v11 offset0:148 offset1:181
	v_lshl_add_u64 v[26:27], v[28:29], 0, v[26:27]
	s_waitcnt lgkmcnt(0)
	v_cvt_pk_bf16_f32 v24, v14, v15
	ds_read2_b32 v[14:15], v11 offset0:214 offset1:247
	s_waitcnt lgkmcnt(0)
	v_cvt_pk_bf16_f32 v25, v14, v15
	global_store_dwordx4 v[26:27], v[22:25], off
	v_or_b32_e32 v26, s0, v19
	ds_read2_b32 v[14:15], v11 offset0:24 offset1:57
	v_ashrrev_i32_e32 v27, 31, v26
	s_waitcnt lgkmcnt(0)
	v_cvt_pk_bf16_f32 v22, v14, v15
	ds_read2_b32 v[14:15], v11 offset0:90 offset1:123
	v_lshlrev_b64 v[26:27], 11, v[26:27]
	s_waitcnt lgkmcnt(0)
	v_cvt_pk_bf16_f32 v23, v14, v15
	ds_read2_b32 v[14:15], v11 offset0:156 offset1:189
	v_lshl_add_u64 v[26:27], v[28:29], 0, v[26:27]
	s_waitcnt lgkmcnt(0)
	v_cvt_pk_bf16_f32 v24, v14, v15
	ds_read2_b32 v[14:15], v11 offset0:222 offset1:255
	s_waitcnt lgkmcnt(0)
	v_cvt_pk_bf16_f32 v25, v14, v15
	global_store_dwordx4 v[26:27], v[22:25], off
	s_waitcnt lgkmcnt(0)
	s_add_i32 s6, s6, s28
	s_cmpk_lt_i32 s6, 0x800
	s_cbranch_scc1 .LBB0_64

; #define LAS __attribute__((address_space(3)))
; __device__ __forceinline__ void tr_item(const float* W, int ldw, int col0, const float* kscale, bf16_t* WT, int K, int row0, LAS float* scr, int item, int nblk, int lane) {
;     const int kb = item / nblk, nb = item % nblk, k0 = 64 * kb, n0 = 32 * nb;
; #pragma unroll 8
;     for (int i = 0; i < 32; ++i) { const int kk = 2 * i + (lane >> 5); float v = W[(size_t)(k0 + kk) * ldw + col0 + n0 + (lane & 31)]; if (kscale) v *= kscale[k0 + kk]; scr[kk * 33 + (lane & 31)] = v; }
.LBB0_72:
	s_lshl_b32 s15, s5, 1
	s_lshl_b32 s20, s14, 1
	v_or_b32_e32 v30, s20, v20
	s_add_i32 s21, s15, 4
	s_add_i32 s22, s20, 4
	s_add_i32 s23, s15, 8
	s_add_i32 s24, s20, 8
	s_add_i32 s25, s15, 12
	s_add_i32 s36, s20, 12
	s_add_i32 s37, s15, 16
	s_add_i32 s40, s20, 16
	s_add_i32 s41, s15, 20
	s_add_i32 s42, s20, 20
	s_add_i32 s43, s15, 24
	s_add_i32 s44, s20, 24
	s_add_i32 s45, s15, 28
	s_add_i32 s46, s20, 28
	v_or_b32_e32 v28, s15, v3
	v_ashrrev_i32_e32 v31, 31, v30
	v_or_b32_e32 v32, s21, v3
	v_or_b32_e32 v34, s22, v20
	v_or_b32_e32 v36, s23, v3
	v_or_b32_e32 v38, s24, v20
	v_or_b32_e32 v40, s25, v3
	v_or_b32_e32 v42, s36, v20
	v_or_b32_e32 v44, s37, v3
	v_or_b32_e32 v50, s40, v20
	v_or_b32_e32 v52, s41, v3
	v_or_b32_e32 v54, s42, v20
	v_or_b32_e32 v56, s43, v3
	v_or_b32_e32 v58, s44, v20
	v_or_b32_e32 v60, s45, v3
	v_or_b32_e32 v62, s46, v20
	v_ashrrev_i32_e32 v29, 31, v28
	v_lshlrev_b64 v[30:31], 12, v[30:31]
	v_ashrrev_i32_e32 v35, 31, v34
	v_ashrrev_i32_e32 v33, 31, v32
	v_ashrrev_i32_e32 v39, 31, v38
	v_ashrrev_i32_e32 v37, 31, v36
	v_ashrrev_i32_e32 v43, 31, v42
	v_ashrrev_i32_e32 v41, 31, v40
	v_ashrrev_i32_e32 v51, 31, v50
	v_ashrrev_i32_e32 v45, 31, v44
	v_ashrrev_i32_e32 v55, 31, v54
	v_ashrrev_i32_e32 v53, 31, v52
	v_ashrrev_i32_e32 v59, 31, v58
	v_ashrrev_i32_e32 v57, 31, v56
	v_ashrrev_i32_e32 v63, 31, v62
	v_ashrrev_i32_e32 v61, 31, v60
	v_lshlrev_b64 v[28:29], 12, v[28:29]
	v_lshl_add_u64 v[30:31], v[18:19], 0, v[30:31]
	v_lshlrev_b64 v[32:33], 12, v[32:33]
	v_lshlrev_b64 v[34:35], 12, v[34:35]
	v_lshlrev_b64 v[36:37], 12, v[36:37]
	v_lshlrev_b64 v[38:39], 12, v[38:39]
	v_lshlrev_b64 v[40:41], 12, v[40:41]
	v_lshlrev_b64 v[42:43], 12, v[42:43]
	v_lshlrev_b64 v[44:45], 12, v[44:45]
	v_lshlrev_b64 v[50:51], 12, v[50:51]
	v_lshlrev_b64 v[52:53], 12, v[52:53]
	v_lshlrev_b64 v[54:55], 12, v[54:55]
	v_lshlrev_b64 v[56:57], 12, v[56:57]
	v_lshlrev_b64 v[58:59], 12, v[58:59]
	v_lshlrev_b64 v[60:61], 12, v[60:61]
	v_lshlrev_b64 v[62:63], 12, v[62:63]
	v_lshl_add_u64 v[28:29], v[18:19], 0, v[28:29]
	v_lshl_add_u64 v[34:35], v[18:19], 0, v[34:35]
	v_lshl_add_u64 v[32:33], v[18:19], 0, v[32:33]
	v_lshl_add_u64 v[38:39], v[18:19], 0, v[38:39]
	v_lshl_add_u64 v[36:37], v[18:19], 0, v[36:37]
	v_lshl_add_u64 v[42:43], v[18:19], 0, v[42:43]
	v_lshl_add_u64 v[40:41], v[18:19], 0, v[40:41]
	v_lshl_add_u64 v[50:51], v[18:19], 0, v[50:51]
	v_lshl_add_u64 v[44:45], v[18:19], 0, v[44:45]
	v_lshl_add_u64 v[54:55], v[18:19], 0, v[54:55]
	v_lshl_add_u64 v[52:53], v[18:19], 0, v[52:53]
	v_lshl_add_u64 v[58:59], v[18:19], 0, v[58:59]
	v_lshl_add_u64 v[56:57], v[18:19], 0, v[56:57]
	v_lshl_add_u64 v[62:63], v[18:19], 0, v[62:63]
	v_lshl_add_u64 v[60:61], v[18:19], 0, v[60:61]
	global_load_dword v9, v[30:31], off
	global_load_dword v22, v[28:29], off
	global_load_dword v24, v[34:35], off
	global_load_dword v26, v[32:33], off
	global_load_dword v46, v[38:39], off
	global_load_dword v48, v[36:37], off
	global_load_dword v64, v[42:43], off
	global_load_dword v65, v[40:41], off
	global_load_dword v66, v[50:51], off
	global_load_dword v67, v[44:45], off
	global_load_dword v68, v[54:55], off
	global_load_dword v69, v[52:53], off
	global_load_dword v70, v[58:59], off
	global_load_dword v71, v[56:57], off
	global_load_dword v72, v[62:63], off
	global_load_dword v73, v[60:61], off
	v_or_b32_e32 v30, s15, v1
	v_or_b32_e32 v28, s20, v4
	s_add_i32 s14, s14, 16
	s_add_i32 s5, s5, 16
	s_add_i32 s1, s1, -16
	v_mad_u64_u32 v[28:29], s[38:39], v28, s7, v[14:15]
	v_mad_u64_u32 v[30:31], s[38:39], v30, s7, v[14:15]
	v_or_b32_e32 v29, s21, v1
	v_or_b32_e32 v31, s22, v4
	v_or_b32_e32 v38, s23, v1
	v_or_b32_e32 v36, s24, v4
	v_or_b32_e32 v42, s25, v1
	v_or_b32_e32 v40, s36, v4
	v_or_b32_e32 v50, s37, v1
	v_or_b32_e32 v44, s40, v4
	v_or_b32_e32 v54, s41, v1
	v_or_b32_e32 v52, s42, v4
	v_or_b32_e32 v58, s43, v1
	v_or_b32_e32 v56, s44, v4
	v_or_b32_e32 v62, s45, v1
	v_or_b32_e32 v60, s46, v4
	s_cmp_lg_u32 s1, 0
	v_mad_u64_u32 v[32:33], s[20:21], v31, s7, v[14:15]
	v_mad_u64_u32 v[34:35], s[20:21], v29, s7, v[14:15]
	v_mad_u64_u32 v[36:37], s[20:21], v36, s7, v[14:15]
	v_mad_u64_u32 v[38:39], s[20:21], v38, s7, v[14:15]
	v_mad_u64_u32 v[40:41], s[20:21], v40, s7, v[14:15]
	v_mad_u64_u32 v[42:43], s[20:21], v42, s7, v[14:15]
	v_mad_u64_u32 v[44:45], s[20:21], v44, s7, v[14:15]
	v_mad_u64_u32 v[50:51], s[20:21], v50, s7, v[14:15]
	v_mad_u64_u32 v[52:53], s[20:21], v52, s7, v[14:15]
	v_mad_u64_u32 v[54:55], s[20:21], v54, s7, v[14:15]
	v_mad_u64_u32 v[56:57], s[20:21], v56, s7, v[14:15]
	v_mad_u64_u32 v[58:59], s[20:21], v58, s7, v[14:15]
	v_mad_u64_u32 v[60:61], s[20:21], v60, s7, v[14:15]
	v_mad_u64_u32 v[62:63], s[20:21], v62, s7, v[14:15]
	s_waitcnt vmcnt(15)
	ds_write_b32 v28, v9
	s_waitcnt vmcnt(14)
	ds_write_b32 v30, v22
	s_waitcnt vmcnt(13)
	ds_write_b32 v32, v24
	s_waitcnt vmcnt(12)
	ds_write_b32 v34, v26
	s_waitcnt vmcnt(11)
	ds_write_b32 v36, v46
	s_waitcnt vmcnt(10)
	ds_write_b32 v38, v48
	s_waitcnt vmcnt(9)
	ds_write_b32 v40, v64
	s_waitcnt vmcnt(8)
	ds_write_b32 v42, v65
	s_waitcnt vmcnt(7)
	ds_write_b32 v44, v66
	s_waitcnt vmcnt(6)
	ds_write_b32 v50, v67
	s_waitcnt vmcnt(5)
	ds_write_b32 v52, v68
	s_waitcnt vmcnt(4)
	ds_write_b32 v54, v69
	s_waitcnt vmcnt(3)
	ds_write_b32 v56, v70
	s_waitcnt vmcnt(2)
	ds_write_b32 v58, v71
	s_waitcnt vmcnt(1)
	ds_write_b32 v60, v72
	s_waitcnt vmcnt(0)
	ds_write_b32 v62, v73
	s_cbranch_scc1 .LBB0_72
; __device__ __forceinline__ unsigned cvt_pk_bf16(float lo, float hi) { unsigned r; asm volatile("s_nop 0\n\tv_cvt_pk_bf16_f32 %0, %1, %2\n\ts_nop 1" : "=v"(r) : "v"(lo), "v"(hi)); return r; }
; #define LAS __attribute__((address_space(3)))
; #define LDS_FENCE() asm volatile("s_waitcnt lgkmcnt(0)" ::: "memory")
; __device__ __forceinline__ void tr_item(const float* W, int ldw, int col0, const float* kscale, bf16_t* WT, int K, int row0, LAS float* scr, int item, int nblk, int lane) {
;     ...
;     LDS_FENCE();
;     const int c = lane & 7;
; #pragma unroll
;     for (int j = 0; j < 4; ++j) { const int n = (lane >> 3) + 8 * j; const LAS float* s = scr + (8 * c) * 33 + n;
;         u32x4 o; o.x = cvt_pk_bf16(s[0 * 33], s[1 * 33]); o.y = cvt_pk_bf16(s[2 * 33], s[3 * 33]); o.z = cvt_pk_bf16(s[4 * 33], s[5 * 33]); o.w = cvt_pk_bf16(s[6 * 33], s[7 * 33]);
;         *(u32x4*)(WT + (size_t)(row0 + n0 + n) * K + k0 + 8 * c) = o; }
;     LDS_FENCE();
	s_waitcnt lgkmcnt(0)
	v_or_b32_e32 v32, s0, v5
	ds_read2_b32 v[18:19], v15 offset1:33
	s_ashr_i32 s5, s4, 31
	v_ashrrev_i32_e32 v33, 31, v32
	s_waitcnt lgkmcnt(0)
	v_cvt_pk_bf16_f32 v28, v18, v19
	ds_read2_b32 v[18:19], v15 offset0:66 offset1:99
	v_lshl_add_u64 v[34:35], s[4:5], 1, v[16:17]
	v_lshlrev_b64 v[32:33], 13, v[32:33]
	s_waitcnt lgkmcnt(0)
	v_cvt_pk_bf16_f32 v29, v18, v19
	ds_read2_b32 v[18:19], v15 offset0:132 offset1:165
	v_lshl_add_u64 v[32:33], v[34:35], 0, v[32:33]
	s_waitcnt lgkmcnt(0)
	v_cvt_pk_bf16_f32 v30, v18, v19
	ds_read2_b32 v[18:19], v15 offset0:198 offset1:231
	s_waitcnt lgkmcnt(0)
	v_cvt_pk_bf16_f32 v31, v18, v19
	global_store_dwordx4 v[32:33], v[28:31], off
	v_or_b32_e32 v32, s0, v23
	ds_read2_b32 v[18:19], v15 offset0:8 offset1:41
	v_ashrrev_i32_e32 v33, 31, v32
	s_waitcnt lgkmcnt(0)
	v_cvt_pk_bf16_f32 v28, v18, v19
	ds_read2_b32 v[18:19], v15 offset0:74 offset1:107
	v_lshlrev_b64 v[32:33], 13, v[32:33]
	s_waitcnt lgkmcnt(0)
	v_cvt_pk_bf16_f32 v29, v18, v19
	ds_read2_b32 v[18:19], v15 offset0:140 offset1:173
	v_lshl_add_u64 v[32:33], v[34:35], 0, v[32:33]
	s_waitcnt lgkmcnt(0)
	v_cvt_pk_bf16_f32 v30, v18, v19
	ds_read2_b32 v[18:19], v15 offset0:206 offset1:239
	s_waitcnt lgkmcnt(0)
	v_cvt_pk_bf16_f32 v31, v18, v19
	global_store_dwordx4 v[32:33], v[28:31], off
	v_or_b32_e32 v32, s0, v25
	ds_read2_b32 v[18:19], v15 offset0:16 offset1:49
	v_ashrrev_i32_e32 v33, 31, v32
	s_waitcnt lgkmcnt(0)
	v_cvt_pk_bf16_f32 v28, v18, v19
	ds_read2_b32 v[18:19], v15 offset0:82 offset1:115
	v_lshlrev_b64 v[32:33], 13, v[32:33]
	s_waitcnt lgkmcnt(0)
	v_cvt_pk_bf16_f32 v29, v18, v19
	ds_read2_b32 v[18:19], v15 offset0:148 offset1:181
	v_lshl_add_u64 v[32:33], v[34:35], 0, v[32:33]
	s_waitcnt lgkmcnt(0)
	v_cvt_pk_bf16_f32 v30, v18, v19
	ds_read2_b32 v[18:19], v15 offset0:214 offset1:247
	s_waitcnt lgkmcnt(0)
	v_cvt_pk_bf16_f32 v31, v18, v19
	global_store_dwordx4 v[32:33], v[28:31], off
	v_or_b32_e32 v32, s0, v27
	ds_read2_b32 v[18:19], v15 offset0:24 offset1:57
	v_ashrrev_i32_e32 v33, 31, v32
	s_waitcnt lgkmcnt(0)
	v_cvt_pk_bf16_f32 v28, v18, v19
	ds_read2_b32 v[18:19], v15 offset0:90 offset1:123
	v_lshlrev_b64 v[32:33], 13, v[32:33]
	s_waitcnt lgkmcnt(0)
	v_cvt_pk_bf16_f32 v29, v18, v19
	ds_read2_b32 v[18:19], v15 offset0:156 offset1:189
	v_lshl_add_u64 v[32:33], v[34:35], 0, v[32:33]
	s_waitcnt lgkmcnt(0)
	v_cvt_pk_bf16_f32 v30, v18, v19
	ds_read2_b32 v[18:19], v15 offset0:222 offset1:255
	s_waitcnt lgkmcnt(0)
	v_cvt_pk_bf16_f32 v31, v18, v19
	global_store_dwordx4 v[32:33], v[28:31], off
	s_waitcnt lgkmcnt(0)
	s_add_i32 s6, s6, s28
	s_cmpk_lt_i32 s6, 0x800
	s_cbranch_scc1 .LBB0_71
	v_mov_b32_e32 v10, v4
	v_mov_b32_e32 v14, v2
	v_mov_b32_e32 v34, v5

; __device__ __forceinline__ unsigned cvt_pk_bf16(float lo, float hi) { unsigned r; asm volatile("s_nop 0\n\tv_cvt_pk_bf16_f32 %0, %1, %2\n\ts_nop 1" : "=v"(r) : "v"(lo), "v"(hi)); return r; }
; #define LAS __attribute__((address_space(3)))
; #define LDS_FENCE() asm volatile("s_waitcnt lgkmcnt(0)" ::: "memory")
; __device__ __forceinline__ void tr_item(const float* W, int ldw, int col0, const float* kscale, bf16_t* WT, int K, int row0, LAS float* scr, int item, int nblk, int lane) {
;     const int kb = item / nblk, nb = item % nblk, k0 = 64 * kb, n0 = 32 * nb;
; #pragma unroll 8
;     for (int i = 0; i < 32; ++i) { const int kk = 2 * i + (lane >> 5); float v = W[(size_t)(k0 + kk) * ldw + col0 + n0 + (lane & 31)]; if (kscale) v *= kscale[k0 + kk]; scr[kk * 33 + (lane & 31)] = v; }
;     LDS_FENCE();
;     const int c = lane & 7;
; #pragma unroll
;     for (int j = 0; j < 4; ++j) { const int n = (lane >> 3) + 8 * j; const LAS float* s = scr + (8 * c) * 33 + n;
;         u32x4 o; o.x = cvt_pk_bf16(s[0 * 33], s[1 * 33]); o.y = cvt_pk_bf16(s[2 * 33], s[3 * 33]); o.z = cvt_pk_bf16(s[4 * 33], s[5 * 33]); o.w = cvt_pk_bf16(s[6 * 33], s[7 * 33]);
;         *(u32x4*)(WT + (size_t)(row0 + n0 + n) * K + k0 + 8 * c) = o; }
;     LDS_FENCE();
; }
; __device__ __forceinline__ void phase_p0(const Params& p, LAS unsigned char* lds, int wg, int G, int tid, int wid, int lane) {
;     ...
;     for (int m = 0; m < 16; ++m) {
;         tr_matrix(p.lru_wa + (size_t)m * 16384, 128, 0, 128, 128, nullptr, WGt + (size_t)(m * 2 + 0) * 16384, 0, scr, base, gw, NGW, lane);
;         tr_matrix(p.lru_wi + (size_t)m * 16384, 128, 0, 128, 128, nullptr, WGt + (size_t)(m * 2 + 1) * 16384, 0, scr, base, gw, NGW, lane);
.LBB0_79:
	s_or_b64 exec, exec, s[22:23]
	s_waitcnt lgkmcnt(0)
	v_or_b32_e32 v44, s14, v34
	ds_read2_b32 v[32:33], v35 offset1:33
	s_ashr_i32 s21, s20, 31
	v_ashrrev_i32_e32 v45, 31, v44
	s_waitcnt lgkmcnt(0)
	s_nop 0
	v_cvt_pk_bf16_f32 v40, v32, v33
	ds_read2_b32 v[32:33], v35 offset0:66 offset1:99
	v_lshl_add_u64 v[50:51], s[20:21], 1, v[30:31]
	v_lshlrev_b64 v[44:45], 8, v[44:45]
	s_waitcnt lgkmcnt(0)
	s_nop 0
	v_cvt_pk_bf16_f32 v41, v32, v33
	ds_read2_b32 v[32:33], v35 offset0:132 offset1:165
	v_lshl_add_u64 v[44:45], v[50:51], 0, v[44:45]
	s_waitcnt lgkmcnt(0)
	v_cvt_pk_bf16_f32 v42, v32, v33
	ds_read2_b32 v[32:33], v35 offset0:198 offset1:231
	s_waitcnt lgkmcnt(0)
	v_cvt_pk_bf16_f32 v43, v32, v33
	global_store_dwordx4 v[44:45], v[40:43], off
	v_or_b32_e32 v44, s14, v23
	ds_read2_b32 v[32:33], v36 offset1:33
	v_ashrrev_i32_e32 v45, 31, v44
	s_waitcnt lgkmcnt(0)
	v_cvt_pk_bf16_f32 v40, v32, v33
	ds_read2_b32 v[32:33], v36 offset0:66 offset1:99
	v_lshlrev_b64 v[44:45], 8, v[44:45]
	s_waitcnt lgkmcnt(0)
	v_cvt_pk_bf16_f32 v41, v32, v33
	ds_read2_b32 v[32:33], v36 offset0:132 offset1:165
	v_lshl_add_u64 v[44:45], v[50:51], 0, v[44:45]
	s_waitcnt lgkmcnt(0)
	v_cvt_pk_bf16_f32 v42, v32, v33
	ds_read2_b32 v[32:33], v36 offset0:198 offset1:231
	s_waitcnt lgkmcnt(0)
	v_cvt_pk_bf16_f32 v43, v32, v33
	global_store_dwordx4 v[44:45], v[40:43], off
	v_or_b32_e32 v44, s14, v25
	ds_read2_b32 v[32:33], v37 offset1:33
	v_ashrrev_i32_e32 v45, 31, v44
	s_waitcnt lgkmcnt(0)
	v_cvt_pk_bf16_f32 v40, v32, v33
	ds_read2_b32 v[32:33], v37 offset0:66 offset1:99
	v_lshlrev_b64 v[44:45], 8, v[44:45]
	s_waitcnt lgkmcnt(0)
	v_cvt_pk_bf16_f32 v41, v32, v33
	ds_read2_b32 v[32:33], v37 offset0:132 offset1:165
	v_lshl_add_u64 v[44:45], v[50:51], 0, v[44:45]
	s_waitcnt lgkmcnt(0)
	v_cvt_pk_bf16_f32 v42, v32, v33
	ds_read2_b32 v[32:33], v37 offset0:198 offset1:231
	s_waitcnt lgkmcnt(0)
	v_cvt_pk_bf16_f32 v43, v32, v33
	global_store_dwordx4 v[44:45], v[40:43], off
	v_or_b32_e32 v44, s14, v27
	ds_read2_b32 v[32:33], v38 offset1:33
	v_ashrrev_i32_e32 v45, 31, v44
	s_waitcnt lgkmcnt(0)
	v_cvt_pk_bf16_f32 v40, v32, v33
	ds_read2_b32 v[32:33], v38 offset0:66 offset1:99
	v_lshlrev_b64 v[44:45], 8, v[44:45]
	s_waitcnt lgkmcnt(0)
	v_cvt_pk_bf16_f32 v41, v32, v33
	ds_read2_b32 v[32:33], v38 offset0:132 offset1:165
	v_lshl_add_u64 v[44:45], v[50:51], 0, v[44:45]
	s_waitcnt lgkmcnt(0)
	v_cvt_pk_bf16_f32 v42, v32, v33
	ds_read2_b32 v[32:33], v38 offset0:198 offset1:231
	s_waitcnt lgkmcnt(0)
	v_cvt_pk_bf16_f32 v43, v32, v33
	global_store_dwordx4 v[44:45], v[40:43], off
	s_waitcnt lgkmcnt(0)
	s_add_i32 s38, s38, s28
	s_cmp_lt_i32 s38, 8
	s_cbranch_scc0 .LBB0_86

; __device__ __forceinline__ unsigned cvt_pk_bf16(float lo, float hi) { unsigned r; asm volatile("s_nop 0\n\tv_cvt_pk_bf16_f32 %0, %1, %2\n\ts_nop 1" : "=v"(r) : "v"(lo), "v"(hi)); return r; }
; #define LAS __attribute__((address_space(3)))
; #define LDS_FENCE() asm volatile("s_waitcnt lgkmcnt(0)" ::: "memory")
; __device__ __forceinline__ void tr_item(const float* W, int ldw, int col0, const float* kscale, bf16_t* WT, int K, int row0, LAS float* scr, int item, int nblk, int lane) {
;     const int kb = item / nblk, nb = item % nblk, k0 = 64 * kb, n0 = 32 * nb;
; #pragma unroll 8
;     for (int i = 0; i < 32; ++i) { const int kk = 2 * i + (lane >> 5); float v = W[(size_t)(k0 + kk) * ldw + col0 + n0 + (lane & 31)]; if (kscale) v *= kscale[k0 + kk]; scr[kk * 33 + (lane & 31)] = v; }
;     LDS_FENCE();
;     const int c = lane & 7;
; #pragma unroll
;     for (int j = 0; j < 4; ++j) { const int n = (lane >> 3) + 8 * j; const LAS float* s = scr + (8 * c) * 33 + n;
;         u32x4 o; o.x = cvt_pk_bf16(s[0 * 33], s[1 * 33]); o.y = cvt_pk_bf16(s[2 * 33], s[3 * 33]); o.z = cvt_pk_bf16(s[4 * 33], s[5 * 33]); o.w = cvt_pk_bf16(s[6 * 33], s[7 * 33]);
;         *(u32x4*)(WT + (size_t)(row0 + n0 + n) * K + k0 + 8 * c) = o; }
;     LDS_FENCE();
; }
; __device__ __forceinline__ void phase_p0(const Params& p, LAS unsigned char* lds, int wg, int G, int tid, int wid, int lane) {
;     ...
;     for (int m = 0; m < 16; ++m) {
;         tr_matrix(p.lru_wa + (size_t)m * 16384, 128, 0, 128, 128, nullptr, WGt + (size_t)(m * 2 + 0) * 16384, 0, scr, base, gw, NGW, lane);
;         tr_matrix(p.lru_wi + (size_t)m * 16384, 128, 0, 128, 128, nullptr, WGt + (size_t)(m * 2 + 1) * 16384, 0, scr, base, gw, NGW, lane);
.LBB0_88:
	s_or_b64 exec, exec, s[20:21]
	s_waitcnt lgkmcnt(0)
	v_or_b32_e32 v44, s6, v34
	ds_read2_b32 v[32:33], v35 offset1:33
	s_ashr_i32 s15, s14, 31
	v_ashrrev_i32_e32 v45, 31, v44
	s_waitcnt lgkmcnt(0)
	s_nop 0
	v_cvt_pk_bf16_f32 v40, v32, v33
	ds_read2_b32 v[32:33], v35 offset0:66 offset1:99
	v_lshl_add_u64 v[50:51], s[14:15], 1, v[30:31]
	v_lshlrev_b64 v[44:45], 8, v[44:45]
	s_waitcnt lgkmcnt(0)
	s_nop 0
	v_cvt_pk_bf16_f32 v41, v32, v33
	ds_read2_b32 v[32:33], v35 offset0:132 offset1:165
	v_lshl_add_u64 v[44:45], v[50:51], 0, v[44:45]
	s_waitcnt lgkmcnt(0)
	v_cvt_pk_bf16_f32 v42, v32, v33
	ds_read2_b32 v[32:33], v35 offset0:198 offset1:231
	s_waitcnt lgkmcnt(0)
	v_cvt_pk_bf16_f32 v43, v32, v33
	global_store_dwordx4 v[44:45], v[40:43], off
	v_or_b32_e32 v44, s6, v23
	ds_read2_b32 v[32:33], v36 offset1:33
	v_ashrrev_i32_e32 v45, 31, v44
	s_waitcnt lgkmcnt(0)
	v_cvt_pk_bf16_f32 v40, v32, v33
	ds_read2_b32 v[32:33], v36 offset0:66 offset1:99
	v_lshlrev_b64 v[44:45], 8, v[44:45]
	s_waitcnt lgkmcnt(0)
	v_cvt_pk_bf16_f32 v41, v32, v33
	ds_read2_b32 v[32:33], v36 offset0:132 offset1:165
	v_lshl_add_u64 v[44:45], v[50:51], 0, v[44:45]
	s_waitcnt lgkmcnt(0)
	v_cvt_pk_bf16_f32 v42, v32, v33
	ds_read2_b32 v[32:33], v36 offset0:198 offset1:231
	s_waitcnt lgkmcnt(0)
	v_cvt_pk_bf16_f32 v43, v32, v33
	global_store_dwordx4 v[44:45], v[40:43], off
	v_or_b32_e32 v44, s6, v25
	ds_read2_b32 v[32:33], v37 offset1:33
	v_ashrrev_i32_e32 v45, 31, v44
	s_waitcnt lgkmcnt(0)
	v_cvt_pk_bf16_f32 v40, v32, v33
	ds_read2_b32 v[32:33], v37 offset0:66 offset1:99
	v_lshlrev_b64 v[44:45], 8, v[44:45]
	s_waitcnt lgkmcnt(0)
	v_cvt_pk_bf16_f32 v41, v32, v33
	ds_read2_b32 v[32:33], v37 offset0:132 offset1:165
	v_lshl_add_u64 v[44:45], v[50:51], 0, v[44:45]
	s_waitcnt lgkmcnt(0)
	v_cvt_pk_bf16_f32 v42, v32, v33
	ds_read2_b32 v[32:33], v37 offset0:198 offset1:231
	s_waitcnt lgkmcnt(0)
	v_cvt_pk_bf16_f32 v43, v32, v33
	global_store_dwordx4 v[44:45], v[40:43], off
	v_or_b32_e32 v44, s6, v27
	ds_read2_b32 v[32:33], v38 offset1:33
	v_ashrrev_i32_e32 v45, 31, v44
	s_waitcnt lgkmcnt(0)
	v_cvt_pk_bf16_f32 v40, v32, v33
	ds_read2_b32 v[32:33], v38 offset0:66 offset1:99
	v_lshlrev_b64 v[44:45], 8, v[44:45]
	s_waitcnt lgkmcnt(0)
	v_cvt_pk_bf16_f32 v41, v32, v33
	ds_read2_b32 v[32:33], v38 offset0:132 offset1:165
	v_lshl_add_u64 v[44:45], v[50:51], 0, v[44:45]
	s_waitcnt lgkmcnt(0)
	v_cvt_pk_bf16_f32 v42, v32, v33
	ds_read2_b32 v[32:33], v38 offset0:198 offset1:231
	s_waitcnt lgkmcnt(0)
	v_cvt_pk_bf16_f32 v43, v32, v33
	global_store_dwordx4 v[44:45], v[40:43], off
	s_waitcnt lgkmcnt(0)
	s_add_i32 s22, s22, s28
	s_cmp_lt_i32 s22, 8
	s_cbranch_scc0 .LBB0_76

; __device__ __forceinline__ unsigned cvt_pk_bf16(float lo, float hi) { unsigned r; asm volatile("s_nop 0\n\tv_cvt_pk_bf16_f32 %0, %1, %2\n\ts_nop 1" : "=v"(r) : "v"(lo), "v"(hi)); return r; }
; __device__ __forceinline__ void phase_ln0(const Params& p, int g, int gw, int NGW, int lane) {
;     ...
;     for (int row = gw; row < RG; row += NGW) {
;         const int mrow = (row < CGR) ? 32 : g * BG + (row - CGR) / SEQ;
;         const float* sh = mod + (size_t)mrow * MODW; const float* sc = sh + DM;
;         f32x4 v[4]; float s = 0.f;
; #pragma unroll
;         for (int j = 0; j < 4; ++j) { v[j] = nx[j]; s += (v[j].x + v[j].y) + (v[j].z + v[j].w); }
;         if (row + NGW < RG) { const float* src = ln0_src(p, g, row + NGW);
; #pragma unroll
;             for (int j = 0; j < 4; ++j) nx[j] = *(const f32x4*)(src + 4 * lane + 256 * j); }
;         const float mean = wave_sum(s, lane) * (1.f / DM); float s2 = 0.f;
; #pragma unroll
;         for (int j = 0; j < 4; ++j) { v[j] = v[j] - mean; s2 += (v[j].x * v[j].x + v[j].y * v[j].y) + (v[j].z * v[j].z + v[j].w * v[j].w); }
;         const float rstd = __builtin_amdgcn_rsqf(wave_sum(s2, lane) * (1.f / DM) + 1e-6f);
; #pragma unroll
;         for (int j = 0; j < 4; ++j) { const int col = 4 * lane + 256 * j; const f32x4 a = *(const f32x4*)(sc + col), b = *(const f32x4*)(sh + col);
;             const f32x4 o = v[j] * rstd * (a + 1.f) + b; u32x2 w; w.x = cvt_pk_bf16(o.x, o.y); w.y = cvt_pk_bf16(o.z, o.w);
;             *(u32x2*)(h0 + (size_t)row * DM + col) = w; }
.LBB0_242:
	v_add_f32_e32 v32, v28, v29
	v_add_f32_e32 v33, v30, v31
	v_add_f32_e32 v32, v32, v33
	v_add_f32_e32 v33, v8, v9
	v_add_f32_e32 v34, v10, v11
	v_add_f32_e32 v32, 0, v32
	v_add_f32_e32 v33, v33, v34
	v_add_f32_e32 v32, v33, v32
	v_add_f32_e32 v33, v4, v5
	v_add_f32_e32 v34, v6, v7
	v_add_f32_e32 v33, v33, v34
	v_add_f32_e32 v32, v33, v32
	v_add_f32_e32 v33, v0, v1
	v_add_f32_e32 v34, v2, v3
	v_add_f32_e32 v33, v33, v34
	v_add_f32_e32 v32, v33, v32
	ds_bpermute_b32 v33, v40, v32
	s_lshl_b64 s[2:3], s[2:3], 2
	s_add_u32 s2, s94, s2
	s_addc_u32 s3, s95, s3
	s_add_u32 s4, s2, 0x1000
	s_waitcnt lgkmcnt(0)
	v_add_f32_e32 v32, v32, v33
	ds_bpermute_b32 v33, v41, v32
	s_addc_u32 s5, s3, 0
	s_andn2_b64 vcc, exec, s[0:1]
	s_waitcnt lgkmcnt(0)
	v_add_f32_e32 v32, v32, v33
	ds_bpermute_b32 v33, v42, v32
	s_waitcnt lgkmcnt(0)
	v_add_f32_e32 v32, v32, v33
	ds_bpermute_b32 v33, v43, v32
	s_waitcnt lgkmcnt(0)
	v_add_f32_e32 v32, v32, v33
	ds_bpermute_b32 v33, v44, v32
	s_waitcnt lgkmcnt(0)
	v_add_f32_e32 v32, v32, v33
	ds_bpermute_b32 v33, v45, v32
	s_waitcnt lgkmcnt(0)
	v_add_f32_e32 v38, v32, v33
	v_fmac_f32_e32 v29, 0xba800000, v38
	v_fmac_f32_e32 v28, 0xba800000, v38
	v_fmac_f32_e32 v31, 0xba800000, v38
	v_fmac_f32_e32 v30, 0xba800000, v38
	v_pk_mul_f32 v[32:33], v[30:31], v[30:31]
	v_pk_mul_f32 v[34:35], v[28:29], v[28:29]
	v_fmac_f32_e32 v9, 0xba800000, v38
	v_pk_mov_b32 v[50:51], v[34:35], v[32:33] op_sel:[1,0]
	v_mov_b32_e32 v35, v33
	v_pk_add_f32 v[32:33], v[50:51], v[34:35]
	v_fmac_f32_e32 v8, 0xba800000, v38
	v_fmac_f32_e32 v11, 0xba800000, v38
	v_fmac_f32_e32 v10, 0xba800000, v38
	v_pk_add_f32 v[32:33], v[32:33], v[32:33] op_sel_hi:[0,1]
	v_pk_mul_f32 v[34:35], v[10:11], v[10:11]
	v_pk_mul_f32 v[50:51], v[8:9], v[8:9]
	v_fmac_f32_e32 v4, 0xba800000, v38
	v_pk_mov_b32 v[52:53], v[50:51], v[34:35] op_sel:[1,0]
	v_mov_b32_e32 v51, v35
	v_fmac_f32_e32 v5, 0xba800000, v38
	v_fmac_f32_e32 v6, 0xba800000, v38
	v_mul_f32_e32 v32, v4, v4
	v_pk_add_f32 v[34:35], v[52:53], v[50:51]
	v_fmac_f32_e32 v7, 0xba800000, v38
	v_pk_fma_f32 v[50:51], v[4:5], v[4:5], v[32:33] op_sel_hi:[1,1,0]
	v_mul_f32_e32 v32, v6, v6
	v_pk_add_f32 v[34:35], v[34:35], v[34:35] op_sel_hi:[0,1]
	v_pk_fma_f32 v[52:53], v[6:7], v[6:7], v[32:33] op_sel_hi:[1,1,0]
	v_fmac_f32_e32 v3, 0xba800000, v38
	v_fmac_f32_e32 v2, 0xba800000, v38
	v_fmac_f32_e32 v1, 0xba800000, v38
	v_fmac_f32_e32 v0, 0xba800000, v38
	v_mul_f32_e32 v50, v0, v0
	v_mul_f32_e32 v52, v1, v1
	v_mul_f32_e32 v32, v2, v2
	v_mul_f32_e32 v34, v3, v3
	v_pk_add_f32 v[50:51], v[50:51], v[52:53]
	v_pk_add_f32 v[32:33], v[32:33], v[34:35]
	s_nop 0
	v_pk_add_f32 v[32:33], v[50:51], v[32:33]
	s_nop 0
	v_add_f32_e32 v32, v32, v33
	ds_bpermute_b32 v33, v40, v32
	s_waitcnt lgkmcnt(0)
	v_add_f32_e32 v32, v32, v33
	ds_bpermute_b32 v33, v41, v32
	s_waitcnt lgkmcnt(0)
	v_add_f32_e32 v32, v32, v33
	ds_bpermute_b32 v33, v42, v32
	s_waitcnt lgkmcnt(0)
	v_add_f32_e32 v32, v32, v33
	ds_bpermute_b32 v33, v43, v32
	s_waitcnt lgkmcnt(0)
	v_add_f32_e32 v32, v32, v33
	ds_bpermute_b32 v33, v44, v32
	s_waitcnt lgkmcnt(0)
	v_add_f32_e32 v32, v32, v33
	ds_bpermute_b32 v33, v45, v32
	s_waitcnt lgkmcnt(0)
	v_add_f32_e32 v32, v32, v33
	v_fmamk_f32 v32, v32, 0x3a800000, v238
	v_rsq_f32_e32 v38, v32
	global_load_dwordx4 v[32:35], v39, s[4:5]
	global_load_dwordx4 v[50:53], v39, s[2:3]
	v_pk_mul_f32 v[28:29], v[28:29], v[38:39] op_sel_hi:[1,0]
	v_pk_mul_f32 v[30:31], v[30:31], v[38:39] op_sel_hi:[1,0]
	v_pk_mul_f32 v[8:9], v[8:9], v[38:39] op_sel_hi:[1,0]
	v_pk_mul_f32 v[10:11], v[10:11], v[38:39] op_sel_hi:[1,0]
	v_pk_mul_f32 v[4:5], v[4:5], v[38:39] op_sel_hi:[1,0]
	v_pk_mul_f32 v[6:7], v[6:7], v[38:39] op_sel_hi:[1,0]
	v_pk_mul_f32 v[0:1], v[0:1], v[38:39] op_sel_hi:[1,0]
	v_pk_mul_f32 v[2:3], v[2:3], v[38:39] op_sel_hi:[1,0]
	s_waitcnt vmcnt(1)
	v_pk_add_f32 v[32:33], v[32:33], 1.0 op_sel_hi:[1,0]
	v_pk_add_f32 v[34:35], v[34:35], 1.0 op_sel_hi:[1,0]
	s_waitcnt vmcnt(0)
	v_pk_fma_f32 v[28:29], v[32:33], v[28:29], v[50:51]
	v_pk_fma_f32 v[30:31], v[34:35], v[30:31], v[52:53]
	v_cvt_pk_bf16_f32 v28, v28, v29
	s_nop 0
	v_cvt_pk_bf16_f32 v29, v30, v31
	global_store_dwordx2 v[36:37], v[28:29], off
	global_load_dwordx4 v[28:31], v46, s[4:5]
	s_nop 0
	global_load_dwordx4 v[32:35], v39, s[2:3] offset:1024
	s_waitcnt vmcnt(1)
	v_pk_add_f32 v[28:29], v[28:29], 1.0 op_sel_hi:[1,0]
	v_pk_add_f32 v[30:31], v[30:31], 1.0 op_sel_hi:[1,0]
	s_waitcnt vmcnt(0)
	v_pk_fma_f32 v[8:9], v[28:29], v[8:9], v[32:33]
	v_pk_fma_f32 v[10:11], v[30:31], v[10:11], v[34:35]
	v_cvt_pk_bf16_f32 v8, v8, v9
	s_nop 0
	v_cvt_pk_bf16_f32 v9, v10, v11
	global_store_dwordx2 v[36:37], v[8:9], off offset:512
	global_load_dwordx4 v[8:11], v47, s[4:5]
	s_nop 0
	global_load_dwordx4 v[28:31], v39, s[2:3] offset:2048
	s_waitcnt vmcnt(1)
	v_pk_add_f32 v[8:9], v[8:9], 1.0 op_sel_hi:[1,0]
	v_pk_add_f32 v[10:11], v[10:11], 1.0 op_sel_hi:[1,0]
	s_waitcnt vmcnt(0)
	v_pk_fma_f32 v[4:5], v[8:9], v[4:5], v[28:29]
	v_pk_fma_f32 v[6:7], v[10:11], v[6:7], v[30:31]
	v_cvt_pk_bf16_f32 v4, v4, v5
	v_mov_b32_e32 v28, v16
	v_cvt_pk_bf16_f32 v5, v6, v7
	global_store_dwordx2 v[36:37], v[4:5], off offset:1024
	global_load_dwordx4 v[4:7], v48, s[4:5]
	s_nop 0
	global_load_dwordx4 v[8:11], v39, s[2:3] offset:3072
	v_readlane_b32 s2, v255, 2
	v_readlane_b32 s3, v255, 3
	v_mov_b32_e32 v29, v17
	v_mov_b32_e32 v30, v18
	v_mov_b32_e32 v31, v19
	s_waitcnt vmcnt(1)
	v_pk_add_f32 v[4:5], v[4:5], 1.0 op_sel_hi:[1,0]
	v_pk_add_f32 v[6:7], v[6:7], 1.0 op_sel_hi:[1,0]
	s_waitcnt vmcnt(0)
	v_pk_fma_f32 v[0:1], v[4:5], v[0:1], v[8:9]
	v_pk_fma_f32 v[2:3], v[6:7], v[2:3], v[10:11]
	v_cvt_pk_bf16_f32 v0, v0, v1
	v_mov_b32_e32 v8, v20
	v_cvt_pk_bf16_f32 v1, v2, v3
	global_store_dwordx2 v[36:37], v[0:1], off offset:1536
	v_lshl_add_u64 v[36:37], v[36:37], 0, s[2:3]
	v_mov_b32_e32 v9, v21
	v_mov_b32_e32 v10, v22
	v_mov_b32_e32 v11, v23
	v_mov_b32_e32 v4, v24
	v_mov_b32_e32 v5, v25
	v_mov_b32_e32 v6, v26
	v_mov_b32_e32 v7, v27
	v_mov_b32_e32 v0, v12
	v_mov_b32_e32 v1, v13
	v_mov_b32_e32 v2, v14
	v_mov_b32_e32 v3, v15
	s_cbranch_vccz .LBB0_247

; __device__ __forceinline__ unsigned cvt_pk_bf16(float lo, float hi) { unsigned r; asm volatile("s_nop 0\n\tv_cvt_pk_bf16_f32 %0, %1, %2\n\ts_nop 1" : "=v"(r) : "v"(lo), "v"(hi)); return r; }
;     __device__ __forceinline__ void operator()(f32x4 (&acc)[2][2][4][2], const Unit& u, int wr, int wc, int fr, int fq) const {
;     ...
; #pragma unroll
;         for (int bj = 0; bj < 2; ++bj)
; #pragma unroll
;             for (int n = 0; n < 2; ++n) { const int col = col0 + bj * 128 + n * 16; const f32x4 gv = *(const f32x4*)(gr + col);
;                 f32x4 bv = (f32x4){0.f, 0.f, 0.f, 0.f}; if (bias) bv = *(const f32x4*)(bias + col);
; #pragma unroll
;                 for (int ai = 0; ai < 2; ++ai)
; #pragma unroll
;                     for (int m = 0; m < 4; ++m) { const size_t row = row0 + ai * 128 + m * 16;
;                         const f32x4 o = gv * (acc[ai][bj][m][n] + bv); u32x2 w; w.x = cvt_pk_bf16(o[0], o[1]); w.y = cvt_pk_bf16(o[2], o[3]);
;                         *(u32x2*)(O + row * 1024 + col) = w; } }
.LBB0_258:
	s_waitcnt vmcnt(0)
	v_pk_add_f32 v[34:35], v[36:37], v[60:61]
	v_pk_add_f32 v[28:29], v[28:29], v[60:61]
	v_pk_add_f32 v[20:21], v[20:21], v[60:61]
	v_pk_add_f32 v[16:17], v[16:17], v[60:61]
	v_pk_add_f32 v[12:13], v[12:13], v[60:61]
	v_pk_add_f32 v[8:9], v[8:9], v[60:61]
	v_pk_add_f32 v[4:5], v[4:5], v[60:61]
	v_pk_add_f32 v[0:1], v[0:1], v[60:61]
	v_pk_add_f32 v[32:33], v[38:39], v[62:63]
	v_pk_mul_f32 v[34:35], v[24:25], v[34:35]
	v_pk_add_f32 v[30:31], v[30:31], v[62:63]
	v_pk_mul_f32 v[28:29], v[24:25], v[28:29]
	v_pk_add_f32 v[22:23], v[22:23], v[62:63]
	v_pk_mul_f32 v[20:21], v[24:25], v[20:21]
	v_pk_add_f32 v[18:19], v[18:19], v[62:63]
	v_pk_mul_f32 v[16:17], v[24:25], v[16:17]
	v_pk_add_f32 v[14:15], v[14:15], v[62:63]
	v_pk_mul_f32 v[12:13], v[24:25], v[12:13]
	v_pk_add_f32 v[10:11], v[10:11], v[62:63]
	v_pk_mul_f32 v[8:9], v[24:25], v[8:9]
	v_pk_add_f32 v[6:7], v[6:7], v[62:63]
	v_pk_mul_f32 v[4:5], v[24:25], v[4:5]
	v_pk_add_f32 v[2:3], v[2:3], v[62:63]
	v_pk_mul_f32 v[0:1], v[24:25], v[0:1]
	s_and_b64 vcc, exec, s[2:3]
	s_mov_b32 s51, s12
	s_mov_b32 s26, s14
	s_mov_b64 s[28:29], s[24:25]
	s_mov_b64 s[4:5], s[22:23]
	v_pk_mul_f32 v[32:33], v[26:27], v[32:33]
	v_cvt_pk_bf16_f32 v34, v34, v35
	v_pk_mul_f32 v[30:31], v[26:27], v[30:31]
	v_cvt_pk_bf16_f32 v35, v32, v33
	global_store_dwordx2 v[124:125], v[34:35], off offset:288
	v_cvt_pk_bf16_f32 v28, v28, v29
	v_cvt_pk_bf16_f32 v29, v30, v31
	global_store_dwordx2 v[120:121], v[28:29], off offset:288
	v_pk_mul_f32 v[22:23], v[26:27], v[22:23]
	v_cvt_pk_bf16_f32 v20, v20, v21
	v_pk_mul_f32 v[18:19], v[26:27], v[18:19]
	v_cvt_pk_bf16_f32 v21, v22, v23
	global_store_dwordx2 v[116:117], v[20:21], off offset:288
	v_cvt_pk_bf16_f32 v16, v16, v17
	v_cvt_pk_bf16_f32 v17, v18, v19
	global_store_dwordx2 v[112:113], v[16:17], off offset:288
	v_pk_mul_f32 v[14:15], v[26:27], v[14:15]
	v_cvt_pk_bf16_f32 v12, v12, v13
	v_pk_mul_f32 v[10:11], v[26:27], v[10:11]
	v_cvt_pk_bf16_f32 v13, v14, v15
	global_store_dwordx2 v[106:107], v[12:13], off offset:288
	v_cvt_pk_bf16_f32 v8, v8, v9
	v_cvt_pk_bf16_f32 v9, v10, v11
	global_store_dwordx2 v[104:105], v[8:9], off offset:288
	v_pk_mul_f32 v[6:7], v[26:27], v[6:7]
	v_cvt_pk_bf16_f32 v4, v4, v5
	v_pk_mul_f32 v[2:3], v[26:27], v[2:3]
	v_cvt_pk_bf16_f32 v5, v6, v7
	global_store_dwordx2 v[102:103], v[4:5], off offset:288
	v_cvt_pk_bf16_f32 v0, v0, v1
	v_cvt_pk_bf16_f32 v1, v2, v3
	s_nop 1
	global_store_dwordx2 v[100:101], v[0:1], off offset:288
	s_cbranch_vccnz .LBB0_275

; __device__ __forceinline__ unsigned cvt_pk_bf16(float lo, float hi) { unsigned r; asm volatile("s_nop 0\n\tv_cvt_pk_bf16_f32 %0, %1, %2\n\ts_nop 1" : "=v"(r) : "v"(lo), "v"(hi)); return r; }
;     __device__ __forceinline__ void operator()(f32x4 (&acc)[2][2][4][2], const Unit& u, int wr, int wc, int fr, int fq) const {
;         const int row0 = u.pm * 256 + wr * 64 + fr, col0 = u.pn * 256 + wc * 32 + 4 * fq;
;         const float* gr = gate + (size_t)(bbase + (u.pm * 256) / SEQ) * MODW;
; #pragma unroll
;         for (int bj = 0; bj < 2; ++bj)
; #pragma unroll
;             for (int n = 0; n < 2; ++n) { const int col = col0 + bj * 128 + n * 16; const f32x4 gv = *(const f32x4*)(gr + col);
;                 f32x4 bv = (f32x4){0.f, 0.f, 0.f, 0.f}; if (bias) bv = *(const f32x4*)(bias + col);
; #pragma unroll
;                 for (int ai = 0; ai < 2; ++ai)
; #pragma unroll
;                     for (int m = 0; m < 4; ++m) { const size_t row = row0 + ai * 128 + m * 16;
;                         const f32x4 o = gv * (acc[ai][bj][m][n] + bv); u32x2 w; w.x = cvt_pk_bf16(o[0], o[1]); w.y = cvt_pk_bf16(o[2], o[3]);
;                         *(u32x2*)(O + row * 1024 + col) = w; } }
.LBB0_269:
	v_lshl_add_u32 v154, s26, 8, v150
	s_waitcnt vmcnt(0)
	v_pk_add_f32 v[124:125], v[124:125], v[134:135]
	v_ashrrev_i32_e32 v155, 31, v154
	v_pk_add_f32 v[126:127], v[126:127], v[136:137]
	v_pk_mul_f32 v[124:125], v[130:131], v[124:125]
	v_pk_mul_f32 v[126:127], v[132:133], v[126:127]
	s_nop 0
	v_cvt_pk_bf16_f32 v156, v124, v125
	v_lshlrev_b64 v[124:125], 11, v[154:155]
	s_nop 0
	v_cvt_pk_bf16_f32 v157, v126, v127
	v_lshl_add_u64 v[124:125], s[0:1], 0, v[124:125]
	v_lshlrev_b64 v[126:127], 1, v[148:149]
	v_or_b32_e32 v148, 16, v154
	v_pk_add_f32 v[120:121], v[120:121], v[134:135]
	v_lshl_add_u64 v[124:125], v[124:125], 0, v[126:127]
	v_ashrrev_i32_e32 v149, 31, v148
	v_pk_add_f32 v[122:123], v[122:123], v[136:137]
	v_pk_mul_f32 v[120:121], v[130:131], v[120:121]
	global_store_dwordx2 v[124:125], v[156:157], off
	v_pk_mul_f32 v[122:123], v[132:133], v[122:123]
	v_cvt_pk_bf16_f32 v156, v120, v121
	v_lshlrev_b64 v[120:121], 11, v[148:149]
	v_cvt_pk_bf16_f32 v157, v122, v123
	v_lshl_add_u64 v[120:121], s[0:1], 0, v[120:121]
	v_or_b32_e32 v122, 32, v154
	v_pk_add_f32 v[116:117], v[116:117], v[134:135]
	v_lshl_add_u64 v[120:121], v[120:121], 0, v[126:127]
	v_ashrrev_i32_e32 v123, 31, v122
	v_pk_add_f32 v[118:119], v[118:119], v[136:137]
	v_pk_mul_f32 v[116:117], v[130:131], v[116:117]
	global_store_dwordx2 v[120:121], v[156:157], off
	v_pk_mul_f32 v[118:119], v[132:133], v[118:119]
	v_cvt_pk_bf16_f32 v148, v116, v117
	v_lshlrev_b64 v[116:117], 11, v[122:123]
	v_cvt_pk_bf16_f32 v149, v118, v119
	v_lshl_add_u64 v[116:117], s[0:1], 0, v[116:117]
	v_or_b32_e32 v118, 48, v154
	v_pk_add_f32 v[112:113], v[112:113], v[134:135]
	v_lshl_add_u64 v[116:117], v[116:117], 0, v[126:127]
	v_ashrrev_i32_e32 v119, 31, v118
	v_pk_mul_f32 v[112:113], v[130:131], v[112:113]
	global_store_dwordx2 v[116:117], v[148:149], off
	v_cvt_pk_bf16_f32 v122, v112, v113
	v_lshlrev_b64 v[112:113], 11, v[118:119]
	v_lshl_add_u64 v[112:113], s[0:1], 0, v[112:113]
	v_pk_add_f32 v[110:111], v[110:111], v[136:137]
	v_pk_add_f32 v[108:109], v[108:109], v[134:135]
	v_pk_add_f32 v[114:115], v[114:115], v[136:137]
	v_lshl_add_u64 v[112:113], v[112:113], 0, v[126:127]
	v_pk_mul_f32 v[110:111], v[132:133], v[110:111]
	v_pk_mul_f32 v[108:109], v[130:131], v[108:109]
	v_pk_mul_f32 v[114:115], v[132:133], v[114:115]
	v_pk_add_f32 v[106:107], v[106:107], v[136:137]
	v_cvt_pk_bf16_f32 v123, v114, v115
	global_store_dwordx2 v[112:113], v[122:123], off
	v_cvt_pk_bf16_f32 v108, v108, v109
	v_cvt_pk_bf16_f32 v109, v110, v111
	v_add_co_u32_e32 v110, vcc, s63, v124
	v_pk_add_f32 v[104:105], v[104:105], v[134:135]
	s_nop 0
	v_addc_co_u32_e32 v111, vcc, 0, v125, vcc
	v_pk_mul_f32 v[106:107], v[132:133], v[106:107]
	v_pk_mul_f32 v[104:105], v[130:131], v[104:105]
	global_store_dwordx2 v[110:111], v[108:109], off
	v_cvt_pk_bf16_f32 v104, v104, v105
	v_cvt_pk_bf16_f32 v105, v106, v107
	v_add_co_u32_e32 v106, vcc, s66, v124
	v_pk_add_f32 v[102:103], v[102:103], v[136:137]
	v_pk_add_f32 v[100:101], v[100:101], v[134:135]
	v_addc_co_u32_e32 v107, vcc, 0, v125, vcc
	v_pk_mul_f32 v[102:103], v[132:133], v[102:103]
	v_pk_mul_f32 v[100:101], v[130:131], v[100:101]
	s_mov_b32 s55, 0x50000
	global_store_dwordx2 v[106:107], v[104:105], off
	v_cvt_pk_bf16_f32 v100, v100, v101
	v_cvt_pk_bf16_f32 v101, v102, v103
	v_add_co_u32_e32 v102, vcc, s55, v124
	v_pk_add_f32 v[94:95], v[94:95], v[136:137]
	v_pk_add_f32 v[92:93], v[92:93], v[134:135]
	v_addc_co_u32_e32 v103, vcc, 0, v125, vcc
	v_pk_mul_f32 v[94:95], v[132:133], v[94:95]
	v_pk_mul_f32 v[92:93], v[130:131], v[92:93]
	global_store_dwordx2 v[102:103], v[100:101], off
	v_cvt_pk_bf16_f32 v92, v92, v93
	v_cvt_pk_bf16_f32 v93, v94, v95
	v_add_co_u32_e32 v94, vcc, 0x58000, v124
	v_mov_b32_e32 v129, 0
	s_nop 0
	v_addc_co_u32_e32 v95, vcc, 0, v125, vcc
	global_store_dwordx2 v[94:95], v[92:93], off
	global_load_dwordx4 v[92:95], v[146:147], off offset:64
	s_and_b64 vcc, exec, s[4:5]
	v_mov_b32_e32 v130, 0
	v_mov_b32_e32 v131, 0
	s_mov_b32 s56, 0x800000
	s_mov_b32 s58, 0x3f317217
	s_mov_b32 s59, 0x7f800000
	s_movk_i32 s78, 0x2a00
	v_readlane_b32 s79, v255, 35
	s_cbranch_vccnz .LBB0_271
	global_load_dwordx4 v[128:131], v[144:145], off offset:64
; __device__ __forceinline__ unsigned cvt_pk_bf16(float lo, float hi) { unsigned r; asm volatile("s_nop 0\n\tv_cvt_pk_bf16_f32 %0, %1, %2\n\ts_nop 1" : "=v"(r) : "v"(lo), "v"(hi)); return r; }
;     __device__ __forceinline__ void operator()(f32x4 (&acc)[2][2][4][2], const Unit& u, int wr, int wc, int fr, int fq) const {
;     ...
; #pragma unroll
;         for (int bj = 0; bj < 2; ++bj)
; #pragma unroll
;             for (int n = 0; n < 2; ++n) { const int col = col0 + bj * 128 + n * 16; const f32x4 gv = *(const f32x4*)(gr + col);
;                 f32x4 bv = (f32x4){0.f, 0.f, 0.f, 0.f}; if (bias) bv = *(const f32x4*)(bias + col);
; #pragma unroll
;                 for (int ai = 0; ai < 2; ++ai)
; #pragma unroll
;                     for (int m = 0; m < 4; ++m) { const size_t row = row0 + ai * 128 + m * 16;
;                         const f32x4 o = gv * (acc[ai][bj][m][n] + bv); u32x2 w; w.x = cvt_pk_bf16(o[0], o[1]); w.y = cvt_pk_bf16(o[2], o[3]);
;                         *(u32x2*)(O + row * 1024 + col) = w; } }
.LBB0_271:
	s_mov_b64 s[28:29], 0x40000
	v_lshl_add_u64 v[106:107], v[124:125], 0, s[28:29]
	s_mov_b64 s[28:29], 0x50000
	v_lshl_add_u64 v[102:103], v[124:125], 0, s[28:29]
	s_mov_b64 s[28:29], 0x58000
	s_waitcnt vmcnt(0)
	v_pk_add_f32 v[96:97], v[96:97], v[128:129]
	v_pk_add_f32 v[88:89], v[88:89], v[128:129]
	v_pk_add_f32 v[84:85], v[84:85], v[128:129]
	v_pk_add_f32 v[80:81], v[80:81], v[128:129]
	v_pk_add_f32 v[76:77], v[76:77], v[128:129]
	v_pk_add_f32 v[72:73], v[72:73], v[128:129]
	v_pk_add_f32 v[68:69], v[68:69], v[128:129]
	v_pk_add_f32 v[60:61], v[60:61], v[128:129]
	v_lshl_add_u64 v[104:105], v[124:125], 0, s[64:65]
	v_lshl_add_u64 v[100:101], v[124:125], 0, s[28:29]
	v_pk_add_f32 v[98:99], v[98:99], v[130:131]
	v_pk_mul_f32 v[96:97], v[92:93], v[96:97]
	v_pk_add_f32 v[90:91], v[90:91], v[130:131]
	v_pk_mul_f32 v[88:89], v[92:93], v[88:89]
	v_pk_add_f32 v[86:87], v[86:87], v[130:131]
	v_pk_mul_f32 v[84:85], v[92:93], v[84:85]
	v_pk_add_f32 v[82:83], v[82:83], v[130:131]
	v_pk_mul_f32 v[80:81], v[92:93], v[80:81]
	v_pk_add_f32 v[78:79], v[78:79], v[130:131]
	v_pk_mul_f32 v[76:77], v[92:93], v[76:77]
	v_pk_add_f32 v[74:75], v[74:75], v[130:131]
	v_pk_mul_f32 v[72:73], v[92:93], v[72:73]
	v_pk_add_f32 v[70:71], v[70:71], v[130:131]
	v_pk_mul_f32 v[68:69], v[92:93], v[68:69]
	v_pk_add_f32 v[62:63], v[62:63], v[130:131]
	v_pk_mul_f32 v[60:61], v[92:93], v[60:61]
	v_pk_mul_f32 v[98:99], v[94:95], v[98:99]
	v_cvt_pk_bf16_f32 v96, v96, v97
	v_pk_mul_f32 v[90:91], v[94:95], v[90:91]
	v_cvt_pk_bf16_f32 v97, v98, v99
	global_store_dwordx2 v[124:125], v[96:97], off offset:32
	v_cvt_pk_bf16_f32 v88, v88, v89
	v_cvt_pk_bf16_f32 v89, v90, v91
	global_store_dwordx2 v[120:121], v[88:89], off offset:32
	v_pk_mul_f32 v[86:87], v[94:95], v[86:87]
	v_cvt_pk_bf16_f32 v84, v84, v85
	v_pk_mul_f32 v[82:83], v[94:95], v[82:83]
	v_cvt_pk_bf16_f32 v85, v86, v87
	global_store_dwordx2 v[116:117], v[84:85], off offset:32
	v_cvt_pk_bf16_f32 v80, v80, v81
	v_cvt_pk_bf16_f32 v81, v82, v83
	global_store_dwordx2 v[112:113], v[80:81], off offset:32
	v_pk_mul_f32 v[78:79], v[94:95], v[78:79]
	v_cvt_pk_bf16_f32 v76, v76, v77
	v_pk_mul_f32 v[74:75], v[94:95], v[74:75]
	v_cvt_pk_bf16_f32 v77, v78, v79
	global_store_dwordx2 v[106:107], v[76:77], off offset:32
	v_cvt_pk_bf16_f32 v72, v72, v73
	v_cvt_pk_bf16_f32 v73, v74, v75
	global_store_dwordx2 v[104:105], v[72:73], off offset:32
	v_pk_mul_f32 v[70:71], v[94:95], v[70:71]
	v_cvt_pk_bf16_f32 v68, v68, v69
	v_pk_mul_f32 v[62:63], v[94:95], v[62:63]
	v_cvt_pk_bf16_f32 v69, v70, v71
	global_store_dwordx2 v[102:103], v[68:69], off offset:32
	v_cvt_pk_bf16_f32 v60, v60, v61
	v_cvt_pk_bf16_f32 v61, v62, v63
	global_store_dwordx2 v[100:101], v[60:61], off offset:32
	global_load_dwordx4 v[68:71], v[146:147], off offset:512
	v_mov_b32_e32 v60, 0
	s_and_b64 vcc, exec, s[4:5]
	v_mov_b32_e32 v72, 0
	v_mov_b32_e32 v73, 0
	v_mov_b32_e32 v74, 0
	v_mov_b32_e32 v75, 0
	s_cbranch_vccnz .LBB0_273
	global_load_dwordx4 v[72:75], v[144:145], off offset:512
.LBB0_273:
	s_waitcnt vmcnt(0)
	v_pk_add_f32 v[64:65], v[64:65], v[72:73]
	v_pk_add_f32 v[56:57], v[56:57], v[72:73]
	v_pk_add_f32 v[52:53], v[52:53], v[72:73]
	v_pk_add_f32 v[48:49], v[48:49], v[72:73]
	v_pk_add_f32 v[44:45], v[44:45], v[72:73]
	v_pk_add_f32 v[40:41], v[40:41], v[72:73]
	v_pk_add_f32 v[32:33], v[32:33], v[72:73]
	v_pk_add_f32 v[24:25], v[24:25], v[72:73]
	v_pk_add_f32 v[62:63], v[66:67], v[74:75]
	v_pk_mul_f32 v[64:65], v[68:69], v[64:65]
	v_pk_add_f32 v[58:59], v[58:59], v[74:75]
	v_pk_mul_f32 v[56:57], v[68:69], v[56:57]
	v_pk_add_f32 v[54:55], v[54:55], v[74:75]
	v_pk_mul_f32 v[52:53], v[68:69], v[52:53]
	v_pk_add_f32 v[50:51], v[50:51], v[74:75]
	v_pk_mul_f32 v[48:49], v[68:69], v[48:49]
	v_pk_add_f32 v[46:47], v[46:47], v[74:75]
	v_pk_mul_f32 v[44:45], v[68:69], v[44:45]
	v_pk_add_f32 v[42:43], v[42:43], v[74:75]
	v_pk_mul_f32 v[40:41], v[68:69], v[40:41]
	v_pk_add_f32 v[34:35], v[34:35], v[74:75]
	v_pk_mul_f32 v[32:33], v[68:69], v[32:33]
	v_pk_add_f32 v[26:27], v[26:27], v[74:75]
	v_pk_mul_f32 v[24:25], v[68:69], v[24:25]
	v_pk_mul_f32 v[62:63], v[70:71], v[62:63]
	v_cvt_pk_bf16_f32 v64, v64, v65
	v_pk_mul_f32 v[58:59], v[70:71], v[58:59]
	v_cvt_pk_bf16_f32 v65, v62, v63
	global_store_dwordx2 v[124:125], v[64:65], off offset:256
	v_cvt_pk_bf16_f32 v56, v56, v57
	v_cvt_pk_bf16_f32 v57, v58, v59
	global_store_dwordx2 v[120:121], v[56:57], off offset:256
	v_pk_mul_f32 v[54:55], v[70:71], v[54:55]
	v_cvt_pk_bf16_f32 v52, v52, v53
	v_pk_mul_f32 v[50:51], v[70:71], v[50:51]
	v_cvt_pk_bf16_f32 v53, v54, v55
	global_store_dwordx2 v[116:117], v[52:53], off offset:256
	v_cvt_pk_bf16_f32 v48, v48, v49
	v_cvt_pk_bf16_f32 v49, v50, v51
	global_store_dwordx2 v[112:113], v[48:49], off offset:256
	v_pk_mul_f32 v[46:47], v[70:71], v[46:47]
	v_cvt_pk_bf16_f32 v44, v44, v45
	v_pk_mul_f32 v[42:43], v[70:71], v[42:43]
	v_cvt_pk_bf16_f32 v45, v46, v47
	global_store_dwordx2 v[106:107], v[44:45], off offset:256
	v_cvt_pk_bf16_f32 v40, v40, v41
	v_cvt_pk_bf16_f32 v41, v42, v43
	global_store_dwordx2 v[104:105], v[40:41], off offset:256
	v_pk_mul_f32 v[34:35], v[70:71], v[34:35]
	v_cvt_pk_bf16_f32 v32, v32, v33
	v_pk_mul_f32 v[26:27], v[70:71], v[26:27]
	v_cvt_pk_bf16_f32 v33, v34, v35
	global_store_dwordx2 v[102:103], v[32:33], off offset:256
	v_cvt_pk_bf16_f32 v24, v24, v25
	v_cvt_pk_bf16_f32 v25, v26, v27
	global_store_dwordx2 v[100:101], v[24:25], off offset:256
	global_load_dwordx4 v[24:27], v[146:147], off offset:576
	s_and_b64 vcc, exec, s[4:5]
	v_mov_b32_e32 v61, 0
	v_mov_b32_e32 v62, 0
	v_mov_b32_e32 v63, 0
	s_cbranch_vccnz .LBB0_258
	global_load_dwordx4 v[60:63], v[144:145], off offset:576
	s_branch .LBB0_258

; #define PG8_STAGE(bufoff, gbase, voff) do { _Pragma("unroll") for (int _i = 0; _i < 2; ++_i) \
;         __builtin_amdgcn_global_load_lds((const unsigned*)((const char*)(gbase) + (voff)[_i]), (PG8_LAS unsigned*)(lds + (bufoff) + ldsw + _i * 8192), 16, 0, 0); } while (0)
; #define PG8_LDA(dst, b, h) do { _Pragma("unroll") for (int m = 0; m < 4; ++m) _Pragma("unroll") for (int k = 0; k < 2; ++k) dst[m][k] = *(const PG8_LAS bf16x8*)(lds + PG8_SA(b, h) + aoff + m * 2048 + k * 1024); } while (0)
; #define PG8_LDB(dst, b, h) do { _Pragma("unroll") for (int n = 0; n < 2; ++n) _Pragma("unroll") for (int k = 0; k < 2; ++k) dst[n][k] = *(const PG8_LAS bf16x8*)(lds + PG8_SB(b, h) + boff + n * 2048 + k * 1024); } while (0)
; #define PG8_MMA(ai, bj, At, Bt) do { __builtin_amdgcn_s_setprio(1); _Pragma("unroll") for (int m = 0; m < 4; ++m) _Pragma("unroll") for (int n = 0; n < 2; ++n) _Pragma("unroll") for (int k = 0; k < 2; ++k) \
;         acc[ai][bj][m][n] = __builtin_amdgcn_mfma_f32_16x16x32_bf16(Bt[n][k], At[m][k], acc[ai][bj][m][n], 0, 0, 0); __builtin_amdgcn_s_setprio(0); } while (0)
; #define PG8_WAIT_V(n) asm volatile("s_waitcnt vmcnt(" #n ")" ::: "memory")
; #define PG8_WAIT_L(n) asm volatile("s_waitcnt lgkmcnt(" #n ")" ::: "memory")
; #define PG8_BAR __builtin_amdgcn_s_barrier()
; #define PG8_SCHED __builtin_amdgcn_sched_barrier(0)
; template <class Epi, class Sched>
; __device__ __forceinline__ void gemm_phase(PG8_LAS unsigned char* lds, const Gemm g, const Sched& S, const Epi& E, int tid_in) {
;     ...
;             PG8_LDB(B0, 0, 0); PG8_SCHED; PG8_LDA(At, 0, 0); PG8_STAGE(PG8_SA(1, 1), a1 + hstep, voffA);
;             PG8_WAIT_L(8); PG8_BAR; PG8_WAIT_L(0); PG8_MMA(0, 0, At, B0); PG8_BAR; PG8_SCHED;
;             PG8_LDB(B1, 0, 1); PG8_STAGE(PG8_SB(0, 0), b2, voffB);
;             PG8_BAR; PG8_WAIT_L(0); PG8_MMA(0, 1, At, B1); PG8_BAR;
;             PG8_LDA(At, 0, 1); PG8_STAGE(PG8_SA(0, 0), a2, voffA);
;             PG8_BAR; PG8_WAIT_L(0); PG8_MMA(1, 0, At, B0); PG8_BAR; PG8_SCHED;
;             PG8_STAGE(PG8_SB(0, 1), b2 + hstep, voffB);
;             PG8_WAIT_V(6); PG8_BAR; PG8_MMA(1, 1, At, B1); PG8_BAR;
.LBB0_295:
	s_add_u32 s24, s22, 0xfffc0080
	s_addc_u32 s25, s23, -1
	s_add_i32 s51, 0, 0x10000
	v_add_u32_e32 v154, s51, v151
	ds_read_b128 v[120:123], v154
	ds_read_b128 v[124:127], v154 offset:1024
	ds_read_b128 v[146:149], v154 offset:2048
	ds_read_b128 v[154:157], v154 offset:3072
	s_cmp_eq_u32 s50, 12
	s_cselect_b32 s27, s9, s25
	s_cselect_b32 s26, s45, s24
	s_cselect_b32 s25, s5, s49
	s_cselect_b32 s24, s46, s48
	v_lshl_add_u64 v[190:191], s[22:23], 0, v[142:143]
	s_add_i32 m0, s15, 0xc000
	ds_read_b128 v[158:161], v153
	ds_read_b128 v[162:165], v153 offset:1024
	ds_read_b128 v[166:169], v153 offset:2048
	ds_read_b128 v[170:173], v153 offset:3072
	ds_read_b128 v[174:177], v153 offset:4096
	ds_read_b128 v[178:181], v153 offset:5120
	ds_read_b128 v[182:185], v153 offset:6144
	ds_read_b128 v[186:189], v153 offset:7168
	global_load_lds_dwordx4 v[190:191], off
	v_lshl_add_u64 v[190:191], s[22:23], 0, v[144:145]
	s_add_i32 m0, s15, 0xe000
	s_nop 0
	global_load_lds_dwordx4 v[190:191], off
	s_waitcnt lgkmcnt(8)
	s_barrier
	s_waitcnt lgkmcnt(0)
	s_setprio 1
	s_waitcnt lgkmcnt(0)
	v_mfma_f32_16x16x32_bf16 v[132:135], v[120:123], v[158:161], v[132:135]
	v_mfma_f32_16x16x32_bf16 v[128:131], v[146:149], v[158:161], v[128:131]
	v_mfma_f32_16x16x32_bf16 v[116:119], v[120:123], v[166:169], v[116:119]
	v_mfma_f32_16x16x32_bf16 v[112:115], v[146:149], v[166:169], v[112:115]
	v_mfma_f32_16x16x32_bf16 v[108:111], v[120:123], v[174:177], v[108:111]
	v_mfma_f32_16x16x32_bf16 v[104:107], v[146:149], v[174:177], v[104:107]
	v_mfma_f32_16x16x32_bf16 v[100:103], v[120:123], v[182:185], v[100:103]
	v_mfma_f32_16x16x32_bf16 v[96:99], v[146:149], v[182:185], v[96:99]
	v_mfma_f32_16x16x32_bf16 v[132:135], v[124:127], v[162:165], v[132:135]
	v_mfma_f32_16x16x32_bf16 v[128:131], v[154:157], v[162:165], v[128:131]
	v_mfma_f32_16x16x32_bf16 v[116:119], v[124:127], v[170:173], v[116:119]
	v_mfma_f32_16x16x32_bf16 v[112:115], v[154:157], v[170:173], v[112:115]
	v_mfma_f32_16x16x32_bf16 v[108:111], v[124:127], v[178:181], v[108:111]
	v_mfma_f32_16x16x32_bf16 v[104:107], v[154:157], v[178:181], v[104:107]
	v_mfma_f32_16x16x32_bf16 v[100:103], v[124:127], v[186:189], v[100:103]
	v_mfma_f32_16x16x32_bf16 v[96:99], v[154:157], v[186:189], v[96:99]
	s_setprio 0
	s_barrier
	s_add_i32 s54, 0, 0x14000
	v_add_u32_e32 v190, s54, v151
	s_add_i32 s51, s51, s38
	ds_read_b128 v[194:197], v190
	ds_read_b128 v[200:203], v190 offset:1024
	ds_read_b128 v[204:207], v190 offset:2048
	ds_read_b128 v[208:211], v190 offset:3072
	v_lshl_add_u64 v[190:191], s[24:25], 0, v[192:193]
	s_mov_b32 m0, s51
	v_lshl_add_u64 v[212:213], s[24:25], 0, v[140:141]
	global_load_lds_dwordx4 v[190:191], off
	s_add_i32 m0, s51, 0x2000
	s_nop 0
	global_load_lds_dwordx4 v[212:213], off
	s_barrier
	s_waitcnt lgkmcnt(0)
	s_setprio 1
	s_waitcnt lgkmcnt(0)
	v_mfma_f32_16x16x32_bf16 v[60:63], v[194:197], v[158:161], v[60:63]
	v_mfma_f32_16x16x32_bf16 v[56:59], v[204:207], v[158:161], v[56:59]
	v_mfma_f32_16x16x32_bf16 v[52:55], v[194:197], v[166:169], v[52:55]
	v_mfma_f32_16x16x32_bf16 v[48:51], v[204:207], v[166:169], v[48:51]
	v_mfma_f32_16x16x32_bf16 v[44:47], v[194:197], v[174:177], v[44:47]
	v_mfma_f32_16x16x32_bf16 v[40:43], v[204:207], v[174:177], v[40:43]
	v_mfma_f32_16x16x32_bf16 v[36:39], v[194:197], v[182:185], v[36:39]
	v_mfma_f32_16x16x32_bf16 v[32:35], v[204:207], v[182:185], v[32:35]
	v_mfma_f32_16x16x32_bf16 v[60:63], v[200:203], v[162:165], v[60:63]
	v_mfma_f32_16x16x32_bf16 v[56:59], v[208:211], v[162:165], v[56:59]
	v_mfma_f32_16x16x32_bf16 v[52:55], v[200:203], v[170:173], v[52:55]
	v_mfma_f32_16x16x32_bf16 v[48:51], v[208:211], v[170:173], v[48:51]
	v_mfma_f32_16x16x32_bf16 v[44:47], v[200:203], v[178:181], v[44:47]
	v_mfma_f32_16x16x32_bf16 v[40:43], v[208:211], v[178:181], v[40:43]
	v_mfma_f32_16x16x32_bf16 v[36:39], v[200:203], v[186:189], v[36:39]
	v_mfma_f32_16x16x32_bf16 v[32:35], v[208:211], v[186:189], v[32:35]
	s_setprio 0
	s_mov_b32 m0, s15
	v_lshl_add_u64 v[214:215], s[26:27], 0, v[136:137]
	s_barrier
	ds_read_b128 v[158:161], v153 offset:16384
	ds_read_b128 v[162:165], v153 offset:17408
	ds_read_b128 v[166:169], v153 offset:18432
	ds_read_b128 v[170:173], v153 offset:19456
	ds_read_b128 v[174:177], v153 offset:20480
	ds_read_b128 v[178:181], v153 offset:21504
	ds_read_b128 v[182:185], v153 offset:22528
	ds_read_b128 v[186:189], v153 offset:23552
	global_load_lds_dwordx4 v[214:215], off
	v_lshl_add_u64 v[216:217], s[26:27], 0, v[138:139]
	s_mov_b32 m0, s39
	s_nop 0
	global_load_lds_dwordx4 v[216:217], off
	s_barrier
	s_waitcnt lgkmcnt(0)
	s_setprio 1
	s_waitcnt lgkmcnt(0)
	v_mfma_f32_16x16x32_bf16 v[92:95], v[120:123], v[158:161], v[92:95]
	v_mfma_f32_16x16x32_bf16 v[88:91], v[146:149], v[158:161], v[88:91]
	v_mfma_f32_16x16x32_bf16 v[84:87], v[120:123], v[166:169], v[84:87]
	v_mfma_f32_16x16x32_bf16 v[80:83], v[146:149], v[166:169], v[80:83]
	v_mfma_f32_16x16x32_bf16 v[76:79], v[120:123], v[174:177], v[76:79]
	v_mfma_f32_16x16x32_bf16 v[72:75], v[146:149], v[174:177], v[72:75]
	v_mfma_f32_16x16x32_bf16 v[68:71], v[120:123], v[182:185], v[68:71]
	v_mfma_f32_16x16x32_bf16 v[64:67], v[146:149], v[182:185], v[64:67]
	v_mfma_f32_16x16x32_bf16 v[92:95], v[124:127], v[162:165], v[92:95]
	v_mfma_f32_16x16x32_bf16 v[88:91], v[154:157], v[162:165], v[88:91]
	v_mfma_f32_16x16x32_bf16 v[84:87], v[124:127], v[170:173], v[84:87]
	v_mfma_f32_16x16x32_bf16 v[80:83], v[154:157], v[170:173], v[80:83]
	v_mfma_f32_16x16x32_bf16 v[76:79], v[124:127], v[178:181], v[76:79]
	v_mfma_f32_16x16x32_bf16 v[72:75], v[154:157], v[178:181], v[72:75]
	v_mfma_f32_16x16x32_bf16 v[68:71], v[124:127], v[186:189], v[68:71]
	v_mfma_f32_16x16x32_bf16 v[64:67], v[154:157], v[186:189], v[64:67]
	s_setprio 0
	s_barrier
; #define PG8_STAGE(bufoff, gbase, voff) do { _Pragma("unroll") for (int _i = 0; _i < 2; ++_i) \
;         __builtin_amdgcn_global_load_lds((const unsigned*)((const char*)(gbase) + (voff)[_i]), (PG8_LAS unsigned*)(lds + (bufoff) + ldsw + _i * 8192), 16, 0, 0); } while (0)
; #define PG8_LDA(dst, b, h) do { _Pragma("unroll") for (int m = 0; m < 4; ++m) _Pragma("unroll") for (int k = 0; k < 2; ++k) dst[m][k] = *(const PG8_LAS bf16x8*)(lds + PG8_SA(b, h) + aoff + m * 2048 + k * 1024); } while (0)
; #define PG8_LDB(dst, b, h) do { _Pragma("unroll") for (int n = 0; n < 2; ++n) _Pragma("unroll") for (int k = 0; k < 2; ++k) dst[n][k] = *(const PG8_LAS bf16x8*)(lds + PG8_SB(b, h) + boff + n * 2048 + k * 1024); } while (0)
; #define PG8_MMA(ai, bj, At, Bt) do { __builtin_amdgcn_s_setprio(1); _Pragma("unroll") for (int m = 0; m < 4; ++m) _Pragma("unroll") for (int n = 0; n < 2; ++n) _Pragma("unroll") for (int k = 0; k < 2; ++k) \
;         acc[ai][bj][m][n] = __builtin_amdgcn_mfma_f32_16x16x32_bf16(Bt[n][k], At[m][k], acc[ai][bj][m][n], 0, 0, 0); __builtin_amdgcn_s_setprio(0); } while (0)
; #define PG8_WAIT_V(n) asm volatile("s_waitcnt vmcnt(" #n ")" ::: "memory")
; #define PG8_WAIT_L(n) asm volatile("s_waitcnt lgkmcnt(" #n ")" ::: "memory")
; #define PG8_BAR __builtin_amdgcn_s_barrier()
; #define PG8_SCHED __builtin_amdgcn_sched_barrier(0)
; template <class Epi, class Sched>
; __device__ __forceinline__ void gemm_phase(PG8_LAS unsigned char* lds, const Gemm g, const Sched& S, const Epi& E, int tid_in) {
;     ...
;             PG8_WAIT_V(6); PG8_BAR; PG8_MMA(1, 1, At, B1); PG8_BAR;
;             PG8_LDB(B0, 1, 0); PG8_SCHED; PG8_LDA(At, 1, 0); PG8_STAGE(PG8_SA(0, 1), a2 + hstep, voffA);
;             PG8_WAIT_L(8); PG8_BAR; PG8_WAIT_L(0); PG8_MMA(0, 0, At, B0); PG8_BAR; PG8_SCHED;
;             PG8_LDB(B1, 1, 1); PG8_STAGE(PG8_SB(1, 0), b3, voffB);
;             PG8_BAR; PG8_WAIT_L(0); PG8_MMA(0, 1, At, B1); PG8_BAR;
;             PG8_LDA(At, 1, 1); PG8_STAGE(PG8_SA(1, 0), a3, voffA);
;             PG8_BAR; PG8_WAIT_L(0); PG8_MMA(1, 0, At, B0); PG8_BAR; PG8_SCHED;
	s_add_u32 s52, s24, 0x40000
	s_addc_u32 s53, s25, 0
	s_add_i32 s51, s54, s38
	v_lshl_add_u64 v[120:121], s[52:53], 0, v[192:193]
	s_mov_b32 m0, s51
	s_nop 0
	global_load_lds_dwordx4 v[120:121], off
	v_lshl_add_u64 v[120:121], s[52:53], 0, v[140:141]
	s_add_i32 m0, s51, 0x2000
	s_nop 0
	global_load_lds_dwordx4 v[120:121], off
	s_waitcnt vmcnt(6)
	s_barrier
	s_setprio 1
	v_mfma_f32_16x16x32_bf16 v[28:31], v[194:197], v[158:161], v[28:31]
	v_mfma_f32_16x16x32_bf16 v[24:27], v[204:207], v[158:161], v[24:27]
	v_mfma_f32_16x16x32_bf16 v[20:23], v[194:197], v[166:169], v[20:23]
	v_mfma_f32_16x16x32_bf16 v[16:19], v[204:207], v[166:169], v[16:19]
	v_mfma_f32_16x16x32_bf16 v[12:15], v[194:197], v[174:177], v[12:15]
	v_mfma_f32_16x16x32_bf16 v[8:11], v[204:207], v[174:177], v[8:11]
	v_mfma_f32_16x16x32_bf16 v[4:7], v[194:197], v[182:185], v[4:7]
	v_mfma_f32_16x16x32_bf16 v[0:3], v[204:207], v[182:185], v[0:3]
	v_mfma_f32_16x16x32_bf16 v[28:31], v[200:203], v[162:165], v[28:31]
	v_mfma_f32_16x16x32_bf16 v[24:27], v[208:211], v[162:165], v[24:27]
	v_mfma_f32_16x16x32_bf16 v[20:23], v[200:203], v[170:173], v[20:23]
	v_mfma_f32_16x16x32_bf16 v[16:19], v[208:211], v[170:173], v[16:19]
	v_mfma_f32_16x16x32_bf16 v[12:15], v[200:203], v[178:181], v[12:15]
	v_mfma_f32_16x16x32_bf16 v[8:11], v[208:211], v[178:181], v[8:11]
	v_mfma_f32_16x16x32_bf16 v[4:7], v[200:203], v[186:189], v[4:7]
	v_mfma_f32_16x16x32_bf16 v[0:3], v[208:211], v[186:189], v[0:3]
	s_setprio 0
	s_add_i32 s51, 0, 0x18000
	v_add_u32_e32 v154, s51, v151
	s_barrier
	ds_read_b128 v[120:123], v154
	ds_read_b128 v[124:127], v154 offset:1024
	ds_read_b128 v[146:149], v154 offset:2048
	ds_read_b128 v[154:157], v154 offset:3072
	s_add_u32 s26, s26, 0x40000
	s_addc_u32 s27, s27, 0
	s_mov_b32 m0, s40
	v_lshl_add_u64 v[194:195], s[26:27], 0, v[136:137]
	ds_read_b128 v[158:161], v153 offset:32768
	ds_read_b128 v[162:165], v153 offset:33792
	ds_read_b128 v[166:169], v153 offset:34816
	ds_read_b128 v[170:173], v153 offset:35840
	ds_read_b128 v[174:177], v153 offset:36864
	ds_read_b128 v[178:181], v153 offset:37888
	ds_read_b128 v[182:185], v153 offset:38912
	ds_read_b128 v[186:189], v153 offset:39936
	global_load_lds_dwordx4 v[194:195], off
	v_lshl_add_u64 v[194:195], s[26:27], 0, v[138:139]
	s_mov_b32 m0, s41
	s_nop 0
	global_load_lds_dwordx4 v[194:195], off
	s_waitcnt lgkmcnt(8)
	s_barrier
	s_waitcnt lgkmcnt(0)
	s_setprio 1
	s_waitcnt lgkmcnt(0)
	v_mfma_f32_16x16x32_bf16 v[132:135], v[120:123], v[158:161], v[132:135]
	v_mfma_f32_16x16x32_bf16 v[128:131], v[146:149], v[158:161], v[128:131]
	v_mfma_f32_16x16x32_bf16 v[116:119], v[120:123], v[166:169], v[116:119]
	v_mfma_f32_16x16x32_bf16 v[112:115], v[146:149], v[166:169], v[112:115]
	v_mfma_f32_16x16x32_bf16 v[108:111], v[120:123], v[174:177], v[108:111]
	v_mfma_f32_16x16x32_bf16 v[104:107], v[146:149], v[174:177], v[104:107]
	v_mfma_f32_16x16x32_bf16 v[100:103], v[120:123], v[182:185], v[100:103]
	v_mfma_f32_16x16x32_bf16 v[96:99], v[146:149], v[182:185], v[96:99]
	v_mfma_f32_16x16x32_bf16 v[132:135], v[124:127], v[162:165], v[132:135]
	v_mfma_f32_16x16x32_bf16 v[128:131], v[154:157], v[162:165], v[128:131]
	v_mfma_f32_16x16x32_bf16 v[116:119], v[124:127], v[170:173], v[116:119]
	v_mfma_f32_16x16x32_bf16 v[112:115], v[154:157], v[170:173], v[112:115]
	v_mfma_f32_16x16x32_bf16 v[108:111], v[124:127], v[178:181], v[108:111]
	v_mfma_f32_16x16x32_bf16 v[104:107], v[154:157], v[178:181], v[104:107]
	v_mfma_f32_16x16x32_bf16 v[100:103], v[124:127], v[186:189], v[100:103]
	v_mfma_f32_16x16x32_bf16 v[96:99], v[154:157], v[186:189], v[96:99]
	s_setprio 0
	s_barrier
	s_add_i32 s26, 0, 0x1c000
	s_add_i32 s27, s51, s38
	v_add_u32_e32 v199, s26, v151
	v_lshl_add_u64 v[190:191], v[190:191], 0, s[74:75]
	s_mov_b32 m0, s27
	ds_read_b128 v[194:197], v199
	ds_read_b128 v[200:203], v199 offset:1024
	ds_read_b128 v[204:207], v199 offset:2048
	ds_read_b128 v[208:211], v199 offset:3072
	global_load_lds_dwordx4 v[190:191], off
	v_lshl_add_u64 v[190:191], v[212:213], 0, s[74:75]
	s_add_i32 m0, s27, 0x2000
	s_nop 0
	global_load_lds_dwordx4 v[190:191], off
	s_barrier
	s_waitcnt lgkmcnt(0)
	s_setprio 1
	s_waitcnt lgkmcnt(0)
	v_mfma_f32_16x16x32_bf16 v[60:63], v[194:197], v[158:161], v[60:63]
	v_mfma_f32_16x16x32_bf16 v[56:59], v[204:207], v[158:161], v[56:59]
	v_mfma_f32_16x16x32_bf16 v[52:55], v[194:197], v[166:169], v[52:55]
	v_mfma_f32_16x16x32_bf16 v[48:51], v[204:207], v[166:169], v[48:51]
	v_mfma_f32_16x16x32_bf16 v[44:47], v[194:197], v[174:177], v[44:47]
	v_mfma_f32_16x16x32_bf16 v[40:43], v[204:207], v[174:177], v[40:43]
	v_mfma_f32_16x16x32_bf16 v[36:39], v[194:197], v[182:185], v[36:39]
	v_mfma_f32_16x16x32_bf16 v[32:35], v[204:207], v[182:185], v[32:35]
	v_mfma_f32_16x16x32_bf16 v[60:63], v[200:203], v[162:165], v[60:63]
	v_mfma_f32_16x16x32_bf16 v[56:59], v[208:211], v[162:165], v[56:59]
	v_mfma_f32_16x16x32_bf16 v[52:55], v[200:203], v[170:173], v[52:55]
	v_mfma_f32_16x16x32_bf16 v[48:51], v[208:211], v[170:173], v[48:51]
	v_mfma_f32_16x16x32_bf16 v[44:47], v[200:203], v[178:181], v[44:47]
	v_mfma_f32_16x16x32_bf16 v[40:43], v[208:211], v[178:181], v[40:43]
	v_mfma_f32_16x16x32_bf16 v[36:39], v[200:203], v[186:189], v[36:39]
	v_mfma_f32_16x16x32_bf16 v[32:35], v[208:211], v[186:189], v[32:35]
	s_setprio 0
	s_mov_b32 m0, s42
	v_lshl_add_u64 v[190:191], v[214:215], 0, s[74:75]
	s_barrier
	ds_read_b128 v[158:161], v153 offset:49152
	ds_read_b128 v[162:165], v153 offset:50176
	ds_read_b128 v[166:169], v153 offset:51200
	ds_read_b128 v[170:173], v153 offset:52224
	ds_read_b128 v[174:177], v153 offset:53248
	ds_read_b128 v[178:181], v153 offset:54272
	ds_read_b128 v[182:185], v153 offset:55296
	ds_read_b128 v[186:189], v153 offset:56320
	global_load_lds_dwordx4 v[190:191], off
	v_lshl_add_u64 v[190:191], v[216:217], 0, s[74:75]
	s_mov_b32 m0, s43
	s_nop 0
	global_load_lds_dwordx4 v[190:191], off
	s_barrier
; __device__ __forceinline__ unsigned cvt_pk_bf16(float lo, float hi) { unsigned r; asm volatile("s_nop 0\n\tv_cvt_pk_bf16_f32 %0, %1, %2\n\ts_nop 1" : "=v"(r) : "v"(lo), "v"(hi)); return r; }
; #define PG8_STAGE(bufoff, gbase, voff) do { _Pragma("unroll") for (int _i = 0; _i < 2; ++_i) \
;         __builtin_amdgcn_global_load_lds((const unsigned*)((const char*)(gbase) + (voff)[_i]), (PG8_LAS unsigned*)(lds + (bufoff) + ldsw + _i * 8192), 16, 0, 0); } while (0)
; #define PG8_MMA(ai, bj, At, Bt) do { __builtin_amdgcn_s_setprio(1); _Pragma("unroll") for (int m = 0; m < 4; ++m) _Pragma("unroll") for (int n = 0; n < 2; ++n) _Pragma("unroll") for (int k = 0; k < 2; ++k) \
;         acc[ai][bj][m][n] = __builtin_amdgcn_mfma_f32_16x16x32_bf16(Bt[n][k], At[m][k], acc[ai][bj][m][n], 0, 0, 0); __builtin_amdgcn_s_setprio(0); } while (0)
; #define PG8_WAIT_V(n) asm volatile("s_waitcnt vmcnt(" #n ")" ::: "memory")
; #define PG8_WAIT_L(n) asm volatile("s_waitcnt lgkmcnt(" #n ")" ::: "memory")
; template <class Epi, class Sched>
; __device__ __forceinline__ void gemm_phase(PG8_LAS unsigned char* lds, const Gemm g, const Sched& S, const Epi& E, int tid_in) {
;     ...
;             PG8_BAR; PG8_WAIT_L(0); PG8_MMA(1, 0, At, B0); PG8_BAR; PG8_SCHED;
;             PG8_STAGE(PG8_SB(1, 1), b3 + hstep, voffB);
;             PG8_WAIT_V(6); PG8_BAR; PG8_MMA(1, 1, At, B1); PG8_BAR;
;     __device__ __forceinline__ void operator()(f32x4 (&acc)[2][2][4][2], const Unit& u, int wr, int wc, int fr, int fq) const {
;         const int row0 = u.pm * 256 + wr * 64 + fr, col0 = u.pn * 256 + wc * 32 + 8 * fq;
; #pragma unroll
;         for (int bj = 0; bj < 2; ++bj) { const f32x4 b0 = *(const f32x4*)(bias + col0 + bj * 128), b1 = *(const f32x4*)(bias + col0 + bj * 128 + 4);
; #pragma unroll
;             for (int ai = 0; ai < 2; ++ai)
; #pragma unroll
;                 for (int m = 0; m < 4; ++m) { f32x4 v0 = acc[ai][bj][m][0] + b0, v1 = acc[ai][bj][m][1] + b1;
; #pragma unroll
;                     for (int j = 0; j < 4; ++j) { v0[j] = fmaxf(v0[j], 0.f); v0[j] *= v0[j]; v1[j] = fmaxf(v1[j], 0.f); v1[j] *= v1[j]; }
;                     u32x4 w; w.x = cvt_pk_bf16(v0[0], v0[1]); w.y = cvt_pk_bf16(v0[2], v0[3]); w.z = cvt_pk_bf16(v1[0], v1[1]); w.w = cvt_pk_bf16(v1[2], v1[3]);
;                     *(u32x4*)(O + (size_t)(row0 + ai * 128 + m * 16) * 4096 + col0 + bj * 128) = w; } }
	s_waitcnt lgkmcnt(0)
	s_setprio 1
	s_waitcnt lgkmcnt(0)
	v_mfma_f32_16x16x32_bf16 v[92:95], v[120:123], v[158:161], v[92:95]
	v_mfma_f32_16x16x32_bf16 v[88:91], v[146:149], v[158:161], v[88:91]
	v_mfma_f32_16x16x32_bf16 v[84:87], v[120:123], v[166:169], v[84:87]
	v_mfma_f32_16x16x32_bf16 v[80:83], v[146:149], v[166:169], v[80:83]
	v_mfma_f32_16x16x32_bf16 v[76:79], v[120:123], v[174:177], v[76:79]
	v_mfma_f32_16x16x32_bf16 v[72:75], v[146:149], v[174:177], v[72:75]
	v_mfma_f32_16x16x32_bf16 v[68:71], v[120:123], v[182:185], v[68:71]
	v_mfma_f32_16x16x32_bf16 v[64:67], v[146:149], v[182:185], v[64:67]
	v_mfma_f32_16x16x32_bf16 v[92:95], v[124:127], v[162:165], v[92:95]
	v_mfma_f32_16x16x32_bf16 v[88:91], v[154:157], v[162:165], v[88:91]
	v_mfma_f32_16x16x32_bf16 v[84:87], v[124:127], v[170:173], v[84:87]
	v_mfma_f32_16x16x32_bf16 v[80:83], v[154:157], v[170:173], v[80:83]
	v_mfma_f32_16x16x32_bf16 v[76:79], v[124:127], v[178:181], v[76:79]
	v_mfma_f32_16x16x32_bf16 v[72:75], v[154:157], v[178:181], v[72:75]
	v_mfma_f32_16x16x32_bf16 v[68:71], v[124:127], v[186:189], v[68:71]
	v_mfma_f32_16x16x32_bf16 v[64:67], v[154:157], v[186:189], v[64:67]
	s_setprio 0
	s_barrier
	s_add_u32 s24, s24, 0x40080
	s_addc_u32 s25, s25, 0
	s_add_i32 s26, s26, s38
	v_lshl_add_u64 v[120:121], s[24:25], 0, v[192:193]
	s_mov_b32 m0, s26
	s_nop 0
	global_load_lds_dwordx4 v[120:121], off
	v_lshl_add_u64 v[120:121], s[24:25], 0, v[140:141]
	s_add_i32 m0, s26, 0x2000
	s_nop 0
	global_load_lds_dwordx4 v[120:121], off
	s_waitcnt vmcnt(6)
	s_barrier
	s_setprio 1
	v_mfma_f32_16x16x32_bf16 v[28:31], v[194:197], v[158:161], v[28:31]
	v_mfma_f32_16x16x32_bf16 v[24:27], v[204:207], v[158:161], v[24:27]
	v_mfma_f32_16x16x32_bf16 v[20:23], v[194:197], v[166:169], v[20:23]
	v_mfma_f32_16x16x32_bf16 v[16:19], v[204:207], v[166:169], v[16:19]
	v_mfma_f32_16x16x32_bf16 v[12:15], v[194:197], v[174:177], v[12:15]
	v_mfma_f32_16x16x32_bf16 v[8:11], v[204:207], v[174:177], v[8:11]
	v_mfma_f32_16x16x32_bf16 v[4:7], v[194:197], v[182:185], v[4:7]
	v_mfma_f32_16x16x32_bf16 v[0:3], v[204:207], v[182:185], v[0:3]
	v_mfma_f32_16x16x32_bf16 v[28:31], v[200:203], v[162:165], v[28:31]
	v_mfma_f32_16x16x32_bf16 v[24:27], v[208:211], v[162:165], v[24:27]
	v_mfma_f32_16x16x32_bf16 v[20:23], v[200:203], v[170:173], v[20:23]
	v_mfma_f32_16x16x32_bf16 v[16:19], v[208:211], v[170:173], v[16:19]
	v_mfma_f32_16x16x32_bf16 v[12:15], v[200:203], v[178:181], v[12:15]
	v_mfma_f32_16x16x32_bf16 v[8:11], v[208:211], v[178:181], v[8:11]
	v_mfma_f32_16x16x32_bf16 v[4:7], v[200:203], v[186:189], v[4:7]
	v_mfma_f32_16x16x32_bf16 v[0:3], v[208:211], v[186:189], v[0:3]
	s_setprio 0
	s_add_i32 s50, s50, 2
	s_add_u32 s22, s22, 0x100
	s_addc_u32 s23, s23, 0
	s_add_u32 s48, s48, 0x100
	s_addc_u32 s49, s49, 0
	s_cmp_gt_u32 s50, 13
	s_barrier
	s_cbranch_scc0 .LBB0_295
	v_lshl_or_b32 v154, s33, 8, v152
	v_ashrrev_i32_e32 v155, 31, v154
	v_lshl_add_u64 v[146:147], v[154:155], 2, s[6:7]
	global_load_dwordx4 v[120:123], v[146:147], off offset:16
	global_load_dwordx4 v[124:127], v[146:147], off
	v_lshl_add_u32 v148, s14, 8, v150
	v_ashrrev_i32_e32 v149, 31, v148
	s_mov_b32 s5, 0x100000
	s_mov_b64 s[22:23], 0x100000
	s_mov_b32 s33, s4
	s_mov_b32 s14, s8
	s_mov_b64 s[24:25], s[12:13]
	s_waitcnt vmcnt(0)
	v_pk_add_f32 v[128:129], v[128:129], v[120:121]
	v_pk_add_f32 v[134:135], v[134:135], v[126:127]
	v_pk_add_f32 v[132:133], v[132:133], v[124:125]
	v_pk_add_f32 v[130:131], v[130:131], v[122:123]
	v_max_f32_e32 v132, 0, v132
	v_max_f32_e32 v128, 0, v128
	v_max_f32_e32 v133, 0, v133
	v_max_f32_e32 v129, 0, v129
	v_max_f32_e32 v134, 0, v134
	v_mul_f32_e32 v132, v132, v132
	v_mul_f32_e32 v128, v128, v128
	v_mul_f32_e32 v133, v133, v133
	v_mul_f32_e32 v129, v129, v129
	v_mul_f32_e32 v134, v134, v134
	v_max_f32_e32 v130, 0, v130
	v_max_f32_e32 v135, 0, v135
	v_max_f32_e32 v131, 0, v131
	v_mul_f32_e32 v130, v130, v130
	v_mul_f32_e32 v135, v135, v135
	v_mul_f32_e32 v131, v131, v131
	v_cvt_pk_bf16_f32 v132, v132, v133
	v_cvt_pk_bf16_f32 v133, v134, v135
	v_cvt_pk_bf16_f32 v134, v128, v129
	v_lshlrev_b64 v[128:129], 13, v[148:149]
	v_cvt_pk_bf16_f32 v135, v130, v131
	v_lshl_add_u64 v[128:129], s[0:1], 0, v[128:129]
	v_lshlrev_b64 v[130:131], 1, v[154:155]
	v_pk_add_f32 v[114:115], v[114:115], v[122:123]
	v_lshl_add_u64 v[128:129], v[128:129], 0, v[130:131]
	v_pk_add_f32 v[118:119], v[118:119], v[126:127]
	v_pk_add_f32 v[116:117], v[116:117], v[124:125]
	v_pk_add_f32 v[112:113], v[112:113], v[120:121]
	v_max_f32_e32 v114, 0, v114
	global_store_dwordx4 v[128:129], v[132:135], off
	v_max_f32_e32 v116, 0, v116
	v_max_f32_e32 v112, 0, v112
	v_mul_f32_e32 v132, v114, v114
	v_max_f32_e32 v114, 0, v119
	v_mul_f32_e32 v116, v116, v116
	v_mul_f32_e32 v112, v112, v112
	v_max_f32_e32 v117, 0, v117
	v_max_f32_e32 v113, 0, v113
	v_max_f32_e32 v118, 0, v118
	v_mul_f32_e32 v119, v114, v114
	v_max_f32_e32 v114, 0, v115
	v_mul_f32_e32 v117, v117, v117
	v_mul_f32_e32 v113, v113, v113
	v_mul_f32_e32 v118, v118, v118
	v_mul_f32_e32 v133, v114, v114
	v_cvt_pk_bf16_f32 v114, v116, v117
	v_cvt_pk_bf16_f32 v115, v118, v119
	v_cvt_pk_bf16_f32 v116, v112, v113
	v_or_b32_e32 v112, 16, v148
	v_ashrrev_i32_e32 v113, 31, v112
	v_lshlrev_b64 v[112:113], 13, v[112:113]
	v_lshl_add_u64 v[112:113], s[0:1], 0, v[112:113]
	v_pk_add_f32 v[106:107], v[106:107], v[122:123]
	v_lshl_add_u64 v[112:113], v[112:113], 0, v[130:131]
	v_pk_add_f32 v[110:111], v[110:111], v[126:127]
	v_pk_add_f32 v[108:109], v[108:109], v[124:125]
	v_pk_add_f32 v[104:105], v[104:105], v[120:121]
	v_max_f32_e32 v106, 0, v106
	v_cvt_pk_bf16_f32 v117, v132, v133
	global_store_dwordx4 v[112:113], v[114:117], off
; __device__ __forceinline__ unsigned cvt_pk_bf16(float lo, float hi) { unsigned r; asm volatile("s_nop 0\n\tv_cvt_pk_bf16_f32 %0, %1, %2\n\ts_nop 1" : "=v"(r) : "v"(lo), "v"(hi)); return r; }
;     __device__ __forceinline__ void operator()(f32x4 (&acc)[2][2][4][2], const Unit& u, int wr, int wc, int fr, int fq) const {
;     ...
;         for (int bj = 0; bj < 2; ++bj) { const f32x4 b0 = *(const f32x4*)(bias + col0 + bj * 128), b1 = *(const f32x4*)(bias + col0 + bj * 128 + 4);
; #pragma unroll
;             for (int ai = 0; ai < 2; ++ai)
; #pragma unroll
;                 for (int m = 0; m < 4; ++m) { f32x4 v0 = acc[ai][bj][m][0] + b0, v1 = acc[ai][bj][m][1] + b1;
; #pragma unroll
;                     for (int j = 0; j < 4; ++j) { v0[j] = fmaxf(v0[j], 0.f); v0[j] *= v0[j]; v1[j] = fmaxf(v1[j], 0.f); v1[j] *= v1[j]; }
;                     u32x4 w; w.x = cvt_pk_bf16(v0[0], v0[1]); w.y = cvt_pk_bf16(v0[2], v0[3]); w.z = cvt_pk_bf16(v1[0], v1[1]); w.w = cvt_pk_bf16(v1[2], v1[3]);
;                     *(u32x4*)(O + (size_t)(row0 + ai * 128 + m * 16) * 4096 + col0 + bj * 128) = w; } }
	v_max_f32_e32 v108, 0, v108
	v_max_f32_e32 v104, 0, v104
	v_mul_f32_e32 v114, v106, v106
	v_max_f32_e32 v106, 0, v111
	v_mul_f32_e32 v108, v108, v108
	v_mul_f32_e32 v104, v104, v104
	v_max_f32_e32 v109, 0, v109
	v_max_f32_e32 v105, 0, v105
	v_max_f32_e32 v110, 0, v110
	v_mul_f32_e32 v111, v106, v106
	v_max_f32_e32 v106, 0, v107
	v_mul_f32_e32 v109, v109, v109
	v_mul_f32_e32 v105, v105, v105
	v_mul_f32_e32 v110, v110, v110
	v_mul_f32_e32 v115, v106, v106
	v_cvt_pk_bf16_f32 v106, v108, v109
	v_cvt_pk_bf16_f32 v107, v110, v111
	v_cvt_pk_bf16_f32 v108, v104, v105
	v_or_b32_e32 v104, 32, v148
	v_ashrrev_i32_e32 v105, 31, v104
	v_lshlrev_b64 v[104:105], 13, v[104:105]
	v_lshl_add_u64 v[104:105], s[0:1], 0, v[104:105]
	v_pk_add_f32 v[98:99], v[98:99], v[122:123]
	v_lshl_add_u64 v[104:105], v[104:105], 0, v[130:131]
	v_pk_add_f32 v[102:103], v[102:103], v[126:127]
	v_pk_add_f32 v[100:101], v[100:101], v[124:125]
	v_pk_add_f32 v[96:97], v[96:97], v[120:121]
	v_max_f32_e32 v98, 0, v98
	v_cvt_pk_bf16_f32 v109, v114, v115
	global_store_dwordx4 v[104:105], v[106:109], off
	v_max_f32_e32 v100, 0, v100
	v_max_f32_e32 v96, 0, v96
	v_mul_f32_e32 v106, v98, v98
	v_max_f32_e32 v98, 0, v103
	v_mul_f32_e32 v100, v100, v100
	v_mul_f32_e32 v96, v96, v96
	v_max_f32_e32 v101, 0, v101
	v_max_f32_e32 v97, 0, v97
	v_max_f32_e32 v102, 0, v102
	v_mul_f32_e32 v103, v98, v98
	v_max_f32_e32 v98, 0, v99
	v_mul_f32_e32 v101, v101, v101
	v_mul_f32_e32 v97, v97, v97
	v_mul_f32_e32 v102, v102, v102
	v_mul_f32_e32 v107, v98, v98
	v_cvt_pk_bf16_f32 v98, v100, v101
	v_cvt_pk_bf16_f32 v99, v102, v103
	v_cvt_pk_bf16_f32 v100, v96, v97
	v_or_b32_e32 v96, 48, v148
	v_ashrrev_i32_e32 v97, 31, v96
	v_lshlrev_b64 v[96:97], 13, v[96:97]
	v_lshl_add_u64 v[96:97], s[0:1], 0, v[96:97]
	v_pk_add_f32 v[90:91], v[90:91], v[122:123]
	v_lshl_add_u64 v[96:97], v[96:97], 0, v[130:131]
	v_pk_add_f32 v[94:95], v[94:95], v[126:127]
	v_max_f32_e32 v90, 0, v90
	v_cvt_pk_bf16_f32 v101, v106, v107
	global_store_dwordx4 v[96:97], v[98:101], off
	v_pk_add_f32 v[92:93], v[92:93], v[124:125]
	v_max_f32_e32 v94, 0, v94
	v_mul_f32_e32 v98, v90, v90
	v_max_f32_e32 v90, 0, v95
	v_max_f32_e32 v92, 0, v92
	v_max_f32_e32 v93, 0, v93
	v_mul_f32_e32 v94, v94, v94
	v_mul_f32_e32 v95, v90, v90
	v_max_f32_e32 v90, 0, v91
	v_pk_add_f32 v[88:89], v[88:89], v[120:121]
	v_mul_f32_e32 v92, v92, v92
	v_mul_f32_e32 v93, v93, v93
	v_mul_f32_e32 v99, v90, v90
	v_cvt_pk_bf16_f32 v90, v92, v93
	v_cvt_pk_bf16_f32 v91, v94, v95
	v_add_co_u32_e32 v94, vcc, s5, v128
	v_pk_add_f32 v[82:83], v[82:83], v[122:123]
	v_max_f32_e32 v88, 0, v88
	v_max_f32_e32 v89, 0, v89
	v_addc_co_u32_e32 v95, vcc, 0, v129, vcc
	v_pk_add_f32 v[86:87], v[86:87], v[126:127]
	v_max_f32_e32 v82, 0, v82
	v_mul_f32_e32 v88, v88, v88
	v_mul_f32_e32 v89, v89, v89
	v_cvt_pk_bf16_f32 v92, v88, v89
	v_cvt_pk_bf16_f32 v93, v98, v99
	global_store_dwordx4 v[94:95], v[90:93], off
	v_pk_add_f32 v[84:85], v[84:85], v[124:125]
	v_max_f32_e32 v86, 0, v86
	v_mul_f32_e32 v90, v82, v82
	v_max_f32_e32 v82, 0, v87
	v_max_f32_e32 v84, 0, v84
	v_max_f32_e32 v85, 0, v85
	v_mul_f32_e32 v86, v86, v86
	v_mul_f32_e32 v87, v82, v82
	v_max_f32_e32 v82, 0, v83
	s_mov_b32 s5, 0x120000
	v_pk_add_f32 v[80:81], v[80:81], v[120:121]
	v_mul_f32_e32 v84, v84, v84
	v_mul_f32_e32 v85, v85, v85
	v_mul_f32_e32 v91, v82, v82
	v_cvt_pk_bf16_f32 v82, v84, v85
	v_cvt_pk_bf16_f32 v83, v86, v87
	v_add_co_u32_e32 v86, vcc, s5, v128
	v_pk_add_f32 v[74:75], v[74:75], v[122:123]
	v_max_f32_e32 v80, 0, v80
	v_max_f32_e32 v81, 0, v81
	v_addc_co_u32_e32 v87, vcc, 0, v129, vcc
	v_pk_add_f32 v[78:79], v[78:79], v[126:127]
	v_max_f32_e32 v74, 0, v74
	v_mul_f32_e32 v80, v80, v80
	v_mul_f32_e32 v81, v81, v81
	v_cvt_pk_bf16_f32 v84, v80, v81
	v_cvt_pk_bf16_f32 v85, v90, v91
	global_store_dwordx4 v[86:87], v[82:85], off
	v_pk_add_f32 v[76:77], v[76:77], v[124:125]
	v_max_f32_e32 v78, 0, v78
	v_mul_f32_e32 v82, v74, v74
	v_max_f32_e32 v74, 0, v79
	v_max_f32_e32 v76, 0, v76
	v_max_f32_e32 v77, 0, v77
	v_mul_f32_e32 v78, v78, v78
	v_mul_f32_e32 v79, v74, v74
	v_max_f32_e32 v74, 0, v75
	s_mov_b32 s5, 0x140000
	v_pk_add_f32 v[72:73], v[72:73], v[120:121]
	v_mul_f32_e32 v76, v76, v76
	v_mul_f32_e32 v77, v77, v77
	v_mul_f32_e32 v83, v74, v74
	v_cvt_pk_bf16_f32 v74, v76, v77
	v_cvt_pk_bf16_f32 v75, v78, v79
	v_add_co_u32_e32 v78, vcc, s5, v128
	v_pk_add_f32 v[64:65], v[64:65], v[120:121]
	v_max_f32_e32 v72, 0, v72
	v_max_f32_e32 v73, 0, v73
	v_addc_co_u32_e32 v79, vcc, 0, v129, vcc
	v_pk_add_f32 v[68:69], v[68:69], v[124:125]
	v_pk_add_f32 v[66:67], v[66:67], v[122:123]
	v_max_f32_e32 v64, 0, v64
	v_mul_f32_e32 v72, v72, v72
	v_mul_f32_e32 v73, v73, v73
	v_cvt_pk_bf16_f32 v76, v72, v73
	v_cvt_pk_bf16_f32 v77, v82, v83
	global_store_dwordx4 v[78:79], v[74:77], off
	v_pk_add_f32 v[70:71], v[70:71], v[126:127]
	v_max_f32_e32 v68, 0, v68
	v_mul_f32_e32 v74, v64, v64
	v_max_f32_e32 v64, 0, v69
	v_max_f32_e32 v65, 0, v65
	v_max_f32_e32 v66, 0, v66
	v_mul_f32_e32 v68, v68, v68
	v_mul_f32_e32 v64, v64, v64
	v_mul_f32_e32 v69, v65, v65
	v_max_f32_e32 v65, 0, v70
	v_mul_f32_e32 v70, v66, v66
	v_max_f32_e32 v66, 0, v71
	s_mov_b32 s5, 0x160000
	v_mul_f32_e32 v65, v65, v65
	v_mul_f32_e32 v66, v66, v66
	v_max_f32_e32 v67, 0, v67
	v_cvt_pk_bf16_f32 v64, v68, v64
	v_add_co_u32_e32 v68, vcc, s5, v128
	v_mul_f32_e32 v67, v67, v67
	v_cvt_pk_bf16_f32 v65, v65, v66
	v_cvt_pk_bf16_f32 v66, v74, v69
	s_nop 0
	v_addc_co_u32_e32 v69, vcc, 0, v129, vcc
	v_cvt_pk_bf16_f32 v67, v70, v67
	global_store_dwordx4 v[68:69], v[64:67], off
	global_load_dwordx4 v[64:67], v[146:147], off offset:528
	s_nop 0
	global_load_dwordx4 v[68:71], v[146:147], off offset:512
	v_lshl_add_u64 v[88:89], v[128:129], 0, s[22:23]
	s_mov_b64 s[22:23], 0x120000
	v_lshl_add_u64 v[80:81], v[128:129], 0, s[22:23]
	s_mov_b64 s[22:23], 0x140000
	v_lshl_add_u64 v[72:73], v[128:129], 0, s[22:23]
	s_mov_b64 s[22:23], 0x160000
	v_lshl_add_u64 v[74:75], v[128:129], 0, s[22:23]
	s_and_b64 vcc, exec, s[2:3]
	s_mov_b64 s[22:23], s[10:11]
	s_waitcnt vmcnt(0)
; __device__ __forceinline__ unsigned cvt_pk_bf16(float lo, float hi) { unsigned r; asm volatile("s_nop 0\n\tv_cvt_pk_bf16_f32 %0, %1, %2\n\ts_nop 1" : "=v"(r) : "v"(lo), "v"(hi)); return r; }
;     __device__ __forceinline__ void operator()(f32x4 (&acc)[2][2][4][2], const Unit& u, int wr, int wc, int fr, int fq) const {
;     ...
;         for (int bj = 0; bj < 2; ++bj) { const f32x4 b0 = *(const f32x4*)(bias + col0 + bj * 128), b1 = *(const f32x4*)(bias + col0 + bj * 128 + 4);
; #pragma unroll
;             for (int ai = 0; ai < 2; ++ai)
; #pragma unroll
;                 for (int m = 0; m < 4; ++m) { f32x4 v0 = acc[ai][bj][m][0] + b0, v1 = acc[ai][bj][m][1] + b1;
; #pragma unroll
;                     for (int j = 0; j < 4; ++j) { v0[j] = fmaxf(v0[j], 0.f); v0[j] *= v0[j]; v1[j] = fmaxf(v1[j], 0.f); v1[j] *= v1[j]; }
;                     u32x4 w; w.x = cvt_pk_bf16(v0[0], v0[1]); w.y = cvt_pk_bf16(v0[2], v0[3]); w.z = cvt_pk_bf16(v1[0], v1[1]); w.w = cvt_pk_bf16(v1[2], v1[3]);
;                     *(u32x4*)(O + (size_t)(row0 + ai * 128 + m * 16) * 4096 + col0 + bj * 128) = w; } }
	v_pk_add_f32 v[56:57], v[56:57], v[64:65]
	v_pk_add_f32 v[60:61], v[60:61], v[68:69]
	v_pk_add_f32 v[58:59], v[58:59], v[66:67]
	v_max_f32_e32 v56, 0, v56
	v_pk_add_f32 v[62:63], v[62:63], v[70:71]
	v_mul_f32_e32 v76, v56, v56
	v_max_f32_e32 v56, 0, v61
	v_max_f32_e32 v57, 0, v57
	v_max_f32_e32 v58, 0, v58
	v_max_f32_e32 v60, 0, v60
	v_mul_f32_e32 v56, v56, v56
	v_mul_f32_e32 v61, v57, v57
	v_max_f32_e32 v57, 0, v62
	v_mul_f32_e32 v62, v58, v58
	v_max_f32_e32 v58, 0, v63
	v_max_f32_e32 v59, 0, v59
	v_pk_add_f32 v[48:49], v[48:49], v[64:65]
	v_mul_f32_e32 v60, v60, v60
	v_mul_f32_e32 v57, v57, v57
	v_mul_f32_e32 v58, v58, v58
	v_mul_f32_e32 v59, v59, v59
	v_cvt_pk_bf16_f32 v56, v60, v56
	v_pk_add_f32 v[52:53], v[52:53], v[68:69]
	v_pk_add_f32 v[50:51], v[50:51], v[66:67]
	v_max_f32_e32 v48, 0, v48
	v_cvt_pk_bf16_f32 v57, v57, v58
	v_cvt_pk_bf16_f32 v58, v76, v61
	v_cvt_pk_bf16_f32 v59, v62, v59
	global_store_dwordx4 v[128:129], v[56:59], off offset:256
	v_pk_add_f32 v[54:55], v[54:55], v[70:71]
	v_max_f32_e32 v49, 0, v49
	v_mul_f32_e32 v56, v48, v48
	v_max_f32_e32 v48, 0, v53
	v_max_f32_e32 v50, 0, v50
	v_max_f32_e32 v52, 0, v52
	v_mul_f32_e32 v48, v48, v48
	v_mul_f32_e32 v53, v49, v49
	v_max_f32_e32 v49, 0, v54
	v_mul_f32_e32 v54, v50, v50
	v_max_f32_e32 v50, 0, v55
	v_max_f32_e32 v51, 0, v51
	v_pk_add_f32 v[40:41], v[40:41], v[64:65]
	v_mul_f32_e32 v52, v52, v52
	v_mul_f32_e32 v49, v49, v49
	v_mul_f32_e32 v50, v50, v50
	v_mul_f32_e32 v51, v51, v51
	v_cvt_pk_bf16_f32 v48, v52, v48
	v_pk_add_f32 v[44:45], v[44:45], v[68:69]
	v_pk_add_f32 v[42:43], v[42:43], v[66:67]
	v_max_f32_e32 v40, 0, v40
	v_cvt_pk_bf16_f32 v49, v49, v50
	v_cvt_pk_bf16_f32 v50, v56, v53
	v_cvt_pk_bf16_f32 v51, v54, v51
	global_store_dwordx4 v[112:113], v[48:51], off offset:256
	v_pk_add_f32 v[46:47], v[46:47], v[70:71]
	v_max_f32_e32 v41, 0, v41
	v_mul_f32_e32 v48, v40, v40
	v_max_f32_e32 v40, 0, v45
	v_max_f32_e32 v42, 0, v42
	v_max_f32_e32 v44, 0, v44
	v_mul_f32_e32 v40, v40, v40
	v_mul_f32_e32 v45, v41, v41
	v_max_f32_e32 v41, 0, v46
	v_mul_f32_e32 v46, v42, v42
	v_max_f32_e32 v42, 0, v47
	v_max_f32_e32 v43, 0, v43
	v_pk_add_f32 v[32:33], v[32:33], v[64:65]
	v_mul_f32_e32 v44, v44, v44
	v_mul_f32_e32 v41, v41, v41
	v_mul_f32_e32 v42, v42, v42
	v_mul_f32_e32 v43, v43, v43
	v_cvt_pk_bf16_f32 v40, v44, v40
	v_pk_add_f32 v[36:37], v[36:37], v[68:69]
	v_pk_add_f32 v[34:35], v[34:35], v[66:67]
	v_max_f32_e32 v32, 0, v32
	v_cvt_pk_bf16_f32 v41, v41, v42
	v_cvt_pk_bf16_f32 v42, v48, v45
	v_cvt_pk_bf16_f32 v43, v46, v43
	global_store_dwordx4 v[104:105], v[40:43], off offset:256
	v_pk_add_f32 v[38:39], v[38:39], v[70:71]
	v_max_f32_e32 v33, 0, v33
	v_mul_f32_e32 v40, v32, v32
	v_max_f32_e32 v32, 0, v37
	v_max_f32_e32 v34, 0, v34
	v_max_f32_e32 v36, 0, v36
	v_mul_f32_e32 v32, v32, v32
	v_mul_f32_e32 v37, v33, v33
	v_max_f32_e32 v33, 0, v38
	v_mul_f32_e32 v38, v34, v34
	v_max_f32_e32 v34, 0, v39
	v_max_f32_e32 v35, 0, v35
	v_pk_add_f32 v[24:25], v[24:25], v[64:65]
	v_mul_f32_e32 v36, v36, v36
	v_mul_f32_e32 v33, v33, v33
	v_mul_f32_e32 v34, v34, v34
	v_mul_f32_e32 v35, v35, v35
	v_cvt_pk_bf16_f32 v32, v36, v32
	v_pk_add_f32 v[28:29], v[28:29], v[68:69]
	v_pk_add_f32 v[26:27], v[26:27], v[66:67]
	v_max_f32_e32 v24, 0, v24
	v_cvt_pk_bf16_f32 v33, v33, v34
	v_cvt_pk_bf16_f32 v34, v40, v37
	v_cvt_pk_bf16_f32 v35, v38, v35
	global_store_dwordx4 v[96:97], v[32:35], off offset:256
	v_pk_add_f32 v[30:31], v[30:31], v[70:71]
	v_max_f32_e32 v25, 0, v25
	v_mul_f32_e32 v32, v24, v24
	v_max_f32_e32 v24, 0, v29
	v_max_f32_e32 v26, 0, v26
	v_max_f32_e32 v28, 0, v28
	v_mul_f32_e32 v24, v24, v24
	v_mul_f32_e32 v29, v25, v25
	v_max_f32_e32 v25, 0, v30
	v_mul_f32_e32 v30, v26, v26
	v_max_f32_e32 v26, 0, v31
	v_max_f32_e32 v27, 0, v27
	v_pk_add_f32 v[16:17], v[16:17], v[64:65]
	v_mul_f32_e32 v28, v28, v28
	v_mul_f32_e32 v25, v25, v25
	v_mul_f32_e32 v26, v26, v26
	v_mul_f32_e32 v27, v27, v27
	v_cvt_pk_bf16_f32 v24, v28, v24
	v_pk_add_f32 v[20:21], v[20:21], v[68:69]
	v_pk_add_f32 v[18:19], v[18:19], v[66:67]
	v_max_f32_e32 v16, 0, v16
	v_cvt_pk_bf16_f32 v25, v25, v26
	v_cvt_pk_bf16_f32 v26, v32, v29
	v_cvt_pk_bf16_f32 v27, v30, v27
	global_store_dwordx4 v[88:89], v[24:27], off offset:256
	v_pk_add_f32 v[22:23], v[22:23], v[70:71]
	v_max_f32_e32 v17, 0, v17
	v_mul_f32_e32 v24, v16, v16
	v_max_f32_e32 v16, 0, v21
	v_max_f32_e32 v18, 0, v18
	v_max_f32_e32 v20, 0, v20
	v_mul_f32_e32 v16, v16, v16
	v_mul_f32_e32 v21, v17, v17
	v_max_f32_e32 v17, 0, v22
	v_mul_f32_e32 v22, v18, v18
	v_max_f32_e32 v18, 0, v23
	v_max_f32_e32 v19, 0, v19
	v_pk_add_f32 v[8:9], v[8:9], v[64:65]
	v_mul_f32_e32 v20, v20, v20
	v_mul_f32_e32 v17, v17, v17
	v_mul_f32_e32 v18, v18, v18
	v_mul_f32_e32 v19, v19, v19
	v_cvt_pk_bf16_f32 v16, v20, v16
	v_pk_add_f32 v[12:13], v[12:13], v[68:69]
	v_pk_add_f32 v[10:11], v[10:11], v[66:67]
	v_max_f32_e32 v8, 0, v8
	v_cvt_pk_bf16_f32 v17, v17, v18
	v_cvt_pk_bf16_f32 v18, v24, v21
	v_cvt_pk_bf16_f32 v19, v22, v19
	global_store_dwordx4 v[80:81], v[16:19], off offset:256
	v_pk_add_f32 v[14:15], v[14:15], v[70:71]
	v_max_f32_e32 v9, 0, v9
	v_mul_f32_e32 v16, v8, v8
	v_max_f32_e32 v8, 0, v13
	v_max_f32_e32 v10, 0, v10
	v_max_f32_e32 v12, 0, v12
	v_mul_f32_e32 v8, v8, v8
	v_mul_f32_e32 v13, v9, v9
	v_max_f32_e32 v9, 0, v14
	v_mul_f32_e32 v14, v10, v10
	v_max_f32_e32 v10, 0, v15
	v_max_f32_e32 v11, 0, v11
	v_pk_add_f32 v[2:3], v[2:3], v[66:67]
	v_pk_add_f32 v[0:1], v[0:1], v[64:65]
	v_mul_f32_e32 v12, v12, v12
	v_mul_f32_e32 v9, v9, v9
	v_mul_f32_e32 v10, v10, v10
	v_mul_f32_e32 v11, v11, v11
	v_cvt_pk_bf16_f32 v8, v12, v8
	v_pk_add_f32 v[6:7], v[6:7], v[70:71]
	v_pk_add_f32 v[4:5], v[4:5], v[68:69]
	v_max_f32_e32 v0, 0, v0
	v_max_f32_e32 v1, 0, v1
	v_max_f32_e32 v2, 0, v2
	v_cvt_pk_bf16_f32 v9, v9, v10
	v_cvt_pk_bf16_f32 v10, v16, v13
	v_cvt_pk_bf16_f32 v11, v14, v11
	global_store_dwordx4 v[72:73], v[8:11], off offset:256
	v_max_f32_e32 v3, 0, v3
	v_max_f32_e32 v4, 0, v4
	v_mul_f32_e32 v8, v0, v0
	v_max_f32_e32 v0, 0, v5
	v_mul_f32_e32 v5, v1, v1
	v_max_f32_e32 v1, 0, v6
	v_mul_f32_e32 v6, v2, v2
	v_max_f32_e32 v2, 0, v7
	v_mul_f32_e32 v0, v0, v0
	v_mul_f32_e32 v1, v1, v1
	v_mul_f32_e32 v2, v2, v2
	v_mul_f32_e32 v3, v3, v3
	v_mul_f32_e32 v4, v4, v4
	v_cvt_pk_bf16_f32 v0, v4, v0
	v_cvt_pk_bf16_f32 v1, v1, v2
	v_cvt_pk_bf16_f32 v2, v8, v5
	v_cvt_pk_bf16_f32 v3, v6, v3
	s_nop 1
	global_store_dwordx4 v[74:75], v[0:3], off offset:256
	s_cbranch_vccz .LBB0_288
	s_waitcnt vmcnt(0)
	s_cmpk_gt_u32 s28, 0xff
	s_cbranch_scc1 .LBB0_299
	s_barrier

; __device__ __forceinline__ float bflo(unsigned w) { return __uint_as_float(w << 16); }
; __device__ __forceinline__ float bfhi(unsigned w) { return __uint_as_float(w & 0xffff0000u); }
; __device__ __forceinline__ void phase_ln1(const Params& p, int g, int gw, int NGW, int lane) {
;     ...
;     for (int row = gw; row < TG; row += NGW) {
;         const int b = g * BG + row / SEQ; const float* sh = mod + (size_t)b * MODW + 3 * DM; const float* sc = sh + DM;
;         float* xr = x1 + (size_t)row * DM;
;         f32x4 v[4]; float s = 0.f;
; #pragma unroll
;         for (int j = 0; j < 4; ++j) { const u32x2 bw = nb[j];
;             v[j] = nx[j] * ALPHA + (f32x4){bflo(bw.x), bfhi(bw.x), bflo(bw.y), bfhi(bw.y)}; s += (v[j].x + v[j].y) + (v[j].z + v[j].w); }
;         if (row + NGW < TG) { const size_t nr = (size_t)(row + NGW) * DM;
; #pragma unroll
;             for (int j = 0; j < 4; ++j) { nx[j] = *(const f32x4*)(xbase + nr + 4 * lane + 256 * j); nb[j] = *(const u32x2*)(brbase + nr + 4 * lane + 256 * j); } }
;         float mean = wave_sum(s, lane) * (1.f / DM); float s2 = 0.f;
; #pragma unroll
;         for (int j = 0; j < 4; ++j) { v[j] = v[j] - mean; s2 += (v[j].x * v[j].x + v[j].y * v[j].y) + (v[j].z * v[j].z + v[j].w * v[j].w); }
;         float rstd = __builtin_amdgcn_rsqf(wave_sum(s2, lane) * (1.f / DM) + 1e-6f);
;         s = 0.f;
; #pragma unroll
;         for (int j = 0; j < 4; ++j) { const int col = 4 * lane + 256 * j; const f32x4 ga = gaH[j], be = beH[j];
;             v[j] = v[j] * rstd * ga + be; *(f32x4*)(xr + col) = v[j]; s += (v[j].x + v[j].y) + (v[j].z + v[j].w); }
;         mean = wave_sum(s, lane) * (1.f / DM); s2 = 0.f;
; #pragma unroll
;         for (int j = 0; j < 4; ++j) { v[j] = v[j] - mean; s2 += (v[j].x * v[j].x + v[j].y * v[j].y) + (v[j].z * v[j].z + v[j].w * v[j].w); }
;         rstd = __builtin_amdgcn_rsqf(wave_sum(s2, lane) * (1.f / DM) + 1e-6f);
.LBB0_305:
	v_lshlrev_b32_e32 v98, 16, v86
	v_and_b32_e32 v99, 0xffff0000, v86
	v_lshlrev_b32_e32 v86, 16, v87
	v_and_b32_e32 v87, 0xffff0000, v87
	v_pk_fma_f32 v[62:63], v[62:63], s[70:71], v[86:87] op_sel_hi:[1,0,1]
	v_pk_fma_f32 v[60:61], v[60:61], s[70:71], v[98:99] op_sel_hi:[1,0,1]
	v_add_f32_e32 v87, v62, v63
	v_add_f32_e32 v86, v60, v61
	v_add_f32_e32 v86, v86, v87
	v_add_f32_e32 v98, 0, v86
	v_lshlrev_b32_e32 v86, 16, v84
	v_and_b32_e32 v87, 0xffff0000, v84
	v_lshlrev_b32_e32 v84, 16, v85
	v_and_b32_e32 v85, 0xffff0000, v85
	v_pk_fma_f32 v[58:59], v[58:59], s[70:71], v[84:85] op_sel_hi:[1,0,1]
	v_pk_fma_f32 v[56:57], v[56:57], s[70:71], v[86:87] op_sel_hi:[1,0,1]
	v_add_f32_e32 v85, v58, v59
	v_add_f32_e32 v84, v56, v57
	v_add_f32_e32 v84, v84, v85
	v_add_f32_e32 v86, v84, v98
	v_lshlrev_b32_e32 v84, 16, v82
	v_and_b32_e32 v85, 0xffff0000, v82
	v_lshlrev_b32_e32 v82, 16, v83
	v_and_b32_e32 v83, 0xffff0000, v83
	v_pk_fma_f32 v[82:83], v[54:55], s[70:71], v[82:83] op_sel_hi:[1,0,1]
	v_pk_fma_f32 v[84:85], v[52:53], s[70:71], v[84:85] op_sel_hi:[1,0,1]
	v_add_f32_e32 v53, v82, v83
	v_add_f32_e32 v52, v84, v85
	v_add_f32_e32 v52, v52, v53
	v_add_f32_e32 v98, v52, v86
	v_lshlrev_b32_e32 v52, 16, v80
	v_and_b32_e32 v53, 0xffff0000, v80
	v_lshlrev_b32_e32 v54, 16, v81
	v_and_b32_e32 v55, 0xffff0000, v81
	v_pk_fma_f32 v[80:81], v[50:51], s[70:71], v[54:55] op_sel_hi:[1,0,1]
	v_pk_fma_f32 v[86:87], v[48:49], s[70:71], v[52:53] op_sel_hi:[1,0,1]
	v_add_f32_e32 v49, v80, v81
	v_add_f32_e32 v48, v86, v87
	v_add_f32_e32 v48, v48, v49
	v_add_f32_e32 v48, v48, v98
	ds_bpermute_b32 v49, v88, v48
	s_ashr_i32 s1, s4, 31
	s_lshr_b32 s1, s1, 21
	s_add_i32 s1, s4, s1
	s_ashr_i32 s1, s1, 11
	s_waitcnt lgkmcnt(0)
	v_add_f32_e32 v48, v48, v49
	ds_bpermute_b32 v49, v89, v48
	s_add_i32 s1, s1, s76
	s_mul_hi_i32 s4, s1, 0x6000
	s_mulk_i32 s1, 0x6000
	s_add_u32 s1, s94, s1
	s_waitcnt lgkmcnt(0)
	v_add_f32_e32 v48, v48, v49
	ds_bpermute_b32 v49, v90, v48
	s_addc_u32 s7, s95, s4
	s_add_u32 s4, s1, 0x3000
	s_addc_u32 s5, s7, 0
	s_add_u32 s6, s1, 0x4000
	s_waitcnt lgkmcnt(0)
	v_add_f32_e32 v48, v48, v49
	ds_bpermute_b32 v49, v91, v48
	s_addc_u32 s7, s7, 0
	s_mov_b32 s1, 0xf900000
	s_waitcnt lgkmcnt(0)
	v_add_f32_e32 v48, v48, v49
	ds_bpermute_b32 v49, v92, v48
	s_waitcnt lgkmcnt(0)
	v_add_f32_e32 v48, v48, v49
	ds_bpermute_b32 v49, v93, v48
	s_waitcnt lgkmcnt(0)
	v_add_f32_e32 v98, v48, v49
	v_fmamk_f32 v61, v98, 0xba800000, v61
	v_fmac_f32_e32 v60, 0xba800000, v98
	v_fmamk_f32 v63, v98, 0xba800000, v63
	v_fmac_f32_e32 v62, 0xba800000, v98
	v_pk_mul_f32 v[48:49], v[62:63], v[62:63]
	v_pk_mul_f32 v[50:51], v[60:61], v[60:61]
	v_fmamk_f32 v57, v98, 0xba800000, v57
	v_pk_mov_b32 v[52:53], v[50:51], v[48:49] op_sel:[1,0]
	v_mov_b32_e32 v51, v49
	v_pk_add_f32 v[48:49], v[52:53], v[50:51]
	v_fmac_f32_e32 v56, 0xba800000, v98
	v_fmamk_f32 v59, v98, 0xba800000, v59
	v_fmac_f32_e32 v58, 0xba800000, v98
	v_pk_add_f32 v[48:49], v[48:49], v[48:49] op_sel_hi:[0,1]
	v_pk_mul_f32 v[50:51], v[58:59], v[58:59]
	v_pk_mul_f32 v[52:53], v[56:57], v[56:57]
	v_fmac_f32_e32 v84, 0xba800000, v98
	v_pk_mov_b32 v[54:55], v[52:53], v[50:51] op_sel:[1,0]
	v_mov_b32_e32 v53, v51
	v_fmamk_f32 v85, v98, 0xba800000, v85
	v_fmac_f32_e32 v82, 0xba800000, v98
	v_mul_f32_e32 v48, v84, v84
	v_pk_add_f32 v[50:51], v[54:55], v[52:53]
	v_fmamk_f32 v83, v98, 0xba800000, v83
	v_pk_fma_f32 v[52:53], v[84:85], v[84:85], v[48:49] op_sel_hi:[1,1,0]
	v_mul_f32_e32 v48, v82, v82
	v_pk_add_f32 v[50:51], v[50:51], v[50:51] op_sel_hi:[0,1]
	v_pk_fma_f32 v[54:55], v[82:83], v[82:83], v[48:49] op_sel_hi:[1,1,0]
	v_fmamk_f32 v81, v98, 0xba800000, v81
	v_fmac_f32_e32 v80, 0xba800000, v98
	v_fmamk_f32 v87, v98, 0xba800000, v87
	v_fmac_f32_e32 v86, 0xba800000, v98
	v_mul_f32_e32 v52, v86, v86
	v_mul_f32_e32 v54, v87, v87
	v_mul_f32_e32 v48, v80, v80
	v_mul_f32_e32 v50, v81, v81
	v_pk_add_f32 v[52:53], v[52:53], v[54:55]
	v_pk_add_f32 v[48:49], v[48:49], v[50:51]
	s_nop 0
	v_pk_add_f32 v[48:49], v[52:53], v[48:49]
	v_lshl_add_u64 v[52:53], s[94:95], 0, v[68:69]
	v_add_f32_e32 v48, v48, v49
	ds_bpermute_b32 v49, v88, v48
	v_add_co_u32_e32 v100, vcc, s89, v52
	s_waitcnt lgkmcnt(0)
	v_add_f32_e32 v48, v48, v49
	ds_bpermute_b32 v49, v89, v48
	v_addc_co_u32_e32 v101, vcc, 0, v53, vcc
	s_waitcnt lgkmcnt(0)
	v_add_f32_e32 v48, v48, v49
	ds_bpermute_b32 v49, v90, v48
	s_waitcnt lgkmcnt(0)
	v_add_f32_e32 v48, v48, v49
	ds_bpermute_b32 v49, v91, v48
	s_waitcnt lgkmcnt(0)
	v_add_f32_e32 v48, v48, v49
	ds_bpermute_b32 v49, v92, v48
	s_waitcnt lgkmcnt(0)
	v_add_f32_e32 v48, v48, v49
	ds_bpermute_b32 v49, v93, v48
	s_waitcnt lgkmcnt(0)
	v_add_f32_e32 v48, v48, v49
	v_fmamk_f32 v48, v48, 0x3a800000, v238
	v_rsq_f32_e32 v98, v48
	s_nop 0
	v_pk_mul_f32 v[50:51], v[62:63], v[98:99] op_sel_hi:[1,0]
	v_pk_mul_f32 v[48:49], v[60:61], v[98:99] op_sel_hi:[1,0]
	v_pk_fma_f32 v[50:51], v[2:3], v[50:51], v[6:7]
	v_pk_fma_f32 v[48:49], v[0:1], v[48:49], v[4:5]
	v_mov_b32_e32 v55, v51
	v_pk_mov_b32 v[52:53], v[48:49], v[50:51] op_sel:[1,0]
	v_mov_b32_e32 v54, v48
	v_pk_add_f32 v[52:53], v[52:53], v[54:55]
	global_store_dwordx4 v[100:101], v[48:51], off
	v_add_f32_e32 v52, v52, v53
	v_add_f32_e32 v99, 0, v52
	v_pk_mul_f32 v[54:55], v[58:59], v[98:99] op_sel_hi:[1,0]
	v_pk_mul_f32 v[52:53], v[56:57], v[98:99] op_sel_hi:[1,0]
	v_pk_fma_f32 v[54:55], v[10:11], v[54:55], v[14:15]
	v_pk_fma_f32 v[52:53], v[8:9], v[52:53], v[12:13]
	v_mov_b32_e32 v59, v55
	v_pk_mov_b32 v[56:57], v[52:53], v[54:55] op_sel:[1,0]
	v_mov_b32_e32 v58, v52
	v_pk_add_f32 v[56:57], v[56:57], v[58:59]
	v_pk_mul_f32 v[58:59], v[82:83], v[98:99] op_sel_hi:[1,0]
	v_pk_add_f32 v[102:103], v[56:57], v[56:57] op_sel_hi:[0,1]
	v_pk_mul_f32 v[56:57], v[84:85], v[98:99] op_sel_hi:[1,0]
	v_pk_mul_f32 v[60:61], v[86:87], v[98:99] op_sel_hi:[1,0]
	v_pk_mul_f32 v[62:63], v[80:81], v[98:99] op_sel_hi:[1,0]
	v_pk_fma_f32 v[56:57], v[16:17], v[56:57], v[20:21]
	v_pk_fma_f32 v[58:59], v[18:19], v[58:59], v[22:23]
	v_pk_fma_f32 v[62:63], v[26:27], v[62:63], v[30:31]
	v_pk_fma_f32 v[60:61], v[24:25], v[60:61], v[28:29]
	v_add_f32_e32 v83, v56, v57
	v_add_f32_e32 v85, v58, v59
	v_mov_b32_e32 v82, v60
	v_mov_b32_e32 v84, v61
	v_mov_b32_e32 v102, v62
	v_mov_b32_e32 v98, v63
	v_pk_add_f32 v[80:81], v[82:83], v[84:85]
	v_pk_add_f32 v[82:83], v[102:103], v[98:99]
	global_store_dwordx4 v[100:101], v[52:55], off offset:1024
	v_pk_add_f32 v[80:81], v[80:81], v[82:83]
	global_store_dwordx4 v[100:101], v[56:59], off offset:2048
	v_add_f32_e32 v80, v80, v81
	ds_bpermute_b32 v81, v88, v80
	global_store_dwordx4 v[100:101], v[60:63], off offset:3072
	s_waitcnt lgkmcnt(0)
; __device__ __forceinline__ unsigned cvt_pk_bf16(float lo, float hi) { unsigned r; asm volatile("s_nop 0\n\tv_cvt_pk_bf16_f32 %0, %1, %2\n\ts_nop 1" : "=v"(r) : "v"(lo), "v"(hi)); return r; }
; __device__ __forceinline__ void phase_ln1(const Params& p, int g, int gw, int NGW, int lane) {
;     ...
;         mean = wave_sum(s, lane) * (1.f / DM); s2 = 0.f;
; #pragma unroll
;         for (int j = 0; j < 4; ++j) { v[j] = v[j] - mean; s2 += (v[j].x * v[j].x + v[j].y * v[j].y) + (v[j].z * v[j].z + v[j].w * v[j].w); }
;         rstd = __builtin_amdgcn_rsqf(wave_sum(s2, lane) * (1.f / DM) + 1e-6f);
; #pragma unroll
;         for (int j = 0; j < 4; ++j) { const int col = 4 * lane + 256 * j; const f32x4 a = *(const f32x4*)(sc + col), bb = *(const f32x4*)(sh + col);
;             const f32x4 o = v[j] * rstd * (a + 1.f) + bb; u32x2 w; w.x = cvt_pk_bf16(o.x, o.y); w.y = cvt_pk_bf16(o.z, o.w);
;             *(u32x2*)(h1 + (size_t)row * DM + col) = w; }
	v_add_f32_e32 v80, v80, v81
	ds_bpermute_b32 v81, v89, v80
	s_waitcnt lgkmcnt(0)
	v_add_f32_e32 v80, v80, v81
	ds_bpermute_b32 v81, v90, v80
	s_waitcnt lgkmcnt(0)
	v_add_f32_e32 v80, v80, v81
	ds_bpermute_b32 v81, v91, v80
	s_waitcnt lgkmcnt(0)
	v_add_f32_e32 v80, v80, v81
	ds_bpermute_b32 v81, v92, v80
	s_waitcnt lgkmcnt(0)
	v_add_f32_e32 v80, v80, v81
	ds_bpermute_b32 v81, v93, v80
	s_waitcnt lgkmcnt(0)
	v_add_f32_e32 v98, v80, v81
	v_fmamk_f32 v49, v98, 0xba800000, v49
	v_fmac_f32_e32 v48, 0xba800000, v98
	v_fmamk_f32 v51, v98, 0xba800000, v51
	v_fmac_f32_e32 v50, 0xba800000, v98
	v_pk_mul_f32 v[80:81], v[50:51], v[50:51]
	v_pk_mul_f32 v[82:83], v[48:49], v[48:49]
	v_fmamk_f32 v53, v98, 0xba800000, v53
	v_pk_mov_b32 v[84:85], v[82:83], v[80:81] op_sel:[1,0]
	v_mov_b32_e32 v83, v81
	v_pk_add_f32 v[80:81], v[84:85], v[82:83]
	v_fmac_f32_e32 v52, 0xba800000, v98
	v_fmamk_f32 v55, v98, 0xba800000, v55
	v_fmac_f32_e32 v54, 0xba800000, v98
	v_pk_add_f32 v[80:81], v[80:81], v[80:81] op_sel_hi:[0,1]
	v_pk_mul_f32 v[82:83], v[54:55], v[54:55]
	v_pk_mul_f32 v[84:85], v[52:53], v[52:53]
	v_fmac_f32_e32 v56, 0xba800000, v98
	v_pk_mov_b32 v[86:87], v[84:85], v[82:83] op_sel:[1,0]
	v_mov_b32_e32 v85, v83
	v_fmamk_f32 v57, v98, 0xba800000, v57
	v_fmac_f32_e32 v58, 0xba800000, v98
	v_mul_f32_e32 v80, v56, v56
	v_pk_add_f32 v[82:83], v[86:87], v[84:85]
	v_fmamk_f32 v59, v98, 0xba800000, v59
	v_pk_fma_f32 v[84:85], v[56:57], v[56:57], v[80:81] op_sel_hi:[1,1,0]
	v_mul_f32_e32 v80, v58, v58
	v_pk_add_f32 v[82:83], v[82:83], v[82:83] op_sel_hi:[0,1]
	v_pk_fma_f32 v[86:87], v[58:59], v[58:59], v[80:81] op_sel_hi:[1,1,0]
	v_fmamk_f32 v63, v98, 0xba800000, v63
	v_fmac_f32_e32 v62, 0xba800000, v98
	v_fmamk_f32 v61, v98, 0xba800000, v61
	v_fmac_f32_e32 v60, 0xba800000, v98
	v_mul_f32_e32 v84, v60, v60
	v_mul_f32_e32 v86, v61, v61
	v_mul_f32_e32 v80, v62, v62
	v_mul_f32_e32 v82, v63, v63
	v_pk_add_f32 v[84:85], v[84:85], v[86:87]
	v_pk_add_f32 v[80:81], v[80:81], v[82:83]
	s_nop 0
	v_pk_add_f32 v[80:81], v[84:85], v[80:81]
	global_load_dwordx4 v[82:85], v94, s[6:7]
	global_load_dwordx4 v[98:101], v94, s[4:5]
	v_add_f32_e32 v80, v80, v81
	ds_bpermute_b32 v81, v88, v80
	s_waitcnt lgkmcnt(0)
	v_add_f32_e32 v80, v80, v81
	ds_bpermute_b32 v81, v89, v80
	s_waitcnt lgkmcnt(0)
	v_add_f32_e32 v80, v80, v81
	ds_bpermute_b32 v81, v90, v80
	s_waitcnt lgkmcnt(0)
	v_add_f32_e32 v80, v80, v81
	ds_bpermute_b32 v81, v91, v80
	s_waitcnt lgkmcnt(0)
	v_add_f32_e32 v80, v80, v81
	ds_bpermute_b32 v81, v92, v80
	s_waitcnt lgkmcnt(0)
	v_add_f32_e32 v80, v80, v81
	ds_bpermute_b32 v81, v93, v80
	s_waitcnt lgkmcnt(0)
	v_add_f32_e32 v80, v80, v81
	v_fmamk_f32 v80, v80, 0x3a800000, v238
	v_rsq_f32_e32 v80, v80
	s_waitcnt vmcnt(1)
	v_pk_add_f32 v[84:85], v[84:85], 1.0 op_sel_hi:[1,0]
	v_pk_mul_f32 v[48:49], v[48:49], v[80:81] op_sel_hi:[1,0]
	v_pk_mul_f32 v[50:51], v[50:51], v[80:81] op_sel_hi:[1,0]
	v_pk_add_f32 v[82:83], v[82:83], 1.0 op_sel_hi:[1,0]
	s_waitcnt vmcnt(0)
	v_pk_fma_f32 v[50:51], v[84:85], v[50:51], v[100:101]
	v_pk_fma_f32 v[48:49], v[82:83], v[48:49], v[98:99]
	v_pk_mul_f32 v[52:53], v[52:53], v[80:81] op_sel_hi:[1,0]
	v_cvt_pk_bf16_f32 v48, v48, v49
	v_cvt_pk_bf16_f32 v49, v50, v51
	v_lshl_add_u64 v[50:51], s[94:95], 0, v[70:71]
	v_add_co_u32_e32 v86, vcc, s1, v50
	v_pk_mul_f32 v[54:55], v[54:55], v[80:81] op_sel_hi:[1,0]
	s_nop 0
	v_addc_co_u32_e32 v87, vcc, 0, v51, vcc
	global_store_dwordx2 v[86:87], v[48:49], off
	global_load_dwordx4 v[48:51], v95, s[6:7]
	s_nop 0
	global_load_dwordx4 v[82:85], v95, s[4:5]
	v_pk_mul_f32 v[56:57], v[56:57], v[80:81] op_sel_hi:[1,0]
	v_pk_mul_f32 v[58:59], v[58:59], v[80:81] op_sel_hi:[1,0]
	s_and_b64 vcc, exec, s[2:3]
	s_waitcnt vmcnt(1)
	v_pk_add_f32 v[48:49], v[48:49], 1.0 op_sel_hi:[1,0]
	v_pk_add_f32 v[50:51], v[50:51], 1.0 op_sel_hi:[1,0]
	s_waitcnt vmcnt(0)
	v_pk_fma_f32 v[48:49], v[48:49], v[52:53], v[82:83]
	v_pk_fma_f32 v[50:51], v[50:51], v[54:55], v[84:85]
	v_cvt_pk_bf16_f32 v48, v48, v49
	v_mov_b64_e32 v[82:83], v[74:75]
	v_cvt_pk_bf16_f32 v49, v50, v51
	global_store_dwordx2 v[86:87], v[48:49], off offset:512
	global_load_dwordx4 v[48:51], v96, s[6:7]
	s_nop 0
	global_load_dwordx4 v[52:55], v96, s[4:5]
	v_mov_b64_e32 v[84:85], v[76:77]
	s_waitcnt vmcnt(1)
	v_pk_add_f32 v[48:49], v[48:49], 1.0 op_sel_hi:[1,0]
	v_pk_add_f32 v[50:51], v[50:51], 1.0 op_sel_hi:[1,0]
	s_waitcnt vmcnt(0)
	v_pk_fma_f32 v[48:49], v[48:49], v[56:57], v[52:53]
	v_pk_fma_f32 v[50:51], v[50:51], v[58:59], v[54:55]
	v_cvt_pk_bf16_f32 v48, v48, v49
	v_pk_mul_f32 v[56:57], v[60:61], v[80:81] op_sel_hi:[1,0]
	v_cvt_pk_bf16_f32 v49, v50, v51
	global_store_dwordx2 v[86:87], v[48:49], off offset:1024
	global_load_dwordx4 v[48:51], v97, s[6:7]
	s_nop 0
	global_load_dwordx4 v[52:55], v97, s[4:5]
	v_readlane_b32 s4, v255, 2
	v_readlane_b32 s5, v255, 3
	v_pk_mul_f32 v[58:59], v[62:63], v[80:81] op_sel_hi:[1,0]
	v_mov_b64_e32 v[80:81], v[72:73]
	v_lshl_add_u64 v[70:71], v[70:71], 0, s[4:5]
	v_readlane_b32 s4, v255, 0
	v_readlane_b32 s5, v255, 1
	v_mov_b32_e32 v60, v32
	v_mov_b32_e32 v61, v33
	v_lshl_add_u64 v[68:69], v[68:69], 0, s[4:5]
	s_mov_b32 s4, s0
	v_mov_b32_e32 v62, v34
	v_mov_b32_e32 v63, v35
	s_waitcnt vmcnt(1)
	v_pk_add_f32 v[48:49], v[48:49], 1.0 op_sel_hi:[1,0]
	v_pk_add_f32 v[50:51], v[50:51], 1.0 op_sel_hi:[1,0]
	s_waitcnt vmcnt(0)
	v_pk_fma_f32 v[48:49], v[48:49], v[56:57], v[52:53]
	v_pk_fma_f32 v[50:51], v[50:51], v[58:59], v[54:55]
	v_cvt_pk_bf16_f32 v48, v48, v49
	v_mov_b32_e32 v56, v36
	v_cvt_pk_bf16_f32 v49, v50, v51
	global_store_dwordx2 v[86:87], v[48:49], off offset:1536
	v_mov_b64_e32 v[86:87], v[78:79]
	v_mov_b32_e32 v57, v37
	v_mov_b32_e32 v58, v38
	v_mov_b32_e32 v59, v39
	v_mov_b32_e32 v52, v40
	v_mov_b32_e32 v53, v41
	v_mov_b32_e32 v54, v42
	v_mov_b32_e32 v55, v43
	v_mov_b32_e32 v48, v44
	v_mov_b32_e32 v49, v45
	v_mov_b32_e32 v50, v46
	v_mov_b32_e32 v51, v47
	s_cbranch_vccnz .LBB0_308

; #define PG8_STAGE(bufoff, gbase, voff) do { _Pragma("unroll") for (int _i = 0; _i < 2; ++_i) \
;         __builtin_amdgcn_global_load_lds((const unsigned*)((const char*)(gbase) + (voff)[_i]), (PG8_LAS unsigned*)(lds + (bufoff) + ldsw + _i * 8192), 16, 0, 0); } while (0)
; #define PG8_LDA(dst, b, h) do { _Pragma("unroll") for (int m = 0; m < 4; ++m) _Pragma("unroll") for (int k = 0; k < 2; ++k) dst[m][k] = *(const PG8_LAS bf16x8*)(lds + PG8_SA(b, h) + aoff + m * 2048 + k * 1024); } while (0)
; #define PG8_LDB(dst, b, h) do { _Pragma("unroll") for (int n = 0; n < 2; ++n) _Pragma("unroll") for (int k = 0; k < 2; ++k) dst[n][k] = *(const PG8_LAS bf16x8*)(lds + PG8_SB(b, h) + boff + n * 2048 + k * 1024); } while (0)
; #define PG8_MMA(ai, bj, At, Bt) do { __builtin_amdgcn_s_setprio(1); _Pragma("unroll") for (int m = 0; m < 4; ++m) _Pragma("unroll") for (int n = 0; n < 2; ++n) _Pragma("unroll") for (int k = 0; k < 2; ++k) \
;         acc[ai][bj][m][n] = __builtin_amdgcn_mfma_f32_16x16x32_bf16(Bt[n][k], At[m][k], acc[ai][bj][m][n], 0, 0, 0); __builtin_amdgcn_s_setprio(0); } while (0)
; #define PG8_WAIT_L(n) asm volatile("s_waitcnt lgkmcnt(" #n ")" ::: "memory")
; #define PG8_BAR __builtin_amdgcn_s_barrier()
; #define PG8_SCHED __builtin_amdgcn_sched_barrier(0)
; template <class Epi, class Sched>
; __device__ __forceinline__ void gemm_phase(PG8_LAS unsigned char* lds, const Gemm g, const Sched& S, const Epi& E, int tid_in) {
;     ...
;             PG8_LDB(B0, 0, 0); PG8_SCHED; PG8_LDA(At, 0, 0); PG8_STAGE(PG8_SA(1, 1), a1 + hstep, voffA);
;             PG8_WAIT_L(8); PG8_BAR; PG8_WAIT_L(0); PG8_MMA(0, 0, At, B0); PG8_BAR; PG8_SCHED;
;             PG8_LDB(B1, 0, 1); PG8_STAGE(PG8_SB(0, 0), b2, voffB);
;             PG8_BAR; PG8_WAIT_L(0); PG8_MMA(0, 1, At, B1); PG8_BAR;
;             PG8_LDA(At, 0, 1); PG8_STAGE(PG8_SA(0, 0), a2, voffA);
;             PG8_BAR; PG8_WAIT_L(0); PG8_MMA(1, 0, At, B0); PG8_BAR; PG8_SCHED;
.LBB0_325:
	s_add_u32 s16, s14, 0x100
	s_addc_u32 s17, s15, 0
	s_add_i32 s46, 0, 0x10000
	v_add_u32_e32 v138, s46, v141
	ds_read_b128 v[128:131], v138
	ds_read_b128 v[144:147], v138 offset:1024
	ds_read_b128 v[148:151], v138 offset:2048
	ds_read_b128 v[152:155], v138 offset:3072
	s_cmp_eq_u32 s45, 12
	s_cselect_b32 s21, s7, s17
	s_cselect_b32 s20, s41, s16
	s_cselect_b32 s19, s5, s44
	s_cselect_b32 s18, s42, s43
	v_lshl_add_u64 v[138:139], s[14:15], 0, v[134:135]
	s_add_i32 m0, s13, 0xc000
	ds_read_b128 v[156:159], v143
	ds_read_b128 v[160:163], v143 offset:1024
	ds_read_b128 v[164:167], v143 offset:2048
	ds_read_b128 v[168:171], v143 offset:3072
	ds_read_b128 v[172:175], v143 offset:4096
	ds_read_b128 v[176:179], v143 offset:5120
	ds_read_b128 v[180:183], v143 offset:6144
	ds_read_b128 v[184:187], v143 offset:7168
	global_load_lds_dwordx4 v[138:139], off
	v_lshl_add_u64 v[138:139], s[14:15], 0, v[136:137]
	s_add_i32 m0, s13, 0xe000
	s_nop 0
	global_load_lds_dwordx4 v[138:139], off
	s_waitcnt lgkmcnt(8)
	s_barrier
	s_waitcnt lgkmcnt(0)
	s_setprio 1
	s_waitcnt lgkmcnt(0)
	v_mfma_f32_16x16x32_bf16 v[124:127], v[128:131], v[156:159], v[124:127]
	v_mfma_f32_16x16x32_bf16 v[92:95], v[148:151], v[156:159], v[92:95]
	v_mfma_f32_16x16x32_bf16 v[120:123], v[128:131], v[164:167], v[120:123]
	v_mfma_f32_16x16x32_bf16 v[88:91], v[148:151], v[164:167], v[88:91]
	v_mfma_f32_16x16x32_bf16 v[116:119], v[128:131], v[172:175], v[116:119]
	v_mfma_f32_16x16x32_bf16 v[84:87], v[148:151], v[172:175], v[84:87]
	v_mfma_f32_16x16x32_bf16 v[112:115], v[128:131], v[180:183], v[112:115]
	v_mfma_f32_16x16x32_bf16 v[80:83], v[148:151], v[180:183], v[80:83]
	v_mfma_f32_16x16x32_bf16 v[124:127], v[144:147], v[160:163], v[124:127]
	v_mfma_f32_16x16x32_bf16 v[92:95], v[152:155], v[160:163], v[92:95]
	v_mfma_f32_16x16x32_bf16 v[120:123], v[144:147], v[168:171], v[120:123]
	v_mfma_f32_16x16x32_bf16 v[88:91], v[152:155], v[168:171], v[88:91]
	v_mfma_f32_16x16x32_bf16 v[116:119], v[144:147], v[176:179], v[116:119]
	v_mfma_f32_16x16x32_bf16 v[84:87], v[152:155], v[176:179], v[84:87]
	v_mfma_f32_16x16x32_bf16 v[112:115], v[144:147], v[184:187], v[112:115]
	v_mfma_f32_16x16x32_bf16 v[80:83], v[152:155], v[184:187], v[80:83]
	s_setprio 0
	s_barrier
	s_add_i32 s48, 0, 0x14000
	v_add_u32_e32 v138, s48, v141
	s_add_i32 s14, s46, s28
	ds_read_b128 v[188:191], v138
	ds_read_b128 v[194:197], v138 offset:1024
	ds_read_b128 v[200:203], v138 offset:2048
	ds_read_b128 v[204:207], v138 offset:3072
	v_lshl_add_u64 v[138:139], s[18:19], 0, v[192:193]
	s_mov_b32 m0, s14
	v_lshl_add_u64 v[208:209], s[18:19], 0, v[132:133]
	global_load_lds_dwordx4 v[138:139], off
	s_add_i32 m0, s14, 0x2000
	s_nop 0
	global_load_lds_dwordx4 v[208:209], off
	s_barrier
	s_waitcnt lgkmcnt(0)
	s_setprio 1
	s_waitcnt lgkmcnt(0)
	v_mfma_f32_16x16x32_bf16 v[60:63], v[188:191], v[156:159], v[60:63]
	v_mfma_f32_16x16x32_bf16 v[28:31], v[200:203], v[156:159], v[28:31]
	v_mfma_f32_16x16x32_bf16 v[56:59], v[188:191], v[164:167], v[56:59]
	v_mfma_f32_16x16x32_bf16 v[24:27], v[200:203], v[164:167], v[24:27]
	v_mfma_f32_16x16x32_bf16 v[52:55], v[188:191], v[172:175], v[52:55]
	v_mfma_f32_16x16x32_bf16 v[20:23], v[200:203], v[172:175], v[20:23]
	v_mfma_f32_16x16x32_bf16 v[48:51], v[188:191], v[180:183], v[48:51]
	v_mfma_f32_16x16x32_bf16 v[16:19], v[200:203], v[180:183], v[16:19]
	v_mfma_f32_16x16x32_bf16 v[60:63], v[194:197], v[160:163], v[60:63]
	v_mfma_f32_16x16x32_bf16 v[28:31], v[204:207], v[160:163], v[28:31]
	v_mfma_f32_16x16x32_bf16 v[56:59], v[194:197], v[168:171], v[56:59]
	v_mfma_f32_16x16x32_bf16 v[24:27], v[204:207], v[168:171], v[24:27]
	v_mfma_f32_16x16x32_bf16 v[52:55], v[194:197], v[176:179], v[52:55]
	v_mfma_f32_16x16x32_bf16 v[20:23], v[204:207], v[176:179], v[20:23]
	v_mfma_f32_16x16x32_bf16 v[48:51], v[194:197], v[184:187], v[48:51]
	v_mfma_f32_16x16x32_bf16 v[16:19], v[204:207], v[184:187], v[16:19]
	s_setprio 0
	s_mov_b32 m0, s13
	v_lshl_add_u64 v[210:211], s[20:21], 0, v[192:193]
	s_barrier
	ds_read_b128 v[156:159], v143 offset:16384
	ds_read_b128 v[160:163], v143 offset:17408
	ds_read_b128 v[164:167], v143 offset:18432
	ds_read_b128 v[168:171], v143 offset:19456
	ds_read_b128 v[172:175], v143 offset:20480
	ds_read_b128 v[176:179], v143 offset:21504
	ds_read_b128 v[180:183], v143 offset:22528
	ds_read_b128 v[184:187], v143 offset:23552
	global_load_lds_dwordx4 v[210:211], off
	v_lshl_add_u64 v[212:213], s[20:21], 0, v[132:133]
	s_mov_b32 m0, s29
	s_nop 0
	global_load_lds_dwordx4 v[212:213], off
	s_barrier
	s_waitcnt lgkmcnt(0)
	s_setprio 1
	s_waitcnt lgkmcnt(0)
	v_mfma_f32_16x16x32_bf16 v[108:111], v[128:131], v[156:159], v[108:111]
	v_mfma_f32_16x16x32_bf16 v[76:79], v[148:151], v[156:159], v[76:79]
	v_mfma_f32_16x16x32_bf16 v[104:107], v[128:131], v[164:167], v[104:107]
	v_mfma_f32_16x16x32_bf16 v[72:75], v[148:151], v[164:167], v[72:75]
	v_mfma_f32_16x16x32_bf16 v[100:103], v[128:131], v[172:175], v[100:103]
	v_mfma_f32_16x16x32_bf16 v[68:71], v[148:151], v[172:175], v[68:71]
	v_mfma_f32_16x16x32_bf16 v[96:99], v[128:131], v[180:183], v[96:99]
	v_mfma_f32_16x16x32_bf16 v[64:67], v[148:151], v[180:183], v[64:67]
	v_mfma_f32_16x16x32_bf16 v[108:111], v[144:147], v[160:163], v[108:111]
	v_mfma_f32_16x16x32_bf16 v[76:79], v[152:155], v[160:163], v[76:79]
	v_mfma_f32_16x16x32_bf16 v[104:107], v[144:147], v[168:171], v[104:107]
	v_mfma_f32_16x16x32_bf16 v[72:75], v[152:155], v[168:171], v[72:75]
	v_mfma_f32_16x16x32_bf16 v[100:103], v[144:147], v[176:179], v[100:103]
	v_mfma_f32_16x16x32_bf16 v[68:71], v[152:155], v[176:179], v[68:71]
	v_mfma_f32_16x16x32_bf16 v[96:99], v[144:147], v[184:187], v[96:99]
	v_mfma_f32_16x16x32_bf16 v[64:67], v[152:155], v[184:187], v[64:67]
	s_setprio 0
	s_barrier
; #define PG8_STAGE(bufoff, gbase, voff) do { _Pragma("unroll") for (int _i = 0; _i < 2; ++_i) \
;         __builtin_amdgcn_global_load_lds((const unsigned*)((const char*)(gbase) + (voff)[_i]), (PG8_LAS unsigned*)(lds + (bufoff) + ldsw + _i * 8192), 16, 0, 0); } while (0)
; #define PG8_LDA(dst, b, h) do { _Pragma("unroll") for (int m = 0; m < 4; ++m) _Pragma("unroll") for (int k = 0; k < 2; ++k) dst[m][k] = *(const PG8_LAS bf16x8*)(lds + PG8_SA(b, h) + aoff + m * 2048 + k * 1024); } while (0)
; #define PG8_LDB(dst, b, h) do { _Pragma("unroll") for (int n = 0; n < 2; ++n) _Pragma("unroll") for (int k = 0; k < 2; ++k) dst[n][k] = *(const PG8_LAS bf16x8*)(lds + PG8_SB(b, h) + boff + n * 2048 + k * 1024); } while (0)
; #define PG8_MMA(ai, bj, At, Bt) do { __builtin_amdgcn_s_setprio(1); _Pragma("unroll") for (int m = 0; m < 4; ++m) _Pragma("unroll") for (int n = 0; n < 2; ++n) _Pragma("unroll") for (int k = 0; k < 2; ++k) \
;         acc[ai][bj][m][n] = __builtin_amdgcn_mfma_f32_16x16x32_bf16(Bt[n][k], At[m][k], acc[ai][bj][m][n], 0, 0, 0); __builtin_amdgcn_s_setprio(0); } while (0)
; #define PG8_WAIT_V(n) asm volatile("s_waitcnt vmcnt(" #n ")" ::: "memory")
; #define PG8_WAIT_L(n) asm volatile("s_waitcnt lgkmcnt(" #n ")" ::: "memory")
; #define PG8_BAR __builtin_amdgcn_s_barrier()
; #define PG8_SCHED __builtin_amdgcn_sched_barrier(0)
; template <class Epi, class Sched>
; __device__ __forceinline__ void gemm_phase(PG8_LAS unsigned char* lds, const Gemm g, const Sched& S, const Epi& E, int tid_in) {
;     ...
;             PG8_STAGE(PG8_SB(0, 1), b2 + hstep, voffB);
;             PG8_WAIT_V(6); PG8_BAR; PG8_MMA(1, 1, At, B1); PG8_BAR;
;             PG8_LDB(B0, 1, 0); PG8_SCHED; PG8_LDA(At, 1, 0); PG8_STAGE(PG8_SA(0, 1), a2 + hstep, voffA);
;             PG8_WAIT_L(8); PG8_BAR; PG8_WAIT_L(0); PG8_MMA(0, 0, At, B0); PG8_BAR; PG8_SCHED;
;             PG8_LDB(B1, 1, 1); PG8_STAGE(PG8_SB(1, 0), b3, voffB);
;             PG8_BAR; PG8_WAIT_L(0); PG8_MMA(0, 1, At, B1); PG8_BAR;
;             PG8_LDA(At, 1, 1); PG8_STAGE(PG8_SA(1, 0), a3, voffA);
;             PG8_BAR; PG8_WAIT_L(0); PG8_MMA(1, 0, At, B0); PG8_BAR; PG8_SCHED;
	s_add_u32 s14, s18, 0x40000
	s_addc_u32 s15, s19, 0
	s_add_i32 s46, s48, s28
	v_lshl_add_u64 v[128:129], s[14:15], 0, v[192:193]
	s_mov_b32 m0, s46
	s_nop 0
	global_load_lds_dwordx4 v[128:129], off
	v_lshl_add_u64 v[128:129], s[14:15], 0, v[132:133]
	s_add_i32 m0, s46, 0x2000
	s_nop 0
	global_load_lds_dwordx4 v[128:129], off
	s_waitcnt vmcnt(6)
	s_barrier
	s_setprio 1
	v_mfma_f32_16x16x32_bf16 v[44:47], v[188:191], v[156:159], v[44:47]
	v_mfma_f32_16x16x32_bf16 v[12:15], v[200:203], v[156:159], v[12:15]
	v_mfma_f32_16x16x32_bf16 v[40:43], v[188:191], v[164:167], v[40:43]
	v_mfma_f32_16x16x32_bf16 v[8:11], v[200:203], v[164:167], v[8:11]
	v_mfma_f32_16x16x32_bf16 v[36:39], v[188:191], v[172:175], v[36:39]
	v_mfma_f32_16x16x32_bf16 v[4:7], v[200:203], v[172:175], v[4:7]
	v_mfma_f32_16x16x32_bf16 v[32:35], v[188:191], v[180:183], v[32:35]
	v_mfma_f32_16x16x32_bf16 v[0:3], v[200:203], v[180:183], v[0:3]
	v_mfma_f32_16x16x32_bf16 v[44:47], v[194:197], v[160:163], v[44:47]
	v_mfma_f32_16x16x32_bf16 v[12:15], v[204:207], v[160:163], v[12:15]
	v_mfma_f32_16x16x32_bf16 v[40:43], v[194:197], v[168:171], v[40:43]
	v_mfma_f32_16x16x32_bf16 v[8:11], v[204:207], v[168:171], v[8:11]
	v_mfma_f32_16x16x32_bf16 v[36:39], v[194:197], v[176:179], v[36:39]
	v_mfma_f32_16x16x32_bf16 v[4:7], v[204:207], v[176:179], v[4:7]
	v_mfma_f32_16x16x32_bf16 v[32:35], v[194:197], v[184:187], v[32:35]
	v_mfma_f32_16x16x32_bf16 v[0:3], v[204:207], v[184:187], v[0:3]
	s_setprio 0
	s_add_i32 s46, 0, 0x18000
	v_add_u32_e32 v152, s46, v141
	s_barrier
	ds_read_b128 v[128:131], v152
	ds_read_b128 v[144:147], v152 offset:1024
	ds_read_b128 v[148:151], v152 offset:2048
	ds_read_b128 v[152:155], v152 offset:3072
	s_add_u32 s14, s20, 0x40000
	s_addc_u32 s15, s21, 0
	s_mov_b32 m0, s30
	v_lshl_add_u64 v[188:189], s[14:15], 0, v[192:193]
	ds_read_b128 v[156:159], v143 offset:32768
	ds_read_b128 v[160:163], v143 offset:33792
	ds_read_b128 v[164:167], v143 offset:34816
	ds_read_b128 v[168:171], v143 offset:35840
	ds_read_b128 v[172:175], v143 offset:36864
	ds_read_b128 v[176:179], v143 offset:37888
	ds_read_b128 v[180:183], v143 offset:38912
	ds_read_b128 v[184:187], v143 offset:39936
	global_load_lds_dwordx4 v[188:189], off
	v_lshl_add_u64 v[188:189], s[14:15], 0, v[132:133]
	s_mov_b32 m0, s31
	s_nop 0
	global_load_lds_dwordx4 v[188:189], off
	s_waitcnt lgkmcnt(8)
	s_barrier
	s_waitcnt lgkmcnt(0)
	s_setprio 1
	s_waitcnt lgkmcnt(0)
	v_mfma_f32_16x16x32_bf16 v[124:127], v[128:131], v[156:159], v[124:127]
	v_mfma_f32_16x16x32_bf16 v[92:95], v[148:151], v[156:159], v[92:95]
	v_mfma_f32_16x16x32_bf16 v[120:123], v[128:131], v[164:167], v[120:123]
	v_mfma_f32_16x16x32_bf16 v[88:91], v[148:151], v[164:167], v[88:91]
	v_mfma_f32_16x16x32_bf16 v[116:119], v[128:131], v[172:175], v[116:119]
	v_mfma_f32_16x16x32_bf16 v[84:87], v[148:151], v[172:175], v[84:87]
	v_mfma_f32_16x16x32_bf16 v[112:115], v[128:131], v[180:183], v[112:115]
	v_mfma_f32_16x16x32_bf16 v[80:83], v[148:151], v[180:183], v[80:83]
	v_mfma_f32_16x16x32_bf16 v[124:127], v[144:147], v[160:163], v[124:127]
	v_mfma_f32_16x16x32_bf16 v[92:95], v[152:155], v[160:163], v[92:95]
	v_mfma_f32_16x16x32_bf16 v[120:123], v[144:147], v[168:171], v[120:123]
	v_mfma_f32_16x16x32_bf16 v[88:91], v[152:155], v[168:171], v[88:91]
	v_mfma_f32_16x16x32_bf16 v[116:119], v[144:147], v[176:179], v[116:119]
	v_mfma_f32_16x16x32_bf16 v[84:87], v[152:155], v[176:179], v[84:87]
	v_mfma_f32_16x16x32_bf16 v[112:115], v[144:147], v[184:187], v[112:115]
	v_mfma_f32_16x16x32_bf16 v[80:83], v[152:155], v[184:187], v[80:83]
	s_setprio 0
	s_barrier
	s_add_i32 s20, 0, 0x1c000
	s_add_i32 s14, s46, s28
	v_add_u32_e32 v199, s20, v141
	v_lshl_add_u64 v[138:139], v[138:139], 0, s[74:75]
	s_mov_b32 m0, s14
	ds_read_b128 v[188:191], v199
	ds_read_b128 v[194:197], v199 offset:1024
	ds_read_b128 v[200:203], v199 offset:2048
	ds_read_b128 v[204:207], v199 offset:3072
	global_load_lds_dwordx4 v[138:139], off
	v_lshl_add_u64 v[138:139], v[208:209], 0, s[74:75]
	s_add_i32 m0, s14, 0x2000
	s_nop 0
	global_load_lds_dwordx4 v[138:139], off
	s_barrier
	s_waitcnt lgkmcnt(0)
	s_setprio 1
	s_waitcnt lgkmcnt(0)
	v_mfma_f32_16x16x32_bf16 v[60:63], v[188:191], v[156:159], v[60:63]
	v_mfma_f32_16x16x32_bf16 v[28:31], v[200:203], v[156:159], v[28:31]
	v_mfma_f32_16x16x32_bf16 v[56:59], v[188:191], v[164:167], v[56:59]
	v_mfma_f32_16x16x32_bf16 v[24:27], v[200:203], v[164:167], v[24:27]
	v_mfma_f32_16x16x32_bf16 v[52:55], v[188:191], v[172:175], v[52:55]
	v_mfma_f32_16x16x32_bf16 v[20:23], v[200:203], v[172:175], v[20:23]
	v_mfma_f32_16x16x32_bf16 v[48:51], v[188:191], v[180:183], v[48:51]
	v_mfma_f32_16x16x32_bf16 v[16:19], v[200:203], v[180:183], v[16:19]
	v_mfma_f32_16x16x32_bf16 v[60:63], v[194:197], v[160:163], v[60:63]
	v_mfma_f32_16x16x32_bf16 v[28:31], v[204:207], v[160:163], v[28:31]
	v_mfma_f32_16x16x32_bf16 v[56:59], v[194:197], v[168:171], v[56:59]
	v_mfma_f32_16x16x32_bf16 v[24:27], v[204:207], v[168:171], v[24:27]
	v_mfma_f32_16x16x32_bf16 v[52:55], v[194:197], v[176:179], v[52:55]
	v_mfma_f32_16x16x32_bf16 v[20:23], v[204:207], v[176:179], v[20:23]
	v_mfma_f32_16x16x32_bf16 v[48:51], v[194:197], v[184:187], v[48:51]
	v_mfma_f32_16x16x32_bf16 v[16:19], v[204:207], v[184:187], v[16:19]
	s_setprio 0
	s_mov_b32 m0, s38
	v_lshl_add_u64 v[138:139], v[210:211], 0, s[74:75]
	s_barrier
	ds_read_b128 v[156:159], v143 offset:49152
	ds_read_b128 v[160:163], v143 offset:50176
	ds_read_b128 v[164:167], v143 offset:51200
	ds_read_b128 v[168:171], v143 offset:52224
	ds_read_b128 v[172:175], v143 offset:53248
	ds_read_b128 v[176:179], v143 offset:54272
	ds_read_b128 v[180:183], v143 offset:55296
	ds_read_b128 v[184:187], v143 offset:56320
	global_load_lds_dwordx4 v[138:139], off
	v_lshl_add_u64 v[138:139], v[212:213], 0, s[74:75]
	s_mov_b32 m0, s39
	s_nop 0
	global_load_lds_dwordx4 v[138:139], off
	s_barrier
; __device__ __forceinline__ unsigned cvt_pk_bf16(float lo, float hi) { unsigned r; asm volatile("s_nop 0\n\tv_cvt_pk_bf16_f32 %0, %1, %2\n\ts_nop 1" : "=v"(r) : "v"(lo), "v"(hi)); return r; }
; #define PG8_STAGE(bufoff, gbase, voff) do { _Pragma("unroll") for (int _i = 0; _i < 2; ++_i) \
;         __builtin_amdgcn_global_load_lds((const unsigned*)((const char*)(gbase) + (voff)[_i]), (PG8_LAS unsigned*)(lds + (bufoff) + ldsw + _i * 8192), 16, 0, 0); } while (0)
; #define PG8_MMA(ai, bj, At, Bt) do { __builtin_amdgcn_s_setprio(1); _Pragma("unroll") for (int m = 0; m < 4; ++m) _Pragma("unroll") for (int n = 0; n < 2; ++n) _Pragma("unroll") for (int k = 0; k < 2; ++k) \
;         acc[ai][bj][m][n] = __builtin_amdgcn_mfma_f32_16x16x32_bf16(Bt[n][k], At[m][k], acc[ai][bj][m][n], 0, 0, 0); __builtin_amdgcn_s_setprio(0); } while (0)
; #define PG8_WAIT_V(n) asm volatile("s_waitcnt vmcnt(" #n ")" ::: "memory")
; #define PG8_BAR __builtin_amdgcn_s_barrier()
; template <class Epi, class Sched>
; __device__ __forceinline__ void gemm_phase(PG8_LAS unsigned char* lds, const Gemm g, const Sched& S, const Epi& E, int tid_in) {
;     ...
;             PG8_STAGE(PG8_SB(1, 1), b3 + hstep, voffB);
;             PG8_WAIT_V(6); PG8_BAR; PG8_MMA(1, 1, At, B1); PG8_BAR;
;     __device__ __forceinline__ void operator()(f32x4 (&acc)[2][2][4][2], const Unit& u, int wr, int wc, int fr, int fq) const {
;         const int row0 = u.pm * 256 + wr * 64 + fr, col0 = u.pn * 256 + wc * 32 + 4 * fq;
;         const float* gr = gate + (size_t)(bbase + (u.pm * 256) / SEQ) * MODW;
; #pragma unroll
;         for (int bj = 0; bj < 2; ++bj)
; #pragma unroll
;             for (int n = 0; n < 2; ++n) { const int col = col0 + bj * 128 + n * 16; const f32x4 gv = *(const f32x4*)(gr + col);
;                 f32x4 bv = (f32x4){0.f, 0.f, 0.f, 0.f}; if (bias) bv = *(const f32x4*)(bias + col);
; #pragma unroll
;                 for (int ai = 0; ai < 2; ++ai)
; #pragma unroll
;                     for (int m = 0; m < 4; ++m) { const size_t row = row0 + ai * 128 + m * 16;
;                         const f32x4 o = gv * (acc[ai][bj][m][n] + bv); u32x2 w; w.x = cvt_pk_bf16(o[0], o[1]); w.y = cvt_pk_bf16(o[2], o[3]);
	s_waitcnt lgkmcnt(0)
	s_setprio 1
	s_waitcnt lgkmcnt(0)
	v_mfma_f32_16x16x32_bf16 v[108:111], v[128:131], v[156:159], v[108:111]
	v_mfma_f32_16x16x32_bf16 v[76:79], v[148:151], v[156:159], v[76:79]
	v_mfma_f32_16x16x32_bf16 v[104:107], v[128:131], v[164:167], v[104:107]
	v_mfma_f32_16x16x32_bf16 v[72:75], v[148:151], v[164:167], v[72:75]
	v_mfma_f32_16x16x32_bf16 v[100:103], v[128:131], v[172:175], v[100:103]
	v_mfma_f32_16x16x32_bf16 v[68:71], v[148:151], v[172:175], v[68:71]
	v_mfma_f32_16x16x32_bf16 v[96:99], v[128:131], v[180:183], v[96:99]
	v_mfma_f32_16x16x32_bf16 v[64:67], v[148:151], v[180:183], v[64:67]
	v_mfma_f32_16x16x32_bf16 v[108:111], v[144:147], v[160:163], v[108:111]
	v_mfma_f32_16x16x32_bf16 v[76:79], v[152:155], v[160:163], v[76:79]
	v_mfma_f32_16x16x32_bf16 v[104:107], v[144:147], v[168:171], v[104:107]
	v_mfma_f32_16x16x32_bf16 v[72:75], v[152:155], v[168:171], v[72:75]
	v_mfma_f32_16x16x32_bf16 v[100:103], v[144:147], v[176:179], v[100:103]
	v_mfma_f32_16x16x32_bf16 v[68:71], v[152:155], v[176:179], v[68:71]
	v_mfma_f32_16x16x32_bf16 v[96:99], v[144:147], v[184:187], v[96:99]
	v_mfma_f32_16x16x32_bf16 v[64:67], v[152:155], v[184:187], v[64:67]
	s_setprio 0
	s_barrier
	s_add_u32 s14, s18, 0x40080
	s_addc_u32 s15, s19, 0
	s_add_i32 s18, s20, s28
	v_lshl_add_u64 v[128:129], s[14:15], 0, v[192:193]
	s_mov_b32 m0, s18
	s_nop 0
	global_load_lds_dwordx4 v[128:129], off
	v_lshl_add_u64 v[128:129], s[14:15], 0, v[132:133]
	s_add_i32 m0, s18, 0x2000
	s_nop 0
	global_load_lds_dwordx4 v[128:129], off
	s_waitcnt vmcnt(6)
	s_barrier
	s_setprio 1
	v_mfma_f32_16x16x32_bf16 v[44:47], v[188:191], v[156:159], v[44:47]
	v_mfma_f32_16x16x32_bf16 v[12:15], v[200:203], v[156:159], v[12:15]
	v_mfma_f32_16x16x32_bf16 v[40:43], v[188:191], v[164:167], v[40:43]
	v_mfma_f32_16x16x32_bf16 v[8:11], v[200:203], v[164:167], v[8:11]
	v_mfma_f32_16x16x32_bf16 v[36:39], v[188:191], v[172:175], v[36:39]
	v_mfma_f32_16x16x32_bf16 v[4:7], v[200:203], v[172:175], v[4:7]
	v_mfma_f32_16x16x32_bf16 v[32:35], v[188:191], v[180:183], v[32:35]
	v_mfma_f32_16x16x32_bf16 v[0:3], v[200:203], v[180:183], v[0:3]
	v_mfma_f32_16x16x32_bf16 v[44:47], v[194:197], v[160:163], v[44:47]
	v_mfma_f32_16x16x32_bf16 v[12:15], v[204:207], v[160:163], v[12:15]
	v_mfma_f32_16x16x32_bf16 v[40:43], v[194:197], v[168:171], v[40:43]
	v_mfma_f32_16x16x32_bf16 v[8:11], v[204:207], v[168:171], v[8:11]
	v_mfma_f32_16x16x32_bf16 v[36:39], v[194:197], v[176:179], v[36:39]
	v_mfma_f32_16x16x32_bf16 v[4:7], v[204:207], v[176:179], v[4:7]
	v_mfma_f32_16x16x32_bf16 v[32:35], v[194:197], v[184:187], v[32:35]
	v_mfma_f32_16x16x32_bf16 v[0:3], v[204:207], v[184:187], v[0:3]
	s_setprio 0
	s_add_i32 s45, s45, 2
	s_add_u32 s43, s43, 0x100
	s_addc_u32 s44, s44, 0
	s_cmp_gt_u32 s45, 13
	s_mov_b64 s[14:15], s[16:17]
	s_barrier
	s_cbranch_scc0 .LBB0_325
	s_ashr_i32 s5, s12, 31
	s_lshr_b32 s5, s5, 29
	s_add_i32 s5, s12, s5
	s_ashr_i32 s5, s5, 3
	s_add_i32 s5, s5, s76
	s_mul_hi_i32 s7, s5, 0x6000
	s_mulk_i32 s5, 0x6000
	v_lshl_or_b32 v146, s33, 8, v142
	s_add_u32 s14, s36, s5
	s_addc_u32 s15, s37, s7
	v_ashrrev_i32_e32 v147, 31, v146
	v_lshl_add_u64 v[138:139], v[146:147], 2, s[14:15]
	global_load_dwordx4 v[128:131], v[138:139], off
	v_lshl_add_u32 v144, s12, 8, v140
	v_pk_add_f32 v[124:125], v[124:125], 0 op_sel_hi:[1,0]
	v_ashrrev_i32_e32 v145, 31, v144
	v_pk_add_f32 v[126:127], v[126:127], 0 op_sel_hi:[1,0]
	v_pk_add_f32 v[120:121], v[120:121], 0 op_sel_hi:[1,0]
	v_pk_add_f32 v[122:123], v[122:123], 0 op_sel_hi:[1,0]
	v_pk_add_f32 v[116:117], v[116:117], 0 op_sel_hi:[1,0]
	v_pk_add_f32 v[118:119], v[118:119], 0 op_sel_hi:[1,0]
	v_pk_add_f32 v[112:113], v[112:113], 0 op_sel_hi:[1,0]
	v_pk_add_f32 v[114:115], v[114:115], 0 op_sel_hi:[1,0]
	v_pk_add_f32 v[110:111], v[110:111], 0 op_sel_hi:[1,0]
	v_pk_add_f32 v[108:109], v[108:109], 0 op_sel_hi:[1,0]
	v_pk_add_f32 v[106:107], v[106:107], 0 op_sel_hi:[1,0]
	v_pk_add_f32 v[104:105], v[104:105], 0 op_sel_hi:[1,0]
	v_pk_add_f32 v[102:103], v[102:103], 0 op_sel_hi:[1,0]
	v_pk_add_f32 v[100:101], v[100:101], 0 op_sel_hi:[1,0]
	v_pk_add_f32 v[98:99], v[98:99], 0 op_sel_hi:[1,0]
	v_pk_add_f32 v[96:97], v[96:97], 0 op_sel_hi:[1,0]
	s_mov_b32 s5, 0x58000
	s_mov_b64 s[14:15], 0x40000
	v_pk_add_f32 v[92:93], v[92:93], 0 op_sel_hi:[1,0]
	v_pk_add_f32 v[88:89], v[88:89], 0 op_sel_hi:[1,0]
	v_pk_add_f32 v[84:85], v[84:85], 0 op_sel_hi:[1,0]
	v_pk_add_f32 v[80:81], v[80:81], 0 op_sel_hi:[1,0]
	v_pk_add_f32 v[76:77], v[76:77], 0 op_sel_hi:[1,0]
	v_pk_add_f32 v[72:73], v[72:73], 0 op_sel_hi:[1,0]
	v_pk_add_f32 v[68:69], v[68:69], 0 op_sel_hi:[1,0]
	v_pk_add_f32 v[64:65], v[64:65], 0 op_sel_hi:[1,0]
	v_pk_add_f32 v[94:95], v[94:95], 0 op_sel_hi:[1,0]
	v_pk_add_f32 v[90:91], v[90:91], 0 op_sel_hi:[1,0]
	v_pk_add_f32 v[86:87], v[86:87], 0 op_sel_hi:[1,0]
	v_pk_add_f32 v[82:83], v[82:83], 0 op_sel_hi:[1,0]
	v_pk_add_f32 v[78:79], v[78:79], 0 op_sel_hi:[1,0]
	v_pk_add_f32 v[74:75], v[74:75], 0 op_sel_hi:[1,0]
	v_pk_add_f32 v[70:71], v[70:71], 0 op_sel_hi:[1,0]
	v_pk_add_f32 v[66:67], v[66:67], 0 op_sel_hi:[1,0]
	v_pk_add_f32 v[60:61], v[60:61], 0 op_sel_hi:[1,0]
	v_pk_add_f32 v[56:57], v[56:57], 0 op_sel_hi:[1,0]
	v_pk_add_f32 v[52:53], v[52:53], 0 op_sel_hi:[1,0]
	v_pk_add_f32 v[48:49], v[48:49], 0 op_sel_hi:[1,0]
	v_pk_add_f32 v[44:45], v[44:45], 0 op_sel_hi:[1,0]
	v_pk_add_f32 v[40:41], v[40:41], 0 op_sel_hi:[1,0]
	v_pk_add_f32 v[36:37], v[36:37], 0 op_sel_hi:[1,0]
	v_pk_add_f32 v[32:33], v[32:33], 0 op_sel_hi:[1,0]
	v_pk_add_f32 v[62:63], v[62:63], 0 op_sel_hi:[1,0]
	v_pk_add_f32 v[58:59], v[58:59], 0 op_sel_hi:[1,0]
	v_pk_add_f32 v[54:55], v[54:55], 0 op_sel_hi:[1,0]
	v_pk_add_f32 v[50:51], v[50:51], 0 op_sel_hi:[1,0]
	v_pk_add_f32 v[46:47], v[46:47], 0 op_sel_hi:[1,0]
	v_pk_add_f32 v[42:43], v[42:43], 0 op_sel_hi:[1,0]
	v_pk_add_f32 v[38:39], v[38:39], 0 op_sel_hi:[1,0]
	v_pk_add_f32 v[34:35], v[34:35], 0 op_sel_hi:[1,0]
	v_pk_add_f32 v[28:29], v[28:29], 0 op_sel_hi:[1,0]
	v_pk_add_f32 v[24:25], v[24:25], 0 op_sel_hi:[1,0]
	v_pk_add_f32 v[20:21], v[20:21], 0 op_sel_hi:[1,0]
	v_pk_add_f32 v[16:17], v[16:17], 0 op_sel_hi:[1,0]
	v_pk_add_f32 v[12:13], v[12:13], 0 op_sel_hi:[1,0]
	v_pk_add_f32 v[8:9], v[8:9], 0 op_sel_hi:[1,0]
	v_pk_add_f32 v[4:5], v[4:5], 0 op_sel_hi:[1,0]
	v_pk_add_f32 v[0:1], v[0:1], 0 op_sel_hi:[1,0]
	v_pk_add_f32 v[30:31], v[30:31], 0 op_sel_hi:[1,0]
	v_pk_add_f32 v[26:27], v[26:27], 0 op_sel_hi:[1,0]
	v_pk_add_f32 v[22:23], v[22:23], 0 op_sel_hi:[1,0]
	v_pk_add_f32 v[18:19], v[18:19], 0 op_sel_hi:[1,0]
	v_pk_add_f32 v[14:15], v[14:15], 0 op_sel_hi:[1,0]
	v_pk_add_f32 v[10:11], v[10:11], 0 op_sel_hi:[1,0]
	v_pk_add_f32 v[6:7], v[6:7], 0 op_sel_hi:[1,0]
	v_pk_add_f32 v[2:3], v[2:3], 0 op_sel_hi:[1,0]
	s_mov_b32 s33, s4
	s_mov_b32 s12, s6
	s_mov_b64 s[16:17], s[10:11]
	s_waitcnt vmcnt(0)
; __device__ __forceinline__ unsigned cvt_pk_bf16(float lo, float hi) { unsigned r; asm volatile("s_nop 0\n\tv_cvt_pk_bf16_f32 %0, %1, %2\n\ts_nop 1" : "=v"(r) : "v"(lo), "v"(hi)); return r; }
;     __device__ __forceinline__ void operator()(f32x4 (&acc)[2][2][4][2], const Unit& u, int wr, int wc, int fr, int fq) const {
;     ...
;         for (int bj = 0; bj < 2; ++bj)
; #pragma unroll
;             for (int n = 0; n < 2; ++n) { const int col = col0 + bj * 128 + n * 16; const f32x4 gv = *(const f32x4*)(gr + col);
;                 f32x4 bv = (f32x4){0.f, 0.f, 0.f, 0.f}; if (bias) bv = *(const f32x4*)(bias + col);
; #pragma unroll
;                 for (int ai = 0; ai < 2; ++ai)
; #pragma unroll
;                     for (int m = 0; m < 4; ++m) { const size_t row = row0 + ai * 128 + m * 16;
;                         const f32x4 o = gv * (acc[ai][bj][m][n] + bv); u32x2 w; w.x = cvt_pk_bf16(o[0], o[1]); w.y = cvt_pk_bf16(o[2], o[3]);
;                         *(u32x2*)(O + row * 1024 + col) = w; } }
	v_pk_mul_f32 v[124:125], v[124:125], v[128:129]
	v_pk_mul_f32 v[126:127], v[126:127], v[130:131]
	v_cvt_pk_bf16_f32 v148, v124, v125
	v_lshlrev_b64 v[124:125], 11, v[144:145]
	v_cvt_pk_bf16_f32 v149, v126, v127
	v_lshl_add_u64 v[124:125], s[0:1], 0, v[124:125]
	v_lshlrev_b64 v[126:127], 1, v[146:147]
	v_or_b32_e32 v146, 16, v144
	v_lshl_add_u64 v[124:125], v[124:125], 0, v[126:127]
	v_ashrrev_i32_e32 v147, 31, v146
	v_pk_mul_f32 v[120:121], v[120:121], v[128:129]
	global_store_dwordx2 v[124:125], v[148:149], off
	v_pk_mul_f32 v[122:123], v[122:123], v[130:131]
	v_cvt_pk_bf16_f32 v148, v120, v121
	v_lshlrev_b64 v[120:121], 11, v[146:147]
	v_cvt_pk_bf16_f32 v149, v122, v123
	v_lshl_add_u64 v[120:121], s[0:1], 0, v[120:121]
	v_or_b32_e32 v122, 32, v144
	v_lshl_add_u64 v[120:121], v[120:121], 0, v[126:127]
	v_ashrrev_i32_e32 v123, 31, v122
	v_pk_mul_f32 v[116:117], v[116:117], v[128:129]
	global_store_dwordx2 v[120:121], v[148:149], off
	v_pk_mul_f32 v[118:119], v[118:119], v[130:131]
	v_cvt_pk_bf16_f32 v146, v116, v117
	v_lshlrev_b64 v[116:117], 11, v[122:123]
	v_cvt_pk_bf16_f32 v147, v118, v119
	v_lshl_add_u64 v[116:117], s[0:1], 0, v[116:117]
	v_or_b32_e32 v118, 48, v144
	v_lshl_add_u64 v[116:117], v[116:117], 0, v[126:127]
	v_ashrrev_i32_e32 v119, 31, v118
	v_pk_mul_f32 v[112:113], v[112:113], v[128:129]
	global_store_dwordx2 v[116:117], v[146:147], off
	v_cvt_pk_bf16_f32 v122, v112, v113
	v_lshlrev_b64 v[112:113], 11, v[118:119]
	v_lshl_add_u64 v[112:113], s[0:1], 0, v[112:113]
	v_pk_mul_f32 v[114:115], v[114:115], v[130:131]
	v_lshl_add_u64 v[112:113], v[112:113], 0, v[126:127]
	v_pk_mul_f32 v[110:111], v[110:111], v[130:131]
	v_cvt_pk_bf16_f32 v123, v114, v115
	global_store_dwordx2 v[112:113], v[122:123], off
	v_pk_mul_f32 v[108:109], v[108:109], v[128:129]
	v_pk_mul_f32 v[106:107], v[106:107], v[130:131]
	v_cvt_pk_bf16_f32 v114, v108, v109
	v_cvt_pk_bf16_f32 v115, v110, v111
	v_add_co_u32_e32 v110, vcc, s63, v124
	v_pk_mul_f32 v[104:105], v[104:105], v[128:129]
	s_nop 0
	v_addc_co_u32_e32 v111, vcc, 0, v125, vcc
	global_store_dwordx2 v[110:111], v[114:115], off
	v_cvt_pk_bf16_f32 v110, v104, v105
	v_cvt_pk_bf16_f32 v111, v106, v107
	v_add_co_u32_e32 v106, vcc, s66, v124
	v_pk_mul_f32 v[102:103], v[102:103], v[130:131]
	s_nop 0
	v_addc_co_u32_e32 v107, vcc, 0, v125, vcc
	global_store_dwordx2 v[106:107], v[110:111], off
	v_pk_mul_f32 v[100:101], v[100:101], v[128:129]
	v_pk_mul_f32 v[98:99], v[98:99], v[130:131]
	v_cvt_pk_bf16_f32 v106, v100, v101
	v_cvt_pk_bf16_f32 v107, v102, v103
	v_add_co_u32_e32 v102, vcc, s55, v124
	v_pk_mul_f32 v[96:97], v[96:97], v[128:129]
	s_nop 0
	v_addc_co_u32_e32 v103, vcc, 0, v125, vcc
	global_store_dwordx2 v[102:103], v[106:107], off
	v_cvt_pk_bf16_f32 v96, v96, v97
	v_cvt_pk_bf16_f32 v97, v98, v99
	v_add_co_u32_e32 v98, vcc, s5, v124
	v_lshl_add_u64 v[108:109], v[124:125], 0, s[14:15]
	s_nop 0
	v_addc_co_u32_e32 v99, vcc, 0, v125, vcc
	global_store_dwordx2 v[98:99], v[96:97], off
	global_load_dwordx4 v[96:99], v[138:139], off offset:64
	s_mov_b64 s[14:15], 0x50000
	v_lshl_add_u64 v[100:101], v[124:125], 0, s[14:15]
	s_mov_b64 s[14:15], 0x58000
	v_lshl_add_u64 v[104:105], v[124:125], 0, s[64:65]
	v_lshl_add_u64 v[102:103], v[124:125], 0, s[14:15]
	s_and_b64 vcc, exec, s[2:3]
	s_mov_b64 s[14:15], s[8:9]
	s_waitcnt vmcnt(0)
	v_pk_mul_f32 v[92:93], v[92:93], v[96:97]
	v_pk_mul_f32 v[88:89], v[88:89], v[96:97]
	v_pk_mul_f32 v[84:85], v[84:85], v[96:97]
	v_pk_mul_f32 v[80:81], v[80:81], v[96:97]
	v_pk_mul_f32 v[76:77], v[76:77], v[96:97]
	v_pk_mul_f32 v[72:73], v[72:73], v[96:97]
	v_pk_mul_f32 v[68:69], v[68:69], v[96:97]
	v_pk_mul_f32 v[64:65], v[64:65], v[96:97]
	v_pk_mul_f32 v[94:95], v[94:95], v[98:99]
	v_cvt_pk_bf16_f32 v92, v92, v93
	v_pk_mul_f32 v[90:91], v[90:91], v[98:99]
	v_cvt_pk_bf16_f32 v93, v94, v95
	global_store_dwordx2 v[124:125], v[92:93], off offset:32
	v_cvt_pk_bf16_f32 v88, v88, v89
	v_cvt_pk_bf16_f32 v89, v90, v91
	global_store_dwordx2 v[120:121], v[88:89], off offset:32
	v_pk_mul_f32 v[86:87], v[86:87], v[98:99]
	v_cvt_pk_bf16_f32 v84, v84, v85
	v_pk_mul_f32 v[82:83], v[82:83], v[98:99]
	v_cvt_pk_bf16_f32 v85, v86, v87
	global_store_dwordx2 v[116:117], v[84:85], off offset:32
	v_cvt_pk_bf16_f32 v80, v80, v81
	v_cvt_pk_bf16_f32 v81, v82, v83
	global_store_dwordx2 v[112:113], v[80:81], off offset:32
	v_pk_mul_f32 v[78:79], v[78:79], v[98:99]
	v_cvt_pk_bf16_f32 v76, v76, v77
	v_pk_mul_f32 v[74:75], v[74:75], v[98:99]
	v_cvt_pk_bf16_f32 v77, v78, v79
	global_store_dwordx2 v[108:109], v[76:77], off offset:32
	v_cvt_pk_bf16_f32 v72, v72, v73
	v_cvt_pk_bf16_f32 v73, v74, v75
	global_store_dwordx2 v[104:105], v[72:73], off offset:32
	v_pk_mul_f32 v[70:71], v[70:71], v[98:99]
	v_cvt_pk_bf16_f32 v68, v68, v69
	v_pk_mul_f32 v[66:67], v[66:67], v[98:99]
	v_cvt_pk_bf16_f32 v69, v70, v71
	global_store_dwordx2 v[100:101], v[68:69], off offset:32
	v_cvt_pk_bf16_f32 v64, v64, v65
	v_cvt_pk_bf16_f32 v65, v66, v67
	global_store_dwordx2 v[102:103], v[64:65], off offset:32
	global_load_dwordx4 v[64:67], v[138:139], off offset:512
	s_waitcnt vmcnt(0)
; __device__ __forceinline__ unsigned cvt_pk_bf16(float lo, float hi) { unsigned r; asm volatile("s_nop 0\n\tv_cvt_pk_bf16_f32 %0, %1, %2\n\ts_nop 1" : "=v"(r) : "v"(lo), "v"(hi)); return r; }
;     __device__ __forceinline__ void operator()(f32x4 (&acc)[2][2][4][2], const Unit& u, int wr, int wc, int fr, int fq) const {
;     ...
;         for (int bj = 0; bj < 2; ++bj)
; #pragma unroll
;             for (int n = 0; n < 2; ++n) { const int col = col0 + bj * 128 + n * 16; const f32x4 gv = *(const f32x4*)(gr + col);
;                 f32x4 bv = (f32x4){0.f, 0.f, 0.f, 0.f}; if (bias) bv = *(const f32x4*)(bias + col);
; #pragma unroll
;                 for (int ai = 0; ai < 2; ++ai)
; #pragma unroll
;                     for (int m = 0; m < 4; ++m) { const size_t row = row0 + ai * 128 + m * 16;
;                         const f32x4 o = gv * (acc[ai][bj][m][n] + bv); u32x2 w; w.x = cvt_pk_bf16(o[0], o[1]); w.y = cvt_pk_bf16(o[2], o[3]);
;                         *(u32x2*)(O + row * 1024 + col) = w; } }
	v_pk_mul_f32 v[60:61], v[60:61], v[64:65]
	v_pk_mul_f32 v[56:57], v[56:57], v[64:65]
	v_pk_mul_f32 v[52:53], v[52:53], v[64:65]
	v_pk_mul_f32 v[48:49], v[48:49], v[64:65]
	v_pk_mul_f32 v[44:45], v[44:45], v[64:65]
	v_pk_mul_f32 v[40:41], v[40:41], v[64:65]
	v_pk_mul_f32 v[36:37], v[36:37], v[64:65]
	v_pk_mul_f32 v[32:33], v[32:33], v[64:65]
	v_pk_mul_f32 v[62:63], v[62:63], v[66:67]
	v_cvt_pk_bf16_f32 v60, v60, v61
	v_pk_mul_f32 v[58:59], v[58:59], v[66:67]
	v_cvt_pk_bf16_f32 v61, v62, v63
	global_store_dwordx2 v[124:125], v[60:61], off offset:256
	v_cvt_pk_bf16_f32 v56, v56, v57
	v_cvt_pk_bf16_f32 v57, v58, v59
	global_store_dwordx2 v[120:121], v[56:57], off offset:256
	v_pk_mul_f32 v[54:55], v[54:55], v[66:67]
	v_cvt_pk_bf16_f32 v52, v52, v53
	v_pk_mul_f32 v[50:51], v[50:51], v[66:67]
	v_cvt_pk_bf16_f32 v53, v54, v55
	global_store_dwordx2 v[116:117], v[52:53], off offset:256
	v_cvt_pk_bf16_f32 v48, v48, v49
	v_cvt_pk_bf16_f32 v49, v50, v51
	global_store_dwordx2 v[112:113], v[48:49], off offset:256
	v_pk_mul_f32 v[46:47], v[46:47], v[66:67]
	v_cvt_pk_bf16_f32 v44, v44, v45
	v_pk_mul_f32 v[42:43], v[42:43], v[66:67]
	v_cvt_pk_bf16_f32 v45, v46, v47
	global_store_dwordx2 v[108:109], v[44:45], off offset:256
	v_cvt_pk_bf16_f32 v40, v40, v41
	v_cvt_pk_bf16_f32 v41, v42, v43
	global_store_dwordx2 v[104:105], v[40:41], off offset:256
	v_pk_mul_f32 v[38:39], v[38:39], v[66:67]
	v_cvt_pk_bf16_f32 v36, v36, v37
	v_pk_mul_f32 v[34:35], v[34:35], v[66:67]
	v_cvt_pk_bf16_f32 v37, v38, v39
	global_store_dwordx2 v[100:101], v[36:37], off offset:256
	v_cvt_pk_bf16_f32 v32, v32, v33
	v_cvt_pk_bf16_f32 v33, v34, v35
	global_store_dwordx2 v[102:103], v[32:33], off offset:256
	global_load_dwordx4 v[32:35], v[138:139], off offset:576
	s_waitcnt vmcnt(0)
	v_pk_mul_f32 v[28:29], v[28:29], v[32:33]
	v_pk_mul_f32 v[24:25], v[24:25], v[32:33]
	v_pk_mul_f32 v[20:21], v[20:21], v[32:33]
	v_pk_mul_f32 v[16:17], v[16:17], v[32:33]
	v_pk_mul_f32 v[12:13], v[12:13], v[32:33]
	v_pk_mul_f32 v[8:9], v[8:9], v[32:33]
	v_pk_mul_f32 v[4:5], v[4:5], v[32:33]
	v_pk_mul_f32 v[0:1], v[0:1], v[32:33]
	v_pk_mul_f32 v[30:31], v[30:31], v[34:35]
	v_cvt_pk_bf16_f32 v28, v28, v29
	v_pk_mul_f32 v[26:27], v[26:27], v[34:35]
	v_cvt_pk_bf16_f32 v29, v30, v31
	global_store_dwordx2 v[124:125], v[28:29], off offset:288
	v_cvt_pk_bf16_f32 v24, v24, v25
	v_cvt_pk_bf16_f32 v25, v26, v27
	global_store_dwordx2 v[120:121], v[24:25], off offset:288
	v_pk_mul_f32 v[22:23], v[22:23], v[34:35]
	v_cvt_pk_bf16_f32 v20, v20, v21
	v_pk_mul_f32 v[18:19], v[18:19], v[34:35]
	v_cvt_pk_bf16_f32 v21, v22, v23
	global_store_dwordx2 v[116:117], v[20:21], off offset:288
	v_cvt_pk_bf16_f32 v16, v16, v17
	v_cvt_pk_bf16_f32 v17, v18, v19
	global_store_dwordx2 v[112:113], v[16:17], off offset:288
	v_pk_mul_f32 v[14:15], v[14:15], v[34:35]
	v_cvt_pk_bf16_f32 v12, v12, v13
	v_pk_mul_f32 v[10:11], v[10:11], v[34:35]
	v_cvt_pk_bf16_f32 v13, v14, v15
	global_store_dwordx2 v[108:109], v[12:13], off offset:288
	v_cvt_pk_bf16_f32 v8, v8, v9
	v_cvt_pk_bf16_f32 v9, v10, v11
	global_store_dwordx2 v[104:105], v[8:9], off offset:288
	v_pk_mul_f32 v[6:7], v[6:7], v[34:35]
	v_cvt_pk_bf16_f32 v4, v4, v5
	v_pk_mul_f32 v[2:3], v[2:3], v[34:35]
	v_cvt_pk_bf16_f32 v5, v6, v7
	global_store_dwordx2 v[100:101], v[4:5], off offset:288
	v_cvt_pk_bf16_f32 v0, v0, v1
	v_cvt_pk_bf16_f32 v1, v2, v3
	s_nop 1
	global_store_dwordx2 v[102:103], v[0:1], off offset:288
	s_cbranch_vccz .LBB0_318
	s_waitcnt vmcnt(0)
	s_cmpk_gt_u32 s22, 0xff
	s_cbranch_scc1 .LBB0_329
	s_barrier

; #define PG8_STAGE(bufoff, gbase, voff) do { _Pragma("unroll") for (int _i = 0; _i < 2; ++_i) \
;         __builtin_amdgcn_global_load_lds((const unsigned*)((const char*)(gbase) + (voff)[_i]), (PG8_LAS unsigned*)(lds + (bufoff) + ldsw + _i * 8192), 16, 0, 0); } while (0)
; #define PG8_LDA(dst, b, h) do { _Pragma("unroll") for (int m = 0; m < 4; ++m) _Pragma("unroll") for (int k = 0; k < 2; ++k) dst[m][k] = *(const PG8_LAS bf16x8*)(lds + PG8_SA(b, h) + aoff + m * 2048 + k * 1024); } while (0)
; #define PG8_LDB(dst, b, h) do { _Pragma("unroll") for (int n = 0; n < 2; ++n) _Pragma("unroll") for (int k = 0; k < 2; ++k) dst[n][k] = *(const PG8_LAS bf16x8*)(lds + PG8_SB(b, h) + boff + n * 2048 + k * 1024); } while (0)
; #define PG8_MMA(ai, bj, At, Bt) do { __builtin_amdgcn_s_setprio(1); _Pragma("unroll") for (int m = 0; m < 4; ++m) _Pragma("unroll") for (int n = 0; n < 2; ++n) _Pragma("unroll") for (int k = 0; k < 2; ++k) \
;         acc[ai][bj][m][n] = __builtin_amdgcn_mfma_f32_16x16x32_bf16(Bt[n][k], At[m][k], acc[ai][bj][m][n], 0, 0, 0); __builtin_amdgcn_s_setprio(0); } while (0)
; #define PG8_WAIT_L(n) asm volatile("s_waitcnt lgkmcnt(" #n ")" ::: "memory")
; #define PG8_BAR __builtin_amdgcn_s_barrier()
; #define PG8_SCHED __builtin_amdgcn_sched_barrier(0)
; template <class Epi, class Sched>
; __device__ __forceinline__ void gemm_phase(PG8_LAS unsigned char* lds, const Gemm g, const Sched& S, const Epi& E, int tid_in) {
;     ...
;             PG8_LDB(B0, 0, 0); PG8_SCHED; PG8_LDA(At, 0, 0); PG8_STAGE(PG8_SA(1, 1), a1 + hstep, voffA);
;             PG8_WAIT_L(8); PG8_BAR; PG8_WAIT_L(0); PG8_MMA(0, 0, At, B0); PG8_BAR; PG8_SCHED;
;             PG8_LDB(B1, 0, 1); PG8_STAGE(PG8_SB(0, 0), b2, voffB);
;             PG8_BAR; PG8_WAIT_L(0); PG8_MMA(0, 1, At, B1); PG8_BAR;
;             PG8_LDA(At, 0, 1); PG8_STAGE(PG8_SA(0, 0), a2, voffA);
;             PG8_BAR; PG8_WAIT_L(0); PG8_MMA(1, 0, At, B0); PG8_BAR; PG8_SCHED;
.LBB0_350:
	s_add_u32 s20, s18, 0xfff80080
	s_addc_u32 s21, s19, -1
	s_add_i32 s46, 0, 0x10000
	v_add_u32_e32 v146, s46, v171
	ds_read_b128 v[134:137], v146
	ds_read_b128 v[138:141], v146 offset:1024
	ds_read_b128 v[142:145], v146 offset:2048
	ds_read_b128 v[146:149], v146 offset:3072
	s_cmp_eq_u32 s45, 28
	s_cselect_b32 s23, s11, s21
	s_cselect_b32 s22, s41, s20
	s_cselect_b32 s21, s9, s44
	s_cselect_b32 s20, s42, s43
	v_lshl_add_u64 v[186:187], s[18:19], 0, v[130:131]
	s_add_i32 m0, s17, 0xc000
	ds_read_b128 v[150:153], v173
	ds_read_b128 v[154:157], v173 offset:1024
	ds_read_b128 v[158:161], v173 offset:2048
	ds_read_b128 v[162:165], v173 offset:3072
	ds_read_b128 v[166:169], v173 offset:4096
	ds_read_b128 v[174:177], v173 offset:5120
	ds_read_b128 v[178:181], v173 offset:6144
	ds_read_b128 v[182:185], v173 offset:7168
	global_load_lds_dwordx4 v[186:187], off
	v_lshl_add_u64 v[186:187], s[18:19], 0, v[132:133]
	s_add_i32 m0, s17, 0xe000
	s_nop 0
	global_load_lds_dwordx4 v[186:187], off
	s_waitcnt lgkmcnt(8)
	s_barrier
	s_waitcnt lgkmcnt(0)
	s_setprio 1
	s_waitcnt lgkmcnt(0)
	v_mfma_f32_16x16x32_bf16 v[124:127], v[134:137], v[150:153], v[124:127]
	v_mfma_f32_16x16x32_bf16 v[120:123], v[142:145], v[150:153], v[120:123]
	v_mfma_f32_16x16x32_bf16 v[108:111], v[134:137], v[158:161], v[108:111]
	v_mfma_f32_16x16x32_bf16 v[104:107], v[142:145], v[158:161], v[104:107]
	v_mfma_f32_16x16x32_bf16 v[96:99], v[134:137], v[166:169], v[96:99]
	v_mfma_f32_16x16x32_bf16 v[88:91], v[142:145], v[166:169], v[88:91]
	v_mfma_f32_16x16x32_bf16 v[80:83], v[134:137], v[178:181], v[80:83]
	v_mfma_f32_16x16x32_bf16 v[72:75], v[142:145], v[178:181], v[72:75]
	v_mfma_f32_16x16x32_bf16 v[124:127], v[138:141], v[154:157], v[124:127]
	v_mfma_f32_16x16x32_bf16 v[120:123], v[146:149], v[154:157], v[120:123]
	v_mfma_f32_16x16x32_bf16 v[108:111], v[138:141], v[162:165], v[108:111]
	v_mfma_f32_16x16x32_bf16 v[104:107], v[146:149], v[162:165], v[104:107]
	v_mfma_f32_16x16x32_bf16 v[96:99], v[138:141], v[174:177], v[96:99]
	v_mfma_f32_16x16x32_bf16 v[88:91], v[146:149], v[174:177], v[88:91]
	v_mfma_f32_16x16x32_bf16 v[80:83], v[138:141], v[182:185], v[80:83]
	v_mfma_f32_16x16x32_bf16 v[72:75], v[146:149], v[182:185], v[72:75]
	s_setprio 0
	s_barrier
	s_add_i32 s50, 0, 0x14000
	v_add_u32_e32 v190, s50, v171
	s_add_i32 s46, s46, s30
	ds_read_b128 v[186:189], v190
	ds_read_b128 v[194:197], v190 offset:1024
	ds_read_b128 v[200:203], v190 offset:2048
	ds_read_b128 v[204:207], v190 offset:3072
	v_lshl_add_u64 v[190:191], s[20:21], 0, v[192:193]
	s_mov_b32 m0, s46
	v_lshl_add_u64 v[208:209], s[20:21], 0, v[128:129]
	global_load_lds_dwordx4 v[190:191], off
	s_add_i32 m0, s46, 0x2000
	s_nop 0
	global_load_lds_dwordx4 v[208:209], off
	s_barrier
	s_waitcnt lgkmcnt(0)
	s_setprio 1
	s_waitcnt lgkmcnt(0)
	v_mfma_f32_16x16x32_bf16 v[116:119], v[186:189], v[150:153], v[116:119]
	v_mfma_f32_16x16x32_bf16 v[112:115], v[200:203], v[150:153], v[112:115]
	v_mfma_f32_16x16x32_bf16 v[100:103], v[186:189], v[158:161], v[100:103]
	v_mfma_f32_16x16x32_bf16 v[92:95], v[200:203], v[158:161], v[92:95]
	v_mfma_f32_16x16x32_bf16 v[84:87], v[186:189], v[166:169], v[84:87]
	v_mfma_f32_16x16x32_bf16 v[76:79], v[200:203], v[166:169], v[76:79]
	v_mfma_f32_16x16x32_bf16 v[68:71], v[186:189], v[178:181], v[68:71]
	v_mfma_f32_16x16x32_bf16 v[64:67], v[200:203], v[178:181], v[64:67]
	v_mfma_f32_16x16x32_bf16 v[116:119], v[194:197], v[154:157], v[116:119]
	v_mfma_f32_16x16x32_bf16 v[112:115], v[204:207], v[154:157], v[112:115]
	v_mfma_f32_16x16x32_bf16 v[100:103], v[194:197], v[162:165], v[100:103]
	v_mfma_f32_16x16x32_bf16 v[92:95], v[204:207], v[162:165], v[92:95]
	v_mfma_f32_16x16x32_bf16 v[84:87], v[194:197], v[174:177], v[84:87]
	v_mfma_f32_16x16x32_bf16 v[76:79], v[204:207], v[174:177], v[76:79]
	v_mfma_f32_16x16x32_bf16 v[68:71], v[194:197], v[182:185], v[68:71]
	v_mfma_f32_16x16x32_bf16 v[64:67], v[204:207], v[182:185], v[64:67]
	s_setprio 0
	s_mov_b32 m0, s17
	v_lshl_add_u64 v[210:211], s[22:23], 0, v[192:193]
	s_barrier
	ds_read_b128 v[150:153], v173 offset:16384
	ds_read_b128 v[154:157], v173 offset:17408
	ds_read_b128 v[158:161], v173 offset:18432
	ds_read_b128 v[162:165], v173 offset:19456
	ds_read_b128 v[166:169], v173 offset:20480
	ds_read_b128 v[174:177], v173 offset:21504
	ds_read_b128 v[178:181], v173 offset:22528
	ds_read_b128 v[182:185], v173 offset:23552
	global_load_lds_dwordx4 v[210:211], off
	v_lshl_add_u64 v[212:213], s[22:23], 0, v[128:129]
	s_mov_b32 m0, s31
	s_nop 0
	global_load_lds_dwordx4 v[212:213], off
	s_barrier
	s_waitcnt lgkmcnt(0)
	s_setprio 1
	s_waitcnt lgkmcnt(0)
	v_mfma_f32_16x16x32_bf16 v[60:63], v[134:137], v[150:153], v[60:63]
	v_mfma_f32_16x16x32_bf16 v[56:59], v[142:145], v[150:153], v[56:59]
	v_mfma_f32_16x16x32_bf16 v[48:51], v[134:137], v[158:161], v[48:51]
	v_mfma_f32_16x16x32_bf16 v[40:43], v[142:145], v[158:161], v[40:43]
	v_mfma_f32_16x16x32_bf16 v[32:35], v[134:137], v[166:169], v[32:35]
	v_mfma_f32_16x16x32_bf16 v[24:27], v[142:145], v[166:169], v[24:27]
	v_mfma_f32_16x16x32_bf16 v[16:19], v[134:137], v[178:181], v[16:19]
	v_mfma_f32_16x16x32_bf16 v[8:11], v[142:145], v[178:181], v[8:11]
	v_mfma_f32_16x16x32_bf16 v[60:63], v[138:141], v[154:157], v[60:63]
	v_mfma_f32_16x16x32_bf16 v[56:59], v[146:149], v[154:157], v[56:59]
	v_mfma_f32_16x16x32_bf16 v[48:51], v[138:141], v[162:165], v[48:51]
	v_mfma_f32_16x16x32_bf16 v[40:43], v[146:149], v[162:165], v[40:43]
	v_mfma_f32_16x16x32_bf16 v[32:35], v[138:141], v[174:177], v[32:35]
	v_mfma_f32_16x16x32_bf16 v[24:27], v[146:149], v[174:177], v[24:27]
	v_mfma_f32_16x16x32_bf16 v[16:19], v[138:141], v[182:185], v[16:19]
	v_mfma_f32_16x16x32_bf16 v[8:11], v[146:149], v[182:185], v[8:11]
	s_setprio 0
	s_barrier
; #define PG8_STAGE(bufoff, gbase, voff) do { _Pragma("unroll") for (int _i = 0; _i < 2; ++_i) \
;         __builtin_amdgcn_global_load_lds((const unsigned*)((const char*)(gbase) + (voff)[_i]), (PG8_LAS unsigned*)(lds + (bufoff) + ldsw + _i * 8192), 16, 0, 0); } while (0)
; #define PG8_LDA(dst, b, h) do { _Pragma("unroll") for (int m = 0; m < 4; ++m) _Pragma("unroll") for (int k = 0; k < 2; ++k) dst[m][k] = *(const PG8_LAS bf16x8*)(lds + PG8_SA(b, h) + aoff + m * 2048 + k * 1024); } while (0)
; #define PG8_LDB(dst, b, h) do { _Pragma("unroll") for (int n = 0; n < 2; ++n) _Pragma("unroll") for (int k = 0; k < 2; ++k) dst[n][k] = *(const PG8_LAS bf16x8*)(lds + PG8_SB(b, h) + boff + n * 2048 + k * 1024); } while (0)
; #define PG8_MMA(ai, bj, At, Bt) do { __builtin_amdgcn_s_setprio(1); _Pragma("unroll") for (int m = 0; m < 4; ++m) _Pragma("unroll") for (int n = 0; n < 2; ++n) _Pragma("unroll") for (int k = 0; k < 2; ++k) \
;         acc[ai][bj][m][n] = __builtin_amdgcn_mfma_f32_16x16x32_bf16(Bt[n][k], At[m][k], acc[ai][bj][m][n], 0, 0, 0); __builtin_amdgcn_s_setprio(0); } while (0)
; #define PG8_WAIT_V(n) asm volatile("s_waitcnt vmcnt(" #n ")" ::: "memory")
; #define PG8_WAIT_L(n) asm volatile("s_waitcnt lgkmcnt(" #n ")" ::: "memory")
; #define PG8_BAR __builtin_amdgcn_s_barrier()
; #define PG8_SCHED __builtin_amdgcn_sched_barrier(0)
; template <class Epi, class Sched>
; __device__ __forceinline__ void gemm_phase(PG8_LAS unsigned char* lds, const Gemm g, const Sched& S, const Epi& E, int tid_in) {
;     ...
;             PG8_STAGE(PG8_SB(0, 1), b2 + hstep, voffB);
;             PG8_WAIT_V(6); PG8_BAR; PG8_MMA(1, 1, At, B1); PG8_BAR;
;             PG8_LDB(B0, 1, 0); PG8_SCHED; PG8_LDA(At, 1, 0); PG8_STAGE(PG8_SA(0, 1), a2 + hstep, voffA);
;             PG8_WAIT_L(8); PG8_BAR; PG8_WAIT_L(0); PG8_MMA(0, 0, At, B0); PG8_BAR; PG8_SCHED;
;             PG8_LDB(B1, 1, 1); PG8_STAGE(PG8_SB(1, 0), b3, voffB);
;             PG8_BAR; PG8_WAIT_L(0); PG8_MMA(0, 1, At, B1); PG8_BAR;
;             PG8_LDA(At, 1, 1); PG8_STAGE(PG8_SA(1, 0), a3, voffA);
;             PG8_BAR; PG8_WAIT_L(0); PG8_MMA(1, 0, At, B0); PG8_BAR; PG8_SCHED;
	s_add_u32 s48, s20, 0x80000
	s_addc_u32 s49, s21, 0
	s_add_i32 s46, s50, s30
	v_lshl_add_u64 v[134:135], s[48:49], 0, v[192:193]
	s_mov_b32 m0, s46
	s_nop 0
	global_load_lds_dwordx4 v[134:135], off
	v_lshl_add_u64 v[134:135], s[48:49], 0, v[128:129]
	s_add_i32 m0, s46, 0x2000
	s_nop 0
	global_load_lds_dwordx4 v[134:135], off
	s_waitcnt vmcnt(6)
	s_barrier
	s_setprio 1
	v_mfma_f32_16x16x32_bf16 v[52:55], v[186:189], v[150:153], v[52:55]
	v_mfma_f32_16x16x32_bf16 v[44:47], v[200:203], v[150:153], v[44:47]
	v_mfma_f32_16x16x32_bf16 v[36:39], v[186:189], v[158:161], v[36:39]
	v_mfma_f32_16x16x32_bf16 v[28:31], v[200:203], v[158:161], v[28:31]
	v_mfma_f32_16x16x32_bf16 v[20:23], v[186:189], v[166:169], v[20:23]
	v_mfma_f32_16x16x32_bf16 v[12:15], v[200:203], v[166:169], v[12:15]
	v_mfma_f32_16x16x32_bf16 v[4:7], v[186:189], v[178:181], v[4:7]
	v_mfma_f32_16x16x32_bf16 v[0:3], v[200:203], v[178:181], v[0:3]
	v_mfma_f32_16x16x32_bf16 v[52:55], v[194:197], v[154:157], v[52:55]
	v_mfma_f32_16x16x32_bf16 v[44:47], v[204:207], v[154:157], v[44:47]
	v_mfma_f32_16x16x32_bf16 v[36:39], v[194:197], v[162:165], v[36:39]
	v_mfma_f32_16x16x32_bf16 v[28:31], v[204:207], v[162:165], v[28:31]
	v_mfma_f32_16x16x32_bf16 v[20:23], v[194:197], v[174:177], v[20:23]
	v_mfma_f32_16x16x32_bf16 v[12:15], v[204:207], v[174:177], v[12:15]
	v_mfma_f32_16x16x32_bf16 v[4:7], v[194:197], v[182:185], v[4:7]
	v_mfma_f32_16x16x32_bf16 v[0:3], v[204:207], v[182:185], v[0:3]
	s_setprio 0
	s_add_i32 s46, 0, 0x18000
	v_add_u32_e32 v146, s46, v171
	s_barrier
	ds_read_b128 v[134:137], v146
	ds_read_b128 v[138:141], v146 offset:1024
	ds_read_b128 v[142:145], v146 offset:2048
	ds_read_b128 v[146:149], v146 offset:3072
	s_add_u32 s22, s22, 0x80000
	s_addc_u32 s23, s23, 0
	s_mov_b32 m0, s36
	v_lshl_add_u64 v[186:187], s[22:23], 0, v[192:193]
	ds_read_b128 v[150:153], v173 offset:32768
	ds_read_b128 v[154:157], v173 offset:33792
	ds_read_b128 v[158:161], v173 offset:34816
	ds_read_b128 v[162:165], v173 offset:35840
	ds_read_b128 v[166:169], v173 offset:36864
	ds_read_b128 v[174:177], v173 offset:37888
	ds_read_b128 v[178:181], v173 offset:38912
	ds_read_b128 v[182:185], v173 offset:39936
	global_load_lds_dwordx4 v[186:187], off
	v_lshl_add_u64 v[186:187], s[22:23], 0, v[128:129]
	s_mov_b32 m0, s37
	s_nop 0
	global_load_lds_dwordx4 v[186:187], off
	s_waitcnt lgkmcnt(8)
	s_barrier
	s_waitcnt lgkmcnt(0)
	s_setprio 1
	s_waitcnt lgkmcnt(0)
	v_mfma_f32_16x16x32_bf16 v[124:127], v[134:137], v[150:153], v[124:127]
	v_mfma_f32_16x16x32_bf16 v[120:123], v[142:145], v[150:153], v[120:123]
	v_mfma_f32_16x16x32_bf16 v[108:111], v[134:137], v[158:161], v[108:111]
	v_mfma_f32_16x16x32_bf16 v[104:107], v[142:145], v[158:161], v[104:107]
	v_mfma_f32_16x16x32_bf16 v[96:99], v[134:137], v[166:169], v[96:99]
	v_mfma_f32_16x16x32_bf16 v[88:91], v[142:145], v[166:169], v[88:91]
	v_mfma_f32_16x16x32_bf16 v[80:83], v[134:137], v[178:181], v[80:83]
	v_mfma_f32_16x16x32_bf16 v[72:75], v[142:145], v[178:181], v[72:75]
	v_mfma_f32_16x16x32_bf16 v[124:127], v[138:141], v[154:157], v[124:127]
	v_mfma_f32_16x16x32_bf16 v[120:123], v[146:149], v[154:157], v[120:123]
	v_mfma_f32_16x16x32_bf16 v[108:111], v[138:141], v[162:165], v[108:111]
	v_mfma_f32_16x16x32_bf16 v[104:107], v[146:149], v[162:165], v[104:107]
	v_mfma_f32_16x16x32_bf16 v[96:99], v[138:141], v[174:177], v[96:99]
	v_mfma_f32_16x16x32_bf16 v[88:91], v[146:149], v[174:177], v[88:91]
	v_mfma_f32_16x16x32_bf16 v[80:83], v[138:141], v[182:185], v[80:83]
	v_mfma_f32_16x16x32_bf16 v[72:75], v[146:149], v[182:185], v[72:75]
	s_setprio 0
	s_barrier
	s_add_i32 s22, 0, 0x1c000
	s_add_i32 s23, s46, s30
	v_add_u32_e32 v199, s22, v171
	v_lshl_add_u64 v[190:191], v[190:191], 0, s[74:75]
	s_mov_b32 m0, s23
	ds_read_b128 v[186:189], v199
	ds_read_b128 v[194:197], v199 offset:1024
	ds_read_b128 v[200:203], v199 offset:2048
	ds_read_b128 v[204:207], v199 offset:3072
	global_load_lds_dwordx4 v[190:191], off
	v_lshl_add_u64 v[190:191], v[208:209], 0, s[74:75]
	s_add_i32 m0, s23, 0x2000
	s_nop 0
	global_load_lds_dwordx4 v[190:191], off
	s_barrier
	s_waitcnt lgkmcnt(0)
	s_setprio 1
	s_waitcnt lgkmcnt(0)
	v_mfma_f32_16x16x32_bf16 v[116:119], v[186:189], v[150:153], v[116:119]
	v_mfma_f32_16x16x32_bf16 v[112:115], v[200:203], v[150:153], v[112:115]
	v_mfma_f32_16x16x32_bf16 v[100:103], v[186:189], v[158:161], v[100:103]
	v_mfma_f32_16x16x32_bf16 v[92:95], v[200:203], v[158:161], v[92:95]
	v_mfma_f32_16x16x32_bf16 v[84:87], v[186:189], v[166:169], v[84:87]
	v_mfma_f32_16x16x32_bf16 v[76:79], v[200:203], v[166:169], v[76:79]
	v_mfma_f32_16x16x32_bf16 v[68:71], v[186:189], v[178:181], v[68:71]
	v_mfma_f32_16x16x32_bf16 v[64:67], v[200:203], v[178:181], v[64:67]
	v_mfma_f32_16x16x32_bf16 v[116:119], v[194:197], v[154:157], v[116:119]
	v_mfma_f32_16x16x32_bf16 v[112:115], v[204:207], v[154:157], v[112:115]
	v_mfma_f32_16x16x32_bf16 v[100:103], v[194:197], v[162:165], v[100:103]
	v_mfma_f32_16x16x32_bf16 v[92:95], v[204:207], v[162:165], v[92:95]
	v_mfma_f32_16x16x32_bf16 v[84:87], v[194:197], v[174:177], v[84:87]
	v_mfma_f32_16x16x32_bf16 v[76:79], v[204:207], v[174:177], v[76:79]
	v_mfma_f32_16x16x32_bf16 v[68:71], v[194:197], v[182:185], v[68:71]
	v_mfma_f32_16x16x32_bf16 v[64:67], v[204:207], v[182:185], v[64:67]
	s_setprio 0
	s_mov_b32 m0, s38
	v_lshl_add_u64 v[190:191], v[210:211], 0, s[74:75]
	s_barrier
	ds_read_b128 v[150:153], v173 offset:49152
	ds_read_b128 v[154:157], v173 offset:50176
	ds_read_b128 v[158:161], v173 offset:51200
	ds_read_b128 v[162:165], v173 offset:52224
	ds_read_b128 v[166:169], v173 offset:53248
	ds_read_b128 v[174:177], v173 offset:54272
	ds_read_b128 v[178:181], v173 offset:55296
	ds_read_b128 v[182:185], v173 offset:56320
	global_load_lds_dwordx4 v[190:191], off
	v_lshl_add_u64 v[190:191], v[212:213], 0, s[74:75]
	s_mov_b32 m0, s39
	s_nop 0
	global_load_lds_dwordx4 v[190:191], off
	s_barrier
; #define PG8_STAGE(bufoff, gbase, voff) do { _Pragma("unroll") for (int _i = 0; _i < 2; ++_i) \
;         __builtin_amdgcn_global_load_lds((const unsigned*)((const char*)(gbase) + (voff)[_i]), (PG8_LAS unsigned*)(lds + (bufoff) + ldsw + _i * 8192), 16, 0, 0); } while (0)
; #define PG8_MMA(ai, bj, At, Bt) do { __builtin_amdgcn_s_setprio(1); _Pragma("unroll") for (int m = 0; m < 4; ++m) _Pragma("unroll") for (int n = 0; n < 2; ++n) _Pragma("unroll") for (int k = 0; k < 2; ++k) \
;         acc[ai][bj][m][n] = __builtin_amdgcn_mfma_f32_16x16x32_bf16(Bt[n][k], At[m][k], acc[ai][bj][m][n], 0, 0, 0); __builtin_amdgcn_s_setprio(0); } while (0)
; #define PG8_WAIT_V(n) asm volatile("s_waitcnt vmcnt(" #n ")" ::: "memory")
; #define PG8_BAR __builtin_amdgcn_s_barrier()
; template <class Epi, class Sched>
; __device__ __forceinline__ void gemm_phase(PG8_LAS unsigned char* lds, const Gemm g, const Sched& S, const Epi& E, int tid_in) {
;     ...
;             PG8_STAGE(PG8_SB(1, 1), b3 + hstep, voffB);
;             PG8_WAIT_V(6); PG8_BAR; PG8_MMA(1, 1, At, B1); PG8_BAR;
;     __device__ __forceinline__ void operator()(f32x4 (&acc)[2][2][4][2], const Unit& u, int wr, int wc, int fr, int fq) const {
;         const int row0 = u.pm * 256 + wr * 64 + fr, col0 = u.pn * 256 + wc * 32 + 4 * fq;
; #pragma unroll
;         for (int ai = 0; ai < 2; ++ai) {
;             u32x2 gw[4][2][2];
; #pragma unroll
;             for (int m = 0; m < 4; ++m)
; #pragma unroll
;                 for (int bj = 0; bj < 2; ++bj)
; #pragma unroll
;                     for (int n = 0; n < 2; ++n) gw[m][bj][n] = *(const u32x2*)(gates + (size_t)(row0 + ai * 128 + m * 16) * 2048 + col0 + bj * 128 + n * 16);
	s_waitcnt lgkmcnt(0)
	s_setprio 1
	s_waitcnt lgkmcnt(0)
	v_mfma_f32_16x16x32_bf16 v[60:63], v[134:137], v[150:153], v[60:63]
	v_mfma_f32_16x16x32_bf16 v[56:59], v[142:145], v[150:153], v[56:59]
	v_mfma_f32_16x16x32_bf16 v[48:51], v[134:137], v[158:161], v[48:51]
	v_mfma_f32_16x16x32_bf16 v[40:43], v[142:145], v[158:161], v[40:43]
	v_mfma_f32_16x16x32_bf16 v[32:35], v[134:137], v[166:169], v[32:35]
	v_mfma_f32_16x16x32_bf16 v[24:27], v[142:145], v[166:169], v[24:27]
	v_mfma_f32_16x16x32_bf16 v[16:19], v[134:137], v[178:181], v[16:19]
	v_mfma_f32_16x16x32_bf16 v[8:11], v[142:145], v[178:181], v[8:11]
	v_mfma_f32_16x16x32_bf16 v[60:63], v[138:141], v[154:157], v[60:63]
	v_mfma_f32_16x16x32_bf16 v[56:59], v[146:149], v[154:157], v[56:59]
	v_mfma_f32_16x16x32_bf16 v[48:51], v[138:141], v[162:165], v[48:51]
	v_mfma_f32_16x16x32_bf16 v[40:43], v[146:149], v[162:165], v[40:43]
	v_mfma_f32_16x16x32_bf16 v[32:35], v[138:141], v[174:177], v[32:35]
	v_mfma_f32_16x16x32_bf16 v[24:27], v[146:149], v[174:177], v[24:27]
	v_mfma_f32_16x16x32_bf16 v[16:19], v[138:141], v[182:185], v[16:19]
	v_mfma_f32_16x16x32_bf16 v[8:11], v[146:149], v[182:185], v[8:11]
	s_setprio 0
	s_barrier
	s_add_u32 s20, s20, 0x80080
	s_addc_u32 s21, s21, 0
	s_add_i32 s22, s22, s30
	v_lshl_add_u64 v[134:135], s[20:21], 0, v[192:193]
	s_mov_b32 m0, s22
	s_nop 0
	global_load_lds_dwordx4 v[134:135], off
	v_lshl_add_u64 v[134:135], s[20:21], 0, v[128:129]
	s_add_i32 m0, s22, 0x2000
	s_nop 0
	global_load_lds_dwordx4 v[134:135], off
	s_waitcnt vmcnt(6)
	s_barrier
	s_setprio 1
	v_mfma_f32_16x16x32_bf16 v[52:55], v[186:189], v[150:153], v[52:55]
	v_mfma_f32_16x16x32_bf16 v[44:47], v[200:203], v[150:153], v[44:47]
	v_mfma_f32_16x16x32_bf16 v[36:39], v[186:189], v[158:161], v[36:39]
	v_mfma_f32_16x16x32_bf16 v[28:31], v[200:203], v[158:161], v[28:31]
	v_mfma_f32_16x16x32_bf16 v[20:23], v[186:189], v[166:169], v[20:23]
	v_mfma_f32_16x16x32_bf16 v[12:15], v[200:203], v[166:169], v[12:15]
	v_mfma_f32_16x16x32_bf16 v[4:7], v[186:189], v[178:181], v[4:7]
	v_mfma_f32_16x16x32_bf16 v[0:3], v[200:203], v[178:181], v[0:3]
	v_mfma_f32_16x16x32_bf16 v[52:55], v[194:197], v[154:157], v[52:55]
	v_mfma_f32_16x16x32_bf16 v[44:47], v[204:207], v[154:157], v[44:47]
	v_mfma_f32_16x16x32_bf16 v[36:39], v[194:197], v[162:165], v[36:39]
	v_mfma_f32_16x16x32_bf16 v[28:31], v[204:207], v[162:165], v[28:31]
	v_mfma_f32_16x16x32_bf16 v[20:23], v[194:197], v[174:177], v[20:23]
	v_mfma_f32_16x16x32_bf16 v[12:15], v[204:207], v[174:177], v[12:15]
	v_mfma_f32_16x16x32_bf16 v[4:7], v[194:197], v[182:185], v[4:7]
	v_mfma_f32_16x16x32_bf16 v[0:3], v[204:207], v[182:185], v[0:3]
	s_setprio 0
	s_add_i32 s45, s45, 2
	s_add_u32 s18, s18, 0x100
	s_addc_u32 s19, s19, 0
	s_add_u32 s43, s43, 0x100
	s_addc_u32 s44, s44, 0
	s_cmp_gt_u32 s45, 29
	s_barrier
	s_cbranch_scc0 .LBB0_350
	v_lshl_or_b32 v134, s33, 8, v172
	v_lshl_add_u32 v136, s16, 8, v170
	v_ashrrev_i32_e32 v135, 31, v134
	v_lshlrev_b64 v[134:135], 1, v[134:135]
	v_ashrrev_i32_e32 v137, 31, v136
	v_lshl_add_u64 v[138:139], s[0:1], 0, v[134:135]
	v_lshlrev_b64 v[140:141], 12, v[136:137]
	v_lshl_add_u64 v[140:141], v[138:139], 0, v[140:141]
	global_load_dwordx2 v[174:175], v[140:141], off
	global_load_dwordx2 v[176:177], v[140:141], off offset:32
	global_load_dwordx2 v[178:179], v[140:141], off offset:256
	global_load_dwordx2 v[180:181], v[140:141], off offset:288
	v_or_b32_e32 v166, 16, v136
	v_ashrrev_i32_e32 v167, 31, v166
	v_lshlrev_b64 v[140:141], 12, v[166:167]
	v_lshl_add_u64 v[140:141], v[138:139], 0, v[140:141]
	global_load_dwordx2 v[168:169], v[140:141], off
	global_load_dwordx2 v[164:165], v[140:141], off offset:32
	global_load_dwordx2 v[162:163], v[140:141], off offset:256
	global_load_dwordx2 v[160:161], v[140:141], off offset:288
	v_or_b32_e32 v156, 32, v136
	v_ashrrev_i32_e32 v157, 31, v156
	v_lshlrev_b64 v[140:141], 12, v[156:157]
	v_lshl_add_u64 v[140:141], v[138:139], 0, v[140:141]
	global_load_dwordx2 v[158:159], v[140:141], off
	global_load_dwordx2 v[154:155], v[140:141], off offset:32
	global_load_dwordx2 v[152:153], v[140:141], off offset:256
	global_load_dwordx2 v[146:147], v[140:141], off offset:288
	v_or_b32_e32 v148, 48, v136
	v_ashrrev_i32_e32 v149, 31, v148
	v_lshlrev_b64 v[140:141], 12, v[148:149]
	v_lshl_add_u64 v[140:141], v[138:139], 0, v[140:141]
	global_load_dwordx2 v[150:151], v[140:141], off
	global_load_dwordx2 v[144:145], v[140:141], off offset:32
	global_load_dwordx2 v[142:143], v[140:141], off offset:256
	s_nop 0
	global_load_dwordx2 v[140:141], v[140:141], off offset:288
	v_lshlrev_b64 v[182:183], 11, v[136:137]
	s_and_b64 vcc, exec, s[2:3]
	s_mov_b32 s33, s8
	s_mov_b32 s16, s10
	s_mov_b64 s[20:21], s[14:15]
	s_mov_b64 s[18:19], s[12:13]
	s_waitcnt vmcnt(0)
; __device__ __forceinline__ unsigned cvt_pk_bf16(float lo, float hi) { unsigned r; asm volatile("s_nop 0\n\tv_cvt_pk_bf16_f32 %0, %1, %2\n\ts_nop 1" : "=v"(r) : "v"(lo), "v"(hi)); return r; }
; __device__ __forceinline__ float bflo(unsigned w) { return __uint_as_float(w << 16); }
; __device__ __forceinline__ float bfhi(unsigned w) { return __uint_as_float(w & 0xffff0000u); }
;     __device__ __forceinline__ void operator()(f32x4 (&acc)[2][2][4][2], const Unit& u, int wr, int wc, int fr, int fq) const {
;     ...
;             for (int m = 0; m < 4; ++m) { const size_t row = row0 + ai * 128 + m * 16;
; #pragma unroll
;                 for (int bj = 0; bj < 2; ++bj)
; #pragma unroll
;                     for (int n = 0; n < 2; ++n) { const int col = col0 + bj * 128 + n * 16; const u32x2 g2 = gw[m][bj][n];
;                         const f32x4 gv = (f32x4){bflo(g2.x), bfhi(g2.x), bflo(g2.y), bfhi(g2.y)};
;                         const f32x4 o = gv * acc[ai][bj][m][n]; u32x2 w; w.x = cvt_pk_bf16(o[0], o[1]); w.y = cvt_pk_bf16(o[2], o[3]); *(u32x2*)(tmp + row * 1024 + col) = w; } }
	v_lshlrev_b32_e32 v184, 16, v174
	v_and_b32_e32 v185, 0xffff0000, v174
	v_lshlrev_b32_e32 v174, 16, v175
	v_and_b32_e32 v175, 0xffff0000, v175
	v_pk_mul_f32 v[126:127], v[126:127], v[174:175]
	v_pk_mul_f32 v[124:125], v[124:125], v[184:185]
	v_lshlrev_b32_e32 v174, 16, v177
	v_cvt_pk_bf16_f32 v124, v124, v125
	v_cvt_pk_bf16_f32 v125, v126, v127
	v_lshl_add_u64 v[126:127], s[4:5], 0, v[182:183]
	v_lshl_add_u64 v[126:127], v[126:127], 0, v[134:135]
	global_store_dwordx2 v[126:127], v[124:125], off
	v_lshlrev_b32_e32 v124, 16, v176
	v_and_b32_e32 v125, 0xffff0000, v176
	v_and_b32_e32 v175, 0xffff0000, v177
	v_pk_mul_f32 v[120:121], v[120:121], v[124:125]
	v_pk_mul_f32 v[122:123], v[122:123], v[174:175]
	v_cvt_pk_bf16_f32 v120, v120, v121
	s_nop 0
	v_cvt_pk_bf16_f32 v121, v122, v123
	global_store_dwordx2 v[126:127], v[120:121], off offset:32
	v_lshlrev_b32_e32 v120, 16, v178
	v_and_b32_e32 v121, 0xffff0000, v178
	v_lshlrev_b32_e32 v122, 16, v179
	v_and_b32_e32 v123, 0xffff0000, v179
	v_pk_mul_f32 v[116:117], v[116:117], v[120:121]
	v_pk_mul_f32 v[118:119], v[118:119], v[122:123]
	v_cvt_pk_bf16_f32 v116, v116, v117
	s_nop 0
	v_cvt_pk_bf16_f32 v117, v118, v119
	global_store_dwordx2 v[126:127], v[116:117], off offset:256
	v_lshlrev_b32_e32 v116, 16, v180
	v_and_b32_e32 v117, 0xffff0000, v180
	v_lshlrev_b32_e32 v118, 16, v181
	v_and_b32_e32 v119, 0xffff0000, v181
	v_pk_mul_f32 v[114:115], v[114:115], v[118:119]
	v_pk_mul_f32 v[112:113], v[112:113], v[116:117]
	v_lshlrev_b32_e32 v116, 16, v169
	v_cvt_pk_bf16_f32 v112, v112, v113
	v_cvt_pk_bf16_f32 v113, v114, v115
	v_lshlrev_b32_e32 v114, 16, v168
	v_and_b32_e32 v115, 0xffff0000, v168
	v_and_b32_e32 v117, 0xffff0000, v169
	global_store_dwordx2 v[126:127], v[112:113], off offset:288
	v_lshlrev_b64 v[112:113], 11, v[166:167]
	v_pk_mul_f32 v[110:111], v[110:111], v[116:117]
	v_pk_mul_f32 v[108:109], v[108:109], v[114:115]
	s_nop 0
	v_cvt_pk_bf16_f32 v108, v108, v109
	v_cvt_pk_bf16_f32 v109, v110, v111
	v_lshl_add_u64 v[110:111], s[4:5], 0, v[112:113]
	v_lshl_add_u64 v[110:111], v[110:111], 0, v[134:135]
	global_store_dwordx2 v[110:111], v[108:109], off
	v_lshlrev_b32_e32 v108, 16, v164
	v_and_b32_e32 v109, 0xffff0000, v164
	v_lshlrev_b32_e32 v112, 16, v165
	v_and_b32_e32 v113, 0xffff0000, v165
	v_pk_mul_f32 v[104:105], v[104:105], v[108:109]
	v_pk_mul_f32 v[106:107], v[106:107], v[112:113]
	v_cvt_pk_bf16_f32 v104, v104, v105
	s_nop 0
	v_cvt_pk_bf16_f32 v105, v106, v107
	global_store_dwordx2 v[110:111], v[104:105], off offset:32
	v_lshlrev_b32_e32 v104, 16, v162
	v_and_b32_e32 v105, 0xffff0000, v162
	v_lshlrev_b32_e32 v106, 16, v163
	v_and_b32_e32 v107, 0xffff0000, v163
	v_pk_mul_f32 v[100:101], v[100:101], v[104:105]
	v_pk_mul_f32 v[102:103], v[102:103], v[106:107]
	v_cvt_pk_bf16_f32 v100, v100, v101
	s_nop 0
	v_cvt_pk_bf16_f32 v101, v102, v103
	global_store_dwordx2 v[110:111], v[100:101], off offset:256
	v_lshlrev_b32_e32 v100, 16, v160
	v_and_b32_e32 v101, 0xffff0000, v160
	v_lshlrev_b32_e32 v102, 16, v161
	v_and_b32_e32 v103, 0xffff0000, v161
	v_pk_mul_f32 v[92:93], v[92:93], v[100:101]
	v_pk_mul_f32 v[94:95], v[94:95], v[102:103]
	v_cvt_pk_bf16_f32 v92, v92, v93
	v_lshlrev_b32_e32 v100, 16, v159
	v_cvt_pk_bf16_f32 v93, v94, v95
	global_store_dwordx2 v[110:111], v[92:93], off offset:288
	v_lshlrev_b64 v[92:93], 11, v[156:157]
	v_lshlrev_b32_e32 v94, 16, v158
	v_and_b32_e32 v95, 0xffff0000, v158
	v_and_b32_e32 v101, 0xffff0000, v159
	v_pk_mul_f32 v[94:95], v[96:97], v[94:95]
	v_lshl_add_u64 v[92:93], s[4:5], 0, v[92:93]
	v_pk_mul_f32 v[98:99], v[98:99], v[100:101]
	v_cvt_pk_bf16_f32 v94, v94, v95
	v_lshl_add_u64 v[92:93], v[92:93], 0, v[134:135]
	v_cvt_pk_bf16_f32 v95, v98, v99
	global_store_dwordx2 v[92:93], v[94:95], off
	v_lshlrev_b32_e32 v94, 16, v154
	v_and_b32_e32 v95, 0xffff0000, v154
	v_lshlrev_b32_e32 v96, 16, v155
	v_and_b32_e32 v97, 0xffff0000, v155
	v_pk_mul_f32 v[88:89], v[88:89], v[94:95]
	v_pk_mul_f32 v[90:91], v[90:91], v[96:97]
	v_cvt_pk_bf16_f32 v88, v88, v89
	v_add_u32_e32 v94, 0xa0, v136
	v_cvt_pk_bf16_f32 v89, v90, v91
	global_store_dwordx2 v[92:93], v[88:89], off offset:32
	v_lshlrev_b32_e32 v88, 16, v152
	v_and_b32_e32 v89, 0xffff0000, v152
	v_lshlrev_b32_e32 v90, 16, v153
	v_and_b32_e32 v91, 0xffff0000, v153
	v_pk_mul_f32 v[84:85], v[84:85], v[88:89]
	v_pk_mul_f32 v[86:87], v[86:87], v[90:91]
	v_cvt_pk_bf16_f32 v84, v84, v85
	v_ashrrev_i32_e32 v95, 31, v94
	v_cvt_pk_bf16_f32 v85, v86, v87
	global_store_dwordx2 v[92:93], v[84:85], off offset:256
	v_lshlrev_b32_e32 v84, 16, v146
	v_and_b32_e32 v85, 0xffff0000, v146
	v_lshlrev_b32_e32 v86, 16, v147
	v_and_b32_e32 v87, 0xffff0000, v147
	v_pk_mul_f32 v[76:77], v[76:77], v[84:85]
	v_pk_mul_f32 v[78:79], v[78:79], v[86:87]
	v_cvt_pk_bf16_f32 v76, v76, v77
	v_lshlrev_b32_e32 v84, 16, v151
	v_cvt_pk_bf16_f32 v77, v78, v79
	global_store_dwordx2 v[92:93], v[76:77], off offset:288
	v_lshlrev_b64 v[76:77], 11, v[148:149]
	v_lshlrev_b32_e32 v78, 16, v150
	v_and_b32_e32 v79, 0xffff0000, v150
	v_and_b32_e32 v85, 0xffff0000, v151
	v_pk_mul_f32 v[78:79], v[80:81], v[78:79]
	v_lshl_add_u64 v[76:77], s[4:5], 0, v[76:77]
	v_pk_mul_f32 v[82:83], v[82:83], v[84:85]
	v_cvt_pk_bf16_f32 v78, v78, v79
	v_lshl_add_u64 v[76:77], v[76:77], 0, v[134:135]
	v_cvt_pk_bf16_f32 v79, v82, v83
	global_store_dwordx2 v[76:77], v[78:79], off
	v_lshlrev_b32_e32 v78, 16, v144
	v_and_b32_e32 v79, 0xffff0000, v144
	v_lshlrev_b32_e32 v80, 16, v145
	v_and_b32_e32 v81, 0xffff0000, v145
	v_pk_mul_f32 v[72:73], v[72:73], v[78:79]
	v_pk_mul_f32 v[74:75], v[74:75], v[80:81]
	v_cvt_pk_bf16_f32 v72, v72, v73
	v_add_u32_e32 v84, 0x90, v136
	v_cvt_pk_bf16_f32 v73, v74, v75
; __device__ __forceinline__ unsigned cvt_pk_bf16(float lo, float hi) { unsigned r; asm volatile("s_nop 0\n\tv_cvt_pk_bf16_f32 %0, %1, %2\n\ts_nop 1" : "=v"(r) : "v"(lo), "v"(hi)); return r; }
; __device__ __forceinline__ float bflo(unsigned w) { return __uint_as_float(w << 16); }
; __device__ __forceinline__ float bfhi(unsigned w) { return __uint_as_float(w & 0xffff0000u); }
;     __device__ __forceinline__ void operator()(f32x4 (&acc)[2][2][4][2], const Unit& u, int wr, int wc, int fr, int fq) const {
;     ...
;             u32x2 gw[4][2][2];
; #pragma unroll
;             for (int m = 0; m < 4; ++m)
; #pragma unroll
;                 for (int bj = 0; bj < 2; ++bj)
; #pragma unroll
;                     for (int n = 0; n < 2; ++n) gw[m][bj][n] = *(const u32x2*)(gates + (size_t)(row0 + ai * 128 + m * 16) * 2048 + col0 + bj * 128 + n * 16);
; #pragma unroll
;             for (int m = 0; m < 4; ++m) { const size_t row = row0 + ai * 128 + m * 16;
; #pragma unroll
;                 for (int bj = 0; bj < 2; ++bj)
; #pragma unroll
;                     for (int n = 0; n < 2; ++n) { const int col = col0 + bj * 128 + n * 16; const u32x2 g2 = gw[m][bj][n];
;                         const f32x4 gv = (f32x4){bflo(g2.x), bfhi(g2.x), bflo(g2.y), bfhi(g2.y)};
;                         const f32x4 o = gv * acc[ai][bj][m][n]; u32x2 w; w.x = cvt_pk_bf16(o[0], o[1]); w.y = cvt_pk_bf16(o[2], o[3]); *(u32x2*)(tmp + row * 1024 + col) = w; } }
	global_store_dwordx2 v[76:77], v[72:73], off offset:32
	v_lshlrev_b32_e32 v72, 16, v142
	v_and_b32_e32 v73, 0xffff0000, v142
	v_lshlrev_b32_e32 v74, 16, v143
	v_and_b32_e32 v75, 0xffff0000, v143
	v_pk_mul_f32 v[68:69], v[68:69], v[72:73]
	v_pk_mul_f32 v[70:71], v[70:71], v[74:75]
	v_cvt_pk_bf16_f32 v68, v68, v69
	v_add_u32_e32 v74, 0x80, v136
	v_cvt_pk_bf16_f32 v69, v70, v71
	global_store_dwordx2 v[76:77], v[68:69], off offset:256
	v_lshlrev_b32_e32 v68, 16, v140
	v_and_b32_e32 v69, 0xffff0000, v140
	v_lshlrev_b32_e32 v70, 16, v141
	v_and_b32_e32 v71, 0xffff0000, v141
	v_pk_mul_f32 v[64:65], v[64:65], v[68:69]
	v_pk_mul_f32 v[66:67], v[66:67], v[70:71]
	v_cvt_pk_bf16_f32 v64, v64, v65
	v_ashrrev_i32_e32 v75, 31, v74
	v_cvt_pk_bf16_f32 v65, v66, v67
	global_store_dwordx2 v[76:77], v[64:65], off offset:288
	v_lshlrev_b64 v[64:65], 12, v[74:75]
	v_lshl_add_u64 v[64:65], v[138:139], 0, v[64:65]
	global_load_dwordx2 v[76:77], v[64:65], off
	global_load_dwordx2 v[78:79], v[64:65], off offset:32
	global_load_dwordx2 v[80:81], v[64:65], off offset:256
	global_load_dwordx2 v[82:83], v[64:65], off offset:288
	v_ashrrev_i32_e32 v85, 31, v84
	v_lshlrev_b64 v[64:65], 12, v[84:85]
	v_lshl_add_u64 v[64:65], v[138:139], 0, v[64:65]
	global_load_dwordx2 v[86:87], v[64:65], off
	global_load_dwordx2 v[88:89], v[64:65], off offset:32
	global_load_dwordx2 v[90:91], v[64:65], off offset:256
	global_load_dwordx2 v[92:93], v[64:65], off offset:288
	v_lshlrev_b64 v[64:65], 12, v[94:95]
	v_lshl_add_u64 v[64:65], v[138:139], 0, v[64:65]
	global_load_dwordx2 v[96:97], v[64:65], off
	global_load_dwordx2 v[98:99], v[64:65], off offset:32
	global_load_dwordx2 v[100:101], v[64:65], off offset:256
	global_load_dwordx2 v[102:103], v[64:65], off offset:288
	v_add_u32_e32 v70, 0xb0, v136
	v_ashrrev_i32_e32 v71, 31, v70
	v_lshlrev_b64 v[64:65], 12, v[70:71]
	v_lshl_add_u64 v[64:65], v[138:139], 0, v[64:65]
	global_load_dwordx2 v[72:73], v[64:65], off
	global_load_dwordx2 v[68:69], v[64:65], off offset:32
	global_load_dwordx2 v[66:67], v[64:65], off offset:256
	s_nop 0
	global_load_dwordx2 v[64:65], v[64:65], off offset:288
	v_lshlrev_b64 v[74:75], 11, v[74:75]
	s_waitcnt vmcnt(0)
; __device__ __forceinline__ unsigned cvt_pk_bf16(float lo, float hi) { unsigned r; asm volatile("s_nop 0\n\tv_cvt_pk_bf16_f32 %0, %1, %2\n\ts_nop 1" : "=v"(r) : "v"(lo), "v"(hi)); return r; }
; __device__ __forceinline__ float bflo(unsigned w) { return __uint_as_float(w << 16); }
; __device__ __forceinline__ float bfhi(unsigned w) { return __uint_as_float(w & 0xffff0000u); }
;     __device__ __forceinline__ void operator()(f32x4 (&acc)[2][2][4][2], const Unit& u, int wr, int wc, int fr, int fq) const {
;     ...
;             for (int m = 0; m < 4; ++m) { const size_t row = row0 + ai * 128 + m * 16;
; #pragma unroll
;                 for (int bj = 0; bj < 2; ++bj)
; #pragma unroll
;                     for (int n = 0; n < 2; ++n) { const int col = col0 + bj * 128 + n * 16; const u32x2 g2 = gw[m][bj][n];
;                         const f32x4 gv = (f32x4){bflo(g2.x), bfhi(g2.x), bflo(g2.y), bfhi(g2.y)};
;                         const f32x4 o = gv * acc[ai][bj][m][n]; u32x2 w; w.x = cvt_pk_bf16(o[0], o[1]); w.y = cvt_pk_bf16(o[2], o[3]); *(u32x2*)(tmp + row * 1024 + col) = w; } }
	v_lshlrev_b32_e32 v104, 16, v76
	v_and_b32_e32 v105, 0xffff0000, v76
	v_lshlrev_b32_e32 v76, 16, v77
	v_and_b32_e32 v77, 0xffff0000, v77
	v_pk_mul_f32 v[62:63], v[62:63], v[76:77]
	v_pk_mul_f32 v[60:61], v[60:61], v[104:105]
	s_nop 0
	v_cvt_pk_bf16_f32 v60, v60, v61
	v_cvt_pk_bf16_f32 v61, v62, v63
	v_lshl_add_u64 v[62:63], s[4:5], 0, v[74:75]
	v_lshl_add_u64 v[62:63], v[62:63], 0, v[134:135]
	global_store_dwordx2 v[62:63], v[60:61], off
	v_lshlrev_b32_e32 v60, 16, v78
	v_and_b32_e32 v61, 0xffff0000, v78
	v_lshlrev_b32_e32 v74, 16, v79
	v_and_b32_e32 v75, 0xffff0000, v79
	v_pk_mul_f32 v[56:57], v[56:57], v[60:61]
	v_pk_mul_f32 v[58:59], v[58:59], v[74:75]
	v_cvt_pk_bf16_f32 v56, v56, v57
	s_nop 0
	v_cvt_pk_bf16_f32 v57, v58, v59
	global_store_dwordx2 v[62:63], v[56:57], off offset:32
	v_lshlrev_b32_e32 v56, 16, v80
	v_and_b32_e32 v57, 0xffff0000, v80
	v_lshlrev_b32_e32 v58, 16, v81
	v_and_b32_e32 v59, 0xffff0000, v81
	v_pk_mul_f32 v[52:53], v[52:53], v[56:57]
	v_pk_mul_f32 v[54:55], v[54:55], v[58:59]
	v_cvt_pk_bf16_f32 v52, v52, v53
	s_nop 0
	v_cvt_pk_bf16_f32 v53, v54, v55
	global_store_dwordx2 v[62:63], v[52:53], off offset:256
	v_lshlrev_b32_e32 v52, 16, v82
	v_and_b32_e32 v53, 0xffff0000, v82
	v_lshlrev_b32_e32 v54, 16, v83
	v_and_b32_e32 v55, 0xffff0000, v83
	v_pk_mul_f32 v[44:45], v[44:45], v[52:53]
	v_pk_mul_f32 v[46:47], v[46:47], v[54:55]
	v_cvt_pk_bf16_f32 v44, v44, v45
	v_lshlrev_b32_e32 v52, 16, v87
	v_cvt_pk_bf16_f32 v45, v46, v47
	global_store_dwordx2 v[62:63], v[44:45], off offset:288
	v_lshlrev_b64 v[44:45], 11, v[84:85]
	v_lshlrev_b32_e32 v46, 16, v86
	v_and_b32_e32 v47, 0xffff0000, v86
	v_and_b32_e32 v53, 0xffff0000, v87
	v_pk_mul_f32 v[46:47], v[48:49], v[46:47]
	v_lshl_add_u64 v[44:45], s[4:5], 0, v[44:45]
	v_pk_mul_f32 v[50:51], v[50:51], v[52:53]
	v_cvt_pk_bf16_f32 v46, v46, v47
	v_lshl_add_u64 v[44:45], v[44:45], 0, v[134:135]
	v_cvt_pk_bf16_f32 v47, v50, v51
	global_store_dwordx2 v[44:45], v[46:47], off
	v_lshlrev_b32_e32 v46, 16, v88
	v_and_b32_e32 v47, 0xffff0000, v88
	v_lshlrev_b32_e32 v48, 16, v89
	v_and_b32_e32 v49, 0xffff0000, v89
	v_pk_mul_f32 v[40:41], v[40:41], v[46:47]
	v_pk_mul_f32 v[42:43], v[42:43], v[48:49]
	v_cvt_pk_bf16_f32 v40, v40, v41
	s_nop 0
	v_cvt_pk_bf16_f32 v41, v42, v43
	global_store_dwordx2 v[44:45], v[40:41], off offset:32
	v_lshlrev_b32_e32 v40, 16, v90
	v_and_b32_e32 v41, 0xffff0000, v90
	v_lshlrev_b32_e32 v42, 16, v91
	v_and_b32_e32 v43, 0xffff0000, v91
	v_pk_mul_f32 v[36:37], v[36:37], v[40:41]
	v_pk_mul_f32 v[38:39], v[38:39], v[42:43]
	v_cvt_pk_bf16_f32 v36, v36, v37
	s_nop 0
	v_cvt_pk_bf16_f32 v37, v38, v39
	global_store_dwordx2 v[44:45], v[36:37], off offset:256
	v_lshlrev_b32_e32 v36, 16, v92
	v_and_b32_e32 v37, 0xffff0000, v92
	v_lshlrev_b32_e32 v38, 16, v93
	v_and_b32_e32 v39, 0xffff0000, v93
	v_pk_mul_f32 v[28:29], v[28:29], v[36:37]
	v_pk_mul_f32 v[30:31], v[30:31], v[38:39]
	v_cvt_pk_bf16_f32 v28, v28, v29
	v_lshlrev_b32_e32 v36, 16, v97
	v_cvt_pk_bf16_f32 v29, v30, v31
	global_store_dwordx2 v[44:45], v[28:29], off offset:288
	v_lshlrev_b64 v[28:29], 11, v[94:95]
	v_lshlrev_b32_e32 v30, 16, v96
	v_and_b32_e32 v31, 0xffff0000, v96
	v_and_b32_e32 v37, 0xffff0000, v97
	v_pk_mul_f32 v[30:31], v[32:33], v[30:31]
	v_lshl_add_u64 v[28:29], s[4:5], 0, v[28:29]
	v_pk_mul_f32 v[34:35], v[34:35], v[36:37]
	v_cvt_pk_bf16_f32 v30, v30, v31
	v_lshl_add_u64 v[28:29], v[28:29], 0, v[134:135]
	v_cvt_pk_bf16_f32 v31, v34, v35
	global_store_dwordx2 v[28:29], v[30:31], off
	v_lshlrev_b32_e32 v30, 16, v98
	v_and_b32_e32 v31, 0xffff0000, v98
	v_lshlrev_b32_e32 v32, 16, v99
	v_and_b32_e32 v33, 0xffff0000, v99
	v_pk_mul_f32 v[24:25], v[24:25], v[30:31]
	v_pk_mul_f32 v[26:27], v[26:27], v[32:33]
	v_cvt_pk_bf16_f32 v24, v24, v25
	s_nop 0
	v_cvt_pk_bf16_f32 v25, v26, v27
	global_store_dwordx2 v[28:29], v[24:25], off offset:32
	v_lshlrev_b32_e32 v24, 16, v100
	v_and_b32_e32 v25, 0xffff0000, v100
	v_lshlrev_b32_e32 v26, 16, v101
	v_and_b32_e32 v27, 0xffff0000, v101
	v_pk_mul_f32 v[20:21], v[20:21], v[24:25]
	v_pk_mul_f32 v[22:23], v[22:23], v[26:27]
	v_cvt_pk_bf16_f32 v20, v20, v21
	s_nop 0
	v_cvt_pk_bf16_f32 v21, v22, v23
	global_store_dwordx2 v[28:29], v[20:21], off offset:256
	v_lshlrev_b32_e32 v20, 16, v102
	v_and_b32_e32 v21, 0xffff0000, v102
	v_lshlrev_b32_e32 v22, 16, v103
	v_and_b32_e32 v23, 0xffff0000, v103
	v_pk_mul_f32 v[12:13], v[12:13], v[20:21]
	v_pk_mul_f32 v[14:15], v[14:15], v[22:23]
	v_cvt_pk_bf16_f32 v12, v12, v13
	v_lshlrev_b32_e32 v20, 16, v73
	v_cvt_pk_bf16_f32 v13, v14, v15
	global_store_dwordx2 v[28:29], v[12:13], off offset:288
	v_lshlrev_b64 v[12:13], 11, v[70:71]
	v_lshlrev_b32_e32 v14, 16, v72
	v_and_b32_e32 v15, 0xffff0000, v72
	v_and_b32_e32 v21, 0xffff0000, v73
	v_pk_mul_f32 v[14:15], v[16:17], v[14:15]
	v_lshl_add_u64 v[12:13], s[4:5], 0, v[12:13]
	v_pk_mul_f32 v[18:19], v[18:19], v[20:21]
	v_cvt_pk_bf16_f32 v14, v14, v15
	v_lshl_add_u64 v[12:13], v[12:13], 0, v[134:135]
	v_cvt_pk_bf16_f32 v15, v18, v19
	global_store_dwordx2 v[12:13], v[14:15], off
	v_lshlrev_b32_e32 v14, 16, v68
	v_and_b32_e32 v15, 0xffff0000, v68
	v_lshlrev_b32_e32 v16, 16, v69
	v_and_b32_e32 v17, 0xffff0000, v69
	v_pk_mul_f32 v[8:9], v[8:9], v[14:15]
	v_pk_mul_f32 v[10:11], v[10:11], v[16:17]
	v_cvt_pk_bf16_f32 v8, v8, v9
	s_nop 0
	v_cvt_pk_bf16_f32 v9, v10, v11
	global_store_dwordx2 v[12:13], v[8:9], off offset:32
	v_lshlrev_b32_e32 v8, 16, v66
	v_and_b32_e32 v9, 0xffff0000, v66
	v_lshlrev_b32_e32 v10, 16, v67
	v_and_b32_e32 v11, 0xffff0000, v67
	v_pk_mul_f32 v[4:5], v[4:5], v[8:9]
	v_pk_mul_f32 v[6:7], v[6:7], v[10:11]
	v_cvt_pk_bf16_f32 v4, v4, v5
	s_nop 0
	v_cvt_pk_bf16_f32 v5, v6, v7
	global_store_dwordx2 v[12:13], v[4:5], off offset:256
	v_lshlrev_b32_e32 v4, 16, v64
	v_and_b32_e32 v5, 0xffff0000, v64
	v_lshlrev_b32_e32 v6, 16, v65
	v_and_b32_e32 v7, 0xffff0000, v65
	v_pk_mul_f32 v[0:1], v[0:1], v[4:5]
	v_pk_mul_f32 v[2:3], v[2:3], v[6:7]
	v_cvt_pk_bf16_f32 v0, v0, v1
	s_nop 0
	v_cvt_pk_bf16_f32 v1, v2, v3
	s_nop 1
	global_store_dwordx2 v[12:13], v[0:1], off offset:288
	s_cbranch_vccz .LBB0_343
	s_waitcnt vmcnt(0)
	s_cmpk_gt_u32 s24, 0xff
	s_cbranch_scc1 .LBB0_354
	s_barrier

; #define PG8_STAGE(bufoff, gbase, voff) do { _Pragma("unroll") for (int _i = 0; _i < 2; ++_i) \
;         __builtin_amdgcn_global_load_lds((const unsigned*)((const char*)(gbase) + (voff)[_i]), (PG8_LAS unsigned*)(lds + (bufoff) + ldsw + _i * 8192), 16, 0, 0); } while (0)
; #define PG8_LDA(dst, b, h) do { _Pragma("unroll") for (int m = 0; m < 4; ++m) _Pragma("unroll") for (int k = 0; k < 2; ++k) dst[m][k] = *(const PG8_LAS bf16x8*)(lds + PG8_SA(b, h) + aoff + m * 2048 + k * 1024); } while (0)
; #define PG8_LDB(dst, b, h) do { _Pragma("unroll") for (int n = 0; n < 2; ++n) _Pragma("unroll") for (int k = 0; k < 2; ++k) dst[n][k] = *(const PG8_LAS bf16x8*)(lds + PG8_SB(b, h) + boff + n * 2048 + k * 1024); } while (0)
; #define PG8_MMA(ai, bj, At, Bt) do { __builtin_amdgcn_s_setprio(1); _Pragma("unroll") for (int m = 0; m < 4; ++m) _Pragma("unroll") for (int n = 0; n < 2; ++n) _Pragma("unroll") for (int k = 0; k < 2; ++k) \
;         acc[ai][bj][m][n] = __builtin_amdgcn_mfma_f32_16x16x32_bf16(Bt[n][k], At[m][k], acc[ai][bj][m][n], 0, 0, 0); __builtin_amdgcn_s_setprio(0); } while (0)
; #define PG8_WAIT_L(n) asm volatile("s_waitcnt lgkmcnt(" #n ")" ::: "memory")
; #define PG8_BAR __builtin_amdgcn_s_barrier()
; #define PG8_SCHED __builtin_amdgcn_sched_barrier(0)
; template <class Epi, class Sched>
; __device__ __forceinline__ void gemm_phase(PG8_LAS unsigned char* lds, const Gemm g, const Sched& S, const Epi& E, int tid_in) {
;     ...
;             PG8_LDB(B0, 0, 0); PG8_SCHED; PG8_LDA(At, 0, 0); PG8_STAGE(PG8_SA(1, 1), a1 + hstep, voffA);
;             PG8_WAIT_L(8); PG8_BAR; PG8_WAIT_L(0); PG8_MMA(0, 0, At, B0); PG8_BAR; PG8_SCHED;
;             PG8_LDB(B1, 0, 1); PG8_STAGE(PG8_SB(0, 0), b2, voffB);
;             PG8_BAR; PG8_WAIT_L(0); PG8_MMA(0, 1, At, B1); PG8_BAR;
;             PG8_LDA(At, 0, 1); PG8_STAGE(PG8_SA(0, 0), a2, voffA);
;             PG8_BAR; PG8_WAIT_L(0); PG8_MMA(1, 0, At, B0); PG8_BAR; PG8_SCHED;
.LBB0_370:
	s_add_u32 s20, s18, 0xfffc0080
	s_addc_u32 s21, s19, -1
	s_add_i32 s46, 0, 0x10000
	v_add_u32_e32 v146, s46, v214
	ds_read_b128 v[134:137], v146
	ds_read_b128 v[138:141], v146 offset:1024
	ds_read_b128 v[142:145], v146 offset:2048
	ds_read_b128 v[146:149], v146 offset:3072
	s_cmp_eq_u32 s45, 12
	s_cselect_b32 s23, s11, s21
	s_cselect_b32 s22, s41, s20
	s_cselect_b32 s21, s9, s44
	s_cselect_b32 s20, s42, s43
	v_lshl_add_u64 v[182:183], s[18:19], 0, v[130:131]
	s_add_i32 m0, s17, 0xc000
	ds_read_b128 v[150:153], v216
	ds_read_b128 v[154:157], v216 offset:1024
	ds_read_b128 v[158:161], v216 offset:2048
	ds_read_b128 v[162:165], v216 offset:3072
	ds_read_b128 v[166:169], v216 offset:4096
	ds_read_b128 v[170:173], v216 offset:5120
	ds_read_b128 v[174:177], v216 offset:6144
	ds_read_b128 v[178:181], v216 offset:7168
	global_load_lds_dwordx4 v[182:183], off
	v_lshl_add_u64 v[182:183], s[18:19], 0, v[132:133]
	s_add_i32 m0, s17, 0xe000
	s_nop 0
	global_load_lds_dwordx4 v[182:183], off
	s_waitcnt lgkmcnt(8)
	s_barrier
	s_waitcnt lgkmcnt(0)
	s_setprio 1
	s_waitcnt lgkmcnt(0)
	v_mfma_f32_16x16x32_bf16 v[124:127], v[134:137], v[150:153], v[124:127]
	v_mfma_f32_16x16x32_bf16 v[120:123], v[142:145], v[150:153], v[120:123]
	v_mfma_f32_16x16x32_bf16 v[108:111], v[134:137], v[158:161], v[108:111]
	v_mfma_f32_16x16x32_bf16 v[104:107], v[142:145], v[158:161], v[104:107]
	v_mfma_f32_16x16x32_bf16 v[92:95], v[134:137], v[166:169], v[92:95]
	v_mfma_f32_16x16x32_bf16 v[88:91], v[142:145], v[166:169], v[88:91]
	v_mfma_f32_16x16x32_bf16 v[76:79], v[134:137], v[174:177], v[76:79]
	v_mfma_f32_16x16x32_bf16 v[72:75], v[142:145], v[174:177], v[72:75]
	v_mfma_f32_16x16x32_bf16 v[124:127], v[138:141], v[154:157], v[124:127]
	v_mfma_f32_16x16x32_bf16 v[120:123], v[146:149], v[154:157], v[120:123]
	v_mfma_f32_16x16x32_bf16 v[108:111], v[138:141], v[162:165], v[108:111]
	v_mfma_f32_16x16x32_bf16 v[104:107], v[146:149], v[162:165], v[104:107]
	v_mfma_f32_16x16x32_bf16 v[92:95], v[138:141], v[170:173], v[92:95]
	v_mfma_f32_16x16x32_bf16 v[88:91], v[146:149], v[170:173], v[88:91]
	v_mfma_f32_16x16x32_bf16 v[76:79], v[138:141], v[178:181], v[76:79]
	v_mfma_f32_16x16x32_bf16 v[72:75], v[146:149], v[178:181], v[72:75]
	s_setprio 0
	s_barrier
	s_add_i32 s50, 0, 0x14000
	v_add_u32_e32 v190, s50, v214
	s_add_i32 s46, s46, s30
	ds_read_b128 v[182:185], v190
	ds_read_b128 v[186:189], v190 offset:1024
	ds_read_b128 v[194:197], v190 offset:2048
	ds_read_b128 v[200:203], v190 offset:3072
	v_lshl_add_u64 v[190:191], s[20:21], 0, v[192:193]
	s_mov_b32 m0, s46
	v_lshl_add_u64 v[204:205], s[20:21], 0, v[128:129]
	global_load_lds_dwordx4 v[190:191], off
	s_add_i32 m0, s46, 0x2000
	s_nop 0
	global_load_lds_dwordx4 v[204:205], off
	s_barrier
	s_waitcnt lgkmcnt(0)
	s_setprio 1
	s_waitcnt lgkmcnt(0)
	v_mfma_f32_16x16x32_bf16 v[116:119], v[182:185], v[150:153], v[116:119]
	v_mfma_f32_16x16x32_bf16 v[112:115], v[194:197], v[150:153], v[112:115]
	v_mfma_f32_16x16x32_bf16 v[100:103], v[182:185], v[158:161], v[100:103]
	v_mfma_f32_16x16x32_bf16 v[96:99], v[194:197], v[158:161], v[96:99]
	v_mfma_f32_16x16x32_bf16 v[84:87], v[182:185], v[166:169], v[84:87]
	v_mfma_f32_16x16x32_bf16 v[80:83], v[194:197], v[166:169], v[80:83]
	v_mfma_f32_16x16x32_bf16 v[68:71], v[182:185], v[174:177], v[68:71]
	v_mfma_f32_16x16x32_bf16 v[64:67], v[194:197], v[174:177], v[64:67]
	v_mfma_f32_16x16x32_bf16 v[116:119], v[186:189], v[154:157], v[116:119]
	v_mfma_f32_16x16x32_bf16 v[112:115], v[200:203], v[154:157], v[112:115]
	v_mfma_f32_16x16x32_bf16 v[100:103], v[186:189], v[162:165], v[100:103]
	v_mfma_f32_16x16x32_bf16 v[96:99], v[200:203], v[162:165], v[96:99]
	v_mfma_f32_16x16x32_bf16 v[84:87], v[186:189], v[170:173], v[84:87]
	v_mfma_f32_16x16x32_bf16 v[80:83], v[200:203], v[170:173], v[80:83]
	v_mfma_f32_16x16x32_bf16 v[68:71], v[186:189], v[178:181], v[68:71]
	v_mfma_f32_16x16x32_bf16 v[64:67], v[200:203], v[178:181], v[64:67]
	s_setprio 0
	s_mov_b32 m0, s17
	v_lshl_add_u64 v[206:207], s[22:23], 0, v[192:193]
	s_barrier
	ds_read_b128 v[150:153], v216 offset:16384
	ds_read_b128 v[154:157], v216 offset:17408
	ds_read_b128 v[158:161], v216 offset:18432
	ds_read_b128 v[162:165], v216 offset:19456
	ds_read_b128 v[166:169], v216 offset:20480
	ds_read_b128 v[170:173], v216 offset:21504
	ds_read_b128 v[174:177], v216 offset:22528
	ds_read_b128 v[178:181], v216 offset:23552
	global_load_lds_dwordx4 v[206:207], off
	v_lshl_add_u64 v[208:209], s[22:23], 0, v[128:129]
	s_mov_b32 m0, s31
	s_nop 0
	global_load_lds_dwordx4 v[208:209], off
	s_barrier
	s_waitcnt lgkmcnt(0)
	s_setprio 1
	s_waitcnt lgkmcnt(0)
	v_mfma_f32_16x16x32_bf16 v[60:63], v[134:137], v[150:153], v[60:63]
	v_mfma_f32_16x16x32_bf16 v[56:59], v[142:145], v[150:153], v[56:59]
	v_mfma_f32_16x16x32_bf16 v[44:47], v[134:137], v[158:161], v[44:47]
	v_mfma_f32_16x16x32_bf16 v[40:43], v[142:145], v[158:161], v[40:43]
	v_mfma_f32_16x16x32_bf16 v[28:31], v[134:137], v[166:169], v[28:31]
	v_mfma_f32_16x16x32_bf16 v[24:27], v[142:145], v[166:169], v[24:27]
	v_mfma_f32_16x16x32_bf16 v[12:15], v[134:137], v[174:177], v[12:15]
	v_mfma_f32_16x16x32_bf16 v[8:11], v[142:145], v[174:177], v[8:11]
	v_mfma_f32_16x16x32_bf16 v[60:63], v[138:141], v[154:157], v[60:63]
	v_mfma_f32_16x16x32_bf16 v[56:59], v[146:149], v[154:157], v[56:59]
	v_mfma_f32_16x16x32_bf16 v[44:47], v[138:141], v[162:165], v[44:47]
	v_mfma_f32_16x16x32_bf16 v[40:43], v[146:149], v[162:165], v[40:43]
	v_mfma_f32_16x16x32_bf16 v[28:31], v[138:141], v[170:173], v[28:31]
	v_mfma_f32_16x16x32_bf16 v[24:27], v[146:149], v[170:173], v[24:27]
	v_mfma_f32_16x16x32_bf16 v[12:15], v[138:141], v[178:181], v[12:15]
	v_mfma_f32_16x16x32_bf16 v[8:11], v[146:149], v[178:181], v[8:11]
	s_setprio 0
	s_barrier
; #define PG8_STAGE(bufoff, gbase, voff) do { _Pragma("unroll") for (int _i = 0; _i < 2; ++_i) \
;         __builtin_amdgcn_global_load_lds((const unsigned*)((const char*)(gbase) + (voff)[_i]), (PG8_LAS unsigned*)(lds + (bufoff) + ldsw + _i * 8192), 16, 0, 0); } while (0)
; #define PG8_LDA(dst, b, h) do { _Pragma("unroll") for (int m = 0; m < 4; ++m) _Pragma("unroll") for (int k = 0; k < 2; ++k) dst[m][k] = *(const PG8_LAS bf16x8*)(lds + PG8_SA(b, h) + aoff + m * 2048 + k * 1024); } while (0)
; #define PG8_LDB(dst, b, h) do { _Pragma("unroll") for (int n = 0; n < 2; ++n) _Pragma("unroll") for (int k = 0; k < 2; ++k) dst[n][k] = *(const PG8_LAS bf16x8*)(lds + PG8_SB(b, h) + boff + n * 2048 + k * 1024); } while (0)
; #define PG8_MMA(ai, bj, At, Bt) do { __builtin_amdgcn_s_setprio(1); _Pragma("unroll") for (int m = 0; m < 4; ++m) _Pragma("unroll") for (int n = 0; n < 2; ++n) _Pragma("unroll") for (int k = 0; k < 2; ++k) \
;         acc[ai][bj][m][n] = __builtin_amdgcn_mfma_f32_16x16x32_bf16(Bt[n][k], At[m][k], acc[ai][bj][m][n], 0, 0, 0); __builtin_amdgcn_s_setprio(0); } while (0)
; #define PG8_WAIT_V(n) asm volatile("s_waitcnt vmcnt(" #n ")" ::: "memory")
; #define PG8_WAIT_L(n) asm volatile("s_waitcnt lgkmcnt(" #n ")" ::: "memory")
; #define PG8_BAR __builtin_amdgcn_s_barrier()
; #define PG8_SCHED __builtin_amdgcn_sched_barrier(0)
; template <class Epi, class Sched>
; __device__ __forceinline__ void gemm_phase(PG8_LAS unsigned char* lds, const Gemm g, const Sched& S, const Epi& E, int tid_in) {
;     ...
;             PG8_STAGE(PG8_SB(0, 1), b2 + hstep, voffB);
;             PG8_WAIT_V(6); PG8_BAR; PG8_MMA(1, 1, At, B1); PG8_BAR;
;             PG8_LDB(B0, 1, 0); PG8_SCHED; PG8_LDA(At, 1, 0); PG8_STAGE(PG8_SA(0, 1), a2 + hstep, voffA);
;             PG8_WAIT_L(8); PG8_BAR; PG8_WAIT_L(0); PG8_MMA(0, 0, At, B0); PG8_BAR; PG8_SCHED;
;             PG8_LDB(B1, 1, 1); PG8_STAGE(PG8_SB(1, 0), b3, voffB);
;             PG8_BAR; PG8_WAIT_L(0); PG8_MMA(0, 1, At, B1); PG8_BAR;
;             PG8_LDA(At, 1, 1); PG8_STAGE(PG8_SA(1, 0), a3, voffA);
;             PG8_BAR; PG8_WAIT_L(0); PG8_MMA(1, 0, At, B0); PG8_BAR; PG8_SCHED;
	s_add_u32 s48, s20, 0x40000
	s_addc_u32 s49, s21, 0
	s_add_i32 s46, s50, s30
	v_lshl_add_u64 v[134:135], s[48:49], 0, v[192:193]
	s_mov_b32 m0, s46
	s_nop 0
	global_load_lds_dwordx4 v[134:135], off
	v_lshl_add_u64 v[134:135], s[48:49], 0, v[128:129]
	s_add_i32 m0, s46, 0x2000
	s_nop 0
	global_load_lds_dwordx4 v[134:135], off
	s_waitcnt vmcnt(6)
	s_barrier
	s_setprio 1
	v_mfma_f32_16x16x32_bf16 v[52:55], v[182:185], v[150:153], v[52:55]
	v_mfma_f32_16x16x32_bf16 v[48:51], v[194:197], v[150:153], v[48:51]
	v_mfma_f32_16x16x32_bf16 v[36:39], v[182:185], v[158:161], v[36:39]
	v_mfma_f32_16x16x32_bf16 v[32:35], v[194:197], v[158:161], v[32:35]
	v_mfma_f32_16x16x32_bf16 v[20:23], v[182:185], v[166:169], v[20:23]
	v_mfma_f32_16x16x32_bf16 v[16:19], v[194:197], v[166:169], v[16:19]
	v_mfma_f32_16x16x32_bf16 v[4:7], v[182:185], v[174:177], v[4:7]
	v_mfma_f32_16x16x32_bf16 v[0:3], v[194:197], v[174:177], v[0:3]
	v_mfma_f32_16x16x32_bf16 v[52:55], v[186:189], v[154:157], v[52:55]
	v_mfma_f32_16x16x32_bf16 v[48:51], v[200:203], v[154:157], v[48:51]
	v_mfma_f32_16x16x32_bf16 v[36:39], v[186:189], v[162:165], v[36:39]
	v_mfma_f32_16x16x32_bf16 v[32:35], v[200:203], v[162:165], v[32:35]
	v_mfma_f32_16x16x32_bf16 v[20:23], v[186:189], v[170:173], v[20:23]
	v_mfma_f32_16x16x32_bf16 v[16:19], v[200:203], v[170:173], v[16:19]
	v_mfma_f32_16x16x32_bf16 v[4:7], v[186:189], v[178:181], v[4:7]
	v_mfma_f32_16x16x32_bf16 v[0:3], v[200:203], v[178:181], v[0:3]
	s_setprio 0
	s_add_i32 s46, 0, 0x18000
	v_add_u32_e32 v146, s46, v214
	s_barrier
	ds_read_b128 v[134:137], v146
	ds_read_b128 v[138:141], v146 offset:1024
	ds_read_b128 v[142:145], v146 offset:2048
	ds_read_b128 v[146:149], v146 offset:3072
	s_add_u32 s22, s22, 0x40000
	s_addc_u32 s23, s23, 0
	s_mov_b32 m0, s36
	v_lshl_add_u64 v[182:183], s[22:23], 0, v[192:193]
	ds_read_b128 v[150:153], v216 offset:32768
	ds_read_b128 v[154:157], v216 offset:33792
	ds_read_b128 v[158:161], v216 offset:34816
	ds_read_b128 v[162:165], v216 offset:35840
	ds_read_b128 v[166:169], v216 offset:36864
	ds_read_b128 v[170:173], v216 offset:37888
	ds_read_b128 v[174:177], v216 offset:38912
	ds_read_b128 v[178:181], v216 offset:39936
	global_load_lds_dwordx4 v[182:183], off
	v_lshl_add_u64 v[182:183], s[22:23], 0, v[128:129]
	s_mov_b32 m0, s37
	s_nop 0
	global_load_lds_dwordx4 v[182:183], off
	s_waitcnt lgkmcnt(8)
	s_barrier
	s_waitcnt lgkmcnt(0)
	s_setprio 1
	s_waitcnt lgkmcnt(0)
	v_mfma_f32_16x16x32_bf16 v[124:127], v[134:137], v[150:153], v[124:127]
	v_mfma_f32_16x16x32_bf16 v[120:123], v[142:145], v[150:153], v[120:123]
	v_mfma_f32_16x16x32_bf16 v[108:111], v[134:137], v[158:161], v[108:111]
	v_mfma_f32_16x16x32_bf16 v[104:107], v[142:145], v[158:161], v[104:107]
	v_mfma_f32_16x16x32_bf16 v[92:95], v[134:137], v[166:169], v[92:95]
	v_mfma_f32_16x16x32_bf16 v[88:91], v[142:145], v[166:169], v[88:91]
	v_mfma_f32_16x16x32_bf16 v[76:79], v[134:137], v[174:177], v[76:79]
	v_mfma_f32_16x16x32_bf16 v[72:75], v[142:145], v[174:177], v[72:75]
	v_mfma_f32_16x16x32_bf16 v[124:127], v[138:141], v[154:157], v[124:127]
	v_mfma_f32_16x16x32_bf16 v[120:123], v[146:149], v[154:157], v[120:123]
	v_mfma_f32_16x16x32_bf16 v[108:111], v[138:141], v[162:165], v[108:111]
	v_mfma_f32_16x16x32_bf16 v[104:107], v[146:149], v[162:165], v[104:107]
	v_mfma_f32_16x16x32_bf16 v[92:95], v[138:141], v[170:173], v[92:95]
	v_mfma_f32_16x16x32_bf16 v[88:91], v[146:149], v[170:173], v[88:91]
	v_mfma_f32_16x16x32_bf16 v[76:79], v[138:141], v[178:181], v[76:79]
	v_mfma_f32_16x16x32_bf16 v[72:75], v[146:149], v[178:181], v[72:75]
	s_setprio 0
	s_barrier
	s_add_i32 s22, 0, 0x1c000
	s_add_i32 s23, s46, s30
	v_add_u32_e32 v200, s22, v214
	v_lshl_add_u64 v[190:191], v[190:191], 0, s[74:75]
	s_mov_b32 m0, s23
	ds_read_b128 v[182:185], v200
	ds_read_b128 v[186:189], v200 offset:1024
	ds_read_b128 v[194:197], v200 offset:2048
	ds_read_b128 v[200:203], v200 offset:3072
	global_load_lds_dwordx4 v[190:191], off
	v_lshl_add_u64 v[190:191], v[204:205], 0, s[74:75]
	s_add_i32 m0, s23, 0x2000
	s_nop 0
	global_load_lds_dwordx4 v[190:191], off
	s_barrier
	s_waitcnt lgkmcnt(0)
	s_setprio 1
	s_waitcnt lgkmcnt(0)
	v_mfma_f32_16x16x32_bf16 v[116:119], v[182:185], v[150:153], v[116:119]
	v_mfma_f32_16x16x32_bf16 v[112:115], v[194:197], v[150:153], v[112:115]
	v_mfma_f32_16x16x32_bf16 v[100:103], v[182:185], v[158:161], v[100:103]
	v_mfma_f32_16x16x32_bf16 v[96:99], v[194:197], v[158:161], v[96:99]
	v_mfma_f32_16x16x32_bf16 v[84:87], v[182:185], v[166:169], v[84:87]
	v_mfma_f32_16x16x32_bf16 v[80:83], v[194:197], v[166:169], v[80:83]
	v_mfma_f32_16x16x32_bf16 v[68:71], v[182:185], v[174:177], v[68:71]
	v_mfma_f32_16x16x32_bf16 v[64:67], v[194:197], v[174:177], v[64:67]
	v_mfma_f32_16x16x32_bf16 v[116:119], v[186:189], v[154:157], v[116:119]
	v_mfma_f32_16x16x32_bf16 v[112:115], v[200:203], v[154:157], v[112:115]
	v_mfma_f32_16x16x32_bf16 v[100:103], v[186:189], v[162:165], v[100:103]
	v_mfma_f32_16x16x32_bf16 v[96:99], v[200:203], v[162:165], v[96:99]
	v_mfma_f32_16x16x32_bf16 v[84:87], v[186:189], v[170:173], v[84:87]
	v_mfma_f32_16x16x32_bf16 v[80:83], v[200:203], v[170:173], v[80:83]
	v_mfma_f32_16x16x32_bf16 v[68:71], v[186:189], v[178:181], v[68:71]
	v_mfma_f32_16x16x32_bf16 v[64:67], v[200:203], v[178:181], v[64:67]
	s_setprio 0
	s_mov_b32 m0, s38
	v_lshl_add_u64 v[190:191], v[206:207], 0, s[74:75]
	s_barrier
	ds_read_b128 v[150:153], v216 offset:49152
	ds_read_b128 v[154:157], v216 offset:50176
	ds_read_b128 v[158:161], v216 offset:51200
	ds_read_b128 v[162:165], v216 offset:52224
	ds_read_b128 v[166:169], v216 offset:53248
	ds_read_b128 v[170:173], v216 offset:54272
	ds_read_b128 v[174:177], v216 offset:55296
	ds_read_b128 v[178:181], v216 offset:56320
	global_load_lds_dwordx4 v[190:191], off
	v_lshl_add_u64 v[190:191], v[208:209], 0, s[74:75]
	s_mov_b32 m0, s39
	s_nop 0
	global_load_lds_dwordx4 v[190:191], off
	s_barrier
; #define PG8_STAGE(bufoff, gbase, voff) do { _Pragma("unroll") for (int _i = 0; _i < 2; ++_i) \
;         __builtin_amdgcn_global_load_lds((const unsigned*)((const char*)(gbase) + (voff)[_i]), (PG8_LAS unsigned*)(lds + (bufoff) + ldsw + _i * 8192), 16, 0, 0); } while (0)
; #define PG8_MMA(ai, bj, At, Bt) do { __builtin_amdgcn_s_setprio(1); _Pragma("unroll") for (int m = 0; m < 4; ++m) _Pragma("unroll") for (int n = 0; n < 2; ++n) _Pragma("unroll") for (int k = 0; k < 2; ++k) \
;         acc[ai][bj][m][n] = __builtin_amdgcn_mfma_f32_16x16x32_bf16(Bt[n][k], At[m][k], acc[ai][bj][m][n], 0, 0, 0); __builtin_amdgcn_s_setprio(0); } while (0)
; #define PG8_WAIT_V(n) asm volatile("s_waitcnt vmcnt(" #n ")" ::: "memory")
; #define PG8_BAR __builtin_amdgcn_s_barrier()
; template <class Epi, class Sched>
; __device__ __forceinline__ void gemm_phase(PG8_LAS unsigned char* lds, const Gemm g, const Sched& S, const Epi& E, int tid_in) {
;     ...
;             PG8_STAGE(PG8_SB(1, 1), b3 + hstep, voffB);
;             PG8_WAIT_V(6); PG8_BAR; PG8_MMA(1, 1, At, B1); PG8_BAR;
;     __device__ __forceinline__ void operator()(f32x4 (&acc)[2][2][4][2], const Unit& u, int wr, int wc, int fr, int fq) const {
;         const int row0 = u.pm * 256 + wr * 64 + fr, col0 = u.pn * 256 + wc * 32 + 4 * fq;
; #pragma unroll
;         for (int ai = 0; ai < 2; ++ai) {
;             u32x2 gw[4][2][2], tw[4][2][2];
; #pragma unroll
;             for (int m = 0; m < 4; ++m)
; #pragma unroll
;                 for (int bj = 0; bj < 2; ++bj)
; #pragma unroll
;                     for (int n = 0; n < 2; ++n) { const size_t row = row0 + ai * 128 + m * 16; const int col = col0 + bj * 128 + n * 16;
;                         gw[m][bj][n] = *(const u32x2*)(gates + row * 2048 + 1024 + col); tw[m][bj][n] = *(const u32x2*)(tmp + row * 1024 + col); }
	s_waitcnt lgkmcnt(0)
	s_setprio 1
	s_waitcnt lgkmcnt(0)
	v_mfma_f32_16x16x32_bf16 v[60:63], v[134:137], v[150:153], v[60:63]
	v_mfma_f32_16x16x32_bf16 v[56:59], v[142:145], v[150:153], v[56:59]
	v_mfma_f32_16x16x32_bf16 v[44:47], v[134:137], v[158:161], v[44:47]
	v_mfma_f32_16x16x32_bf16 v[40:43], v[142:145], v[158:161], v[40:43]
	v_mfma_f32_16x16x32_bf16 v[28:31], v[134:137], v[166:169], v[28:31]
	v_mfma_f32_16x16x32_bf16 v[24:27], v[142:145], v[166:169], v[24:27]
	v_mfma_f32_16x16x32_bf16 v[12:15], v[134:137], v[174:177], v[12:15]
	v_mfma_f32_16x16x32_bf16 v[8:11], v[142:145], v[174:177], v[8:11]
	v_mfma_f32_16x16x32_bf16 v[60:63], v[138:141], v[154:157], v[60:63]
	v_mfma_f32_16x16x32_bf16 v[56:59], v[146:149], v[154:157], v[56:59]
	v_mfma_f32_16x16x32_bf16 v[44:47], v[138:141], v[162:165], v[44:47]
	v_mfma_f32_16x16x32_bf16 v[40:43], v[146:149], v[162:165], v[40:43]
	v_mfma_f32_16x16x32_bf16 v[28:31], v[138:141], v[170:173], v[28:31]
	v_mfma_f32_16x16x32_bf16 v[24:27], v[146:149], v[170:173], v[24:27]
	v_mfma_f32_16x16x32_bf16 v[12:15], v[138:141], v[178:181], v[12:15]
	v_mfma_f32_16x16x32_bf16 v[8:11], v[146:149], v[178:181], v[8:11]
	s_setprio 0
	s_barrier
	s_add_u32 s20, s20, 0x40080
	s_addc_u32 s21, s21, 0
	s_add_i32 s22, s22, s30
	v_lshl_add_u64 v[134:135], s[20:21], 0, v[192:193]
	s_mov_b32 m0, s22
	s_nop 0
	global_load_lds_dwordx4 v[134:135], off
	v_lshl_add_u64 v[134:135], s[20:21], 0, v[128:129]
	s_add_i32 m0, s22, 0x2000
	s_nop 0
	global_load_lds_dwordx4 v[134:135], off
	s_waitcnt vmcnt(6)
	s_barrier
	s_setprio 1
	v_mfma_f32_16x16x32_bf16 v[52:55], v[182:185], v[150:153], v[52:55]
	v_mfma_f32_16x16x32_bf16 v[48:51], v[194:197], v[150:153], v[48:51]
	v_mfma_f32_16x16x32_bf16 v[36:39], v[182:185], v[158:161], v[36:39]
	v_mfma_f32_16x16x32_bf16 v[32:35], v[194:197], v[158:161], v[32:35]
	v_mfma_f32_16x16x32_bf16 v[20:23], v[182:185], v[166:169], v[20:23]
	v_mfma_f32_16x16x32_bf16 v[16:19], v[194:197], v[166:169], v[16:19]
	v_mfma_f32_16x16x32_bf16 v[4:7], v[182:185], v[174:177], v[4:7]
	v_mfma_f32_16x16x32_bf16 v[0:3], v[194:197], v[174:177], v[0:3]
	v_mfma_f32_16x16x32_bf16 v[52:55], v[186:189], v[154:157], v[52:55]
	v_mfma_f32_16x16x32_bf16 v[48:51], v[200:203], v[154:157], v[48:51]
	v_mfma_f32_16x16x32_bf16 v[36:39], v[186:189], v[162:165], v[36:39]
	v_mfma_f32_16x16x32_bf16 v[32:35], v[200:203], v[162:165], v[32:35]
	v_mfma_f32_16x16x32_bf16 v[20:23], v[186:189], v[170:173], v[20:23]
	v_mfma_f32_16x16x32_bf16 v[16:19], v[200:203], v[170:173], v[16:19]
	v_mfma_f32_16x16x32_bf16 v[4:7], v[186:189], v[178:181], v[4:7]
	v_mfma_f32_16x16x32_bf16 v[0:3], v[200:203], v[178:181], v[0:3]
	s_setprio 0
	s_add_i32 s45, s45, 2
	s_add_u32 s18, s18, 0x100
	s_addc_u32 s19, s19, 0
	s_add_u32 s43, s43, 0x100
	s_addc_u32 s44, s44, 0
	s_cmp_gt_u32 s45, 13
	s_barrier
	s_cbranch_scc0 .LBB0_370
	v_lshl_add_u32 v136, s16, 8, v199
	v_lshl_or_b32 v134, s33, 8, v215
	v_ashrrev_i32_e32 v137, 31, v136
	v_lshlrev_b64 v[138:139], 12, v[136:137]
	v_ashrrev_i32_e32 v135, 31, v134
	v_lshl_add_u64 v[138:139], s[0:1], 0, v[138:139]
	v_lshlrev_b64 v[134:135], 1, v[134:135]
	v_lshl_add_u64 v[138:139], v[138:139], 0, v[134:135]
	global_load_dwordx2 v[194:195], v[138:139], off offset:2048
	v_lshlrev_b64 v[212:213], 11, v[136:137]
	v_lshl_add_u64 v[140:141], s[4:5], 0, v[212:213]
	v_lshl_add_u64 v[140:141], v[140:141], 0, v[134:135]
	global_load_dwordx2 v[196:197], v[140:141], off
	global_load_dwordx2 v[210:211], v[138:139], off offset:2080
	global_load_dwordx2 v[208:209], v[140:141], off offset:32
	global_load_dwordx2 v[206:207], v[138:139], off offset:2304
	global_load_dwordx2 v[204:205], v[140:141], off offset:256
	global_load_dwordx2 v[202:203], v[138:139], off offset:2336
	global_load_dwordx2 v[200:201], v[140:141], off offset:288
	v_or_b32_e32 v138, 16, v136
	v_ashrrev_i32_e32 v139, 31, v138
	v_lshlrev_b64 v[140:141], 12, v[138:139]
	v_lshl_add_u64 v[140:141], s[0:1], 0, v[140:141]
	v_lshl_add_u64 v[140:141], v[140:141], 0, v[134:135]
	global_load_dwordx2 v[190:191], v[140:141], off offset:2048
	v_lshlrev_b64 v[184:185], 11, v[138:139]
	v_lshl_add_u64 v[138:139], s[4:5], 0, v[184:185]
	v_lshl_add_u64 v[138:139], v[138:139], 0, v[134:135]
	global_load_dwordx2 v[188:189], v[138:139], off
	global_load_dwordx2 v[186:187], v[140:141], off offset:2080
	global_load_dwordx2 v[182:183], v[138:139], off offset:32
	global_load_dwordx2 v[172:173], v[140:141], off offset:2304
	global_load_dwordx2 v[170:171], v[138:139], off offset:256
	global_load_dwordx2 v[156:157], v[140:141], off offset:2336
	global_load_dwordx2 v[154:155], v[138:139], off offset:288
	v_or_b32_e32 v138, 32, v136
	v_ashrrev_i32_e32 v139, 31, v138
	v_lshlrev_b64 v[140:141], 12, v[138:139]
	v_lshl_add_u64 v[140:141], s[0:1], 0, v[140:141]
	v_lshl_add_u64 v[140:141], v[140:141], 0, v[134:135]
	global_load_dwordx2 v[180:181], v[140:141], off offset:2048
	v_lshlrev_b64 v[166:167], 11, v[138:139]
	v_lshl_add_u64 v[138:139], s[4:5], 0, v[166:167]
	v_lshl_add_u64 v[138:139], v[138:139], 0, v[134:135]
	global_load_dwordx2 v[176:177], v[138:139], off
	global_load_dwordx2 v[168:169], v[140:141], off offset:2080
	global_load_dwordx2 v[160:161], v[138:139], off offset:32
	global_load_dwordx2 v[152:153], v[140:141], off offset:2304
	global_load_dwordx2 v[148:149], v[138:139], off offset:256
	global_load_dwordx2 v[144:145], v[140:141], off offset:2336
	s_nop 0
	global_load_dwordx2 v[140:141], v[138:139], off offset:288
	v_or_b32_e32 v138, 48, v136
	v_ashrrev_i32_e32 v139, 31, v138
	v_lshlrev_b64 v[142:143], 12, v[138:139]
	v_lshl_add_u64 v[142:143], s[0:1], 0, v[142:143]
	v_lshl_add_u64 v[142:143], v[142:143], 0, v[134:135]
	global_load_dwordx2 v[178:179], v[142:143], off offset:2048
	v_lshlrev_b64 v[162:163], 11, v[138:139]
	v_lshl_add_u64 v[138:139], s[4:5], 0, v[162:163]
	v_lshl_add_u64 v[138:139], v[138:139], 0, v[134:135]
	global_load_dwordx2 v[174:175], v[138:139], off
	global_load_dwordx2 v[164:165], v[142:143], off offset:2080
	global_load_dwordx2 v[158:159], v[138:139], off offset:32
	global_load_dwordx2 v[150:151], v[142:143], off offset:2304
	global_load_dwordx2 v[146:147], v[138:139], off offset:256
	s_nop 0
	global_load_dwordx2 v[142:143], v[142:143], off offset:2336
	s_nop 0
	global_load_dwordx2 v[138:139], v[138:139], off offset:288
	s_and_b64 vcc, exec, s[2:3]
	s_mov_b32 s33, s8
	s_mov_b32 s16, s10
	s_mov_b64 s[20:21], s[14:15]
	s_mov_b64 s[18:19], s[12:13]
	s_waitcnt vmcnt(0)
; __device__ __forceinline__ unsigned cvt_pk_bf16(float lo, float hi) { unsigned r; asm volatile("s_nop 0\n\tv_cvt_pk_bf16_f32 %0, %1, %2\n\ts_nop 1" : "=v"(r) : "v"(lo), "v"(hi)); return r; }
; __device__ __forceinline__ float bflo(unsigned w) { return __uint_as_float(w << 16); }
; __device__ __forceinline__ float bfhi(unsigned w) { return __uint_as_float(w & 0xffff0000u); }
;     __device__ __forceinline__ void operator()(f32x4 (&acc)[2][2][4][2], const Unit& u, int wr, int wc, int fr, int fq) const {
;     ...
;             for (int m = 0; m < 4; ++m) { const size_t row = row0 + ai * 128 + m * 16;
; #pragma unroll
;                 for (int bj = 0; bj < 2; ++bj)
; #pragma unroll
;                     for (int n = 0; n < 2; ++n) { const int col = col0 + bj * 128 + n * 16; const u32x2 g2 = gw[m][bj][n], t2 = tw[m][bj][n];
;                         const f32x4 gv = (f32x4){bflo(g2.x), bfhi(g2.x), bflo(g2.y), bfhi(g2.y)};
;                         const f32x4 o = (f32x4){bflo(t2.x), bfhi(t2.x), bflo(t2.y), bfhi(t2.y)} + gv * acc[ai][bj][m][n];
;                         u32x2 w; w.x = cvt_pk_bf16(o[0], o[1]); w.y = cvt_pk_bf16(o[2], o[3]); *(u32x2*)(merged + row * 1024 + col) = w; } }
	v_lshlrev_b32_e32 v220, 16, v196
	v_and_b32_e32 v221, 0xffff0000, v196
	v_lshlrev_b32_e32 v218, 16, v194
	v_and_b32_e32 v219, 0xffff0000, v194
	v_lshlrev_b32_e32 v194, 16, v195
	v_and_b32_e32 v195, 0xffff0000, v195
	v_lshlrev_b32_e32 v196, 16, v197
	v_and_b32_e32 v197, 0xffff0000, v197
	v_pk_fma_f32 v[124:125], v[124:125], v[218:219], v[220:221]
	v_pk_fma_f32 v[126:127], v[126:127], v[194:195], v[196:197]
	v_cvt_pk_bf16_f32 v194, v124, v125
	v_lshl_add_u64 v[124:125], s[6:7], 0, v[212:213]
	v_cvt_pk_bf16_f32 v195, v126, v127
	v_lshl_add_u64 v[124:125], v[124:125], 0, v[134:135]
	v_lshlrev_b32_e32 v126, 16, v210
	v_and_b32_e32 v127, 0xffff0000, v210
	v_lshlrev_b32_e32 v196, 16, v208
	v_and_b32_e32 v197, 0xffff0000, v208
	global_store_dwordx2 v[124:125], v[194:195], off
	v_lshlrev_b32_e32 v194, 16, v211
	v_and_b32_e32 v195, 0xffff0000, v211
	v_lshlrev_b32_e32 v208, 16, v209
	v_and_b32_e32 v209, 0xffff0000, v209
	v_pk_fma_f32 v[120:121], v[120:121], v[126:127], v[196:197]
	v_pk_fma_f32 v[122:123], v[122:123], v[194:195], v[208:209]
	v_cvt_pk_bf16_f32 v120, v120, v121
	v_lshlrev_b32_e32 v126, 16, v204
	v_cvt_pk_bf16_f32 v121, v122, v123
	global_store_dwordx2 v[124:125], v[120:121], off offset:32
	v_lshlrev_b32_e32 v120, 16, v206
	v_and_b32_e32 v121, 0xffff0000, v206
	v_and_b32_e32 v127, 0xffff0000, v204
	v_lshlrev_b32_e32 v122, 16, v207
	v_and_b32_e32 v123, 0xffff0000, v207
	v_lshlrev_b32_e32 v194, 16, v205
	v_and_b32_e32 v195, 0xffff0000, v205
	v_pk_fma_f32 v[116:117], v[116:117], v[120:121], v[126:127]
	v_pk_fma_f32 v[118:119], v[118:119], v[122:123], v[194:195]
	v_cvt_pk_bf16_f32 v116, v116, v117
	v_lshlrev_b32_e32 v120, 16, v200
	v_cvt_pk_bf16_f32 v117, v118, v119
	global_store_dwordx2 v[124:125], v[116:117], off offset:256
	v_lshlrev_b32_e32 v116, 16, v202
	v_and_b32_e32 v117, 0xffff0000, v202
	v_and_b32_e32 v121, 0xffff0000, v200
	v_lshlrev_b32_e32 v118, 16, v203
	v_and_b32_e32 v119, 0xffff0000, v203
	v_lshlrev_b32_e32 v122, 16, v201
	v_and_b32_e32 v123, 0xffff0000, v201
	v_pk_fma_f32 v[112:113], v[112:113], v[116:117], v[120:121]
	v_pk_fma_f32 v[114:115], v[114:115], v[118:119], v[122:123]
	v_cvt_pk_bf16_f32 v112, v112, v113
	v_lshlrev_b32_e32 v116, 16, v188
	v_cvt_pk_bf16_f32 v113, v114, v115
	global_store_dwordx2 v[124:125], v[112:113], off offset:288
	v_lshlrev_b32_e32 v112, 16, v190
	v_and_b32_e32 v113, 0xffff0000, v190
	v_lshlrev_b32_e32 v114, 16, v191
	v_and_b32_e32 v115, 0xffff0000, v191
	v_and_b32_e32 v117, 0xffff0000, v188
	v_lshlrev_b32_e32 v118, 16, v189
	v_and_b32_e32 v119, 0xffff0000, v189
	v_pk_fma_f32 v[110:111], v[110:111], v[114:115], v[118:119]
	v_pk_fma_f32 v[108:109], v[108:109], v[112:113], v[116:117]
	v_lshlrev_b32_e32 v114, 16, v182
	v_cvt_pk_bf16_f32 v108, v108, v109
	v_cvt_pk_bf16_f32 v109, v110, v111
	v_lshl_add_u64 v[110:111], s[6:7], 0, v[184:185]
	v_lshl_add_u64 v[110:111], v[110:111], 0, v[134:135]
	global_store_dwordx2 v[110:111], v[108:109], off
	v_lshlrev_b32_e32 v108, 16, v186
	v_and_b32_e32 v109, 0xffff0000, v186
	v_and_b32_e32 v115, 0xffff0000, v182
	v_lshlrev_b32_e32 v112, 16, v187
	v_and_b32_e32 v113, 0xffff0000, v187
	v_lshlrev_b32_e32 v116, 16, v183
	v_and_b32_e32 v117, 0xffff0000, v183
	v_pk_fma_f32 v[104:105], v[104:105], v[108:109], v[114:115]
	v_pk_fma_f32 v[106:107], v[106:107], v[112:113], v[116:117]
	v_cvt_pk_bf16_f32 v104, v104, v105
	v_lshlrev_b32_e32 v108, 16, v170
	v_cvt_pk_bf16_f32 v105, v106, v107
	global_store_dwordx2 v[110:111], v[104:105], off offset:32
	v_lshlrev_b32_e32 v104, 16, v172
	v_and_b32_e32 v105, 0xffff0000, v172
	v_and_b32_e32 v109, 0xffff0000, v170
	v_lshlrev_b32_e32 v106, 16, v173
	v_and_b32_e32 v107, 0xffff0000, v173
	v_lshlrev_b32_e32 v112, 16, v171
	v_and_b32_e32 v113, 0xffff0000, v171
	v_pk_fma_f32 v[100:101], v[100:101], v[104:105], v[108:109]
	v_pk_fma_f32 v[102:103], v[102:103], v[106:107], v[112:113]
	v_cvt_pk_bf16_f32 v100, v100, v101
	v_lshlrev_b32_e32 v104, 16, v154
	v_cvt_pk_bf16_f32 v101, v102, v103
	global_store_dwordx2 v[110:111], v[100:101], off offset:256
	v_lshlrev_b32_e32 v100, 16, v156
	v_and_b32_e32 v101, 0xffff0000, v156
	v_and_b32_e32 v105, 0xffff0000, v154
	v_lshlrev_b32_e32 v102, 16, v157
	v_and_b32_e32 v103, 0xffff0000, v157
	v_lshlrev_b32_e32 v106, 16, v155
	v_and_b32_e32 v107, 0xffff0000, v155
	v_pk_fma_f32 v[96:97], v[96:97], v[100:101], v[104:105]
	v_pk_fma_f32 v[98:99], v[98:99], v[102:103], v[106:107]
	v_cvt_pk_bf16_f32 v96, v96, v97
	v_lshlrev_b32_e32 v100, 16, v176
	v_cvt_pk_bf16_f32 v97, v98, v99
	global_store_dwordx2 v[110:111], v[96:97], off offset:288
	v_lshlrev_b32_e32 v96, 16, v180
	v_and_b32_e32 v97, 0xffff0000, v180
	v_lshlrev_b32_e32 v98, 16, v181
	v_and_b32_e32 v99, 0xffff0000, v181
	v_and_b32_e32 v101, 0xffff0000, v176
	v_lshlrev_b32_e32 v102, 16, v177
	v_and_b32_e32 v103, 0xffff0000, v177
	v_pk_fma_f32 v[94:95], v[94:95], v[98:99], v[102:103]
	v_pk_fma_f32 v[92:93], v[92:93], v[96:97], v[100:101]
	v_lshlrev_b32_e32 v98, 16, v160
	v_cvt_pk_bf16_f32 v92, v92, v93
	v_cvt_pk_bf16_f32 v93, v94, v95
	v_lshl_add_u64 v[94:95], s[6:7], 0, v[166:167]
	v_lshl_add_u64 v[94:95], v[94:95], 0, v[134:135]
	global_store_dwordx2 v[94:95], v[92:93], off
	v_lshlrev_b32_e32 v92, 16, v168
	v_and_b32_e32 v93, 0xffff0000, v168
	v_and_b32_e32 v99, 0xffff0000, v160
	v_lshlrev_b32_e32 v96, 16, v169
	v_and_b32_e32 v97, 0xffff0000, v169
	v_lshlrev_b32_e32 v100, 16, v161
	v_and_b32_e32 v101, 0xffff0000, v161
	v_pk_fma_f32 v[88:89], v[88:89], v[92:93], v[98:99]
	v_pk_fma_f32 v[90:91], v[90:91], v[96:97], v[100:101]
	v_cvt_pk_bf16_f32 v88, v88, v89
	v_lshlrev_b32_e32 v92, 16, v148
	v_cvt_pk_bf16_f32 v89, v90, v91
	global_store_dwordx2 v[94:95], v[88:89], off offset:32
; __device__ __forceinline__ unsigned cvt_pk_bf16(float lo, float hi) { unsigned r; asm volatile("s_nop 0\n\tv_cvt_pk_bf16_f32 %0, %1, %2\n\ts_nop 1" : "=v"(r) : "v"(lo), "v"(hi)); return r; }
; __device__ __forceinline__ float bflo(unsigned w) { return __uint_as_float(w << 16); }
; __device__ __forceinline__ float bfhi(unsigned w) { return __uint_as_float(w & 0xffff0000u); }
;     __device__ __forceinline__ void operator()(f32x4 (&acc)[2][2][4][2], const Unit& u, int wr, int wc, int fr, int fq) const {
;     ...
;             u32x2 gw[4][2][2], tw[4][2][2];
; #pragma unroll
;             for (int m = 0; m < 4; ++m)
; #pragma unroll
;                 for (int bj = 0; bj < 2; ++bj)
; #pragma unroll
;                     for (int n = 0; n < 2; ++n) { const size_t row = row0 + ai * 128 + m * 16; const int col = col0 + bj * 128 + n * 16;
;                         gw[m][bj][n] = *(const u32x2*)(gates + row * 2048 + 1024 + col); tw[m][bj][n] = *(const u32x2*)(tmp + row * 1024 + col); }
; #pragma unroll
;             for (int m = 0; m < 4; ++m) { const size_t row = row0 + ai * 128 + m * 16;
; #pragma unroll
;                 for (int bj = 0; bj < 2; ++bj)
; #pragma unroll
;                     for (int n = 0; n < 2; ++n) { const int col = col0 + bj * 128 + n * 16; const u32x2 g2 = gw[m][bj][n], t2 = tw[m][bj][n];
;                         const f32x4 gv = (f32x4){bflo(g2.x), bfhi(g2.x), bflo(g2.y), bfhi(g2.y)};
;                         const f32x4 o = (f32x4){bflo(t2.x), bfhi(t2.x), bflo(t2.y), bfhi(t2.y)} + gv * acc[ai][bj][m][n];
;                         u32x2 w; w.x = cvt_pk_bf16(o[0], o[1]); w.y = cvt_pk_bf16(o[2], o[3]); *(u32x2*)(merged + row * 1024 + col) = w; } }
	v_lshlrev_b32_e32 v88, 16, v152
	v_and_b32_e32 v89, 0xffff0000, v152
	v_and_b32_e32 v93, 0xffff0000, v148
	v_lshlrev_b32_e32 v90, 16, v153
	v_and_b32_e32 v91, 0xffff0000, v153
	v_lshlrev_b32_e32 v96, 16, v149
	v_and_b32_e32 v97, 0xffff0000, v149
	v_pk_fma_f32 v[84:85], v[84:85], v[88:89], v[92:93]
	v_pk_fma_f32 v[86:87], v[86:87], v[90:91], v[96:97]
	v_cvt_pk_bf16_f32 v84, v84, v85
	v_lshlrev_b32_e32 v88, 16, v140
	v_cvt_pk_bf16_f32 v85, v86, v87
	global_store_dwordx2 v[94:95], v[84:85], off offset:256
	v_lshlrev_b32_e32 v84, 16, v144
	v_and_b32_e32 v85, 0xffff0000, v144
	v_and_b32_e32 v89, 0xffff0000, v140
	v_lshlrev_b32_e32 v86, 16, v145
	v_and_b32_e32 v87, 0xffff0000, v145
	v_lshlrev_b32_e32 v90, 16, v141
	v_and_b32_e32 v91, 0xffff0000, v141
	v_pk_fma_f32 v[80:81], v[80:81], v[84:85], v[88:89]
	v_pk_fma_f32 v[82:83], v[82:83], v[86:87], v[90:91]
	v_cvt_pk_bf16_f32 v80, v80, v81
	v_lshlrev_b32_e32 v84, 16, v174
	v_cvt_pk_bf16_f32 v81, v82, v83
	global_store_dwordx2 v[94:95], v[80:81], off offset:288
	v_lshlrev_b32_e32 v80, 16, v178
	v_and_b32_e32 v81, 0xffff0000, v178
	v_lshlrev_b32_e32 v82, 16, v179
	v_and_b32_e32 v83, 0xffff0000, v179
	v_and_b32_e32 v85, 0xffff0000, v174
	v_lshlrev_b32_e32 v86, 16, v175
	v_and_b32_e32 v87, 0xffff0000, v175
	v_pk_fma_f32 v[78:79], v[78:79], v[82:83], v[86:87]
	v_pk_fma_f32 v[76:77], v[76:77], v[80:81], v[84:85]
	v_lshlrev_b32_e32 v82, 16, v158
	v_cvt_pk_bf16_f32 v76, v76, v77
	v_cvt_pk_bf16_f32 v77, v78, v79
	v_lshl_add_u64 v[78:79], s[6:7], 0, v[162:163]
	v_lshl_add_u64 v[78:79], v[78:79], 0, v[134:135]
	global_store_dwordx2 v[78:79], v[76:77], off
	v_lshlrev_b32_e32 v76, 16, v164
	v_and_b32_e32 v77, 0xffff0000, v164
	v_and_b32_e32 v83, 0xffff0000, v158
	v_lshlrev_b32_e32 v80, 16, v165
	v_and_b32_e32 v81, 0xffff0000, v165
	v_lshlrev_b32_e32 v84, 16, v159
	v_and_b32_e32 v85, 0xffff0000, v159
	v_pk_fma_f32 v[72:73], v[72:73], v[76:77], v[82:83]
	v_pk_fma_f32 v[74:75], v[74:75], v[80:81], v[84:85]
	v_cvt_pk_bf16_f32 v72, v72, v73
	v_lshlrev_b32_e32 v76, 16, v146
	v_cvt_pk_bf16_f32 v73, v74, v75
	global_store_dwordx2 v[78:79], v[72:73], off offset:32
	v_lshlrev_b32_e32 v72, 16, v150
	v_and_b32_e32 v73, 0xffff0000, v150
	v_and_b32_e32 v77, 0xffff0000, v146
	v_lshlrev_b32_e32 v74, 16, v151
	v_and_b32_e32 v75, 0xffff0000, v151
	v_lshlrev_b32_e32 v80, 16, v147
	v_and_b32_e32 v81, 0xffff0000, v147
	v_pk_fma_f32 v[68:69], v[68:69], v[72:73], v[76:77]
	v_pk_fma_f32 v[70:71], v[70:71], v[74:75], v[80:81]
	v_cvt_pk_bf16_f32 v68, v68, v69
	v_lshlrev_b32_e32 v72, 16, v138
	v_cvt_pk_bf16_f32 v69, v70, v71
	global_store_dwordx2 v[78:79], v[68:69], off offset:256
	v_lshlrev_b32_e32 v68, 16, v142
	v_and_b32_e32 v69, 0xffff0000, v142
	v_and_b32_e32 v73, 0xffff0000, v138
	v_pk_fma_f32 v[64:65], v[64:65], v[68:69], v[72:73]
	v_lshlrev_b32_e32 v70, 16, v143
	v_and_b32_e32 v71, 0xffff0000, v143
	v_lshlrev_b32_e32 v74, 16, v139
	v_and_b32_e32 v75, 0xffff0000, v139
	v_cvt_pk_bf16_f32 v64, v64, v65
	v_pk_fma_f32 v[66:67], v[66:67], v[70:71], v[74:75]
	s_nop 0
	v_cvt_pk_bf16_f32 v65, v66, v67
	global_store_dwordx2 v[78:79], v[64:65], off offset:288
	v_add_u32_e32 v64, 0x80, v136
	v_ashrrev_i32_e32 v65, 31, v64
	v_lshlrev_b64 v[66:67], 12, v[64:65]
	v_lshl_add_u64 v[66:67], s[0:1], 0, v[66:67]
	v_lshl_add_u64 v[66:67], v[66:67], 0, v[134:135]
	global_load_dwordx2 v[116:117], v[66:67], off offset:2048
	v_lshlrev_b64 v[114:115], 11, v[64:65]
	v_lshl_add_u64 v[64:65], s[4:5], 0, v[114:115]
	v_lshl_add_u64 v[64:65], v[64:65], 0, v[134:135]
	global_load_dwordx2 v[118:119], v[64:65], off
	global_load_dwordx2 v[120:121], v[66:67], off offset:2080
	global_load_dwordx2 v[122:123], v[64:65], off offset:32
	global_load_dwordx2 v[124:125], v[66:67], off offset:2304
	global_load_dwordx2 v[126:127], v[64:65], off offset:256
	global_load_dwordx2 v[138:139], v[66:67], off offset:2336
	global_load_dwordx2 v[140:141], v[64:65], off offset:288
	v_add_u32_e32 v64, 0x90, v136
	v_ashrrev_i32_e32 v65, 31, v64
	v_lshlrev_b64 v[66:67], 12, v[64:65]
	v_lshl_add_u64 v[66:67], s[0:1], 0, v[66:67]
	v_lshl_add_u64 v[66:67], v[66:67], 0, v[134:135]
	global_load_dwordx2 v[142:143], v[66:67], off offset:2048
	v_lshlrev_b64 v[108:109], 11, v[64:65]
	v_lshl_add_u64 v[64:65], s[4:5], 0, v[108:109]
	v_lshl_add_u64 v[64:65], v[64:65], 0, v[134:135]
	global_load_dwordx2 v[144:145], v[64:65], off
	global_load_dwordx2 v[112:113], v[66:67], off offset:2080
	global_load_dwordx2 v[110:111], v[64:65], off offset:32
	global_load_dwordx2 v[106:107], v[66:67], off offset:2304
	global_load_dwordx2 v[104:105], v[64:65], off offset:256
	global_load_dwordx2 v[100:101], v[66:67], off offset:2336
	global_load_dwordx2 v[102:103], v[64:65], off offset:288
	v_add_u32_e32 v64, 0xa0, v136
	v_ashrrev_i32_e32 v65, 31, v64
	v_lshlrev_b64 v[66:67], 12, v[64:65]
	v_lshl_add_u64 v[66:67], s[0:1], 0, v[66:67]
	v_lshl_add_u64 v[66:67], v[66:67], 0, v[134:135]
	global_load_dwordx2 v[96:97], v[66:67], off offset:2048
	v_lshlrev_b64 v[90:91], 11, v[64:65]
	v_lshl_add_u64 v[64:65], s[4:5], 0, v[90:91]
	v_lshl_add_u64 v[64:65], v[64:65], 0, v[134:135]
	global_load_dwordx2 v[98:99], v[64:65], off
	global_load_dwordx2 v[94:95], v[66:67], off offset:2080
	global_load_dwordx2 v[92:93], v[64:65], off offset:32
	global_load_dwordx2 v[88:89], v[66:67], off offset:2304
	global_load_dwordx2 v[86:87], v[64:65], off offset:256
	global_load_dwordx2 v[82:83], v[66:67], off offset:2336
	global_load_dwordx2 v[84:85], v[64:65], off offset:288
	v_add_u32_e32 v64, 0xb0, v136
	v_ashrrev_i32_e32 v65, 31, v64
	v_lshlrev_b64 v[66:67], 12, v[64:65]
	v_lshl_add_u64 v[66:67], s[0:1], 0, v[66:67]
	v_lshl_add_u64 v[66:67], v[66:67], 0, v[134:135]
	global_load_dwordx2 v[78:79], v[66:67], off offset:2048
	v_lshlrev_b64 v[72:73], 11, v[64:65]
	v_lshl_add_u64 v[64:65], s[4:5], 0, v[72:73]
	v_lshl_add_u64 v[136:137], v[64:65], 0, v[134:135]
	global_load_dwordx2 v[80:81], v[136:137], off
	global_load_dwordx2 v[76:77], v[66:67], off offset:2080
	global_load_dwordx2 v[74:75], v[136:137], off offset:32
	global_load_dwordx2 v[70:71], v[66:67], off offset:2304
	global_load_dwordx2 v[68:69], v[136:137], off offset:256
	global_load_dwordx2 v[64:65], v[66:67], off offset:2336
	s_nop 0
	global_load_dwordx2 v[66:67], v[136:137], off offset:288
	s_waitcnt vmcnt(0)
; __device__ __forceinline__ unsigned cvt_pk_bf16(float lo, float hi) { unsigned r; asm volatile("s_nop 0\n\tv_cvt_pk_bf16_f32 %0, %1, %2\n\ts_nop 1" : "=v"(r) : "v"(lo), "v"(hi)); return r; }
; __device__ __forceinline__ float bflo(unsigned w) { return __uint_as_float(w << 16); }
; __device__ __forceinline__ float bfhi(unsigned w) { return __uint_as_float(w & 0xffff0000u); }
;     __device__ __forceinline__ void operator()(f32x4 (&acc)[2][2][4][2], const Unit& u, int wr, int wc, int fr, int fq) const {
;     ...
;             for (int m = 0; m < 4; ++m) { const size_t row = row0 + ai * 128 + m * 16;
; #pragma unroll
;                 for (int bj = 0; bj < 2; ++bj)
; #pragma unroll
;                     for (int n = 0; n < 2; ++n) { const int col = col0 + bj * 128 + n * 16; const u32x2 g2 = gw[m][bj][n], t2 = tw[m][bj][n];
;                         const f32x4 gv = (f32x4){bflo(g2.x), bfhi(g2.x), bflo(g2.y), bfhi(g2.y)};
;                         const f32x4 o = (f32x4){bflo(t2.x), bfhi(t2.x), bflo(t2.y), bfhi(t2.y)} + gv * acc[ai][bj][m][n];
;                         u32x2 w; w.x = cvt_pk_bf16(o[0], o[1]); w.y = cvt_pk_bf16(o[2], o[3]); *(u32x2*)(merged + row * 1024 + col) = w; } }
	v_lshlrev_b32_e32 v146, 16, v118
	v_and_b32_e32 v147, 0xffff0000, v118
	v_lshlrev_b32_e32 v136, 16, v116
	v_and_b32_e32 v137, 0xffff0000, v116
	v_lshlrev_b32_e32 v116, 16, v117
	v_and_b32_e32 v117, 0xffff0000, v117
	v_lshlrev_b32_e32 v118, 16, v119
	v_and_b32_e32 v119, 0xffff0000, v119
	v_pk_fma_f32 v[62:63], v[62:63], v[116:117], v[118:119]
	v_pk_fma_f32 v[60:61], v[60:61], v[136:137], v[146:147]
	v_lshlrev_b32_e32 v116, 16, v122
	v_cvt_pk_bf16_f32 v60, v60, v61
	v_cvt_pk_bf16_f32 v61, v62, v63
	v_lshl_add_u64 v[62:63], s[6:7], 0, v[114:115]
	v_lshl_add_u64 v[62:63], v[62:63], 0, v[134:135]
	global_store_dwordx2 v[62:63], v[60:61], off
	v_lshlrev_b32_e32 v60, 16, v120
	v_and_b32_e32 v61, 0xffff0000, v120
	v_and_b32_e32 v117, 0xffff0000, v122
	v_lshlrev_b32_e32 v114, 16, v121
	v_and_b32_e32 v115, 0xffff0000, v121
	v_lshlrev_b32_e32 v118, 16, v123
	v_and_b32_e32 v119, 0xffff0000, v123
	v_pk_fma_f32 v[56:57], v[56:57], v[60:61], v[116:117]
	v_pk_fma_f32 v[58:59], v[58:59], v[114:115], v[118:119]
	v_cvt_pk_bf16_f32 v56, v56, v57
	v_lshlrev_b32_e32 v60, 16, v126
	v_cvt_pk_bf16_f32 v57, v58, v59
	global_store_dwordx2 v[62:63], v[56:57], off offset:32
	v_lshlrev_b32_e32 v56, 16, v124
	v_and_b32_e32 v57, 0xffff0000, v124
	v_and_b32_e32 v61, 0xffff0000, v126
	v_lshlrev_b32_e32 v58, 16, v125
	v_and_b32_e32 v59, 0xffff0000, v125
	v_lshlrev_b32_e32 v114, 16, v127
	v_and_b32_e32 v115, 0xffff0000, v127
	v_pk_fma_f32 v[52:53], v[52:53], v[56:57], v[60:61]
	v_pk_fma_f32 v[54:55], v[54:55], v[58:59], v[114:115]
	v_cvt_pk_bf16_f32 v52, v52, v53
	v_lshlrev_b32_e32 v56, 16, v140
	v_cvt_pk_bf16_f32 v53, v54, v55
	global_store_dwordx2 v[62:63], v[52:53], off offset:256
	v_lshlrev_b32_e32 v52, 16, v138
	v_and_b32_e32 v53, 0xffff0000, v138
	v_and_b32_e32 v57, 0xffff0000, v140
	v_lshlrev_b32_e32 v54, 16, v139
	v_and_b32_e32 v55, 0xffff0000, v139
	v_lshlrev_b32_e32 v58, 16, v141
	v_and_b32_e32 v59, 0xffff0000, v141
	v_pk_fma_f32 v[48:49], v[48:49], v[52:53], v[56:57]
	v_pk_fma_f32 v[50:51], v[50:51], v[54:55], v[58:59]
	v_cvt_pk_bf16_f32 v48, v48, v49
	v_lshlrev_b32_e32 v52, 16, v144
	v_cvt_pk_bf16_f32 v49, v50, v51
	global_store_dwordx2 v[62:63], v[48:49], off offset:288
	v_lshlrev_b32_e32 v48, 16, v142
	v_and_b32_e32 v49, 0xffff0000, v142
	v_lshlrev_b32_e32 v50, 16, v143
	v_and_b32_e32 v51, 0xffff0000, v143
	v_and_b32_e32 v53, 0xffff0000, v144
	v_lshlrev_b32_e32 v54, 16, v145
	v_and_b32_e32 v55, 0xffff0000, v145
	v_pk_fma_f32 v[46:47], v[46:47], v[50:51], v[54:55]
	v_pk_fma_f32 v[44:45], v[44:45], v[48:49], v[52:53]
	v_lshlrev_b32_e32 v50, 16, v110
	v_cvt_pk_bf16_f32 v44, v44, v45
	v_cvt_pk_bf16_f32 v45, v46, v47
	v_lshl_add_u64 v[46:47], s[6:7], 0, v[108:109]
	v_lshl_add_u64 v[46:47], v[46:47], 0, v[134:135]
	global_store_dwordx2 v[46:47], v[44:45], off
	v_lshlrev_b32_e32 v44, 16, v112
	v_and_b32_e32 v45, 0xffff0000, v112
	v_and_b32_e32 v51, 0xffff0000, v110
	v_lshlrev_b32_e32 v48, 16, v113
	v_and_b32_e32 v49, 0xffff0000, v113
	v_lshlrev_b32_e32 v52, 16, v111
	v_and_b32_e32 v53, 0xffff0000, v111
	v_pk_fma_f32 v[40:41], v[40:41], v[44:45], v[50:51]
	v_pk_fma_f32 v[42:43], v[42:43], v[48:49], v[52:53]
	v_cvt_pk_bf16_f32 v40, v40, v41
	v_lshlrev_b32_e32 v44, 16, v104
	v_cvt_pk_bf16_f32 v41, v42, v43
	global_store_dwordx2 v[46:47], v[40:41], off offset:32
	v_lshlrev_b32_e32 v40, 16, v106
	v_and_b32_e32 v41, 0xffff0000, v106
	v_and_b32_e32 v45, 0xffff0000, v104
	v_lshlrev_b32_e32 v42, 16, v107
	v_and_b32_e32 v43, 0xffff0000, v107
	v_lshlrev_b32_e32 v48, 16, v105
	v_and_b32_e32 v49, 0xffff0000, v105
	v_pk_fma_f32 v[36:37], v[36:37], v[40:41], v[44:45]
	v_pk_fma_f32 v[38:39], v[38:39], v[42:43], v[48:49]
	v_cvt_pk_bf16_f32 v36, v36, v37
	v_lshlrev_b32_e32 v40, 16, v102
	v_cvt_pk_bf16_f32 v37, v38, v39
	global_store_dwordx2 v[46:47], v[36:37], off offset:256
	v_lshlrev_b32_e32 v36, 16, v100
	v_and_b32_e32 v37, 0xffff0000, v100
	v_and_b32_e32 v41, 0xffff0000, v102
	v_lshlrev_b32_e32 v38, 16, v101
	v_and_b32_e32 v39, 0xffff0000, v101
	v_lshlrev_b32_e32 v42, 16, v103
	v_and_b32_e32 v43, 0xffff0000, v103
	v_pk_fma_f32 v[32:33], v[32:33], v[36:37], v[40:41]
	v_pk_fma_f32 v[34:35], v[34:35], v[38:39], v[42:43]
	v_cvt_pk_bf16_f32 v32, v32, v33
	v_lshlrev_b32_e32 v36, 16, v98
	v_cvt_pk_bf16_f32 v33, v34, v35
; __device__ __forceinline__ unsigned cvt_pk_bf16(float lo, float hi) { unsigned r; asm volatile("s_nop 0\n\tv_cvt_pk_bf16_f32 %0, %1, %2\n\ts_nop 1" : "=v"(r) : "v"(lo), "v"(hi)); return r; }
; __device__ __forceinline__ float bflo(unsigned w) { return __uint_as_float(w << 16); }
; __device__ __forceinline__ float bfhi(unsigned w) { return __uint_as_float(w & 0xffff0000u); }
;     __device__ __forceinline__ void operator()(f32x4 (&acc)[2][2][4][2], const Unit& u, int wr, int wc, int fr, int fq) const {
;     ...
;             for (int m = 0; m < 4; ++m) { const size_t row = row0 + ai * 128 + m * 16;
; #pragma unroll
;                 for (int bj = 0; bj < 2; ++bj)
; #pragma unroll
;                     for (int n = 0; n < 2; ++n) { const int col = col0 + bj * 128 + n * 16; const u32x2 g2 = gw[m][bj][n], t2 = tw[m][bj][n];
;                         const f32x4 gv = (f32x4){bflo(g2.x), bfhi(g2.x), bflo(g2.y), bfhi(g2.y)};
;                         const f32x4 o = (f32x4){bflo(t2.x), bfhi(t2.x), bflo(t2.y), bfhi(t2.y)} + gv * acc[ai][bj][m][n];
;                         u32x2 w; w.x = cvt_pk_bf16(o[0], o[1]); w.y = cvt_pk_bf16(o[2], o[3]); *(u32x2*)(merged + row * 1024 + col) = w; } }
	global_store_dwordx2 v[46:47], v[32:33], off offset:288
	v_lshlrev_b32_e32 v32, 16, v96
	v_and_b32_e32 v33, 0xffff0000, v96
	v_lshlrev_b32_e32 v34, 16, v97
	v_and_b32_e32 v35, 0xffff0000, v97
	v_and_b32_e32 v37, 0xffff0000, v98
	v_lshlrev_b32_e32 v38, 16, v99
	v_and_b32_e32 v39, 0xffff0000, v99
	v_pk_fma_f32 v[30:31], v[30:31], v[34:35], v[38:39]
	v_pk_fma_f32 v[28:29], v[28:29], v[32:33], v[36:37]
	v_lshlrev_b32_e32 v34, 16, v92
	v_cvt_pk_bf16_f32 v28, v28, v29
	v_cvt_pk_bf16_f32 v29, v30, v31
	v_lshl_add_u64 v[30:31], s[6:7], 0, v[90:91]
	v_lshl_add_u64 v[30:31], v[30:31], 0, v[134:135]
	global_store_dwordx2 v[30:31], v[28:29], off
	v_lshlrev_b32_e32 v28, 16, v94
	v_and_b32_e32 v29, 0xffff0000, v94
	v_and_b32_e32 v35, 0xffff0000, v92
	v_lshlrev_b32_e32 v32, 16, v95
	v_and_b32_e32 v33, 0xffff0000, v95
	v_lshlrev_b32_e32 v36, 16, v93
	v_and_b32_e32 v37, 0xffff0000, v93
	v_pk_fma_f32 v[24:25], v[24:25], v[28:29], v[34:35]
	v_pk_fma_f32 v[26:27], v[26:27], v[32:33], v[36:37]
	v_cvt_pk_bf16_f32 v24, v24, v25
	v_lshlrev_b32_e32 v28, 16, v86
	v_cvt_pk_bf16_f32 v25, v26, v27
	global_store_dwordx2 v[30:31], v[24:25], off offset:32
	v_lshlrev_b32_e32 v24, 16, v88
	v_and_b32_e32 v25, 0xffff0000, v88
	v_and_b32_e32 v29, 0xffff0000, v86
	v_lshlrev_b32_e32 v26, 16, v89
	v_and_b32_e32 v27, 0xffff0000, v89
	v_lshlrev_b32_e32 v32, 16, v87
	v_and_b32_e32 v33, 0xffff0000, v87
	v_pk_fma_f32 v[20:21], v[20:21], v[24:25], v[28:29]
	v_pk_fma_f32 v[22:23], v[22:23], v[26:27], v[32:33]
	v_cvt_pk_bf16_f32 v20, v20, v21
	v_lshlrev_b32_e32 v24, 16, v84
	v_cvt_pk_bf16_f32 v21, v22, v23
	global_store_dwordx2 v[30:31], v[20:21], off offset:256
	v_lshlrev_b32_e32 v20, 16, v82
	v_and_b32_e32 v21, 0xffff0000, v82
	v_and_b32_e32 v25, 0xffff0000, v84
	v_lshlrev_b32_e32 v22, 16, v83
	v_and_b32_e32 v23, 0xffff0000, v83
	v_lshlrev_b32_e32 v26, 16, v85
	v_and_b32_e32 v27, 0xffff0000, v85
	v_pk_fma_f32 v[16:17], v[16:17], v[20:21], v[24:25]
	v_pk_fma_f32 v[18:19], v[18:19], v[22:23], v[26:27]
	v_cvt_pk_bf16_f32 v16, v16, v17
	v_lshlrev_b32_e32 v20, 16, v80
	v_cvt_pk_bf16_f32 v17, v18, v19
	global_store_dwordx2 v[30:31], v[16:17], off offset:288
	v_lshlrev_b32_e32 v16, 16, v78
	v_and_b32_e32 v17, 0xffff0000, v78
	v_lshlrev_b32_e32 v18, 16, v79
	v_and_b32_e32 v19, 0xffff0000, v79
	v_and_b32_e32 v21, 0xffff0000, v80
	v_lshlrev_b32_e32 v22, 16, v81
	v_and_b32_e32 v23, 0xffff0000, v81
	v_pk_fma_f32 v[14:15], v[14:15], v[18:19], v[22:23]
	v_pk_fma_f32 v[12:13], v[12:13], v[16:17], v[20:21]
	v_lshlrev_b32_e32 v18, 16, v74
	v_cvt_pk_bf16_f32 v12, v12, v13
	v_cvt_pk_bf16_f32 v13, v14, v15
	v_lshl_add_u64 v[14:15], s[6:7], 0, v[72:73]
	v_lshl_add_u64 v[14:15], v[14:15], 0, v[134:135]
	global_store_dwordx2 v[14:15], v[12:13], off
	v_lshlrev_b32_e32 v12, 16, v76
	v_and_b32_e32 v13, 0xffff0000, v76
	v_and_b32_e32 v19, 0xffff0000, v74
	v_lshlrev_b32_e32 v16, 16, v77
	v_and_b32_e32 v17, 0xffff0000, v77
	v_lshlrev_b32_e32 v20, 16, v75
	v_and_b32_e32 v21, 0xffff0000, v75
	v_pk_fma_f32 v[8:9], v[8:9], v[12:13], v[18:19]
	v_pk_fma_f32 v[10:11], v[10:11], v[16:17], v[20:21]
	v_cvt_pk_bf16_f32 v8, v8, v9
	v_lshlrev_b32_e32 v12, 16, v68
	v_cvt_pk_bf16_f32 v9, v10, v11
	global_store_dwordx2 v[14:15], v[8:9], off offset:32
	v_lshlrev_b32_e32 v8, 16, v70
	v_and_b32_e32 v9, 0xffff0000, v70
	v_and_b32_e32 v13, 0xffff0000, v68
	v_lshlrev_b32_e32 v10, 16, v71
	v_and_b32_e32 v11, 0xffff0000, v71
	v_lshlrev_b32_e32 v16, 16, v69
	v_and_b32_e32 v17, 0xffff0000, v69
	v_pk_fma_f32 v[4:5], v[4:5], v[8:9], v[12:13]
	v_pk_fma_f32 v[6:7], v[6:7], v[10:11], v[16:17]
	v_cvt_pk_bf16_f32 v4, v4, v5
	v_lshlrev_b32_e32 v8, 16, v66
	v_cvt_pk_bf16_f32 v5, v6, v7
	global_store_dwordx2 v[14:15], v[4:5], off offset:256
	v_lshlrev_b32_e32 v4, 16, v64
	v_and_b32_e32 v5, 0xffff0000, v64
	v_and_b32_e32 v9, 0xffff0000, v66
	v_lshlrev_b32_e32 v6, 16, v65
	v_and_b32_e32 v7, 0xffff0000, v65
	v_lshlrev_b32_e32 v10, 16, v67
	v_and_b32_e32 v11, 0xffff0000, v67
	v_pk_fma_f32 v[0:1], v[0:1], v[4:5], v[8:9]
	v_pk_fma_f32 v[2:3], v[2:3], v[6:7], v[10:11]
	v_cvt_pk_bf16_f32 v0, v0, v1
	s_nop 0
	v_cvt_pk_bf16_f32 v1, v2, v3
	s_nop 1
	global_store_dwordx2 v[14:15], v[0:1], off offset:288
	s_cbranch_vccz .LBB0_363
	s_waitcnt vmcnt(0)
	s_cmpk_gt_u32 s24, 0xff
	s_cbranch_scc1 .LBB0_374
	s_barrier

; __device__ __forceinline__ unsigned cvt_pk_bf16(float lo, float hi) { unsigned r; asm volatile("s_nop 0\n\tv_cvt_pk_bf16_f32 %0, %1, %2\n\ts_nop 1" : "=v"(r) : "v"(lo), "v"(hi)); return r; }
; #define LAS __attribute__((address_space(3)))
; #define LDS_FENCE() asm volatile("s_waitcnt lgkmcnt(0)" ::: "memory")
;     __device__ __forceinline__ void operator()(f32x4 (&acc)[2][2][4][2], const Unit& u, int wr, int wc, int fr, int fq) const {
;     ...
;             LDS_FENCE(); __builtin_amdgcn_s_barrier(); asm volatile("" ::: "memory");
; #pragma unroll
;             for (int ai = 0; ai < 2; ++ai)
; #pragma unroll
;                 for (int m = 0; m < 4; ++m) { const f32x4 s4 = *(const LAS f32x4*)(xb + (ai * 128 + m * 16) * 4);
;                     const float rstd = __builtin_amdgcn_rsqf(((s4.x + s4.y) + (s4.z + s4.w)) * (1.f / 256.f) + 1e-5f);
; #pragma unroll
;                     for (int bj = 0; bj < 2; ++bj) { const size_t idx = (size_t)(row0 + ai * 128 + m * 16) * 2048 + u.pn * 256 + bj * 128 + c8;
;                         const f32x4 v0 = acc[ai][bj][m][0] * rstd, v1 = acc[ai][bj][m][1] * rstd;
;                         u32x4 w; w.x = cvt_pk_bf16(v0[0], v0[1]); w.y = cvt_pk_bf16(v0[2], v0[3]); w.z = cvt_pk_bf16(v1[0], v1[1]); w.w = cvt_pk_bf16(v1[2], v1[3]);
;                         *(u32x4*)(y1 + idx) = w; } }
.LBB0_383:
	s_or_b64 exec, exec, s[24:25]
	s_waitcnt lgkmcnt(0)
	s_barrier
	s_waitcnt lgkmcnt(0)
	ds_read_b128 v[64:67], v199
	v_lshlrev_b64 v[70:71], 12, v[214:215]
	v_lshl_add_u64 v[70:71], s[6:7], 0, v[70:71]
	s_lshl_b64 s[0:1], s[0:1], 1
	v_lshl_add_u64 v[70:71], v[70:71], 0, s[0:1]
	s_waitcnt lgkmcnt(0)
	v_mov_b32_e32 v68, v65
	v_mov_b32_e32 v69, v66
	v_mov_b32_e32 v65, v67
	v_pk_add_f32 v[64:65], v[68:69], v[64:65]
	v_lshlrev_b32_e32 v192, 1, v208
	v_add_f32_e32 v64, v64, v65
	v_fmamk_f32 v64, v64, 0x3b800000, v236
	v_rsq_f32_e32 v68, v64
	s_nop 0
	v_pk_mul_f32 v[66:67], v[184:185], v[68:69] op_sel_hi:[1,0]
	v_pk_mul_f32 v[64:65], v[222:223], v[68:69] op_sel_hi:[1,0]
	v_pk_mul_f32 v[72:73], v[186:187], v[68:69] op_sel_hi:[1,0]
	v_pk_mul_f32 v[74:75], v[188:189], v[68:69] op_sel_hi:[1,0]
	v_cvt_pk_bf16_f32 v64, v64, v65
	v_cvt_pk_bf16_f32 v65, v66, v67
	s_nop 0
	v_cvt_pk_bf16_f32 v66, v74, v75
	v_cvt_pk_bf16_f32 v67, v72, v73
	v_lshl_add_u64 v[72:73], v[70:71], 0, v[192:193]
	global_store_dwordx4 v[72:73], v[64:67], off
	v_pk_mul_f32 v[70:71], v[178:179], v[68:69] op_sel_hi:[1,0]
	s_nop 0
	v_pk_mul_f32 v[66:67], v[176:177], v[68:69] op_sel_hi:[1,0]
	v_pk_mul_f32 v[64:65], v[190:191], v[68:69] op_sel_hi:[1,0]
	v_pk_mul_f32 v[68:69], v[180:181], v[68:69] op_sel_hi:[1,0]
	v_cvt_pk_bf16_f32 v64, v64, v65
	v_cvt_pk_bf16_f32 v65, v66, v67
	s_nop 0
	v_cvt_pk_bf16_f32 v66, v68, v69
	v_cvt_pk_bf16_f32 v67, v70, v71
	ds_read_b128 v[68:71], v199 offset:256
	global_store_dwordx4 v[72:73], v[64:67], off offset:256
	s_waitcnt lgkmcnt(0)
	v_mov_b32_e32 v74, v69
	v_mov_b32_e32 v75, v70
	v_mov_b32_e32 v69, v71
	v_pk_add_f32 v[68:69], v[74:75], v[68:69]
	v_lshlrev_b64 v[70:71], 12, v[216:217]
	v_add_f32_e32 v68, v68, v69
	v_fmamk_f32 v68, v68, 0x3b800000, v236
	v_rsq_f32_e32 v68, v68
	v_lshl_add_u64 v[70:71], s[6:7], 0, v[70:71]
	v_lshl_add_u64 v[70:71], v[70:71], 0, s[0:1]
	v_pk_mul_f32 v[66:67], v[168:169], v[68:69] op_sel_hi:[1,0]
	v_pk_mul_f32 v[64:65], v[182:183], v[68:69] op_sel_hi:[1,0]
	v_pk_mul_f32 v[72:73], v[170:171], v[68:69] op_sel_hi:[1,0]
	v_pk_mul_f32 v[74:75], v[172:173], v[68:69] op_sel_hi:[1,0]
	v_cvt_pk_bf16_f32 v64, v64, v65
	v_cvt_pk_bf16_f32 v65, v66, v67
	s_nop 0
	v_cvt_pk_bf16_f32 v66, v74, v75
	v_cvt_pk_bf16_f32 v67, v72, v73
	v_lshl_add_u64 v[72:73], v[70:71], 0, v[192:193]
	global_store_dwordx4 v[72:73], v[64:67], off
	v_pk_mul_f32 v[70:71], v[162:163], v[68:69] op_sel_hi:[1,0]
	s_nop 0
	v_pk_mul_f32 v[66:67], v[160:161], v[68:69] op_sel_hi:[1,0]
	v_pk_mul_f32 v[64:65], v[174:175], v[68:69] op_sel_hi:[1,0]
	v_pk_mul_f32 v[68:69], v[164:165], v[68:69] op_sel_hi:[1,0]
	v_cvt_pk_bf16_f32 v64, v64, v65
	v_cvt_pk_bf16_f32 v65, v66, v67
	s_nop 0
	v_cvt_pk_bf16_f32 v66, v68, v69
	v_cvt_pk_bf16_f32 v67, v70, v71
	ds_read_b128 v[68:71], v199 offset:512
	global_store_dwordx4 v[72:73], v[64:67], off offset:256
	s_waitcnt lgkmcnt(0)
	v_mov_b32_e32 v74, v69
	v_mov_b32_e32 v75, v70
	v_mov_b32_e32 v69, v71
	v_pk_add_f32 v[68:69], v[74:75], v[68:69]
	v_lshlrev_b64 v[70:71], 12, v[218:219]
	v_add_f32_e32 v68, v68, v69
	v_fmamk_f32 v68, v68, 0x3b800000, v236
	v_rsq_f32_e32 v68, v68
	v_lshl_add_u64 v[70:71], s[6:7], 0, v[70:71]
	v_lshl_add_u64 v[70:71], v[70:71], 0, s[0:1]
	v_pk_mul_f32 v[66:67], v[152:153], v[68:69] op_sel_hi:[1,0]
	v_pk_mul_f32 v[64:65], v[166:167], v[68:69] op_sel_hi:[1,0]
	v_pk_mul_f32 v[72:73], v[154:155], v[68:69] op_sel_hi:[1,0]
	v_pk_mul_f32 v[74:75], v[156:157], v[68:69] op_sel_hi:[1,0]
	v_cvt_pk_bf16_f32 v64, v64, v65
	v_cvt_pk_bf16_f32 v65, v66, v67
	s_nop 0
	v_cvt_pk_bf16_f32 v66, v74, v75
	v_cvt_pk_bf16_f32 v67, v72, v73
	v_lshl_add_u64 v[72:73], v[70:71], 0, v[192:193]
	global_store_dwordx4 v[72:73], v[64:67], off
	v_pk_mul_f32 v[70:71], v[146:147], v[68:69] op_sel_hi:[1,0]
	s_nop 0
	v_pk_mul_f32 v[66:67], v[144:145], v[68:69] op_sel_hi:[1,0]
	v_pk_mul_f32 v[64:65], v[158:159], v[68:69] op_sel_hi:[1,0]
	v_pk_mul_f32 v[68:69], v[148:149], v[68:69] op_sel_hi:[1,0]
	v_cvt_pk_bf16_f32 v64, v64, v65
	v_cvt_pk_bf16_f32 v65, v66, v67
	s_nop 0
	v_cvt_pk_bf16_f32 v66, v68, v69
	v_cvt_pk_bf16_f32 v67, v70, v71
	ds_read_b128 v[68:71], v199 offset:768
	global_store_dwordx4 v[72:73], v[64:67], off offset:256
	s_waitcnt lgkmcnt(0)
	v_mov_b32_e32 v74, v69
	v_mov_b32_e32 v75, v70
	v_mov_b32_e32 v69, v71
	v_pk_add_f32 v[68:69], v[74:75], v[68:69]
	v_lshlrev_b64 v[70:71], 12, v[220:221]
	v_add_f32_e32 v68, v68, v69
	v_fmamk_f32 v68, v68, 0x3b800000, v236
	v_rsq_f32_e32 v68, v68
	v_lshl_add_u64 v[70:71], s[6:7], 0, v[70:71]
	v_lshl_add_u64 v[70:71], v[70:71], 0, s[0:1]
	v_pk_mul_f32 v[66:67], v[136:137], v[68:69] op_sel_hi:[1,0]
	v_pk_mul_f32 v[64:65], v[150:151], v[68:69] op_sel_hi:[1,0]
	v_pk_mul_f32 v[72:73], v[138:139], v[68:69] op_sel_hi:[1,0]
	v_pk_mul_f32 v[74:75], v[140:141], v[68:69] op_sel_hi:[1,0]
	v_cvt_pk_bf16_f32 v64, v64, v65
	v_cvt_pk_bf16_f32 v65, v66, v67
	s_nop 0
	v_cvt_pk_bf16_f32 v66, v74, v75
	v_cvt_pk_bf16_f32 v67, v72, v73
	v_lshl_add_u64 v[72:73], v[70:71], 0, v[192:193]
	global_store_dwordx4 v[72:73], v[64:67], off
	v_pk_mul_f32 v[70:71], v[226:227], v[68:69] op_sel_hi:[1,0]
	s_nop 0
	v_pk_mul_f32 v[66:67], v[128:129], v[68:69] op_sel_hi:[1,0]
	v_pk_mul_f32 v[64:65], v[142:143], v[68:69] op_sel_hi:[1,0]
	v_pk_mul_f32 v[68:69], v[132:133], v[68:69] op_sel_hi:[1,0]
	v_cvt_pk_bf16_f32 v64, v64, v65
	v_cvt_pk_bf16_f32 v65, v66, v67
	s_nop 0
	v_cvt_pk_bf16_f32 v66, v68, v69
	v_cvt_pk_bf16_f32 v67, v70, v71
	ds_read_b128 v[68:71], v199 offset:2048
	global_store_dwordx4 v[72:73], v[64:67], off offset:256
	s_waitcnt lgkmcnt(0)
; __device__ __forceinline__ unsigned cvt_pk_bf16(float lo, float hi) { unsigned r; asm volatile("s_nop 0\n\tv_cvt_pk_bf16_f32 %0, %1, %2\n\ts_nop 1" : "=v"(r) : "v"(lo), "v"(hi)); return r; }
; #define LAS __attribute__((address_space(3)))
;     __device__ __forceinline__ void operator()(f32x4 (&acc)[2][2][4][2], const Unit& u, int wr, int wc, int fr, int fq) const {
;     ...
; #pragma unroll
;             for (int ai = 0; ai < 2; ++ai)
; #pragma unroll
;                 for (int m = 0; m < 4; ++m) { const f32x4 s4 = *(const LAS f32x4*)(xb + (ai * 128 + m * 16) * 4);
;                     const float rstd = __builtin_amdgcn_rsqf(((s4.x + s4.y) + (s4.z + s4.w)) * (1.f / 256.f) + 1e-5f);
; #pragma unroll
;                     for (int bj = 0; bj < 2; ++bj) { const size_t idx = (size_t)(row0 + ai * 128 + m * 16) * 2048 + u.pn * 256 + bj * 128 + c8;
;                         const f32x4 v0 = acc[ai][bj][m][0] * rstd, v1 = acc[ai][bj][m][1] * rstd;
;                         u32x4 w; w.x = cvt_pk_bf16(v0[0], v0[1]); w.y = cvt_pk_bf16(v0[2], v0[3]); w.z = cvt_pk_bf16(v1[0], v1[1]); w.w = cvt_pk_bf16(v1[2], v1[3]);
;                         *(u32x4*)(y1 + idx) = w; } }
	v_mov_b32_e32 v74, v69
	v_mov_b32_e32 v75, v70
	v_mov_b32_e32 v69, v71
	v_pk_add_f32 v[68:69], v[74:75], v[68:69]
	v_lshlrev_b64 v[64:65], 12, v[224:225]
	v_add_f32_e32 v68, v68, v69
	v_fmamk_f32 v68, v68, 0x3b800000, v236
	v_rsq_f32_e32 v68, v68
	s_nop 0
	v_pk_mul_f32 v[60:61], v[60:61], v[68:69] op_sel_hi:[1,0]
	v_pk_mul_f32 v[66:67], v[58:59], v[68:69] op_sel_hi:[1,0]
	v_pk_mul_f32 v[58:59], v[56:57], v[68:69] op_sel_hi:[1,0]
	v_cvt_pk_bf16_f32 v56, v60, v61
	v_lshl_add_u64 v[60:61], s[6:7], 0, v[64:65]
	v_lshl_add_u64 v[60:61], v[60:61], 0, s[0:1]
	v_pk_mul_f32 v[62:63], v[62:63], v[68:69] op_sel_hi:[1,0]
	v_lshl_add_u64 v[60:61], v[60:61], 0, v[192:193]
	v_cvt_pk_bf16_f32 v57, v62, v63
	v_cvt_pk_bf16_f32 v58, v58, v59
	v_cvt_pk_bf16_f32 v59, v66, v67
	global_store_dwordx4 v[60:61], v[56:59], off
	v_pk_mul_f32 v[54:55], v[54:55], v[68:69] op_sel_hi:[1,0]
	v_pk_mul_f32 v[52:53], v[52:53], v[68:69] op_sel_hi:[1,0]
	v_pk_mul_f32 v[56:57], v[50:51], v[68:69] op_sel_hi:[1,0]
	v_pk_mul_f32 v[50:51], v[48:49], v[68:69] op_sel_hi:[1,0]
	v_cvt_pk_bf16_f32 v48, v52, v53
	v_cvt_pk_bf16_f32 v49, v54, v55
	s_nop 0
	v_cvt_pk_bf16_f32 v50, v50, v51
	v_cvt_pk_bf16_f32 v51, v56, v57
	ds_read_b128 v[52:55], v199 offset:2304
	global_store_dwordx4 v[60:61], v[48:51], off offset:256
	s_waitcnt lgkmcnt(0)
	v_mov_b32_e32 v56, v53
	v_mov_b32_e32 v57, v54
	v_mov_b32_e32 v53, v55
	v_pk_add_f32 v[52:53], v[56:57], v[52:53]
	v_lshlrev_b64 v[48:49], 12, v[130:131]
	v_add_f32_e32 v52, v52, v53
	v_fmamk_f32 v52, v52, 0x3b800000, v236
	v_rsq_f32_e32 v52, v52
	s_nop 0
	v_pk_mul_f32 v[44:45], v[44:45], v[52:53] op_sel_hi:[1,0]
	v_pk_mul_f32 v[50:51], v[42:43], v[52:53] op_sel_hi:[1,0]
	v_pk_mul_f32 v[42:43], v[40:41], v[52:53] op_sel_hi:[1,0]
	v_cvt_pk_bf16_f32 v40, v44, v45
	v_lshl_add_u64 v[44:45], s[6:7], 0, v[48:49]
	v_lshl_add_u64 v[44:45], v[44:45], 0, s[0:1]
	v_pk_mul_f32 v[46:47], v[46:47], v[52:53] op_sel_hi:[1,0]
	v_lshl_add_u64 v[44:45], v[44:45], 0, v[192:193]
	v_cvt_pk_bf16_f32 v41, v46, v47
	v_cvt_pk_bf16_f32 v42, v42, v43
	v_cvt_pk_bf16_f32 v43, v50, v51
	global_store_dwordx4 v[44:45], v[40:43], off
	v_pk_mul_f32 v[38:39], v[38:39], v[52:53] op_sel_hi:[1,0]
	v_pk_mul_f32 v[36:37], v[36:37], v[52:53] op_sel_hi:[1,0]
	v_pk_mul_f32 v[40:41], v[34:35], v[52:53] op_sel_hi:[1,0]
	v_pk_mul_f32 v[34:35], v[32:33], v[52:53] op_sel_hi:[1,0]
	v_cvt_pk_bf16_f32 v32, v36, v37
	v_cvt_pk_bf16_f32 v33, v38, v39
	s_nop 0
	v_cvt_pk_bf16_f32 v34, v34, v35
	v_cvt_pk_bf16_f32 v35, v40, v41
	ds_read_b128 v[36:39], v199 offset:2560
	global_store_dwordx4 v[44:45], v[32:35], off offset:256
	s_waitcnt lgkmcnt(0)
	v_mov_b32_e32 v40, v37
	v_mov_b32_e32 v41, v38
	v_mov_b32_e32 v37, v39
	v_pk_add_f32 v[36:37], v[40:41], v[36:37]
	v_lshlrev_b64 v[32:33], 12, v[134:135]
	v_add_f32_e32 v36, v36, v37
	v_fmamk_f32 v36, v36, 0x3b800000, v236
	v_rsq_f32_e32 v36, v36
	s_nop 0
	v_pk_mul_f32 v[28:29], v[28:29], v[36:37] op_sel_hi:[1,0]
	v_pk_mul_f32 v[34:35], v[26:27], v[36:37] op_sel_hi:[1,0]
	v_pk_mul_f32 v[26:27], v[24:25], v[36:37] op_sel_hi:[1,0]
	v_cvt_pk_bf16_f32 v24, v28, v29
	v_lshl_add_u64 v[28:29], s[6:7], 0, v[32:33]
	v_lshl_add_u64 v[28:29], v[28:29], 0, s[0:1]
	v_pk_mul_f32 v[30:31], v[30:31], v[36:37] op_sel_hi:[1,0]
	v_lshl_add_u64 v[28:29], v[28:29], 0, v[192:193]
	v_cvt_pk_bf16_f32 v25, v30, v31
	v_cvt_pk_bf16_f32 v26, v26, v27
	v_cvt_pk_bf16_f32 v27, v34, v35
	global_store_dwordx4 v[28:29], v[24:27], off
	v_pk_mul_f32 v[22:23], v[22:23], v[36:37] op_sel_hi:[1,0]
	v_pk_mul_f32 v[20:21], v[20:21], v[36:37] op_sel_hi:[1,0]
	v_pk_mul_f32 v[24:25], v[18:19], v[36:37] op_sel_hi:[1,0]
	v_pk_mul_f32 v[18:19], v[16:17], v[36:37] op_sel_hi:[1,0]
	v_cvt_pk_bf16_f32 v16, v20, v21
	v_cvt_pk_bf16_f32 v17, v22, v23
	s_nop 0
	v_cvt_pk_bf16_f32 v18, v18, v19
	v_cvt_pk_bf16_f32 v19, v24, v25
	ds_read_b128 v[20:23], v199 offset:2816
	global_store_dwordx4 v[28:29], v[16:19], off offset:256
	s_waitcnt lgkmcnt(0)
	v_mov_b32_e32 v24, v21
	v_mov_b32_e32 v25, v22
	v_mov_b32_e32 v21, v23
	v_pk_add_f32 v[20:21], v[24:25], v[20:21]
	v_lshlrev_b64 v[16:17], 12, v[228:229]
	v_add_f32_e32 v20, v20, v21
	v_fmamk_f32 v20, v20, 0x3b800000, v236
	v_rsq_f32_e32 v20, v20
	s_nop 0
	v_pk_mul_f32 v[12:13], v[12:13], v[20:21] op_sel_hi:[1,0]
	v_pk_mul_f32 v[18:19], v[10:11], v[20:21] op_sel_hi:[1,0]
	v_pk_mul_f32 v[10:11], v[8:9], v[20:21] op_sel_hi:[1,0]
	v_cvt_pk_bf16_f32 v8, v12, v13
	v_lshl_add_u64 v[12:13], s[6:7], 0, v[16:17]
	v_lshl_add_u64 v[12:13], v[12:13], 0, s[0:1]
	v_pk_mul_f32 v[14:15], v[14:15], v[20:21] op_sel_hi:[1,0]
	v_lshl_add_u64 v[12:13], v[12:13], 0, v[192:193]
	v_cvt_pk_bf16_f32 v9, v14, v15
	v_cvt_pk_bf16_f32 v10, v10, v11
	v_cvt_pk_bf16_f32 v11, v18, v19
	global_store_dwordx4 v[12:13], v[8:11], off
	v_pk_mul_f32 v[6:7], v[6:7], v[20:21] op_sel_hi:[1,0]
	v_pk_mul_f32 v[4:5], v[4:5], v[20:21] op_sel_hi:[1,0]
	v_pk_mul_f32 v[8:9], v[2:3], v[20:21] op_sel_hi:[1,0]
	v_pk_mul_f32 v[2:3], v[0:1], v[20:21] op_sel_hi:[1,0]
	v_cvt_pk_bf16_f32 v0, v4, v5
	v_cvt_pk_bf16_f32 v1, v6, v7
	s_nop 0
	v_cvt_pk_bf16_f32 v2, v2, v3
	v_cvt_pk_bf16_f32 v3, v8, v9
	s_nop 1
	global_store_dwordx4 v[12:13], v[0:3], off offset:256

; #define PG8_STAGE(bufoff, gbase, voff) do { _Pragma("unroll") for (int _i = 0; _i < 2; ++_i) \
;         __builtin_amdgcn_global_load_lds((const unsigned*)((const char*)(gbase) + (voff)[_i]), (PG8_LAS unsigned*)(lds + (bufoff) + ldsw + _i * 8192), 16, 0, 0); } while (0)
; #define PG8_LDA(dst, b, h) do { _Pragma("unroll") for (int m = 0; m < 4; ++m) _Pragma("unroll") for (int k = 0; k < 2; ++k) dst[m][k] = *(const PG8_LAS bf16x8*)(lds + PG8_SA(b, h) + aoff + m * 2048 + k * 1024); } while (0)
; #define PG8_LDB(dst, b, h) do { _Pragma("unroll") for (int n = 0; n < 2; ++n) _Pragma("unroll") for (int k = 0; k < 2; ++k) dst[n][k] = *(const PG8_LAS bf16x8*)(lds + PG8_SB(b, h) + boff + n * 2048 + k * 1024); } while (0)
; #define PG8_MMA(ai, bj, At, Bt) do { __builtin_amdgcn_s_setprio(1); _Pragma("unroll") for (int m = 0; m < 4; ++m) _Pragma("unroll") for (int n = 0; n < 2; ++n) _Pragma("unroll") for (int k = 0; k < 2; ++k) \
;         acc[ai][bj][m][n] = __builtin_amdgcn_mfma_f32_16x16x32_bf16(Bt[n][k], At[m][k], acc[ai][bj][m][n], 0, 0, 0); __builtin_amdgcn_s_setprio(0); } while (0)
; #define PG8_WAIT_L(n) asm volatile("s_waitcnt lgkmcnt(" #n ")" ::: "memory")
; #define PG8_BAR __builtin_amdgcn_s_barrier()
; #define PG8_SCHED __builtin_amdgcn_sched_barrier(0)
; template <class Epi, class Sched>
; __device__ __forceinline__ void gemm_phase(PG8_LAS unsigned char* lds, const Gemm g, const Sched& S, const Epi& E, int tid_in) {
;     ...
;             PG8_LDB(B0, 0, 0); PG8_SCHED; PG8_LDA(At, 0, 0); PG8_STAGE(PG8_SA(1, 1), a1 + hstep, voffA);
;             PG8_WAIT_L(8); PG8_BAR; PG8_WAIT_L(0); PG8_MMA(0, 0, At, B0); PG8_BAR; PG8_SCHED;
;             PG8_LDB(B1, 0, 1); PG8_STAGE(PG8_SB(0, 0), b2, voffB);
;             PG8_BAR; PG8_WAIT_L(0); PG8_MMA(0, 1, At, B1); PG8_BAR;
;             PG8_LDA(At, 0, 1); PG8_STAGE(PG8_SA(0, 0), a2, voffA);
;             PG8_BAR; PG8_WAIT_L(0); PG8_MMA(1, 0, At, B0); PG8_BAR; PG8_SCHED;
.LBB0_388:
	s_add_u32 s28, s26, 0xfffc0080
	s_addc_u32 s29, s27, -1
	s_add_i32 s38, 0, 0x10000
	v_add_u32_e32 v140, s38, v246
	ds_read_b128 v[128:131], v140
	ds_read_b128 v[132:135], v140 offset:1024
	ds_read_b128 v[136:139], v140 offset:2048
	ds_read_b128 v[140:143], v140 offset:3072
	s_cmp_eq_u32 s37, 12
	s_cselect_b32 s31, s1, s29
	s_cselect_b32 s30, s19, s28
	s_cselect_b32 s29, s17, s36
	s_cselect_b32 s28, s25, s33
	v_lshl_add_u64 v[176:177], s[26:27], 0, v[210:211]
	s_add_i32 m0, s73, 0xc000
	ds_read_b128 v[144:147], v251
	ds_read_b128 v[148:151], v251 offset:1024
	ds_read_b128 v[152:155], v251 offset:2048
	ds_read_b128 v[156:159], v251 offset:3072
	ds_read_b128 v[160:163], v251 offset:4096
	ds_read_b128 v[164:167], v251 offset:5120
	ds_read_b128 v[168:171], v251 offset:6144
	ds_read_b128 v[172:175], v251 offset:7168
	global_load_lds_dwordx4 v[176:177], off
	v_lshl_add_u64 v[176:177], s[26:27], 0, v[212:213]
	s_add_i32 m0, s73, 0xe000
	s_nop 0
	global_load_lds_dwordx4 v[176:177], off
	s_waitcnt lgkmcnt(8)
	s_barrier
	s_waitcnt lgkmcnt(0)
	s_setprio 1
	s_waitcnt lgkmcnt(0)
	v_mfma_f32_16x16x32_bf16 v[124:127], v[128:131], v[144:147], v[124:127]
	v_mfma_f32_16x16x32_bf16 v[120:123], v[136:139], v[144:147], v[120:123]
	v_mfma_f32_16x16x32_bf16 v[108:111], v[128:131], v[152:155], v[108:111]
	v_mfma_f32_16x16x32_bf16 v[104:107], v[136:139], v[152:155], v[104:107]
	v_mfma_f32_16x16x32_bf16 v[92:95], v[128:131], v[160:163], v[92:95]
	v_mfma_f32_16x16x32_bf16 v[88:91], v[136:139], v[160:163], v[88:91]
	v_mfma_f32_16x16x32_bf16 v[76:79], v[128:131], v[168:171], v[76:79]
	v_mfma_f32_16x16x32_bf16 v[72:75], v[136:139], v[168:171], v[72:75]
	v_mfma_f32_16x16x32_bf16 v[124:127], v[132:135], v[148:151], v[124:127]
	v_mfma_f32_16x16x32_bf16 v[120:123], v[140:143], v[148:151], v[120:123]
	v_mfma_f32_16x16x32_bf16 v[108:111], v[132:135], v[156:159], v[108:111]
	v_mfma_f32_16x16x32_bf16 v[104:107], v[140:143], v[156:159], v[104:107]
	v_mfma_f32_16x16x32_bf16 v[92:95], v[132:135], v[164:167], v[92:95]
	v_mfma_f32_16x16x32_bf16 v[88:91], v[140:143], v[164:167], v[88:91]
	v_mfma_f32_16x16x32_bf16 v[76:79], v[132:135], v[172:175], v[76:79]
	v_mfma_f32_16x16x32_bf16 v[72:75], v[140:143], v[172:175], v[72:75]
	s_setprio 0
	s_barrier
	s_add_i32 s40, 0, 0x14000
	s_add_i32 s38, s38, s72
	v_add_u32_e32 v188, s40, v246
	v_lshl_add_u64 v[194:195], s[28:29], 0, v[202:203]
	s_mov_b32 m0, s38
	ds_read_b128 v[176:179], v188
	ds_read_b128 v[180:183], v188 offset:1024
	ds_read_b128 v[184:187], v188 offset:2048
	ds_read_b128 v[188:191], v188 offset:3072
	global_load_lds_dwordx4 v[194:195], off
	v_lshl_add_u64 v[196:197], s[28:29], 0, v[206:207]
	s_add_i32 m0, s38, 0x2000
	s_nop 0
	global_load_lds_dwordx4 v[196:197], off
	s_barrier
	s_waitcnt lgkmcnt(0)
	s_setprio 1
	s_waitcnt lgkmcnt(0)
	v_mfma_f32_16x16x32_bf16 v[116:119], v[176:179], v[144:147], v[116:119]
	v_mfma_f32_16x16x32_bf16 v[112:115], v[184:187], v[144:147], v[112:115]
	v_mfma_f32_16x16x32_bf16 v[100:103], v[176:179], v[152:155], v[100:103]
	v_mfma_f32_16x16x32_bf16 v[96:99], v[184:187], v[152:155], v[96:99]
	v_mfma_f32_16x16x32_bf16 v[84:87], v[176:179], v[160:163], v[84:87]
	v_mfma_f32_16x16x32_bf16 v[80:83], v[184:187], v[160:163], v[80:83]
	v_mfma_f32_16x16x32_bf16 v[68:71], v[176:179], v[168:171], v[68:71]
	v_mfma_f32_16x16x32_bf16 v[64:67], v[184:187], v[168:171], v[64:67]
	v_mfma_f32_16x16x32_bf16 v[116:119], v[180:183], v[148:151], v[116:119]
	v_mfma_f32_16x16x32_bf16 v[112:115], v[188:191], v[148:151], v[112:115]
	v_mfma_f32_16x16x32_bf16 v[100:103], v[180:183], v[156:159], v[100:103]
	v_mfma_f32_16x16x32_bf16 v[96:99], v[188:191], v[156:159], v[96:99]
	v_mfma_f32_16x16x32_bf16 v[84:87], v[180:183], v[164:167], v[84:87]
	v_mfma_f32_16x16x32_bf16 v[80:83], v[188:191], v[164:167], v[80:83]
	v_mfma_f32_16x16x32_bf16 v[68:71], v[180:183], v[172:175], v[68:71]
	v_mfma_f32_16x16x32_bf16 v[64:67], v[188:191], v[172:175], v[64:67]
	s_setprio 0
	s_mov_b32 m0, s73
	v_lshl_add_u64 v[214:215], s[30:31], 0, v[200:201]
	s_barrier
	ds_read_b128 v[144:147], v251 offset:16384
	ds_read_b128 v[148:151], v251 offset:17408
	ds_read_b128 v[152:155], v251 offset:18432
	ds_read_b128 v[156:159], v251 offset:19456
	ds_read_b128 v[160:163], v251 offset:20480
	ds_read_b128 v[164:167], v251 offset:21504
	ds_read_b128 v[168:171], v251 offset:22528
	ds_read_b128 v[172:175], v251 offset:23552
	global_load_lds_dwordx4 v[214:215], off
	v_lshl_add_u64 v[216:217], s[30:31], 0, v[204:205]
	s_mov_b32 m0, s76
	s_nop 0
	global_load_lds_dwordx4 v[216:217], off
	s_barrier
	s_waitcnt lgkmcnt(0)
	s_setprio 1
	s_waitcnt lgkmcnt(0)
	v_mfma_f32_16x16x32_bf16 v[60:63], v[128:131], v[144:147], v[60:63]
	v_mfma_f32_16x16x32_bf16 v[56:59], v[136:139], v[144:147], v[56:59]
	v_mfma_f32_16x16x32_bf16 v[44:47], v[128:131], v[152:155], v[44:47]
	v_mfma_f32_16x16x32_bf16 v[40:43], v[136:139], v[152:155], v[40:43]
	v_mfma_f32_16x16x32_bf16 v[28:31], v[128:131], v[160:163], v[28:31]
	v_mfma_f32_16x16x32_bf16 v[24:27], v[136:139], v[160:163], v[24:27]
	v_mfma_f32_16x16x32_bf16 v[12:15], v[128:131], v[168:171], v[12:15]
	v_mfma_f32_16x16x32_bf16 v[8:11], v[136:139], v[168:171], v[8:11]
	v_mfma_f32_16x16x32_bf16 v[60:63], v[132:135], v[148:151], v[60:63]
	v_mfma_f32_16x16x32_bf16 v[56:59], v[140:143], v[148:151], v[56:59]
	v_mfma_f32_16x16x32_bf16 v[44:47], v[132:135], v[156:159], v[44:47]
	v_mfma_f32_16x16x32_bf16 v[40:43], v[140:143], v[156:159], v[40:43]
	v_mfma_f32_16x16x32_bf16 v[28:31], v[132:135], v[164:167], v[28:31]
	v_mfma_f32_16x16x32_bf16 v[24:27], v[140:143], v[164:167], v[24:27]
	v_mfma_f32_16x16x32_bf16 v[12:15], v[132:135], v[172:175], v[12:15]
	v_mfma_f32_16x16x32_bf16 v[8:11], v[140:143], v[172:175], v[8:11]
	s_setprio 0
	s_barrier
; #define PG8_STAGE(bufoff, gbase, voff) do { _Pragma("unroll") for (int _i = 0; _i < 2; ++_i) \
;         __builtin_amdgcn_global_load_lds((const unsigned*)((const char*)(gbase) + (voff)[_i]), (PG8_LAS unsigned*)(lds + (bufoff) + ldsw + _i * 8192), 16, 0, 0); } while (0)
; #define PG8_LDA(dst, b, h) do { _Pragma("unroll") for (int m = 0; m < 4; ++m) _Pragma("unroll") for (int k = 0; k < 2; ++k) dst[m][k] = *(const PG8_LAS bf16x8*)(lds + PG8_SA(b, h) + aoff + m * 2048 + k * 1024); } while (0)
; #define PG8_LDB(dst, b, h) do { _Pragma("unroll") for (int n = 0; n < 2; ++n) _Pragma("unroll") for (int k = 0; k < 2; ++k) dst[n][k] = *(const PG8_LAS bf16x8*)(lds + PG8_SB(b, h) + boff + n * 2048 + k * 1024); } while (0)
; #define PG8_MMA(ai, bj, At, Bt) do { __builtin_amdgcn_s_setprio(1); _Pragma("unroll") for (int m = 0; m < 4; ++m) _Pragma("unroll") for (int n = 0; n < 2; ++n) _Pragma("unroll") for (int k = 0; k < 2; ++k) \
;         acc[ai][bj][m][n] = __builtin_amdgcn_mfma_f32_16x16x32_bf16(Bt[n][k], At[m][k], acc[ai][bj][m][n], 0, 0, 0); __builtin_amdgcn_s_setprio(0); } while (0)
; #define PG8_WAIT_V(n) asm volatile("s_waitcnt vmcnt(" #n ")" ::: "memory")
; #define PG8_WAIT_L(n) asm volatile("s_waitcnt lgkmcnt(" #n ")" ::: "memory")
; #define PG8_BAR __builtin_amdgcn_s_barrier()
; #define PG8_SCHED __builtin_amdgcn_sched_barrier(0)
; template <class Epi, class Sched>
; __device__ __forceinline__ void gemm_phase(PG8_LAS unsigned char* lds, const Gemm g, const Sched& S, const Epi& E, int tid_in) {
;     ...
;             PG8_STAGE(PG8_SB(0, 1), b2 + hstep, voffB);
;             PG8_WAIT_V(6); PG8_BAR; PG8_MMA(1, 1, At, B1); PG8_BAR;
;             PG8_LDB(B0, 1, 0); PG8_SCHED; PG8_LDA(At, 1, 0); PG8_STAGE(PG8_SA(0, 1), a2 + hstep, voffA);
;             PG8_WAIT_L(8); PG8_BAR; PG8_WAIT_L(0); PG8_MMA(0, 0, At, B0); PG8_BAR; PG8_SCHED;
;             PG8_LDB(B1, 1, 1); PG8_STAGE(PG8_SB(1, 0), b3, voffB);
;             PG8_BAR; PG8_WAIT_L(0); PG8_MMA(0, 1, At, B1); PG8_BAR;
;             PG8_LDA(At, 1, 1); PG8_STAGE(PG8_SA(1, 0), a3, voffA);
	s_add_u32 s38, s28, 0x40000
	s_addc_u32 s39, s29, 0
	s_add_i32 s40, s40, s72
	v_lshl_add_u64 v[128:129], s[38:39], 0, v[202:203]
	s_mov_b32 m0, s40
	s_nop 0
	global_load_lds_dwordx4 v[128:129], off
	v_lshl_add_u64 v[128:129], s[38:39], 0, v[206:207]
	s_add_i32 m0, s40, 0x2000
	s_nop 0
	global_load_lds_dwordx4 v[128:129], off
	s_waitcnt vmcnt(6)
	s_barrier
	s_setprio 1
	v_mfma_f32_16x16x32_bf16 v[52:55], v[176:179], v[144:147], v[52:55]
	v_mfma_f32_16x16x32_bf16 v[48:51], v[184:187], v[144:147], v[48:51]
	v_mfma_f32_16x16x32_bf16 v[36:39], v[176:179], v[152:155], v[36:39]
	v_mfma_f32_16x16x32_bf16 v[32:35], v[184:187], v[152:155], v[32:35]
	v_mfma_f32_16x16x32_bf16 v[20:23], v[176:179], v[160:163], v[20:23]
	v_mfma_f32_16x16x32_bf16 v[16:19], v[184:187], v[160:163], v[16:19]
	v_mfma_f32_16x16x32_bf16 v[4:7], v[176:179], v[168:171], v[4:7]
	v_mfma_f32_16x16x32_bf16 v[0:3], v[184:187], v[168:171], v[0:3]
	v_mfma_f32_16x16x32_bf16 v[52:55], v[180:183], v[148:151], v[52:55]
	v_mfma_f32_16x16x32_bf16 v[48:51], v[188:191], v[148:151], v[48:51]
	v_mfma_f32_16x16x32_bf16 v[36:39], v[180:183], v[156:159], v[36:39]
	v_mfma_f32_16x16x32_bf16 v[32:35], v[188:191], v[156:159], v[32:35]
	v_mfma_f32_16x16x32_bf16 v[20:23], v[180:183], v[164:167], v[20:23]
	v_mfma_f32_16x16x32_bf16 v[16:19], v[188:191], v[164:167], v[16:19]
	v_mfma_f32_16x16x32_bf16 v[4:7], v[180:183], v[172:175], v[4:7]
	v_mfma_f32_16x16x32_bf16 v[0:3], v[188:191], v[172:175], v[0:3]
	s_setprio 0
	s_add_i32 s38, 0, 0x18000
	v_add_u32_e32 v140, s38, v246
	s_barrier
	ds_read_b128 v[128:131], v140
	ds_read_b128 v[132:135], v140 offset:1024
	ds_read_b128 v[136:139], v140 offset:2048
	ds_read_b128 v[140:143], v140 offset:3072
	s_add_u32 s30, s30, 0x40000
	s_addc_u32 s31, s31, 0
	s_mov_b32 m0, s77
	v_lshl_add_u64 v[176:177], s[30:31], 0, v[200:201]
	ds_read_b128 v[144:147], v251 offset:32768
	ds_read_b128 v[148:151], v251 offset:33792
	ds_read_b128 v[152:155], v251 offset:34816
	ds_read_b128 v[156:159], v251 offset:35840
	ds_read_b128 v[160:163], v251 offset:36864
	ds_read_b128 v[164:167], v251 offset:37888
	ds_read_b128 v[168:171], v251 offset:38912
	ds_read_b128 v[172:175], v251 offset:39936
	global_load_lds_dwordx4 v[176:177], off
	v_lshl_add_u64 v[176:177], s[30:31], 0, v[204:205]
	s_mov_b32 m0, s78
	s_nop 0
	global_load_lds_dwordx4 v[176:177], off
	s_waitcnt lgkmcnt(8)
	s_barrier
	s_waitcnt lgkmcnt(0)
	s_setprio 1
	s_waitcnt lgkmcnt(0)
	v_mfma_f32_16x16x32_bf16 v[124:127], v[128:131], v[144:147], v[124:127]
	v_mfma_f32_16x16x32_bf16 v[120:123], v[136:139], v[144:147], v[120:123]
	v_mfma_f32_16x16x32_bf16 v[108:111], v[128:131], v[152:155], v[108:111]
	v_mfma_f32_16x16x32_bf16 v[104:107], v[136:139], v[152:155], v[104:107]
	v_mfma_f32_16x16x32_bf16 v[92:95], v[128:131], v[160:163], v[92:95]
	v_mfma_f32_16x16x32_bf16 v[88:91], v[136:139], v[160:163], v[88:91]
	v_mfma_f32_16x16x32_bf16 v[76:79], v[128:131], v[168:171], v[76:79]
	v_mfma_f32_16x16x32_bf16 v[72:75], v[136:139], v[168:171], v[72:75]
	v_mfma_f32_16x16x32_bf16 v[124:127], v[132:135], v[148:151], v[124:127]
	v_mfma_f32_16x16x32_bf16 v[120:123], v[140:143], v[148:151], v[120:123]
	v_mfma_f32_16x16x32_bf16 v[108:111], v[132:135], v[156:159], v[108:111]
	v_mfma_f32_16x16x32_bf16 v[104:107], v[140:143], v[156:159], v[104:107]
	v_mfma_f32_16x16x32_bf16 v[92:95], v[132:135], v[164:167], v[92:95]
	v_mfma_f32_16x16x32_bf16 v[88:91], v[140:143], v[164:167], v[88:91]
	v_mfma_f32_16x16x32_bf16 v[76:79], v[132:135], v[172:175], v[76:79]
	v_mfma_f32_16x16x32_bf16 v[72:75], v[140:143], v[172:175], v[72:75]
	s_setprio 0
	s_barrier
	s_add_i32 s30, 0, 0x1c000
	s_add_i32 s31, s38, s72
	v_add_u32_e32 v188, s30, v246
	v_lshl_add_u64 v[194:195], v[194:195], 0, s[74:75]
	s_mov_b32 m0, s31
	ds_read_b128 v[176:179], v188
	ds_read_b128 v[180:183], v188 offset:1024
	ds_read_b128 v[184:187], v188 offset:2048
	ds_read_b128 v[188:191], v188 offset:3072
	global_load_lds_dwordx4 v[194:195], off
	v_lshl_add_u64 v[194:195], v[196:197], 0, s[74:75]
	s_add_i32 m0, s31, 0x2000
	s_nop 0
	global_load_lds_dwordx4 v[194:195], off
	s_barrier
	s_waitcnt lgkmcnt(0)
	s_setprio 1
	s_waitcnt lgkmcnt(0)
	v_mfma_f32_16x16x32_bf16 v[116:119], v[176:179], v[144:147], v[116:119]
	v_mfma_f32_16x16x32_bf16 v[112:115], v[184:187], v[144:147], v[112:115]
	v_mfma_f32_16x16x32_bf16 v[100:103], v[176:179], v[152:155], v[100:103]
	v_mfma_f32_16x16x32_bf16 v[96:99], v[184:187], v[152:155], v[96:99]
	v_mfma_f32_16x16x32_bf16 v[84:87], v[176:179], v[160:163], v[84:87]
	v_mfma_f32_16x16x32_bf16 v[80:83], v[184:187], v[160:163], v[80:83]
	v_mfma_f32_16x16x32_bf16 v[68:71], v[176:179], v[168:171], v[68:71]
	v_mfma_f32_16x16x32_bf16 v[64:67], v[184:187], v[168:171], v[64:67]
	v_mfma_f32_16x16x32_bf16 v[116:119], v[180:183], v[148:151], v[116:119]
	v_mfma_f32_16x16x32_bf16 v[112:115], v[188:191], v[148:151], v[112:115]
	v_mfma_f32_16x16x32_bf16 v[100:103], v[180:183], v[156:159], v[100:103]
	v_mfma_f32_16x16x32_bf16 v[96:99], v[188:191], v[156:159], v[96:99]
	v_mfma_f32_16x16x32_bf16 v[84:87], v[180:183], v[164:167], v[84:87]
	v_mfma_f32_16x16x32_bf16 v[80:83], v[188:191], v[164:167], v[80:83]
	v_mfma_f32_16x16x32_bf16 v[68:71], v[180:183], v[172:175], v[68:71]
	v_mfma_f32_16x16x32_bf16 v[64:67], v[188:191], v[172:175], v[64:67]
	s_setprio 0
	s_mov_b32 m0, s80
	v_lshl_add_u64 v[194:195], v[214:215], 0, s[74:75]
	s_barrier
	ds_read_b128 v[144:147], v251 offset:49152
	ds_read_b128 v[148:151], v251 offset:50176
	ds_read_b128 v[152:155], v251 offset:51200
	ds_read_b128 v[156:159], v251 offset:52224
	ds_read_b128 v[160:163], v251 offset:53248
	ds_read_b128 v[164:167], v251 offset:54272
	ds_read_b128 v[168:171], v251 offset:55296
	ds_read_b128 v[172:175], v251 offset:56320
	global_load_lds_dwordx4 v[194:195], off
	v_lshl_add_u64 v[194:195], v[216:217], 0, s[74:75]
	s_mov_b32 m0, s81
	s_nop 0
	global_load_lds_dwordx4 v[194:195], off
	s_barrier
; __device__ __forceinline__ unsigned cvt_pk_bf16(float lo, float hi) { unsigned r; asm volatile("s_nop 0\n\tv_cvt_pk_bf16_f32 %0, %1, %2\n\ts_nop 1" : "=v"(r) : "v"(lo), "v"(hi)); return r; }
; #define PG8_STAGE(bufoff, gbase, voff) do { _Pragma("unroll") for (int _i = 0; _i < 2; ++_i) \
;         __builtin_amdgcn_global_load_lds((const unsigned*)((const char*)(gbase) + (voff)[_i]), (PG8_LAS unsigned*)(lds + (bufoff) + ldsw + _i * 8192), 16, 0, 0); } while (0)
; #define PG8_MMA(ai, bj, At, Bt) do { __builtin_amdgcn_s_setprio(1); _Pragma("unroll") for (int m = 0; m < 4; ++m) _Pragma("unroll") for (int n = 0; n < 2; ++n) _Pragma("unroll") for (int k = 0; k < 2; ++k) \
;         acc[ai][bj][m][n] = __builtin_amdgcn_mfma_f32_16x16x32_bf16(Bt[n][k], At[m][k], acc[ai][bj][m][n], 0, 0, 0); __builtin_amdgcn_s_setprio(0); } while (0)
; #define PG8_WAIT_V(n) asm volatile("s_waitcnt vmcnt(" #n ")" ::: "memory")
; #define PG8_WAIT_L(n) asm volatile("s_waitcnt lgkmcnt(" #n ")" ::: "memory")
; #define PG8_BAR __builtin_amdgcn_s_barrier()
; template <class Epi, class Sched>
; __device__ __forceinline__ void gemm_phase(PG8_LAS unsigned char* lds, const Gemm g, const Sched& S, const Epi& E, int tid_in) {
;     ...
;             PG8_BAR; PG8_WAIT_L(0); PG8_MMA(1, 0, At, B0); PG8_BAR; PG8_SCHED;
;             PG8_STAGE(PG8_SB(1, 1), b3 + hstep, voffB);
;             PG8_WAIT_V(6); PG8_BAR; PG8_MMA(1, 1, At, B1); PG8_BAR;
;     __device__ __forceinline__ void operator()(f32x4 (&acc)[2][2][4][2], const Unit& u, int wr, int wc, int fr, int fq) const {
;     ...
; #pragma unroll
;             for (int bj = 0; bj < 2; ++bj) { const int col = (u.pn - 12) * 256 + bj * 128 + c8;
;                 const f32x4 b0 = *(const f32x4*)(b_gate + col), b1 = *(const f32x4*)(b_gate + col + 4);
; #pragma unroll
;                 for (int ai = 0; ai < 2; ++ai)
; #pragma unroll
;                     for (int m = 0; m < 4; ++m) { const f32x4 v0 = acc[ai][bj][m][0] + b0, v1 = acc[ai][bj][m][1] + b1;
;                         u32x4 w; w.x = cvt_pk_bf16(sigmoidf_(v0[0]), sigmoidf_(v0[1])); w.y = cvt_pk_bf16(sigmoidf_(v0[2]), sigmoidf_(v0[3]));
;                         w.z = cvt_pk_bf16(sigmoidf_(v1[0]), sigmoidf_(v1[1])); w.w = cvt_pk_bf16(sigmoidf_(v1[2]), sigmoidf_(v1[3]));
;                         *(u32x4*)(gates + (size_t)(row0 + ai * 128 + m * 16) * 2048 + col) = w; } }
	s_waitcnt lgkmcnt(0)
	s_setprio 1
	s_waitcnt lgkmcnt(0)
	v_mfma_f32_16x16x32_bf16 v[60:63], v[128:131], v[144:147], v[60:63]
	v_mfma_f32_16x16x32_bf16 v[56:59], v[136:139], v[144:147], v[56:59]
	v_mfma_f32_16x16x32_bf16 v[44:47], v[128:131], v[152:155], v[44:47]
	v_mfma_f32_16x16x32_bf16 v[40:43], v[136:139], v[152:155], v[40:43]
	v_mfma_f32_16x16x32_bf16 v[28:31], v[128:131], v[160:163], v[28:31]
	v_mfma_f32_16x16x32_bf16 v[24:27], v[136:139], v[160:163], v[24:27]
	v_mfma_f32_16x16x32_bf16 v[12:15], v[128:131], v[168:171], v[12:15]
	v_mfma_f32_16x16x32_bf16 v[8:11], v[136:139], v[168:171], v[8:11]
	v_mfma_f32_16x16x32_bf16 v[60:63], v[132:135], v[148:151], v[60:63]
	v_mfma_f32_16x16x32_bf16 v[56:59], v[140:143], v[148:151], v[56:59]
	v_mfma_f32_16x16x32_bf16 v[44:47], v[132:135], v[156:159], v[44:47]
	v_mfma_f32_16x16x32_bf16 v[40:43], v[140:143], v[156:159], v[40:43]
	v_mfma_f32_16x16x32_bf16 v[28:31], v[132:135], v[164:167], v[28:31]
	v_mfma_f32_16x16x32_bf16 v[24:27], v[140:143], v[164:167], v[24:27]
	v_mfma_f32_16x16x32_bf16 v[12:15], v[132:135], v[172:175], v[12:15]
	v_mfma_f32_16x16x32_bf16 v[8:11], v[140:143], v[172:175], v[8:11]
	s_setprio 0
	s_barrier
	s_add_u32 s28, s28, 0x40080
	s_addc_u32 s29, s29, 0
	s_add_i32 s30, s30, s72
	v_lshl_add_u64 v[128:129], s[28:29], 0, v[202:203]
	s_mov_b32 m0, s30
	s_nop 0
	global_load_lds_dwordx4 v[128:129], off
	v_lshl_add_u64 v[128:129], s[28:29], 0, v[206:207]
	s_add_i32 m0, s30, 0x2000
	s_nop 0
	global_load_lds_dwordx4 v[128:129], off
	s_waitcnt vmcnt(6)
	s_barrier
	s_setprio 1
	v_mfma_f32_16x16x32_bf16 v[52:55], v[176:179], v[144:147], v[52:55]
	v_mfma_f32_16x16x32_bf16 v[48:51], v[184:187], v[144:147], v[48:51]
	v_mfma_f32_16x16x32_bf16 v[36:39], v[176:179], v[152:155], v[36:39]
	v_mfma_f32_16x16x32_bf16 v[32:35], v[184:187], v[152:155], v[32:35]
	v_mfma_f32_16x16x32_bf16 v[20:23], v[176:179], v[160:163], v[20:23]
	v_mfma_f32_16x16x32_bf16 v[16:19], v[184:187], v[160:163], v[16:19]
	v_mfma_f32_16x16x32_bf16 v[4:7], v[176:179], v[168:171], v[4:7]
	v_mfma_f32_16x16x32_bf16 v[0:3], v[184:187], v[168:171], v[0:3]
	v_mfma_f32_16x16x32_bf16 v[52:55], v[180:183], v[148:151], v[52:55]
	v_mfma_f32_16x16x32_bf16 v[48:51], v[188:191], v[148:151], v[48:51]
	v_mfma_f32_16x16x32_bf16 v[36:39], v[180:183], v[156:159], v[36:39]
	v_mfma_f32_16x16x32_bf16 v[32:35], v[188:191], v[156:159], v[32:35]
	v_mfma_f32_16x16x32_bf16 v[20:23], v[180:183], v[164:167], v[20:23]
	v_mfma_f32_16x16x32_bf16 v[16:19], v[188:191], v[164:167], v[16:19]
	v_mfma_f32_16x16x32_bf16 v[4:7], v[180:183], v[172:175], v[4:7]
	v_mfma_f32_16x16x32_bf16 v[0:3], v[188:191], v[172:175], v[0:3]
	s_setprio 0
	s_add_i32 s37, s37, 2
	s_add_u32 s26, s26, 0x100
	s_addc_u32 s27, s27, 0
	s_add_u32 s33, s33, 0x100
	s_addc_u32 s36, s36, 0
	s_cmp_gt_u32 s37, 13
	s_barrier
	s_cbranch_scc0 .LBB0_388
	v_lshl_add_u32 v214, s0, 8, v209
	s_cmp_gt_i32 s24, 7
	s_mov_b64 s[0:1], -1
	s_cbranch_scc0 .LBB0_395
	s_lshl_b32 s17, s24, 8
	s_cmp_lt_u32 s24, 12
	s_cbranch_scc1 .LBB0_392
	v_or_b32_e32 v128, 0xfffff400, v208
	v_add_u32_e32 v140, s17, v128
	v_readlane_b32 s48, v255, 19
	v_ashrrev_i32_e32 v141, 31, v140
	v_readlane_b32 s49, v255, 20
	v_ashrrev_i32_e32 v215, 31, v214
	v_lshlrev_b64 v[146:147], 1, v[140:141]
	v_lshl_add_u64 v[132:133], v[140:141], 2, s[48:49]
	global_load_dwordx4 v[128:131], v[132:133], off offset:16
	s_nop 0
	global_load_dwordx4 v[132:135], v[132:133], off
	s_mov_b64 s[0:1], 0x80000
	v_or_b32_e32 v140, 0x80, v140
	v_readlane_b32 s50, v255, 21
	v_readlane_b32 s51, v255, 22
	v_readlane_b32 s52, v255, 23
	v_readlane_b32 s53, v255, 24
	v_readlane_b32 s54, v255, 25
	v_readlane_b32 s55, v255, 26
	s_waitcnt vmcnt(0)
	v_pk_add_f32 v[144:145], v[120:121], v[128:129]
	v_pk_add_f32 v[136:137], v[124:125], v[132:133]
	v_pk_add_f32 v[138:139], v[126:127], v[134:135]
	v_mul_f32_e32 v136, 0xbfb8aa3b, v136
	v_mul_f32_e32 v137, 0xbfb8aa3b, v137
	v_exp_f32_e32 v136, v136
	v_exp_f32_e32 v137, v137
	v_pk_add_f32 v[142:143], v[122:123], v[130:131]
	v_pk_add_f32 v[148:149], v[104:105], v[128:129]
	v_add_f32_e32 v136, 1.0, v136
	v_add_f32_e32 v137, 1.0, v137
	v_rcp_f32_e32 v136, v136
	v_rcp_f32_e32 v137, v137
	s_nop 0
	v_cvt_pk_bf16_f32 v136, v136, v137
	v_mul_f32_e32 v137, 0xbfb8aa3b, v138
	v_mul_f32_e32 v138, 0xbfb8aa3b, v139
	v_exp_f32_e32 v137, v137
	v_exp_f32_e32 v138, v138
	v_mul_f32_e32 v139, 0xbfb8aa3b, v145
	v_exp_f32_e32 v139, v139
	v_add_f32_e32 v137, 1.0, v137
	v_add_f32_e32 v138, 1.0, v138
	v_rcp_f32_e32 v137, v137
	v_rcp_f32_e32 v138, v138
	s_nop 0
	v_cvt_pk_bf16_f32 v137, v137, v138
	v_mul_f32_e32 v138, 0xbfb8aa3b, v144
	v_exp_f32_e32 v138, v138
	v_add_f32_e32 v139, 1.0, v139
	v_rcp_f32_e32 v139, v139
	v_pk_add_f32 v[150:151], v[88:89], v[128:129]
	v_add_f32_e32 v138, 1.0, v138
	v_rcp_f32_e32 v138, v138
	s_nop 0
	v_cvt_pk_bf16_f32 v138, v138, v139
	v_mul_f32_e32 v139, 0xbfb8aa3b, v142
	v_mul_f32_e32 v142, 0xbfb8aa3b, v143
	v_exp_f32_e32 v139, v139
	v_exp_f32_e32 v142, v142
	v_pk_add_f32 v[152:153], v[90:91], v[130:131]
	v_pk_add_f32 v[154:155], v[58:59], v[130:131]
	v_add_f32_e32 v139, 1.0, v139
	v_add_f32_e32 v142, 1.0, v142
	v_rcp_f32_e32 v139, v139
	v_rcp_f32_e32 v142, v142
	s_nop 0
	v_cvt_pk_bf16_f32 v139, v139, v142
	v_lshlrev_b64 v[142:143], 12, v[214:215]
	v_lshl_add_u64 v[142:143], s[14:15], 0, v[142:143]
	v_lshl_add_u64 v[144:145], v[142:143], 0, v[146:147]
	global_store_dwordx4 v[144:145], v[136:139], off
	v_pk_add_f32 v[144:145], v[106:107], v[130:131]
	v_pk_add_f32 v[156:157], v[42:43], v[130:131]
	v_pk_add_f32 v[136:137], v[108:109], v[132:133]
	v_pk_add_f32 v[138:139], v[110:111], v[134:135]
	v_mul_f32_e32 v136, 0xbfb8aa3b, v136
; __device__ __forceinline__ unsigned cvt_pk_bf16(float lo, float hi) { unsigned r; asm volatile("s_nop 0\n\tv_cvt_pk_bf16_f32 %0, %1, %2\n\ts_nop 1" : "=v"(r) : "v"(lo), "v"(hi)); return r; }
; __device__ __forceinline__ float sigmoidf_(float x) { return __builtin_amdgcn_rcpf(1.f + __expf(-x)); }
;     __device__ __forceinline__ void operator()(f32x4 (&acc)[2][2][4][2], const Unit& u, int wr, int wc, int fr, int fq) const {
;     ...
; #pragma unroll
;             for (int bj = 0; bj < 2; ++bj) { const int col = (u.pn - 12) * 256 + bj * 128 + c8;
;                 const f32x4 b0 = *(const f32x4*)(b_gate + col), b1 = *(const f32x4*)(b_gate + col + 4);
; #pragma unroll
;                 for (int ai = 0; ai < 2; ++ai)
; #pragma unroll
;                     for (int m = 0; m < 4; ++m) { const f32x4 v0 = acc[ai][bj][m][0] + b0, v1 = acc[ai][bj][m][1] + b1;
;                         u32x4 w; w.x = cvt_pk_bf16(sigmoidf_(v0[0]), sigmoidf_(v0[1])); w.y = cvt_pk_bf16(sigmoidf_(v0[2]), sigmoidf_(v0[3]));
;                         w.z = cvt_pk_bf16(sigmoidf_(v1[0]), sigmoidf_(v1[1])); w.w = cvt_pk_bf16(sigmoidf_(v1[2]), sigmoidf_(v1[3]));
;                         *(u32x4*)(gates + (size_t)(row0 + ai * 128 + m * 16) * 2048 + col) = w; } }
	v_mul_f32_e32 v137, 0xbfb8aa3b, v137
	v_exp_f32_e32 v136, v136
	v_exp_f32_e32 v137, v137
	v_mul_f32_e32 v141, 0xbfb8aa3b, v145
	v_exp_f32_e32 v141, v141
	v_add_f32_e32 v136, 1.0, v136
	v_add_f32_e32 v137, 1.0, v137
	v_rcp_f32_e32 v136, v136
	v_rcp_f32_e32 v137, v137
	s_nop 0
	v_cvt_pk_bf16_f32 v136, v136, v137
	v_mul_f32_e32 v137, 0xbfb8aa3b, v138
	v_mul_f32_e32 v138, 0xbfb8aa3b, v139
	v_exp_f32_e32 v137, v137
	v_exp_f32_e32 v138, v138
	v_mul_f32_e32 v139, 0xbfb8aa3b, v149
	v_exp_f32_e32 v139, v139
	v_add_f32_e32 v137, 1.0, v137
	v_add_f32_e32 v138, 1.0, v138
	v_rcp_f32_e32 v137, v137
	v_rcp_f32_e32 v138, v138
	s_nop 0
	v_cvt_pk_bf16_f32 v137, v137, v138
	v_mul_f32_e32 v138, 0xbfb8aa3b, v148
	v_exp_f32_e32 v138, v138
	v_add_f32_e32 v139, 1.0, v139
	v_rcp_f32_e32 v139, v139
	v_add_f32_e32 v141, 1.0, v141
	v_add_f32_e32 v138, 1.0, v138
	v_rcp_f32_e32 v138, v138
	s_nop 0
	v_cvt_pk_bf16_f32 v138, v138, v139
	v_mul_f32_e32 v139, 0xbfb8aa3b, v144
	v_exp_f32_e32 v139, v139
	v_or_b32_e32 v144, 16, v214
	v_ashrrev_i32_e32 v145, 31, v144
	v_lshlrev_b64 v[144:145], 12, v[144:145]
	v_add_f32_e32 v139, 1.0, v139
	v_lshl_add_u64 v[144:145], s[14:15], 0, v[144:145]
	v_rcp_f32_e32 v139, v139
	v_lshl_add_u64 v[148:149], v[144:145], 0, v[146:147]
	v_rcp_f32_e32 v141, v141
	s_nop 0
	v_cvt_pk_bf16_f32 v139, v139, v141
	global_store_dwordx4 v[148:149], v[136:139], off
	v_pk_add_f32 v[158:159], v[26:27], v[130:131]
	s_nop 0
	v_pk_add_f32 v[136:137], v[94:95], v[134:135]
	v_pk_add_f32 v[138:139], v[92:93], v[132:133]
	v_mul_f32_e32 v136, 0xbfb8aa3b, v136
	v_mul_f32_e32 v138, 0xbfb8aa3b, v138
	v_mul_f32_e32 v139, 0xbfb8aa3b, v139
	v_exp_f32_e32 v136, v136
	v_mul_f32_e32 v137, 0xbfb8aa3b, v137
	v_exp_f32_e32 v138, v138
	v_exp_f32_e32 v139, v139
	v_exp_f32_e32 v137, v137
	v_add_f32_e32 v136, 1.0, v136
	v_add_f32_e32 v138, 1.0, v138
	v_add_f32_e32 v139, 1.0, v139
	v_rcp_f32_e32 v136, v136
	v_add_f32_e32 v137, 1.0, v137
	v_rcp_f32_e32 v138, v138
	v_rcp_f32_e32 v139, v139
	s_nop 0
	v_cvt_pk_bf16_f32 v148, v138, v139
	v_rcp_f32_e32 v137, v137
	s_nop 0
	v_cvt_pk_bf16_f32 v149, v136, v137
	v_mul_f32_e32 v136, 0xbfb8aa3b, v150
	v_exp_f32_e32 v136, v136
	v_mul_f32_e32 v137, 0xbfb8aa3b, v151
	v_exp_f32_e32 v137, v137
	v_add_f32_e32 v136, 1.0, v136
	v_rcp_f32_e32 v136, v136
	v_add_f32_e32 v137, 1.0, v137
	v_rcp_f32_e32 v137, v137
	s_nop 0
	v_cvt_pk_bf16_f32 v150, v136, v137
	v_mul_f32_e32 v136, 0xbfb8aa3b, v152
	v_exp_f32_e32 v136, v136
	v_mul_f32_e32 v137, 0xbfb8aa3b, v153
	v_exp_f32_e32 v137, v137
	v_pk_add_f32 v[152:153], v[74:75], v[130:131]
	v_add_f32_e32 v136, 1.0, v136
	v_rcp_f32_e32 v136, v136
	v_add_f32_e32 v137, 1.0, v137
	v_rcp_f32_e32 v137, v137
	s_nop 0
	v_cvt_pk_bf16_f32 v151, v136, v137
	v_or_b32_e32 v136, 32, v214
	v_ashrrev_i32_e32 v137, 31, v136
	v_lshlrev_b64 v[136:137], 12, v[136:137]
	v_lshl_add_u64 v[136:137], s[14:15], 0, v[136:137]
	v_lshl_add_u64 v[138:139], v[136:137], 0, v[146:147]
	global_store_dwordx4 v[138:139], v[148:151], off
	v_pk_add_f32 v[138:139], v[78:79], v[134:135]
	s_nop 0
	v_pk_add_f32 v[148:149], v[76:77], v[132:133]
	v_mul_f32_e32 v138, 0xbfb8aa3b, v138
	v_mul_f32_e32 v141, 0xbfb8aa3b, v148
	v_mul_f32_e32 v148, 0xbfb8aa3b, v149
	v_exp_f32_e32 v148, v148
	v_exp_f32_e32 v138, v138
	v_mul_f32_e32 v139, 0xbfb8aa3b, v139
	v_exp_f32_e32 v141, v141
	v_exp_f32_e32 v139, v139
	v_add_f32_e32 v148, 1.0, v148
	v_add_f32_e32 v138, 1.0, v138
	v_pk_add_f32 v[150:151], v[72:73], v[128:129]
	v_add_f32_e32 v141, 1.0, v141
	v_rcp_f32_e32 v148, v148
	v_rcp_f32_e32 v138, v138
	v_add_f32_e32 v139, 1.0, v139
	v_rcp_f32_e32 v141, v141
	s_nop 0
	v_cvt_pk_bf16_f32 v148, v141, v148
	v_rcp_f32_e32 v139, v139
	s_nop 0
	v_cvt_pk_bf16_f32 v149, v138, v139
	v_mul_f32_e32 v138, 0xbfb8aa3b, v150
	v_exp_f32_e32 v138, v138
	v_mul_f32_e32 v139, 0xbfb8aa3b, v151
	v_exp_f32_e32 v139, v139
	v_add_f32_e32 v138, 1.0, v138
	v_rcp_f32_e32 v138, v138
	v_add_f32_e32 v139, 1.0, v139
	v_rcp_f32_e32 v139, v139
	s_nop 0
	v_cvt_pk_bf16_f32 v150, v138, v139
	v_mul_f32_e32 v138, 0xbfb8aa3b, v152
	v_exp_f32_e32 v138, v138
	v_mul_f32_e32 v139, 0xbfb8aa3b, v153
	v_exp_f32_e32 v139, v139
	v_add_f32_e32 v138, 1.0, v138
	v_rcp_f32_e32 v138, v138
	v_add_f32_e32 v139, 1.0, v139
	v_rcp_f32_e32 v139, v139
	s_nop 0
	v_cvt_pk_bf16_f32 v151, v138, v139
	v_or_b32_e32 v138, 48, v214
	v_ashrrev_i32_e32 v139, 31, v138
	v_lshlrev_b64 v[138:139], 12, v[138:139]
	v_lshl_add_u64 v[138:139], s[14:15], 0, v[138:139]
	v_lshl_add_u64 v[152:153], v[138:139], 0, v[146:147]
	global_store_dwordx4 v[152:153], v[148:151], off
	v_pk_add_f32 v[152:153], v[56:57], v[128:129]
	s_nop 0
	v_pk_add_f32 v[150:151], v[60:61], v[132:133]
	v_pk_add_f32 v[148:149], v[62:63], v[134:135]
	v_mul_f32_e32 v141, 0xbfb8aa3b, v150
	v_mul_f32_e32 v150, 0xbfb8aa3b, v151
	v_exp_f32_e32 v141, v141
	v_exp_f32_e32 v150, v150
	v_add_f32_e32 v141, 1.0, v141
	v_add_f32_e32 v150, 1.0, v150
	v_rcp_f32_e32 v141, v141
	v_rcp_f32_e32 v150, v150
	s_nop 0
	v_cvt_pk_bf16_f32 v150, v141, v150
	v_mul_f32_e32 v141, 0xbfb8aa3b, v148
	v_mul_f32_e32 v148, 0xbfb8aa3b, v149
	v_exp_f32_e32 v148, v148
	v_exp_f32_e32 v141, v141
	v_add_f32_e32 v148, 1.0, v148
	v_add_f32_e32 v141, 1.0, v141
	v_rcp_f32_e32 v148, v148
	v_rcp_f32_e32 v141, v141
	s_nop 0
	v_cvt_pk_bf16_f32 v151, v141, v148
	v_mul_f32_e32 v148, 0xbfb8aa3b, v153
	v_mul_f32_e32 v141, 0xbfb8aa3b, v152
	v_exp_f32_e32 v148, v148
	v_exp_f32_e32 v141, v141
	v_add_f32_e32 v148, 1.0, v148
	v_add_f32_e32 v141, 1.0, v141
	v_rcp_f32_e32 v148, v148
	v_rcp_f32_e32 v141, v141
	s_nop 0
	v_cvt_pk_bf16_f32 v152, v141, v148
	v_mul_f32_e32 v148, 0xbfb8aa3b, v155
	v_mul_f32_e32 v141, 0xbfb8aa3b, v154
	v_exp_f32_e32 v148, v148
; __device__ __forceinline__ unsigned cvt_pk_bf16(float lo, float hi) { unsigned r; asm volatile("s_nop 0\n\tv_cvt_pk_bf16_f32 %0, %1, %2\n\ts_nop 1" : "=v"(r) : "v"(lo), "v"(hi)); return r; }
; __device__ __forceinline__ float sigmoidf_(float x) { return __builtin_amdgcn_rcpf(1.f + __expf(-x)); }
;     __device__ __forceinline__ void operator()(f32x4 (&acc)[2][2][4][2], const Unit& u, int wr, int wc, int fr, int fq) const {
;     ...
; #pragma unroll
;             for (int bj = 0; bj < 2; ++bj) { const int col = (u.pn - 12) * 256 + bj * 128 + c8;
;                 const f32x4 b0 = *(const f32x4*)(b_gate + col), b1 = *(const f32x4*)(b_gate + col + 4);
; #pragma unroll
;                 for (int ai = 0; ai < 2; ++ai)
; #pragma unroll
;                     for (int m = 0; m < 4; ++m) { const f32x4 v0 = acc[ai][bj][m][0] + b0, v1 = acc[ai][bj][m][1] + b1;
;                         u32x4 w; w.x = cvt_pk_bf16(sigmoidf_(v0[0]), sigmoidf_(v0[1])); w.y = cvt_pk_bf16(sigmoidf_(v0[2]), sigmoidf_(v0[3]));
;                         w.z = cvt_pk_bf16(sigmoidf_(v1[0]), sigmoidf_(v1[1])); w.w = cvt_pk_bf16(sigmoidf_(v1[2]), sigmoidf_(v1[3]));
;                         *(u32x4*)(gates + (size_t)(row0 + ai * 128 + m * 16) * 2048 + col) = w; } }
	v_exp_f32_e32 v141, v141
	v_add_f32_e32 v148, 1.0, v148
	v_add_f32_e32 v141, 1.0, v141
	v_rcp_f32_e32 v148, v148
	v_rcp_f32_e32 v141, v141
	s_nop 0
	v_cvt_pk_bf16_f32 v153, v141, v148
	v_lshl_add_u64 v[148:149], v[142:143], 0, s[0:1]
	v_lshl_add_u64 v[154:155], v[148:149], 0, v[146:147]
	global_store_dwordx4 v[154:155], v[150:153], off
	v_pk_add_f32 v[154:155], v[40:41], v[128:129]
	s_mov_b64 s[0:1], 0x90000
	v_pk_add_f32 v[152:153], v[44:45], v[132:133]
	v_pk_add_f32 v[150:151], v[46:47], v[134:135]
	v_mul_f32_e32 v141, 0xbfb8aa3b, v152
	v_mul_f32_e32 v152, 0xbfb8aa3b, v153
	v_exp_f32_e32 v141, v141
	v_exp_f32_e32 v152, v152
	v_add_f32_e32 v141, 1.0, v141
	v_add_f32_e32 v152, 1.0, v152
	v_rcp_f32_e32 v141, v141
	v_rcp_f32_e32 v152, v152
	s_nop 0
	v_cvt_pk_bf16_f32 v152, v141, v152
	v_mul_f32_e32 v141, 0xbfb8aa3b, v150
	v_mul_f32_e32 v150, 0xbfb8aa3b, v151
	v_exp_f32_e32 v150, v150
	v_exp_f32_e32 v141, v141
	v_add_f32_e32 v150, 1.0, v150
	v_add_f32_e32 v141, 1.0, v141
	v_rcp_f32_e32 v150, v150
	v_rcp_f32_e32 v141, v141
	s_nop 0
	v_cvt_pk_bf16_f32 v153, v141, v150
	v_mul_f32_e32 v150, 0xbfb8aa3b, v155
	v_mul_f32_e32 v141, 0xbfb8aa3b, v154
	v_exp_f32_e32 v150, v150
	v_exp_f32_e32 v141, v141
	v_add_f32_e32 v150, 1.0, v150
	v_add_f32_e32 v141, 1.0, v141
	v_rcp_f32_e32 v150, v150
	v_rcp_f32_e32 v141, v141
	s_nop 0
	v_cvt_pk_bf16_f32 v154, v141, v150
	v_mul_f32_e32 v150, 0xbfb8aa3b, v157
	v_mul_f32_e32 v141, 0xbfb8aa3b, v156
	v_exp_f32_e32 v150, v150
	v_exp_f32_e32 v141, v141
	v_add_f32_e32 v150, 1.0, v150
	v_add_f32_e32 v141, 1.0, v141
	v_rcp_f32_e32 v150, v150
	v_rcp_f32_e32 v141, v141
	s_nop 0
	v_cvt_pk_bf16_f32 v155, v141, v150
	v_lshl_add_u64 v[150:151], v[142:143], 0, s[0:1]
	v_lshl_add_u64 v[156:157], v[150:151], 0, v[146:147]
	global_store_dwordx4 v[156:157], v[152:155], off
	v_pk_add_f32 v[156:157], v[24:25], v[128:129]
	s_mov_b64 s[0:1], 0xa0000
	v_pk_add_f32 v[154:155], v[28:29], v[132:133]
	v_pk_add_f32 v[152:153], v[30:31], v[134:135]
	v_mul_f32_e32 v141, 0xbfb8aa3b, v154
	v_mul_f32_e32 v154, 0xbfb8aa3b, v155
	v_exp_f32_e32 v141, v141
	v_exp_f32_e32 v154, v154
	v_pk_add_f32 v[132:133], v[12:13], v[132:133]
	v_pk_add_f32 v[134:135], v[14:15], v[134:135]
	v_add_f32_e32 v141, 1.0, v141
	v_add_f32_e32 v154, 1.0, v154
	v_rcp_f32_e32 v141, v141
	v_rcp_f32_e32 v154, v154
	s_nop 0
	v_cvt_pk_bf16_f32 v154, v141, v154
	v_mul_f32_e32 v141, 0xbfb8aa3b, v152
	v_mul_f32_e32 v152, 0xbfb8aa3b, v153
	v_exp_f32_e32 v152, v152
	v_exp_f32_e32 v141, v141
	v_add_f32_e32 v152, 1.0, v152
	v_add_f32_e32 v141, 1.0, v141
	v_rcp_f32_e32 v152, v152
	v_rcp_f32_e32 v141, v141
	s_nop 0
	v_cvt_pk_bf16_f32 v155, v141, v152
	v_mul_f32_e32 v152, 0xbfb8aa3b, v157
	v_mul_f32_e32 v141, 0xbfb8aa3b, v156
	v_exp_f32_e32 v152, v152
	v_exp_f32_e32 v141, v141
	v_add_f32_e32 v152, 1.0, v152
	v_add_f32_e32 v141, 1.0, v141
	v_rcp_f32_e32 v152, v152
	v_rcp_f32_e32 v141, v141
	s_nop 0
	v_cvt_pk_bf16_f32 v156, v141, v152
	v_mul_f32_e32 v152, 0xbfb8aa3b, v159
	v_mul_f32_e32 v141, 0xbfb8aa3b, v158
	v_exp_f32_e32 v152, v152
	v_exp_f32_e32 v141, v141
	v_add_f32_e32 v152, 1.0, v152
	v_add_f32_e32 v141, 1.0, v141
	v_rcp_f32_e32 v152, v152
	v_rcp_f32_e32 v141, v141
	s_nop 0
	v_cvt_pk_bf16_f32 v157, v141, v152
	v_lshl_add_u64 v[152:153], v[142:143], 0, s[0:1]
	v_lshl_add_u64 v[158:159], v[152:153], 0, v[146:147]
	global_store_dwordx4 v[158:159], v[154:157], off
	s_mov_b64 s[0:1], 0xb0000
	v_ashrrev_i32_e32 v141, 31, v140
	v_pk_add_f32 v[154:155], v[10:11], v[130:131]
	v_pk_add_f32 v[130:131], v[8:9], v[128:129]
	v_mul_f32_e32 v128, 0xbfb8aa3b, v132
	v_mul_f32_e32 v129, 0xbfb8aa3b, v133
	v_exp_f32_e32 v128, v128
	v_exp_f32_e32 v129, v129
	v_mul_f32_e32 v132, 0xbfb8aa3b, v135
	v_mul_f32_e32 v130, 0xbfb8aa3b, v130
	v_add_f32_e32 v128, 1.0, v128
	v_add_f32_e32 v129, 1.0, v129
	v_rcp_f32_e32 v128, v128
	v_rcp_f32_e32 v129, v129
	s_nop 0
	v_cvt_pk_bf16_f32 v128, v128, v129
	v_mul_f32_e32 v129, 0xbfb8aa3b, v134
	v_mul_f32_e32 v131, 0xbfb8aa3b, v131
	v_exp_f32_e32 v129, v129
	v_exp_f32_e32 v132, v132
	v_exp_f32_e32 v130, v130
	v_exp_f32_e32 v131, v131
	v_add_f32_e32 v129, 1.0, v129
	v_add_f32_e32 v132, 1.0, v132
	v_add_f32_e32 v130, 1.0, v130
	v_add_f32_e32 v131, 1.0, v131
	v_rcp_f32_e32 v129, v129
	v_rcp_f32_e32 v132, v132
	v_rcp_f32_e32 v130, v130
	v_rcp_f32_e32 v131, v131
	s_nop 0
	v_cvt_pk_bf16_f32 v129, v129, v132
	v_cvt_pk_bf16_f32 v130, v130, v131
	v_mul_f32_e32 v131, 0xbfb8aa3b, v154
	v_mul_f32_e32 v132, 0xbfb8aa3b, v155
	v_exp_f32_e32 v131, v131
	v_exp_f32_e32 v132, v132
	v_lshl_add_u64 v[154:155], v[142:143], 0, s[0:1]
	s_mov_b64 s[0:1], 0
	v_add_f32_e32 v131, 1.0, v131
	v_add_f32_e32 v132, 1.0, v132
	v_rcp_f32_e32 v131, v131
	v_rcp_f32_e32 v132, v132
	s_nop 0
	v_cvt_pk_bf16_f32 v131, v131, v132
	v_lshl_add_u64 v[132:133], v[154:155], 0, v[146:147]
	global_store_dwordx4 v[132:133], v[128:131], off
	v_lshl_add_u64 v[132:133], v[140:141], 2, s[48:49]
	global_load_dwordx4 v[128:131], v[132:133], off offset:16
	s_nop 0
	global_load_dwordx4 v[132:135], v[132:133], off
	v_lshlrev_b64 v[140:141], 1, v[140:141]
	v_lshl_add_u64 v[142:143], v[142:143], 0, v[140:141]
	v_lshl_add_u64 v[136:137], v[136:137], 0, v[140:141]
	s_waitcnt vmcnt(0)
; __device__ __forceinline__ unsigned cvt_pk_bf16(float lo, float hi) { unsigned r; asm volatile("s_nop 0\n\tv_cvt_pk_bf16_f32 %0, %1, %2\n\ts_nop 1" : "=v"(r) : "v"(lo), "v"(hi)); return r; }
; __device__ __forceinline__ float sigmoidf_(float x) { return __builtin_amdgcn_rcpf(1.f + __expf(-x)); }
;     __device__ __forceinline__ void operator()(f32x4 (&acc)[2][2][4][2], const Unit& u, int wr, int wc, int fr, int fq) const {
;     ...
; #pragma unroll
;             for (int bj = 0; bj < 2; ++bj) { const int col = (u.pn - 12) * 256 + bj * 128 + c8;
;                 const f32x4 b0 = *(const f32x4*)(b_gate + col), b1 = *(const f32x4*)(b_gate + col + 4);
; #pragma unroll
;                 for (int ai = 0; ai < 2; ++ai)
; #pragma unroll
;                     for (int m = 0; m < 4; ++m) { const f32x4 v0 = acc[ai][bj][m][0] + b0, v1 = acc[ai][bj][m][1] + b1;
;                         u32x4 w; w.x = cvt_pk_bf16(sigmoidf_(v0[0]), sigmoidf_(v0[1])); w.y = cvt_pk_bf16(sigmoidf_(v0[2]), sigmoidf_(v0[3]));
;                         w.z = cvt_pk_bf16(sigmoidf_(v1[0]), sigmoidf_(v1[1])); w.w = cvt_pk_bf16(sigmoidf_(v1[2]), sigmoidf_(v1[3]));
;                         *(u32x4*)(gates + (size_t)(row0 + ai * 128 + m * 16) * 2048 + col) = w; } }
	v_pk_add_f32 v[158:159], v[112:113], v[128:129]
	v_pk_add_f32 v[146:147], v[118:119], v[134:135]
	v_pk_add_f32 v[156:157], v[116:117], v[132:133]
	v_mul_f32_e32 v146, 0xbfb8aa3b, v146
	v_mul_f32_e32 v156, 0xbfb8aa3b, v156
	v_mul_f32_e32 v157, 0xbfb8aa3b, v157
	v_mul_f32_e32 v147, 0xbfb8aa3b, v147
	v_exp_f32_e32 v156, v156
	v_exp_f32_e32 v157, v157
	v_exp_f32_e32 v146, v146
	v_exp_f32_e32 v147, v147
	v_add_f32_e32 v156, 1.0, v156
	v_add_f32_e32 v157, 1.0, v157
	v_add_f32_e32 v146, 1.0, v146
	v_add_f32_e32 v147, 1.0, v147
	v_rcp_f32_e32 v156, v156
	v_rcp_f32_e32 v157, v157
	v_rcp_f32_e32 v146, v146
	v_rcp_f32_e32 v147, v147
	s_nop 0
	v_cvt_pk_bf16_f32 v156, v156, v157
	v_cvt_pk_bf16_f32 v157, v146, v147
	v_mul_f32_e32 v146, 0xbfb8aa3b, v158
	v_mul_f32_e32 v147, 0xbfb8aa3b, v159
	v_exp_f32_e32 v146, v146
	v_exp_f32_e32 v147, v147
	v_pk_add_f32 v[160:161], v[114:115], v[130:131]
	v_add_f32_e32 v146, 1.0, v146
	v_add_f32_e32 v147, 1.0, v147
	v_rcp_f32_e32 v146, v146
	v_rcp_f32_e32 v147, v147
	s_nop 0
	v_cvt_pk_bf16_f32 v158, v146, v147
	v_mul_f32_e32 v146, 0xbfb8aa3b, v160
	v_mul_f32_e32 v147, 0xbfb8aa3b, v161
	v_exp_f32_e32 v146, v146
	v_exp_f32_e32 v147, v147
	v_pk_add_f32 v[160:161], v[98:99], v[130:131]
	v_add_f32_e32 v146, 1.0, v146
	v_add_f32_e32 v147, 1.0, v147
	v_rcp_f32_e32 v146, v146
	v_rcp_f32_e32 v147, v147
	s_nop 0
	v_cvt_pk_bf16_f32 v159, v146, v147
	global_store_dwordx4 v[142:143], v[156:159], off
	v_pk_add_f32 v[142:143], v[102:103], v[134:135]
	v_pk_add_f32 v[146:147], v[100:101], v[132:133]
	v_mul_f32_e32 v142, 0xbfb8aa3b, v142
	v_mul_f32_e32 v143, 0xbfb8aa3b, v143
	v_mul_f32_e32 v146, 0xbfb8aa3b, v146
	v_mul_f32_e32 v147, 0xbfb8aa3b, v147
	v_exp_f32_e32 v142, v142
	v_exp_f32_e32 v143, v143
	v_exp_f32_e32 v146, v146
	v_exp_f32_e32 v147, v147
	v_add_f32_e32 v142, 1.0, v142
	v_add_f32_e32 v143, 1.0, v143
	v_pk_add_f32 v[158:159], v[96:97], v[128:129]
	v_add_f32_e32 v146, 1.0, v146
	v_add_f32_e32 v147, 1.0, v147
	v_rcp_f32_e32 v142, v142
	v_rcp_f32_e32 v143, v143
	v_rcp_f32_e32 v146, v146
	v_rcp_f32_e32 v147, v147
	s_nop 0
	v_cvt_pk_bf16_f32 v156, v146, v147
	v_cvt_pk_bf16_f32 v157, v142, v143
	v_mul_f32_e32 v142, 0xbfb8aa3b, v158
	v_mul_f32_e32 v143, 0xbfb8aa3b, v159
	v_exp_f32_e32 v142, v142
	v_exp_f32_e32 v143, v143
	v_pk_add_f32 v[146:147], v[82:83], v[130:131]
	v_add_f32_e32 v142, 1.0, v142
	v_add_f32_e32 v143, 1.0, v143
	v_rcp_f32_e32 v142, v142
	v_rcp_f32_e32 v143, v143
	s_nop 0
	v_cvt_pk_bf16_f32 v158, v142, v143
	v_mul_f32_e32 v142, 0xbfb8aa3b, v160
	v_mul_f32_e32 v143, 0xbfb8aa3b, v161
	v_exp_f32_e32 v142, v142
	v_exp_f32_e32 v143, v143
	v_add_f32_e32 v142, 1.0, v142
	v_add_f32_e32 v143, 1.0, v143
	v_rcp_f32_e32 v142, v142
	v_rcp_f32_e32 v143, v143
	s_nop 0
	v_cvt_pk_bf16_f32 v159, v142, v143
	v_lshl_add_u64 v[142:143], v[144:145], 0, v[140:141]
	global_store_dwordx4 v[142:143], v[156:159], off
	v_pk_add_f32 v[142:143], v[84:85], v[132:133]
	v_pk_add_f32 v[144:145], v[86:87], v[134:135]
	v_mul_f32_e32 v142, 0xbfb8aa3b, v142
	v_mul_f32_e32 v143, 0xbfb8aa3b, v143
	v_exp_f32_e32 v142, v142
	v_exp_f32_e32 v143, v143
	v_pk_add_f32 v[156:157], v[80:81], v[128:129]
	v_add_f32_e32 v142, 1.0, v142
	v_add_f32_e32 v143, 1.0, v143
	v_rcp_f32_e32 v142, v142
	v_rcp_f32_e32 v143, v143
	s_nop 0
	v_cvt_pk_bf16_f32 v142, v142, v143
	v_mul_f32_e32 v143, 0xbfb8aa3b, v144
	v_mul_f32_e32 v144, 0xbfb8aa3b, v145
	v_exp_f32_e32 v143, v143
	v_exp_f32_e32 v144, v144
	v_mul_f32_e32 v145, 0xbfb8aa3b, v157
	v_exp_f32_e32 v145, v145
	v_add_f32_e32 v143, 1.0, v143
	v_add_f32_e32 v144, 1.0, v144
	v_rcp_f32_e32 v143, v143
	v_rcp_f32_e32 v144, v144
	s_nop 0
	v_cvt_pk_bf16_f32 v143, v143, v144
	v_mul_f32_e32 v144, 0xbfb8aa3b, v156
	v_exp_f32_e32 v144, v144
	v_add_f32_e32 v145, 1.0, v145
	v_rcp_f32_e32 v145, v145
	v_add_f32_e32 v144, 1.0, v144
	v_rcp_f32_e32 v144, v144
	s_nop 0
	v_cvt_pk_bf16_f32 v144, v144, v145
	v_mul_f32_e32 v145, 0xbfb8aa3b, v146
	v_exp_f32_e32 v145, v145
	v_mul_f32_e32 v146, 0xbfb8aa3b, v147
	v_exp_f32_e32 v146, v146
	v_add_f32_e32 v145, 1.0, v145
	v_rcp_f32_e32 v145, v145
	v_add_f32_e32 v146, 1.0, v146
	v_rcp_f32_e32 v146, v146
	s_nop 0
	v_cvt_pk_bf16_f32 v145, v145, v146
	global_store_dwordx4 v[136:137], v[142:145], off
	v_pk_add_f32 v[136:137], v[70:71], v[134:135]
	v_pk_add_f32 v[146:147], v[66:67], v[130:131]
	v_pk_add_f32 v[142:143], v[68:69], v[132:133]
	v_mul_f32_e32 v136, 0xbfb8aa3b, v136
	v_mul_f32_e32 v142, 0xbfb8aa3b, v142
	v_mul_f32_e32 v143, 0xbfb8aa3b, v143
	v_mul_f32_e32 v137, 0xbfb8aa3b, v137
	v_exp_f32_e32 v142, v142
	v_exp_f32_e32 v143, v143
	v_exp_f32_e32 v136, v136
	v_exp_f32_e32 v137, v137
	v_add_f32_e32 v142, 1.0, v142
	v_add_f32_e32 v143, 1.0, v143
	v_add_f32_e32 v136, 1.0, v136
	v_add_f32_e32 v137, 1.0, v137
	v_pk_add_f32 v[144:145], v[64:65], v[128:129]
	v_rcp_f32_e32 v142, v142
	v_rcp_f32_e32 v143, v143
	v_rcp_f32_e32 v136, v136
	v_rcp_f32_e32 v137, v137
	s_nop 0
	v_cvt_pk_bf16_f32 v142, v142, v143
	v_cvt_pk_bf16_f32 v143, v136, v137
	v_mul_f32_e32 v136, 0xbfb8aa3b, v144
	v_mul_f32_e32 v137, 0xbfb8aa3b, v145
	v_exp_f32_e32 v136, v136
	v_exp_f32_e32 v137, v137
	v_add_f32_e32 v136, 1.0, v136
	v_add_f32_e32 v137, 1.0, v137
	v_rcp_f32_e32 v136, v136
	v_rcp_f32_e32 v137, v137
	s_nop 0
	v_cvt_pk_bf16_f32 v144, v136, v137
	v_mul_f32_e32 v136, 0xbfb8aa3b, v146
	v_mul_f32_e32 v137, 0xbfb8aa3b, v147
	v_exp_f32_e32 v136, v136
	v_exp_f32_e32 v137, v137
	v_add_f32_e32 v136, 1.0, v136
	v_add_f32_e32 v137, 1.0, v137
	v_rcp_f32_e32 v136, v136
	v_rcp_f32_e32 v137, v137
	s_nop 0
	v_cvt_pk_bf16_f32 v145, v136, v137
	v_lshl_add_u64 v[136:137], v[138:139], 0, v[140:141]
	global_store_dwordx4 v[136:137], v[142:145], off
; __device__ __forceinline__ unsigned cvt_pk_bf16(float lo, float hi) { unsigned r; asm volatile("s_nop 0\n\tv_cvt_pk_bf16_f32 %0, %1, %2\n\ts_nop 1" : "=v"(r) : "v"(lo), "v"(hi)); return r; }
; __device__ __forceinline__ float sigmoidf_(float x) { return __builtin_amdgcn_rcpf(1.f + __expf(-x)); }
;     __device__ __forceinline__ void operator()(f32x4 (&acc)[2][2][4][2], const Unit& u, int wr, int wc, int fr, int fq) const {
;     ...
; #pragma unroll
;             for (int bj = 0; bj < 2; ++bj) { const int col = (u.pn - 12) * 256 + bj * 128 + c8;
;                 const f32x4 b0 = *(const f32x4*)(b_gate + col), b1 = *(const f32x4*)(b_gate + col + 4);
; #pragma unroll
;                 for (int ai = 0; ai < 2; ++ai)
; #pragma unroll
;                     for (int m = 0; m < 4; ++m) { const f32x4 v0 = acc[ai][bj][m][0] + b0, v1 = acc[ai][bj][m][1] + b1;
;                         u32x4 w; w.x = cvt_pk_bf16(sigmoidf_(v0[0]), sigmoidf_(v0[1])); w.y = cvt_pk_bf16(sigmoidf_(v0[2]), sigmoidf_(v0[3]));
;                         w.z = cvt_pk_bf16(sigmoidf_(v1[0]), sigmoidf_(v1[1])); w.w = cvt_pk_bf16(sigmoidf_(v1[2]), sigmoidf_(v1[3]));
;                         *(u32x4*)(gates + (size_t)(row0 + ai * 128 + m * 16) * 2048 + col) = w; } }
	v_pk_add_f32 v[136:137], v[52:53], v[132:133]
	v_pk_add_f32 v[138:139], v[54:55], v[134:135]
	v_mul_f32_e32 v136, 0xbfb8aa3b, v136
	v_mul_f32_e32 v137, 0xbfb8aa3b, v137
	v_exp_f32_e32 v136, v136
	v_exp_f32_e32 v137, v137
	v_pk_add_f32 v[144:145], v[48:49], v[128:129]
	v_pk_add_f32 v[142:143], v[50:51], v[130:131]
	v_add_f32_e32 v136, 1.0, v136
	v_add_f32_e32 v137, 1.0, v137
	v_rcp_f32_e32 v136, v136
	v_rcp_f32_e32 v137, v137
	s_nop 0
	v_cvt_pk_bf16_f32 v136, v136, v137
	v_mul_f32_e32 v137, 0xbfb8aa3b, v138
	v_mul_f32_e32 v138, 0xbfb8aa3b, v139
	v_exp_f32_e32 v137, v137
	v_exp_f32_e32 v138, v138
	v_mul_f32_e32 v139, 0xbfb8aa3b, v145
	v_exp_f32_e32 v139, v139
	v_add_f32_e32 v137, 1.0, v137
	v_add_f32_e32 v138, 1.0, v138
	v_rcp_f32_e32 v137, v137
	v_rcp_f32_e32 v138, v138
	s_nop 0
	v_cvt_pk_bf16_f32 v137, v137, v138
	v_mul_f32_e32 v138, 0xbfb8aa3b, v144
	v_exp_f32_e32 v138, v138
	v_add_f32_e32 v139, 1.0, v139
	v_rcp_f32_e32 v139, v139
	v_pk_add_f32 v[144:145], v[32:33], v[128:129]
	v_add_f32_e32 v138, 1.0, v138
	v_rcp_f32_e32 v138, v138
	s_nop 0
	v_cvt_pk_bf16_f32 v138, v138, v139
	v_mul_f32_e32 v139, 0xbfb8aa3b, v142
	v_mul_f32_e32 v142, 0xbfb8aa3b, v143
	v_exp_f32_e32 v139, v139
	v_exp_f32_e32 v142, v142
	v_add_f32_e32 v139, 1.0, v139
	v_add_f32_e32 v142, 1.0, v142
	v_rcp_f32_e32 v139, v139
	v_rcp_f32_e32 v142, v142
	s_nop 0
	v_cvt_pk_bf16_f32 v139, v139, v142
	v_lshl_add_u64 v[142:143], v[148:149], 0, v[140:141]
	global_store_dwordx4 v[142:143], v[136:139], off
	v_pk_add_f32 v[142:143], v[34:35], v[130:131]
	s_nop 0
	v_pk_add_f32 v[136:137], v[36:37], v[132:133]
	v_pk_add_f32 v[138:139], v[38:39], v[134:135]
	v_mul_f32_e32 v136, 0xbfb8aa3b, v136
	v_mul_f32_e32 v137, 0xbfb8aa3b, v137
	v_exp_f32_e32 v136, v136
	v_exp_f32_e32 v137, v137
	v_add_f32_e32 v136, 1.0, v136
	v_add_f32_e32 v137, 1.0, v137
	v_rcp_f32_e32 v136, v136
	v_rcp_f32_e32 v137, v137
	s_nop 0
	v_cvt_pk_bf16_f32 v136, v136, v137
	v_mul_f32_e32 v137, 0xbfb8aa3b, v138
	v_mul_f32_e32 v138, 0xbfb8aa3b, v139
	v_exp_f32_e32 v137, v137
	v_exp_f32_e32 v138, v138
	v_mul_f32_e32 v139, 0xbfb8aa3b, v145
	v_exp_f32_e32 v139, v139
	v_add_f32_e32 v137, 1.0, v137
	v_add_f32_e32 v138, 1.0, v138
	v_rcp_f32_e32 v137, v137
	v_rcp_f32_e32 v138, v138
	s_nop 0
	v_cvt_pk_bf16_f32 v137, v137, v138
	v_mul_f32_e32 v138, 0xbfb8aa3b, v144
	v_exp_f32_e32 v138, v138
	v_add_f32_e32 v139, 1.0, v139
	v_rcp_f32_e32 v139, v139
	v_pk_add_f32 v[144:145], v[16:17], v[128:129]
	v_add_f32_e32 v138, 1.0, v138
	v_rcp_f32_e32 v138, v138
	s_nop 0
	v_cvt_pk_bf16_f32 v138, v138, v139
	v_mul_f32_e32 v139, 0xbfb8aa3b, v142
	v_mul_f32_e32 v142, 0xbfb8aa3b, v143
	v_exp_f32_e32 v139, v139
	v_exp_f32_e32 v142, v142
	v_add_f32_e32 v139, 1.0, v139
	v_add_f32_e32 v142, 1.0, v142
	v_rcp_f32_e32 v139, v139
	v_rcp_f32_e32 v142, v142
	s_nop 0
	v_cvt_pk_bf16_f32 v139, v139, v142
	v_lshl_add_u64 v[142:143], v[150:151], 0, v[140:141]
	global_store_dwordx4 v[142:143], v[136:139], off
	v_pk_add_f32 v[142:143], v[18:19], v[130:131]
	s_nop 0
	v_pk_add_f32 v[136:137], v[20:21], v[132:133]
	v_pk_add_f32 v[138:139], v[22:23], v[134:135]
	v_mul_f32_e32 v136, 0xbfb8aa3b, v136
	v_mul_f32_e32 v137, 0xbfb8aa3b, v137
	v_exp_f32_e32 v136, v136
	v_exp_f32_e32 v137, v137
	v_pk_add_f32 v[132:133], v[4:5], v[132:133]
	v_pk_add_f32 v[134:135], v[6:7], v[134:135]
	v_add_f32_e32 v136, 1.0, v136
	v_add_f32_e32 v137, 1.0, v137
	v_rcp_f32_e32 v136, v136
	v_rcp_f32_e32 v137, v137
	s_nop 0
	v_cvt_pk_bf16_f32 v136, v136, v137
	v_mul_f32_e32 v137, 0xbfb8aa3b, v138
	v_mul_f32_e32 v138, 0xbfb8aa3b, v139
	v_exp_f32_e32 v137, v137
	v_exp_f32_e32 v138, v138
	v_mul_f32_e32 v139, 0xbfb8aa3b, v145
	v_exp_f32_e32 v139, v139
	v_add_f32_e32 v137, 1.0, v137
	v_add_f32_e32 v138, 1.0, v138
	v_rcp_f32_e32 v137, v137
	v_rcp_f32_e32 v138, v138
	s_nop 0
	v_cvt_pk_bf16_f32 v137, v137, v138
	v_mul_f32_e32 v138, 0xbfb8aa3b, v144
	v_exp_f32_e32 v138, v138
	v_add_f32_e32 v139, 1.0, v139
	v_rcp_f32_e32 v139, v139
	v_add_f32_e32 v138, 1.0, v138
	v_rcp_f32_e32 v138, v138
	s_nop 0
	v_cvt_pk_bf16_f32 v138, v138, v139
	v_mul_f32_e32 v139, 0xbfb8aa3b, v142
	v_mul_f32_e32 v142, 0xbfb8aa3b, v143
	v_exp_f32_e32 v139, v139
	v_exp_f32_e32 v142, v142
	v_add_f32_e32 v139, 1.0, v139
	v_add_f32_e32 v142, 1.0, v142
	v_rcp_f32_e32 v139, v139
	v_rcp_f32_e32 v142, v142
	s_nop 0
	v_cvt_pk_bf16_f32 v139, v139, v142
	v_lshl_add_u64 v[142:143], v[152:153], 0, v[140:141]
	global_store_dwordx4 v[142:143], v[136:139], off
	s_nop 1
	v_pk_add_f32 v[136:137], v[2:3], v[130:131]
	v_pk_add_f32 v[130:131], v[0:1], v[128:129]
	v_mul_f32_e32 v128, 0xbfb8aa3b, v132
	v_mul_f32_e32 v129, 0xbfb8aa3b, v133
	v_exp_f32_e32 v128, v128
	v_exp_f32_e32 v129, v129
	v_mul_f32_e32 v132, 0xbfb8aa3b, v135
	v_mul_f32_e32 v130, 0xbfb8aa3b, v130
	v_add_f32_e32 v128, 1.0, v128
	v_add_f32_e32 v129, 1.0, v129
	v_rcp_f32_e32 v128, v128
	v_rcp_f32_e32 v129, v129
	s_nop 0
	v_cvt_pk_bf16_f32 v128, v128, v129
	v_mul_f32_e32 v129, 0xbfb8aa3b, v134
	v_mul_f32_e32 v131, 0xbfb8aa3b, v131
	v_exp_f32_e32 v129, v129
	v_exp_f32_e32 v132, v132
	v_exp_f32_e32 v130, v130
	v_exp_f32_e32 v131, v131
	v_add_f32_e32 v129, 1.0, v129
	v_add_f32_e32 v132, 1.0, v132
	v_add_f32_e32 v130, 1.0, v130
	v_add_f32_e32 v131, 1.0, v131
	v_rcp_f32_e32 v129, v129
	v_rcp_f32_e32 v132, v132
	v_rcp_f32_e32 v130, v130
	v_rcp_f32_e32 v131, v131
	s_nop 0
	v_cvt_pk_bf16_f32 v129, v129, v132
	v_cvt_pk_bf16_f32 v130, v130, v131
	v_mul_f32_e32 v131, 0xbfb8aa3b, v136
	v_mul_f32_e32 v132, 0xbfb8aa3b, v137
	v_exp_f32_e32 v131, v131
	v_exp_f32_e32 v132, v132
	v_add_f32_e32 v131, 1.0, v131
	v_add_f32_e32 v132, 1.0, v132
	v_rcp_f32_e32 v131, v131
	v_rcp_f32_e32 v132, v132
	s_nop 0
	v_cvt_pk_bf16_f32 v131, v131, v132
	v_lshl_add_u64 v[132:133], v[154:155], 0, v[140:141]
	global_store_dwordx4 v[132:133], v[128:131], off
; __device__ __forceinline__ float bflo(unsigned w) { return __uint_as_float(w << 16); }
; __device__ __forceinline__ float bfhi(unsigned w) { return __uint_as_float(w & 0xffff0000u); }
; __device__ __forceinline__ float gelu_tanh(float x) { const float y = 0.7978845608028654f * (x + 0.044715f * x * x * x); const float t = 1.f - 2.f * __builtin_amdgcn_rcpf(1.f + __expf(2.f * y)); return 0.5f * x * (1.f + t); }
;     __device__ __forceinline__ void operator()(f32x4 (&acc)[2][2][4][2], const Unit& u, int wr, int wc, int fr, int fq) const {
;     ...
;             for (int ai = 0; ai < 2; ++ai) {
;                 u32x4 ya[4][2], yb[4][2];
; #pragma unroll
;                 for (int m = 0; m < 4; ++m)
; #pragma unroll
;                     for (int bj = 0; bj < 2; ++bj) { const size_t idx = (size_t)(row0 + ai * 128 + m * 16) * 1024 + (u.pn - 8) * 256 + bj * 128 + c8;
;                         ya[m][bj] = *(const u32x4*)(ylf + idx); yb[m][bj] = *(const u32x4*)(ylb + idx); }
; #pragma unroll
;                 for (int m = 0; m < 4; ++m)
; #pragma unroll
;                     for (int bj = 0; bj < 2; ++bj) { const size_t idx = (size_t)(row0 + ai * 128 + m * 16) * 1024 + (u.pn - 8) * 256 + bj * 128 + c8;
;                         const u32x4 a = ya[m][bj], b = yb[m][bj];
;                         float yv[8] = {bflo(a.x) + bflo(b.x), bfhi(a.x) + bfhi(b.x), bflo(a.y) + bflo(b.y), bfhi(a.y) + bfhi(b.y), bflo(a.z) + bflo(b.z), bfhi(a.z) + bfhi(b.z), bflo(a.w) + bflo(b.w), bfhi(a.w) + bfhi(b.w)};
;                         float o[8];
; #pragma unroll
;                         for (int n = 0; n < 2; ++n)
; #pragma unroll
;                             for (int j = 0; j < 4; ++j) o[4 * n + j] = yv[4 * n + j] * gelu_tanh(acc[ai][bj][m][n][j]);
.LBB0_392:
	s_andn2_b64 vcc, exec, s[0:1]
	s_cbranch_vccnz .LBB0_394
	v_ashrrev_i32_e32 v215, 31, v214
	v_add_u32_e32 v192, s17, v247
	v_lshlrev_b64 v[128:129], 10, v[214:215]
	v_lshl_add_u64 v[128:129], v[128:129], 0, v[192:193]
	v_lshlrev_b64 v[128:129], 1, v[128:129]
	v_lshl_add_u64 v[130:131], s[10:11], 0, v[128:129]
	global_load_dwordx4 v[230:233], v[130:131], off
	v_lshl_add_u64 v[130:131], s[12:13], 0, v[128:129]
	global_load_dwordx4 v[194:197], v[130:131], off
	v_mov_b64_e32 v[234:235], v[252:253]
	v_lshlrev_b64 v[184:185], 11, v[214:215]
	v_or_b32_e32 v128, 0x100, v128
	v_lshl_add_u64 v[130:131], s[10:11], 0, v[128:129]
	global_load_dwordx4 v[176:179], v[130:131], off
	v_lshl_add_u64 v[128:129], s[12:13], 0, v[128:129]
	global_load_dwordx4 v[180:183], v[128:129], off
	v_or_b32_e32 v190, 16, v214
	v_ashrrev_i32_e32 v191, 31, v190
	v_lshlrev_b64 v[128:129], 10, v[190:191]
	v_lshl_add_u64 v[128:129], v[128:129], 0, v[192:193]
	v_lshlrev_b64 v[128:129], 1, v[128:129]
	v_lshl_add_u64 v[130:131], s[10:11], 0, v[128:129]
	global_load_dwordx4 v[168:171], v[130:131], off
	v_lshl_add_u64 v[130:131], s[12:13], 0, v[128:129]
	v_or_b32_e32 v128, 0x100, v128
	v_or_b32_e32 v188, 32, v214
	global_load_dwordx4 v[172:175], v[130:131], off
	v_lshl_add_u64 v[130:131], s[10:11], 0, v[128:129]
	v_lshl_add_u64 v[128:129], s[12:13], 0, v[128:129]
	v_ashrrev_i32_e32 v189, 31, v188
	global_load_dwordx4 v[160:163], v[130:131], off
	global_load_dwordx4 v[164:167], v[128:129], off
	v_lshlrev_b64 v[128:129], 10, v[188:189]
	v_lshl_add_u64 v[128:129], v[128:129], 0, v[192:193]
	v_lshlrev_b64 v[128:129], 1, v[128:129]
	v_lshl_add_u64 v[130:131], s[10:11], 0, v[128:129]
	global_load_dwordx4 v[152:155], v[130:131], off
	v_lshl_add_u64 v[130:131], s[12:13], 0, v[128:129]
	v_or_b32_e32 v128, 0x100, v128
	v_or_b32_e32 v186, 48, v214
	global_load_dwordx4 v[156:159], v[130:131], off
	v_lshl_add_u64 v[130:131], s[10:11], 0, v[128:129]
	v_lshl_add_u64 v[128:129], s[12:13], 0, v[128:129]
	v_ashrrev_i32_e32 v187, 31, v186
	global_load_dwordx4 v[144:147], v[130:131], off
	global_load_dwordx4 v[148:151], v[128:129], off
	v_lshlrev_b64 v[128:129], 10, v[186:187]
	v_lshl_add_u64 v[128:129], v[128:129], 0, v[192:193]
	v_lshlrev_b64 v[132:133], 1, v[128:129]
	v_lshl_add_u64 v[128:129], s[10:11], 0, v[132:133]
	global_load_dwordx4 v[136:139], v[128:129], off
	v_lshl_add_u64 v[128:129], s[12:13], 0, v[132:133]
	v_or_b32_e32 v132, 0x100, v132
	v_lshl_add_u64 v[184:185], s[10:11], 0, v[184:185]
	s_lshl_b32 s66, s17, 1
	global_load_dwordx4 v[140:143], v[128:129], off
	v_lshl_add_u64 v[128:129], s[10:11], 0, v[132:133]
	v_lshl_add_u64 v[132:133], s[12:13], 0, v[132:133]
	global_load_dwordx4 v[128:131], v[128:129], off
	s_waitcnt vmcnt(0)
	v_lshlrev_b32_e32 v253, 16, v230
	v_and_b32_e32 v229, 0xffff0000, v230
	v_lshlrev_b32_e32 v199, 16, v194
	v_and_b32_e32 v226, 0xffff0000, v194
	v_mul_f32_e32 v194, 0x3d372713, v124
	v_mul_f32_e32 v194, v124, v194
	v_fma_f32 v194, v124, v194, v124
	v_mul_f32_e32 v194, 0x3f4c422a, v194
	v_add_f32_e32 v194, v194, v194
	v_mul_f32_e32 v194, 0x3fb8aa3b, v194
	v_exp_f32_e32 v194, v194
	v_lshlrev_b32_e32 v224, 16, v195
	v_and_b32_e32 v222, 0xffff0000, v195
	v_lshlrev_b32_e32 v220, 16, v196
	v_add_f32_e32 v194, 1.0, v194
	v_rcp_f32_e32 v194, v194
	v_and_b32_e32 v218, 0xffff0000, v196
	v_mul_f32_e32 v196, 0.5, v124
	v_lshlrev_b32_e32 v227, 16, v231
	v_fma_f32 v252, v194, -2.0, 1.0
	v_pk_add_f32 v[194:195], v[252:253], v[198:199]
	v_mov_b32_e32 v199, v226
	v_mul_f32_e32 v194, v196, v194
	v_mul_f32_e32 v230, v194, v195
	v_mul_f32_e32 v194, 0x3d372713, v125
	v_mul_f32_e32 v194, v125, v194
	v_fma_f32 v194, v125, v194, v125
	v_mul_f32_e32 v194, 0x3f4c422a, v194
	v_add_f32_e32 v194, v194, v194
	v_mul_f32_e32 v194, 0x3fb8aa3b, v194
	v_exp_f32_e32 v194, v194
	v_mul_f32_e32 v196, 0.5, v125
	v_lshlrev_b32_e32 v216, 16, v197
	v_and_b32_e32 v215, 0xffff0000, v197
	v_add_f32_e32 v194, 1.0, v194
	v_rcp_f32_e32 v194, v194
	v_mul_f32_e32 v197, 0.5, v126
	v_and_b32_e32 v225, 0xffff0000, v231
	v_lshlrev_b32_e32 v223, 16, v232
	v_fma_f32 v228, v194, -2.0, 1.0
	v_pk_add_f32 v[194:195], v[228:229], v[198:199]
	v_mov_b32_e32 v199, v224
	v_mul_f32_e32 v194, v196, v194
	v_mul_f32_e32 v196, v194, v195
	v_mul_f32_e32 v194, 0x3d372713, v126
	v_mul_f32_e32 v194, v126, v194
	v_fma_f32 v194, v126, v194, v126
	v_mul_f32_e32 v194, 0x3f4c422a, v194
	v_add_f32_e32 v194, v194, v194
	v_mul_f32_e32 v194, 0x3fb8aa3b, v194
	v_exp_f32_e32 v194, v194
	v_and_b32_e32 v221, 0xffff0000, v232
	v_lshlrev_b32_e32 v219, 16, v233
	v_and_b32_e32 v217, 0xffff0000, v233
	v_add_f32_e32 v194, 1.0, v194
	v_rcp_f32_e32 v194, v194
	global_load_dwordx4 v[132:135], v[132:133], off
	v_mov_b64_e32 v[252:253], v[234:235]
	v_fma_f32 v226, v194, -2.0, 1.0
	v_pk_add_f32 v[194:195], v[226:227], v[198:199]
	v_mov_b32_e32 v199, v222
	v_mul_f32_e32 v194, v197, v194
	v_mul_f32_e32 v197, v194, v195
	v_mul_f32_e32 v194, 0x3d372713, v127
	v_mul_f32_e32 v194, v127, v194
	v_fma_f32 v194, v127, v194, v127
	v_mul_f32_e32 v194, 0x3f4c422a, v194
	v_add_f32_e32 v194, v194, v194
	v_mul_f32_e32 v194, 0x3fb8aa3b, v194
	v_exp_f32_e32 v194, v194
	v_mul_f32_e32 v226, 0.5, v127
	v_add_f32_e32 v194, 1.0, v194
	v_rcp_f32_e32 v194, v194
	s_nop 0
	v_fma_f32 v224, v194, -2.0, 1.0
	v_pk_add_f32 v[194:195], v[224:225], v[198:199]
	v_mov_b32_e32 v199, v220
	v_mul_f32_e32 v194, v226, v194
	v_mul_f32_e32 v224, v194, v195
	v_mul_f32_e32 v194, 0x3d372713, v120
	v_mul_f32_e32 v194, v120, v194
	v_fma_f32 v194, v120, v194, v120
	v_mul_f32_e32 v194, 0x3f4c422a, v194
	v_add_f32_e32 v194, v194, v194
	v_mul_f32_e32 v194, 0x3fb8aa3b, v194
	v_exp_f32_e32 v194, v194
; __device__ __forceinline__ unsigned cvt_pk_bf16(float lo, float hi) { unsigned r; asm volatile("s_nop 0\n\tv_cvt_pk_bf16_f32 %0, %1, %2\n\ts_nop 1" : "=v"(r) : "v"(lo), "v"(hi)); return r; }
; __device__ __forceinline__ float bflo(unsigned w) { return __uint_as_float(w << 16); }
; __device__ __forceinline__ float bfhi(unsigned w) { return __uint_as_float(w & 0xffff0000u); }
; __device__ __forceinline__ float gelu_tanh(float x) { const float y = 0.7978845608028654f * (x + 0.044715f * x * x * x); const float t = 1.f - 2.f * __builtin_amdgcn_rcpf(1.f + __expf(2.f * y)); return 0.5f * x * (1.f + t); }
;     __device__ __forceinline__ void operator()(f32x4 (&acc)[2][2][4][2], const Unit& u, int wr, int wc, int fr, int fq) const {
;     ...
;                 for (int m = 0; m < 4; ++m)
; #pragma unroll
;                     for (int bj = 0; bj < 2; ++bj) { const size_t idx = (size_t)(row0 + ai * 128 + m * 16) * 1024 + (u.pn - 8) * 256 + bj * 128 + c8;
;                         const u32x4 a = ya[m][bj], b = yb[m][bj];
;                         float yv[8] = {bflo(a.x) + bflo(b.x), bfhi(a.x) + bfhi(b.x), bflo(a.y) + bflo(b.y), bfhi(a.y) + bfhi(b.y), bflo(a.z) + bflo(b.z), bfhi(a.z) + bfhi(b.z), bflo(a.w) + bflo(b.w), bfhi(a.w) + bfhi(b.w)};
;                         float o[8];
; #pragma unroll
;                         for (int n = 0; n < 2; ++n)
; #pragma unroll
;                             for (int j = 0; j < 4; ++j) o[4 * n + j] = yv[4 * n + j] * gelu_tanh(acc[ai][bj][m][n][j]);
;                         u32x4 w; w.x = cvt_pk_bf16(o[0], o[1]); w.y = cvt_pk_bf16(o[2], o[3]); w.z = cvt_pk_bf16(o[4], o[5]); w.w = cvt_pk_bf16(o[6], o[7]);
;                         *(u32x4*)(ylf + idx) = w; }
	v_mul_f32_e32 v225, 0.5, v120
	v_lshlrev_b32_e32 v226, 16, v183
	v_and_b32_e32 v183, 0xffff0000, v183
	v_add_f32_e32 v194, 1.0, v194
	v_rcp_f32_e32 v194, v194
	s_nop 0
	v_fma_f32 v222, v194, -2.0, 1.0
	v_pk_add_f32 v[194:195], v[222:223], v[198:199]
	v_mov_b32_e32 v199, v218
	v_mul_f32_e32 v194, v225, v194
	v_mul_f32_e32 v222, v194, v195
	v_mul_f32_e32 v194, 0x3d372713, v121
	v_mul_f32_e32 v194, v121, v194
	v_fma_f32 v194, v121, v194, v121
	v_mul_f32_e32 v194, 0x3f4c422a, v194
	v_add_f32_e32 v194, v194, v194
	v_mul_f32_e32 v194, 0x3fb8aa3b, v194
	v_exp_f32_e32 v194, v194
	v_mul_f32_e32 v223, 0.5, v121
	v_and_b32_e32 v225, 0xffff0000, v177
	v_add_f32_e32 v194, 1.0, v194
	v_rcp_f32_e32 v194, v194
	s_nop 0
	v_fma_f32 v220, v194, -2.0, 1.0
	v_pk_add_f32 v[194:195], v[220:221], v[198:199]
	v_mov_b32_e32 v199, v216
	v_mul_f32_e32 v194, v223, v194
	v_mul_f32_e32 v220, v194, v195
	v_mul_f32_e32 v194, 0x3d372713, v122
	v_mul_f32_e32 v194, v122, v194
	v_fma_f32 v194, v122, v194, v122
	v_mul_f32_e32 v194, 0x3f4c422a, v194
	v_add_f32_e32 v194, v194, v194
	v_mul_f32_e32 v194, 0x3fb8aa3b, v194
	v_exp_f32_e32 v194, v194
	v_mul_f32_e32 v221, 0.5, v122
	v_lshlrev_b32_e32 v223, 16, v177
	v_and_b32_e32 v177, 0xffff0000, v179
	v_add_f32_e32 v194, 1.0, v194
	v_rcp_f32_e32 v194, v194
	s_nop 0
	v_fma_f32 v218, v194, -2.0, 1.0
	v_pk_add_f32 v[194:195], v[218:219], v[198:199]
	v_mov_b32_e32 v199, v215
	v_mul_f32_e32 v194, v221, v194
	v_mul_f32_e32 v218, v194, v195
	v_mul_f32_e32 v194, 0x3d372713, v123
	v_mul_f32_e32 v194, v123, v194
	v_fma_f32 v194, v123, v194, v123
	v_mul_f32_e32 v194, 0x3f4c422a, v194
	v_add_f32_e32 v194, v194, v194
	v_mul_f32_e32 v194, 0x3fb8aa3b, v194
	v_exp_f32_e32 v194, v194
	v_mul_f32_e32 v219, 0.5, v123
	v_lshlrev_b32_e32 v221, 16, v178
	v_and_b32_e32 v215, 0xffff0000, v181
	v_add_f32_e32 v194, 1.0, v194
	v_rcp_f32_e32 v194, v194
	s_nop 0
	v_fma_f32 v216, v194, -2.0, 1.0
	v_pk_add_f32 v[194:195], v[216:217], v[198:199]
	v_lshl_add_u64 v[216:217], v[184:185], 0, s[66:67]
	v_mul_f32_e32 v194, v219, v194
	v_and_b32_e32 v219, 0xffff0000, v178
	v_mul_f32_e32 v178, 0x3d372713, v116
	v_mul_f32_e32 v178, v116, v178
	v_fma_f32 v178, v116, v178, v116
	v_mul_f32_e32 v178, 0x3f4c422a, v178
	v_add_f32_e32 v178, v178, v178
	v_mul_f32_e32 v178, 0x3fb8aa3b, v178
	v_exp_f32_e32 v178, v178
	v_lshlrev_b32_e32 v184, 1, v208
	v_mov_b32_e32 v185, v193
	v_mul_f32_e32 v199, v194, v195
	v_add_f32_e32 v178, 1.0, v178
	v_rcp_f32_e32 v178, v178
	s_nop 0
	v_cvt_pk_bf16_f32 v194, v230, v196
	v_cvt_pk_bf16_f32 v195, v197, v224
	v_lshl_add_u64 v[216:217], v[216:217], 0, v[184:185]
	v_cvt_pk_bf16_f32 v196, v222, v220
	v_cvt_pk_bf16_f32 v197, v218, v199
	global_store_dwordx4 v[216:217], v[194:197], off offset:-4096
	v_lshlrev_b32_e32 v199, 16, v180
	v_lshlrev_b32_e32 v218, 16, v182
	v_lshlrev_b32_e32 v195, 16, v176
	v_fma_f32 v194, v178, -2.0, 1.0
	v_and_b32_e32 v197, 0xffff0000, v176
	v_and_b32_e32 v176, 0xffff0000, v180
	v_lshlrev_b32_e32 v180, 16, v181
	v_lshlrev_b32_e32 v181, 16, v179
	v_mul_f32_e32 v196, 0.5, v116
	v_pk_add_f32 v[178:179], v[194:195], v[198:199]
	v_mov_b32_e32 v199, v176
	v_mul_f32_e32 v178, v196, v178
	v_mul_f32_e32 v194, v178, v179
	v_mul_f32_e32 v178, 0x3d372713, v117
	v_mul_f32_e32 v178, v117, v178
	v_fma_f32 v178, v117, v178, v117
	v_mul_f32_e32 v178, 0x3f4c422a, v178
	v_add_f32_e32 v178, v178, v178
	v_mul_f32_e32 v178, 0x3fb8aa3b, v178
	v_exp_f32_e32 v178, v178
	v_mul_f32_e32 v195, 0.5, v117
	v_and_b32_e32 v182, 0xffff0000, v182
	v_add_f32_e32 v178, 1.0, v178
	v_rcp_f32_e32 v178, v178
	s_nop 0
	v_fma_f32 v196, v178, -2.0, 1.0
	v_pk_add_f32 v[178:179], v[196:197], v[198:199]
	v_mov_b32_e32 v199, v180
	v_mul_f32_e32 v176, v195, v178
	v_mul_f32_e32 v195, v176, v179
	v_mul_f32_e32 v176, 0x3d372713, v118
	v_mul_f32_e32 v176, v118, v176
	v_fma_f32 v176, v118, v176, v118
	v_mul_f32_e32 v176, 0x3f4c422a, v176
	v_add_f32_e32 v176, v176, v176
	v_mul_f32_e32 v176, 0x3fb8aa3b, v176
	v_exp_f32_e32 v176, v176
	s_nop 0
	v_add_f32_e32 v176, 1.0, v176
	v_rcp_f32_e32 v176, v176
	s_nop 0
	v_fma_f32 v222, v176, -2.0, 1.0
	v_mul_f32_e32 v176, 0.5, v118
	v_pk_add_f32 v[178:179], v[222:223], v[198:199]
	v_mov_b32_e32 v199, v215
	v_mul_f32_e32 v176, v176, v178
	v_mul_f32_e32 v196, v176, v179
	v_mul_f32_e32 v176, 0x3d372713, v119
	v_mul_f32_e32 v176, v119, v176
	v_fma_f32 v176, v119, v176, v119
	v_mul_f32_e32 v176, 0x3f4c422a, v176
	v_add_f32_e32 v176, v176, v176
	v_mul_f32_e32 v176, 0x3fb8aa3b, v176
	v_exp_f32_e32 v176, v176
	v_mul_f32_e32 v222, 0.5, v60
	v_add_f32_e32 v176, 1.0, v176
	v_rcp_f32_e32 v176, v176
	s_nop 0
	v_fma_f32 v224, v176, -2.0, 1.0
	v_mul_f32_e32 v176, 0.5, v119
	v_pk_add_f32 v[178:179], v[224:225], v[198:199]
	v_mov_b32_e32 v199, v218
	v_mul_f32_e32 v176, v176, v178
	v_mul_f32_e32 v197, v176, v179
	v_mul_f32_e32 v176, 0x3d372713, v112
	v_mul_f32_e32 v176, v112, v176
	v_fma_f32 v176, v112, v176, v112
	v_mul_f32_e32 v176, 0x3f4c422a, v176
	v_add_f32_e32 v176, v176, v176
	v_mul_f32_e32 v176, 0x3fb8aa3b, v176
	v_exp_f32_e32 v176, v176
	s_nop 0
	v_add_f32_e32 v176, 1.0, v176
	v_rcp_f32_e32 v176, v176
	s_nop 0
	v_fma_f32 v220, v176, -2.0, 1.0
	v_mul_f32_e32 v176, 0.5, v112
	v_pk_add_f32 v[178:179], v[220:221], v[198:199]
	v_mov_b32_e32 v199, v182
	v_mul_f32_e32 v176, v176, v178
	v_mul_f32_e32 v215, v176, v179
	v_mul_f32_e32 v176, 0x3d372713, v113
	v_mul_f32_e32 v176, v113, v176
	v_fma_f32 v176, v113, v176, v113
	v_mul_f32_e32 v176, 0x3f4c422a, v176
	v_add_f32_e32 v176, v176, v176
	v_mul_f32_e32 v176, 0x3fb8aa3b, v176
	v_exp_f32_e32 v176, v176
	s_nop 0
	v_add_f32_e32 v176, 1.0, v176
	v_rcp_f32_e32 v176, v176
	s_nop 0
	v_fma_f32 v218, v176, -2.0, 1.0
; __device__ __forceinline__ unsigned cvt_pk_bf16(float lo, float hi) { unsigned r; asm volatile("s_nop 0\n\tv_cvt_pk_bf16_f32 %0, %1, %2\n\ts_nop 1" : "=v"(r) : "v"(lo), "v"(hi)); return r; }
; __device__ __forceinline__ float bflo(unsigned w) { return __uint_as_float(w << 16); }
; __device__ __forceinline__ float bfhi(unsigned w) { return __uint_as_float(w & 0xffff0000u); }
; __device__ __forceinline__ float gelu_tanh(float x) { const float y = 0.7978845608028654f * (x + 0.044715f * x * x * x); const float t = 1.f - 2.f * __builtin_amdgcn_rcpf(1.f + __expf(2.f * y)); return 0.5f * x * (1.f + t); }
;     __device__ __forceinline__ void operator()(f32x4 (&acc)[2][2][4][2], const Unit& u, int wr, int wc, int fr, int fq) const {
;     ...
;                 for (int m = 0; m < 4; ++m)
; #pragma unroll
;                     for (int bj = 0; bj < 2; ++bj) { const size_t idx = (size_t)(row0 + ai * 128 + m * 16) * 1024 + (u.pn - 8) * 256 + bj * 128 + c8;
;                         const u32x4 a = ya[m][bj], b = yb[m][bj];
;                         float yv[8] = {bflo(a.x) + bflo(b.x), bfhi(a.x) + bfhi(b.x), bflo(a.y) + bflo(b.y), bfhi(a.y) + bfhi(b.y), bflo(a.z) + bflo(b.z), bfhi(a.z) + bfhi(b.z), bflo(a.w) + bflo(b.w), bfhi(a.w) + bfhi(b.w)};
;                         float o[8];
; #pragma unroll
;                         for (int n = 0; n < 2; ++n)
; #pragma unroll
;                             for (int j = 0; j < 4; ++j) o[4 * n + j] = yv[4 * n + j] * gelu_tanh(acc[ai][bj][m][n][j]);
;                         u32x4 w; w.x = cvt_pk_bf16(o[0], o[1]); w.y = cvt_pk_bf16(o[2], o[3]); w.z = cvt_pk_bf16(o[4], o[5]); w.w = cvt_pk_bf16(o[6], o[7]);
;                         *(u32x4*)(ylf + idx) = w; }
	v_mul_f32_e32 v176, 0.5, v113
	v_pk_add_f32 v[178:179], v[218:219], v[198:199]
	v_mov_b32_e32 v199, v226
	v_mul_f32_e32 v176, v176, v178
	v_mul_f32_e32 v182, v176, v179
	v_mul_f32_e32 v176, 0x3d372713, v114
	v_mul_f32_e32 v176, v114, v176
	v_fma_f32 v176, v114, v176, v114
	v_mul_f32_e32 v176, 0x3f4c422a, v176
	v_add_f32_e32 v176, v176, v176
	v_mul_f32_e32 v176, 0x3fb8aa3b, v176
	v_exp_f32_e32 v176, v176
	s_nop 0
	v_add_f32_e32 v176, 1.0, v176
	v_rcp_f32_e32 v176, v176
	s_nop 0
	v_fma_f32 v180, v176, -2.0, 1.0
	v_mul_f32_e32 v176, 0.5, v114
	v_pk_add_f32 v[178:179], v[180:181], v[198:199]
	v_mov_b32_e32 v199, v183
	v_mul_f32_e32 v176, v176, v178
	v_mul_f32_e32 v179, v176, v179
	v_mul_f32_e32 v176, 0x3d372713, v115
	v_mul_f32_e32 v176, v115, v176
	v_fma_f32 v176, v115, v176, v115
	v_mul_f32_e32 v176, 0x3f4c422a, v176
	v_add_f32_e32 v176, v176, v176
	v_mul_f32_e32 v176, 0x3fb8aa3b, v176
	v_exp_f32_e32 v176, v176
	v_mul_f32_e32 v178, 0.5, v115
	v_lshlrev_b32_e32 v181, 16, v170
	v_lshlrev_b32_e32 v183, 16, v168
	v_add_f32_e32 v176, 1.0, v176
	v_rcp_f32_e32 v176, v176
	s_nop 0
	v_fma_f32 v176, v176, -2.0, 1.0
	v_pk_add_f32 v[176:177], v[176:177], v[198:199]
	v_lshlrev_b32_e32 v199, 16, v172
	v_mul_f32_e32 v176, v178, v176
	v_mul_f32_e32 v180, v176, v177
	v_cvt_pk_bf16_f32 v176, v194, v195
	v_cvt_pk_bf16_f32 v177, v196, v197
	v_cvt_pk_bf16_f32 v178, v215, v182
	v_cvt_pk_bf16_f32 v179, v179, v180
	global_store_dwordx4 v[216:217], v[176:179], off offset:-3840
	v_lshlrev_b32_e32 v195, 16, v169
	v_and_b32_e32 v197, 0xffff0000, v169
	v_and_b32_e32 v179, 0xffff0000, v170
	v_mul_f32_e32 v170, 0x3d372713, v108
	v_mul_f32_e32 v170, v108, v170
	v_fma_f32 v170, v108, v170, v108
	v_mul_f32_e32 v170, 0x3f4c422a, v170
	v_add_f32_e32 v170, v170, v170
	v_mul_f32_e32 v170, 0x3fb8aa3b, v170
	v_exp_f32_e32 v170, v170
	v_lshlrev_b64 v[176:177], 11, v[190:191]
	v_and_b32_e32 v191, 0xffff0000, v168
	v_and_b32_e32 v168, 0xffff0000, v172
	v_add_f32_e32 v170, 1.0, v170
	v_rcp_f32_e32 v170, v170
	v_lshlrev_b32_e32 v172, 16, v173
	v_and_b32_e32 v178, 0xffff0000, v173
	v_lshlrev_b32_e32 v173, 16, v171
	v_fma_f32 v182, v170, -2.0, 1.0
	v_and_b32_e32 v169, 0xffff0000, v171
	v_mul_f32_e32 v180, 0.5, v108
	v_pk_add_f32 v[170:171], v[182:183], v[198:199]
	v_mov_b32_e32 v199, v168
	v_mul_f32_e32 v170, v180, v170
	v_mul_f32_e32 v182, v170, v171
	v_mul_f32_e32 v170, 0x3d372713, v109
	v_mul_f32_e32 v170, v109, v170
	v_fma_f32 v170, v109, v170, v109
	v_mul_f32_e32 v170, 0x3f4c422a, v170
	v_add_f32_e32 v170, v170, v170
	v_mul_f32_e32 v170, 0x3fb8aa3b, v170
	v_exp_f32_e32 v170, v170
	v_mul_f32_e32 v180, 0.5, v109
	v_lshlrev_b32_e32 v215, 16, v174
	v_and_b32_e32 v174, 0xffff0000, v174
	v_add_f32_e32 v170, 1.0, v170
	v_rcp_f32_e32 v170, v170
	v_lshlrev_b32_e32 v216, 16, v175
	v_and_b32_e32 v175, 0xffff0000, v175
	v_fma_f32 v190, v170, -2.0, 1.0
	v_pk_add_f32 v[170:171], v[190:191], v[198:199]
	v_mov_b32_e32 v199, v172
	v_mul_f32_e32 v168, v180, v170
	v_mul_f32_e32 v183, v168, v171
	v_mul_f32_e32 v168, 0x3d372713, v110
	v_mul_f32_e32 v168, v110, v168
	v_fma_f32 v168, v110, v168, v110
	v_mul_f32_e32 v168, 0x3f4c422a, v168
	v_add_f32_e32 v168, v168, v168
	v_mul_f32_e32 v168, 0x3fb8aa3b, v168
	v_exp_f32_e32 v168, v168
	s_nop 0
	v_add_f32_e32 v168, 1.0, v168
	v_rcp_f32_e32 v168, v168
	s_nop 0
	v_fma_f32 v194, v168, -2.0, 1.0
	v_mul_f32_e32 v168, 0.5, v110
	v_pk_add_f32 v[170:171], v[194:195], v[198:199]
	v_mov_b32_e32 v199, v178
	v_mul_f32_e32 v168, v168, v170
	v_mul_f32_e32 v190, v168, v171
	v_mul_f32_e32 v168, 0x3d372713, v111
	v_mul_f32_e32 v168, v111, v168
	v_fma_f32 v168, v111, v168, v111
	v_mul_f32_e32 v168, 0x3f4c422a, v168
	v_add_f32_e32 v168, v168, v168
	v_mul_f32_e32 v168, 0x3fb8aa3b, v168
	v_exp_f32_e32 v168, v168
	s_nop 0
	v_add_f32_e32 v168, 1.0, v168
	v_rcp_f32_e32 v168, v168
	s_nop 0
	v_fma_f32 v196, v168, -2.0, 1.0
	v_mul_f32_e32 v168, 0.5, v111
	v_pk_add_f32 v[170:171], v[196:197], v[198:199]
	v_mov_b32_e32 v199, v215
	v_mul_f32_e32 v168, v168, v170
	v_mul_f32_e32 v191, v168, v171
	v_mul_f32_e32 v168, 0x3d372713, v104
	v_mul_f32_e32 v168, v104, v168
	v_fma_f32 v168, v104, v168, v104
	v_mul_f32_e32 v168, 0x3f4c422a, v168
	v_add_f32_e32 v168, v168, v168
	v_mul_f32_e32 v168, 0x3fb8aa3b, v168
	v_exp_f32_e32 v168, v168
	s_nop 0
	v_add_f32_e32 v168, 1.0, v168
	v_rcp_f32_e32 v168, v168
	s_nop 0
	v_fma_f32 v180, v168, -2.0, 1.0
	v_mul_f32_e32 v168, 0.5, v104
	v_pk_add_f32 v[170:171], v[180:181], v[198:199]
	v_mov_b32_e32 v199, v174
	v_mul_f32_e32 v168, v168, v170
	v_mul_f32_e32 v180, v168, v171
	v_mul_f32_e32 v168, 0x3d372713, v105
	v_mul_f32_e32 v168, v105, v168
	v_fma_f32 v168, v105, v168, v105
	v_mul_f32_e32 v168, 0x3f4c422a, v168
	v_add_f32_e32 v168, v168, v168
	v_mul_f32_e32 v168, 0x3fb8aa3b, v168
	v_exp_f32_e32 v168, v168
	v_and_b32_e32 v181, 0xffff0000, v161
	v_add_f32_e32 v168, 1.0, v168
	v_rcp_f32_e32 v168, v168
	s_nop 0
	v_fma_f32 v178, v168, -2.0, 1.0
	v_mul_f32_e32 v168, 0.5, v105
	v_pk_add_f32 v[170:171], v[178:179], v[198:199]
	v_mov_b32_e32 v199, v216
	v_mul_f32_e32 v168, v168, v170
	v_mul_f32_e32 v174, v168, v171
	v_mul_f32_e32 v168, 0x3d372713, v106
	v_mul_f32_e32 v168, v106, v168
	v_fma_f32 v168, v106, v168, v106
	v_mul_f32_e32 v168, 0x3f4c422a, v168
	v_add_f32_e32 v168, v168, v168
	v_mul_f32_e32 v168, 0x3fb8aa3b, v168
	v_exp_f32_e32 v168, v168
	v_lshlrev_b32_e32 v179, 16, v161
	v_and_b32_e32 v161, 0xffff0000, v163
	v_add_u32_e32 v216, 0x80, v214
	v_add_f32_e32 v168, 1.0, v168
	v_rcp_f32_e32 v168, v168
	v_ashrrev_i32_e32 v217, 31, v216
	v_fma_f32 v172, v168, -2.0, 1.0
	v_mul_f32_e32 v168, 0.5, v106
	v_pk_add_f32 v[170:171], v[172:173], v[198:199]
; __device__ __forceinline__ unsigned cvt_pk_bf16(float lo, float hi) { unsigned r; asm volatile("s_nop 0\n\tv_cvt_pk_bf16_f32 %0, %1, %2\n\ts_nop 1" : "=v"(r) : "v"(lo), "v"(hi)); return r; }
; __device__ __forceinline__ float bflo(unsigned w) { return __uint_as_float(w << 16); }
; __device__ __forceinline__ float bfhi(unsigned w) { return __uint_as_float(w & 0xffff0000u); }
; __device__ __forceinline__ float gelu_tanh(float x) { const float y = 0.7978845608028654f * (x + 0.044715f * x * x * x); const float t = 1.f - 2.f * __builtin_amdgcn_rcpf(1.f + __expf(2.f * y)); return 0.5f * x * (1.f + t); }
;     __device__ __forceinline__ void operator()(f32x4 (&acc)[2][2][4][2], const Unit& u, int wr, int wc, int fr, int fq) const {
;     ...
;                 for (int m = 0; m < 4; ++m)
; #pragma unroll
;                     for (int bj = 0; bj < 2; ++bj) { const size_t idx = (size_t)(row0 + ai * 128 + m * 16) * 1024 + (u.pn - 8) * 256 + bj * 128 + c8;
;                         const u32x4 a = ya[m][bj], b = yb[m][bj];
;                         float yv[8] = {bflo(a.x) + bflo(b.x), bfhi(a.x) + bfhi(b.x), bflo(a.y) + bflo(b.y), bfhi(a.y) + bfhi(b.y), bflo(a.z) + bflo(b.z), bfhi(a.z) + bfhi(b.z), bflo(a.w) + bflo(b.w), bfhi(a.w) + bfhi(b.w)};
;                         float o[8];
; #pragma unroll
;                         for (int n = 0; n < 2; ++n)
; #pragma unroll
;                             for (int j = 0; j < 4; ++j) o[4 * n + j] = yv[4 * n + j] * gelu_tanh(acc[ai][bj][m][n][j]);
;                         u32x4 w; w.x = cvt_pk_bf16(o[0], o[1]); w.y = cvt_pk_bf16(o[2], o[3]); w.z = cvt_pk_bf16(o[4], o[5]); w.w = cvt_pk_bf16(o[6], o[7]);
;                         *(u32x4*)(ylf + idx) = w; }
	v_mov_b32_e32 v199, v175
	v_mul_f32_e32 v168, v168, v170
	v_mul_f32_e32 v173, v168, v171
	v_mul_f32_e32 v168, 0x3d372713, v107
	v_mul_f32_e32 v168, v107, v168
	v_fma_f32 v168, v107, v168, v107
	v_mul_f32_e32 v168, 0x3f4c422a, v168
	v_add_f32_e32 v168, v168, v168
	v_mul_f32_e32 v168, 0x3fb8aa3b, v168
	v_exp_f32_e32 v168, v168
	v_mul_f32_e32 v170, 0.5, v107
	v_lshlrev_b32_e32 v175, 16, v160
	v_add_f32_e32 v168, 1.0, v168
	v_rcp_f32_e32 v168, v168
	s_nop 0
	v_fma_f32 v168, v168, -2.0, 1.0
	v_pk_add_f32 v[168:169], v[168:169], v[198:199]
	v_lshlrev_b32_e32 v199, 16, v164
	v_mul_f32_e32 v168, v170, v168
	v_mul_f32_e32 v168, v168, v169
	v_cvt_pk_bf16_f32 v170, v182, v183
	v_cvt_pk_bf16_f32 v171, v190, v191
	v_cvt_pk_bf16_f32 v172, v180, v174
	v_cvt_pk_bf16_f32 v173, v173, v168
	v_lshl_add_u64 v[168:169], s[10:11], 0, v[176:177]
	v_lshl_add_u64 v[168:169], v[168:169], 0, s[66:67]
	v_lshl_add_u64 v[168:169], v[168:169], 0, v[184:185]
	global_store_dwordx4 v[168:169], v[170:173], off offset:-4096
	v_and_b32_e32 v177, 0xffff0000, v160
	v_and_b32_e32 v160, 0xffff0000, v164
	v_lshlrev_b32_e32 v173, 16, v162
	v_and_b32_e32 v171, 0xffff0000, v162
	v_mul_f32_e32 v162, 0x3d372713, v100
	v_mul_f32_e32 v162, v100, v162
	v_fma_f32 v162, v100, v162, v100
	v_mul_f32_e32 v162, 0x3f4c422a, v162
	v_add_f32_e32 v162, v162, v162
	v_mul_f32_e32 v162, 0x3fb8aa3b, v162
	v_exp_f32_e32 v162, v162
	v_lshlrev_b32_e32 v164, 16, v165
	v_and_b32_e32 v170, 0xffff0000, v165
	v_lshlrev_b32_e32 v165, 16, v163
	v_add_f32_e32 v162, 1.0, v162
	v_rcp_f32_e32 v162, v162
	v_mul_f32_e32 v172, 0.5, v100
	v_lshlrev_b32_e32 v182, 16, v166
	v_and_b32_e32 v166, 0xffff0000, v166
	v_fma_f32 v174, v162, -2.0, 1.0
	v_pk_add_f32 v[162:163], v[174:175], v[198:199]
	v_mov_b32_e32 v199, v160
	v_mul_f32_e32 v162, v172, v162
	v_mul_f32_e32 v174, v162, v163
	v_mul_f32_e32 v162, 0x3d372713, v101
	v_mul_f32_e32 v162, v101, v162
	v_fma_f32 v162, v101, v162, v101
	v_mul_f32_e32 v162, 0x3f4c422a, v162
	v_add_f32_e32 v162, v162, v162
	v_mul_f32_e32 v162, 0x3fb8aa3b, v162
	v_exp_f32_e32 v162, v162
	v_mul_f32_e32 v172, 0.5, v101
	v_lshlrev_b32_e32 v183, 16, v167
	v_and_b32_e32 v167, 0xffff0000, v167
	v_add_f32_e32 v162, 1.0, v162
	v_rcp_f32_e32 v162, v162
	v_add_u32_e32 v190, 0x90, v214
	v_ashrrev_i32_e32 v191, 31, v190
	v_fma_f32 v176, v162, -2.0, 1.0
	v_pk_add_f32 v[162:163], v[176:177], v[198:199]
	v_mov_b32_e32 v199, v164
	v_mul_f32_e32 v160, v172, v162
	v_mul_f32_e32 v175, v160, v163
	v_mul_f32_e32 v160, 0x3d372713, v102
	v_mul_f32_e32 v160, v102, v160
	v_fma_f32 v160, v102, v160, v102
	v_mul_f32_e32 v160, 0x3f4c422a, v160
	v_add_f32_e32 v160, v160, v160
	v_mul_f32_e32 v160, 0x3fb8aa3b, v160
	v_exp_f32_e32 v160, v160
	s_nop 0
	v_add_f32_e32 v160, 1.0, v160
	v_rcp_f32_e32 v160, v160
	s_nop 0
	v_fma_f32 v178, v160, -2.0, 1.0
	v_mul_f32_e32 v160, 0.5, v102
	v_pk_add_f32 v[162:163], v[178:179], v[198:199]
	v_mov_b32_e32 v199, v170
	v_mul_f32_e32 v160, v160, v162
	v_mul_f32_e32 v176, v160, v163
	v_mul_f32_e32 v160, 0x3d372713, v103
	v_mul_f32_e32 v160, v103, v160
	v_fma_f32 v160, v103, v160, v103
	v_mul_f32_e32 v160, 0x3f4c422a, v160
	v_add_f32_e32 v160, v160, v160
	v_mul_f32_e32 v160, 0x3fb8aa3b, v160
	v_exp_f32_e32 v160, v160
	s_nop 0
	v_add_f32_e32 v160, 1.0, v160
	v_rcp_f32_e32 v160, v160
	s_nop 0
	v_fma_f32 v180, v160, -2.0, 1.0
	v_mul_f32_e32 v160, 0.5, v103
	v_pk_add_f32 v[162:163], v[180:181], v[198:199]
	v_mov_b32_e32 v199, v182
	v_mul_f32_e32 v160, v160, v162
	v_mul_f32_e32 v177, v160, v163
	v_mul_f32_e32 v160, 0x3d372713, v96
	v_mul_f32_e32 v160, v96, v160
	v_fma_f32 v160, v96, v160, v96
	v_mul_f32_e32 v160, 0x3f4c422a, v160
	v_add_f32_e32 v160, v160, v160
	v_mul_f32_e32 v160, 0x3fb8aa3b, v160
	v_exp_f32_e32 v160, v160
	s_nop 0
	v_add_f32_e32 v160, 1.0, v160
	v_rcp_f32_e32 v160, v160
	s_nop 0
	v_fma_f32 v172, v160, -2.0, 1.0
	v_mul_f32_e32 v160, 0.5, v96
	v_pk_add_f32 v[162:163], v[172:173], v[198:199]
	v_mov_b32_e32 v199, v166
	v_mul_f32_e32 v160, v160, v162
	v_mul_f32_e32 v172, v160, v163
	v_mul_f32_e32 v160, 0x3d372713, v97
	v_mul_f32_e32 v160, v97, v160
	v_fma_f32 v160, v97, v160, v97
	v_mul_f32_e32 v160, 0x3f4c422a, v160
	v_add_f32_e32 v160, v160, v160
	v_mul_f32_e32 v160, 0x3fb8aa3b, v160
	v_exp_f32_e32 v160, v160
	v_and_b32_e32 v173, 0xffff0000, v153
	v_add_f32_e32 v160, 1.0, v160
	v_rcp_f32_e32 v160, v160
	s_nop 0
	v_fma_f32 v170, v160, -2.0, 1.0
	v_mul_f32_e32 v160, 0.5, v97
	v_pk_add_f32 v[162:163], v[170:171], v[198:199]
	v_mov_b32_e32 v199, v183
	v_mul_f32_e32 v160, v160, v162
	v_mul_f32_e32 v166, v160, v163
	v_mul_f32_e32 v160, 0x3d372713, v98
	v_mul_f32_e32 v160, v98, v160
	v_fma_f32 v160, v98, v160, v98
	v_mul_f32_e32 v160, 0x3f4c422a, v160
	v_add_f32_e32 v160, v160, v160
	v_mul_f32_e32 v160, 0x3fb8aa3b, v160
	v_exp_f32_e32 v160, v160
	v_lshlrev_b32_e32 v171, 16, v153
	v_and_b32_e32 v153, 0xffff0000, v155
	v_add_f32_e32 v160, 1.0, v160
	v_rcp_f32_e32 v160, v160
	s_nop 0
	v_fma_f32 v164, v160, -2.0, 1.0
	v_mul_f32_e32 v160, 0.5, v98
	v_pk_add_f32 v[162:163], v[164:165], v[198:199]
	v_mov_b32_e32 v199, v167
	v_mul_f32_e32 v160, v160, v162
	v_mul_f32_e32 v163, v160, v163
	v_mul_f32_e32 v160, 0x3d372713, v99
	v_mul_f32_e32 v160, v99, v160
	v_fma_f32 v160, v99, v160, v99
	v_mul_f32_e32 v160, 0x3f4c422a, v160
	v_add_f32_e32 v160, v160, v160
	v_mul_f32_e32 v160, 0x3fb8aa3b, v160
	v_exp_f32_e32 v160, v160
	v_mul_f32_e32 v162, 0.5, v99
	v_lshlrev_b32_e32 v165, 16, v154
	v_lshlrev_b32_e32 v167, 16, v152
	v_add_f32_e32 v160, 1.0, v160
	v_rcp_f32_e32 v160, v160
	s_nop 0
	v_fma_f32 v160, v160, -2.0, 1.0
	v_pk_add_f32 v[160:161], v[160:161], v[198:199]
	v_lshlrev_b32_e32 v199, 16, v156
; __device__ __forceinline__ unsigned cvt_pk_bf16(float lo, float hi) { unsigned r; asm volatile("s_nop 0\n\tv_cvt_pk_bf16_f32 %0, %1, %2\n\ts_nop 1" : "=v"(r) : "v"(lo), "v"(hi)); return r; }
; __device__ __forceinline__ float bflo(unsigned w) { return __uint_as_float(w << 16); }
; __device__ __forceinline__ float bfhi(unsigned w) { return __uint_as_float(w & 0xffff0000u); }
; __device__ __forceinline__ float gelu_tanh(float x) { const float y = 0.7978845608028654f * (x + 0.044715f * x * x * x); const float t = 1.f - 2.f * __builtin_amdgcn_rcpf(1.f + __expf(2.f * y)); return 0.5f * x * (1.f + t); }
;     __device__ __forceinline__ void operator()(f32x4 (&acc)[2][2][4][2], const Unit& u, int wr, int wc, int fr, int fq) const {
;     ...
;                 for (int m = 0; m < 4; ++m)
; #pragma unroll
;                     for (int bj = 0; bj < 2; ++bj) { const size_t idx = (size_t)(row0 + ai * 128 + m * 16) * 1024 + (u.pn - 8) * 256 + bj * 128 + c8;
;                         const u32x4 a = ya[m][bj], b = yb[m][bj];
;                         float yv[8] = {bflo(a.x) + bflo(b.x), bfhi(a.x) + bfhi(b.x), bflo(a.y) + bflo(b.y), bfhi(a.y) + bfhi(b.y), bflo(a.z) + bflo(b.z), bfhi(a.z) + bfhi(b.z), bflo(a.w) + bflo(b.w), bfhi(a.w) + bfhi(b.w)};
;                         float o[8];
; #pragma unroll
;                         for (int n = 0; n < 2; ++n)
; #pragma unroll
;                             for (int j = 0; j < 4; ++j) o[4 * n + j] = yv[4 * n + j] * gelu_tanh(acc[ai][bj][m][n][j]);
;                         u32x4 w; w.x = cvt_pk_bf16(o[0], o[1]); w.y = cvt_pk_bf16(o[2], o[3]); w.z = cvt_pk_bf16(o[4], o[5]); w.w = cvt_pk_bf16(o[6], o[7]);
;                         *(u32x4*)(ylf + idx) = w; }
	v_mul_f32_e32 v160, v162, v160
	v_mul_f32_e32 v164, v160, v161
	v_cvt_pk_bf16_f32 v160, v174, v175
	v_cvt_pk_bf16_f32 v161, v176, v177
	v_cvt_pk_bf16_f32 v162, v172, v166
	v_cvt_pk_bf16_f32 v163, v163, v164
	global_store_dwordx4 v[168:169], v[160:163], off offset:-3840
	v_and_b32_e32 v169, 0xffff0000, v152
	v_and_b32_e32 v152, 0xffff0000, v156
	v_and_b32_e32 v163, 0xffff0000, v154
	v_mul_f32_e32 v154, 0x3d372713, v92
	v_mul_f32_e32 v154, v92, v154
	v_fma_f32 v154, v92, v154, v92
	v_mul_f32_e32 v154, 0x3f4c422a, v154
	v_add_f32_e32 v154, v154, v154
	v_mul_f32_e32 v154, 0x3fb8aa3b, v154
	v_exp_f32_e32 v154, v154
	v_lshlrev_b32_e32 v156, 16, v157
	v_and_b32_e32 v162, 0xffff0000, v157
	v_lshlrev_b32_e32 v157, 16, v155
	v_add_f32_e32 v154, 1.0, v154
	v_rcp_f32_e32 v154, v154
	v_mul_f32_e32 v164, 0.5, v92
	v_lshlrev_b32_e32 v174, 16, v158
	v_and_b32_e32 v158, 0xffff0000, v158
	v_fma_f32 v166, v154, -2.0, 1.0
	v_pk_add_f32 v[154:155], v[166:167], v[198:199]
	v_mov_b32_e32 v199, v152
	v_mul_f32_e32 v154, v164, v154
	v_mul_f32_e32 v166, v154, v155
	v_mul_f32_e32 v154, 0x3d372713, v93
	v_mul_f32_e32 v154, v93, v154
	v_fma_f32 v154, v93, v154, v93
	v_mul_f32_e32 v154, 0x3f4c422a, v154
	v_add_f32_e32 v154, v154, v154
	v_mul_f32_e32 v154, 0x3fb8aa3b, v154
	v_exp_f32_e32 v154, v154
	v_mul_f32_e32 v164, 0.5, v93
	v_lshlrev_b32_e32 v175, 16, v159
	v_and_b32_e32 v159, 0xffff0000, v159
	v_add_f32_e32 v154, 1.0, v154
	v_rcp_f32_e32 v154, v154
	v_lshlrev_b64 v[160:161], 11, v[188:189]
	v_add_u32_e32 v188, 0xa0, v214
	v_ashrrev_i32_e32 v189, 31, v188
	v_fma_f32 v168, v154, -2.0, 1.0
	v_pk_add_f32 v[154:155], v[168:169], v[198:199]
	v_mov_b32_e32 v199, v156
	v_mul_f32_e32 v152, v164, v154
	v_mul_f32_e32 v167, v152, v155
	v_mul_f32_e32 v152, 0x3d372713, v94
	v_mul_f32_e32 v152, v94, v152
	v_fma_f32 v152, v94, v152, v94
	v_mul_f32_e32 v152, 0x3f4c422a, v152
	v_add_f32_e32 v152, v152, v152
	v_mul_f32_e32 v152, 0x3fb8aa3b, v152
	v_exp_f32_e32 v152, v152
	s_nop 0
	v_add_f32_e32 v152, 1.0, v152
	v_rcp_f32_e32 v152, v152
	s_nop 0
	v_fma_f32 v170, v152, -2.0, 1.0
	v_mul_f32_e32 v152, 0.5, v94
	v_pk_add_f32 v[154:155], v[170:171], v[198:199]
	v_mov_b32_e32 v199, v162
	v_mul_f32_e32 v152, v152, v154
	v_mul_f32_e32 v168, v152, v155
	v_mul_f32_e32 v152, 0x3d372713, v95
	v_mul_f32_e32 v152, v95, v152
	v_fma_f32 v152, v95, v152, v95
	v_mul_f32_e32 v152, 0x3f4c422a, v152
	v_add_f32_e32 v152, v152, v152
	v_mul_f32_e32 v152, 0x3fb8aa3b, v152
	v_exp_f32_e32 v152, v152
	s_nop 0
	v_add_f32_e32 v152, 1.0, v152
	v_rcp_f32_e32 v152, v152
	s_nop 0
	v_fma_f32 v172, v152, -2.0, 1.0
	v_mul_f32_e32 v152, 0.5, v95
	v_pk_add_f32 v[154:155], v[172:173], v[198:199]
	v_mov_b32_e32 v199, v174
	v_mul_f32_e32 v152, v152, v154
	v_mul_f32_e32 v169, v152, v155
	v_mul_f32_e32 v152, 0x3d372713, v88
	v_mul_f32_e32 v152, v88, v152
	v_fma_f32 v152, v88, v152, v88
	v_mul_f32_e32 v152, 0x3f4c422a, v152
	v_add_f32_e32 v152, v152, v152
	v_mul_f32_e32 v152, 0x3fb8aa3b, v152
	v_exp_f32_e32 v152, v152
	s_nop 0
	v_add_f32_e32 v152, 1.0, v152
	v_rcp_f32_e32 v152, v152
	s_nop 0
	v_fma_f32 v164, v152, -2.0, 1.0
	v_mul_f32_e32 v152, 0.5, v88
	v_pk_add_f32 v[154:155], v[164:165], v[198:199]
	v_mov_b32_e32 v199, v158
	v_mul_f32_e32 v152, v152, v154
	v_mul_f32_e32 v164, v152, v155
	v_mul_f32_e32 v152, 0x3d372713, v89
	v_mul_f32_e32 v152, v89, v152
	v_fma_f32 v152, v89, v152, v89
	v_mul_f32_e32 v152, 0x3f4c422a, v152
	v_add_f32_e32 v152, v152, v152
	v_mul_f32_e32 v152, 0x3fb8aa3b, v152
	v_exp_f32_e32 v152, v152
	v_and_b32_e32 v165, 0xffff0000, v145
	v_add_f32_e32 v152, 1.0, v152
	v_rcp_f32_e32 v152, v152
	s_nop 0
	v_fma_f32 v162, v152, -2.0, 1.0
	v_mul_f32_e32 v152, 0.5, v89
	v_pk_add_f32 v[154:155], v[162:163], v[198:199]
	v_mov_b32_e32 v199, v175
	v_mul_f32_e32 v152, v152, v154
	v_mul_f32_e32 v158, v152, v155
	v_mul_f32_e32 v152, 0x3d372713, v90
	v_mul_f32_e32 v152, v90, v152
	v_fma_f32 v152, v90, v152, v90
	v_mul_f32_e32 v152, 0x3f4c422a, v152
	v_add_f32_e32 v152, v152, v152
	v_mul_f32_e32 v152, 0x3fb8aa3b, v152
	v_exp_f32_e32 v152, v152
	v_lshlrev_b32_e32 v163, 16, v145
	v_and_b32_e32 v145, 0xffff0000, v147
	v_add_f32_e32 v152, 1.0, v152
	v_rcp_f32_e32 v152, v152
	s_nop 0
	v_fma_f32 v156, v152, -2.0, 1.0
	v_mul_f32_e32 v152, 0.5, v90
	v_pk_add_f32 v[154:155], v[156:157], v[198:199]
	v_mov_b32_e32 v199, v159
	v_mul_f32_e32 v152, v152, v154
	v_mul_f32_e32 v157, v152, v155
	v_mul_f32_e32 v152, 0x3d372713, v91
	v_mul_f32_e32 v152, v91, v152
	v_fma_f32 v152, v91, v152, v91
	v_mul_f32_e32 v152, 0x3f4c422a, v152
	v_add_f32_e32 v152, v152, v152
	v_mul_f32_e32 v152, 0x3fb8aa3b, v152
	v_exp_f32_e32 v152, v152
	v_mul_f32_e32 v154, 0.5, v91
	v_lshlrev_b32_e32 v159, 16, v144
	v_add_f32_e32 v152, 1.0, v152
	v_rcp_f32_e32 v152, v152
	s_nop 0
	v_fma_f32 v152, v152, -2.0, 1.0
	v_pk_add_f32 v[152:153], v[152:153], v[198:199]
	v_lshlrev_b32_e32 v199, 16, v148
	v_mul_f32_e32 v152, v154, v152
	v_mul_f32_e32 v152, v152, v153
	v_cvt_pk_bf16_f32 v154, v166, v167
	v_cvt_pk_bf16_f32 v155, v168, v169
	v_cvt_pk_bf16_f32 v156, v164, v158
	v_cvt_pk_bf16_f32 v157, v157, v152
	v_lshl_add_u64 v[152:153], s[10:11], 0, v[160:161]
	v_lshl_add_u64 v[152:153], v[152:153], 0, s[66:67]
	v_lshl_add_u64 v[152:153], v[152:153], 0, v[184:185]
	global_store_dwordx4 v[152:153], v[154:157], off offset:-4096
	v_and_b32_e32 v161, 0xffff0000, v144
	v_and_b32_e32 v144, 0xffff0000, v148
	v_lshlrev_b32_e32 v157, 16, v146
	v_and_b32_e32 v155, 0xffff0000, v146
	v_mul_f32_e32 v146, 0x3d372713, v84
	v_mul_f32_e32 v146, v84, v146
	v_fma_f32 v146, v84, v146, v84
	v_mul_f32_e32 v146, 0x3f4c422a, v146
	v_add_f32_e32 v146, v146, v146
	v_mul_f32_e32 v146, 0x3fb8aa3b, v146
; __device__ __forceinline__ unsigned cvt_pk_bf16(float lo, float hi) { unsigned r; asm volatile("s_nop 0\n\tv_cvt_pk_bf16_f32 %0, %1, %2\n\ts_nop 1" : "=v"(r) : "v"(lo), "v"(hi)); return r; }
; __device__ __forceinline__ float bflo(unsigned w) { return __uint_as_float(w << 16); }
; __device__ __forceinline__ float bfhi(unsigned w) { return __uint_as_float(w & 0xffff0000u); }
; __device__ __forceinline__ float gelu_tanh(float x) { const float y = 0.7978845608028654f * (x + 0.044715f * x * x * x); const float t = 1.f - 2.f * __builtin_amdgcn_rcpf(1.f + __expf(2.f * y)); return 0.5f * x * (1.f + t); }
;     __device__ __forceinline__ void operator()(f32x4 (&acc)[2][2][4][2], const Unit& u, int wr, int wc, int fr, int fq) const {
;     ...
;                 for (int m = 0; m < 4; ++m)
; #pragma unroll
;                     for (int bj = 0; bj < 2; ++bj) { const size_t idx = (size_t)(row0 + ai * 128 + m * 16) * 1024 + (u.pn - 8) * 256 + bj * 128 + c8;
;                         const u32x4 a = ya[m][bj], b = yb[m][bj];
;                         float yv[8] = {bflo(a.x) + bflo(b.x), bfhi(a.x) + bfhi(b.x), bflo(a.y) + bflo(b.y), bfhi(a.y) + bfhi(b.y), bflo(a.z) + bflo(b.z), bfhi(a.z) + bfhi(b.z), bflo(a.w) + bflo(b.w), bfhi(a.w) + bfhi(b.w)};
;                         float o[8];
; #pragma unroll
;                         for (int n = 0; n < 2; ++n)
; #pragma unroll
;                             for (int j = 0; j < 4; ++j) o[4 * n + j] = yv[4 * n + j] * gelu_tanh(acc[ai][bj][m][n][j]);
;                         u32x4 w; w.x = cvt_pk_bf16(o[0], o[1]); w.y = cvt_pk_bf16(o[2], o[3]); w.z = cvt_pk_bf16(o[4], o[5]); w.w = cvt_pk_bf16(o[6], o[7]);
;                         *(u32x4*)(ylf + idx) = w; }
	v_exp_f32_e32 v146, v146
	v_lshlrev_b32_e32 v148, 16, v149
	v_and_b32_e32 v154, 0xffff0000, v149
	v_lshlrev_b32_e32 v149, 16, v147
	v_add_f32_e32 v146, 1.0, v146
	v_rcp_f32_e32 v146, v146
	v_mul_f32_e32 v156, 0.5, v84
	v_lshlrev_b32_e32 v166, 16, v150
	v_and_b32_e32 v150, 0xffff0000, v150
	v_fma_f32 v158, v146, -2.0, 1.0
	v_pk_add_f32 v[146:147], v[158:159], v[198:199]
	v_mov_b32_e32 v199, v144
	v_mul_f32_e32 v146, v156, v146
	v_mul_f32_e32 v158, v146, v147
	v_mul_f32_e32 v146, 0x3d372713, v85
	v_mul_f32_e32 v146, v85, v146
	v_fma_f32 v146, v85, v146, v85
	v_mul_f32_e32 v146, 0x3f4c422a, v146
	v_add_f32_e32 v146, v146, v146
	v_mul_f32_e32 v146, 0x3fb8aa3b, v146
	v_exp_f32_e32 v146, v146
	v_mul_f32_e32 v156, 0.5, v85
	v_lshlrev_b32_e32 v167, 16, v151
	v_and_b32_e32 v151, 0xffff0000, v151
	v_add_f32_e32 v146, 1.0, v146
	v_rcp_f32_e32 v146, v146
	s_nop 0
	v_fma_f32 v160, v146, -2.0, 1.0
	v_pk_add_f32 v[146:147], v[160:161], v[198:199]
	v_mov_b32_e32 v199, v148
	v_mul_f32_e32 v144, v156, v146
	v_mul_f32_e32 v159, v144, v147
	v_mul_f32_e32 v144, 0x3d372713, v86
	v_mul_f32_e32 v144, v86, v144
	v_fma_f32 v144, v86, v144, v86
	v_mul_f32_e32 v144, 0x3f4c422a, v144
	v_add_f32_e32 v144, v144, v144
	v_mul_f32_e32 v144, 0x3fb8aa3b, v144
	v_exp_f32_e32 v144, v144
	s_nop 0
	v_add_f32_e32 v144, 1.0, v144
	v_rcp_f32_e32 v144, v144
	s_nop 0
	v_fma_f32 v162, v144, -2.0, 1.0
	v_mul_f32_e32 v144, 0.5, v86
	v_pk_add_f32 v[146:147], v[162:163], v[198:199]
	v_mov_b32_e32 v199, v154
	v_mul_f32_e32 v144, v144, v146
	v_mul_f32_e32 v160, v144, v147
	v_mul_f32_e32 v144, 0x3d372713, v87
	v_mul_f32_e32 v144, v87, v144
	v_fma_f32 v144, v87, v144, v87
	v_mul_f32_e32 v144, 0x3f4c422a, v144
	v_add_f32_e32 v144, v144, v144
	v_mul_f32_e32 v144, 0x3fb8aa3b, v144
	v_exp_f32_e32 v144, v144
	s_nop 0
	v_add_f32_e32 v144, 1.0, v144
	v_rcp_f32_e32 v144, v144
	s_nop 0
	v_fma_f32 v164, v144, -2.0, 1.0
	v_mul_f32_e32 v144, 0.5, v87
	v_pk_add_f32 v[146:147], v[164:165], v[198:199]
	v_mov_b32_e32 v199, v166
	v_mul_f32_e32 v144, v144, v146
	v_mul_f32_e32 v161, v144, v147
	v_mul_f32_e32 v144, 0x3d372713, v80
	v_mul_f32_e32 v144, v80, v144
	v_fma_f32 v144, v80, v144, v80
	v_mul_f32_e32 v144, 0x3f4c422a, v144
	v_add_f32_e32 v144, v144, v144
	v_mul_f32_e32 v144, 0x3fb8aa3b, v144
	v_exp_f32_e32 v144, v144
	s_nop 0
	v_add_f32_e32 v144, 1.0, v144
	v_rcp_f32_e32 v144, v144
	s_nop 0
	v_fma_f32 v156, v144, -2.0, 1.0
	v_mul_f32_e32 v144, 0.5, v80
	v_pk_add_f32 v[146:147], v[156:157], v[198:199]
	v_mov_b32_e32 v199, v150
	v_mul_f32_e32 v144, v144, v146
	v_mul_f32_e32 v156, v144, v147
	v_mul_f32_e32 v144, 0x3d372713, v81
	v_mul_f32_e32 v144, v81, v144
	v_fma_f32 v144, v81, v144, v81
	v_mul_f32_e32 v144, 0x3f4c422a, v144
	v_add_f32_e32 v144, v144, v144
	v_mul_f32_e32 v144, 0x3fb8aa3b, v144
	v_exp_f32_e32 v144, v144
	v_and_b32_e32 v157, 0xffff0000, v137
	v_add_f32_e32 v144, 1.0, v144
	v_rcp_f32_e32 v144, v144
	s_nop 0
	v_fma_f32 v154, v144, -2.0, 1.0
	v_mul_f32_e32 v144, 0.5, v81
	v_pk_add_f32 v[146:147], v[154:155], v[198:199]
	v_mov_b32_e32 v199, v167
	v_mul_f32_e32 v144, v144, v146
	v_mul_f32_e32 v150, v144, v147
	v_mul_f32_e32 v144, 0x3d372713, v82
	v_mul_f32_e32 v144, v82, v144
	v_fma_f32 v144, v82, v144, v82
	v_mul_f32_e32 v144, 0x3f4c422a, v144
	v_add_f32_e32 v144, v144, v144
	v_mul_f32_e32 v144, 0x3fb8aa3b, v144
	v_exp_f32_e32 v144, v144
	v_lshlrev_b32_e32 v155, 16, v137
	v_and_b32_e32 v137, 0xffff0000, v139
	v_add_f32_e32 v144, 1.0, v144
	v_rcp_f32_e32 v144, v144
	s_nop 0
	v_fma_f32 v148, v144, -2.0, 1.0
	v_mul_f32_e32 v144, 0.5, v82
	v_pk_add_f32 v[146:147], v[148:149], v[198:199]
	v_mov_b32_e32 v199, v151
	v_mul_f32_e32 v144, v144, v146
	v_mul_f32_e32 v147, v144, v147
	v_mul_f32_e32 v144, 0x3d372713, v83
	v_mul_f32_e32 v144, v83, v144
	v_fma_f32 v144, v83, v144, v83
	v_mul_f32_e32 v144, 0x3f4c422a, v144
	v_add_f32_e32 v144, v144, v144
	v_mul_f32_e32 v144, 0x3fb8aa3b, v144
	v_exp_f32_e32 v144, v144
	v_mul_f32_e32 v146, 0.5, v83
	v_lshlrev_b32_e32 v149, 16, v138
	v_lshlrev_b32_e32 v151, 16, v136
	v_add_f32_e32 v144, 1.0, v144
	v_rcp_f32_e32 v144, v144
	s_nop 0
	v_fma_f32 v144, v144, -2.0, 1.0
	v_pk_add_f32 v[144:145], v[144:145], v[198:199]
	v_lshlrev_b32_e32 v199, 16, v140
	v_mul_f32_e32 v144, v146, v144
	v_mul_f32_e32 v148, v144, v145
	v_cvt_pk_bf16_f32 v144, v158, v159
	v_cvt_pk_bf16_f32 v145, v160, v161
	v_cvt_pk_bf16_f32 v146, v156, v150
	v_cvt_pk_bf16_f32 v147, v147, v148
	global_store_dwordx4 v[152:153], v[144:147], off offset:-3840
	v_and_b32_e32 v153, 0xffff0000, v136
	v_and_b32_e32 v136, 0xffff0000, v140
	v_and_b32_e32 v147, 0xffff0000, v138
	v_mul_f32_e32 v138, 0x3d372713, v76
	v_mul_f32_e32 v138, v76, v138
	v_fma_f32 v138, v76, v138, v76
	v_mul_f32_e32 v138, 0x3f4c422a, v138
	v_add_f32_e32 v138, v138, v138
	v_mul_f32_e32 v138, 0x3fb8aa3b, v138
	v_exp_f32_e32 v138, v138
	v_lshlrev_b32_e32 v140, 16, v141
	v_and_b32_e32 v146, 0xffff0000, v141
	v_lshlrev_b32_e32 v141, 16, v139
	v_add_f32_e32 v138, 1.0, v138
	v_rcp_f32_e32 v138, v138
	v_mul_f32_e32 v148, 0.5, v76
	v_lshlrev_b32_e32 v158, 16, v142
	v_and_b32_e32 v142, 0xffff0000, v142
	v_fma_f32 v150, v138, -2.0, 1.0
	v_pk_add_f32 v[138:139], v[150:151], v[198:199]
	v_mov_b32_e32 v199, v136
	v_mul_f32_e32 v138, v148, v138
	v_mul_f32_e32 v150, v138, v139
	v_mul_f32_e32 v138, 0x3d372713, v77
	v_mul_f32_e32 v138, v77, v138
	v_fma_f32 v138, v77, v138, v77
	v_mul_f32_e32 v138, 0x3f4c422a, v138
	v_add_f32_e32 v138, v138, v138
	v_mul_f32_e32 v138, 0x3fb8aa3b, v138
	v_exp_f32_e32 v138, v138
	v_mul_f32_e32 v148, 0.5, v77
	v_lshlrev_b32_e32 v159, 16, v143
	v_and_b32_e32 v143, 0xffff0000, v143
	v_add_f32_e32 v138, 1.0, v138
	v_rcp_f32_e32 v138, v138
; __device__ __forceinline__ unsigned cvt_pk_bf16(float lo, float hi) { unsigned r; asm volatile("s_nop 0\n\tv_cvt_pk_bf16_f32 %0, %1, %2\n\ts_nop 1" : "=v"(r) : "v"(lo), "v"(hi)); return r; }
; __device__ __forceinline__ float bflo(unsigned w) { return __uint_as_float(w << 16); }
; __device__ __forceinline__ float bfhi(unsigned w) { return __uint_as_float(w & 0xffff0000u); }
; __device__ __forceinline__ float gelu_tanh(float x) { const float y = 0.7978845608028654f * (x + 0.044715f * x * x * x); const float t = 1.f - 2.f * __builtin_amdgcn_rcpf(1.f + __expf(2.f * y)); return 0.5f * x * (1.f + t); }
;     __device__ __forceinline__ void operator()(f32x4 (&acc)[2][2][4][2], const Unit& u, int wr, int wc, int fr, int fq) const {
;     ...
;                 for (int m = 0; m < 4; ++m)
; #pragma unroll
;                     for (int bj = 0; bj < 2; ++bj) { const size_t idx = (size_t)(row0 + ai * 128 + m * 16) * 1024 + (u.pn - 8) * 256 + bj * 128 + c8;
;                         const u32x4 a = ya[m][bj], b = yb[m][bj];
;                         float yv[8] = {bflo(a.x) + bflo(b.x), bfhi(a.x) + bfhi(b.x), bflo(a.y) + bflo(b.y), bfhi(a.y) + bfhi(b.y), bflo(a.z) + bflo(b.z), bfhi(a.z) + bfhi(b.z), bflo(a.w) + bflo(b.w), bfhi(a.w) + bfhi(b.w)};
;                         float o[8];
; #pragma unroll
;                         for (int n = 0; n < 2; ++n)
; #pragma unroll
;                             for (int j = 0; j < 4; ++j) o[4 * n + j] = yv[4 * n + j] * gelu_tanh(acc[ai][bj][m][n][j]);
;                         u32x4 w; w.x = cvt_pk_bf16(o[0], o[1]); w.y = cvt_pk_bf16(o[2], o[3]); w.z = cvt_pk_bf16(o[4], o[5]); w.w = cvt_pk_bf16(o[6], o[7]);
;                         *(u32x4*)(ylf + idx) = w; }
	v_lshlrev_b64 v[144:145], 11, v[186:187]
	v_add_u32_e32 v186, 0xb0, v214
	v_ashrrev_i32_e32 v187, 31, v186
	v_fma_f32 v152, v138, -2.0, 1.0
	v_pk_add_f32 v[138:139], v[152:153], v[198:199]
	v_mov_b32_e32 v199, v140
	v_mul_f32_e32 v136, v148, v138
	v_mul_f32_e32 v151, v136, v139
	v_mul_f32_e32 v136, 0x3d372713, v78
	v_mul_f32_e32 v136, v78, v136
	v_fma_f32 v136, v78, v136, v78
	v_mul_f32_e32 v136, 0x3f4c422a, v136
	v_add_f32_e32 v136, v136, v136
	v_mul_f32_e32 v136, 0x3fb8aa3b, v136
	v_exp_f32_e32 v136, v136
	s_nop 0
	v_add_f32_e32 v136, 1.0, v136
	v_rcp_f32_e32 v136, v136
	s_nop 0
	v_fma_f32 v154, v136, -2.0, 1.0
	v_mul_f32_e32 v136, 0.5, v78
	v_pk_add_f32 v[138:139], v[154:155], v[198:199]
	v_mov_b32_e32 v199, v146
	v_mul_f32_e32 v136, v136, v138
	v_mul_f32_e32 v152, v136, v139
	v_mul_f32_e32 v136, 0x3d372713, v79
	v_mul_f32_e32 v136, v79, v136
	v_fma_f32 v136, v79, v136, v79
	v_mul_f32_e32 v136, 0x3f4c422a, v136
	v_add_f32_e32 v136, v136, v136
	v_mul_f32_e32 v136, 0x3fb8aa3b, v136
	v_exp_f32_e32 v136, v136
	s_nop 0
	v_add_f32_e32 v136, 1.0, v136
	v_rcp_f32_e32 v136, v136
	s_nop 0
	v_fma_f32 v156, v136, -2.0, 1.0
	v_mul_f32_e32 v136, 0.5, v79
	v_pk_add_f32 v[138:139], v[156:157], v[198:199]
	v_mov_b32_e32 v199, v158
	v_mul_f32_e32 v136, v136, v138
	v_mul_f32_e32 v153, v136, v139
	v_mul_f32_e32 v136, 0x3d372713, v72
	v_mul_f32_e32 v136, v72, v136
	v_fma_f32 v136, v72, v136, v72
	v_mul_f32_e32 v136, 0x3f4c422a, v136
	v_add_f32_e32 v136, v136, v136
	v_mul_f32_e32 v136, 0x3fb8aa3b, v136
	v_exp_f32_e32 v136, v136
	s_nop 0
	v_add_f32_e32 v136, 1.0, v136
	v_rcp_f32_e32 v136, v136
	s_nop 0
	v_fma_f32 v148, v136, -2.0, 1.0
	v_mul_f32_e32 v136, 0.5, v72
	v_pk_add_f32 v[138:139], v[148:149], v[198:199]
	v_mov_b32_e32 v199, v142
	v_mul_f32_e32 v136, v136, v138
	v_mul_f32_e32 v148, v136, v139
	v_mul_f32_e32 v136, 0x3d372713, v73
	v_mul_f32_e32 v136, v73, v136
	v_fma_f32 v136, v73, v136, v73
	v_mul_f32_e32 v136, 0x3f4c422a, v136
	v_add_f32_e32 v136, v136, v136
	v_mul_f32_e32 v136, 0x3fb8aa3b, v136
	v_exp_f32_e32 v136, v136
	v_and_b32_e32 v149, 0xffff0000, v129
	v_add_f32_e32 v136, 1.0, v136
	v_rcp_f32_e32 v136, v136
	s_nop 0
	v_fma_f32 v146, v136, -2.0, 1.0
	v_mul_f32_e32 v136, 0.5, v73
	v_pk_add_f32 v[138:139], v[146:147], v[198:199]
	v_mov_b32_e32 v199, v159
	v_mul_f32_e32 v136, v136, v138
	v_mul_f32_e32 v142, v136, v139
	v_mul_f32_e32 v136, 0x3d372713, v74
	v_mul_f32_e32 v136, v74, v136
	v_fma_f32 v136, v74, v136, v74
	v_mul_f32_e32 v136, 0x3f4c422a, v136
	v_add_f32_e32 v136, v136, v136
	v_mul_f32_e32 v136, 0x3fb8aa3b, v136
	v_exp_f32_e32 v136, v136
	v_lshlrev_b32_e32 v147, 16, v129
	v_and_b32_e32 v129, 0xffff0000, v131
	v_add_f32_e32 v136, 1.0, v136
	v_rcp_f32_e32 v136, v136
	s_nop 0
	v_fma_f32 v140, v136, -2.0, 1.0
	v_mul_f32_e32 v136, 0.5, v74
	v_pk_add_f32 v[138:139], v[140:141], v[198:199]
	v_mov_b32_e32 v199, v143
	v_mul_f32_e32 v136, v136, v138
	v_mul_f32_e32 v141, v136, v139
	v_mul_f32_e32 v136, 0x3d372713, v75
	v_mul_f32_e32 v136, v75, v136
	v_fma_f32 v136, v75, v136, v75
	v_mul_f32_e32 v136, 0x3f4c422a, v136
	v_add_f32_e32 v136, v136, v136
	v_mul_f32_e32 v136, 0x3fb8aa3b, v136
	v_exp_f32_e32 v136, v136
	v_mul_f32_e32 v138, 0.5, v75
	v_lshlrev_b32_e32 v143, 16, v128
	v_add_f32_e32 v136, 1.0, v136
	v_rcp_f32_e32 v136, v136
	s_nop 0
	v_fma_f32 v136, v136, -2.0, 1.0
	v_pk_add_f32 v[136:137], v[136:137], v[198:199]
	s_waitcnt vmcnt(0)
	v_lshlrev_b32_e32 v199, 16, v132
	v_mul_f32_e32 v136, v138, v136
	v_mul_f32_e32 v136, v136, v137
	v_cvt_pk_bf16_f32 v138, v150, v151
	v_cvt_pk_bf16_f32 v139, v152, v153
	v_cvt_pk_bf16_f32 v140, v148, v142
	v_cvt_pk_bf16_f32 v141, v141, v136
	v_lshl_add_u64 v[136:137], s[10:11], 0, v[144:145]
	v_lshl_add_u64 v[136:137], v[136:137], 0, s[66:67]
	v_lshl_add_u64 v[136:137], v[136:137], 0, v[184:185]
	global_store_dwordx4 v[136:137], v[138:141], off offset:-4096
	v_and_b32_e32 v145, 0xffff0000, v128
	v_and_b32_e32 v128, 0xffff0000, v132
	v_lshlrev_b32_e32 v141, 16, v130
	v_and_b32_e32 v139, 0xffff0000, v130
	v_mul_f32_e32 v130, 0x3d372713, v68
	v_mul_f32_e32 v130, v68, v130
	v_fma_f32 v130, v68, v130, v68
	v_mul_f32_e32 v130, 0x3f4c422a, v130
	v_add_f32_e32 v130, v130, v130
	v_mul_f32_e32 v130, 0x3fb8aa3b, v130
	v_exp_f32_e32 v130, v130
	v_lshlrev_b32_e32 v132, 16, v133
	v_and_b32_e32 v138, 0xffff0000, v133
	v_lshlrev_b32_e32 v133, 16, v131
	v_add_f32_e32 v130, 1.0, v130
	v_rcp_f32_e32 v130, v130
	v_mul_f32_e32 v140, 0.5, v68
	v_lshlrev_b32_e32 v150, 16, v134
	v_and_b32_e32 v134, 0xffff0000, v134
	v_fma_f32 v142, v130, -2.0, 1.0
	v_pk_add_f32 v[130:131], v[142:143], v[198:199]
	v_mov_b32_e32 v199, v128
	v_mul_f32_e32 v130, v140, v130
	v_mul_f32_e32 v142, v130, v131
	v_mul_f32_e32 v130, 0x3d372713, v69
	v_mul_f32_e32 v130, v69, v130
	v_fma_f32 v130, v69, v130, v69
	v_mul_f32_e32 v130, 0x3f4c422a, v130
	v_add_f32_e32 v130, v130, v130
	v_mul_f32_e32 v130, 0x3fb8aa3b, v130
	v_exp_f32_e32 v130, v130
	v_mul_f32_e32 v140, 0.5, v69
	v_lshlrev_b32_e32 v151, 16, v135
	v_and_b32_e32 v135, 0xffff0000, v135
	v_add_f32_e32 v130, 1.0, v130
	v_rcp_f32_e32 v130, v130
	s_nop 0
	v_fma_f32 v144, v130, -2.0, 1.0
	v_pk_add_f32 v[130:131], v[144:145], v[198:199]
	v_mov_b32_e32 v199, v132
	v_mul_f32_e32 v128, v140, v130
	v_mul_f32_e32 v143, v128, v131
	v_mul_f32_e32 v128, 0x3d372713, v70
	v_mul_f32_e32 v128, v70, v128
	v_fma_f32 v128, v70, v128, v70
	v_mul_f32_e32 v128, 0x3f4c422a, v128
	v_add_f32_e32 v128, v128, v128
	v_mul_f32_e32 v128, 0x3fb8aa3b, v128
	v_exp_f32_e32 v128, v128
	s_nop 0
	v_add_f32_e32 v128, 1.0, v128
	v_rcp_f32_e32 v128, v128
	s_nop 0
	v_fma_f32 v146, v128, -2.0, 1.0
	v_mul_f32_e32 v128, 0.5, v70
; __device__ __forceinline__ unsigned cvt_pk_bf16(float lo, float hi) { unsigned r; asm volatile("s_nop 0\n\tv_cvt_pk_bf16_f32 %0, %1, %2\n\ts_nop 1" : "=v"(r) : "v"(lo), "v"(hi)); return r; }
; __device__ __forceinline__ float bflo(unsigned w) { return __uint_as_float(w << 16); }
; __device__ __forceinline__ float bfhi(unsigned w) { return __uint_as_float(w & 0xffff0000u); }
; __device__ __forceinline__ float gelu_tanh(float x) { const float y = 0.7978845608028654f * (x + 0.044715f * x * x * x); const float t = 1.f - 2.f * __builtin_amdgcn_rcpf(1.f + __expf(2.f * y)); return 0.5f * x * (1.f + t); }
;     __device__ __forceinline__ void operator()(f32x4 (&acc)[2][2][4][2], const Unit& u, int wr, int wc, int fr, int fq) const {
;     ...
;             for (int ai = 0; ai < 2; ++ai) {
;                 u32x4 ya[4][2], yb[4][2];
; #pragma unroll
;                 for (int m = 0; m < 4; ++m)
; #pragma unroll
;                     for (int bj = 0; bj < 2; ++bj) { const size_t idx = (size_t)(row0 + ai * 128 + m * 16) * 1024 + (u.pn - 8) * 256 + bj * 128 + c8;
;                         ya[m][bj] = *(const u32x4*)(ylf + idx); yb[m][bj] = *(const u32x4*)(ylb + idx); }
;     ...
;                 for (int m = 0; m < 4; ++m)
; #pragma unroll
;                     for (int bj = 0; bj < 2; ++bj) { const size_t idx = (size_t)(row0 + ai * 128 + m * 16) * 1024 + (u.pn - 8) * 256 + bj * 128 + c8;
;                         const u32x4 a = ya[m][bj], b = yb[m][bj];
;                         float yv[8] = {bflo(a.x) + bflo(b.x), bfhi(a.x) + bfhi(b.x), bflo(a.y) + bflo(b.y), bfhi(a.y) + bfhi(b.y), bflo(a.z) + bflo(b.z), bfhi(a.z) + bfhi(b.z), bflo(a.w) + bflo(b.w), bfhi(a.w) + bfhi(b.w)};
;                         float o[8];
; #pragma unroll
;                         for (int n = 0; n < 2; ++n)
; #pragma unroll
;                             for (int j = 0; j < 4; ++j) o[4 * n + j] = yv[4 * n + j] * gelu_tanh(acc[ai][bj][m][n][j]);
;                         u32x4 w; w.x = cvt_pk_bf16(o[0], o[1]); w.y = cvt_pk_bf16(o[2], o[3]); w.z = cvt_pk_bf16(o[4], o[5]); w.w = cvt_pk_bf16(o[6], o[7]);
;                         *(u32x4*)(ylf + idx) = w; }
	v_pk_add_f32 v[130:131], v[146:147], v[198:199]
	v_mov_b32_e32 v199, v138
	v_mul_f32_e32 v128, v128, v130
	v_mul_f32_e32 v144, v128, v131
	v_mul_f32_e32 v128, 0x3d372713, v71
	v_mul_f32_e32 v128, v71, v128
	v_fma_f32 v128, v71, v128, v71
	v_mul_f32_e32 v128, 0x3f4c422a, v128
	v_add_f32_e32 v128, v128, v128
	v_mul_f32_e32 v128, 0x3fb8aa3b, v128
	v_exp_f32_e32 v128, v128
	s_nop 0
	v_add_f32_e32 v128, 1.0, v128
	v_rcp_f32_e32 v128, v128
	s_nop 0
	v_fma_f32 v148, v128, -2.0, 1.0
	v_mul_f32_e32 v128, 0.5, v71
	v_pk_add_f32 v[130:131], v[148:149], v[198:199]
	v_mov_b32_e32 v199, v150
	v_mul_f32_e32 v128, v128, v130
	v_mul_f32_e32 v145, v128, v131
	v_mul_f32_e32 v128, 0x3d372713, v64
	v_mul_f32_e32 v128, v64, v128
	v_fma_f32 v128, v64, v128, v64
	v_mul_f32_e32 v128, 0x3f4c422a, v128
	v_add_f32_e32 v128, v128, v128
	v_mul_f32_e32 v128, 0x3fb8aa3b, v128
	v_exp_f32_e32 v128, v128
	s_nop 0
	v_add_f32_e32 v128, 1.0, v128
	v_rcp_f32_e32 v128, v128
	s_nop 0
	v_fma_f32 v140, v128, -2.0, 1.0
	v_mul_f32_e32 v128, 0.5, v64
	v_pk_add_f32 v[130:131], v[140:141], v[198:199]
	v_mov_b32_e32 v199, v134
	v_mul_f32_e32 v128, v128, v130
	v_mul_f32_e32 v140, v128, v131
	v_mul_f32_e32 v128, 0x3d372713, v65
	v_mul_f32_e32 v128, v65, v128
	v_fma_f32 v128, v65, v128, v65
	v_mul_f32_e32 v128, 0x3f4c422a, v128
	v_add_f32_e32 v128, v128, v128
	v_mul_f32_e32 v128, 0x3fb8aa3b, v128
	v_exp_f32_e32 v128, v128
	s_nop 0
	v_add_f32_e32 v128, 1.0, v128
	v_rcp_f32_e32 v128, v128
	s_nop 0
	v_fma_f32 v138, v128, -2.0, 1.0
	v_mul_f32_e32 v128, 0.5, v65
	v_pk_add_f32 v[130:131], v[138:139], v[198:199]
	v_mov_b32_e32 v199, v151
	v_mul_f32_e32 v128, v128, v130
	v_mul_f32_e32 v134, v128, v131
	v_mul_f32_e32 v128, 0x3d372713, v66
	v_mul_f32_e32 v128, v66, v128
	v_fma_f32 v128, v66, v128, v66
	v_mul_f32_e32 v128, 0x3f4c422a, v128
	v_add_f32_e32 v128, v128, v128
	v_mul_f32_e32 v128, 0x3fb8aa3b, v128
	v_exp_f32_e32 v128, v128
	s_nop 0
	v_add_f32_e32 v128, 1.0, v128
	v_rcp_f32_e32 v128, v128
	s_nop 0
	v_fma_f32 v132, v128, -2.0, 1.0
	v_mul_f32_e32 v128, 0.5, v66
	v_pk_add_f32 v[130:131], v[132:133], v[198:199]
	v_mov_b32_e32 v199, v135
	v_mul_f32_e32 v128, v128, v130
	v_mul_f32_e32 v131, v128, v131
	v_mul_f32_e32 v128, 0x3d372713, v67
	v_mul_f32_e32 v128, v67, v128
	v_fma_f32 v128, v67, v128, v67
	v_mul_f32_e32 v128, 0x3f4c422a, v128
	v_add_f32_e32 v128, v128, v128
	v_mul_f32_e32 v128, 0x3fb8aa3b, v128
	v_exp_f32_e32 v128, v128
	v_mul_f32_e32 v130, 0.5, v67
	v_add_f32_e32 v128, 1.0, v128
	v_rcp_f32_e32 v128, v128
	s_nop 0
	v_fma_f32 v128, v128, -2.0, 1.0
	v_pk_add_f32 v[128:129], v[128:129], v[198:199]
	s_nop 0
	v_mul_f32_e32 v128, v130, v128
	v_mul_f32_e32 v132, v128, v129
	v_cvt_pk_bf16_f32 v128, v142, v143
	v_cvt_pk_bf16_f32 v129, v144, v145
	v_cvt_pk_bf16_f32 v130, v140, v134
	v_cvt_pk_bf16_f32 v131, v131, v132
	global_store_dwordx4 v[136:137], v[128:131], off offset:-3840
	s_nop 1
	v_lshlrev_b64 v[128:129], 10, v[216:217]
	v_lshl_add_u64 v[128:129], v[128:129], 0, v[192:193]
	v_lshlrev_b64 v[128:129], 1, v[128:129]
	v_lshl_add_u64 v[130:131], s[10:11], 0, v[128:129]
	global_load_dwordx4 v[194:197], v[130:131], off
	v_lshl_add_u64 v[130:131], s[12:13], 0, v[128:129]
	global_load_dwordx4 v[224:227], v[130:131], off
	v_or_b32_e32 v128, 0x100, v128
	v_lshl_add_u64 v[130:131], s[10:11], 0, v[128:129]
	v_lshl_add_u64 v[128:129], s[12:13], 0, v[128:129]
	global_load_dwordx4 v[176:179], v[130:131], off
	global_load_dwordx4 v[180:183], v[128:129], off
	v_lshlrev_b64 v[128:129], 10, v[190:191]
	v_lshl_add_u64 v[128:129], v[128:129], 0, v[192:193]
	v_lshlrev_b64 v[128:129], 1, v[128:129]
	v_lshl_add_u64 v[130:131], s[10:11], 0, v[128:129]
	global_load_dwordx4 v[168:171], v[130:131], off
	v_lshl_add_u64 v[130:131], s[12:13], 0, v[128:129]
	v_or_b32_e32 v128, 0x100, v128
	global_load_dwordx4 v[172:175], v[130:131], off
	v_lshl_add_u64 v[130:131], s[10:11], 0, v[128:129]
	v_lshl_add_u64 v[128:129], s[12:13], 0, v[128:129]
	global_load_dwordx4 v[160:163], v[130:131], off
	global_load_dwordx4 v[164:167], v[128:129], off
	v_lshlrev_b64 v[128:129], 10, v[188:189]
	v_lshl_add_u64 v[128:129], v[128:129], 0, v[192:193]
	v_lshlrev_b64 v[128:129], 1, v[128:129]
	v_lshl_add_u64 v[130:131], s[10:11], 0, v[128:129]
	global_load_dwordx4 v[152:155], v[130:131], off
	v_lshl_add_u64 v[130:131], s[12:13], 0, v[128:129]
	v_or_b32_e32 v128, 0x100, v128
	global_load_dwordx4 v[156:159], v[130:131], off
	v_lshl_add_u64 v[130:131], s[10:11], 0, v[128:129]
	v_lshl_add_u64 v[128:129], s[12:13], 0, v[128:129]
	global_load_dwordx4 v[144:147], v[130:131], off
	global_load_dwordx4 v[148:151], v[128:129], off
	v_lshlrev_b64 v[128:129], 10, v[186:187]
	v_lshl_add_u64 v[128:129], v[128:129], 0, v[192:193]
	v_lshlrev_b64 v[132:133], 1, v[128:129]
	v_lshl_add_u64 v[128:129], s[10:11], 0, v[132:133]
	v_lshlrev_b64 v[216:217], 11, v[216:217]
	global_load_dwordx4 v[136:139], v[128:129], off
	v_lshl_add_u64 v[128:129], s[12:13], 0, v[132:133]
	v_or_b32_e32 v132, 0x100, v132
	v_lshl_add_u64 v[216:217], s[10:11], 0, v[216:217]
	global_load_dwordx4 v[140:143], v[128:129], off
	v_lshl_add_u64 v[128:129], s[10:11], 0, v[132:133]
	v_lshl_add_u64 v[132:133], s[12:13], 0, v[132:133]
	v_lshl_add_u64 v[216:217], v[216:217], 0, s[66:67]
	global_load_dwordx4 v[128:131], v[128:129], off
	v_lshl_add_u64 v[216:217], v[216:217], 0, v[184:185]
	global_load_dwordx4 v[132:135], v[132:133], off
	s_waitcnt vmcnt(0)
; __device__ __forceinline__ unsigned cvt_pk_bf16(float lo, float hi) { unsigned r; asm volatile("s_nop 0\n\tv_cvt_pk_bf16_f32 %0, %1, %2\n\ts_nop 1" : "=v"(r) : "v"(lo), "v"(hi)); return r; }
; __device__ __forceinline__ float bflo(unsigned w) { return __uint_as_float(w << 16); }
; __device__ __forceinline__ float bfhi(unsigned w) { return __uint_as_float(w & 0xffff0000u); }
; __device__ __forceinline__ float gelu_tanh(float x) { const float y = 0.7978845608028654f * (x + 0.044715f * x * x * x); const float t = 1.f - 2.f * __builtin_amdgcn_rcpf(1.f + __expf(2.f * y)); return 0.5f * x * (1.f + t); }
;     __device__ __forceinline__ void operator()(f32x4 (&acc)[2][2][4][2], const Unit& u, int wr, int wc, int fr, int fq) const {
;     ...
;                 for (int m = 0; m < 4; ++m)
; #pragma unroll
;                     for (int bj = 0; bj < 2; ++bj) { const size_t idx = (size_t)(row0 + ai * 128 + m * 16) * 1024 + (u.pn - 8) * 256 + bj * 128 + c8;
;                         const u32x4 a = ya[m][bj], b = yb[m][bj];
;                         float yv[8] = {bflo(a.x) + bflo(b.x), bfhi(a.x) + bfhi(b.x), bflo(a.y) + bflo(b.y), bfhi(a.y) + bfhi(b.y), bflo(a.z) + bflo(b.z), bfhi(a.z) + bfhi(b.z), bflo(a.w) + bflo(b.w), bfhi(a.w) + bfhi(b.w)};
;                         float o[8];
; #pragma unroll
;                         for (int n = 0; n < 2; ++n)
; #pragma unroll
;                             for (int j = 0; j < 4; ++j) o[4 * n + j] = yv[4 * n + j] * gelu_tanh(acc[ai][bj][m][n][j]);
;                         u32x4 w; w.x = cvt_pk_bf16(o[0], o[1]); w.y = cvt_pk_bf16(o[2], o[3]); w.z = cvt_pk_bf16(o[4], o[5]); w.w = cvt_pk_bf16(o[6], o[7]);
;                         *(u32x4*)(ylf + idx) = w; }
	v_lshlrev_b32_e32 v229, 16, v194
	v_and_b32_e32 v231, 0xffff0000, v194
	v_lshlrev_b32_e32 v194, 16, v225
	v_and_b32_e32 v215, 0xffff0000, v225
	v_lshlrev_b32_e32 v225, 16, v196
	v_and_b32_e32 v223, 0xffff0000, v196
	v_mul_f32_e32 v196, 0x3d372713, v60
	v_mul_f32_e32 v196, v60, v196
	v_fma_f32 v196, v60, v196, v60
	v_mul_f32_e32 v196, 0x3f4c422a, v196
	v_add_f32_e32 v196, v196, v196
	v_mul_f32_e32 v196, 0x3fb8aa3b, v196
	v_exp_f32_e32 v196, v196
	v_lshlrev_b32_e32 v199, 16, v224
	v_lshlrev_b32_e32 v221, 16, v197
	v_and_b32_e32 v219, 0xffff0000, v197
	v_add_f32_e32 v196, 1.0, v196
	v_rcp_f32_e32 v196, v196
	v_and_b32_e32 v192, 0xffff0000, v224
	v_lshlrev_b32_e32 v233, 16, v195
	v_and_b32_e32 v195, 0xffff0000, v195
	v_fma_f32 v228, v196, -2.0, 1.0
	v_pk_add_f32 v[196:197], v[228:229], v[198:199]
	v_mov_b32_e32 v199, v192
	v_mul_f32_e32 v196, v222, v196
	v_mul_f32_e32 v228, v196, v197
	v_mul_f32_e32 v196, 0x3d372713, v61
	v_mul_f32_e32 v196, v61, v196
	v_fma_f32 v196, v61, v196, v61
	v_mul_f32_e32 v196, 0x3f4c422a, v196
	v_add_f32_e32 v196, v196, v196
	v_mul_f32_e32 v196, 0x3fb8aa3b, v196
	v_exp_f32_e32 v196, v196
	v_mul_f32_e32 v222, 0.5, v61
	v_lshlrev_b32_e32 v218, 16, v226
	v_and_b32_e32 v220, 0xffff0000, v226
	v_add_f32_e32 v196, 1.0, v196
	v_rcp_f32_e32 v196, v196
	v_lshlrev_b32_e32 v226, 16, v227
	v_and_b32_e32 v227, 0xffff0000, v227
	v_fma_f32 v230, v196, -2.0, 1.0
	v_pk_add_f32 v[196:197], v[230:231], v[198:199]
	v_mov_b32_e32 v199, v194
	v_mul_f32_e32 v192, v222, v196
	v_mul_f32_e32 v196, 0x3d372713, v62
	v_mul_f32_e32 v196, v62, v196
	v_fma_f32 v196, v62, v196, v62
	v_mul_f32_e32 v196, 0x3f4c422a, v196
	v_add_f32_e32 v196, v196, v196
	v_mul_f32_e32 v196, 0x3fb8aa3b, v196
	v_exp_f32_e32 v196, v196
	v_mul_f32_e32 v192, v192, v197
	v_mul_f32_e32 v222, 0.5, v62
	v_add_f32_e32 v196, 1.0, v196
	v_rcp_f32_e32 v196, v196
	s_nop 0
	v_fma_f32 v232, v196, -2.0, 1.0
	v_pk_add_f32 v[196:197], v[232:233], v[198:199]
	v_mov_b32_e32 v199, v215
	v_mul_f32_e32 v194, v222, v196
	v_mul_f32_e32 v196, v194, v197
	v_mul_f32_e32 v194, 0x3d372713, v63
	v_mul_f32_e32 v194, v63, v194
	v_fma_f32 v194, v63, v194, v63
	v_mul_f32_e32 v194, 0x3f4c422a, v194
	v_add_f32_e32 v194, v194, v194
	v_mul_f32_e32 v194, 0x3fb8aa3b, v194
	v_exp_f32_e32 v194, v194
	v_mul_f32_e32 v197, 0.5, v63
	v_mul_f32_e32 v215, 0.5, v56
	v_add_f32_e32 v194, 1.0, v194
	v_rcp_f32_e32 v194, v194
	s_nop 0
	v_fma_f32 v194, v194, -2.0, 1.0
	v_pk_add_f32 v[194:195], v[194:195], v[198:199]
	v_mov_b32_e32 v199, v218
	v_mul_f32_e32 v194, v197, v194
	v_mul_f32_e32 v197, v194, v195
	v_mul_f32_e32 v194, 0x3d372713, v56
	v_mul_f32_e32 v194, v56, v194
	v_fma_f32 v194, v56, v194, v56
	v_mul_f32_e32 v194, 0x3f4c422a, v194
	v_add_f32_e32 v194, v194, v194
	v_mul_f32_e32 v194, 0x3fb8aa3b, v194
	v_exp_f32_e32 v194, v194
	v_mul_f32_e32 v218, 0.5, v57
	v_add_f32_e32 v194, 1.0, v194
	v_rcp_f32_e32 v194, v194
	s_nop 0
	v_fma_f32 v224, v194, -2.0, 1.0
	v_pk_add_f32 v[194:195], v[224:225], v[198:199]
	v_mov_b32_e32 v199, v220
	v_mul_f32_e32 v194, v215, v194
	v_mul_f32_e32 v215, v194, v195
	v_mul_f32_e32 v194, 0x3d372713, v57
	v_mul_f32_e32 v194, v57, v194
	v_fma_f32 v194, v57, v194, v57
	v_mul_f32_e32 v194, 0x3f4c422a, v194
	v_add_f32_e32 v194, v194, v194
	v_mul_f32_e32 v194, 0x3fb8aa3b, v194
	v_exp_f32_e32 v194, v194
	v_and_b32_e32 v225, 0xffff0000, v177
	v_add_f32_e32 v194, 1.0, v194
	v_rcp_f32_e32 v194, v194
	s_nop 0
	v_fma_f32 v222, v194, -2.0, 1.0
	v_pk_add_f32 v[194:195], v[222:223], v[198:199]
	v_mov_b32_e32 v199, v226
	v_mul_f32_e32 v194, v218, v194
	v_mul_f32_e32 v222, v194, v195
	v_mul_f32_e32 v194, 0x3d372713, v58
	v_mul_f32_e32 v194, v58, v194
	v_fma_f32 v194, v58, v194, v58
	v_mul_f32_e32 v194, 0x3f4c422a, v194
	v_add_f32_e32 v194, v194, v194
	v_mul_f32_e32 v194, 0x3fb8aa3b, v194
	v_exp_f32_e32 v194, v194
	v_mul_f32_e32 v218, 0.5, v58
	v_lshlrev_b32_e32 v223, 16, v177
	v_and_b32_e32 v177, 0xffff0000, v179
	v_add_f32_e32 v194, 1.0, v194
	v_rcp_f32_e32 v194, v194
	v_lshlrev_b32_e32 v226, 16, v183
	v_and_b32_e32 v183, 0xffff0000, v183
	v_fma_f32 v220, v194, -2.0, 1.0
	v_pk_add_f32 v[194:195], v[220:221], v[198:199]
	v_mov_b32_e32 v199, v227
	v_mul_f32_e32 v194, v218, v194
	v_mul_f32_e32 v220, v194, v195
	v_mul_f32_e32 v194, 0x3d372713, v59
	v_mul_f32_e32 v194, v59, v194
	v_fma_f32 v194, v59, v194, v59
	v_mul_f32_e32 v194, 0x3f4c422a, v194
	v_add_f32_e32 v194, v194, v194
	v_mul_f32_e32 v194, 0x3fb8aa3b, v194
	v_exp_f32_e32 v194, v194
	v_mul_f32_e32 v221, 0.5, v59
	v_add_f32_e32 v194, 1.0, v194
	v_rcp_f32_e32 v194, v194
	s_nop 0
	v_fma_f32 v218, v194, -2.0, 1.0
	v_pk_add_f32 v[194:195], v[218:219], v[198:199]
	v_and_b32_e32 v219, 0xffff0000, v178
	v_mul_f32_e32 v194, v221, v194
	v_lshlrev_b32_e32 v221, 16, v178
	v_mul_f32_e32 v178, 0x3d372713, v52
	v_mul_f32_e32 v178, v52, v178
	v_fma_f32 v178, v52, v178, v52
	v_mul_f32_e32 v178, 0x3f4c422a, v178
	v_add_f32_e32 v178, v178, v178
	v_mul_f32_e32 v178, 0x3fb8aa3b, v178
	v_exp_f32_e32 v178, v178
	v_mul_f32_e32 v199, v194, v195
	v_cvt_pk_bf16_f32 v194, v228, v192
	v_cvt_pk_bf16_f32 v195, v196, v197
	v_add_f32_e32 v178, 1.0, v178
	v_rcp_f32_e32 v178, v178
	s_nop 0
	v_cvt_pk_bf16_f32 v196, v215, v222
	v_cvt_pk_bf16_f32 v197, v220, v199
	global_store_dwordx4 v[216:217], v[194:197], off offset:-4096
	v_lshlrev_b32_e32 v199, 16, v180
	v_and_b32_e32 v192, 0xffff0000, v181
	v_lshlrev_b32_e32 v195, 16, v176
	v_fma_f32 v194, v178, -2.0, 1.0
	v_and_b32_e32 v197, 0xffff0000, v176
	v_and_b32_e32 v176, 0xffff0000, v180
	v_lshlrev_b32_e32 v180, 16, v181
	v_lshlrev_b32_e32 v181, 16, v179
	v_mul_f32_e32 v196, 0.5, v52
	v_pk_add_f32 v[178:179], v[194:195], v[198:199]
; __device__ __forceinline__ unsigned cvt_pk_bf16(float lo, float hi) { unsigned r; asm volatile("s_nop 0\n\tv_cvt_pk_bf16_f32 %0, %1, %2\n\ts_nop 1" : "=v"(r) : "v"(lo), "v"(hi)); return r; }
; __device__ __forceinline__ float bflo(unsigned w) { return __uint_as_float(w << 16); }
; __device__ __forceinline__ float bfhi(unsigned w) { return __uint_as_float(w & 0xffff0000u); }
; __device__ __forceinline__ float gelu_tanh(float x) { const float y = 0.7978845608028654f * (x + 0.044715f * x * x * x); const float t = 1.f - 2.f * __builtin_amdgcn_rcpf(1.f + __expf(2.f * y)); return 0.5f * x * (1.f + t); }
;     __device__ __forceinline__ void operator()(f32x4 (&acc)[2][2][4][2], const Unit& u, int wr, int wc, int fr, int fq) const {
;     ...
;                 for (int m = 0; m < 4; ++m)
; #pragma unroll
;                     for (int bj = 0; bj < 2; ++bj) { const size_t idx = (size_t)(row0 + ai * 128 + m * 16) * 1024 + (u.pn - 8) * 256 + bj * 128 + c8;
;                         const u32x4 a = ya[m][bj], b = yb[m][bj];
;                         float yv[8] = {bflo(a.x) + bflo(b.x), bfhi(a.x) + bfhi(b.x), bflo(a.y) + bflo(b.y), bfhi(a.y) + bfhi(b.y), bflo(a.z) + bflo(b.z), bfhi(a.z) + bfhi(b.z), bflo(a.w) + bflo(b.w), bfhi(a.w) + bfhi(b.w)};
;                         float o[8];
; #pragma unroll
;                         for (int n = 0; n < 2; ++n)
; #pragma unroll
;                             for (int j = 0; j < 4; ++j) o[4 * n + j] = yv[4 * n + j] * gelu_tanh(acc[ai][bj][m][n][j]);
;                         u32x4 w; w.x = cvt_pk_bf16(o[0], o[1]); w.y = cvt_pk_bf16(o[2], o[3]); w.z = cvt_pk_bf16(o[4], o[5]); w.w = cvt_pk_bf16(o[6], o[7]);
;                         *(u32x4*)(ylf + idx) = w; }
	v_mov_b32_e32 v199, v176
	v_mul_f32_e32 v178, v196, v178
	v_mul_f32_e32 v194, v178, v179
	v_mul_f32_e32 v178, 0x3d372713, v53
	v_mul_f32_e32 v178, v53, v178
	v_fma_f32 v178, v53, v178, v53
	v_mul_f32_e32 v178, 0x3f4c422a, v178
	v_add_f32_e32 v178, v178, v178
	v_mul_f32_e32 v178, 0x3fb8aa3b, v178
	v_exp_f32_e32 v178, v178
	v_mul_f32_e32 v195, 0.5, v53
	v_lshlrev_b32_e32 v215, 16, v182
	v_and_b32_e32 v182, 0xffff0000, v182
	v_add_f32_e32 v178, 1.0, v178
	v_rcp_f32_e32 v178, v178
	s_nop 0
	v_fma_f32 v196, v178, -2.0, 1.0
	v_pk_add_f32 v[178:179], v[196:197], v[198:199]
	v_mov_b32_e32 v199, v180
	v_mul_f32_e32 v176, v195, v178
	v_mul_f32_e32 v195, v176, v179
	v_mul_f32_e32 v176, 0x3d372713, v54
	v_mul_f32_e32 v176, v54, v176
	v_fma_f32 v176, v54, v176, v54
	v_mul_f32_e32 v176, 0x3f4c422a, v176
	v_add_f32_e32 v176, v176, v176
	v_mul_f32_e32 v176, 0x3fb8aa3b, v176
	v_exp_f32_e32 v176, v176
	s_nop 0
	v_add_f32_e32 v176, 1.0, v176
	v_rcp_f32_e32 v176, v176
	s_nop 0
	v_fma_f32 v222, v176, -2.0, 1.0
	v_mul_f32_e32 v176, 0.5, v54
	v_pk_add_f32 v[178:179], v[222:223], v[198:199]
	v_mov_b32_e32 v199, v192
	v_mul_f32_e32 v176, v176, v178
	v_mul_f32_e32 v196, v176, v179
	v_mul_f32_e32 v176, 0x3d372713, v55
	v_mul_f32_e32 v176, v55, v176
	v_fma_f32 v176, v55, v176, v55
	v_mul_f32_e32 v176, 0x3f4c422a, v176
	v_add_f32_e32 v176, v176, v176
	v_mul_f32_e32 v176, 0x3fb8aa3b, v176
	v_exp_f32_e32 v176, v176
	s_nop 0
	v_add_f32_e32 v176, 1.0, v176
	v_rcp_f32_e32 v176, v176
	s_nop 0
	v_fma_f32 v224, v176, -2.0, 1.0
	v_mul_f32_e32 v176, 0.5, v55
	v_pk_add_f32 v[178:179], v[224:225], v[198:199]
	v_mov_b32_e32 v199, v215
	v_mul_f32_e32 v176, v176, v178
	v_mul_f32_e32 v192, v176, v179
	v_mul_f32_e32 v176, 0x3d372713, v48
	v_mul_f32_e32 v176, v48, v176
	v_fma_f32 v176, v48, v176, v48
	v_mul_f32_e32 v176, 0x3f4c422a, v176
	v_add_f32_e32 v176, v176, v176
	v_mul_f32_e32 v176, 0x3fb8aa3b, v176
	v_exp_f32_e32 v176, v176
	v_lshlrev_b32_e32 v215, 16, v175
	v_and_b32_e32 v175, 0xffff0000, v175
	v_add_f32_e32 v176, 1.0, v176
	v_rcp_f32_e32 v176, v176
	s_nop 0
	v_fma_f32 v220, v176, -2.0, 1.0
	v_mul_f32_e32 v176, 0.5, v48
	v_pk_add_f32 v[178:179], v[220:221], v[198:199]
	v_mov_b32_e32 v199, v182
	v_mul_f32_e32 v176, v176, v178
	v_mul_f32_e32 v197, v176, v179
	v_mul_f32_e32 v176, 0x3d372713, v49
	v_mul_f32_e32 v176, v49, v176
	v_fma_f32 v176, v49, v176, v49
	v_mul_f32_e32 v176, 0x3f4c422a, v176
	v_add_f32_e32 v176, v176, v176
	v_mul_f32_e32 v176, 0x3fb8aa3b, v176
	v_exp_f32_e32 v176, v176
	s_nop 0
	v_add_f32_e32 v176, 1.0, v176
	v_rcp_f32_e32 v176, v176
	s_nop 0
	v_fma_f32 v218, v176, -2.0, 1.0
	v_mul_f32_e32 v176, 0.5, v49
	v_pk_add_f32 v[178:179], v[218:219], v[198:199]
	v_mov_b32_e32 v199, v226
	v_mul_f32_e32 v176, v176, v178
	v_mul_f32_e32 v182, v176, v179
	v_mul_f32_e32 v176, 0x3d372713, v50
	v_mul_f32_e32 v176, v50, v176
	v_fma_f32 v176, v50, v176, v50
	v_mul_f32_e32 v176, 0x3f4c422a, v176
	v_add_f32_e32 v176, v176, v176
	v_mul_f32_e32 v176, 0x3fb8aa3b, v176
	v_exp_f32_e32 v176, v176
	s_nop 0
	v_add_f32_e32 v176, 1.0, v176
	v_rcp_f32_e32 v176, v176
	s_nop 0
	v_fma_f32 v180, v176, -2.0, 1.0
	v_mul_f32_e32 v176, 0.5, v50
	v_pk_add_f32 v[178:179], v[180:181], v[198:199]
	v_mov_b32_e32 v199, v183
	v_mul_f32_e32 v176, v176, v178
	v_mul_f32_e32 v179, v176, v179
	v_mul_f32_e32 v176, 0x3d372713, v51
	v_mul_f32_e32 v176, v51, v176
	v_fma_f32 v176, v51, v176, v51
	v_mul_f32_e32 v176, 0x3f4c422a, v176
	v_add_f32_e32 v176, v176, v176
	v_mul_f32_e32 v176, 0x3fb8aa3b, v176
	v_exp_f32_e32 v176, v176
	v_mul_f32_e32 v178, 0.5, v51
	v_lshlrev_b32_e32 v181, 16, v170
	v_lshlrev_b32_e32 v183, 16, v168
	v_add_f32_e32 v176, 1.0, v176
	v_rcp_f32_e32 v176, v176
	s_nop 0
	v_fma_f32 v176, v176, -2.0, 1.0
	v_pk_add_f32 v[176:177], v[176:177], v[198:199]
	v_lshlrev_b32_e32 v199, 16, v172
	v_mul_f32_e32 v176, v178, v176
	v_mul_f32_e32 v180, v176, v177
	v_cvt_pk_bf16_f32 v176, v194, v195
	v_cvt_pk_bf16_f32 v177, v196, v192
	v_cvt_pk_bf16_f32 v178, v197, v182
	v_cvt_pk_bf16_f32 v179, v179, v180
	global_store_dwordx4 v[216:217], v[176:179], off offset:-3840
	v_lshlrev_b32_e32 v195, 16, v169
	v_and_b32_e32 v197, 0xffff0000, v169
	v_and_b32_e32 v179, 0xffff0000, v170
	v_mul_f32_e32 v170, 0x3d372713, v44
	v_mul_f32_e32 v170, v44, v170
	v_fma_f32 v170, v44, v170, v44
	v_mul_f32_e32 v170, 0x3f4c422a, v170
	v_add_f32_e32 v170, v170, v170
	v_mul_f32_e32 v170, 0x3fb8aa3b, v170
	v_exp_f32_e32 v170, v170
	v_lshlrev_b64 v[176:177], 11, v[190:191]
	v_and_b32_e32 v191, 0xffff0000, v168
	v_and_b32_e32 v168, 0xffff0000, v172
	v_add_f32_e32 v170, 1.0, v170
	v_rcp_f32_e32 v170, v170
	v_lshlrev_b32_e32 v172, 16, v173
	v_and_b32_e32 v178, 0xffff0000, v173
	v_lshlrev_b32_e32 v173, 16, v171
	v_fma_f32 v182, v170, -2.0, 1.0
	v_and_b32_e32 v169, 0xffff0000, v171
	v_mul_f32_e32 v180, 0.5, v44
	v_pk_add_f32 v[170:171], v[182:183], v[198:199]
	v_mov_b32_e32 v199, v168
	v_mul_f32_e32 v170, v180, v170
	v_mul_f32_e32 v182, v170, v171
	v_mul_f32_e32 v170, 0x3d372713, v45
	v_mul_f32_e32 v170, v45, v170
	v_fma_f32 v170, v45, v170, v45
	v_mul_f32_e32 v170, 0x3f4c422a, v170
	v_add_f32_e32 v170, v170, v170
	v_mul_f32_e32 v170, 0x3fb8aa3b, v170
	v_exp_f32_e32 v170, v170
	v_mul_f32_e32 v180, 0.5, v45
	v_lshlrev_b32_e32 v192, 16, v174
	v_and_b32_e32 v174, 0xffff0000, v174
	v_add_f32_e32 v170, 1.0, v170
	v_rcp_f32_e32 v170, v170
	s_nop 0
	v_fma_f32 v190, v170, -2.0, 1.0
	v_pk_add_f32 v[170:171], v[190:191], v[198:199]
	v_mov_b32_e32 v199, v172
	v_mul_f32_e32 v168, v180, v170
	v_mul_f32_e32 v183, v168, v171
	v_mul_f32_e32 v168, 0x3d372713, v46
	v_mul_f32_e32 v168, v46, v168
	v_fma_f32 v168, v46, v168, v46
	v_mul_f32_e32 v168, 0x3f4c422a, v168
; __device__ __forceinline__ unsigned cvt_pk_bf16(float lo, float hi) { unsigned r; asm volatile("s_nop 0\n\tv_cvt_pk_bf16_f32 %0, %1, %2\n\ts_nop 1" : "=v"(r) : "v"(lo), "v"(hi)); return r; }
; __device__ __forceinline__ float bflo(unsigned w) { return __uint_as_float(w << 16); }
; __device__ __forceinline__ float bfhi(unsigned w) { return __uint_as_float(w & 0xffff0000u); }
; __device__ __forceinline__ float gelu_tanh(float x) { const float y = 0.7978845608028654f * (x + 0.044715f * x * x * x); const float t = 1.f - 2.f * __builtin_amdgcn_rcpf(1.f + __expf(2.f * y)); return 0.5f * x * (1.f + t); }
;     __device__ __forceinline__ void operator()(f32x4 (&acc)[2][2][4][2], const Unit& u, int wr, int wc, int fr, int fq) const {
;     ...
;                 for (int m = 0; m < 4; ++m)
; #pragma unroll
;                     for (int bj = 0; bj < 2; ++bj) { const size_t idx = (size_t)(row0 + ai * 128 + m * 16) * 1024 + (u.pn - 8) * 256 + bj * 128 + c8;
;                         const u32x4 a = ya[m][bj], b = yb[m][bj];
;                         float yv[8] = {bflo(a.x) + bflo(b.x), bfhi(a.x) + bfhi(b.x), bflo(a.y) + bflo(b.y), bfhi(a.y) + bfhi(b.y), bflo(a.z) + bflo(b.z), bfhi(a.z) + bfhi(b.z), bflo(a.w) + bflo(b.w), bfhi(a.w) + bfhi(b.w)};
;                         float o[8];
; #pragma unroll
;                         for (int n = 0; n < 2; ++n)
; #pragma unroll
;                             for (int j = 0; j < 4; ++j) o[4 * n + j] = yv[4 * n + j] * gelu_tanh(acc[ai][bj][m][n][j]);
;                         u32x4 w; w.x = cvt_pk_bf16(o[0], o[1]); w.y = cvt_pk_bf16(o[2], o[3]); w.z = cvt_pk_bf16(o[4], o[5]); w.w = cvt_pk_bf16(o[6], o[7]);
;                         *(u32x4*)(ylf + idx) = w; }
	v_add_f32_e32 v168, v168, v168
	v_mul_f32_e32 v168, 0x3fb8aa3b, v168
	v_exp_f32_e32 v168, v168
	s_nop 0
	v_add_f32_e32 v168, 1.0, v168
	v_rcp_f32_e32 v168, v168
	s_nop 0
	v_fma_f32 v194, v168, -2.0, 1.0
	v_mul_f32_e32 v168, 0.5, v46
	v_pk_add_f32 v[170:171], v[194:195], v[198:199]
	v_mov_b32_e32 v199, v178
	v_mul_f32_e32 v168, v168, v170
	v_mul_f32_e32 v190, v168, v171
	v_mul_f32_e32 v168, 0x3d372713, v47
	v_mul_f32_e32 v168, v47, v168
	v_fma_f32 v168, v47, v168, v47
	v_mul_f32_e32 v168, 0x3f4c422a, v168
	v_add_f32_e32 v168, v168, v168
	v_mul_f32_e32 v168, 0x3fb8aa3b, v168
	v_exp_f32_e32 v168, v168
	s_nop 0
	v_add_f32_e32 v168, 1.0, v168
	v_rcp_f32_e32 v168, v168
	s_nop 0
	v_fma_f32 v196, v168, -2.0, 1.0
	v_mul_f32_e32 v168, 0.5, v47
	v_pk_add_f32 v[170:171], v[196:197], v[198:199]
	v_mov_b32_e32 v199, v192
	v_mul_f32_e32 v168, v168, v170
	v_mul_f32_e32 v191, v168, v171
	v_mul_f32_e32 v168, 0x3d372713, v40
	v_mul_f32_e32 v168, v40, v168
	v_fma_f32 v168, v40, v168, v40
	v_mul_f32_e32 v168, 0x3f4c422a, v168
	v_add_f32_e32 v168, v168, v168
	v_mul_f32_e32 v168, 0x3fb8aa3b, v168
	v_exp_f32_e32 v168, v168
	s_nop 0
	v_add_f32_e32 v168, 1.0, v168
	v_rcp_f32_e32 v168, v168
	s_nop 0
	v_fma_f32 v180, v168, -2.0, 1.0
	v_mul_f32_e32 v168, 0.5, v40
	v_pk_add_f32 v[170:171], v[180:181], v[198:199]
	v_mov_b32_e32 v199, v174
	v_mul_f32_e32 v168, v168, v170
	v_mul_f32_e32 v180, v168, v171
	v_mul_f32_e32 v168, 0x3d372713, v41
	v_mul_f32_e32 v168, v41, v168
	v_fma_f32 v168, v41, v168, v41
	v_mul_f32_e32 v168, 0x3f4c422a, v168
	v_add_f32_e32 v168, v168, v168
	v_mul_f32_e32 v168, 0x3fb8aa3b, v168
	v_exp_f32_e32 v168, v168
	v_and_b32_e32 v181, 0xffff0000, v161
	v_add_f32_e32 v168, 1.0, v168
	v_rcp_f32_e32 v168, v168
	s_nop 0
	v_fma_f32 v178, v168, -2.0, 1.0
	v_mul_f32_e32 v168, 0.5, v41
	v_pk_add_f32 v[170:171], v[178:179], v[198:199]
	v_mov_b32_e32 v199, v215
	v_mul_f32_e32 v168, v168, v170
	v_mul_f32_e32 v174, v168, v171
	v_mul_f32_e32 v168, 0x3d372713, v42
	v_mul_f32_e32 v168, v42, v168
	v_fma_f32 v168, v42, v168, v42
	v_mul_f32_e32 v168, 0x3f4c422a, v168
	v_add_f32_e32 v168, v168, v168
	v_mul_f32_e32 v168, 0x3fb8aa3b, v168
	v_exp_f32_e32 v168, v168
	v_lshlrev_b32_e32 v179, 16, v161
	v_and_b32_e32 v161, 0xffff0000, v163
	v_add_f32_e32 v168, 1.0, v168
	v_rcp_f32_e32 v168, v168
	s_nop 0
	v_fma_f32 v172, v168, -2.0, 1.0
	v_mul_f32_e32 v168, 0.5, v42
	v_pk_add_f32 v[170:171], v[172:173], v[198:199]
	v_mov_b32_e32 v199, v175
	v_mul_f32_e32 v168, v168, v170
	v_mul_f32_e32 v173, v168, v171
	v_mul_f32_e32 v168, 0x3d372713, v43
	v_mul_f32_e32 v168, v43, v168
	v_fma_f32 v168, v43, v168, v43
	v_mul_f32_e32 v168, 0x3f4c422a, v168
	v_add_f32_e32 v168, v168, v168
	v_mul_f32_e32 v168, 0x3fb8aa3b, v168
	v_exp_f32_e32 v168, v168
	v_mul_f32_e32 v170, 0.5, v43
	v_lshlrev_b32_e32 v175, 16, v160
	v_add_f32_e32 v168, 1.0, v168
	v_rcp_f32_e32 v168, v168
	s_nop 0
	v_fma_f32 v168, v168, -2.0, 1.0
	v_pk_add_f32 v[168:169], v[168:169], v[198:199]
	v_lshlrev_b32_e32 v199, 16, v164
	v_mul_f32_e32 v168, v170, v168
	v_mul_f32_e32 v168, v168, v169
	v_cvt_pk_bf16_f32 v170, v182, v183
	v_cvt_pk_bf16_f32 v171, v190, v191
	v_cvt_pk_bf16_f32 v172, v180, v174
	v_cvt_pk_bf16_f32 v173, v173, v168
	v_lshl_add_u64 v[168:169], s[10:11], 0, v[176:177]
	v_lshl_add_u64 v[168:169], v[168:169], 0, s[66:67]
	v_lshl_add_u64 v[168:169], v[168:169], 0, v[184:185]
	global_store_dwordx4 v[168:169], v[170:173], off offset:-4096
	v_and_b32_e32 v177, 0xffff0000, v160
	v_and_b32_e32 v160, 0xffff0000, v164
	v_lshlrev_b32_e32 v173, 16, v162
	v_and_b32_e32 v171, 0xffff0000, v162
	v_mul_f32_e32 v162, 0x3d372713, v36
	v_mul_f32_e32 v162, v36, v162
	v_fma_f32 v162, v36, v162, v36
	v_mul_f32_e32 v162, 0x3f4c422a, v162
	v_add_f32_e32 v162, v162, v162
	v_mul_f32_e32 v162, 0x3fb8aa3b, v162
	v_exp_f32_e32 v162, v162
	v_lshlrev_b32_e32 v164, 16, v165
	v_and_b32_e32 v170, 0xffff0000, v165
	v_lshlrev_b32_e32 v165, 16, v163
	v_add_f32_e32 v162, 1.0, v162
	v_rcp_f32_e32 v162, v162
	v_mul_f32_e32 v172, 0.5, v36
	v_lshlrev_b32_e32 v182, 16, v166
	v_and_b32_e32 v166, 0xffff0000, v166
	v_fma_f32 v174, v162, -2.0, 1.0
	v_pk_add_f32 v[162:163], v[174:175], v[198:199]
	v_mov_b32_e32 v199, v160
	v_mul_f32_e32 v162, v172, v162
	v_mul_f32_e32 v174, v162, v163
	v_mul_f32_e32 v162, 0x3d372713, v37
	v_mul_f32_e32 v162, v37, v162
	v_fma_f32 v162, v37, v162, v37
	v_mul_f32_e32 v162, 0x3f4c422a, v162
	v_add_f32_e32 v162, v162, v162
	v_mul_f32_e32 v162, 0x3fb8aa3b, v162
	v_exp_f32_e32 v162, v162
	v_mul_f32_e32 v172, 0.5, v37
	v_lshlrev_b32_e32 v183, 16, v167
	v_and_b32_e32 v167, 0xffff0000, v167
	v_add_f32_e32 v162, 1.0, v162
	v_rcp_f32_e32 v162, v162
	s_nop 0
	v_fma_f32 v176, v162, -2.0, 1.0
	v_pk_add_f32 v[162:163], v[176:177], v[198:199]
	v_mov_b32_e32 v199, v164
	v_mul_f32_e32 v160, v172, v162
	v_mul_f32_e32 v175, v160, v163
	v_mul_f32_e32 v160, 0x3d372713, v38
	v_mul_f32_e32 v160, v38, v160
	v_fma_f32 v160, v38, v160, v38
	v_mul_f32_e32 v160, 0x3f4c422a, v160
	v_add_f32_e32 v160, v160, v160
	v_mul_f32_e32 v160, 0x3fb8aa3b, v160
	v_exp_f32_e32 v160, v160
	s_nop 0
	v_add_f32_e32 v160, 1.0, v160
	v_rcp_f32_e32 v160, v160
	s_nop 0
	v_fma_f32 v178, v160, -2.0, 1.0
	v_mul_f32_e32 v160, 0.5, v38
	v_pk_add_f32 v[162:163], v[178:179], v[198:199]
	v_mov_b32_e32 v199, v170
	v_mul_f32_e32 v160, v160, v162
	v_mul_f32_e32 v176, v160, v163
	v_mul_f32_e32 v160, 0x3d372713, v39
	v_mul_f32_e32 v160, v39, v160
	v_fma_f32 v160, v39, v160, v39
	v_mul_f32_e32 v160, 0x3f4c422a, v160
	v_add_f32_e32 v160, v160, v160
	v_mul_f32_e32 v160, 0x3fb8aa3b, v160
	v_exp_f32_e32 v160, v160
	s_nop 0
	v_add_f32_e32 v160, 1.0, v160
	v_rcp_f32_e32 v160, v160
	s_nop 0
; __device__ __forceinline__ float bflo(unsigned w) { return __uint_as_float(w << 16); }
; __device__ __forceinline__ float bfhi(unsigned w) { return __uint_as_float(w & 0xffff0000u); }
; __device__ __forceinline__ float gelu_tanh(float x) { const float y = 0.7978845608028654f * (x + 0.044715f * x * x * x); const float t = 1.f - 2.f * __builtin_amdgcn_rcpf(1.f + __expf(2.f * y)); return 0.5f * x * (1.f + t); }
;     __device__ __forceinline__ void operator()(f32x4 (&acc)[2][2][4][2], const Unit& u, int wr, int wc, int fr, int fq) const {
;     ...
;                 for (int m = 0; m < 4; ++m)
; #pragma unroll
;                     for (int bj = 0; bj < 2; ++bj) { const size_t idx = (size_t)(row0 + ai * 128 + m * 16) * 1024 + (u.pn - 8) * 256 + bj * 128 + c8;
;                         const u32x4 a = ya[m][bj], b = yb[m][bj];
;                         float yv[8] = {bflo(a.x) + bflo(b.x), bfhi(a.x) + bfhi(b.x), bflo(a.y) + bflo(b.y), bfhi(a.y) + bfhi(b.y), bflo(a.z) + bflo(b.z), bfhi(a.z) + bfhi(b.z), bflo(a.w) + bflo(b.w), bfhi(a.w) + bfhi(b.w)};
;                         float o[8];
; #pragma unroll
;                         for (int n = 0; n < 2; ++n)
; #pragma unroll
;                             for (int j = 0; j < 4; ++j) o[4 * n + j] = yv[4 * n + j] * gelu_tanh(acc[ai][bj][m][n][j]);
	v_fma_f32 v180, v160, -2.0, 1.0
	v_mul_f32_e32 v160, 0.5, v39
	v_pk_add_f32 v[162:163], v[180:181], v[198:199]
	v_mov_b32_e32 v199, v182
	v_mul_f32_e32 v160, v160, v162
	v_mul_f32_e32 v177, v160, v163
	v_mul_f32_e32 v160, 0x3d372713, v32
	v_mul_f32_e32 v160, v32, v160
	v_fma_f32 v160, v32, v160, v32
	v_mul_f32_e32 v160, 0x3f4c422a, v160
	v_add_f32_e32 v160, v160, v160
	v_mul_f32_e32 v160, 0x3fb8aa3b, v160
	v_exp_f32_e32 v160, v160
	s_nop 0
	v_add_f32_e32 v160, 1.0, v160
	v_rcp_f32_e32 v160, v160
	s_nop 0
	v_fma_f32 v172, v160, -2.0, 1.0
	v_mul_f32_e32 v160, 0.5, v32
	v_pk_add_f32 v[162:163], v[172:173], v[198:199]
	v_mov_b32_e32 v199, v166
	v_mul_f32_e32 v160, v160, v162
	v_mul_f32_e32 v172, v160, v163
	v_mul_f32_e32 v160, 0x3d372713, v33
	v_mul_f32_e32 v160, v33, v160
	v_fma_f32 v160, v33, v160, v33
	v_mul_f32_e32 v160, 0x3f4c422a, v160
	v_add_f32_e32 v160, v160, v160
	v_mul_f32_e32 v160, 0x3fb8aa3b, v160
	v_exp_f32_e32 v160, v160
	v_and_b32_e32 v173, 0xffff0000, v153
	v_add_f32_e32 v160, 1.0, v160
	v_rcp_f32_e32 v160, v160
	s_nop 0
	v_fma_f32 v170, v160, -2.0, 1.0
	v_mul_f32_e32 v160, 0.5, v33
	v_pk_add_f32 v[162:163], v[170:171], v[198:199]
	v_mov_b32_e32 v199, v183
	v_mul_f32_e32 v160, v160, v162
	v_mul_f32_e32 v166, v160, v163
	v_mul_f32_e32 v160, 0x3d372713, v34
	v_mul_f32_e32 v160, v34, v160
	v_fma_f32 v160, v34, v160, v34
	v_mul_f32_e32 v160, 0x3f4c422a, v160
	v_add_f32_e32 v160, v160, v160
	v_mul_f32_e32 v160, 0x3fb8aa3b, v160
	v_exp_f32_e32 v160, v160
	v_lshlrev_b32_e32 v171, 16, v153
	v_and_b32_e32 v153, 0xffff0000, v155
	v_add_f32_e32 v160, 1.0, v160
	v_rcp_f32_e32 v160, v160
	s_nop 0
	v_fma_f32 v164, v160, -2.0, 1.0
	v_mul_f32_e32 v160, 0.5, v34
	v_pk_add_f32 v[162:163], v[164:165], v[198:199]
	v_mov_b32_e32 v199, v167
	v_mul_f32_e32 v160, v160, v162
	v_mul_f32_e32 v163, v160, v163
	v_mul_f32_e32 v160, 0x3d372713, v35
	v_mul_f32_e32 v160, v35, v160
	v_fma_f32 v160, v35, v160, v35
	v_mul_f32_e32 v160, 0x3f4c422a, v160
	v_add_f32_e32 v160, v160, v160
	v_mul_f32_e32 v160, 0x3fb8aa3b, v160
	v_exp_f32_e32 v160, v160
	v_mul_f32_e32 v162, 0.5, v35
	v_lshlrev_b32_e32 v165, 16, v154
	v_lshlrev_b32_e32 v167, 16, v152
	v_add_f32_e32 v160, 1.0, v160
	v_rcp_f32_e32 v160, v160
	s_nop 0
	v_fma_f32 v160, v160, -2.0, 1.0
	v_pk_add_f32 v[160:161], v[160:161], v[198:199]
	v_lshlrev_b32_e32 v199, 16, v156
	v_mul_f32_e32 v160, v162, v160
	v_mul_f32_e32 v164, v160, v161
	v_cvt_pk_bf16_f32 v160, v174, v175
	v_cvt_pk_bf16_f32 v161, v176, v177
	v_cvt_pk_bf16_f32 v162, v172, v166
	v_cvt_pk_bf16_f32 v163, v163, v164
	global_store_dwordx4 v[168:169], v[160:163], off offset:-3840
	v_and_b32_e32 v169, 0xffff0000, v152
	v_and_b32_e32 v152, 0xffff0000, v156
	v_and_b32_e32 v163, 0xffff0000, v154
	v_mul_f32_e32 v154, 0x3d372713, v28
	v_mul_f32_e32 v154, v28, v154
	v_fma_f32 v154, v28, v154, v28
	v_mul_f32_e32 v154, 0x3f4c422a, v154
	v_add_f32_e32 v154, v154, v154
	v_mul_f32_e32 v154, 0x3fb8aa3b, v154
	v_exp_f32_e32 v154, v154
	v_lshlrev_b32_e32 v156, 16, v157
	v_and_b32_e32 v162, 0xffff0000, v157
	v_lshlrev_b32_e32 v157, 16, v155
	v_add_f32_e32 v154, 1.0, v154
	v_rcp_f32_e32 v154, v154
	v_mul_f32_e32 v164, 0.5, v28
	v_lshlrev_b32_e32 v174, 16, v158
	v_and_b32_e32 v158, 0xffff0000, v158
	v_fma_f32 v166, v154, -2.0, 1.0
	v_pk_add_f32 v[154:155], v[166:167], v[198:199]
	v_mov_b32_e32 v199, v152
	v_mul_f32_e32 v154, v164, v154
	v_mul_f32_e32 v166, v154, v155
	v_mul_f32_e32 v154, 0x3d372713, v29
	v_mul_f32_e32 v154, v29, v154
	v_fma_f32 v154, v29, v154, v29
	v_mul_f32_e32 v154, 0x3f4c422a, v154
	v_add_f32_e32 v154, v154, v154
	v_mul_f32_e32 v154, 0x3fb8aa3b, v154
	v_exp_f32_e32 v154, v154
	v_mul_f32_e32 v164, 0.5, v29
	v_lshlrev_b32_e32 v175, 16, v159
	v_and_b32_e32 v159, 0xffff0000, v159
	v_add_f32_e32 v154, 1.0, v154
	v_rcp_f32_e32 v154, v154
	v_lshlrev_b64 v[160:161], 11, v[188:189]
	v_fma_f32 v168, v154, -2.0, 1.0
	v_pk_add_f32 v[154:155], v[168:169], v[198:199]
	v_mov_b32_e32 v199, v156
	v_mul_f32_e32 v152, v164, v154
	v_mul_f32_e32 v167, v152, v155
	v_mul_f32_e32 v152, 0x3d372713, v30
	v_mul_f32_e32 v152, v30, v152
	v_fma_f32 v152, v30, v152, v30
	v_mul_f32_e32 v152, 0x3f4c422a, v152
	v_add_f32_e32 v152, v152, v152
	v_mul_f32_e32 v152, 0x3fb8aa3b, v152
	v_exp_f32_e32 v152, v152
	s_nop 0
	v_add_f32_e32 v152, 1.0, v152
	v_rcp_f32_e32 v152, v152
	s_nop 0
	v_fma_f32 v170, v152, -2.0, 1.0
	v_mul_f32_e32 v152, 0.5, v30
	v_pk_add_f32 v[154:155], v[170:171], v[198:199]
	v_mov_b32_e32 v199, v162
	v_mul_f32_e32 v152, v152, v154
	v_mul_f32_e32 v168, v152, v155
	v_mul_f32_e32 v152, 0x3d372713, v31
	v_mul_f32_e32 v152, v31, v152
	v_fma_f32 v152, v31, v152, v31
	v_mul_f32_e32 v152, 0x3f4c422a, v152
	v_add_f32_e32 v152, v152, v152
	v_mul_f32_e32 v152, 0x3fb8aa3b, v152
	v_exp_f32_e32 v152, v152
	s_nop 0
	v_add_f32_e32 v152, 1.0, v152
	v_rcp_f32_e32 v152, v152
	s_nop 0
	v_fma_f32 v172, v152, -2.0, 1.0
	v_mul_f32_e32 v152, 0.5, v31
	v_pk_add_f32 v[154:155], v[172:173], v[198:199]
	v_mov_b32_e32 v199, v174
	v_mul_f32_e32 v152, v152, v154
	v_mul_f32_e32 v169, v152, v155
	v_mul_f32_e32 v152, 0x3d372713, v24
	v_mul_f32_e32 v152, v24, v152
	v_fma_f32 v152, v24, v152, v24
	v_mul_f32_e32 v152, 0x3f4c422a, v152
	v_add_f32_e32 v152, v152, v152
	v_mul_f32_e32 v152, 0x3fb8aa3b, v152
	v_exp_f32_e32 v152, v152
	s_nop 0
	v_add_f32_e32 v152, 1.0, v152
	v_rcp_f32_e32 v152, v152
	s_nop 0
	v_fma_f32 v164, v152, -2.0, 1.0
	v_mul_f32_e32 v152, 0.5, v24
	v_pk_add_f32 v[154:155], v[164:165], v[198:199]
	v_mov_b32_e32 v199, v158
	v_mul_f32_e32 v152, v152, v154
	v_mul_f32_e32 v164, v152, v155
	v_mul_f32_e32 v152, 0x3d372713, v25
	v_mul_f32_e32 v152, v25, v152
	v_fma_f32 v152, v25, v152, v25
; __device__ __forceinline__ unsigned cvt_pk_bf16(float lo, float hi) { unsigned r; asm volatile("s_nop 0\n\tv_cvt_pk_bf16_f32 %0, %1, %2\n\ts_nop 1" : "=v"(r) : "v"(lo), "v"(hi)); return r; }
; __device__ __forceinline__ float bflo(unsigned w) { return __uint_as_float(w << 16); }
; __device__ __forceinline__ float bfhi(unsigned w) { return __uint_as_float(w & 0xffff0000u); }
; __device__ __forceinline__ float gelu_tanh(float x) { const float y = 0.7978845608028654f * (x + 0.044715f * x * x * x); const float t = 1.f - 2.f * __builtin_amdgcn_rcpf(1.f + __expf(2.f * y)); return 0.5f * x * (1.f + t); }
;     __device__ __forceinline__ void operator()(f32x4 (&acc)[2][2][4][2], const Unit& u, int wr, int wc, int fr, int fq) const {
;     ...
;                         ya[m][bj] = *(const u32x4*)(ylf + idx); yb[m][bj] = *(const u32x4*)(ylb + idx); }
; #pragma unroll
;                 for (int m = 0; m < 4; ++m)
; #pragma unroll
;                     for (int bj = 0; bj < 2; ++bj) { const size_t idx = (size_t)(row0 + ai * 128 + m * 16) * 1024 + (u.pn - 8) * 256 + bj * 128 + c8;
;                         const u32x4 a = ya[m][bj], b = yb[m][bj];
;                         float yv[8] = {bflo(a.x) + bflo(b.x), bfhi(a.x) + bfhi(b.x), bflo(a.y) + bflo(b.y), bfhi(a.y) + bfhi(b.y), bflo(a.z) + bflo(b.z), bfhi(a.z) + bfhi(b.z), bflo(a.w) + bflo(b.w), bfhi(a.w) + bfhi(b.w)};
;                         float o[8];
; #pragma unroll
;                         for (int n = 0; n < 2; ++n)
; #pragma unroll
;                             for (int j = 0; j < 4; ++j) o[4 * n + j] = yv[4 * n + j] * gelu_tanh(acc[ai][bj][m][n][j]);
;                         u32x4 w; w.x = cvt_pk_bf16(o[0], o[1]); w.y = cvt_pk_bf16(o[2], o[3]); w.z = cvt_pk_bf16(o[4], o[5]); w.w = cvt_pk_bf16(o[6], o[7]);
;                         *(u32x4*)(ylf + idx) = w; }
	v_mul_f32_e32 v152, 0x3f4c422a, v152
	v_add_f32_e32 v152, v152, v152
	v_mul_f32_e32 v152, 0x3fb8aa3b, v152
	v_exp_f32_e32 v152, v152
	v_and_b32_e32 v165, 0xffff0000, v145
	v_add_f32_e32 v152, 1.0, v152
	v_rcp_f32_e32 v152, v152
	s_nop 0
	v_fma_f32 v162, v152, -2.0, 1.0
	v_mul_f32_e32 v152, 0.5, v25
	v_pk_add_f32 v[154:155], v[162:163], v[198:199]
	v_mov_b32_e32 v199, v175
	v_mul_f32_e32 v152, v152, v154
	v_mul_f32_e32 v158, v152, v155
	v_mul_f32_e32 v152, 0x3d372713, v26
	v_mul_f32_e32 v152, v26, v152
	v_fma_f32 v152, v26, v152, v26
	v_mul_f32_e32 v152, 0x3f4c422a, v152
	v_add_f32_e32 v152, v152, v152
	v_mul_f32_e32 v152, 0x3fb8aa3b, v152
	v_exp_f32_e32 v152, v152
	v_lshlrev_b32_e32 v163, 16, v145
	v_and_b32_e32 v145, 0xffff0000, v147
	v_add_f32_e32 v152, 1.0, v152
	v_rcp_f32_e32 v152, v152
	s_nop 0
	v_fma_f32 v156, v152, -2.0, 1.0
	v_mul_f32_e32 v152, 0.5, v26
	v_pk_add_f32 v[154:155], v[156:157], v[198:199]
	v_mov_b32_e32 v199, v159
	v_mul_f32_e32 v152, v152, v154
	v_mul_f32_e32 v157, v152, v155
	v_mul_f32_e32 v152, 0x3d372713, v27
	v_mul_f32_e32 v152, v27, v152
	v_fma_f32 v152, v27, v152, v27
	v_mul_f32_e32 v152, 0x3f4c422a, v152
	v_add_f32_e32 v152, v152, v152
	v_mul_f32_e32 v152, 0x3fb8aa3b, v152
	v_exp_f32_e32 v152, v152
	v_mul_f32_e32 v154, 0.5, v27
	v_lshlrev_b32_e32 v159, 16, v144
	v_add_f32_e32 v152, 1.0, v152
	v_rcp_f32_e32 v152, v152
	s_nop 0
	v_fma_f32 v152, v152, -2.0, 1.0
	v_pk_add_f32 v[152:153], v[152:153], v[198:199]
	v_lshlrev_b32_e32 v199, 16, v148
	v_mul_f32_e32 v152, v154, v152
	v_mul_f32_e32 v152, v152, v153
	v_cvt_pk_bf16_f32 v154, v166, v167
	v_cvt_pk_bf16_f32 v155, v168, v169
	v_cvt_pk_bf16_f32 v156, v164, v158
	v_cvt_pk_bf16_f32 v157, v157, v152
	v_lshl_add_u64 v[152:153], s[10:11], 0, v[160:161]
	v_lshl_add_u64 v[152:153], v[152:153], 0, s[66:67]
	v_lshl_add_u64 v[152:153], v[152:153], 0, v[184:185]
	global_store_dwordx4 v[152:153], v[154:157], off offset:-4096
	v_and_b32_e32 v161, 0xffff0000, v144
	v_and_b32_e32 v144, 0xffff0000, v148
	v_lshlrev_b32_e32 v157, 16, v146
	v_and_b32_e32 v155, 0xffff0000, v146
	v_mul_f32_e32 v146, 0x3d372713, v20
	v_mul_f32_e32 v146, v20, v146
	v_fma_f32 v146, v20, v146, v20
	v_mul_f32_e32 v146, 0x3f4c422a, v146
	v_add_f32_e32 v146, v146, v146
	v_mul_f32_e32 v146, 0x3fb8aa3b, v146
	v_exp_f32_e32 v146, v146
	v_lshlrev_b32_e32 v148, 16, v149
	v_and_b32_e32 v154, 0xffff0000, v149
	v_lshlrev_b32_e32 v149, 16, v147
	v_add_f32_e32 v146, 1.0, v146
	v_rcp_f32_e32 v146, v146
	v_mul_f32_e32 v156, 0.5, v20
	v_lshlrev_b32_e32 v166, 16, v150
	v_and_b32_e32 v150, 0xffff0000, v150
	v_fma_f32 v158, v146, -2.0, 1.0
	v_pk_add_f32 v[146:147], v[158:159], v[198:199]
	v_mov_b32_e32 v199, v144
	v_mul_f32_e32 v146, v156, v146
	v_mul_f32_e32 v158, v146, v147
	v_mul_f32_e32 v146, 0x3d372713, v21
	v_mul_f32_e32 v146, v21, v146
	v_fma_f32 v146, v21, v146, v21
	v_mul_f32_e32 v146, 0x3f4c422a, v146
	v_add_f32_e32 v146, v146, v146
	v_mul_f32_e32 v146, 0x3fb8aa3b, v146
	v_exp_f32_e32 v146, v146
	v_mul_f32_e32 v156, 0.5, v21
	v_lshlrev_b32_e32 v167, 16, v151
	v_and_b32_e32 v151, 0xffff0000, v151
	v_add_f32_e32 v146, 1.0, v146
	v_rcp_f32_e32 v146, v146
	s_nop 0
	v_fma_f32 v160, v146, -2.0, 1.0
	v_pk_add_f32 v[146:147], v[160:161], v[198:199]
	v_mov_b32_e32 v199, v148
	v_mul_f32_e32 v144, v156, v146
	v_mul_f32_e32 v159, v144, v147
	v_mul_f32_e32 v144, 0x3d372713, v22
	v_mul_f32_e32 v144, v22, v144
	v_fma_f32 v144, v22, v144, v22
	v_mul_f32_e32 v144, 0x3f4c422a, v144
	v_add_f32_e32 v144, v144, v144
	v_mul_f32_e32 v144, 0x3fb8aa3b, v144
	v_exp_f32_e32 v144, v144
	s_nop 0
	v_add_f32_e32 v144, 1.0, v144
	v_rcp_f32_e32 v144, v144
	s_nop 0
	v_fma_f32 v162, v144, -2.0, 1.0
	v_mul_f32_e32 v144, 0.5, v22
	v_pk_add_f32 v[146:147], v[162:163], v[198:199]
	v_mov_b32_e32 v199, v154
	v_mul_f32_e32 v144, v144, v146
	v_mul_f32_e32 v160, v144, v147
	v_mul_f32_e32 v144, 0x3d372713, v23
	v_mul_f32_e32 v144, v23, v144
	v_fma_f32 v144, v23, v144, v23
	v_mul_f32_e32 v144, 0x3f4c422a, v144
	v_add_f32_e32 v144, v144, v144
	v_mul_f32_e32 v144, 0x3fb8aa3b, v144
	v_exp_f32_e32 v144, v144
	s_nop 0
	v_add_f32_e32 v144, 1.0, v144
	v_rcp_f32_e32 v144, v144
	s_nop 0
	v_fma_f32 v164, v144, -2.0, 1.0
	v_mul_f32_e32 v144, 0.5, v23
	v_pk_add_f32 v[146:147], v[164:165], v[198:199]
	v_mov_b32_e32 v199, v166
	v_mul_f32_e32 v144, v144, v146
	v_mul_f32_e32 v161, v144, v147
	v_mul_f32_e32 v144, 0x3d372713, v16
	v_mul_f32_e32 v144, v16, v144
	v_fma_f32 v144, v16, v144, v16
	v_mul_f32_e32 v144, 0x3f4c422a, v144
	v_add_f32_e32 v144, v144, v144
	v_mul_f32_e32 v144, 0x3fb8aa3b, v144
	v_exp_f32_e32 v144, v144
	s_nop 0
	v_add_f32_e32 v144, 1.0, v144
	v_rcp_f32_e32 v144, v144
	s_nop 0
	v_fma_f32 v156, v144, -2.0, 1.0
	v_mul_f32_e32 v144, 0.5, v16
	v_pk_add_f32 v[146:147], v[156:157], v[198:199]
	v_mov_b32_e32 v199, v150
	v_mul_f32_e32 v144, v144, v146
	v_mul_f32_e32 v156, v144, v147
	v_mul_f32_e32 v144, 0x3d372713, v17
	v_mul_f32_e32 v144, v17, v144
	v_fma_f32 v144, v17, v144, v17
	v_mul_f32_e32 v144, 0x3f4c422a, v144
	v_add_f32_e32 v144, v144, v144
	v_mul_f32_e32 v144, 0x3fb8aa3b, v144
	v_exp_f32_e32 v144, v144
	v_and_b32_e32 v157, 0xffff0000, v137
	v_add_f32_e32 v144, 1.0, v144
	v_rcp_f32_e32 v144, v144
	s_nop 0
	v_fma_f32 v154, v144, -2.0, 1.0
	v_mul_f32_e32 v144, 0.5, v17
	v_pk_add_f32 v[146:147], v[154:155], v[198:199]
	v_mov_b32_e32 v199, v167
	v_mul_f32_e32 v144, v144, v146
	v_mul_f32_e32 v150, v144, v147
	v_mul_f32_e32 v144, 0x3d372713, v18
	v_mul_f32_e32 v144, v18, v144
	v_fma_f32 v144, v18, v144, v18
	v_mul_f32_e32 v144, 0x3f4c422a, v144
	v_add_f32_e32 v144, v144, v144
	v_mul_f32_e32 v144, 0x3fb8aa3b, v144
	v_exp_f32_e32 v144, v144
; __device__ __forceinline__ unsigned cvt_pk_bf16(float lo, float hi) { unsigned r; asm volatile("s_nop 0\n\tv_cvt_pk_bf16_f32 %0, %1, %2\n\ts_nop 1" : "=v"(r) : "v"(lo), "v"(hi)); return r; }
; __device__ __forceinline__ float bflo(unsigned w) { return __uint_as_float(w << 16); }
; __device__ __forceinline__ float bfhi(unsigned w) { return __uint_as_float(w & 0xffff0000u); }
; __device__ __forceinline__ float gelu_tanh(float x) { const float y = 0.7978845608028654f * (x + 0.044715f * x * x * x); const float t = 1.f - 2.f * __builtin_amdgcn_rcpf(1.f + __expf(2.f * y)); return 0.5f * x * (1.f + t); }
;     __device__ __forceinline__ void operator()(f32x4 (&acc)[2][2][4][2], const Unit& u, int wr, int wc, int fr, int fq) const {
;     ...
;                         ya[m][bj] = *(const u32x4*)(ylf + idx); yb[m][bj] = *(const u32x4*)(ylb + idx); }
; #pragma unroll
;                 for (int m = 0; m < 4; ++m)
; #pragma unroll
;                     for (int bj = 0; bj < 2; ++bj) { const size_t idx = (size_t)(row0 + ai * 128 + m * 16) * 1024 + (u.pn - 8) * 256 + bj * 128 + c8;
;                         const u32x4 a = ya[m][bj], b = yb[m][bj];
;                         float yv[8] = {bflo(a.x) + bflo(b.x), bfhi(a.x) + bfhi(b.x), bflo(a.y) + bflo(b.y), bfhi(a.y) + bfhi(b.y), bflo(a.z) + bflo(b.z), bfhi(a.z) + bfhi(b.z), bflo(a.w) + bflo(b.w), bfhi(a.w) + bfhi(b.w)};
;                         float o[8];
; #pragma unroll
;                         for (int n = 0; n < 2; ++n)
; #pragma unroll
;                             for (int j = 0; j < 4; ++j) o[4 * n + j] = yv[4 * n + j] * gelu_tanh(acc[ai][bj][m][n][j]);
;                         u32x4 w; w.x = cvt_pk_bf16(o[0], o[1]); w.y = cvt_pk_bf16(o[2], o[3]); w.z = cvt_pk_bf16(o[4], o[5]); w.w = cvt_pk_bf16(o[6], o[7]);
;                         *(u32x4*)(ylf + idx) = w; }
	v_lshlrev_b32_e32 v155, 16, v137
	v_and_b32_e32 v137, 0xffff0000, v139
	v_add_f32_e32 v144, 1.0, v144
	v_rcp_f32_e32 v144, v144
	s_nop 0
	v_fma_f32 v148, v144, -2.0, 1.0
	v_mul_f32_e32 v144, 0.5, v18
	v_pk_add_f32 v[146:147], v[148:149], v[198:199]
	v_mov_b32_e32 v199, v151
	v_mul_f32_e32 v144, v144, v146
	v_mul_f32_e32 v147, v144, v147
	v_mul_f32_e32 v144, 0x3d372713, v19
	v_mul_f32_e32 v144, v19, v144
	v_fma_f32 v144, v19, v144, v19
	v_mul_f32_e32 v144, 0x3f4c422a, v144
	v_add_f32_e32 v144, v144, v144
	v_mul_f32_e32 v144, 0x3fb8aa3b, v144
	v_exp_f32_e32 v144, v144
	v_mul_f32_e32 v146, 0.5, v19
	v_lshlrev_b32_e32 v149, 16, v138
	v_lshlrev_b32_e32 v151, 16, v136
	v_add_f32_e32 v144, 1.0, v144
	v_rcp_f32_e32 v144, v144
	s_nop 0
	v_fma_f32 v144, v144, -2.0, 1.0
	v_pk_add_f32 v[144:145], v[144:145], v[198:199]
	v_lshlrev_b32_e32 v199, 16, v140
	v_mul_f32_e32 v144, v146, v144
	v_mul_f32_e32 v148, v144, v145
	v_cvt_pk_bf16_f32 v144, v158, v159
	v_cvt_pk_bf16_f32 v145, v160, v161
	v_cvt_pk_bf16_f32 v146, v156, v150
	v_cvt_pk_bf16_f32 v147, v147, v148
	global_store_dwordx4 v[152:153], v[144:147], off offset:-3840
	v_and_b32_e32 v153, 0xffff0000, v136
	v_and_b32_e32 v136, 0xffff0000, v140
	v_and_b32_e32 v147, 0xffff0000, v138
	v_mul_f32_e32 v138, 0x3d372713, v12
	v_mul_f32_e32 v138, v12, v138
	v_fma_f32 v138, v12, v138, v12
	v_mul_f32_e32 v138, 0x3f4c422a, v138
	v_add_f32_e32 v138, v138, v138
	v_mul_f32_e32 v138, 0x3fb8aa3b, v138
	v_exp_f32_e32 v138, v138
	v_lshlrev_b32_e32 v140, 16, v141
	v_and_b32_e32 v146, 0xffff0000, v141
	v_lshlrev_b32_e32 v141, 16, v139
	v_add_f32_e32 v138, 1.0, v138
	v_rcp_f32_e32 v138, v138
	v_mul_f32_e32 v148, 0.5, v12
	v_lshlrev_b32_e32 v158, 16, v142
	v_and_b32_e32 v142, 0xffff0000, v142
	v_fma_f32 v150, v138, -2.0, 1.0
	v_pk_add_f32 v[138:139], v[150:151], v[198:199]
	v_mov_b32_e32 v199, v136
	v_mul_f32_e32 v138, v148, v138
	v_mul_f32_e32 v150, v138, v139
	v_mul_f32_e32 v138, 0x3d372713, v13
	v_mul_f32_e32 v138, v13, v138
	v_fma_f32 v138, v13, v138, v13
	v_mul_f32_e32 v138, 0x3f4c422a, v138
	v_add_f32_e32 v138, v138, v138
	v_mul_f32_e32 v138, 0x3fb8aa3b, v138
	v_exp_f32_e32 v138, v138
	v_mul_f32_e32 v148, 0.5, v13
	v_lshlrev_b32_e32 v159, 16, v143
	v_and_b32_e32 v143, 0xffff0000, v143
	v_add_f32_e32 v138, 1.0, v138
	v_rcp_f32_e32 v138, v138
	v_lshlrev_b64 v[144:145], 11, v[186:187]
	v_fma_f32 v152, v138, -2.0, 1.0
	v_pk_add_f32 v[138:139], v[152:153], v[198:199]
	v_mov_b32_e32 v199, v140
	v_mul_f32_e32 v136, v148, v138
	v_mul_f32_e32 v151, v136, v139
	v_mul_f32_e32 v136, 0x3d372713, v14
	v_mul_f32_e32 v136, v14, v136
	v_fma_f32 v136, v14, v136, v14
	v_mul_f32_e32 v136, 0x3f4c422a, v136
	v_add_f32_e32 v136, v136, v136
	v_mul_f32_e32 v136, 0x3fb8aa3b, v136
	v_exp_f32_e32 v136, v136
	s_nop 0
	v_add_f32_e32 v136, 1.0, v136
	v_rcp_f32_e32 v136, v136
	s_nop 0
	v_fma_f32 v154, v136, -2.0, 1.0
	v_mul_f32_e32 v136, 0.5, v14
	v_pk_add_f32 v[138:139], v[154:155], v[198:199]
	v_mov_b32_e32 v199, v146
	v_mul_f32_e32 v136, v136, v138
	v_mul_f32_e32 v152, v136, v139
	v_mul_f32_e32 v136, 0x3d372713, v15
	v_mul_f32_e32 v136, v15, v136
	v_fma_f32 v136, v15, v136, v15
	v_mul_f32_e32 v136, 0x3f4c422a, v136
	v_add_f32_e32 v136, v136, v136
	v_mul_f32_e32 v136, 0x3fb8aa3b, v136
	v_exp_f32_e32 v136, v136
	s_nop 0
	v_add_f32_e32 v136, 1.0, v136
	v_rcp_f32_e32 v136, v136
	s_nop 0
	v_fma_f32 v156, v136, -2.0, 1.0
	v_mul_f32_e32 v136, 0.5, v15
	v_pk_add_f32 v[138:139], v[156:157], v[198:199]
	v_mov_b32_e32 v199, v158
	v_mul_f32_e32 v136, v136, v138
	v_mul_f32_e32 v153, v136, v139
	v_mul_f32_e32 v136, 0x3d372713, v8
	v_mul_f32_e32 v136, v8, v136
	v_fma_f32 v136, v8, v136, v8
	v_mul_f32_e32 v136, 0x3f4c422a, v136
	v_add_f32_e32 v136, v136, v136
	v_mul_f32_e32 v136, 0x3fb8aa3b, v136
	v_exp_f32_e32 v136, v136
	s_nop 0
	v_add_f32_e32 v136, 1.0, v136
	v_rcp_f32_e32 v136, v136
	s_nop 0
	v_fma_f32 v148, v136, -2.0, 1.0
	v_mul_f32_e32 v136, 0.5, v8
	v_pk_add_f32 v[138:139], v[148:149], v[198:199]
	v_mov_b32_e32 v199, v142
	v_mul_f32_e32 v136, v136, v138
	v_mul_f32_e32 v148, v136, v139
	v_mul_f32_e32 v136, 0x3d372713, v9
	v_mul_f32_e32 v136, v9, v136
	v_fma_f32 v136, v9, v136, v9
	v_mul_f32_e32 v136, 0x3f4c422a, v136
	v_add_f32_e32 v136, v136, v136
	v_mul_f32_e32 v136, 0x3fb8aa3b, v136
	v_exp_f32_e32 v136, v136
	v_and_b32_e32 v149, 0xffff0000, v129
	v_add_f32_e32 v136, 1.0, v136
	v_rcp_f32_e32 v136, v136
	s_nop 0
	v_fma_f32 v146, v136, -2.0, 1.0
	v_mul_f32_e32 v136, 0.5, v9
	v_pk_add_f32 v[138:139], v[146:147], v[198:199]
	v_mov_b32_e32 v199, v159
	v_mul_f32_e32 v136, v136, v138
	v_mul_f32_e32 v142, v136, v139
	v_mul_f32_e32 v136, 0x3d372713, v10
	v_mul_f32_e32 v136, v10, v136
	v_fma_f32 v136, v10, v136, v10
	v_mul_f32_e32 v136, 0x3f4c422a, v136
	v_add_f32_e32 v136, v136, v136
	v_mul_f32_e32 v136, 0x3fb8aa3b, v136
	v_exp_f32_e32 v136, v136
	v_lshlrev_b32_e32 v147, 16, v129
	v_and_b32_e32 v129, 0xffff0000, v131
	v_add_f32_e32 v136, 1.0, v136
	v_rcp_f32_e32 v136, v136
	s_nop 0
	v_fma_f32 v140, v136, -2.0, 1.0
	v_mul_f32_e32 v136, 0.5, v10
	v_pk_add_f32 v[138:139], v[140:141], v[198:199]
	v_mov_b32_e32 v199, v143
	v_mul_f32_e32 v136, v136, v138
	v_mul_f32_e32 v141, v136, v139
	v_mul_f32_e32 v136, 0x3d372713, v11
	v_mul_f32_e32 v136, v11, v136
	v_fma_f32 v136, v11, v136, v11
	v_mul_f32_e32 v136, 0x3f4c422a, v136
	v_add_f32_e32 v136, v136, v136
; __device__ __forceinline__ unsigned cvt_pk_bf16(float lo, float hi) { unsigned r; asm volatile("s_nop 0\n\tv_cvt_pk_bf16_f32 %0, %1, %2\n\ts_nop 1" : "=v"(r) : "v"(lo), "v"(hi)); return r; }
; __device__ __forceinline__ float bflo(unsigned w) { return __uint_as_float(w << 16); }
; __device__ __forceinline__ float bfhi(unsigned w) { return __uint_as_float(w & 0xffff0000u); }
; __device__ __forceinline__ float gelu_tanh(float x) { const float y = 0.7978845608028654f * (x + 0.044715f * x * x * x); const float t = 1.f - 2.f * __builtin_amdgcn_rcpf(1.f + __expf(2.f * y)); return 0.5f * x * (1.f + t); }
;     __device__ __forceinline__ void operator()(f32x4 (&acc)[2][2][4][2], const Unit& u, int wr, int wc, int fr, int fq) const {
;     ...
;                         ya[m][bj] = *(const u32x4*)(ylf + idx); yb[m][bj] = *(const u32x4*)(ylb + idx); }
; #pragma unroll
;                 for (int m = 0; m < 4; ++m)
; #pragma unroll
;                     for (int bj = 0; bj < 2; ++bj) { const size_t idx = (size_t)(row0 + ai * 128 + m * 16) * 1024 + (u.pn - 8) * 256 + bj * 128 + c8;
;                         const u32x4 a = ya[m][bj], b = yb[m][bj];
;                         float yv[8] = {bflo(a.x) + bflo(b.x), bfhi(a.x) + bfhi(b.x), bflo(a.y) + bflo(b.y), bfhi(a.y) + bfhi(b.y), bflo(a.z) + bflo(b.z), bfhi(a.z) + bfhi(b.z), bflo(a.w) + bflo(b.w), bfhi(a.w) + bfhi(b.w)};
;                         float o[8];
; #pragma unroll
;                         for (int n = 0; n < 2; ++n)
; #pragma unroll
;                             for (int j = 0; j < 4; ++j) o[4 * n + j] = yv[4 * n + j] * gelu_tanh(acc[ai][bj][m][n][j]);
;                         u32x4 w; w.x = cvt_pk_bf16(o[0], o[1]); w.y = cvt_pk_bf16(o[2], o[3]); w.z = cvt_pk_bf16(o[4], o[5]); w.w = cvt_pk_bf16(o[6], o[7]);
;                         *(u32x4*)(ylf + idx) = w; }
	v_mul_f32_e32 v136, 0x3fb8aa3b, v136
	v_exp_f32_e32 v136, v136
	v_mul_f32_e32 v138, 0.5, v11
	v_lshlrev_b32_e32 v143, 16, v128
	v_add_f32_e32 v136, 1.0, v136
	v_rcp_f32_e32 v136, v136
	s_nop 0
	v_fma_f32 v136, v136, -2.0, 1.0
	v_pk_add_f32 v[136:137], v[136:137], v[198:199]
	v_lshlrev_b32_e32 v199, 16, v132
	v_mul_f32_e32 v136, v138, v136
	v_mul_f32_e32 v136, v136, v137
	v_cvt_pk_bf16_f32 v138, v150, v151
	v_cvt_pk_bf16_f32 v139, v152, v153
	v_cvt_pk_bf16_f32 v140, v148, v142
	v_cvt_pk_bf16_f32 v141, v141, v136
	v_lshl_add_u64 v[136:137], s[10:11], 0, v[144:145]
	v_lshl_add_u64 v[136:137], v[136:137], 0, s[66:67]
	v_lshl_add_u64 v[136:137], v[136:137], 0, v[184:185]
	global_store_dwordx4 v[136:137], v[138:141], off offset:-4096
	v_and_b32_e32 v145, 0xffff0000, v128
	v_and_b32_e32 v128, 0xffff0000, v132
	v_lshlrev_b32_e32 v141, 16, v130
	v_and_b32_e32 v139, 0xffff0000, v130
	v_mul_f32_e32 v130, 0x3d372713, v4
	v_mul_f32_e32 v130, v4, v130
	v_fma_f32 v130, v4, v130, v4
	v_mul_f32_e32 v130, 0x3f4c422a, v130
	v_add_f32_e32 v130, v130, v130
	v_mul_f32_e32 v130, 0x3fb8aa3b, v130
	v_exp_f32_e32 v130, v130
	v_lshlrev_b32_e32 v132, 16, v133
	v_and_b32_e32 v138, 0xffff0000, v133
	v_lshlrev_b32_e32 v133, 16, v131
	v_add_f32_e32 v130, 1.0, v130
	v_rcp_f32_e32 v130, v130
	v_mul_f32_e32 v140, 0.5, v4
	v_lshlrev_b32_e32 v150, 16, v134
	v_and_b32_e32 v134, 0xffff0000, v134
	v_fma_f32 v142, v130, -2.0, 1.0
	v_pk_add_f32 v[130:131], v[142:143], v[198:199]
	v_mov_b32_e32 v199, v128
	v_mul_f32_e32 v130, v140, v130
	v_mul_f32_e32 v142, v130, v131
	v_mul_f32_e32 v130, 0x3d372713, v5
	v_mul_f32_e32 v130, v5, v130
	v_fma_f32 v130, v5, v130, v5
	v_mul_f32_e32 v130, 0x3f4c422a, v130
	v_add_f32_e32 v130, v130, v130
	v_mul_f32_e32 v130, 0x3fb8aa3b, v130
	v_exp_f32_e32 v130, v130
	v_mul_f32_e32 v140, 0.5, v5
	v_lshlrev_b32_e32 v151, 16, v135
	v_and_b32_e32 v135, 0xffff0000, v135
	v_add_f32_e32 v130, 1.0, v130
	v_rcp_f32_e32 v130, v130
	s_nop 0
	v_fma_f32 v144, v130, -2.0, 1.0
	v_pk_add_f32 v[130:131], v[144:145], v[198:199]
	v_mov_b32_e32 v199, v132
	v_mul_f32_e32 v128, v140, v130
	v_mul_f32_e32 v143, v128, v131
	v_mul_f32_e32 v128, 0x3d372713, v6
	v_mul_f32_e32 v128, v6, v128
	v_fma_f32 v128, v6, v128, v6
	v_mul_f32_e32 v128, 0x3f4c422a, v128
	v_add_f32_e32 v128, v128, v128
	v_mul_f32_e32 v128, 0x3fb8aa3b, v128
	v_exp_f32_e32 v128, v128
	s_nop 0
	v_add_f32_e32 v128, 1.0, v128
	v_rcp_f32_e32 v128, v128
	s_nop 0
	v_fma_f32 v146, v128, -2.0, 1.0
	v_mul_f32_e32 v128, 0.5, v6
	v_pk_add_f32 v[130:131], v[146:147], v[198:199]
	v_mov_b32_e32 v199, v138
	v_mul_f32_e32 v128, v128, v130
	v_mul_f32_e32 v144, v128, v131
	v_mul_f32_e32 v128, 0x3d372713, v7
	v_mul_f32_e32 v128, v7, v128
	v_fma_f32 v128, v7, v128, v7
	v_mul_f32_e32 v128, 0x3f4c422a, v128
	v_add_f32_e32 v128, v128, v128
	v_mul_f32_e32 v128, 0x3fb8aa3b, v128
	v_exp_f32_e32 v128, v128
	s_nop 0
	v_add_f32_e32 v128, 1.0, v128
	v_rcp_f32_e32 v128, v128
	s_nop 0
	v_fma_f32 v148, v128, -2.0, 1.0
	v_mul_f32_e32 v128, 0.5, v7
	v_pk_add_f32 v[130:131], v[148:149], v[198:199]
	v_mov_b32_e32 v199, v150
	v_mul_f32_e32 v128, v128, v130
	v_mul_f32_e32 v145, v128, v131
	v_mul_f32_e32 v128, 0x3d372713, v0
	v_mul_f32_e32 v128, v0, v128
	v_fma_f32 v128, v0, v128, v0
	v_mul_f32_e32 v128, 0x3f4c422a, v128
	v_add_f32_e32 v128, v128, v128
	v_mul_f32_e32 v128, 0x3fb8aa3b, v128
	v_exp_f32_e32 v128, v128
	s_nop 0
	v_add_f32_e32 v128, 1.0, v128
	v_rcp_f32_e32 v128, v128
	s_nop 0
	v_fma_f32 v140, v128, -2.0, 1.0
	v_mul_f32_e32 v128, 0.5, v0
	v_pk_add_f32 v[130:131], v[140:141], v[198:199]
	v_mov_b32_e32 v199, v134
	v_mul_f32_e32 v128, v128, v130
	v_mul_f32_e32 v140, v128, v131
	v_mul_f32_e32 v128, 0x3d372713, v1
	v_mul_f32_e32 v128, v1, v128
	v_fma_f32 v128, v1, v128, v1
	v_mul_f32_e32 v128, 0x3f4c422a, v128
	v_add_f32_e32 v128, v128, v128
	v_mul_f32_e32 v128, 0x3fb8aa3b, v128
	v_exp_f32_e32 v128, v128
	s_nop 0
	v_add_f32_e32 v128, 1.0, v128
	v_rcp_f32_e32 v128, v128
	s_nop 0
	v_fma_f32 v138, v128, -2.0, 1.0
	v_mul_f32_e32 v128, 0.5, v1
	v_pk_add_f32 v[130:131], v[138:139], v[198:199]
	v_mov_b32_e32 v199, v151
	v_mul_f32_e32 v128, v128, v130
	v_mul_f32_e32 v134, v128, v131
	v_mul_f32_e32 v128, 0x3d372713, v2
	v_mul_f32_e32 v128, v2, v128
	v_fma_f32 v128, v2, v128, v2
	v_mul_f32_e32 v128, 0x3f4c422a, v128
	v_add_f32_e32 v128, v128, v128
	v_mul_f32_e32 v128, 0x3fb8aa3b, v128
	v_exp_f32_e32 v128, v128
	s_nop 0
	v_add_f32_e32 v128, 1.0, v128
	v_rcp_f32_e32 v128, v128
	s_nop 0
	v_fma_f32 v132, v128, -2.0, 1.0
	v_mul_f32_e32 v128, 0.5, v2
	v_pk_add_f32 v[130:131], v[132:133], v[198:199]
	v_mov_b32_e32 v199, v135
	v_mul_f32_e32 v128, v128, v130
	v_mul_f32_e32 v131, v128, v131
	v_mul_f32_e32 v128, 0x3d372713, v3
	v_mul_f32_e32 v128, v3, v128
	v_fma_f32 v128, v3, v128, v3
	v_mul_f32_e32 v128, 0x3f4c422a, v128
	v_add_f32_e32 v128, v128, v128
	v_mul_f32_e32 v128, 0x3fb8aa3b, v128
	v_exp_f32_e32 v128, v128
	v_mul_f32_e32 v130, 0.5, v3
	v_add_f32_e32 v128, 1.0, v128
	v_rcp_f32_e32 v128, v128
	s_nop 0
	v_fma_f32 v128, v128, -2.0, 1.0
	v_pk_add_f32 v[128:129], v[128:129], v[198:199]
	s_nop 0
	v_mul_f32_e32 v128, v130, v128
	v_mul_f32_e32 v132, v128, v129
	v_cvt_pk_bf16_f32 v128, v142, v143
	v_cvt_pk_bf16_f32 v129, v144, v145
	v_cvt_pk_bf16_f32 v130, v140, v134
	v_cvt_pk_bf16_f32 v131, v131, v132
	s_nop 1
	global_store_dwordx4 v[136:137], v[128:131], off offset:-3840

; #define LDS_FENCE() asm volatile("s_waitcnt lgkmcnt(0)" ::: "memory")
;     ...
;         const bf16_t* XT = xT + ((size_t)chunk * 2048 + head * 64 + pb * 32 + r) * 128;
;         asm volatile("s_waitcnt vmcnt(0)" ::: "memory"); __builtin_amdgcn_s_barrier(); asm volatile("" ::: "memory");
;         if (s + 1 < 18) { const int s1 = s + 1; const bool cx1 = s1 < 2; const int c1 = cx1 ? (DIR ? 1 - s1 : s1) : (DIR ? 17 - s1 : s1 - 2);
;             const size_t rn = (size_t)(cx1 ? bl * 2 + c1 : (CGR / 128) + bl * 16 + c1) * 128;
;             nd0 = dt[(rn + lane) * 64 + DIR * 32 + head]; nd1 = dt[(rn + 64 + lane) * 64 + DIR * 32 + head]; }
;         float c0, c1, ctot;
;         if (DIR == 0) { const float p0 = wave_prefix(d0 * a_neg, lane); const float tot0 = __int_as_float(__builtin_amdgcn_readlane(__float_as_int(p0), 63)); const float p1 = wave_prefix(d1 * a_neg, lane) + tot0; c0 = p0; c1 = p1; ctot = __int_as_float(__builtin_amdgcn_readlane(__float_as_int(p1), 63)); }
;         else { const float s1 = wave_suffix(d1 * a_neg, lane); const float tot1 = __int_as_float(__builtin_amdgcn_readlane(__float_as_int(s1), 0)); const float s0 = wave_suffix(d0 * a_neg, lane) + tot1; c0 = s0; c1 = s1; ctot = __int_as_float(__builtin_amdgcn_readlane(__float_as_int(s0), 0)); }
;         cumL[lane] = c0; cumL[lane + 64] = c1; dtL[lane] = d0; dtL[lane + 64] = d1;
;         sclL[lane] = d0 * __expf(ctot - c0); sclL[lane + 64] = d1 * __expf(ctot - c1);
;         LDS_FENCE();
;         float mref[4];
;         if (DIR == 0) { mref[0] = 0.f; mref[1] = cumL[31]; mref[2] = cumL[63]; mref[3] = cumL[95]; }
;         else { mref[0] = cumL[32]; mref[1] = cumL[64]; mref[2] = cumL[96]; mref[3] = 0.f; }
; #pragma unroll
;         for (int ib = 0; ib < 4; ++ib) mref[ib] = __int_as_float(__builtin_amdgcn_readfirstlane(__float_as_int(mref[ib])));
;         if (!is_ctx) {
; #pragma unroll
;             for (int ib = 0; ib < 4; ++ib) { wL[ib * 128 + lane] = d0 * __expf(mref[ib] - c0); wL[ib * 128 + 64 + lane] = d1 * __expf(mref[ib] - c1); }
.LBB0_427:
	v_mul_f32_e64 v66, v64, -v141
	ds_bpermute_b32 v67, v111, v66
	s_cmp_lt_u32 s52, 2
	s_cselect_b32 s33, 1, 17
	s_cselect_b32 s53, s39, s49
	s_sub_i32 s33, s33, s52
	s_waitcnt lgkmcnt(0)
	v_fma_f32 v67, v64, -v141, v67
	v_cndmask_b32_e64 v66, v67, v66, s[2:3]
	ds_bpermute_b32 v67, v117, v66
	s_add_i32 s54, s33, s53
	v_mov_b32_e32 v70, s76
	s_ashr_i32 s55, s54, 31
	s_lshl_b64 s[54:55], s[54:55], 19
	s_waitcnt lgkmcnt(0)
	v_add_f32_e32 v67, v66, v67
	v_cndmask_b32_e64 v66, v66, v67, s[4:5]
	ds_bpermute_b32 v67, v158, v66
	s_cmp_gt_u32 s52, 1
	v_lshl_add_u64 v[134:135], v[94:95], 0, s[54:55]
	v_lshlrev_b32_e32 v118, 1, v114
	v_mov_b32_e32 v119, 0
	v_lshl_add_u64 v[118:119], v[134:135], 0, v[118:119]
	global_load_dwordx4 v[176:179], v[118:119], off
	global_load_dwordx4 v[180:183], v[118:119], off offset:32
	global_load_dwordx4 v[184:187], v[118:119], off offset:64
	global_load_dwordx4 v[200:203], v[118:119], off offset:96
	global_load_dwordx4 v[204:207], v[118:119], off offset:128
	global_load_dwordx4 v[188:191], v[118:119], off offset:160
	global_load_dwordx4 v[228:231], v[118:119], off offset:192
	global_load_dwordx4 v[232:235], v[118:119], off offset:224
	s_waitcnt lgkmcnt(0)
	v_add_f32_e32 v67, v66, v67
	v_cndmask_b32_e64 v66, v66, v67, s[6:7]
	ds_bpermute_b32 v67, v159, v66
	s_waitcnt lgkmcnt(0)
	v_add_f32_e32 v67, v66, v67
	v_cndmask_b32_e64 v66, v66, v67, s[8:9]
	ds_bpermute_b32 v67, v160, v66
	s_waitcnt lgkmcnt(0)
	v_add_f32_e32 v67, v66, v67
	v_cndmask_b32_e64 v66, v66, v67, s[10:11]
	ds_bpermute_b32 v67, v161, v66
	s_waitcnt lgkmcnt(0)
	v_add_f32_e32 v67, v66, v67
	v_cndmask_b32_e64 v66, v66, v67, s[12:13]
	v_mul_f32_e64 v67, v65, -v141
	ds_bpermute_b32 v68, v111, v67
	v_readlane_b32 s53, v66, 0
	s_waitcnt lgkmcnt(0)
	v_fma_f32 v68, v65, -v141, v68
	v_cndmask_b32_e64 v67, v68, v67, s[2:3]
	ds_bpermute_b32 v68, v117, v67
	s_waitcnt lgkmcnt(0)
	v_add_f32_e32 v68, v67, v68
	v_cndmask_b32_e64 v67, v67, v68, s[4:5]
	ds_bpermute_b32 v68, v158, v67
	s_waitcnt lgkmcnt(0)
	v_add_f32_e32 v68, v67, v68
	v_cndmask_b32_e64 v67, v67, v68, s[6:7]
	ds_bpermute_b32 v68, v159, v67
	s_waitcnt lgkmcnt(0)
	v_add_f32_e32 v68, v67, v68
	v_cndmask_b32_e64 v67, v67, v68, s[8:9]
	ds_bpermute_b32 v68, v160, v67
	s_waitcnt lgkmcnt(0)
	v_add_f32_e32 v68, v67, v68
	v_cndmask_b32_e64 v67, v67, v68, s[10:11]
	ds_bpermute_b32 v68, v161, v67
	s_waitcnt lgkmcnt(0)
	v_add_f32_e32 v68, v67, v68
	v_cndmask_b32_e64 v67, v67, v68, s[12:13]
	v_add_f32_e32 v67, s53, v67
	ds_write2st64_b32 v162, v67, v66 offset1:1
	ds_write2st64_b32 v162, v65, v64 offset0:2 offset1:3
	v_readlane_b32 s53, v67, 0
	s_nop 1
	v_sub_f32_e32 v68, s53, v67
	v_sub_f32_e32 v69, s53, v66
	v_mul_f32_e32 v68, 0x3fb8aa3b, v68
	v_mul_f32_e32 v69, 0x3fb8aa3b, v69
	v_exp_f32_e32 v68, v68
	v_exp_f32_e32 v69, v69
	v_mul_f32_e32 v68, v65, v68
	v_mul_f32_e32 v69, v64, v69
	ds_write2st64_b32 v162, v68, v69 offset0:4 offset1:5
	s_waitcnt lgkmcnt(0)
	ds_read2_b32 v[68:69], v70 offset0:32 offset1:64
	ds_read_b32 v70, v70 offset:384
	s_waitcnt lgkmcnt(0)
	v_readfirstlane_b32 s54, v68
	v_readfirstlane_b32 s55, v69
	s_waitcnt lgkmcnt(0)
	v_readfirstlane_b32 s96, v70
	s_cbranch_scc0 .Lssd_a_ctx
	v_sub_f32_e32 v68, s54, v67
	v_sub_f32_e32 v69, s54, v66
	v_mul_f32_e32 v68, 0x3fb8aa3b, v68
	v_mul_f32_e32 v69, 0x3fb8aa3b, v69
	v_exp_f32_e32 v68, v68
	v_exp_f32_e32 v69, v69
	s_andn2_b64 vcc, exec, s[30:31]
	s_mov_b32 s62, s40
	v_mul_f32_e32 v68, v65, v68
	v_mul_f32_e32 v69, v64, v69
	ds_write2st64_b32 v162, v68, v69 offset0:6 offset1:7
	v_sub_f32_e32 v68, s55, v67
	v_sub_f32_e32 v69, s55, v66
	v_mul_f32_e32 v68, 0x3fb8aa3b, v68
	v_mul_f32_e32 v69, 0x3fb8aa3b, v69
	v_exp_f32_e32 v68, v68
	v_exp_f32_e32 v69, v69
	v_mov_b32_e32 v80, v213
	s_mov_b32 s63, s93
	v_mul_f32_e32 v68, v65, v68
	v_mul_f32_e32 v69, v64, v69
	ds_write2st64_b32 v162, v68, v69 offset0:8 offset1:9
	v_sub_f32_e32 v68, s96, v67
	v_sub_f32_e32 v69, s96, v66
	v_mul_f32_e32 v68, 0x3fb8aa3b, v68
	v_mul_f32_e32 v69, 0x3fb8aa3b, v69
	v_mul_f32_e64 v67, -v67, s71
	v_mul_f32_e64 v66, -v66, s71
	v_exp_f32_e32 v68, v68
	v_exp_f32_e32 v69, v69
	v_exp_f32_e32 v67, v67
	v_exp_f32_e32 v66, v66
	v_mul_f32_e32 v68, v65, v68
	v_mul_f32_e32 v69, v64, v69
	v_mul_f32_e32 v65, v65, v67
	v_mul_f32_e32 v64, v64, v66
	ds_write2st64_b32 v162, v68, v69 offset0:10 offset1:11
	ds_write2st64_b32 v162, v65, v64 offset0:12 offset1:13
	s_waitcnt lgkmcnt(0)
	s_cbranch_vccnz .LBB0_430
;     ...
;             for (int bidx = wid; bidx < 10; bidx += 8) {
;                 int bi2 = bidx >= 6 ? 3 : bidx >= 3 ? 2 : bidx >= 1 ? 1 : 0; int bj2 = bidx - bi2 * (bi2 + 1) / 2;
;                 const int ibk = DIR ? 3 - bi2 : bi2, jbk = DIR ? 3 - bj2 : bj2;
;                 const unsigned io2 = rowoff + (unsigned)ibk * 8192u, jo2 = rowoff + (unsigned)jbk * 8192u;
;                 f32x16 S;
; #pragma unroll
;                 for (int e = 0; e < 16; ++e) S[e] = 0.f;
; #pragma unroll
;                 for (int s8 = 0; s8 < 8; ++s8) S = mfma32(t_ld8(TB, jo2, rx4, 2 * s8 + h), t_ld8(TA, io2, rx4, 2 * s8 + h), S);
;                 asm volatile("s_nop 15\n\ts_nop 3" : "+v"(S));
;                 LAS u32x4* dstp = (LAS u32x4*)(CBL + bidx * 2048 + lane * 32);
;                 u32x4 w0, w1; w0.x = cvt_pk_bf16(S[0], S[1]); w0.y = cvt_pk_bf16(S[2], S[3]); w0.z = cvt_pk_bf16(S[4], S[5]); w0.w = cvt_pk_bf16(S[6], S[7]);
;                 w1.x = cvt_pk_bf16(S[8], S[9]); w1.y = cvt_pk_bf16(S[10], S[11]); w1.z = cvt_pk_bf16(S[12], S[13]); w1.w = cvt_pk_bf16(S[14], S[15]);
;                 dstp[0] = w0; dstp[1] = w1;
;             }
;             LDS_FENCE();
;             asm volatile("" ::: "memory"); __builtin_amdgcn_s_barrier(); asm volatile("" ::: "memory");
;     ...
;             for (int ib = 0; ib < 4; ++ib) {
;                 const unsigned ioff = rowoff + (unsigned)ib * 8192u;
;                 f32x16 Ya;
; #pragma unroll
;                 for (int e = 0; e < 16; ++e) Ya[e] = 0.f;
; #pragma unroll
;                 for (int nb = 0; nb < 4; ++nb)
; #pragma unroll
;                     for (int sp = 0; sp < 2; ++sp) Ya = mfma32(pack_acc(H[nb], sp), t_ld44(TA, ioff, rx4, 4 * nb + 2 * sp, h), Ya);
;                 const float ci = cumL[32 * ib + r];
;                 const float mi = (ib == 0) ? mref[0] : (ib == 1) ? mref[1] : (ib == 2) ? mref[2] : mref[3];
;                 { const float em = __expf(mi);
; #pragma unroll
;                   for (int e = 0; e < 16; ++e) Ya[e] *= em; }
; #pragma unroll 3
;                 for (int jb = (DIR ? ib + 1 : 0); jb < (DIR ? 4 : ib); ++jb) {
;                     f32x16 S;
;                     { const int bi2 = DIR ? 3 - ib : ib, bj2 = DIR ? 3 - jb : jb; const LAS u32x4* srcp = (const LAS u32x4*)(CBL + (bi2 * (bi2 + 1) / 2 + bj2) * 2048 + lane * 32);
;                       const u32x4 w0 = srcp[0], w1 = srcp[1];
.LBB0_429:
	s_cmp_gt_i32 s63, 0
	s_cselect_b64 s[84:85], -1, 0
	s_nop 5
	v_cndmask_b32_e64 v64, 0, 1, s[84:85]
	s_cmp_lt_i32 s63, 3
	v_readfirstlane_b32 s66, v64
	s_cselect_b32 s66, s66, 2
	s_cmp_lt_i32 s63, 6
	s_cselect_b32 s66, s66, 3
	s_add_i32 s69, s66, 1
	s_mul_i32 s69, s69, s66
	s_lshr_b32 s69, s69, 1
	s_lshl_b32 s66, s66, 13
	v_mov_b32_e32 v64, 0x6000
	v_bitop3_b32 v64, s66, v64, v103 bitop3:0x36
	s_add_i32 s66, s62, s69
	v_lshl_add_u32 v81, s66, 13, v163
	v_add_u32_e32 v82, 0, v64
	v_add_u32_e32 v64, v81, v115
	ds_read_b128 v[64:67], v64 offset:57344
	v_add_u32_e32 v68, v82, v115
	ds_read_b128 v[68:71], v68
	v_add_u32_e32 v83, v81, v166
	ds_read_b128 v[136:139], v83 offset:57344
	s_waitcnt lgkmcnt(0)
	v_mfma_f32_32x32x16_bf16 v[64:79], v[64:67], v[68:71], 0
	v_add_u32_e32 v83, v82, v166
	ds_read_b128 v[144:147], v83
	v_add_u32_e32 v83, v81, v167
	s_add_i32 s66, s63, 8
	s_add_i32 s62, s62, -8
	s_cmp_gt_i32 s63, 1
	s_mov_b32 s63, s66
	s_waitcnt lgkmcnt(0)
	v_mfma_f32_32x32x16_bf16 v[64:79], v[136:139], v[144:147], v[64:79]
	ds_read_b128 v[136:139], v83 offset:57344
	v_add_u32_e32 v83, v82, v167
	ds_read_b128 v[144:147], v83
	v_add_u32_e32 v83, v81, v168
	s_waitcnt lgkmcnt(0)
	v_mfma_f32_32x32x16_bf16 v[64:79], v[136:139], v[144:147], v[64:79]
	ds_read_b128 v[136:139], v83 offset:57344
	v_add_u32_e32 v83, v82, v168
	ds_read_b128 v[144:147], v83
	v_add_u32_e32 v83, v81, v169
	s_waitcnt lgkmcnt(0)
	v_mfma_f32_32x32x16_bf16 v[64:79], v[136:139], v[144:147], v[64:79]
	ds_read_b128 v[136:139], v83 offset:57344
	v_add_u32_e32 v83, v82, v169
	ds_read_b128 v[144:147], v83
	v_add_u32_e32 v83, v81, v170
	s_waitcnt lgkmcnt(0)
	v_mfma_f32_32x32x16_bf16 v[64:79], v[136:139], v[144:147], v[64:79]
	ds_read_b128 v[136:139], v83 offset:57344
	v_add_u32_e32 v83, v82, v170
	ds_read_b128 v[144:147], v83
	v_add_u32_e32 v83, v81, v171
	v_add_u32_e32 v81, v81, v172
	s_waitcnt lgkmcnt(0)
	v_mfma_f32_32x32x16_bf16 v[64:79], v[136:139], v[144:147], v[64:79]
	ds_read_b128 v[136:139], v83 offset:57344
	v_add_u32_e32 v83, v82, v171
	ds_read_b128 v[144:147], v83
	s_waitcnt lgkmcnt(0)
	v_mfma_f32_32x32x16_bf16 v[64:79], v[136:139], v[144:147], v[64:79]
	ds_read_b128 v[136:139], v81 offset:57344
	v_add_u32_e32 v81, v82, v172
	ds_read_b128 v[144:147], v81
	v_add_u32_e32 v81, -16, v80
	s_waitcnt lgkmcnt(0)
	v_mfma_f32_32x32x16_bf16 v[64:79], v[136:139], v[144:147], v[64:79]
	s_nop 15
	s_nop 3
	s_nop 0
	s_nop 0
	v_cvt_pk_bf16_f32 v64, v64, v65
	s_nop 0
	v_cvt_pk_bf16_f32 v65, v66, v67
	s_nop 0
	v_cvt_pk_bf16_f32 v66, v68, v69
	s_nop 0
	v_cvt_pk_bf16_f32 v67, v70, v71
	s_nop 0
	v_cvt_pk_bf16_f32 v68, v72, v73
	s_nop 0
	v_cvt_pk_bf16_f32 v69, v74, v75
	s_nop 0
	v_cvt_pk_bf16_f32 v70, v76, v77
	s_nop 0
	v_cvt_pk_bf16_f32 v71, v78, v79
	s_nop 10
	ds_write_b128 v81, v[64:67]
	ds_write_b128 v80, v[68:71]
	v_add_u32_e32 v80, 0x4000, v80
	s_cbranch_scc0 .LBB0_429
.LBB0_430:
	s_waitcnt lgkmcnt(0)
	s_add_i32 s62, s33, s59
	s_barrier
	s_ashr_i32 s63, s62, 31
	s_lshl_b64 s[62:63], s[62:63], 19
	v_lshlrev_b32_e32 v192, 1, v116
	v_lshl_add_u64 v[136:137], v[92:93], 0, s[62:63]
	v_lshl_add_u64 v[138:139], v[134:135], 0, v[192:193]
	s_mov_b32 s97, 0
	s_mov_b32 s83, 3
	s_mov_b32 s84, 32
	s_mov_b32 s85, -1
	s_mov_b32 s33, -6
	s_mov_b32 s86, 12
	v_mov_b32_e32 v85, v214
	s_waitcnt vmcnt(0)
	v_permlane32_swap_b32_e32 v176, v178
	v_permlane32_swap_b32_e32 v177, v179
	v_permlane32_swap_b32_e32 v180, v182
	v_permlane32_swap_b32_e32 v181, v183
	v_permlane32_swap_b32_e32 v184, v186
	v_permlane32_swap_b32_e32 v185, v187
	v_permlane32_swap_b32_e32 v200, v202
	v_permlane32_swap_b32_e32 v201, v203
	v_permlane32_swap_b32_e32 v204, v206
	v_permlane32_swap_b32_e32 v205, v207
	v_permlane32_swap_b32_e32 v188, v190
	v_permlane32_swap_b32_e32 v189, v191
	v_permlane32_swap_b32_e32 v228, v230
	v_permlane32_swap_b32_e32 v229, v231
	v_permlane32_swap_b32_e32 v232, v234
	v_permlane32_swap_b32_e32 v233, v235
	s_nop 1
	s_branch .LBB0_432
.LBB0_431:
	s_waitcnt lgkmcnt(0)
	v_sub_f32_e32 v80, v89, v80
	v_mul_f32_e32 v80, 0x3fb8aa3b, v80
	v_add_u32_e32 v91, s62, v208
	v_exp_f32_e32 v140, v80
	ds_read_b128 v[80:83], v91
	ds_read_b128 v[144:147], v91 offset:16
	v_or_b32_e32 v226, s69, v116
	v_lshl_add_u32 v227, v226, 2, s76
	s_lshl_b32 s66, s69, 1
	s_waitcnt lgkmcnt(0)
	v_lshlrev_b32_e32 v91, 16, v80
	v_and_b32_e32 v152, 0xffff0000, v80
	v_lshlrev_b32_e32 v153, 16, v81
	v_and_b32_e32 v155, 0xffff0000, v81
	v_lshlrev_b32_e32 v156, 16, v82
	v_and_b32_e32 v157, 0xffff0000, v82
	v_lshlrev_b32_e32 v192, 16, v83
	v_and_b32_e32 v194, 0xffff0000, v83
	ds_read_b128 v[148:151], v227 offset:512
	ds_read_b128 v[216:219], v227
	ds_read_b128 v[80:83], v227 offset:32
	s_waitcnt lgkmcnt(3)
	v_lshlrev_b32_e32 v196, 16, v145
	v_and_b32_e32 v197, 0xffff0000, v145
	v_lshlrev_b32_e32 v225, 16, v147
	s_waitcnt lgkmcnt(0)
	v_sub_f32_e32 v145, v89, v216
	v_mul_f32_e32 v145, 0x3fb8aa3b, v145
	v_exp_f32_e32 v145, v145
	v_and_b32_e32 v154, 0xffff0000, v147
	s_waitcnt lgkmcnt(0)
	v_sub_f32_e32 v80, v89, v80
	v_mul_f32_e32 v80, 0x3fb8aa3b, v80
	v_mul_f32_e32 v91, v145, v91
	v_sub_f32_e32 v145, v89, v217
	v_mul_f32_e32 v145, 0x3fb8aa3b, v145
	v_exp_f32_e32 v145, v145
	v_mul_f32_e32 v91, v148, v91
	v_cndmask_b32_e64 v147, v91, 0, s[14:15]
	v_or_b32_e32 v91, 1, v226
	v_mul_f32_e32 v145, v145, v152
	v_mul_f32_e32 v145, v149, v145
	v_cmp_ge_u32_e32 vcc, v91, v87
	v_or_b32_e32 v91, 2, v226
	v_sub_f32_e32 v81, v89, v81
	v_cndmask_b32_e32 v148, 0, v145, vcc
	v_sub_f32_e32 v145, v89, v218
	v_mul_f32_e32 v145, 0x3fb8aa3b, v145
	v_exp_f32_e32 v145, v145
	v_cmp_ge_u32_e32 vcc, v91, v87
	v_sub_f32_e32 v82, v89, v82
	v_sub_f32_e32 v83, v89, v83
	v_mul_f32_e32 v145, v145, v153
	v_mul_f32_e32 v145, v150, v145
	v_cndmask_b32_e32 v149, 0, v145, vcc
	v_sub_f32_e32 v145, v89, v219
	v_mul_f32_e32 v145, 0x3fb8aa3b, v145
	v_exp_f32_e32 v145, v145
	ds_read_b128 v[216:219], v227 offset:544
	v_exp_f32_e32 v80, v80
	v_mul_f32_e32 v81, 0x3fb8aa3b, v81
	v_mul_f32_e32 v82, 0x3fb8aa3b, v82
	v_mul_f32_e32 v83, 0x3fb8aa3b, v83
	v_exp_f32_e32 v81, v81
	v_exp_f32_e32 v82, v82
	v_exp_f32_e32 v83, v83
	v_or_b32_e32 v91, 3, v226
	v_mul_f32_e32 v145, v145, v155
	v_mul_f32_e32 v145, v151, v145
	v_cmp_ge_u32_e32 vcc, v91, v87
	v_or_b32_e32 v91, 8, v226
	v_mul_f32_e32 v80, v80, v156
	v_cndmask_b32_e32 v150, 0, v145, vcc
	s_waitcnt lgkmcnt(0)
; #define LAS __attribute__((address_space(3)))
; __device__ __forceinline__ float bflo(unsigned w) { return __uint_as_float(w << 16); }
; __device__ __forceinline__ float bfhi(unsigned w) { return __uint_as_float(w & 0xffff0000u); }
; __device__ __forceinline__ f32x16 mfma32(bf16x8 a, bf16x8 b, f32x16 c) { return __builtin_amdgcn_mfma_f32_32x32x16_bf16(a, b, c, 0, 0, 0); }
;     ...
;                 {
;                     const int i = 32 * ib + r; const int jb = ib;
;                     f32x16 S;
;                     { const int bi2 = DIR ? 3 - ib : ib, bj2 = DIR ? 3 - jb : jb; const LAS u32x4* srcp = (const LAS u32x4*)(CBL + (bi2 * (bi2 + 1) / 2 + bj2) * 2048 + lane * 32);
;                       const u32x4 w0 = srcp[0], w1 = srcp[1];
;                       S[0] = bflo(w0.x); S[1] = bfhi(w0.x); S[2] = bflo(w0.y); S[3] = bfhi(w0.y); S[4] = bflo(w0.z); S[5] = bfhi(w0.z); S[6] = bflo(w0.w); S[7] = bfhi(w0.w);
;                       S[8] = bflo(w1.x); S[9] = bfhi(w1.x); S[10] = bflo(w1.y); S[11] = bfhi(w1.y); S[12] = bflo(w1.z); S[13] = bfhi(w1.z); S[14] = bflo(w1.w); S[15] = bfhi(w1.w); }
; #pragma unroll
;                     for (int q = 0; q < 4; ++q) {
;                         const int j0 = 32 * jb + 8 * q + 4 * h;
;                         const f32x4 cj = *(const LAS f32x4*)(cumL + j0), dj = *(const LAS f32x4*)(dtL + j0);
; #pragma unroll
;                         for (int k = 0; k < 4; ++k) {
;                             const int j = j0 + k; const bool valid = DIR ? (j >= i) : (j <= i);
;                             float v = S[4 * q + k] * __expf(ci - cj[k]) * dj[k];
;                             v = valid ? v : 0.f;
;                             if (DIR == 0 && j == i) v += Dh;
;                             S[4 * q + k] = v;
;                         }
;                     }
;                     Ya = mfma32(ld44(XT + 32 * jb + 4 * h), pack_acc(S, 0), Ya); Ya = mfma32(ld44(XT + 32 * jb + 16 + 4 * h), pack_acc(S, 1), Ya);
	v_mul_f32_e32 v80, v216, v80
	v_cmp_ge_u32_e32 vcc, v91, v87
	v_or_b32_e32 v91, 9, v226
	v_mul_f32_e32 v81, v81, v157
	v_mul_f32_e32 v82, v82, v192
	v_mul_f32_e32 v83, v83, v194
	v_cndmask_b32_e32 v80, 0, v80, vcc
	v_mul_f32_e32 v81, v217, v81
	v_cmp_ge_u32_e32 vcc, v91, v87
	v_or_b32_e32 v91, 10, v226
	v_mul_f32_e32 v82, v218, v82
	v_mul_f32_e32 v83, v219, v83
	ds_read_b128 v[216:219], v227 offset:64
	ds_read_b128 v[220:223], v227 offset:576
	v_cndmask_b32_e32 v81, 0, v81, vcc
	v_cmp_ge_u32_e32 vcc, v91, v87
	v_lshlrev_b32_e32 v195, 16, v144
	v_and_b32_e32 v144, 0xffff0000, v144
	v_cndmask_b32_e32 v192, 0, v82, vcc
	v_or_b32_e32 v82, 11, v226
	v_cmp_ge_u32_e32 vcc, v82, v87
	v_or_b32_e32 v82, 16, v226
	v_lshlrev_b32_e32 v215, 16, v146
	v_cndmask_b32_e32 v194, 0, v83, vcc
	s_waitcnt lgkmcnt(0)
	v_sub_f32_e32 v83, v89, v216
	v_mul_f32_e32 v83, 0x3fb8aa3b, v83
	v_exp_f32_e32 v83, v83
	v_cmp_ge_u32_e32 vcc, v82, v87
	v_or_b32_e32 v82, 17, v226
	v_and_b32_e32 v224, 0xffff0000, v146
	v_mul_f32_e32 v83, v83, v195
	s_waitcnt lgkmcnt(0)
	v_mul_f32_e32 v83, v220, v83
	v_cndmask_b32_e32 v91, 0, v83, vcc
	v_sub_f32_e32 v83, v89, v217
	v_mul_f32_e32 v83, 0x3fb8aa3b, v83
	v_exp_f32_e32 v83, v83
	v_cmp_ge_u32_e32 vcc, v82, v87
	v_or_b32_e32 v82, 18, v226
	v_pk_mul_f32 v[78:79], v[140:141], v[78:79] op_sel_hi:[0,1]
	v_mul_f32_e32 v83, v83, v144
	v_mul_f32_e32 v83, v221, v83
	v_cndmask_b32_e32 v144, 0, v83, vcc
	v_sub_f32_e32 v83, v89, v218
	v_mul_f32_e32 v83, 0x3fb8aa3b, v83
	v_exp_f32_e32 v83, v83
	v_cmp_ge_u32_e32 vcc, v82, v87
	v_or_b32_e32 v82, 19, v226
	v_pk_mul_f32 v[76:77], v[140:141], v[76:77] op_sel_hi:[0,1]
	v_mul_f32_e32 v83, v83, v196
	v_mul_f32_e32 v83, v222, v83
	v_cndmask_b32_e32 v145, 0, v83, vcc
	v_sub_f32_e32 v83, v89, v219
	v_mul_f32_e32 v83, 0x3fb8aa3b, v83
	v_exp_f32_e32 v83, v83
	v_cmp_ge_u32_e32 vcc, v82, v87
	v_or_b32_e32 v82, 24, v226
	v_pk_mul_f32 v[74:75], v[140:141], v[74:75] op_sel_hi:[0,1]
	v_mul_f32_e32 v83, v83, v197
	v_mul_f32_e32 v83, v223, v83
	ds_read_b128 v[216:219], v227 offset:96
	ds_read_b128 v[220:223], v227 offset:608
	v_cndmask_b32_e32 v146, 0, v83, vcc
	v_cmp_ge_u32_e32 vcc, v82, v87
	v_or_b32_e32 v82, 25, v226
	s_waitcnt lgkmcnt(0)
	v_sub_f32_e32 v83, v89, v216
	v_mul_f32_e32 v83, 0x3fb8aa3b, v83
	v_exp_f32_e32 v83, v83
	v_pk_mul_f32 v[72:73], v[140:141], v[72:73] op_sel_hi:[0,1]
	v_pk_mul_f32 v[70:71], v[140:141], v[70:71] op_sel_hi:[0,1]
	v_pk_mul_f32 v[68:69], v[140:141], v[68:69] op_sel_hi:[0,1]
	v_mul_f32_e32 v83, v83, v215
	s_waitcnt lgkmcnt(0)
	v_mul_f32_e32 v83, v220, v83
	v_cndmask_b32_e32 v151, 0, v83, vcc
	v_sub_f32_e32 v83, v89, v217
	v_mul_f32_e32 v83, 0x3fb8aa3b, v83
	v_exp_f32_e32 v83, v83
	v_cmp_ge_u32_e32 vcc, v82, v87
	v_or_b32_e32 v82, 26, v226
	v_pk_mul_f32 v[66:67], v[140:141], v[66:67] op_sel_hi:[0,1]
	v_mul_f32_e32 v83, v83, v224
	v_mul_f32_e32 v83, v221, v83
	v_cndmask_b32_e32 v152, 0, v83, vcc
	v_sub_f32_e32 v83, v89, v218
	v_mul_f32_e32 v83, 0x3fb8aa3b, v83
	v_exp_f32_e32 v83, v83
	v_cmp_ge_u32_e32 vcc, v82, v87
	v_or_b32_e32 v82, 27, v226
	v_pk_mul_f32 v[64:65], v[140:141], v[64:65] op_sel_hi:[0,1]
	v_mul_f32_e32 v83, v83, v225
	v_mul_f32_e32 v83, v222, v83
	v_cndmask_b32_e32 v153, 0, v83, vcc
	v_sub_f32_e32 v83, v89, v219
	v_mul_f32_e32 v83, 0x3fb8aa3b, v83
	v_exp_f32_e32 v83, v83
	v_cmp_ge_u32_e32 vcc, v82, v87
	s_add_i32 s97, s97, 1
	s_add_i32 s83, s83, -1
	v_mul_f32_e32 v83, v83, v154
	v_mul_f32_e32 v83, v223, v83
	v_cndmask_b32_e32 v89, 0, v83, vcc
	s_cmp_eq_u32 s97, 1
	s_cbranch_scc1 .Lssd_a_dg_0
	s_cmp_eq_u32 s97, 2
	s_cbranch_scc1 .Lssd_a_dg_1
	s_cmp_eq_u32 s97, 3
	s_cbranch_scc1 .Lssd_a_dg_2
	v_mov_b32_e32 v154, v228
	v_mov_b32_e32 v155, v229
	v_mov_b32_e32 v156, v230
	v_mov_b32_e32 v157, v231
	v_mov_b32_e32 v248, v232
	v_mov_b32_e32 v249, v233
	v_mov_b32_e32 v250, v234
	v_mov_b32_e32 v251, v235
	s_branch .Lssd_a_dg_done
.Lssd_a_dg_0:
	v_mov_b32_e32 v154, v176
	v_mov_b32_e32 v155, v177
	v_mov_b32_e32 v156, v178
	v_mov_b32_e32 v157, v179
	v_mov_b32_e32 v248, v180
	v_mov_b32_e32 v249, v181
	v_mov_b32_e32 v250, v182
	v_mov_b32_e32 v251, v183
	s_branch .Lssd_a_dg_done
.Lssd_a_dg_1:
	v_mov_b32_e32 v154, v184
	v_mov_b32_e32 v155, v185
	v_mov_b32_e32 v156, v186
	v_mov_b32_e32 v157, v187
	v_mov_b32_e32 v248, v200
	v_mov_b32_e32 v249, v201
	v_mov_b32_e32 v250, v202
	v_mov_b32_e32 v251, v203
	s_branch .Lssd_a_dg_done
.Lssd_a_dg_2:
	v_mov_b32_e32 v154, v204
	v_mov_b32_e32 v155, v205
	v_mov_b32_e32 v156, v206
	v_mov_b32_e32 v157, v207
	v_mov_b32_e32 v248, v188
	v_mov_b32_e32 v249, v189
	v_mov_b32_e32 v250, v190
	v_mov_b32_e32 v251, v191
; __device__ __forceinline__ unsigned cvt_pk_bf16(float lo, float hi) { unsigned r; asm volatile("s_nop 0\n\tv_cvt_pk_bf16_f32 %0, %1, %2\n\ts_nop 1" : "=v"(r) : "v"(lo), "v"(hi)); return r; }
; __device__ __forceinline__ f32x16 mfma32(bf16x8 a, bf16x8 b, f32x16 c) { return __builtin_amdgcn_mfma_f32_32x32x16_bf16(a, b, c, 0, 0, 0); }
;     ...
;             for (int ib = 0; ib < 4; ++ib) {
;                 const unsigned ioff = rowoff + (unsigned)ib * 8192u;
;                 f32x16 Ya;
; #pragma unroll
;                 for (int e = 0; e < 16; ++e) Ya[e] = 0.f;
; #pragma unroll
;                 for (int nb = 0; nb < 4; ++nb)
; #pragma unroll
;                     for (int sp = 0; sp < 2; ++sp) Ya = mfma32(pack_acc(H[nb], sp), t_ld44(TA, ioff, rx4, 4 * nb + 2 * sp, h), Ya);
;     ...
;                     Ya = mfma32(ld44(XT + 32 * jb + 4 * h), pack_acc(S, 0), Ya); Ya = mfma32(ld44(XT + 32 * jb + 16 + 4 * h), pack_acc(S, 1), Ya);
;                 }
;                 asm volatile("s_nop 15\n\ts_nop 3" : "+v"(Ya));
;                 bf16_t* yr = Y + (size_t)(32 * ib + r) * 2048 + 4 * h;
; #pragma unroll
;                 for (int q = 0; q < 4; ++q) { u32x2 w; w.x = cvt_pk_bf16(Ya[4 * q], Ya[4 * q + 1]); w.y = cvt_pk_bf16(Ya[4 * q + 2], Ya[4 * q + 3]); if (MODE != 3 || w.x == 0x12345678u) *(u32x2*)(yr + 8 * q) = w; }
.Lssd_a_dg_done:
	s_nop 0
	v_cvt_pk_bf16_f32 v216, v147, v148
	s_nop 0
	v_cvt_pk_bf16_f32 v217, v149, v150
	s_nop 0
	v_cvt_pk_bf16_f32 v218, v80, v81
	s_nop 0
	v_cvt_pk_bf16_f32 v219, v192, v194
	s_nop 0
	s_nop 0
	v_cvt_pk_bf16_f32 v144, v91, v144
	s_nop 0
	v_cvt_pk_bf16_f32 v145, v145, v146
	s_nop 0
	v_cvt_pk_bf16_f32 v146, v151, v152
	s_nop 0
	v_cvt_pk_bf16_f32 v147, v153, v89
	v_lshlrev_b32_e32 v192, 12, v87
	s_add_i32 s84, s84, 32
	s_add_i32 s85, s85, -1
	s_add_i32 s62, s33, 2
	s_add_i32 s86, s86, s33
	v_add_u32_e32 v85, 0x280, v85
	s_cmp_eq_u32 s97, 4
	s_mov_b32 s33, s62
	v_mfma_f32_32x32x16_bf16 v[64:79], v[154:157], v[216:219], v[64:79]
	v_mfma_f32_32x32x16_bf16 v[64:79], v[248:251], v[144:147], v[64:79]
	s_nop 15
	s_nop 3
	v_lshl_add_u64 v[80:81], v[136:137], 0, v[192:193]
	s_nop 0
	v_cvt_pk_bf16_f32 v64, v64, v65
	s_nop 0
	v_cvt_pk_bf16_f32 v65, v66, v67
	s_nop 10
	global_store_dwordx2 v[80:81], v[64:65], off
	s_nop 0
	v_cvt_pk_bf16_f32 v64, v68, v69
	s_nop 0
	v_cvt_pk_bf16_f32 v65, v70, v71
	global_store_dwordx2 v[80:81], v[64:65], off offset:16
	s_nop 0
	v_cvt_pk_bf16_f32 v64, v72, v73
	s_nop 0
	v_cvt_pk_bf16_f32 v65, v74, v75
	global_store_dwordx2 v[80:81], v[64:65], off offset:32
	s_nop 0
	v_cvt_pk_bf16_f32 v64, v76, v77
	v_cvt_pk_bf16_f32 v65, v78, v79
	s_nop 1
	global_store_dwordx2 v[80:81], v[64:65], off offset:48
	s_cbranch_scc1 .Lssd_a_back
.LBB0_432:
	v_lshl_add_u32 v87, s97, 13, v211
	v_add_u32_e32 v68, v87, v107
	v_xor_b32_e32 v173, 0x10, v107
	v_add_u32_e32 v70, v87, v173
	s_nop 0
	v_cvt_pk_bf16_f32 v64, v48, v49
	s_nop 0
	v_cvt_pk_bf16_f32 v65, v50, v51
	s_nop 0
	v_cvt_pk_bf16_f32 v66, v52, v53
	s_nop 0
	v_cvt_pk_bf16_f32 v67, v54, v55
	ds_read_b64 v[68:69], v68
	ds_read_b64 v[70:71], v70
	s_waitcnt lgkmcnt(0)
	v_mfma_f32_32x32x16_bf16 v[64:79], v[64:67], v[68:71], 0
	v_xor_b32_e32 v173, 0x20, v107
	v_add_u32_e32 v89, v87, v173
	s_nop 0
	v_cvt_pk_bf16_f32 v80, v56, v57
	s_nop 0
	v_cvt_pk_bf16_f32 v81, v58, v59
	s_nop 0
	v_cvt_pk_bf16_f32 v82, v60, v61
	s_nop 0
	v_cvt_pk_bf16_f32 v83, v62, v63
	v_xor_b32_e32 v173, 0x30, v107
	v_add_u32_e32 v91, v87, v173
	ds_read_b64 v[144:145], v89
	ds_read_b64 v[146:147], v91
	s_waitcnt lgkmcnt(0)
	v_mfma_f32_32x32x16_bf16 v[64:79], v[80:83], v[144:147], v[64:79]
	v_xor_b32_e32 v173, 0x40, v107
	v_add_u32_e32 v89, v87, v173
	s_nop 0
	v_cvt_pk_bf16_f32 v80, v32, v33
	s_nop 0
	v_cvt_pk_bf16_f32 v81, v34, v35
	s_nop 0
	v_cvt_pk_bf16_f32 v82, v36, v37
	s_nop 0
	v_cvt_pk_bf16_f32 v83, v38, v39
	v_xor_b32_e32 v173, 0x50, v107
	v_add_u32_e32 v91, v87, v173
	ds_read_b64 v[144:145], v89
	ds_read_b64 v[146:147], v91
	s_waitcnt lgkmcnt(0)
	v_mfma_f32_32x32x16_bf16 v[64:79], v[80:83], v[144:147], v[64:79]
	v_xor_b32_e32 v173, 0x60, v107
	v_add_u32_e32 v89, v87, v173
	s_nop 0
	v_cvt_pk_bf16_f32 v80, v40, v41
	s_nop 0
	v_cvt_pk_bf16_f32 v81, v42, v43
	s_nop 0
	v_cvt_pk_bf16_f32 v82, v44, v45
	s_nop 0
	v_cvt_pk_bf16_f32 v83, v46, v47
	v_xor_b32_e32 v173, 0x70, v107
	v_add_u32_e32 v91, v87, v173
	ds_read_b64 v[144:145], v89
	ds_read_b64 v[146:147], v91
	s_waitcnt lgkmcnt(0)
	v_mfma_f32_32x32x16_bf16 v[64:79], v[80:83], v[144:147], v[64:79]
	v_xor_b32_e32 v173, 0x80, v107
	v_add_u32_e32 v89, v87, v173
	s_nop 0
	v_cvt_pk_bf16_f32 v80, v16, v17
	s_nop 0
	v_cvt_pk_bf16_f32 v81, v18, v19
	s_nop 0
	v_cvt_pk_bf16_f32 v82, v20, v21
	s_nop 0
	v_cvt_pk_bf16_f32 v83, v22, v23
	v_xor_b32_e32 v173, 0x90, v107
	v_add_u32_e32 v91, v87, v173
	ds_read_b64 v[144:145], v89
	ds_read_b64 v[146:147], v91
	s_waitcnt lgkmcnt(0)
	v_mfma_f32_32x32x16_bf16 v[64:79], v[80:83], v[144:147], v[64:79]
	v_xor_b32_e32 v173, 0xa0, v107
	v_add_u32_e32 v89, v87, v173
	s_nop 0
	v_cvt_pk_bf16_f32 v80, v24, v25
	s_nop 0
	v_cvt_pk_bf16_f32 v81, v26, v27
	s_nop 0
	v_cvt_pk_bf16_f32 v82, v28, v29
	s_nop 0
	v_cvt_pk_bf16_f32 v83, v30, v31
	v_xor_b32_e32 v173, 0xb0, v107
	v_add_u32_e32 v91, v87, v173
	ds_read_b64 v[144:145], v89
	ds_read_b64 v[146:147], v91
	s_waitcnt lgkmcnt(0)
	v_mfma_f32_32x32x16_bf16 v[64:79], v[80:83], v[144:147], v[64:79]
	v_xor_b32_e32 v173, 0xc0, v107
	v_add_u32_e32 v89, v87, v173
	s_nop 0
	v_cvt_pk_bf16_f32 v80, v0, v1
	s_nop 0
	v_cvt_pk_bf16_f32 v81, v2, v3
	s_nop 0
	v_cvt_pk_bf16_f32 v82, v4, v5
	s_nop 0
	v_cvt_pk_bf16_f32 v83, v6, v7
	v_xor_b32_e32 v173, 0xd0, v107
	v_add_u32_e32 v91, v87, v173
	ds_read_b64 v[144:145], v89
	ds_read_b64 v[146:147], v91
	s_waitcnt lgkmcnt(0)
	v_mfma_f32_32x32x16_bf16 v[64:79], v[80:83], v[144:147], v[64:79]
	v_xor_b32_e32 v173, 0xe0, v107
	v_add_u32_e32 v89, v87, v173
	s_nop 0
	v_cvt_pk_bf16_f32 v80, v8, v9
	s_nop 0
	v_cvt_pk_bf16_f32 v81, v10, v11
	s_nop 0
	v_cvt_pk_bf16_f32 v82, v12, v13
	s_nop 0
	v_cvt_pk_bf16_f32 v83, v14, v15
	v_xor_b32_e32 v173, 0xf0, v107
	v_add_u32_e32 v87, v87, v173
	ds_read_b64 v[144:145], v89
	ds_read_b64 v[146:147], v87
	s_waitcnt lgkmcnt(0)
	v_mfma_f32_32x32x16_bf16 v[64:79], v[80:83], v[144:147], v[64:79]
	s_lshl_b32 s69, s97, 5
	v_or_b32_e32 v87, s69, v99
	v_lshl_add_u32 v80, v87, 2, s76
	ds_read_b32 v89, v80
	s_cmp_lt_i32 s97, 1
	v_mov_b32_e32 v80, s54
	s_cbranch_scc1 .LBB0_437
	s_cmp_lg_u32 s97, 1
	s_cbranch_scc0 .LBB0_435
	s_cmp_eq_u32 s97, 2
	v_mov_b32_e32 v80, s96
	s_cselect_b64 vcc, -1, 0
	v_cndmask_b32_e32 v80, 0, v80, vcc
	s_cbranch_execz .LBB0_436
	s_branch .LBB0_437

; __device__ __forceinline__ unsigned cvt_pk_bf16(float lo, float hi) { unsigned r; asm volatile("s_nop 0\n\tv_cvt_pk_bf16_f32 %0, %1, %2\n\ts_nop 1" : "=v"(r) : "v"(lo), "v"(hi)); return r; }
; #define LAS __attribute__((address_space(3)))
;     ...
;                 for (int jb = (DIR ? ib + 1 : 0); jb < (DIR ? 4 : ib); ++jb) {
;                     f32x16 S;
;                     { const int bi2 = DIR ? 3 - ib : ib, bj2 = DIR ? 3 - jb : jb; const LAS u32x4* srcp = (const LAS u32x4*)(CBL + (bi2 * (bi2 + 1) / 2 + bj2) * 2048 + lane * 32);
;                       const u32x4 w0 = srcp[0], w1 = srcp[1];
;                       S[0] = bflo(w0.x); S[1] = bfhi(w0.x); S[2] = bflo(w0.y); S[3] = bfhi(w0.y); S[4] = bflo(w0.z); S[5] = bfhi(w0.z); S[6] = bflo(w0.w); S[7] = bfhi(w0.w);
;                       S[8] = bflo(w1.x); S[9] = bfhi(w1.x); S[10] = bflo(w1.y); S[11] = bfhi(w1.y); S[12] = bflo(w1.z); S[13] = bfhi(w1.z); S[14] = bflo(w1.w); S[15] = bfhi(w1.w); }
; #pragma unroll
;                     for (int q = 0; q < 4; ++q) { const f32x4 w4 = *(const LAS f32x4*)(wL + ib * 128 + 32 * jb + 8 * q + 4 * h);
; #pragma unroll
;                         for (int k = 0; k < 4; ++k) S[4 * q + k] *= w4[k]; }
;                     Ya = mfma32(ld44(XT + 32 * jb + 4 * h), pack_acc(S, 0), Ya); Ya = mfma32(ld44(XT + 32 * jb + 16 + 4 * h), pack_acc(S, 1), Ya);
;                 }
;     ...
;         const float dec = __expf(ctot);
; #pragma unroll
;         for (int nb = 0; nb < 4; ++nb)
; #pragma unroll
;             for (int e = 0; e < 16; ++e) H[nb][e] *= dec;
; #pragma unroll
;         for (int s8 = 0; s8 < ((MODE == 2 || MODE == 3) ? 0 : 8); ++s8) {
;             const u32x4 xr = *(const u32x4*)(XT + 16 * s8 + 8 * h);
;             const f32x4 sa = *(const LAS f32x4*)(sclL + 16 * s8 + 8 * h), sb = *(const LAS f32x4*)(sclL + 16 * s8 + 8 * h + 4);
;             u32x4 w; w.x = cvt_pk_bf16(bflo(xr.x) * sa.x, bfhi(xr.x) * sa.y); w.y = cvt_pk_bf16(bflo(xr.y) * sa.z, bfhi(xr.y) * sa.w);
;             w.z = cvt_pk_bf16(bflo(xr.z) * sb.x, bfhi(xr.z) * sb.y); w.w = cvt_pk_bf16(bflo(xr.w) * sb.z, bfhi(xr.w) * sb.w);
;             const bf16x8 Xs = __builtin_bit_cast(bf16x8, w);
; #pragma unroll
;             for (int nb = 0; nb < 4; ++nb) H[nb] = mfma32(t_ld8(TC, rowoff + (unsigned)nb * 8192u, rx4, 2 * s8 + h), Xs, H[nb]);
;         }
.LBB0_439:
	v_add_u32_e32 v83, 0, v81
	v_add_u32_e32 v91, 0x21800, v83
	ds_read_b128 v[144:147], v91
	v_add_u32_e32 v83, 0x21810, v83
	v_add_u32_e32 v196, 0, v82
	ds_read_b128 v[148:151], v83
	s_add_i32 s62, s62, -1
	s_waitcnt lgkmcnt(0)
	v_lshlrev_b32_e32 v83, 16, v144
	v_and_b32_e32 v91, 0xffff0000, v144
	v_add_u32_e32 v144, 0x18680, v196
	v_lshlrev_b32_e32 v140, 16, v145
	v_and_b32_e32 v152, 0xffff0000, v145
	v_lshlrev_b32_e32 v153, 16, v146
	v_and_b32_e32 v154, 0xffff0000, v146
	v_lshlrev_b32_e32 v155, 16, v147
	v_and_b32_e32 v156, 0xffff0000, v147
	ds_read_b128 v[144:147], v144
	s_waitcnt lgkmcnt(1)
	v_lshlrev_b32_e32 v157, 16, v148
	v_and_b32_e32 v148, 0xffff0000, v148
	v_lshlrev_b32_e32 v192, 16, v149
	v_and_b32_e32 v149, 0xffff0000, v149
	s_waitcnt lgkmcnt(0)
	v_mul_f32_e32 v83, v144, v83
	v_add_u32_e32 v144, 0x186a0, v196
	v_mul_f32_e32 v91, v145, v91
	v_mul_f32_e32 v140, v146, v140
	v_mul_f32_e32 v197, v147, v152
	ds_read_b128 v[144:147], v144
	v_lshlrev_b32_e32 v194, 16, v150
	v_and_b32_e32 v150, 0xffff0000, v150
	v_lshlrev_b32_e32 v195, 16, v151
	v_and_b32_e32 v151, 0xffff0000, v151
	s_waitcnt lgkmcnt(0)
	v_mul_f32_e32 v215, v144, v153
	v_add_u32_e32 v144, 0x186c0, v196
	v_mul_f32_e32 v154, v145, v154
	v_mul_f32_e32 v155, v146, v155
	v_mul_f32_e32 v156, v147, v156
	ds_read_b128 v[144:147], v144
	v_lshl_add_u64 v[152:153], s[66:67], 1, v[138:139]
	s_add_i32 s66, s66, 32
	v_add_u32_e32 v81, 0xfffff800, v81
	v_add_u32_e32 v82, 0x80, v82
	s_waitcnt lgkmcnt(0)
	v_mul_f32_e32 v157, v144, v157
	v_add_u32_e32 v144, 0x186e0, v196
	v_mul_f32_e32 v216, v145, v148
	v_mul_f32_e32 v192, v146, v192
	v_mul_f32_e32 v217, v147, v149
	ds_read_b128 v[144:147], v144
	s_cmp_eq_u32 s62, 0
	s_waitcnt lgkmcnt(0)
	v_mul_f32_e32 v194, v144, v194
	v_mul_f32_e32 v196, v145, v150
	v_mul_f32_e32 v195, v146, v195
	v_mul_f32_e32 v218, v147, v151
	s_cmp_eq_u32 s66, 64
	s_cbranch_scc1 .Lssd_a_jb_1
	s_cmp_eq_u32 s66, 96
	s_cbranch_scc1 .Lssd_a_jb_2
	v_mov_b32_e32 v144, v228
	v_mov_b32_e32 v145, v229
	v_mov_b32_e32 v146, v230
	v_mov_b32_e32 v147, v231
	v_mov_b32_e32 v248, v232
	v_mov_b32_e32 v249, v233
	v_mov_b32_e32 v250, v234
	v_mov_b32_e32 v251, v235
	s_branch .Lssd_a_jb_done
.Lssd_a_jb_1:
	v_mov_b32_e32 v144, v184
	v_mov_b32_e32 v145, v185
	v_mov_b32_e32 v146, v186
	v_mov_b32_e32 v147, v187
	v_mov_b32_e32 v248, v200
	v_mov_b32_e32 v249, v201
	v_mov_b32_e32 v250, v202
	v_mov_b32_e32 v251, v203
	s_branch .Lssd_a_jb_done
.Lssd_a_jb_2:
	v_mov_b32_e32 v144, v204
	v_mov_b32_e32 v145, v205
	v_mov_b32_e32 v146, v206
	v_mov_b32_e32 v147, v207
	v_mov_b32_e32 v248, v188
	v_mov_b32_e32 v249, v189
	v_mov_b32_e32 v250, v190
	v_mov_b32_e32 v251, v191
.Lssd_a_jb_done:
	s_cmp_eq_u32 s62, 0
	s_nop 0
	v_cvt_pk_bf16_f32 v148, v83, v91
	s_nop 0
	v_cvt_pk_bf16_f32 v149, v140, v197
	s_nop 0
	v_cvt_pk_bf16_f32 v150, v215, v154
	s_nop 1
	s_nop 0
	v_cvt_pk_bf16_f32 v151, v155, v156
	s_nop 1
	v_mfma_f32_32x32x16_bf16 v[64:79], v[144:147], v[148:151], v[64:79]
	s_nop 0
	v_cvt_pk_bf16_f32 v148, v157, v216
	s_nop 0
	v_cvt_pk_bf16_f32 v149, v192, v217
	s_nop 0
	v_cvt_pk_bf16_f32 v150, v194, v196
	s_nop 1
	s_nop 0
	v_cvt_pk_bf16_f32 v151, v195, v218
	s_nop 1
	v_mfma_f32_32x32x16_bf16 v[64:79], v[248:251], v[148:151], v[64:79]
	s_cbranch_scc0 .LBB0_439
	s_sub_i32 s62, 3, s97
	s_sub_i32 s63, 4, s97
	s_mul_i32 s63, s62, s63
	s_lshr_b32 s63, s63, 1
	s_add_i32 s63, s63, s62
	s_lshl_b32 s62, s63, 11
	s_branch .LBB0_431
.LBB0_441:
	v_mul_f32_e32 v64, s53, v239
	v_exp_f32_e32 v64, v64
	v_lshlrev_b32_e32 v192, 1, v114
	v_add_u32_e32 v66, v209, v164
	s_andn2_b64 vcc, exec, s[80:81]
	v_pk_mul_f32 v[62:63], v[62:63], v[64:65] op_sel_hi:[1,0]
	v_pk_mul_f32 v[60:61], v[60:61], v[64:65] op_sel_hi:[1,0]
	v_pk_mul_f32 v[58:59], v[58:59], v[64:65] op_sel_hi:[1,0]
	v_pk_mul_f32 v[56:57], v[56:57], v[64:65] op_sel_hi:[1,0]
	v_pk_mul_f32 v[54:55], v[54:55], v[64:65] op_sel_hi:[1,0]
	v_pk_mul_f32 v[52:53], v[52:53], v[64:65] op_sel_hi:[1,0]
	v_pk_mul_f32 v[50:51], v[50:51], v[64:65] op_sel_hi:[1,0]
	v_pk_mul_f32 v[48:49], v[48:49], v[64:65] op_sel_hi:[1,0]
	v_pk_mul_f32 v[46:47], v[46:47], v[64:65] op_sel_hi:[1,0]
	v_pk_mul_f32 v[44:45], v[44:45], v[64:65] op_sel_hi:[1,0]
	v_pk_mul_f32 v[42:43], v[42:43], v[64:65] op_sel_hi:[1,0]
	v_pk_mul_f32 v[40:41], v[40:41], v[64:65] op_sel_hi:[1,0]
	v_pk_mul_f32 v[38:39], v[38:39], v[64:65] op_sel_hi:[1,0]
	v_pk_mul_f32 v[36:37], v[36:37], v[64:65] op_sel_hi:[1,0]
	v_pk_mul_f32 v[34:35], v[34:35], v[64:65] op_sel_hi:[1,0]
	v_pk_mul_f32 v[32:33], v[32:33], v[64:65] op_sel_hi:[1,0]
	v_pk_mul_f32 v[30:31], v[30:31], v[64:65] op_sel_hi:[1,0]
	v_pk_mul_f32 v[28:29], v[28:29], v[64:65] op_sel_hi:[1,0]
	v_pk_mul_f32 v[26:27], v[26:27], v[64:65] op_sel_hi:[1,0]
	v_pk_mul_f32 v[24:25], v[24:25], v[64:65] op_sel_hi:[1,0]
	v_pk_mul_f32 v[22:23], v[22:23], v[64:65] op_sel_hi:[1,0]
	v_pk_mul_f32 v[20:21], v[20:21], v[64:65] op_sel_hi:[1,0]
	v_pk_mul_f32 v[18:19], v[18:19], v[64:65] op_sel_hi:[1,0]
	v_pk_mul_f32 v[16:17], v[16:17], v[64:65] op_sel_hi:[1,0]
	v_pk_mul_f32 v[14:15], v[14:15], v[64:65] op_sel_hi:[1,0]
	v_pk_mul_f32 v[12:13], v[12:13], v[64:65] op_sel_hi:[1,0]
	v_pk_mul_f32 v[10:11], v[10:11], v[64:65] op_sel_hi:[1,0]
	v_pk_mul_f32 v[8:9], v[8:9], v[64:65] op_sel_hi:[1,0]
	v_pk_mul_f32 v[6:7], v[6:7], v[64:65] op_sel_hi:[1,0]
	v_pk_mul_f32 v[4:5], v[4:5], v[64:65] op_sel_hi:[1,0]
	v_pk_mul_f32 v[2:3], v[2:3], v[64:65] op_sel_hi:[1,0]
	v_pk_mul_f32 v[0:1], v[0:1], v[64:65] op_sel_hi:[1,0]
	v_lshl_add_u64 v[64:65], v[134:135], 0, v[192:193]
	s_waitcnt lgkmcnt(0)
	ds_read_b128 v[72:75], v66 offset:1024
	ds_read_b128 v[76:79], v66 offset:1040
	ds_read_b128 v[144:147], v66 offset:1088
	ds_read_b128 v[148:151], v66 offset:1104
	s_waitcnt lgkmcnt(2)
; __device__ __forceinline__ unsigned cvt_pk_bf16(float lo, float hi) { unsigned r; asm volatile("s_nop 0\n\tv_cvt_pk_bf16_f32 %0, %1, %2\n\ts_nop 1" : "=v"(r) : "v"(lo), "v"(hi)); return r; }
; #define LAS __attribute__((address_space(3)))
; __device__ __forceinline__ float bflo(unsigned w) { return __uint_as_float(w << 16); }
; __device__ __forceinline__ float bfhi(unsigned w) { return __uint_as_float(w & 0xffff0000u); }
;     ...
;         for (int s8 = 0; s8 < ((MODE == 2 || MODE == 3) ? 0 : 8); ++s8) {
;             const u32x4 xr = *(const u32x4*)(XT + 16 * s8 + 8 * h);
;             const f32x4 sa = *(const LAS f32x4*)(sclL + 16 * s8 + 8 * h), sb = *(const LAS f32x4*)(sclL + 16 * s8 + 8 * h + 4);
;             u32x4 w; w.x = cvt_pk_bf16(bflo(xr.x) * sa.x, bfhi(xr.x) * sa.y); w.y = cvt_pk_bf16(bflo(xr.y) * sa.z, bfhi(xr.y) * sa.w);
;             w.z = cvt_pk_bf16(bflo(xr.z) * sb.x, bfhi(xr.z) * sb.y); w.w = cvt_pk_bf16(bflo(xr.w) * sb.z, bfhi(xr.w) * sb.w);
;             const bf16x8 Xs = __builtin_bit_cast(bf16x8, w);
	v_lshlrev_b32_e32 v67, 16, v176
	v_and_b32_e32 v65, 0xffff0000, v176
	v_mul_f32_e32 v67, v72, v67
	v_mul_f32_e32 v65, v73, v65
	v_cvt_pk_bf16_f32 v176, v67, v65
	v_lshlrev_b32_e32 v67, 16, v177
	v_and_b32_e32 v65, 0xffff0000, v177
	v_mul_f32_e32 v67, v74, v67
	v_mul_f32_e32 v65, v75, v65
	v_cvt_pk_bf16_f32 v177, v67, v65
	v_lshlrev_b32_e32 v67, 16, v178
	v_and_b32_e32 v65, 0xffff0000, v178
	v_mul_f32_e32 v67, v76, v67
	v_mul_f32_e32 v65, v77, v65
	v_cvt_pk_bf16_f32 v178, v67, v65
	v_lshlrev_b32_e32 v67, 16, v179
	v_and_b32_e32 v65, 0xffff0000, v179
	v_mul_f32_e32 v67, v78, v67
	v_mul_f32_e32 v65, v79, v65
	v_cvt_pk_bf16_f32 v179, v67, v65
	ds_read_b128 v[72:75], v66 offset:1152
	ds_read_b128 v[76:79], v66 offset:1168
	s_waitcnt lgkmcnt(2)
	v_lshlrev_b32_e32 v67, 16, v180
	v_and_b32_e32 v65, 0xffff0000, v180
	v_mul_f32_e32 v67, v144, v67
	v_mul_f32_e32 v65, v145, v65
	v_cvt_pk_bf16_f32 v180, v67, v65
	v_lshlrev_b32_e32 v67, 16, v181
	v_and_b32_e32 v65, 0xffff0000, v181
	v_mul_f32_e32 v67, v146, v67
	v_mul_f32_e32 v65, v147, v65
	v_cvt_pk_bf16_f32 v181, v67, v65
	v_lshlrev_b32_e32 v67, 16, v182
	v_and_b32_e32 v65, 0xffff0000, v182
	v_mul_f32_e32 v67, v148, v67
	v_mul_f32_e32 v65, v149, v65
	v_cvt_pk_bf16_f32 v182, v67, v65
	v_lshlrev_b32_e32 v67, 16, v183
	v_and_b32_e32 v65, 0xffff0000, v183
	v_mul_f32_e32 v67, v150, v67
	v_mul_f32_e32 v65, v151, v65
	v_cvt_pk_bf16_f32 v183, v67, v65
	ds_read_b128 v[144:147], v66 offset:1216
	ds_read_b128 v[148:151], v66 offset:1232
	s_waitcnt lgkmcnt(2)
	v_lshlrev_b32_e32 v67, 16, v184
	v_and_b32_e32 v65, 0xffff0000, v184
	v_mul_f32_e32 v67, v72, v67
	v_mul_f32_e32 v65, v73, v65
	v_cvt_pk_bf16_f32 v184, v67, v65
	v_lshlrev_b32_e32 v67, 16, v185
	v_and_b32_e32 v65, 0xffff0000, v185
	v_mul_f32_e32 v67, v74, v67
	v_mul_f32_e32 v65, v75, v65
	v_cvt_pk_bf16_f32 v185, v67, v65
	v_lshlrev_b32_e32 v67, 16, v186
	v_and_b32_e32 v65, 0xffff0000, v186
	v_mul_f32_e32 v67, v76, v67
	v_mul_f32_e32 v65, v77, v65
	v_cvt_pk_bf16_f32 v186, v67, v65
	v_lshlrev_b32_e32 v67, 16, v187
	v_and_b32_e32 v65, 0xffff0000, v187
	v_mul_f32_e32 v67, v78, v67
	v_mul_f32_e32 v65, v79, v65
	v_cvt_pk_bf16_f32 v187, v67, v65
	ds_read_b128 v[72:75], v66 offset:1280
	ds_read_b128 v[76:79], v66 offset:1296
	s_waitcnt lgkmcnt(2)
	v_lshlrev_b32_e32 v67, 16, v200
	v_and_b32_e32 v65, 0xffff0000, v200
	v_mul_f32_e32 v67, v144, v67
	v_mul_f32_e32 v65, v145, v65
	v_cvt_pk_bf16_f32 v200, v67, v65
	v_lshlrev_b32_e32 v67, 16, v201
	v_and_b32_e32 v65, 0xffff0000, v201
	v_mul_f32_e32 v67, v146, v67
	v_mul_f32_e32 v65, v147, v65
	v_cvt_pk_bf16_f32 v201, v67, v65
	v_lshlrev_b32_e32 v67, 16, v202
	v_and_b32_e32 v65, 0xffff0000, v202
	v_mul_f32_e32 v67, v148, v67
	v_mul_f32_e32 v65, v149, v65
	v_cvt_pk_bf16_f32 v202, v67, v65
	v_lshlrev_b32_e32 v67, 16, v203
	v_and_b32_e32 v65, 0xffff0000, v203
	v_mul_f32_e32 v67, v150, v67
	v_mul_f32_e32 v65, v151, v65
	v_cvt_pk_bf16_f32 v203, v67, v65
	ds_read_b128 v[144:147], v66 offset:1344
	ds_read_b128 v[148:151], v66 offset:1360
	s_waitcnt lgkmcnt(2)
	v_lshlrev_b32_e32 v67, 16, v204
	v_and_b32_e32 v65, 0xffff0000, v204
	v_mul_f32_e32 v67, v72, v67
	v_mul_f32_e32 v65, v73, v65
	v_cvt_pk_bf16_f32 v204, v67, v65
	v_lshlrev_b32_e32 v67, 16, v205
	v_and_b32_e32 v65, 0xffff0000, v205
	v_mul_f32_e32 v67, v74, v67
	v_mul_f32_e32 v65, v75, v65
	v_cvt_pk_bf16_f32 v205, v67, v65
	v_lshlrev_b32_e32 v67, 16, v206
	v_and_b32_e32 v65, 0xffff0000, v206
	v_mul_f32_e32 v67, v76, v67
	v_mul_f32_e32 v65, v77, v65
	v_cvt_pk_bf16_f32 v206, v67, v65
	v_lshlrev_b32_e32 v67, 16, v207
	v_and_b32_e32 v65, 0xffff0000, v207
	v_mul_f32_e32 v67, v78, v67
	v_mul_f32_e32 v65, v79, v65
	v_cvt_pk_bf16_f32 v207, v67, v65
	ds_read_b128 v[72:75], v66 offset:1408
	ds_read_b128 v[76:79], v66 offset:1424
	s_waitcnt lgkmcnt(2)
	v_lshlrev_b32_e32 v67, 16, v188
	v_and_b32_e32 v65, 0xffff0000, v188
	v_mul_f32_e32 v67, v144, v67
	v_mul_f32_e32 v65, v145, v65
	v_cvt_pk_bf16_f32 v188, v67, v65
	v_lshlrev_b32_e32 v67, 16, v189
	v_and_b32_e32 v65, 0xffff0000, v189
	v_mul_f32_e32 v67, v146, v67
	v_mul_f32_e32 v65, v147, v65
	v_cvt_pk_bf16_f32 v189, v67, v65
	v_lshlrev_b32_e32 v67, 16, v190
	v_and_b32_e32 v65, 0xffff0000, v190
	v_mul_f32_e32 v67, v148, v67
	v_mul_f32_e32 v65, v149, v65
	v_cvt_pk_bf16_f32 v190, v67, v65
	v_lshlrev_b32_e32 v67, 16, v191
	v_and_b32_e32 v65, 0xffff0000, v191
	v_mul_f32_e32 v67, v150, v67
	v_mul_f32_e32 v65, v151, v65
	v_cvt_pk_bf16_f32 v191, v67, v65
	ds_read_b128 v[144:147], v66 offset:1472
	ds_read_b128 v[148:151], v66 offset:1488
	s_waitcnt lgkmcnt(2)
	v_lshlrev_b32_e32 v67, 16, v228
	v_and_b32_e32 v65, 0xffff0000, v228
	v_mul_f32_e32 v67, v72, v67
	v_mul_f32_e32 v65, v73, v65
	v_cvt_pk_bf16_f32 v228, v67, v65
	v_lshlrev_b32_e32 v67, 16, v229
	v_and_b32_e32 v65, 0xffff0000, v229
	v_mul_f32_e32 v67, v74, v67
	v_mul_f32_e32 v65, v75, v65
	v_cvt_pk_bf16_f32 v229, v67, v65
	v_lshlrev_b32_e32 v67, 16, v230
	v_and_b32_e32 v65, 0xffff0000, v230
	v_mul_f32_e32 v67, v76, v67
	v_mul_f32_e32 v65, v77, v65
	v_cvt_pk_bf16_f32 v230, v67, v65
	v_lshlrev_b32_e32 v67, 16, v231
	v_and_b32_e32 v65, 0xffff0000, v231
	v_mul_f32_e32 v67, v78, v67
	v_mul_f32_e32 v65, v79, v65
	v_cvt_pk_bf16_f32 v231, v67, v65
	s_waitcnt lgkmcnt(0)
; __device__ __forceinline__ unsigned cvt_pk_bf16(float lo, float hi) { unsigned r; asm volatile("s_nop 0\n\tv_cvt_pk_bf16_f32 %0, %1, %2\n\ts_nop 1" : "=v"(r) : "v"(lo), "v"(hi)); return r; }
; #define LAS __attribute__((address_space(3)))
; __device__ __forceinline__ float bflo(unsigned w) { return __uint_as_float(w << 16); }
; __device__ __forceinline__ float bfhi(unsigned w) { return __uint_as_float(w & 0xffff0000u); }
; __device__ __forceinline__ f32x16 mfma32(bf16x8 a, bf16x8 b, f32x16 c) { return __builtin_amdgcn_mfma_f32_32x32x16_bf16(a, b, c, 0, 0, 0); }
;     ...
;         for (int s8 = 0; s8 < ((MODE == 2 || MODE == 3) ? 0 : 8); ++s8) {
;             const u32x4 xr = *(const u32x4*)(XT + 16 * s8 + 8 * h);
;             const f32x4 sa = *(const LAS f32x4*)(sclL + 16 * s8 + 8 * h), sb = *(const LAS f32x4*)(sclL + 16 * s8 + 8 * h + 4);
;             u32x4 w; w.x = cvt_pk_bf16(bflo(xr.x) * sa.x, bfhi(xr.x) * sa.y); w.y = cvt_pk_bf16(bflo(xr.y) * sa.z, bfhi(xr.y) * sa.w);
;             w.z = cvt_pk_bf16(bflo(xr.z) * sb.x, bfhi(xr.z) * sb.y); w.w = cvt_pk_bf16(bflo(xr.w) * sb.z, bfhi(xr.w) * sb.w);
;             const bf16x8 Xs = __builtin_bit_cast(bf16x8, w);
; #pragma unroll
;             for (int nb = 0; nb < 4; ++nb) H[nb] = mfma32(t_ld8(TC, rowoff + (unsigned)nb * 8192u, rx4, 2 * s8 + h), Xs, H[nb]);
;         }
	v_lshlrev_b32_e32 v67, 16, v232
	v_and_b32_e32 v65, 0xffff0000, v232
	v_mul_f32_e32 v67, v144, v67
	v_mul_f32_e32 v65, v145, v65
	v_cvt_pk_bf16_f32 v232, v67, v65
	v_lshlrev_b32_e32 v67, 16, v233
	v_and_b32_e32 v65, 0xffff0000, v233
	v_mul_f32_e32 v67, v146, v67
	v_mul_f32_e32 v65, v147, v65
	v_cvt_pk_bf16_f32 v233, v67, v65
	v_lshlrev_b32_e32 v67, 16, v234
	v_and_b32_e32 v65, 0xffff0000, v234
	v_mul_f32_e32 v67, v148, v67
	v_mul_f32_e32 v65, v149, v65
	v_cvt_pk_bf16_f32 v234, v67, v65
	v_lshlrev_b32_e32 v67, 16, v235
	v_and_b32_e32 v65, 0xffff0000, v235
	v_mul_f32_e32 v67, v150, v67
	v_mul_f32_e32 v65, v151, v65
	v_cvt_pk_bf16_f32 v235, v67, v65
	s_nop 1
	v_add_u32_e32 v64, v210, v115
	ds_read_b128 v[72:75], v64
	ds_read_b128 v[76:79], v64 offset:8192
	ds_read_b128 v[144:147], v64 offset:16384
	ds_read_b128 v[148:151], v64 offset:24576
	s_waitcnt lgkmcnt(3)
	v_mfma_f32_32x32x16_bf16 v[48:63], v[72:75], v[176:179], v[48:63]
	v_add_u32_e32 v64, v210, v166
	ds_read_b128 v[72:75], v64
	s_waitcnt lgkmcnt(3)
	v_mfma_f32_32x32x16_bf16 v[32:47], v[76:79], v[176:179], v[32:47]
	ds_read_b128 v[76:79], v64 offset:8192
	s_waitcnt lgkmcnt(3)
	v_mfma_f32_32x32x16_bf16 v[16:31], v[144:147], v[176:179], v[16:31]
	ds_read_b128 v[144:147], v64 offset:16384
	s_waitcnt lgkmcnt(3)
	v_mfma_f32_32x32x16_bf16 v[0:15], v[148:151], v[176:179], v[0:15]
	ds_read_b128 v[148:151], v64 offset:24576
	s_waitcnt lgkmcnt(3)
	v_mfma_f32_32x32x16_bf16 v[48:63], v[72:75], v[180:183], v[48:63]
	v_add_u32_e32 v64, v210, v167
	ds_read_b128 v[72:75], v64
	s_waitcnt lgkmcnt(3)
	v_mfma_f32_32x32x16_bf16 v[32:47], v[76:79], v[180:183], v[32:47]
	ds_read_b128 v[76:79], v64 offset:8192
	s_waitcnt lgkmcnt(3)
	v_mfma_f32_32x32x16_bf16 v[16:31], v[144:147], v[180:183], v[16:31]
	ds_read_b128 v[144:147], v64 offset:16384
	s_waitcnt lgkmcnt(3)
	v_mfma_f32_32x32x16_bf16 v[0:15], v[148:151], v[180:183], v[0:15]
	ds_read_b128 v[148:151], v64 offset:24576
	s_waitcnt lgkmcnt(3)
	v_mfma_f32_32x32x16_bf16 v[48:63], v[72:75], v[184:187], v[48:63]
	v_add_u32_e32 v64, v210, v168
	ds_read_b128 v[72:75], v64
	s_waitcnt lgkmcnt(3)
	v_mfma_f32_32x32x16_bf16 v[32:47], v[76:79], v[184:187], v[32:47]
	ds_read_b128 v[76:79], v64 offset:8192
	s_waitcnt lgkmcnt(3)
	v_mfma_f32_32x32x16_bf16 v[16:31], v[144:147], v[184:187], v[16:31]
	ds_read_b128 v[144:147], v64 offset:16384
	s_waitcnt lgkmcnt(3)
	v_mfma_f32_32x32x16_bf16 v[0:15], v[148:151], v[184:187], v[0:15]
	ds_read_b128 v[148:151], v64 offset:24576
	s_waitcnt lgkmcnt(3)
	v_mfma_f32_32x32x16_bf16 v[48:63], v[72:75], v[200:203], v[48:63]
	v_add_u32_e32 v64, v210, v169
	ds_read_b128 v[72:75], v64
	s_waitcnt lgkmcnt(3)
	v_mfma_f32_32x32x16_bf16 v[32:47], v[76:79], v[200:203], v[32:47]
	ds_read_b128 v[76:79], v64 offset:8192
	s_waitcnt lgkmcnt(3)
	v_mfma_f32_32x32x16_bf16 v[16:31], v[144:147], v[200:203], v[16:31]
	ds_read_b128 v[144:147], v64 offset:16384
	s_waitcnt lgkmcnt(3)
	v_mfma_f32_32x32x16_bf16 v[0:15], v[148:151], v[200:203], v[0:15]
	ds_read_b128 v[148:151], v64 offset:24576
	s_waitcnt lgkmcnt(3)
	v_mfma_f32_32x32x16_bf16 v[48:63], v[72:75], v[204:207], v[48:63]
	v_add_u32_e32 v64, v210, v170
	ds_read_b128 v[72:75], v64
	s_waitcnt lgkmcnt(3)
	v_mfma_f32_32x32x16_bf16 v[32:47], v[76:79], v[204:207], v[32:47]
	ds_read_b128 v[76:79], v64 offset:8192
	s_waitcnt lgkmcnt(3)
	v_mfma_f32_32x32x16_bf16 v[16:31], v[144:147], v[204:207], v[16:31]
	ds_read_b128 v[144:147], v64 offset:16384
	s_waitcnt lgkmcnt(3)
	v_mfma_f32_32x32x16_bf16 v[0:15], v[148:151], v[204:207], v[0:15]
	ds_read_b128 v[148:151], v64 offset:24576
	s_waitcnt lgkmcnt(3)
	v_mfma_f32_32x32x16_bf16 v[48:63], v[72:75], v[188:191], v[48:63]
	v_add_u32_e32 v64, v210, v171
	ds_read_b128 v[72:75], v64
	s_waitcnt lgkmcnt(3)
	v_mfma_f32_32x32x16_bf16 v[32:47], v[76:79], v[188:191], v[32:47]
	ds_read_b128 v[76:79], v64 offset:8192
	s_waitcnt lgkmcnt(3)
	v_mfma_f32_32x32x16_bf16 v[16:31], v[144:147], v[188:191], v[16:31]
	ds_read_b128 v[144:147], v64 offset:16384
	s_waitcnt lgkmcnt(3)
	v_mfma_f32_32x32x16_bf16 v[0:15], v[148:151], v[188:191], v[0:15]
	ds_read_b128 v[148:151], v64 offset:24576
	s_waitcnt lgkmcnt(3)
	v_mfma_f32_32x32x16_bf16 v[48:63], v[72:75], v[228:231], v[48:63]
	v_add_u32_e32 v64, v210, v172
	ds_read_b128 v[72:75], v64
	s_waitcnt lgkmcnt(3)
	v_mfma_f32_32x32x16_bf16 v[32:47], v[76:79], v[228:231], v[32:47]
	ds_read_b128 v[76:79], v64 offset:8192
	s_waitcnt lgkmcnt(3)
	v_mfma_f32_32x32x16_bf16 v[16:31], v[144:147], v[228:231], v[16:31]
	ds_read_b128 v[144:147], v64 offset:16384
	s_waitcnt lgkmcnt(3)
	v_mfma_f32_32x32x16_bf16 v[0:15], v[148:151], v[228:231], v[0:15]
	ds_read_b128 v[148:151], v64 offset:24576
	s_waitcnt lgkmcnt(3)
	v_mfma_f32_32x32x16_bf16 v[48:63], v[72:75], v[232:235], v[48:63]
	s_waitcnt lgkmcnt(2)
	v_mfma_f32_32x32x16_bf16 v[32:47], v[76:79], v[232:235], v[32:47]
	s_waitcnt lgkmcnt(1)
	v_mfma_f32_32x32x16_bf16 v[16:31], v[144:147], v[232:235], v[16:31]
	s_waitcnt lgkmcnt(0)
	s_barrier
; __device__ __forceinline__ f32x16 mfma32(bf16x8 a, bf16x8 b, f32x16 c) { return __builtin_amdgcn_mfma_f32_32x32x16_bf16(a, b, c, 0, 0, 0); }
;     ...
;             for (int nb = 0; nb < 4; ++nb) H[nb] = mfma32(t_ld8(TC, rowoff + (unsigned)nb * 8192u, rx4, 2 * s8 + h), Xs, H[nb]);
;         }
;         asm volatile("" ::: "memory"); __builtin_amdgcn_s_barrier(); asm volatile("" ::: "memory");
;         if (s + 1 < 18) {
;             const int s1 = s + 1; const bool ctx1 = s1 < 2; const int c1n = ctx1 ? (DIR ? 1 - s1 : s1) : (DIR ? 17 - s1 : s1 - 2);
;             const int chn = ctx1 ? bl * 2 + c1n : (CGR / 128) + bl * 16 + c1n;
;             tile_load(TC, bT + ((size_t)chn * 1024 + grp * 128) * 128, 128, wid, lane);
;             if (!ctx1) { const size_t rown = (size_t)chn * 128; tile_load(TA, cm + rown * 1024 + grp * 128, 1024, wid, lane); tile_load(TB, bm + rown * 1024 + grp * 128, 1024, wid, lane); }
;         }
	v_mfma_f32_32x32x16_bf16 v[0:15], v[148:151], v[232:235], v[0:15]
	s_cbranch_vccnz .LBB0_424
	s_add_i32 s33, s58, s48
	s_cmp_eq_u32 s52, 0
	s_cselect_b64 s[54:55], -1, 0
	s_and_b64 vcc, s[54:55], exec
	s_cselect_b32 s54, s39, s33
	s_ashr_i32 s55, s54, 31
	s_lshl_b64 s[62:63], s[54:55], 18
	s_add_u32 s54, s50, s62
	s_addc_u32 s55, s51, s63
	v_lshl_add_u64 v[64:65], v[96:97], 1, s[54:55]
	v_mov_b32_e32 v85, v193
	s_mov_b32 m0, s41
	v_lshl_add_u64 v[64:65], v[64:65], 0, v[84:85]
	global_load_lds_dwordx4 v[64:65], off
	v_lshl_add_u64 v[64:65], v[100:101], 1, s[54:55]
	v_mov_b32_e32 v87, v193
	v_lshl_add_u64 v[64:65], v[64:65], 0, v[86:87]
	s_mov_b32 m0, s44
	v_mov_b32_e32 v89, v193
	global_load_lds_dwordx4 v[64:65], off
	v_lshl_add_u64 v[64:65], v[104:105], 1, s[54:55]
	v_lshl_add_u64 v[64:65], v[64:65], 0, v[88:89]
	s_mov_b32 m0, s45
	v_mov_b32_e32 v91, v193
	global_load_lds_dwordx4 v[64:65], off
	v_lshl_add_u64 v[64:65], v[108:109], 1, s[54:55]
	v_lshl_add_u64 v[64:65], v[64:65], 0, v[90:91]
	s_mov_b32 m0, s46
	s_nop 0
	global_load_lds_dwordx4 v[64:65], off
	s_cbranch_vccnz .LBB0_424
	s_add_u32 s54, s56, s62
	s_addc_u32 s55, s61, s63
	v_lshlrev_b64 v[64:65], 1, v[120:121]
	v_lshl_add_u64 v[66:67], s[54:55], 0, v[64:65]
	s_mov_b32 m0, s73
	v_lshl_add_u64 v[66:67], v[66:67], 0, v[84:85]
	global_load_lds_dwordx4 v[66:67], off
	v_lshlrev_b64 v[66:67], 1, v[122:123]
	v_lshl_add_u64 v[68:69], s[54:55], 0, v[66:67]
	s_add_i32 s33, s87, 0
	v_lshl_add_u64 v[68:69], v[68:69], 0, v[86:87]
	s_mov_b32 m0, s33
	s_add_i32 s53, s68, 0
	global_load_lds_dwordx4 v[68:69], off
	v_lshlrev_b64 v[68:69], 1, v[124:125]
	v_lshl_add_u64 v[70:71], s[54:55], 0, v[68:69]
	v_lshl_add_u64 v[70:71], v[70:71], 0, v[88:89]
	s_mov_b32 m0, s53
	s_add_i32 s58, s38, 0
	global_load_lds_dwordx4 v[70:71], off
	v_lshlrev_b64 v[70:71], 1, v[126:127]
	v_lshl_add_u64 v[72:73], s[54:55], 0, v[70:71]
	s_add_u32 s54, s65, s62
	s_addc_u32 s55, s91, s63
	v_lshl_add_u64 v[72:73], v[72:73], 0, v[90:91]
	s_mov_b32 m0, s58
	v_lshl_add_u64 v[64:65], s[54:55], 0, v[64:65]
	global_load_lds_dwordx4 v[72:73], off
	v_lshl_add_u64 v[64:65], v[64:65], 0, v[84:85]
	s_add_i32 m0, s73, 0x8000
	s_nop 0
	global_load_lds_dwordx4 v[64:65], off
	v_lshl_add_u64 v[64:65], s[54:55], 0, v[66:67]
	v_lshl_add_u64 v[64:65], v[64:65], 0, v[86:87]
	s_add_i32 m0, s33, 0x8000
	s_nop 0
	global_load_lds_dwordx4 v[64:65], off
	v_lshl_add_u64 v[64:65], s[54:55], 0, v[68:69]
	v_lshl_add_u64 v[64:65], v[64:65], 0, v[88:89]
	s_add_i32 m0, s53, 0x8000
	s_nop 0
	global_load_lds_dwordx4 v[64:65], off
	v_lshl_add_u64 v[64:65], s[54:55], 0, v[70:71]
	v_lshl_add_u64 v[64:65], v[64:65], 0, v[90:91]
	s_add_i32 m0, s58, 0x8000
	s_nop 0
	global_load_lds_dwordx4 v[64:65], off
	s_branch .LBB0_424

;     ...
;             const u32x4 xr = *(const u32x4*)(XT + 16 * s8 + 8 * h);
.Lssd_a_back:
	v_permlane32_swap_b32_e32 v176, v178
	v_permlane32_swap_b32_e32 v177, v179
	v_permlane32_swap_b32_e32 v180, v182
	v_permlane32_swap_b32_e32 v181, v183
	v_permlane32_swap_b32_e32 v184, v186
	v_permlane32_swap_b32_e32 v185, v187
	v_permlane32_swap_b32_e32 v200, v202
	v_permlane32_swap_b32_e32 v201, v203
	v_permlane32_swap_b32_e32 v204, v206
	v_permlane32_swap_b32_e32 v205, v207
	v_permlane32_swap_b32_e32 v188, v190
	v_permlane32_swap_b32_e32 v189, v191
	v_permlane32_swap_b32_e32 v228, v230
	v_permlane32_swap_b32_e32 v229, v231
	v_permlane32_swap_b32_e32 v232, v234
	v_permlane32_swap_b32_e32 v233, v235
	s_nop 1
	s_branch .LBB0_441

; #define LDS_FENCE() asm volatile("s_waitcnt lgkmcnt(0)" ::: "memory")
;     ...
;         const bf16_t* XT = xT + ((size_t)chunk * 2048 + head * 64 + pb * 32 + r) * 128;
;         asm volatile("s_waitcnt vmcnt(0)" ::: "memory"); __builtin_amdgcn_s_barrier(); asm volatile("" ::: "memory");
;         if (s + 1 < 18) { const int s1 = s + 1; const bool cx1 = s1 < 2; const int c1 = cx1 ? (DIR ? 1 - s1 : s1) : (DIR ? 17 - s1 : s1 - 2);
;             const size_t rn = (size_t)(cx1 ? bl * 2 + c1 : (CGR / 128) + bl * 16 + c1) * 128;
;             nd0 = dt[(rn + lane) * 64 + DIR * 32 + head]; nd1 = dt[(rn + 64 + lane) * 64 + DIR * 32 + head]; }
;         float c0, c1, ctot;
;         if (DIR == 0) { const float p0 = wave_prefix(d0 * a_neg, lane); const float tot0 = __int_as_float(__builtin_amdgcn_readlane(__float_as_int(p0), 63)); const float p1 = wave_prefix(d1 * a_neg, lane) + tot0; c0 = p0; c1 = p1; ctot = __int_as_float(__builtin_amdgcn_readlane(__float_as_int(p1), 63)); }
;         else { const float s1 = wave_suffix(d1 * a_neg, lane); const float tot1 = __int_as_float(__builtin_amdgcn_readlane(__float_as_int(s1), 0)); const float s0 = wave_suffix(d0 * a_neg, lane) + tot1; c0 = s0; c1 = s1; ctot = __int_as_float(__builtin_amdgcn_readlane(__float_as_int(s0), 0)); }
;         cumL[lane] = c0; cumL[lane + 64] = c1; dtL[lane] = d0; dtL[lane + 64] = d1;
;         sclL[lane] = d0 * __expf(ctot - c0); sclL[lane + 64] = d1 * __expf(ctot - c1);
;         LDS_FENCE();
;         float mref[4];
;         if (DIR == 0) { mref[0] = 0.f; mref[1] = cumL[31]; mref[2] = cumL[63]; mref[3] = cumL[95]; }
;         else { mref[0] = cumL[32]; mref[1] = cumL[64]; mref[2] = cumL[96]; mref[3] = 0.f; }
; #pragma unroll
;         for (int ib = 0; ib < 4; ++ib) mref[ib] = __int_as_float(__builtin_amdgcn_readfirstlane(__float_as_int(mref[ib])));
;         if (!is_ctx) {
; #pragma unroll
;             for (int ib = 0; ib < 4; ++ib) { wL[ib * 128 + lane] = d0 * __expf(mref[ib] - c0); wL[ib * 128 + 64 + lane] = d1 * __expf(mref[ib] - c1); }
;     ...
;             for (int bidx = wid; bidx < 10; bidx += 8) {
;                 int bi2 = bidx >= 6 ? 3 : bidx >= 3 ? 2 : bidx >= 1 ? 1 : 0; int bj2 = bidx - bi2 * (bi2 + 1) / 2;
;                 const int ibk = DIR ? 3 - bi2 : bi2, jbk = DIR ? 3 - bj2 : bj2;
;                 const unsigned io2 = rowoff + (unsigned)ibk * 8192u, jo2 = rowoff + (unsigned)jbk * 8192u;
.LBB0_449:
	v_mul_f32_e64 v66, v64, -v215
	ds_bpermute_b32 v67, v188, v66
	v_mul_f32_e64 v68, v65, -v215
	ds_bpermute_b32 v69, v188, v68
	v_sub_co_u32_e64 v80, s[52:53], s61, 2
	s_waitcnt lgkmcnt(0)
	v_fma_f32 v67, v64, -v215, v67
	v_cndmask_b32_e64 v66, v67, v66, s[16:17]
	v_fma_f32 v69, v65, -v215, v69
	ds_bpermute_b32 v67, v189, v66
	v_cndmask_b32_e64 v68, v69, v68, s[16:17]
	ds_bpermute_b32 v69, v189, v68
	v_cndmask_b32_e64 v70, 0, 1, s[52:53]
	s_and_b64 s[52:53], s[52:53], exec
	s_waitcnt lgkmcnt(0)
	v_add_f32_e32 v67, v66, v67
	v_cndmask_b32_e64 v66, v67, v66, s[18:19]
	s_waitcnt lgkmcnt(0)
	v_add_f32_e32 v69, v68, v69
	ds_bpermute_b32 v67, v190, v66
	v_cndmask_b32_e64 v68, v69, v68, s[18:19]
	ds_bpermute_b32 v69, v190, v68
	v_readfirstlane_b32 s33, v80
	s_cselect_b32 s33, s61, s33
	s_waitcnt lgkmcnt(0)
	v_add_f32_e32 v67, v66, v67
	v_cndmask_b32_e64 v66, v67, v66, s[20:21]
	s_waitcnt lgkmcnt(0)
	v_add_f32_e32 v69, v68, v69
	ds_bpermute_b32 v67, v191, v66
	v_cndmask_b32_e64 v68, v69, v68, s[20:21]
	ds_bpermute_b32 v69, v191, v68
	s_cselect_b32 s51, s78, s79
	s_add_i32 s52, s51, s33
	s_waitcnt lgkmcnt(0)
	v_add_f32_e32 v67, v66, v67
	v_cndmask_b32_e64 v66, v67, v66, s[22:23]
	s_waitcnt lgkmcnt(0)
	v_add_f32_e32 v69, v68, v69
	ds_bpermute_b32 v67, v199, v66
	v_cndmask_b32_e64 v68, v69, v68, s[22:23]
	ds_bpermute_b32 v69, v199, v68
	v_mov_b32_e32 v71, s76
	v_cmp_ne_u32_e32 vcc, 1, v70
	s_waitcnt lgkmcnt(0)
	v_add_f32_e32 v67, v66, v67
	v_cndmask_b32_e64 v66, v67, v66, s[24:25]
	s_waitcnt lgkmcnt(0)
	v_add_f32_e32 v69, v68, v69
	ds_bpermute_b32 v67, v161, v66
	v_cndmask_b32_e64 v68, v69, v68, s[24:25]
	ds_bpermute_b32 v69, v161, v68
	s_ashr_i32 s53, s52, 31
	s_lshl_b64 s[80:81], s[52:53], 19
	s_waitcnt lgkmcnt(0)
	v_add_f32_e32 v67, v66, v67
	v_cndmask_b32_e64 v66, v67, v66, s[12:13]
	s_waitcnt lgkmcnt(0)
	v_add_f32_e32 v67, v68, v69
	v_readlane_b32 s33, v66, 63
	v_cndmask_b32_e64 v67, v67, v68, s[12:13]
	v_lshl_add_u64 v[148:149], v[144:145], 0, s[80:81]
	v_lshlrev_b32_e32 v132, 1, v114
	v_mov_b32_e32 v133, 0
	v_lshl_add_u64 v[132:133], v[148:149], 0, v[132:133]
	global_load_dwordx4 v[176:179], v[132:133], off
	global_load_dwordx4 v[180:183], v[132:133], off offset:32
	global_load_dwordx4 v[184:187], v[132:133], off offset:64
	global_load_dwordx4 v[200:203], v[132:133], off offset:96
	global_load_dwordx4 v[204:207], v[132:133], off offset:128
	global_load_dwordx2 v[234:235], v[132:133], off offset:160
	global_load_dwordx2 v[244:245], v[132:133], off offset:168
	global_load_dwordx2 v[158:159], v[132:133], off offset:192
	global_load_dwordx2 v[110:111], v[132:133], off offset:200
	global_load_dwordx2 v[118:119], v[132:133], off offset:224
	global_load_dwordx2 v[174:175], v[132:133], off offset:232
	v_add_f32_e32 v67, s33, v67
	ds_write2st64_b32 v162, v66, v67 offset1:1
	ds_write2st64_b32 v162, v64, v65 offset0:2 offset1:3
	v_readlane_b32 s51, v67, 63
	s_and_b64 vcc, exec, vcc
	s_nop 0
	v_sub_f32_e32 v68, s51, v66
	v_sub_f32_e32 v69, s51, v67
	v_mul_f32_e32 v68, 0x3fb8aa3b, v68
	v_mul_f32_e32 v69, 0x3fb8aa3b, v69
	v_exp_f32_e32 v68, v68
	v_exp_f32_e32 v69, v69
	v_mul_f32_e32 v68, v64, v68
	v_mul_f32_e32 v69, v65, v69
	ds_write2st64_b32 v162, v68, v69 offset0:4 offset1:5
	s_waitcnt lgkmcnt(0)
	ds_read2_b32 v[68:69], v71 offset0:31 offset1:63
	ds_read_b32 v70, v71 offset:380
	s_waitcnt lgkmcnt(0)
	v_readfirstlane_b32 s52, v68
	v_readfirstlane_b32 s53, v69
	s_waitcnt lgkmcnt(0)
	v_readfirstlane_b32 s54, v70
	s_cbranch_vccz .Lssd_b_ctx
	v_mul_f32_e64 v68, -v66, s71
	v_mul_f32_e64 v69, -v67, s71
	v_exp_f32_e32 v68, v68
	v_exp_f32_e32 v69, v69
	v_sub_f32_e32 v70, s53, v66
	v_mul_f32_e32 v70, 0x3fb8aa3b, v70
	v_mul_f32_e32 v68, v64, v68
	v_mul_f32_e32 v69, v65, v69
	ds_write2st64_b32 v162, v68, v69 offset0:6 offset1:7
	v_sub_f32_e32 v68, s52, v66
	v_sub_f32_e32 v69, s52, v67
	v_mul_f32_e32 v68, 0x3fb8aa3b, v68
	v_mul_f32_e32 v69, 0x3fb8aa3b, v69
	v_exp_f32_e32 v68, v68
	v_exp_f32_e32 v69, v69
	v_sub_f32_e32 v66, s54, v66
	v_mul_f32_e32 v66, 0x3fb8aa3b, v66
	v_mul_f32_e32 v68, v64, v68
	v_mul_f32_e32 v69, v65, v69
	ds_write2st64_b32 v162, v68, v69 offset0:8 offset1:9
	v_sub_f32_e32 v69, s53, v67
	v_sub_f32_e32 v67, s54, v67
	v_mul_f32_e32 v69, 0x3fb8aa3b, v69
	v_mul_f32_e32 v67, 0x3fb8aa3b, v67
	v_exp_f32_e32 v70, v70
	v_exp_f32_e32 v69, v69
	v_exp_f32_e32 v66, v66
	v_exp_f32_e32 v67, v67
	v_mul_f32_e32 v68, v64, v70
	v_mul_f32_e32 v69, v65, v69
	v_mul_f32_e32 v64, v64, v66
	v_mul_f32_e32 v65, v65, v67
	ds_write2st64_b32 v162, v68, v69 offset0:10 offset1:11
	ds_write2st64_b32 v162, v64, v65 offset0:12 offset1:13
	s_waitcnt lgkmcnt(0)
	s_andn2_b64 vcc, exec, s[30:31]
	s_lshl_b32 s33, s93, 13
	v_or3_b32 v81, v115, s33, v103
	v_add_u32_e32 v81, 0x8000, v81
	v_or3_b32 v82, v166, s33, v103
	v_add_u32_e32 v82, 0x8000, v82
	v_or3_b32 v83, v167, s33, v103
	v_add_u32_e32 v83, 0x8000, v83
	v_or3_b32 v84, v168, s33, v103
	v_add_u32_e32 v84, 0x8000, v84
	v_or3_b32 v85, v169, s33, v103
	v_add_u32_e32 v85, 0x8000, v85
	v_or3_b32 v86, v170, s33, v103
	v_add_u32_e32 v86, 0x8000, v86
	v_or3_b32 v87, v171, s33, v103
	v_add_u32_e32 v87, 0x8000, v87
	v_or3_b32 v88, v172, s33, v103
	v_add_u32_e32 v88, 0x8000, v88
	v_lshl_or_b32 v89, s93, 11, v165
	s_mov_b32 s33, s93
	s_cbranch_vccnz .LBB0_452
; #define LAS __attribute__((address_space(3)))
;     ...
;             for (int bidx = wid; bidx < 10; bidx += 8) {
;                 int bi2 = bidx >= 6 ? 3 : bidx >= 3 ? 2 : bidx >= 1 ? 1 : 0; int bj2 = bidx - bi2 * (bi2 + 1) / 2;
;                 const int ibk = DIR ? 3 - bi2 : bi2, jbk = DIR ? 3 - bj2 : bj2;
;                 const unsigned io2 = rowoff + (unsigned)ibk * 8192u, jo2 = rowoff + (unsigned)jbk * 8192u;
;                 f32x16 S;
; #pragma unroll
;                 for (int e = 0; e < 16; ++e) S[e] = 0.f;
; #pragma unroll
;                 for (int s8 = 0; s8 < 8; ++s8) S = mfma32(t_ld8(TB, jo2, rx4, 2 * s8 + h), t_ld8(TA, io2, rx4, 2 * s8 + h), S);
;                 asm volatile("s_nop 15\n\ts_nop 3" : "+v"(S));
;                 LAS u32x4* dstp = (LAS u32x4*)(CBL + bidx * 2048 + lane * 32);
;                 u32x4 w0, w1; w0.x = cvt_pk_bf16(S[0], S[1]); w0.y = cvt_pk_bf16(S[2], S[3]); w0.z = cvt_pk_bf16(S[4], S[5]); w0.w = cvt_pk_bf16(S[6], S[7]);
;                 w1.x = cvt_pk_bf16(S[8], S[9]); w1.y = cvt_pk_bf16(S[10], S[11]); w1.z = cvt_pk_bf16(S[12], S[13]); w1.w = cvt_pk_bf16(S[14], S[15]);
;                 dstp[0] = w0; dstp[1] = w1;
;             }
;             LDS_FENCE();
;             asm volatile("" ::: "memory"); __builtin_amdgcn_s_barrier(); asm volatile("" ::: "memory");
;     ...
;                 {
;                     const int i = 32 * ib + r; const int jb = ib;
;                     f32x16 S;
;                     { const int bi2 = DIR ? 3 - ib : ib, bj2 = DIR ? 3 - jb : jb; const LAS u32x4* srcp = (const LAS u32x4*)(CBL + (bi2 * (bi2 + 1) / 2 + bj2) * 2048 + lane * 32);
;                       const u32x4 w0 = srcp[0], w1 = srcp[1];
;                       S[0] = bflo(w0.x); S[1] = bfhi(w0.x); S[2] = bflo(w0.y); S[3] = bfhi(w0.y); S[4] = bflo(w0.z); S[5] = bfhi(w0.z); S[6] = bflo(w0.w); S[7] = bfhi(w0.w);
;                       S[8] = bflo(w1.x); S[9] = bfhi(w1.x); S[10] = bflo(w1.y); S[11] = bfhi(w1.y); S[12] = bflo(w1.z); S[13] = bfhi(w1.z); S[14] = bflo(w1.w); S[15] = bfhi(w1.w); }
; #pragma unroll
;                     for (int q = 0; q < 4; ++q) {
;                         const int j0 = 32 * jb + 8 * q + 4 * h;
;                         const f32x4 cj = *(const LAS f32x4*)(cumL + j0), dj = *(const LAS f32x4*)(dtL + j0);
; #pragma unroll
;                         for (int k = 0; k < 4; ++k) {
.LBB0_451:
	s_cmp_gt_i32 s33, 0
	s_cselect_b64 s[58:59], -1, 0
	s_nop 2
	v_cndmask_b32_e64 v64, 0, 1, s[58:59]
	s_cmp_lt_i32 s33, 3
	v_readfirstlane_b32 s55, v64
	s_cselect_b32 s55, s55, 2
	s_cmp_lt_i32 s33, 6
	s_cselect_b32 s55, s55, 3
	s_add_i32 s58, s55, 1
	s_mul_i32 s58, s58, s55
	v_lshl_add_u32 v94, s55, 13, v163
	s_lshl_b32 s55, s58, 12
	s_and_b32 s55, s55, 0x1e000
	s_sub_i32 s55, 0, s55
	v_add_u32_e32 v64, s55, v81
	ds_read_b128 v[64:67], v64
	v_add_u32_e32 v68, v94, v115
	ds_read_b128 v[68:71], v68
	v_add_u32_e32 v90, s55, v82
	ds_read_b128 v[90:93], v90
	v_add_u32_e32 v95, v94, v166
	s_waitcnt lgkmcnt(0)
	v_mfma_f32_32x32x16_bf16 v[64:79], v[64:67], v[68:71], 0
	ds_read_b128 v[150:153], v95
	v_add_u32_e32 v95, v94, v167
	v_add_u32_e32 v82, 0x10000, v82
	v_add_u32_e32 v81, 0x10000, v81
	s_waitcnt lgkmcnt(0)
	v_mfma_f32_32x32x16_bf16 v[64:79], v[90:93], v[150:153], v[64:79]
	v_add_u32_e32 v90, s55, v83
	ds_read_b128 v[90:93], v90
	ds_read_b128 v[150:153], v95
	v_add_u32_e32 v95, v94, v168
	v_add_u32_e32 v83, 0x10000, v83
	s_waitcnt lgkmcnt(0)
	v_mfma_f32_32x32x16_bf16 v[64:79], v[90:93], v[150:153], v[64:79]
	v_add_u32_e32 v90, s55, v84
	ds_read_b128 v[90:93], v90
	ds_read_b128 v[150:153], v95
	v_add_u32_e32 v95, v94, v169
	v_add_u32_e32 v84, 0x10000, v84
	s_waitcnt lgkmcnt(0)
	v_mfma_f32_32x32x16_bf16 v[64:79], v[90:93], v[150:153], v[64:79]
	v_add_u32_e32 v90, s55, v85
	ds_read_b128 v[90:93], v90
	ds_read_b128 v[150:153], v95
	v_add_u32_e32 v95, v94, v170
	v_add_u32_e32 v85, 0x10000, v85
	s_waitcnt lgkmcnt(0)
	v_mfma_f32_32x32x16_bf16 v[64:79], v[90:93], v[150:153], v[64:79]
	v_add_u32_e32 v90, s55, v86
	ds_read_b128 v[90:93], v90
	ds_read_b128 v[150:153], v95
	v_add_u32_e32 v95, v94, v171
	v_add_u32_e32 v94, v94, v172
	v_add_u32_e32 v86, 0x10000, v86
	s_waitcnt lgkmcnt(0)
	v_mfma_f32_32x32x16_bf16 v[64:79], v[90:93], v[150:153], v[64:79]
	v_add_u32_e32 v90, s55, v87
	ds_read_b128 v[90:93], v90
	ds_read_b128 v[150:153], v95
	v_add_u32_e32 v87, 0x10000, v87
	s_waitcnt lgkmcnt(0)
	v_mfma_f32_32x32x16_bf16 v[64:79], v[90:93], v[150:153], v[64:79]
	v_add_u32_e32 v90, s55, v88
	ds_read_b128 v[90:93], v90
	ds_read_b128 v[150:153], v94
	s_add_i32 s55, s33, 8
	v_add_u32_e32 v88, 0x10000, v88
	s_cmp_gt_i32 s33, 1
	s_mov_b32 s33, s55
	s_waitcnt lgkmcnt(0)
	v_mfma_f32_32x32x16_bf16 v[64:79], v[90:93], v[150:153], v[64:79]
	s_nop 15
	s_nop 3
	v_add_u32_e32 v90, 0, v89
	v_add_u32_e32 v91, 0x20000, v90
	s_nop 0
	v_cvt_pk_bf16_f32 v64, v64, v65
	s_nop 0
	v_cvt_pk_bf16_f32 v65, v66, v67
	s_nop 0
	v_cvt_pk_bf16_f32 v66, v68, v69
	s_nop 0
	v_cvt_pk_bf16_f32 v67, v70, v71
	s_nop 0
	v_cvt_pk_bf16_f32 v68, v72, v73
	s_nop 0
	v_cvt_pk_bf16_f32 v69, v74, v75
	s_nop 0
	v_cvt_pk_bf16_f32 v70, v76, v77
	s_nop 0
	v_cvt_pk_bf16_f32 v71, v78, v79
	s_nop 9
	ds_write_b128 v91, v[64:67]
	v_add_u32_e32 v64, 0x20010, v90
	v_add_u32_e32 v89, 0x4000, v89
	ds_write_b128 v64, v[68:71]
	s_cbranch_scc0 .LBB0_451
.LBB0_452:
	s_waitcnt lgkmcnt(0)
	v_add_u32_e32 v64, s41, v80
	s_barrier
	v_ashrrev_i32_e32 v65, 31, v64
	v_lshlrev_b64 v[64:65], 19, v[64:65]
	v_lshlrev_b32_e32 v192, 1, v116
	v_lshl_add_u64 v[150:151], v[142:143], 0, v[64:65]
	v_lshl_add_u64 v[152:153], v[148:149], 0, v[192:193]
	v_lshl_add_u64 v[154:155], v[146:147], 0, s[80:81]
	s_mov_b32 s58, 2
	s_mov_b32 s55, 0
	v_mov_b32_e32 v135, v214
	s_mov_b32 s66, 0
	s_waitcnt vmcnt(0)
	v_permlane32_swap_b32_e32 v176, v178
	v_permlane32_swap_b32_e32 v177, v179
	v_permlane32_swap_b32_e32 v180, v182
	v_permlane32_swap_b32_e32 v181, v183
	v_permlane32_swap_b32_e32 v184, v186
	v_permlane32_swap_b32_e32 v185, v187
	v_permlane32_swap_b32_e32 v200, v202
	v_permlane32_swap_b32_e32 v201, v203
	v_permlane32_swap_b32_e32 v204, v206
	v_permlane32_swap_b32_e32 v205, v207
	v_permlane32_swap_b32_e32 v234, v244
	v_permlane32_swap_b32_e32 v235, v245
	v_permlane32_swap_b32_e32 v158, v110
	v_permlane32_swap_b32_e32 v159, v111
	v_permlane32_swap_b32_e32 v118, v174
	v_permlane32_swap_b32_e32 v119, v175
	s_nop 1
	s_branch .LBB0_454
.LBB0_453:
	s_waitcnt lgkmcnt(0)
	v_sub_f32_e32 v80, v139, v141
	s_add_i32 s63, s64, s66
	v_mul_f32_e32 v80, 0x3fb8aa3b, v80
	v_lshl_add_u32 v85, s63, 11, v208
	v_exp_f32_e32 v84, v80
	ds_read_b128 v[80:83], v85
	ds_read_b128 v[86:89], v85 offset:16
	v_or_b32_e32 v156, s59, v116
	v_lshl_add_u32 v157, v156, 2, s76
	s_lshl_b32 s66, s59, 1
	s_waitcnt lgkmcnt(0)
	v_lshlrev_b32_e32 v85, 16, v80
	v_and_b32_e32 v192, 0xffff0000, v80
	v_lshlrev_b32_e32 v194, 16, v81
	v_and_b32_e32 v195, 0xffff0000, v81
	v_lshlrev_b32_e32 v196, 16, v82
	v_and_b32_e32 v197, 0xffff0000, v82
	v_lshlrev_b32_e32 v219, 16, v83
	v_and_b32_e32 v224, 0xffff0000, v83
	s_waitcnt lgkmcnt(0)
	v_lshlrev_b32_e32 v228, 16, v86
	v_and_b32_e32 v90, 0xffff0000, v86
	v_lshlrev_b32_e32 v91, 16, v87
	v_and_b32_e32 v92, 0xffff0000, v87
	v_lshlrev_b32_e32 v93, 16, v88
	v_and_b32_e32 v94, 0xffff0000, v88
	v_lshlrev_b32_e32 v95, 16, v89
	v_and_b32_e32 v141, 0xffff0000, v89
	ds_read_b128 v[86:89], v157 offset:512
	ds_read_b128 v[220:223], v157
	ds_read_b128 v[80:83], v157 offset:32
	s_add_i32 s59, s58, 2
	s_add_i32 s55, s55, s58
	v_add_u32_e32 v135, 0x200, v135
	s_waitcnt lgkmcnt(0)
	v_sub_f32_e32 v220, v139, v220
	v_mul_f32_e32 v220, 0x3fb8aa3b, v220
	v_exp_f32_e32 v220, v220
	s_waitcnt lgkmcnt(0)
; #define LAS __attribute__((address_space(3)))
; __device__ __forceinline__ f32x16 mfma32(bf16x8 a, bf16x8 b, f32x16 c) { return __builtin_amdgcn_mfma_f32_32x32x16_bf16(a, b, c, 0, 0, 0); }
;     ...
;                     for (int q = 0; q < 4; ++q) {
;                         const int j0 = 32 * jb + 8 * q + 4 * h;
;                         const f32x4 cj = *(const LAS f32x4*)(cumL + j0), dj = *(const LAS f32x4*)(dtL + j0);
; #pragma unroll
;                         for (int k = 0; k < 4; ++k) {
;                             const int j = j0 + k; const bool valid = DIR ? (j >= i) : (j <= i);
;                             float v = S[4 * q + k] * __expf(ci - cj[k]) * dj[k];
;                             v = valid ? v : 0.f;
;                             if (DIR == 0 && j == i) v += Dh;
;                             S[4 * q + k] = v;
;                         }
;                     }
;                     Ya = mfma32(ld44(XT + 32 * jb + 4 * h), pack_acc(S, 0), Ya); Ya = mfma32(ld44(XT + 32 * jb + 16 + 4 * h), pack_acc(S, 1), Ya);
	v_sub_f32_e32 v80, v139, v80
	v_sub_f32_e32 v81, v139, v81
	v_sub_f32_e32 v82, v139, v82
	v_mul_f32_e32 v85, v220, v85
	v_sub_f32_e32 v220, v139, v221
	v_mul_f32_e32 v220, 0x3fb8aa3b, v220
	v_exp_f32_e32 v220, v220
	v_mul_f32_e32 v85, v86, v85
	v_cndmask_b32_e64 v85, v85, 0, s[26:27]
	v_add_f32_e32 v86, v216, v85
	v_mul_f32_e32 v192, v220, v192
	v_mul_f32_e32 v87, v87, v192
	v_sub_f32_e32 v192, v139, v222
	v_mul_f32_e32 v192, 0x3fb8aa3b, v192
	v_exp_f32_e32 v192, v192
	v_cndmask_b32_e64 v85, v85, v86, s[28:29]
	v_or_b32_e32 v86, 1, v156
	v_cndmask_b32_e64 v87, 0, v87, s[14:15]
	v_mul_f32_e32 v192, v192, v194
	v_mul_f32_e32 v88, v88, v192
	v_sub_f32_e32 v192, v139, v223
	v_cmp_eq_u32_e32 vcc, v86, v137
	v_add_f32_e32 v86, v216, v87
	v_mul_f32_e32 v192, 0x3fb8aa3b, v192
	v_cndmask_b32_e32 v86, v87, v86, vcc
	v_or_b32_e32 v87, 2, v156
	v_exp_f32_e32 v192, v192
	v_sub_f32_e32 v83, v139, v83
	v_cmp_le_u32_e32 vcc, v87, v137
	v_mul_f32_e32 v80, 0x3fb8aa3b, v80
	v_mul_f32_e32 v81, 0x3fb8aa3b, v81
	v_mul_f32_e32 v82, 0x3fb8aa3b, v82
	v_mul_f32_e32 v83, 0x3fb8aa3b, v83
	v_cndmask_b32_e32 v88, 0, v88, vcc
	ds_read_b128 v[220:223], v157 offset:544
	v_exp_f32_e32 v80, v80
	v_exp_f32_e32 v81, v81
	v_exp_f32_e32 v82, v82
	v_exp_f32_e32 v83, v83
	v_cmp_eq_u32_e32 vcc, v87, v137
	v_add_f32_e32 v87, v216, v88
	v_mul_f32_e32 v192, v192, v195
	v_cndmask_b32_e32 v87, v88, v87, vcc
	v_or_b32_e32 v88, 3, v156
	v_mul_f32_e32 v89, v89, v192
	v_cmp_le_u32_e32 vcc, v88, v137
	v_mul_f32_e32 v80, v80, v196
	v_mul_f32_e32 v81, v81, v197
	v_cndmask_b32_e32 v89, 0, v89, vcc
	v_mul_f32_e32 v82, v82, v219
	v_mul_f32_e32 v83, v83, v224
	v_cmp_eq_u32_e32 vcc, v88, v137
	v_add_f32_e32 v88, v216, v89
	s_waitcnt lgkmcnt(0)
	v_mul_f32_e32 v80, v220, v80
	v_mul_f32_e32 v81, v221, v81
	v_mul_f32_e32 v82, v222, v82
	v_mul_f32_e32 v83, v223, v83
	ds_read_b128 v[220:223], v157 offset:64
	ds_read_b128 v[224:227], v157 offset:576
	v_cndmask_b32_e32 v88, v89, v88, vcc
	v_or_b32_e32 v89, 8, v156
	v_cmp_le_u32_e32 vcc, v89, v137
	s_waitcnt lgkmcnt(0)
	v_sub_f32_e32 v194, v139, v221
	v_mul_f32_e32 v194, 0x3fb8aa3b, v194
	v_cndmask_b32_e32 v80, 0, v80, vcc
	v_cmp_eq_u32_e32 vcc, v89, v137
	v_add_f32_e32 v89, v216, v80
	v_exp_f32_e32 v194, v194
	v_cndmask_b32_e32 v80, v80, v89, vcc
	v_or_b32_e32 v89, 9, v156
	v_cmp_le_u32_e32 vcc, v89, v137
	v_mul_f32_e32 v90, v194, v90
	v_sub_f32_e32 v194, v139, v222
	v_cndmask_b32_e32 v81, 0, v81, vcc
	v_cmp_eq_u32_e32 vcc, v89, v137
	v_add_f32_e32 v89, v216, v81
	v_sub_f32_e32 v192, v139, v220
	v_cndmask_b32_e32 v81, v81, v89, vcc
	v_or_b32_e32 v89, 10, v156
	v_cmp_le_u32_e32 vcc, v89, v137
	v_mul_f32_e32 v194, 0x3fb8aa3b, v194
	v_mul_f32_e32 v192, 0x3fb8aa3b, v192
	v_cndmask_b32_e32 v82, 0, v82, vcc
	v_cmp_eq_u32_e32 vcc, v89, v137
	v_add_f32_e32 v89, v216, v82
	v_exp_f32_e32 v194, v194
	v_cndmask_b32_e32 v82, v82, v89, vcc
	v_or_b32_e32 v89, 11, v156
	v_exp_f32_e32 v192, v192
	v_cmp_le_u32_e32 vcc, v89, v137
	v_mul_f32_e32 v91, v194, v91
	v_sub_f32_e32 v194, v139, v223
	v_cndmask_b32_e32 v83, 0, v83, vcc
	v_cmp_eq_u32_e32 vcc, v89, v137
	v_add_f32_e32 v89, v216, v83
	v_mul_f32_e32 v192, v192, v228
	v_cndmask_b32_e32 v83, v83, v89, vcc
	v_or_b32_e32 v89, 16, v156
	v_mul_f32_e32 v194, 0x3fb8aa3b, v194
	s_waitcnt lgkmcnt(0)
	v_mul_f32_e32 v192, v224, v192
	v_cmp_le_u32_e32 vcc, v89, v137
	v_exp_f32_e32 v194, v194
	v_mul_f32_e32 v90, v225, v90
	v_cndmask_b32_e32 v192, 0, v192, vcc
	v_cmp_eq_u32_e32 vcc, v89, v137
	v_add_f32_e32 v89, v216, v192
	v_mul_f32_e32 v92, v194, v92
	v_cndmask_b32_e32 v89, v192, v89, vcc
	v_or_b32_e32 v192, 17, v156
	v_cmp_le_u32_e32 vcc, v192, v137
	v_mul_f32_e32 v91, v226, v91
	v_mul_f32_e32 v92, v227, v92
	v_cndmask_b32_e32 v90, 0, v90, vcc
	ds_read_b128 v[220:223], v157 offset:96
	ds_read_b128 v[224:227], v157 offset:608
	v_cmp_eq_u32_e32 vcc, v192, v137
	v_add_f32_e32 v192, v216, v90
	v_pk_mul_f32 v[78:79], v[84:85], v[78:79] op_sel_hi:[0,1]
	v_cndmask_b32_e32 v90, v90, v192, vcc
	v_or_b32_e32 v192, 18, v156
	v_cmp_le_u32_e32 vcc, v192, v137
	s_waitcnt lgkmcnt(0)
	v_sub_f32_e32 v157, v139, v220
	v_mul_f32_e32 v157, 0x3fb8aa3b, v157
	v_cndmask_b32_e32 v91, 0, v91, vcc
	v_cmp_eq_u32_e32 vcc, v192, v137
	v_add_f32_e32 v192, v216, v91
	v_exp_f32_e32 v157, v157
	v_cndmask_b32_e32 v91, v91, v192, vcc
	v_or_b32_e32 v192, 19, v156
	v_cmp_le_u32_e32 vcc, v192, v137
	v_mul_f32_e32 v93, v157, v93
	s_waitcnt lgkmcnt(0)
	v_mul_f32_e32 v93, v224, v93
	v_cndmask_b32_e32 v92, 0, v92, vcc
	v_cmp_eq_u32_e32 vcc, v192, v137
	v_add_f32_e32 v192, v216, v92
	v_pk_mul_f32 v[76:77], v[84:85], v[76:77] op_sel_hi:[0,1]
	v_cndmask_b32_e32 v92, v92, v192, vcc
	v_or_b32_e32 v192, 24, v156
	v_cmp_le_u32_e32 vcc, v192, v137
	v_pk_mul_f32 v[74:75], v[84:85], v[74:75] op_sel_hi:[0,1]
	v_pk_mul_f32 v[72:73], v[84:85], v[72:73] op_sel_hi:[0,1]
	v_cndmask_b32_e32 v93, 0, v93, vcc
	v_cmp_eq_u32_e32 vcc, v192, v137
	v_sub_f32_e32 v192, v139, v221
	v_mul_f32_e32 v192, 0x3fb8aa3b, v192
	v_exp_f32_e32 v192, v192
	v_add_f32_e32 v157, v216, v93
	v_cndmask_b32_e32 v93, v93, v157, vcc
	v_or_b32_e32 v157, 25, v156
	v_mul_f32_e32 v94, v192, v94
	v_sub_f32_e32 v192, v139, v222
	v_mul_f32_e32 v192, 0x3fb8aa3b, v192
	v_exp_f32_e32 v192, v192
	v_mul_f32_e32 v94, v225, v94
	v_cmp_le_u32_e32 vcc, v157, v137
	v_sub_f32_e32 v139, v139, v223
	v_mul_f32_e32 v139, 0x3fb8aa3b, v139
	v_cndmask_b32_e32 v94, 0, v94, vcc
	v_cmp_eq_u32_e32 vcc, v157, v137
	v_add_f32_e32 v157, v216, v94
	v_exp_f32_e32 v139, v139
	v_cndmask_b32_e32 v94, v94, v157, vcc
	v_or_b32_e32 v157, 26, v156
	v_mul_f32_e32 v95, v192, v95
	v_mul_f32_e32 v95, v226, v95
	v_cmp_le_u32_e32 vcc, v157, v137
	v_or_b32_e32 v156, 27, v156
	v_mul_f32_e32 v139, v139, v141
	v_cndmask_b32_e32 v95, 0, v95, vcc
	v_cmp_eq_u32_e32 vcc, v157, v137
	v_add_f32_e32 v157, v216, v95
	v_mul_f32_e32 v139, v227, v139
	v_cndmask_b32_e32 v95, v95, v157, vcc
	v_cmp_le_u32_e32 vcc, v156, v137
	v_pk_mul_f32 v[70:71], v[84:85], v[70:71] op_sel_hi:[0,1]
	v_pk_mul_f32 v[68:69], v[84:85], v[68:69] op_sel_hi:[0,1]
	v_cndmask_b32_e32 v139, 0, v139, vcc
	v_cmp_eq_u32_e32 vcc, v156, v137
	s_cmp_eq_u32 s66, 0
	s_cbranch_scc1 .Lssd_b_dg_0
	s_cmp_eq_u32 s66, 64
	s_cbranch_scc1 .Lssd_b_dg_1
	s_cmp_eq_u32 s66, 128
	s_cbranch_scc1 .Lssd_b_dg_2
	v_mov_b32_e32 v220, v158
	v_mov_b32_e32 v221, v159
	v_mov_b32_e32 v222, v110
	v_mov_b32_e32 v223, v111
	v_mov_b32_e32 v128, v118
	v_mov_b32_e32 v129, v119
	v_mov_b32_e32 v130, v174
	v_mov_b32_e32 v131, v175
	s_branch .Lssd_b_dg_done
; __device__ __forceinline__ unsigned cvt_pk_bf16(float lo, float hi) { unsigned r; asm volatile("s_nop 0\n\tv_cvt_pk_bf16_f32 %0, %1, %2\n\ts_nop 1" : "=v"(r) : "v"(lo), "v"(hi)); return r; }
; __device__ __forceinline__ f32x16 mfma32(bf16x8 a, bf16x8 b, f32x16 c) { return __builtin_amdgcn_mfma_f32_32x32x16_bf16(a, b, c, 0, 0, 0); }
;     ...
;             for (int ib = 0; ib < 4; ++ib) {
;                 const unsigned ioff = rowoff + (unsigned)ib * 8192u;
;                 f32x16 Ya;
; #pragma unroll
;                 for (int e = 0; e < 16; ++e) Ya[e] = 0.f;
; #pragma unroll
;                 for (int nb = 0; nb < 4; ++nb)
; #pragma unroll
;                     for (int sp = 0; sp < 2; ++sp) Ya = mfma32(pack_acc(H[nb], sp), t_ld44(TA, ioff, rx4, 4 * nb + 2 * sp, h), Ya);
;     ...
;                     Ya = mfma32(ld44(XT + 32 * jb + 4 * h), pack_acc(S, 0), Ya); Ya = mfma32(ld44(XT + 32 * jb + 16 + 4 * h), pack_acc(S, 1), Ya);
;                 }
;                 asm volatile("s_nop 15\n\ts_nop 3" : "+v"(Ya));
;                 bf16_t* yr = Y + (size_t)(32 * ib + r) * 2048 + 4 * h;
; #pragma unroll
;                 for (int q = 0; q < 4; ++q) { u32x2 w; w.x = cvt_pk_bf16(Ya[4 * q], Ya[4 * q + 1]); w.y = cvt_pk_bf16(Ya[4 * q + 2], Ya[4 * q + 3]); if (MODE != 3 || w.x == 0x12345678u) *(u32x2*)(yr + 8 * q) = w; }
.Lssd_b_dg_0:
	v_mov_b32_e32 v220, v176
	v_mov_b32_e32 v221, v177
	v_mov_b32_e32 v222, v178
	v_mov_b32_e32 v223, v179
	v_mov_b32_e32 v128, v180
	v_mov_b32_e32 v129, v181
	v_mov_b32_e32 v130, v182
	v_mov_b32_e32 v131, v183
	s_branch .Lssd_b_dg_done
.Lssd_b_dg_1:
	v_mov_b32_e32 v220, v184
	v_mov_b32_e32 v221, v185
	v_mov_b32_e32 v222, v186
	v_mov_b32_e32 v223, v187
	v_mov_b32_e32 v128, v200
	v_mov_b32_e32 v129, v201
	v_mov_b32_e32 v130, v202
	v_mov_b32_e32 v131, v203
	s_branch .Lssd_b_dg_done
.Lssd_b_dg_2:
	v_mov_b32_e32 v220, v204
	v_mov_b32_e32 v221, v205
	v_mov_b32_e32 v222, v206
	v_mov_b32_e32 v223, v207
	v_mov_b32_e32 v128, v234
	v_mov_b32_e32 v129, v235
	v_mov_b32_e32 v130, v244
	v_mov_b32_e32 v131, v245
.Lssd_b_dg_done:
	v_pk_mul_f32 v[66:67], v[84:85], v[66:67] op_sel_hi:[0,1]
	v_pk_mul_f32 v[64:65], v[84:85], v[64:65] op_sel_hi:[0,1]
	s_nop 0
	v_cvt_pk_bf16_f32 v84, v85, v86
	s_nop 0
	v_cvt_pk_bf16_f32 v85, v87, v88
	s_nop 0
	v_cvt_pk_bf16_f32 v86, v80, v81
	s_nop 1
	s_nop 0
	v_cvt_pk_bf16_f32 v87, v82, v83
	s_nop 1
	v_mfma_f32_32x32x16_bf16 v[64:79], v[220:223], v[84:87], v[64:79]
	v_add_f32_e32 v141, v216, v139
	v_cndmask_b32_e32 v139, v139, v141, vcc
	s_nop 0
	v_cvt_pk_bf16_f32 v84, v89, v90
	s_nop 0
	v_cvt_pk_bf16_f32 v85, v91, v92
	s_nop 0
	v_cvt_pk_bf16_f32 v86, v93, v94
	s_nop 0
	v_cvt_pk_bf16_f32 v87, v95, v139
	s_nop 1
	v_lshlrev_b32_e32 v192, 12, v137
	v_mfma_f32_32x32x16_bf16 v[64:79], v[128:131], v[84:87], v[64:79]
	s_nop 15
	s_nop 3
	v_lshl_add_u64 v[80:81], v[150:151], 0, v[192:193]
	s_nop 0
	v_cvt_pk_bf16_f32 v64, v64, v65
	s_nop 0
	v_cvt_pk_bf16_f32 v65, v66, v67
	s_cmp_eq_u32 s62, 4
	s_nop 9
	global_store_dwordx2 v[80:81], v[64:65], off
	s_nop 0
	v_cvt_pk_bf16_f32 v64, v68, v69
	s_nop 0
	v_cvt_pk_bf16_f32 v65, v70, v71
	global_store_dwordx2 v[80:81], v[64:65], off offset:16
	s_nop 0
	v_cvt_pk_bf16_f32 v64, v72, v73
	s_nop 0
	v_cvt_pk_bf16_f32 v65, v74, v75
	s_mov_b32 s58, s59
	s_mov_b32 s66, s33
	global_store_dwordx2 v[80:81], v[64:65], off offset:32
	v_cvt_pk_bf16_f32 v64, v76, v77
	v_cvt_pk_bf16_f32 v65, v78, v79
	s_nop 1
	global_store_dwordx2 v[80:81], v[64:65], off offset:48
	s_cbranch_scc1 .Lssd_b_back
.LBB0_454:
	v_lshl_add_u32 v88, s66, 13, v211
	v_add_u32_e32 v68, v88, v107
	v_xor_b32_e32 v173, 0x10, v107
	v_add_u32_e32 v70, v88, v173
	s_nop 0
	v_cvt_pk_bf16_f32 v64, v48, v49
	s_nop 0
	v_cvt_pk_bf16_f32 v65, v50, v51
	s_nop 0
	v_cvt_pk_bf16_f32 v66, v52, v53
	s_nop 0
	v_cvt_pk_bf16_f32 v67, v54, v55
	ds_read_b64 v[68:69], v68
	ds_read_b64 v[70:71], v70
	s_waitcnt lgkmcnt(0)
	v_mfma_f32_32x32x16_bf16 v[64:79], v[64:67], v[68:71], 0
	v_xor_b32_e32 v173, 0x20, v107
	v_add_u32_e32 v84, v88, v173
	v_xor_b32_e32 v173, 0x30, v107
	v_add_u32_e32 v86, v88, v173
	s_nop 0
	v_cvt_pk_bf16_f32 v80, v56, v57
	s_nop 0
	v_cvt_pk_bf16_f32 v81, v58, v59
	s_nop 0
	v_cvt_pk_bf16_f32 v82, v60, v61
	s_nop 0
	v_cvt_pk_bf16_f32 v83, v62, v63
	ds_read_b64 v[84:85], v84
	ds_read_b64 v[86:87], v86
	s_waitcnt lgkmcnt(0)
	v_mfma_f32_32x32x16_bf16 v[64:79], v[80:83], v[84:87], v[64:79]
	v_xor_b32_e32 v173, 0x40, v107
	v_add_u32_e32 v84, v88, v173
	v_xor_b32_e32 v173, 0x50, v107
	v_add_u32_e32 v86, v88, v173
	s_nop 0
	v_cvt_pk_bf16_f32 v80, v32, v33
	s_nop 0
	v_cvt_pk_bf16_f32 v81, v34, v35
	s_nop 0
	v_cvt_pk_bf16_f32 v82, v36, v37
	s_nop 0
	v_cvt_pk_bf16_f32 v83, v38, v39
	ds_read_b64 v[84:85], v84
	ds_read_b64 v[86:87], v86
	s_waitcnt lgkmcnt(0)
	v_mfma_f32_32x32x16_bf16 v[64:79], v[80:83], v[84:87], v[64:79]
	v_xor_b32_e32 v173, 0x60, v107
	v_add_u32_e32 v84, v88, v173
	v_xor_b32_e32 v173, 0x70, v107
	v_add_u32_e32 v86, v88, v173
	s_nop 0
	v_cvt_pk_bf16_f32 v80, v40, v41
	s_nop 0
	v_cvt_pk_bf16_f32 v81, v42, v43
	s_nop 0
	v_cvt_pk_bf16_f32 v82, v44, v45
	s_nop 0
	v_cvt_pk_bf16_f32 v83, v46, v47
	ds_read_b64 v[84:85], v84
	ds_read_b64 v[86:87], v86
	s_waitcnt lgkmcnt(0)
	v_mfma_f32_32x32x16_bf16 v[64:79], v[80:83], v[84:87], v[64:79]
	v_xor_b32_e32 v173, 0x80, v107
	v_add_u32_e32 v84, v88, v173
	v_xor_b32_e32 v173, 0x90, v107
	v_add_u32_e32 v86, v88, v173
	s_nop 0
	v_cvt_pk_bf16_f32 v80, v16, v17
	s_nop 0
	v_cvt_pk_bf16_f32 v81, v18, v19
	s_nop 0
	v_cvt_pk_bf16_f32 v82, v20, v21
	s_nop 0
	v_cvt_pk_bf16_f32 v83, v22, v23
	ds_read_b64 v[84:85], v84
	ds_read_b64 v[86:87], v86
	s_waitcnt lgkmcnt(0)
	v_mfma_f32_32x32x16_bf16 v[64:79], v[80:83], v[84:87], v[64:79]
	v_xor_b32_e32 v173, 0xa0, v107
	v_add_u32_e32 v84, v88, v173
	v_xor_b32_e32 v173, 0xb0, v107
	v_add_u32_e32 v86, v88, v173
	s_nop 0
	v_cvt_pk_bf16_f32 v80, v24, v25
	s_nop 0
	v_cvt_pk_bf16_f32 v81, v26, v27
	s_nop 0
	v_cvt_pk_bf16_f32 v82, v28, v29
	s_nop 0
	v_cvt_pk_bf16_f32 v83, v30, v31
	ds_read_b64 v[84:85], v84
	ds_read_b64 v[86:87], v86
	s_waitcnt lgkmcnt(0)
	v_mfma_f32_32x32x16_bf16 v[64:79], v[80:83], v[84:87], v[64:79]
	v_xor_b32_e32 v173, 0xc0, v107
	v_add_u32_e32 v84, v88, v173
	v_xor_b32_e32 v173, 0xd0, v107
	v_add_u32_e32 v86, v88, v173
	s_nop 0
	v_cvt_pk_bf16_f32 v80, v0, v1
	s_nop 0
	v_cvt_pk_bf16_f32 v81, v2, v3
	s_nop 0
	v_cvt_pk_bf16_f32 v82, v4, v5
	s_nop 0
	v_cvt_pk_bf16_f32 v83, v6, v7
	ds_read_b64 v[84:85], v84
	ds_read_b64 v[86:87], v86
	s_waitcnt lgkmcnt(0)
	v_mfma_f32_32x32x16_bf16 v[64:79], v[80:83], v[84:87], v[64:79]
	v_xor_b32_e32 v173, 0xe0, v107
	v_add_u32_e32 v84, v88, v173
	v_xor_b32_e32 v173, 0xf0, v107
	v_add_u32_e32 v86, v88, v173
	s_nop 0
	v_cvt_pk_bf16_f32 v80, v8, v9
	s_nop 0
	v_cvt_pk_bf16_f32 v81, v10, v11
	s_nop 0
	v_cvt_pk_bf16_f32 v82, v12, v13
	s_nop 0
	v_cvt_pk_bf16_f32 v83, v14, v15
	ds_read_b64 v[84:85], v84
	ds_read_b64 v[86:87], v86
	s_waitcnt lgkmcnt(0)
	v_mfma_f32_32x32x16_bf16 v[64:79], v[80:83], v[84:87], v[64:79]
	s_lshl_b32 s59, s66, 5
	v_or_b32_e32 v137, s59, v99
	v_lshl_add_u32 v80, v137, 2, s76
	ds_read_b32 v139, v80
	s_cmp_lt_i32 s66, 1
	s_cbranch_scc1 .LBB0_458
	s_cmp_eq_u32 s66, 1
	s_mov_b64 s[62:63], -1
	s_cbranch_scc0 .LBB0_457
	s_mov_b64 s[62:63], 0

; #define LAS __attribute__((address_space(3)))
; __device__ __forceinline__ float bflo(unsigned w) { return __uint_as_float(w << 16); }
; __device__ __forceinline__ float bfhi(unsigned w) { return __uint_as_float(w & 0xffff0000u); }
; __device__ __forceinline__ f32x16 mfma32(bf16x8 a, bf16x8 b, f32x16 c) { return __builtin_amdgcn_mfma_f32_32x32x16_bf16(a, b, c, 0, 0, 0); }
;     ...
;                 for (int jb = (DIR ? ib + 1 : 0); jb < (DIR ? 4 : ib); ++jb) {
;                     f32x16 S;
;                     { const int bi2 = DIR ? 3 - ib : ib, bj2 = DIR ? 3 - jb : jb; const LAS u32x4* srcp = (const LAS u32x4*)(CBL + (bi2 * (bi2 + 1) / 2 + bj2) * 2048 + lane * 32);
;                       const u32x4 w0 = srcp[0], w1 = srcp[1];
;                       S[0] = bflo(w0.x); S[1] = bfhi(w0.x); S[2] = bflo(w0.y); S[3] = bfhi(w0.y); S[4] = bflo(w0.z); S[5] = bfhi(w0.z); S[6] = bflo(w0.w); S[7] = bfhi(w0.w);
;                       S[8] = bflo(w1.x); S[9] = bfhi(w1.x); S[10] = bflo(w1.y); S[11] = bfhi(w1.y); S[12] = bflo(w1.z); S[13] = bfhi(w1.z); S[14] = bflo(w1.w); S[15] = bfhi(w1.w); }
; #pragma unroll
;                     for (int q = 0; q < 4; ++q) { const f32x4 w4 = *(const LAS f32x4*)(wL + ib * 128 + 32 * jb + 8 * q + 4 * h);
; #pragma unroll
;                         for (int k = 0; k < 4; ++k) S[4 * q + k] *= w4[k]; }
;                     Ya = mfma32(ld44(XT + 32 * jb + 4 * h), pack_acc(S, 0), Ya); Ya = mfma32(ld44(XT + 32 * jb + 16 + 4 * h), pack_acc(S, 1), Ya);
.LBB0_464:
	v_add_u32_e32 v194, 0, v192
	v_add_u32_e32 v195, 0x20000, v194
	ds_read_b128 v[220:223], v195
	v_add_u32_e32 v194, 0x20010, v194
	v_add_u32_e32 v248, 0, v219
	ds_read_b128 v[224:227], v194
	s_add_i32 s62, s62, -1
	s_waitcnt lgkmcnt(0)
	v_lshlrev_b32_e32 v194, 16, v220
	v_and_b32_e32 v195, 0xffff0000, v220
	v_add_u32_e32 v220, 0x18600, v248
	v_lshlrev_b32_e32 v196, 16, v221
	v_and_b32_e32 v197, 0xffff0000, v221
	v_lshlrev_b32_e32 v228, 16, v222
	v_and_b32_e32 v229, 0xffff0000, v222
	v_lshlrev_b32_e32 v230, 16, v223
	v_and_b32_e32 v231, 0xffff0000, v223
	ds_read_b128 v[220:223], v220
	s_waitcnt lgkmcnt(1)
	v_lshlrev_b32_e32 v232, 16, v224
	v_and_b32_e32 v224, 0xffff0000, v224
	v_lshlrev_b32_e32 v233, 16, v225
	v_and_b32_e32 v225, 0xffff0000, v225
	s_waitcnt lgkmcnt(0)
	v_mul_f32_e32 v194, v220, v194
	v_add_u32_e32 v220, 0x18620, v248
	v_mul_f32_e32 v195, v221, v195
	v_mul_f32_e32 v196, v222, v196
	v_mul_f32_e32 v197, v223, v197
	ds_read_b128 v[220:223], v220
	v_lshlrev_b32_e32 v246, 16, v226
	v_and_b32_e32 v226, 0xffff0000, v226
	v_lshlrev_b32_e32 v247, 16, v227
	v_and_b32_e32 v227, 0xffff0000, v227
	s_waitcnt lgkmcnt(0)
	v_mul_f32_e32 v228, v220, v228
	v_add_u32_e32 v220, 0x18640, v248
	v_mul_f32_e32 v229, v221, v229
	v_mul_f32_e32 v230, v222, v230
	v_mul_f32_e32 v231, v223, v231
	ds_read_b128 v[220:223], v220
	v_add_u32_e32 v192, 0x800, v192
	v_add_u32_e32 v219, 0x80, v219
	s_cmp_eq_u32 s62, 0
	s_waitcnt lgkmcnt(0)
	v_mul_f32_e32 v232, v220, v232
	v_add_u32_e32 v220, 0x18660, v248
	v_mul_f32_e32 v249, v221, v224
	v_mul_f32_e32 v233, v222, v233
	v_mul_f32_e32 v250, v223, v225
	ds_read_b128 v[220:223], v220
	s_waitcnt lgkmcnt(0)
	v_mul_f32_e32 v246, v220, v246
	v_mul_f32_e32 v248, v221, v226
	v_mul_f32_e32 v247, v222, v247
	v_mul_f32_e32 v251, v223, v227
	s_sub_i32 s100, s66, s62
	s_cmp_eq_u32 s100, 1
	s_cbranch_scc1 .Lssd_b_jb_0
	s_cmp_eq_u32 s100, 2
	s_cbranch_scc1 .Lssd_b_jb_1
	v_mov_b32_e32 v220, v204
	v_mov_b32_e32 v221, v205
	v_mov_b32_e32 v222, v206
	v_mov_b32_e32 v223, v207
	v_mov_b32_e32 v128, v234
	v_mov_b32_e32 v129, v235
	v_mov_b32_e32 v130, v244
	v_mov_b32_e32 v131, v245
	s_branch .Lssd_b_jb_done

; __device__ __forceinline__ f32x16 mfma32(bf16x8 a, bf16x8 b, f32x16 c) { return __builtin_amdgcn_mfma_f32_32x32x16_bf16(a, b, c, 0, 0, 0); }
;     ...
;                     Ya = mfma32(ld44(XT + 32 * jb + 4 * h), pack_acc(S, 0), Ya); Ya = mfma32(ld44(XT + 32 * jb + 16 + 4 * h), pack_acc(S, 1), Ya);
.Lssd_b_jb_1:
	v_mov_b32_e32 v220, v184
	v_mov_b32_e32 v221, v185
	v_mov_b32_e32 v222, v186
	v_mov_b32_e32 v223, v187
	v_mov_b32_e32 v128, v200
	v_mov_b32_e32 v129, v201
	v_mov_b32_e32 v130, v202
	v_mov_b32_e32 v131, v203
.Lssd_b_jb_done:
	s_cmp_eq_u32 s62, 0
	s_nop 0
	v_cvt_pk_bf16_f32 v224, v194, v195
	s_nop 0
	v_cvt_pk_bf16_f32 v225, v196, v197
	s_nop 0
	v_cvt_pk_bf16_f32 v226, v228, v229
	s_nop 1
	s_nop 0
	v_cvt_pk_bf16_f32 v227, v230, v231
	s_nop 1
	v_mfma_f32_32x32x16_bf16 v[64:79], v[220:223], v[224:227], v[64:79]
	s_nop 0
	v_cvt_pk_bf16_f32 v224, v232, v249
	s_nop 0
	v_cvt_pk_bf16_f32 v225, v233, v250
	s_nop 0
	v_cvt_pk_bf16_f32 v226, v246, v248
	s_nop 0
	v_cvt_pk_bf16_f32 v227, v247, v251
	s_nop 1
	v_lshl_add_u64 v[156:157], v[156:157], 0, 64
	v_mfma_f32_32x32x16_bf16 v[64:79], v[128:131], v[224:227], v[64:79]
	s_cbranch_scc0 .LBB0_464
	s_mov_b32 s62, s33
	s_branch .LBB0_453

; __device__ __forceinline__ unsigned cvt_pk_bf16(float lo, float hi) { unsigned r; asm volatile("s_nop 0\n\tv_cvt_pk_bf16_f32 %0, %1, %2\n\ts_nop 1" : "=v"(r) : "v"(lo), "v"(hi)); return r; }
; #define LAS __attribute__((address_space(3)))
; __device__ __forceinline__ float bflo(unsigned w) { return __uint_as_float(w << 16); }
; __device__ __forceinline__ float bfhi(unsigned w) { return __uint_as_float(w & 0xffff0000u); }
;     ...
;         const float dec = __expf(ctot);
; #pragma unroll
;         for (int nb = 0; nb < 4; ++nb)
; #pragma unroll
;             for (int e = 0; e < 16; ++e) H[nb][e] *= dec;
; #pragma unroll
;         for (int s8 = 0; s8 < ((MODE == 2 || MODE == 3) ? 0 : 8); ++s8) {
;             const u32x4 xr = *(const u32x4*)(XT + 16 * s8 + 8 * h);
;             const f32x4 sa = *(const LAS f32x4*)(sclL + 16 * s8 + 8 * h), sb = *(const LAS f32x4*)(sclL + 16 * s8 + 8 * h + 4);
;             u32x4 w; w.x = cvt_pk_bf16(bflo(xr.x) * sa.x, bfhi(xr.x) * sa.y); w.y = cvt_pk_bf16(bflo(xr.y) * sa.z, bfhi(xr.y) * sa.w);
;             w.z = cvt_pk_bf16(bflo(xr.z) * sb.x, bfhi(xr.z) * sb.y); w.w = cvt_pk_bf16(bflo(xr.w) * sb.z, bfhi(xr.w) * sb.w);
;             const bf16x8 Xs = __builtin_bit_cast(bf16x8, w);
.LBB0_468:
	v_mul_f32_e32 v64, s51, v239
	v_exp_f32_e32 v64, v64
	v_lshlrev_b32_e32 v192, 1, v114
	v_add_u32_e32 v66, v209, v164
	s_andn2_b64 vcc, exec, s[0:1]
	v_pk_mul_f32 v[62:63], v[62:63], v[64:65] op_sel_hi:[1,0]
	v_pk_mul_f32 v[60:61], v[60:61], v[64:65] op_sel_hi:[1,0]
	v_pk_mul_f32 v[58:59], v[58:59], v[64:65] op_sel_hi:[1,0]
	v_pk_mul_f32 v[56:57], v[56:57], v[64:65] op_sel_hi:[1,0]
	v_pk_mul_f32 v[54:55], v[54:55], v[64:65] op_sel_hi:[1,0]
	v_pk_mul_f32 v[52:53], v[52:53], v[64:65] op_sel_hi:[1,0]
	v_pk_mul_f32 v[50:51], v[50:51], v[64:65] op_sel_hi:[1,0]
	v_pk_mul_f32 v[48:49], v[48:49], v[64:65] op_sel_hi:[1,0]
	v_pk_mul_f32 v[46:47], v[46:47], v[64:65] op_sel_hi:[1,0]
	v_pk_mul_f32 v[44:45], v[44:45], v[64:65] op_sel_hi:[1,0]
	v_pk_mul_f32 v[42:43], v[42:43], v[64:65] op_sel_hi:[1,0]
	v_pk_mul_f32 v[40:41], v[40:41], v[64:65] op_sel_hi:[1,0]
	v_pk_mul_f32 v[38:39], v[38:39], v[64:65] op_sel_hi:[1,0]
	v_pk_mul_f32 v[36:37], v[36:37], v[64:65] op_sel_hi:[1,0]
	v_pk_mul_f32 v[34:35], v[34:35], v[64:65] op_sel_hi:[1,0]
	v_pk_mul_f32 v[32:33], v[32:33], v[64:65] op_sel_hi:[1,0]
	v_pk_mul_f32 v[30:31], v[30:31], v[64:65] op_sel_hi:[1,0]
	v_pk_mul_f32 v[28:29], v[28:29], v[64:65] op_sel_hi:[1,0]
	v_pk_mul_f32 v[26:27], v[26:27], v[64:65] op_sel_hi:[1,0]
	v_pk_mul_f32 v[24:25], v[24:25], v[64:65] op_sel_hi:[1,0]
	v_pk_mul_f32 v[22:23], v[22:23], v[64:65] op_sel_hi:[1,0]
	v_pk_mul_f32 v[20:21], v[20:21], v[64:65] op_sel_hi:[1,0]
	v_pk_mul_f32 v[18:19], v[18:19], v[64:65] op_sel_hi:[1,0]
	v_pk_mul_f32 v[16:17], v[16:17], v[64:65] op_sel_hi:[1,0]
	v_pk_mul_f32 v[14:15], v[14:15], v[64:65] op_sel_hi:[1,0]
	v_pk_mul_f32 v[12:13], v[12:13], v[64:65] op_sel_hi:[1,0]
	v_pk_mul_f32 v[10:11], v[10:11], v[64:65] op_sel_hi:[1,0]
	v_pk_mul_f32 v[8:9], v[8:9], v[64:65] op_sel_hi:[1,0]
	v_pk_mul_f32 v[6:7], v[6:7], v[64:65] op_sel_hi:[1,0]
	v_pk_mul_f32 v[4:5], v[4:5], v[64:65] op_sel_hi:[1,0]
	v_pk_mul_f32 v[2:3], v[2:3], v[64:65] op_sel_hi:[1,0]
	v_pk_mul_f32 v[0:1], v[0:1], v[64:65] op_sel_hi:[1,0]
	v_lshl_add_u64 v[64:65], v[148:149], 0, v[192:193]
	s_waitcnt lgkmcnt(0)
	ds_read_b128 v[72:75], v66 offset:1024
	ds_read_b128 v[76:79], v66 offset:1040
	ds_read_b128 v[80:83], v66 offset:1088
	ds_read_b128 v[84:87], v66 offset:1104
	s_waitcnt lgkmcnt(2)
	v_lshlrev_b32_e32 v67, 16, v176
	v_and_b32_e32 v65, 0xffff0000, v176
	v_mul_f32_e32 v67, v72, v67
	v_mul_f32_e32 v65, v73, v65
	v_cvt_pk_bf16_f32 v176, v67, v65
	v_lshlrev_b32_e32 v67, 16, v177
	v_and_b32_e32 v65, 0xffff0000, v177
	v_mul_f32_e32 v67, v74, v67
	v_mul_f32_e32 v65, v75, v65
	v_cvt_pk_bf16_f32 v177, v67, v65
	v_lshlrev_b32_e32 v67, 16, v178
	v_and_b32_e32 v65, 0xffff0000, v178
	v_mul_f32_e32 v67, v76, v67
	v_mul_f32_e32 v65, v77, v65
	v_cvt_pk_bf16_f32 v178, v67, v65
	v_lshlrev_b32_e32 v67, 16, v179
	v_and_b32_e32 v65, 0xffff0000, v179
	v_mul_f32_e32 v67, v78, v67
	v_mul_f32_e32 v65, v79, v65
	v_cvt_pk_bf16_f32 v179, v67, v65
	ds_read_b128 v[72:75], v66 offset:1152
	ds_read_b128 v[76:79], v66 offset:1168
	s_waitcnt lgkmcnt(2)
	v_lshlrev_b32_e32 v67, 16, v180
	v_and_b32_e32 v65, 0xffff0000, v180
	v_mul_f32_e32 v67, v80, v67
	v_mul_f32_e32 v65, v81, v65
	v_cvt_pk_bf16_f32 v180, v67, v65
	v_lshlrev_b32_e32 v67, 16, v181
	v_and_b32_e32 v65, 0xffff0000, v181
	v_mul_f32_e32 v67, v82, v67
	v_mul_f32_e32 v65, v83, v65
	v_cvt_pk_bf16_f32 v181, v67, v65
	v_lshlrev_b32_e32 v67, 16, v182
	v_and_b32_e32 v65, 0xffff0000, v182
	v_mul_f32_e32 v67, v84, v67
	v_mul_f32_e32 v65, v85, v65
	v_cvt_pk_bf16_f32 v182, v67, v65
	v_lshlrev_b32_e32 v67, 16, v183
	v_and_b32_e32 v65, 0xffff0000, v183
	v_mul_f32_e32 v67, v86, v67
	v_mul_f32_e32 v65, v87, v65
	v_cvt_pk_bf16_f32 v183, v67, v65
	ds_read_b128 v[80:83], v66 offset:1216
	ds_read_b128 v[84:87], v66 offset:1232
	s_waitcnt lgkmcnt(2)
	v_lshlrev_b32_e32 v67, 16, v184
	v_and_b32_e32 v65, 0xffff0000, v184
	v_mul_f32_e32 v67, v72, v67
	v_mul_f32_e32 v65, v73, v65
	v_cvt_pk_bf16_f32 v184, v67, v65
	v_lshlrev_b32_e32 v67, 16, v185
	v_and_b32_e32 v65, 0xffff0000, v185
	v_mul_f32_e32 v67, v74, v67
	v_mul_f32_e32 v65, v75, v65
	v_cvt_pk_bf16_f32 v185, v67, v65
	v_lshlrev_b32_e32 v67, 16, v186
	v_and_b32_e32 v65, 0xffff0000, v186
	v_mul_f32_e32 v67, v76, v67
	v_mul_f32_e32 v65, v77, v65
	v_cvt_pk_bf16_f32 v186, v67, v65
	v_lshlrev_b32_e32 v67, 16, v187
	v_and_b32_e32 v65, 0xffff0000, v187
	v_mul_f32_e32 v67, v78, v67
	v_mul_f32_e32 v65, v79, v65
	v_cvt_pk_bf16_f32 v187, v67, v65
	ds_read_b128 v[72:75], v66 offset:1280
	ds_read_b128 v[76:79], v66 offset:1296
	s_waitcnt lgkmcnt(2)
	v_lshlrev_b32_e32 v67, 16, v200
	v_and_b32_e32 v65, 0xffff0000, v200
	v_mul_f32_e32 v67, v80, v67
	v_mul_f32_e32 v65, v81, v65
	v_cvt_pk_bf16_f32 v200, v67, v65
	v_lshlrev_b32_e32 v67, 16, v201
	v_and_b32_e32 v65, 0xffff0000, v201
	v_mul_f32_e32 v67, v82, v67
	v_mul_f32_e32 v65, v83, v65
	v_cvt_pk_bf16_f32 v201, v67, v65
	v_lshlrev_b32_e32 v67, 16, v202
	v_and_b32_e32 v65, 0xffff0000, v202
	v_mul_f32_e32 v67, v84, v67
	v_mul_f32_e32 v65, v85, v65
	v_cvt_pk_bf16_f32 v202, v67, v65
	v_lshlrev_b32_e32 v67, 16, v203
	v_and_b32_e32 v65, 0xffff0000, v203
	v_mul_f32_e32 v67, v86, v67
	v_mul_f32_e32 v65, v87, v65
	v_cvt_pk_bf16_f32 v203, v67, v65
	ds_read_b128 v[80:83], v66 offset:1344
	ds_read_b128 v[84:87], v66 offset:1360
	s_waitcnt lgkmcnt(2)
; __device__ __forceinline__ unsigned cvt_pk_bf16(float lo, float hi) { unsigned r; asm volatile("s_nop 0\n\tv_cvt_pk_bf16_f32 %0, %1, %2\n\ts_nop 1" : "=v"(r) : "v"(lo), "v"(hi)); return r; }
; #define LAS __attribute__((address_space(3)))
; __device__ __forceinline__ float bflo(unsigned w) { return __uint_as_float(w << 16); }
; __device__ __forceinline__ float bfhi(unsigned w) { return __uint_as_float(w & 0xffff0000u); }
; __device__ __forceinline__ f32x16 mfma32(bf16x8 a, bf16x8 b, f32x16 c) { return __builtin_amdgcn_mfma_f32_32x32x16_bf16(a, b, c, 0, 0, 0); }
;     ...
;         for (int s8 = 0; s8 < ((MODE == 2 || MODE == 3) ? 0 : 8); ++s8) {
;             const u32x4 xr = *(const u32x4*)(XT + 16 * s8 + 8 * h);
;             const f32x4 sa = *(const LAS f32x4*)(sclL + 16 * s8 + 8 * h), sb = *(const LAS f32x4*)(sclL + 16 * s8 + 8 * h + 4);
;             u32x4 w; w.x = cvt_pk_bf16(bflo(xr.x) * sa.x, bfhi(xr.x) * sa.y); w.y = cvt_pk_bf16(bflo(xr.y) * sa.z, bfhi(xr.y) * sa.w);
;             w.z = cvt_pk_bf16(bflo(xr.z) * sb.x, bfhi(xr.z) * sb.y); w.w = cvt_pk_bf16(bflo(xr.w) * sb.z, bfhi(xr.w) * sb.w);
;             const bf16x8 Xs = __builtin_bit_cast(bf16x8, w);
; #pragma unroll
;             for (int nb = 0; nb < 4; ++nb) H[nb] = mfma32(t_ld8(TC, rowoff + (unsigned)nb * 8192u, rx4, 2 * s8 + h), Xs, H[nb]);
;         }
	v_lshlrev_b32_e32 v67, 16, v204
	v_and_b32_e32 v65, 0xffff0000, v204
	v_mul_f32_e32 v67, v72, v67
	v_mul_f32_e32 v65, v73, v65
	v_cvt_pk_bf16_f32 v204, v67, v65
	v_lshlrev_b32_e32 v67, 16, v205
	v_and_b32_e32 v65, 0xffff0000, v205
	v_mul_f32_e32 v67, v74, v67
	v_mul_f32_e32 v65, v75, v65
	v_cvt_pk_bf16_f32 v205, v67, v65
	v_lshlrev_b32_e32 v67, 16, v206
	v_and_b32_e32 v65, 0xffff0000, v206
	v_mul_f32_e32 v67, v76, v67
	v_mul_f32_e32 v65, v77, v65
	v_cvt_pk_bf16_f32 v206, v67, v65
	v_lshlrev_b32_e32 v67, 16, v207
	v_and_b32_e32 v65, 0xffff0000, v207
	v_mul_f32_e32 v67, v78, v67
	v_mul_f32_e32 v65, v79, v65
	v_cvt_pk_bf16_f32 v207, v67, v65
	ds_read_b128 v[72:75], v66 offset:1408
	ds_read_b128 v[76:79], v66 offset:1424
	s_waitcnt lgkmcnt(2)
	v_lshlrev_b32_e32 v67, 16, v234
	v_and_b32_e32 v65, 0xffff0000, v234
	v_mul_f32_e32 v67, v80, v67
	v_mul_f32_e32 v65, v81, v65
	v_cvt_pk_bf16_f32 v220, v67, v65
	v_lshlrev_b32_e32 v67, 16, v235
	v_and_b32_e32 v65, 0xffff0000, v235
	v_mul_f32_e32 v67, v82, v67
	v_mul_f32_e32 v65, v83, v65
	v_cvt_pk_bf16_f32 v221, v67, v65
	v_lshlrev_b32_e32 v67, 16, v244
	v_and_b32_e32 v65, 0xffff0000, v244
	v_mul_f32_e32 v67, v84, v67
	v_mul_f32_e32 v65, v85, v65
	v_cvt_pk_bf16_f32 v222, v67, v65
	v_lshlrev_b32_e32 v67, 16, v245
	v_and_b32_e32 v65, 0xffff0000, v245
	v_mul_f32_e32 v67, v86, v67
	v_mul_f32_e32 v65, v87, v65
	v_cvt_pk_bf16_f32 v223, v67, v65
	ds_read_b128 v[80:83], v66 offset:1472
	ds_read_b128 v[84:87], v66 offset:1488
	s_waitcnt lgkmcnt(2)
	v_lshlrev_b32_e32 v67, 16, v158
	v_and_b32_e32 v65, 0xffff0000, v158
	v_mul_f32_e32 v67, v72, v67
	v_mul_f32_e32 v65, v73, v65
	v_cvt_pk_bf16_f32 v224, v67, v65
	v_lshlrev_b32_e32 v67, 16, v159
	v_and_b32_e32 v65, 0xffff0000, v159
	v_mul_f32_e32 v67, v74, v67
	v_mul_f32_e32 v65, v75, v65
	v_cvt_pk_bf16_f32 v225, v67, v65
	v_lshlrev_b32_e32 v67, 16, v110
	v_and_b32_e32 v65, 0xffff0000, v110
	v_mul_f32_e32 v67, v76, v67
	v_mul_f32_e32 v65, v77, v65
	v_cvt_pk_bf16_f32 v226, v67, v65
	v_lshlrev_b32_e32 v67, 16, v111
	v_and_b32_e32 v65, 0xffff0000, v111
	v_mul_f32_e32 v67, v78, v67
	v_mul_f32_e32 v65, v79, v65
	v_cvt_pk_bf16_f32 v227, v67, v65
	s_waitcnt lgkmcnt(0)
	v_lshlrev_b32_e32 v67, 16, v118
	v_and_b32_e32 v65, 0xffff0000, v118
	v_mul_f32_e32 v67, v80, v67
	v_mul_f32_e32 v65, v81, v65
	v_cvt_pk_bf16_f32 v128, v67, v65
	v_lshlrev_b32_e32 v67, 16, v119
	v_and_b32_e32 v65, 0xffff0000, v119
	v_mul_f32_e32 v67, v82, v67
	v_mul_f32_e32 v65, v83, v65
	v_cvt_pk_bf16_f32 v129, v67, v65
	v_lshlrev_b32_e32 v67, 16, v174
	v_and_b32_e32 v65, 0xffff0000, v174
	v_mul_f32_e32 v67, v84, v67
	v_mul_f32_e32 v65, v85, v65
	v_cvt_pk_bf16_f32 v130, v67, v65
	v_lshlrev_b32_e32 v67, 16, v175
	v_and_b32_e32 v65, 0xffff0000, v175
	v_mul_f32_e32 v67, v86, v67
	v_mul_f32_e32 v65, v87, v65
	v_cvt_pk_bf16_f32 v131, v67, v65
	s_nop 1
	v_add_u32_e32 v64, v210, v115
	ds_read_b128 v[72:75], v64
	ds_read_b128 v[76:79], v64 offset:8192
	ds_read_b128 v[80:83], v64 offset:16384
	ds_read_b128 v[84:87], v64 offset:24576
	s_waitcnt lgkmcnt(3)
	v_mfma_f32_32x32x16_bf16 v[48:63], v[72:75], v[176:179], v[48:63]
	v_add_u32_e32 v64, v210, v166
	ds_read_b128 v[72:75], v64
	s_waitcnt lgkmcnt(3)
	v_mfma_f32_32x32x16_bf16 v[32:47], v[76:79], v[176:179], v[32:47]
	ds_read_b128 v[76:79], v64 offset:8192
	s_waitcnt lgkmcnt(3)
	v_mfma_f32_32x32x16_bf16 v[16:31], v[80:83], v[176:179], v[16:31]
	ds_read_b128 v[80:83], v64 offset:16384
	s_waitcnt lgkmcnt(3)
	v_mfma_f32_32x32x16_bf16 v[0:15], v[84:87], v[176:179], v[0:15]
	ds_read_b128 v[84:87], v64 offset:24576
	s_waitcnt lgkmcnt(3)
	v_mfma_f32_32x32x16_bf16 v[48:63], v[72:75], v[180:183], v[48:63]
	v_add_u32_e32 v64, v210, v167
	ds_read_b128 v[72:75], v64
	s_waitcnt lgkmcnt(3)
	v_mfma_f32_32x32x16_bf16 v[32:47], v[76:79], v[180:183], v[32:47]
	ds_read_b128 v[76:79], v64 offset:8192
	s_waitcnt lgkmcnt(3)
	v_mfma_f32_32x32x16_bf16 v[16:31], v[80:83], v[180:183], v[16:31]
	ds_read_b128 v[80:83], v64 offset:16384
	s_waitcnt lgkmcnt(3)
	v_mfma_f32_32x32x16_bf16 v[0:15], v[84:87], v[180:183], v[0:15]
	ds_read_b128 v[84:87], v64 offset:24576
	s_waitcnt lgkmcnt(3)
	v_mfma_f32_32x32x16_bf16 v[48:63], v[72:75], v[184:187], v[48:63]
	v_add_u32_e32 v64, v210, v168
	ds_read_b128 v[72:75], v64
	s_waitcnt lgkmcnt(3)
	v_mfma_f32_32x32x16_bf16 v[32:47], v[76:79], v[184:187], v[32:47]
	ds_read_b128 v[76:79], v64 offset:8192
	s_waitcnt lgkmcnt(3)
	v_mfma_f32_32x32x16_bf16 v[16:31], v[80:83], v[184:187], v[16:31]
	ds_read_b128 v[80:83], v64 offset:16384
	s_waitcnt lgkmcnt(3)
	v_mfma_f32_32x32x16_bf16 v[0:15], v[84:87], v[184:187], v[0:15]
	ds_read_b128 v[84:87], v64 offset:24576
	s_waitcnt lgkmcnt(3)
	v_mfma_f32_32x32x16_bf16 v[48:63], v[72:75], v[200:203], v[48:63]
	v_add_u32_e32 v64, v210, v169
	ds_read_b128 v[72:75], v64
	s_waitcnt lgkmcnt(3)
	v_mfma_f32_32x32x16_bf16 v[32:47], v[76:79], v[200:203], v[32:47]
	ds_read_b128 v[76:79], v64 offset:8192
	s_waitcnt lgkmcnt(3)
; __device__ __forceinline__ f32x16 mfma32(bf16x8 a, bf16x8 b, f32x16 c) { return __builtin_amdgcn_mfma_f32_32x32x16_bf16(a, b, c, 0, 0, 0); }
;     ...
;             for (int nb = 0; nb < 4; ++nb) H[nb] = mfma32(t_ld8(TC, rowoff + (unsigned)nb * 8192u, rx4, 2 * s8 + h), Xs, H[nb]);
;         }
;         asm volatile("" ::: "memory"); __builtin_amdgcn_s_barrier(); asm volatile("" ::: "memory");
;         if (s + 1 < 18) {
;             const int s1 = s + 1; const bool ctx1 = s1 < 2; const int c1n = ctx1 ? (DIR ? 1 - s1 : s1) : (DIR ? 17 - s1 : s1 - 2);
;             const int chn = ctx1 ? bl * 2 + c1n : (CGR / 128) + bl * 16 + c1n;
;             tile_load(TC, bT + ((size_t)chn * 1024 + grp * 128) * 128, 128, wid, lane);
;             if (!ctx1) { const size_t rown = (size_t)chn * 128; tile_load(TA, cm + rown * 1024 + grp * 128, 1024, wid, lane); tile_load(TB, bm + rown * 1024 + grp * 128, 1024, wid, lane); }
;         }
	v_mfma_f32_32x32x16_bf16 v[16:31], v[80:83], v[200:203], v[16:31]
	ds_read_b128 v[80:83], v64 offset:16384
	s_waitcnt lgkmcnt(3)
	v_mfma_f32_32x32x16_bf16 v[0:15], v[84:87], v[200:203], v[0:15]
	ds_read_b128 v[84:87], v64 offset:24576
	s_waitcnt lgkmcnt(3)
	v_mfma_f32_32x32x16_bf16 v[48:63], v[72:75], v[204:207], v[48:63]
	v_add_u32_e32 v64, v210, v170
	ds_read_b128 v[72:75], v64
	s_waitcnt lgkmcnt(3)
	v_mfma_f32_32x32x16_bf16 v[32:47], v[76:79], v[204:207], v[32:47]
	ds_read_b128 v[76:79], v64 offset:8192
	s_waitcnt lgkmcnt(3)
	v_mfma_f32_32x32x16_bf16 v[16:31], v[80:83], v[204:207], v[16:31]
	ds_read_b128 v[80:83], v64 offset:16384
	s_waitcnt lgkmcnt(3)
	v_mfma_f32_32x32x16_bf16 v[0:15], v[84:87], v[204:207], v[0:15]
	ds_read_b128 v[84:87], v64 offset:24576
	s_waitcnt lgkmcnt(3)
	v_mfma_f32_32x32x16_bf16 v[48:63], v[72:75], v[220:223], v[48:63]
	v_add_u32_e32 v64, v210, v171
	ds_read_b128 v[72:75], v64
	s_waitcnt lgkmcnt(3)
	v_mfma_f32_32x32x16_bf16 v[32:47], v[76:79], v[220:223], v[32:47]
	ds_read_b128 v[76:79], v64 offset:8192
	s_waitcnt lgkmcnt(3)
	v_mfma_f32_32x32x16_bf16 v[16:31], v[80:83], v[220:223], v[16:31]
	ds_read_b128 v[80:83], v64 offset:16384
	s_waitcnt lgkmcnt(3)
	v_mfma_f32_32x32x16_bf16 v[0:15], v[84:87], v[220:223], v[0:15]
	ds_read_b128 v[84:87], v64 offset:24576
	s_waitcnt lgkmcnt(3)
	v_mfma_f32_32x32x16_bf16 v[48:63], v[72:75], v[224:227], v[48:63]
	v_add_u32_e32 v64, v210, v172
	ds_read_b128 v[72:75], v64
	s_waitcnt lgkmcnt(3)
	v_mfma_f32_32x32x16_bf16 v[32:47], v[76:79], v[224:227], v[32:47]
	ds_read_b128 v[76:79], v64 offset:8192
	s_waitcnt lgkmcnt(3)
	v_mfma_f32_32x32x16_bf16 v[16:31], v[80:83], v[224:227], v[16:31]
	ds_read_b128 v[80:83], v64 offset:16384
	s_waitcnt lgkmcnt(3)
	v_mfma_f32_32x32x16_bf16 v[0:15], v[84:87], v[224:227], v[0:15]
	ds_read_b128 v[84:87], v64 offset:24576
	s_waitcnt lgkmcnt(3)
	v_mfma_f32_32x32x16_bf16 v[48:63], v[72:75], v[128:131], v[48:63]
	s_waitcnt lgkmcnt(2)
	v_mfma_f32_32x32x16_bf16 v[32:47], v[76:79], v[128:131], v[32:47]
	s_waitcnt lgkmcnt(1)
	v_mfma_f32_32x32x16_bf16 v[16:31], v[80:83], v[128:131], v[16:31]
	s_waitcnt lgkmcnt(0)
	s_barrier
	v_mfma_f32_32x32x16_bf16 v[0:15], v[84:87], v[128:131], v[0:15]
	s_cbranch_vccnz .LBB0_446
	v_sub_co_u32_e64 v64, s[0:1], s61, 1
	s_and_b64 vcc, s[0:1], exec
	v_readfirstlane_b32 s0, v64
	s_cselect_b32 s0, 1, s0
	s_cselect_b32 s1, s78, s79
	s_add_i32 s0, s1, s0
	s_ashr_i32 s1, s0, 31
	s_lshl_b64 s[0:1], s[0:1], 18
	s_add_u32 s52, s56, s0
	s_addc_u32 s53, s46, s1
	v_lshl_add_u64 v[64:65], v[96:97], 1, s[52:53]
	v_mov_b32_e32 v135, v193
	s_mov_b32 m0, s39
	v_lshl_add_u64 v[64:65], v[64:65], 0, v[134:135]
	global_load_lds_dwordx4 v[64:65], off
	v_lshl_add_u64 v[64:65], v[100:101], 1, s[52:53]
	v_mov_b32_e32 v137, v193
	v_lshl_add_u64 v[64:65], v[64:65], 0, v[136:137]
	s_mov_b32 m0, s91
	v_mov_b32_e32 v139, v193
	global_load_lds_dwordx4 v[64:65], off
	v_lshl_add_u64 v[64:65], v[104:105], 1, s[52:53]
	v_lshl_add_u64 v[64:65], v[64:65], 0, v[138:139]
	s_mov_b32 m0, s44
	v_mov_b32_e32 v141, v193
	global_load_lds_dwordx4 v[64:65], off
	v_lshl_add_u64 v[64:65], v[108:109], 1, s[52:53]
	v_lshl_add_u64 v[64:65], v[64:65], 0, v[140:141]
	s_mov_b32 m0, s45
	s_nop 0
	global_load_lds_dwordx4 v[64:65], off
	s_cbranch_vccnz .LBB0_446
	s_add_u32 s52, s43, s0
	s_addc_u32 s53, s48, s1
	v_lshlrev_b64 v[64:65], 1, v[120:121]
	v_lshl_add_u64 v[66:67], s[52:53], 0, v[64:65]
	s_mov_b32 m0, s73
	v_lshl_add_u64 v[66:67], v[66:67], 0, v[134:135]
	global_load_lds_dwordx4 v[66:67], off
	v_lshlrev_b64 v[66:67], 1, v[122:123]
	v_lshl_add_u64 v[68:69], s[52:53], 0, v[66:67]
	s_add_i32 s33, s87, 0
	v_lshl_add_u64 v[68:69], v[68:69], 0, v[136:137]
	s_mov_b32 m0, s33
	s_add_i32 s51, s68, 0
	global_load_lds_dwordx4 v[68:69], off
	v_lshlrev_b64 v[68:69], 1, v[124:125]
	v_lshl_add_u64 v[70:71], s[52:53], 0, v[68:69]
	v_lshl_add_u64 v[70:71], v[70:71], 0, v[138:139]
	s_mov_b32 m0, s51
	s_nop 0
	global_load_lds_dwordx4 v[70:71], off
	v_lshlrev_b64 v[70:71], 1, v[126:127]
	v_lshl_add_u64 v[72:73], s[52:53], 0, v[70:71]
	s_add_i32 s52, s38, 0
	s_add_u32 s0, s49, s0
	s_addc_u32 s1, s50, s1
	v_lshl_add_u64 v[72:73], v[72:73], 0, v[140:141]
	s_mov_b32 m0, s52
	v_lshl_add_u64 v[64:65], s[0:1], 0, v[64:65]
	global_load_lds_dwordx4 v[72:73], off
	v_lshl_add_u64 v[64:65], v[64:65], 0, v[134:135]
	s_add_i32 m0, s73, 0x8000
	s_nop 0
	global_load_lds_dwordx4 v[64:65], off
	v_lshl_add_u64 v[64:65], s[0:1], 0, v[66:67]
	v_lshl_add_u64 v[64:65], v[64:65], 0, v[136:137]
	s_add_i32 m0, s33, 0x8000
	s_nop 0
	global_load_lds_dwordx4 v[64:65], off
	v_lshl_add_u64 v[64:65], s[0:1], 0, v[68:69]
	v_lshl_add_u64 v[64:65], v[64:65], 0, v[138:139]
	s_add_i32 m0, s51, 0x8000
	s_nop 0
	global_load_lds_dwordx4 v[64:65], off
	v_lshl_add_u64 v[64:65], s[0:1], 0, v[70:71]
	v_lshl_add_u64 v[64:65], v[64:65], 0, v[140:141]
	s_add_i32 m0, s52, 0x8000
	s_nop 0
	global_load_lds_dwordx4 v[64:65], off
	s_branch .LBB0_446
	s_branch .LBB0_471

;     ...
;             const u32x4 xr = *(const u32x4*)(XT + 16 * s8 + 8 * h);
.Lssd_b_back:
	v_permlane32_swap_b32_e32 v176, v178
	v_permlane32_swap_b32_e32 v177, v179
	v_permlane32_swap_b32_e32 v180, v182
	v_permlane32_swap_b32_e32 v181, v183
	v_permlane32_swap_b32_e32 v184, v186
	v_permlane32_swap_b32_e32 v185, v187
	v_permlane32_swap_b32_e32 v200, v202
	v_permlane32_swap_b32_e32 v201, v203
	v_permlane32_swap_b32_e32 v204, v206
	v_permlane32_swap_b32_e32 v205, v207
	v_permlane32_swap_b32_e32 v234, v244
	v_permlane32_swap_b32_e32 v235, v245
	v_permlane32_swap_b32_e32 v158, v110
	v_permlane32_swap_b32_e32 v159, v111
	v_permlane32_swap_b32_e32 v118, v174
	v_permlane32_swap_b32_e32 v119, v175
	s_nop 1
	s_branch .LBB0_468

; __device__ __forceinline__ f32x16 mfma32(bf16x8 a, bf16x8 b, f32x16 c) { return __builtin_amdgcn_mfma_f32_32x32x16_bf16(a, b, c, 0, 0, 0); }
; template <int DIR>
; __device__ __forceinline__ void lru_item(const Params& p, int item, int lane) {
;     ...
;     for (int t = 0; t < 72; ++t) {
;         const bool is_ctx = t < 8;
;         const int tile = is_ctx ? (DIR ? 7 - t : t) : (DIR ? 71 - t : t - 8);
;         f32x16 Aa, Ai, Au;
; #pragma unroll
;         for (int e = 0; e < 16; ++e) { Aa[e] = 0.f; Ai[e] = 0.f; Au[e] = 0.f; }
; #pragma unroll
;         for (int s = 0; s < 8; ++s) { Aa = mfma32(uf[s], Wa[s], Aa); Ai = mfma32(uf[s], Wi[s], Ai); }
;         Au = mfma32(ui0, I0, Au); Au = mfma32(ui1, I1, Au);
;         { const int tn = t + 1 < 72 ? t + 1 : 71; const bf16_t* up = uu + (tile_row0(tn) + r) * 1024 + blk * 128 + 8 * h;
; #pragma unroll
;           for (int s = 0; s < 8; ++s) uf[s] = ld8(up + 16 * s);
;           ui0 = ld8(up + 32 * db); ui1 = ld8(up + 32 * db + 16); }
;         float av[16], bv[16];
; #pragma unroll
;         for (int e = 0; e < 16; e += 2) {
;             const f32x2 xa = (f32x2){Aa[e], Aa[e + 1]} + ba, xi = (f32x2){Ai[e], Ai[e + 1]} + bi, uv = (f32x2){Au[e], Au[e + 1]};
;             const f32x2 ta = xa * -1.4426950408889634f, ti = xi * -1.4426950408889634f;
;             f32x2 da, di; da.x = __builtin_amdgcn_exp2f(ta.x); da.y = __builtin_amdgcn_exp2f(ta.y); di.x = __builtin_amdgcn_exp2f(ti.x); di.y = __builtin_amdgcn_exp2f(ti.y);
;             da = da + 1.f; di = di + 1.f;
;             f32x2 ra, ri; ra.x = __builtin_amdgcn_rcpf(da.x); ra.y = __builtin_amdgcn_rcpf(da.y); ri.x = __builtin_amdgcn_rcpf(di.x); ri.y = __builtin_amdgcn_rcpf(di.y);
;             const f32x2 la = ra * (c8 * 1.4426950408889634f);
;             f32x2 a; a.x = __builtin_amdgcn_exp2f(la.x); a.y = __builtin_amdgcn_exp2f(la.y);
;             f32x2 om = 1.f - a * a; om.x = fmaxf(om.x, 0.f); om.y = fmaxf(om.y, 0.f);
;             f32x2 sq; sq.x = __builtin_amdgcn_sqrtf(om.x); sq.y = __builtin_amdgcn_sqrtf(om.y);
.LBB0_481:
	s_waitcnt vmcnt(0)
	v_mfma_f32_32x32x16_bf16 v[32:47], v[156:159], v[56:59], 0
	v_mov_b64_e32 v[186:187], v[126:127]
	v_mov_b64_e32 v[184:185], v[124:125]
	s_mov_b32 s15, s12
	s_add_i32 s12, s12, 1
	s_cmp_lg_u32 s8, 0xffb90000
	s_cselect_b32 s22, s12, 0x47
	s_cmp_lt_u32 s22, 8
	v_mfma_f32_32x32x16_bf16 v[32:47], v[148:151], v[64:67], v[32:47]
	s_cselect_b64 s[18:19], -1, 0
	s_and_b64 s[20:21], s[18:19], exec
	s_cselect_b32 s20, 7, 0x47
	s_sub_i32 s20, s20, s22
	s_lshl_b32 s20, s20, 5
	s_ashr_i32 s21, s20, 31
	s_and_b64 s[18:19], s[18:19], exec
	v_mfma_f32_32x32x16_bf16 v[16:31], v[156:159], v[60:63], 0
	s_cselect_b32 s19, s4, s13
	s_cselect_b32 s18, s5, s14
	s_add_u32 s19, s19, s20
	s_addc_u32 s18, s18, s21
	v_mov_b32_e32 v125, s18
	v_or_b32_e32 v124, s19, v160
	v_lshlrev_b64 v[124:125], 11, v[124:125]
	v_mfma_f32_32x32x16_bf16 v[32:47], v[144:147], v[72:75], v[32:47]
	s_cmp_lt_u32 s15, 8
	v_mfma_f32_32x32x16_bf16 v[16:31], v[148:151], v[68:71], v[16:31]
	v_mfma_f32_32x32x16_bf16 v[32:47], v[140:143], v[80:83], v[32:47]
	v_mfma_f32_32x32x16_bf16 v[16:31], v[144:147], v[76:79], v[16:31]
	v_mfma_f32_32x32x16_bf16 v[32:47], v[136:139], v[88:91], v[32:47]
	v_mfma_f32_32x32x16_bf16 v[16:31], v[140:143], v[84:87], v[16:31]
	v_mfma_f32_32x32x16_bf16 v[32:47], v[132:135], v[96:99], v[32:47]
	v_mfma_f32_32x32x16_bf16 v[16:31], v[136:139], v[92:95], v[16:31]
	v_mfma_f32_32x32x16_bf16 v[32:47], v[128:131], v[104:107], v[32:47]
	v_mfma_f32_32x32x16_bf16 v[16:31], v[132:135], v[100:103], v[16:31]
	v_mfma_f32_32x32x16_bf16 v[32:47], v[184:187], v[112:115], v[32:47]
	v_mfma_f32_32x32x16_bf16 v[16:31], v[128:131], v[108:111], v[16:31]
	s_nop 10
	v_add_f32_e64 v32, v170, v32
	v_add_f32_e64 v33, v171, v33
	v_add_f32_e64 v34, v170, v34
	v_add_f32_e64 v35, v171, v35
	v_mul_f32_e64 v32, v32, s90
	v_mul_f32_e64 v33, v33, s90
	v_pk_mul_f32 v[34:35], v[34:35], s[90:91] op_sel_hi:[1,0]
	v_exp_f32_e32 v32, v32
	v_exp_f32_e32 v33, v33
	v_exp_f32_e32 v34, v34
	v_mfma_f32_32x32x16_bf16 v[16:31], v[184:187], v[116:119], v[16:31]
	v_exp_f32_e32 v35, v35
	v_pk_add_f32 v[32:33], v[32:33], 1.0 op_sel_hi:[1,0]
	v_pk_add_f32 v[36:37], v[170:171], v[36:37]
	v_rcp_f32_e32 v32, v32
	v_rcp_f32_e32 v33, v33
	v_pk_mul_f32 v[36:37], v[36:37], s[90:91] op_sel_hi:[1,0]
	s_nop 5
	v_pk_add_f32 v[16:17], v[172:173], v[16:17]
	v_mfma_f32_32x32x16_bf16 v[0:15], v[152:155], v[48:51], 0
	v_mul_f32_e64 v16, v16, s90
	v_mul_f32_e64 v17, v17, s90
	v_exp_f32_e32 v36, v36
	v_exp_f32_e32 v184, v16
	v_exp_f32_e32 v185, v17
	v_pk_mul_f32 v[16:17], v[176:177], v[32:33]
	v_exp_f32_e32 v37, v37
	v_exp_f32_e32 v16, v16
	v_exp_f32_e32 v17, v17
	v_mfma_f32_32x32x16_bf16 v[0:15], v[120:123], v[52:55], v[0:15]
	v_add_f32_e64 v32, v184, 1.0
	v_add_f32_e64 v33, v185, 1.0
	v_lshl_add_u64 v[152:153], v[174:175], 0, v[124:125]
	v_fma_f32 v184, -v16, v16, 1.0
	v_fma_f32 v185, -v17, v17, 1.0
	v_rcp_f32_e32 v32, v32
	v_rcp_f32_e32 v33, v33
	v_max_f32_e32 v184, 0, v184
	v_max_f32_e32 v185, 0, v185
	v_sqrt_f32_e32 v184, v184
	v_sqrt_f32_e32 v185, v185
	s_nop 0
	v_pk_mul_f32 v[0:1], v[32:33], v[0:1]
	global_load_dwordx4 v[156:159], v[152:153], off
	global_load_dwordx4 v[148:151], v[152:153], off offset:32
	global_load_dwordx4 v[144:147], v[152:153], off offset:64
	global_load_dwordx4 v[140:143], v[152:153], off offset:96
	global_load_dwordx4 v[136:139], v[152:153], off offset:128
	global_load_dwordx4 v[132:135], v[152:153], off offset:160
	global_load_dwordx4 v[128:131], v[152:153], off offset:192
	global_load_dwordx4 v[124:127], v[152:153], off offset:224
	v_lshl_add_u64 v[120:121], v[152:153], 0, s[66:67]
	v_pk_mul_f32 v[32:33], v[0:1], v[184:185]
	v_pk_add_f32 v[0:1], v[172:173], v[18:19]
	v_pk_add_f32 v[18:19], v[34:35], 1.0 op_sel_hi:[1,0]
	v_pk_mul_f32 v[0:1], v[0:1], s[90:91] op_sel_hi:[1,0]
	v_rcp_f32_e32 v18, v18
	v_rcp_f32_e32 v19, v19
	v_exp_f32_e32 v34, v0
	v_exp_f32_e32 v35, v1
	global_load_dwordx4 v[152:155], v[120:121], off
	s_nop 0
	global_load_dwordx4 v[120:123], v[120:121], off offset:32
	v_pk_mul_f32 v[0:1], v[176:177], v[18:19]
	v_pk_add_f32 v[18:19], v[34:35], 1.0 op_sel_hi:[1,0]
	v_exp_f32_e32 v0, v0
	v_exp_f32_e32 v1, v1
	v_rcp_f32_e32 v18, v18
	v_rcp_f32_e32 v19, v19
	v_pk_fma_f32 v[34:35], v[0:1], v[0:1], 1.0 op_sel_hi:[1,1,0] neg_lo:[1,0,0] neg_hi:[1,0,0]
	s_nop 0
	v_max_f32_e32 v34, 0, v34
	v_max_f32_e32 v35, 0, v35
	v_pk_mul_f32 v[2:3], v[18:19], v[2:3]
	v_pk_add_f32 v[18:19], v[172:173], v[20:21]
	v_pk_add_f32 v[20:21], v[36:37], 1.0 op_sel_hi:[1,0]
	v_sqrt_f32_e32 v34, v34
	v_sqrt_f32_e32 v35, v35
	v_rcp_f32_e32 v20, v20
	v_rcp_f32_e32 v21, v21
	v_pk_mul_f32 v[18:19], v[18:19], s[90:91] op_sel_hi:[1,0]
	v_pk_mul_f32 v[2:3], v[2:3], v[34:35]
	v_exp_f32_e32 v34, v18
	v_exp_f32_e32 v35, v19
	v_pk_mul_f32 v[18:19], v[176:177], v[20:21]
	v_pk_add_f32 v[36:37], v[170:171], v[38:39]
	v_exp_f32_e32 v18, v18
	v_exp_f32_e32 v19, v19
	v_pk_add_f32 v[20:21], v[34:35], 1.0 op_sel_hi:[1,0]
	v_pk_mul_f32 v[36:37], v[36:37], s[90:91] op_sel_hi:[1,0]
	v_rcp_f32_e32 v20, v20
	v_pk_fma_f32 v[34:35], v[18:19], v[18:19], 1.0 op_sel_hi:[1,1,0] neg_lo:[1,0,0] neg_hi:[1,0,0]
	v_rcp_f32_e32 v21, v21
	v_max_f32_e32 v34, 0, v34
	v_max_f32_e32 v35, 0, v35
	v_sqrt_f32_e32 v34, v34
	v_sqrt_f32_e32 v35, v35
	v_exp_f32_e32 v36, v36
	v_exp_f32_e32 v37, v37
	v_pk_mul_f32 v[4:5], v[20:21], v[4:5]
	s_nop 0
	v_pk_mul_f32 v[20:21], v[4:5], v[34:35]
	v_pk_add_f32 v[4:5], v[172:173], v[22:23]
	v_pk_add_f32 v[22:23], v[36:37], 1.0 op_sel_hi:[1,0]
	v_pk_mul_f32 v[4:5], v[4:5], s[90:91] op_sel_hi:[1,0]
	v_rcp_f32_e32 v22, v22
	v_rcp_f32_e32 v23, v23
	v_exp_f32_e32 v34, v4
	v_exp_f32_e32 v35, v5
; template <int DIR>
; __device__ __forceinline__ void lru_item(const Params& p, int item, int lane) {
;     ...
;         for (int e = 0; e < 16; e += 2) {
;             const f32x2 xa = (f32x2){Aa[e], Aa[e + 1]} + ba, xi = (f32x2){Ai[e], Ai[e + 1]} + bi, uv = (f32x2){Au[e], Au[e + 1]};
;             const f32x2 ta = xa * -1.4426950408889634f, ti = xi * -1.4426950408889634f;
;             f32x2 da, di; da.x = __builtin_amdgcn_exp2f(ta.x); da.y = __builtin_amdgcn_exp2f(ta.y); di.x = __builtin_amdgcn_exp2f(ti.x); di.y = __builtin_amdgcn_exp2f(ti.y);
;             da = da + 1.f; di = di + 1.f;
;             f32x2 ra, ri; ra.x = __builtin_amdgcn_rcpf(da.x); ra.y = __builtin_amdgcn_rcpf(da.y); ri.x = __builtin_amdgcn_rcpf(di.x); ri.y = __builtin_amdgcn_rcpf(di.y);
;             const f32x2 la = ra * (c8 * 1.4426950408889634f);
;             f32x2 a; a.x = __builtin_amdgcn_exp2f(la.x); a.y = __builtin_amdgcn_exp2f(la.y);
;             f32x2 om = 1.f - a * a; om.x = fmaxf(om.x, 0.f); om.y = fmaxf(om.y, 0.f);
;             f32x2 sq; sq.x = __builtin_amdgcn_sqrtf(om.x); sq.y = __builtin_amdgcn_sqrtf(om.y);
;             const f32x2 b = sq * (ri * uv);
;             const int k0 = DIR ? 15 - e : e, k1 = DIR ? 14 - e : e + 1;
;             av[k0] = a.x; bv[k0] = b.x; av[k1] = a.y; bv[k1] = b.y;
;         }
;         const int hh = DIR ? 1 - h : h;
;         float Ag[4], Bg[4];
; #pragma unroll
;         for (int q = 0; q < 4; q += 2) {
;             f32x2 A = (f32x2){av[4 * q], av[4 * q + 4]}, B = (f32x2){bv[4 * q], bv[4 * q + 4]};
; #pragma unroll
;             for (int k = 1; k < 4; ++k) { const f32x2 ak = (f32x2){av[4 * q + k], av[4 * q + 4 + k]}, bk = (f32x2){bv[4 * q + k], bv[4 * q + 4 + k]};
;                 A = A * ak; B = B * ak + bk; av[4 * q + k] = A.x; av[4 * q + 4 + k] = A.y; bv[4 * q + k] = B.x; bv[4 * q + 4 + k] = B.y; }
;             Ag[q] = A.x; Ag[q + 1] = A.y; Bg[q] = B.x; Bg[q + 1] = B.y;
;         }
;         float Ap[4], Bp[4];
; #pragma unroll
;         for (int q = 0; q < 4; ++q) { Ap[q] = lane_get(Ag[q], lane ^ 32); Bp[q] = lane_get(Bg[q], lane ^ 32); }
;         float st = hst, hs[4];
; #pragma unroll
;         for (int Gi = 0; Gi < 8; ++Gi) {
;             const int q = Gi >> 1; const bool own = (hh == (Gi & 1));
;             const float A = own ? Ag[q] : Ap[q], B = own ? Bg[q] : Bp[q];
;             if (own) hs[q] = st;
	v_pk_add_f32 v[36:37], v[170:171], v[40:41]
	v_pk_mul_f32 v[4:5], v[176:177], v[22:23]
	v_pk_mul_f32 v[36:37], v[36:37], s[90:91] op_sel_hi:[1,0]
	v_pk_add_f32 v[22:23], v[34:35], 1.0 op_sel_hi:[1,0]
	v_exp_f32_e32 v4, v4
	v_exp_f32_e32 v5, v5
	v_rcp_f32_e32 v22, v22
	v_rcp_f32_e32 v23, v23
	v_exp_f32_e32 v36, v36
	v_exp_f32_e32 v37, v37
	v_pk_fma_f32 v[34:35], v[4:5], v[4:5], 1.0 op_sel_hi:[1,1,0] neg_lo:[1,0,0] neg_hi:[1,0,0]
	v_pk_mul_f32 v[6:7], v[22:23], v[6:7]
	v_pk_add_f32 v[22:23], v[172:173], v[24:25]
	v_pk_add_f32 v[24:25], v[36:37], 1.0 op_sel_hi:[1,0]
	v_max_f32_e32 v34, 0, v34
	v_max_f32_e32 v35, 0, v35
	v_rcp_f32_e32 v24, v24
	v_rcp_f32_e32 v25, v25
	v_sqrt_f32_e32 v34, v34
	v_sqrt_f32_e32 v35, v35
	v_pk_mul_f32 v[22:23], v[22:23], s[90:91] op_sel_hi:[1,0]
	v_pk_mul_f32 v[24:25], v[176:177], v[24:25]
	v_exp_f32_e32 v22, v22
	v_exp_f32_e32 v23, v23
	v_pk_mul_f32 v[6:7], v[6:7], v[34:35]
	v_exp_f32_e32 v34, v24
	v_exp_f32_e32 v35, v25
	v_pk_add_f32 v[36:37], v[170:171], v[42:43]
	v_pk_add_f32 v[22:23], v[22:23], 1.0 op_sel_hi:[1,0]
	v_pk_mul_f32 v[36:37], v[36:37], s[90:91] op_sel_hi:[1,0]
	v_rcp_f32_e32 v22, v22
	v_rcp_f32_e32 v23, v23
	v_exp_f32_e32 v36, v36
	v_exp_f32_e32 v37, v37
	v_pk_fma_f32 v[24:25], v[34:35], v[34:35], 1.0 op_sel_hi:[1,1,0] neg_lo:[1,0,0] neg_hi:[1,0,0]
	v_pk_mul_f32 v[8:9], v[22:23], v[8:9]
	v_max_f32_e32 v24, 0, v24
	v_max_f32_e32 v25, 0, v25
	v_sqrt_f32_e32 v24, v24
	v_sqrt_f32_e32 v25, v25
	v_pk_add_f32 v[22:23], v[36:37], 1.0 op_sel_hi:[1,0]
	v_mov_b32_e32 v42, v6
	v_rcp_f32_e32 v22, v22
	v_rcp_f32_e32 v23, v23
	v_pk_mul_f32 v[38:39], v[8:9], v[24:25]
	v_pk_add_f32 v[8:9], v[172:173], v[26:27]
	v_pk_add_f32 v[26:27], v[170:171], v[44:45]
	v_pk_mul_f32 v[8:9], v[8:9], s[90:91] op_sel_hi:[1,0]
	v_pk_mul_f32 v[26:27], v[26:27], s[90:91] op_sel_hi:[1,0]
	v_exp_f32_e32 v24, v8
	v_exp_f32_e32 v25, v9
	v_pk_mul_f32 v[8:9], v[176:177], v[22:23]
	v_exp_f32_e32 v26, v26
	v_exp_f32_e32 v8, v8
	v_exp_f32_e32 v9, v9
	v_pk_add_f32 v[22:23], v[24:25], 1.0 op_sel_hi:[1,0]
	v_exp_f32_e32 v27, v27
	v_rcp_f32_e32 v22, v22
	v_pk_fma_f32 v[24:25], v[8:9], v[8:9], 1.0 op_sel_hi:[1,1,0] neg_lo:[1,0,0] neg_hi:[1,0,0]
	v_rcp_f32_e32 v23, v23
	v_max_f32_e32 v24, 0, v24
	v_max_f32_e32 v25, 0, v25
	v_sqrt_f32_e32 v24, v24
	v_sqrt_f32_e32 v25, v25
	v_pk_mul_f32 v[10:11], v[22:23], v[10:11]
	v_pk_add_f32 v[22:23], v[172:173], v[28:29]
	v_pk_add_f32 v[28:29], v[172:173], v[30:31]
	v_pk_mul_f32 v[10:11], v[10:11], v[24:25]
	v_pk_add_f32 v[24:25], v[26:27], 1.0 op_sel_hi:[1,0]
	v_pk_mul_f32 v[22:23], v[22:23], s[90:91] op_sel_hi:[1,0]
	v_rcp_f32_e32 v24, v24
	v_rcp_f32_e32 v25, v25
	v_exp_f32_e32 v22, v22
	v_exp_f32_e32 v23, v23
	v_pk_mul_f32 v[28:29], v[28:29], s[90:91] op_sel_hi:[1,0]
	v_pk_mul_f32 v[24:25], v[176:177], v[24:25]
	v_exp_f32_e32 v28, v28
	v_exp_f32_e32 v36, v24
	v_exp_f32_e32 v37, v25
	v_pk_add_f32 v[22:23], v[22:23], 1.0 op_sel_hi:[1,0]
	v_exp_f32_e32 v29, v29
	v_rcp_f32_e32 v24, v22
	v_rcp_f32_e32 v25, v23
	v_pk_fma_f32 v[22:23], v[36:37], v[36:37], 1.0 op_sel_hi:[1,1,0] neg_lo:[1,0,0] neg_hi:[1,0,0]
	v_pk_add_f32 v[28:29], v[28:29], 1.0 op_sel_hi:[1,0]
	v_max_f32_e32 v26, 0, v22
	v_max_f32_e32 v27, 0, v23
	v_pk_add_f32 v[22:23], v[170:171], v[46:47]
	v_sqrt_f32_e32 v26, v26
	v_pk_mul_f32 v[22:23], v[22:23], s[90:91] op_sel_hi:[1,0]
	v_sqrt_f32_e32 v27, v27
	v_exp_f32_e32 v22, v22
	v_exp_f32_e32 v23, v23
	v_rcp_f32_e32 v28, v28
	v_rcp_f32_e32 v29, v29
	v_pk_mul_f32 v[12:13], v[24:25], v[12:13]
	v_pk_add_f32 v[22:23], v[22:23], 1.0 op_sel_hi:[1,0]
	v_pk_mul_f32 v[40:41], v[12:13], v[26:27]
	v_rcp_f32_e32 v22, v22
	v_rcp_f32_e32 v23, v23
	v_pk_mul_f32 v[12:13], v[28:29], v[14:15]
	v_mov_b32_e32 v15, v9
	v_mov_b32_e32 v25, v11
	v_pk_mul_f32 v[22:23], v[176:177], v[22:23]
	v_mov_b32_e32 v27, v8
	v_exp_f32_e32 v22, v22
	v_exp_f32_e32 v23, v23
	v_mov_b32_e32 v29, v10
	v_mov_b32_e32 v43, v2
	v_mov_b32_e32 v26, v22
	v_pk_fma_f32 v[30:31], v[22:23], v[22:23], 1.0 op_sel_hi:[1,1,0] neg_lo:[1,0,0] neg_hi:[1,0,0]
	v_mov_b32_e32 v14, v23
	v_max_f32_e32 v30, 0, v30
	v_max_f32_e32 v31, 0, v31
	v_sqrt_f32_e32 v30, v30
	v_sqrt_f32_e32 v31, v31
	v_pk_mul_f32 v[14:15], v[14:15], v[26:27]
	v_mov_b32_e32 v44, v21
	v_mov_b32_e32 v45, v33
	v_pk_mul_f32 v[12:13], v[12:13], v[30:31]
	v_mov_b32_e32 v30, v41
	v_mov_b32_e32 v24, v13
	v_mov_b32_e32 v28, v12
	v_pk_fma_f32 v[24:25], v[26:27], v[24:25], v[28:29]
	v_mov_b32_e32 v28, v37
	v_mov_b32_e32 v29, v35
	v_mov_b32_e32 v31, v39
	v_pk_mul_f32 v[26:27], v[28:29], v[14:15]
	v_pk_fma_f32 v[28:29], v[28:29], v[24:25], v[30:31]
	v_mov_b32_e32 v37, v34
	v_mov_b32_e32 v41, v38
	v_pk_mul_f32 v[30:31], v[36:37], v[26:27]
	v_pk_fma_f32 v[34:35], v[36:37], v[28:29], v[40:41]
	v_mov_b32_e32 v36, v5
	v_mov_b32_e32 v37, v1
	v_mov_b32_e32 v38, v7
	v_mov_b32_e32 v39, v3
	v_mov_b32_e32 v40, v4
	v_mov_b32_e32 v41, v0
	v_pk_mul_f32 v[36:37], v[36:37], v[40:41]
	v_pk_fma_f32 v[38:39], v[40:41], v[38:39], v[42:43]
	v_mov_b32_e32 v42, v19
	v_mov_b32_e32 v43, v17
	ds_bpermute_b32 v4, v180, v30
	ds_bpermute_b32 v8, v180, v34
	v_pk_mul_f32 v[40:41], v[42:43], v[36:37]
	v_pk_fma_f32 v[42:43], v[42:43], v[38:39], v[44:45]
	v_mov_b32_e32 v19, v16
	v_mov_b32_e32 v21, v32
	v_pk_mul_f32 v[16:17], v[18:19], v[40:41]
	v_pk_fma_f32 v[18:19], v[18:19], v[42:43], v[20:21]
	ds_bpermute_b32 v12, v180, v31
	ds_bpermute_b32 v20, v180, v35
	ds_bpermute_b32 v21, v180, v16
	ds_bpermute_b32 v22, v180, v18
	s_waitcnt lgkmcnt(0)
	v_cndmask_b32_e64 v10, v30, v4, s[2:3]
	v_cndmask_b32_e64 v6, v34, v8, s[2:3]
	ds_bpermute_b32 v0, v180, v17
	ds_bpermute_b32 v2, v180, v19
	v_fmac_f32_e32 v6, v183, v10
	v_cndmask_b32_e64 v4, v4, v30, s[2:3]
	v_cndmask_b32_e64 v8, v8, v34, s[2:3]
	v_fmac_f32_e32 v8, v4, v6
	v_cndmask_b32_e64 v4, v31, v12, s[2:3]
	v_cndmask_b32_e64 v10, v35, v20, s[2:3]
	v_fmac_f32_e32 v10, v4, v8
	v_cndmask_b32_e64 v4, v12, v31, s[2:3]
	v_cndmask_b32_e64 v12, v20, v35, s[2:3]
	v_fmac_f32_e32 v12, v4, v10
	v_cndmask_b32_e64 v4, v16, v21, s[2:3]
	v_cndmask_b32_e64 v20, v18, v22, s[2:3]
	v_fmac_f32_e32 v20, v4, v12
	v_cndmask_b32_e64 v4, v21, v16, s[2:3]
	v_cndmask_b32_e64 v21, v22, v18, s[2:3]
	v_fmac_f32_e32 v21, v4, v20
	s_waitcnt lgkmcnt(1)
	v_cndmask_b32_e64 v22, v17, v0, s[2:3]
	s_waitcnt lgkmcnt(0)
	v_cndmask_b32_e64 v4, v19, v2, s[2:3]
	v_fmac_f32_e32 v4, v22, v21
	s_cbranch_scc1 .LBB0_480
; __device__ __forceinline__ unsigned short f2bf(float f) { return (unsigned short)(cvt_pk_bf16(f, 0.f) & 0xffffu); }
; template <int DIR>
; __device__ __forceinline__ void lru_item(const Params& p, int item, int lane) {
;     ...
;         float st = hst, hs[4];
; #pragma unroll
;         for (int Gi = 0; Gi < 8; ++Gi) {
;             const int q = Gi >> 1; const bool own = (hh == (Gi & 1));
;             const float A = own ? Ag[q] : Ap[q], B = own ? Bg[q] : Bp[q];
;             if (own) hs[q] = st;
;             st = A * st + B;
;         }
;         hst = st;
;         if (!is_ctx) {
;             bf16_t* yr = yl + ((size_t)bl * 2048 + tile * 32) * 1024 + d;
; #pragma unroll
;             for (int e = 0; e < 16; ++e) { const int k = DIR ? 15 - e : e; const float hv = av[k] * hs[k >> 2] + bv[k];
;                 const int tok = (e & 3) + 8 * (e >> 2) + 4 * h; yr[(size_t)tok * 1024] = f2bf(hv); }
;         }
	v_cndmask_b32_e64 v22, v21, v4, s[2:3]
	v_cndmask_b32_e64 v12, v12, v20, s[2:3]
	v_lshl_add_u64 v[20:21], v[178:179], 0, s[8:9]
	s_mov_b32 s15, 0x1bd70000
	v_add_co_u32_e32 v32, vcc, s15, v20
	s_mov_b32 s15, 0x1bd71000
	s_nop 0
	v_addc_co_u32_e32 v33, vcc, 0, v21, vcc
	v_cndmask_b32_e64 v8, v8, v10, s[2:3]
	v_cndmask_b32_e64 v10, v183, v6, s[2:3]
	v_fma_f32 v6, v17, v22, v19
	v_add_co_u32_e32 v44, vcc, s15, v20
	v_cvt_pk_bf16_f32 v6, v6, v193
	s_mov_b32 s15, 0x1bd74000
	s_nop 0
	v_addc_co_u32_e32 v45, vcc, 0, v21, vcc
	global_store_short v[44:45], v6, off offset:-4096
	v_fma_f32 v6, v41, v22, v43
	v_cvt_pk_bf16_f32 v6, v6, v193
	global_store_short v[32:33], v6, off offset:2048
	v_fma_f32 v6, v37, v22, v39
	v_add_co_u32_e32 v32, vcc, s15, v20
	v_cvt_pk_bf16_f32 v6, v6, v193
	global_store_short v[44:45], v6, off
	v_fmac_f32_e32 v3, v1, v22
	v_cvt_pk_bf16_f32 v1, v3, v193
	v_addc_co_u32_e32 v33, vcc, 0, v21, vcc
	s_mov_b32 s15, 0x1bd75000
	global_store_short v[44:45], v1, off offset:2048
	v_fma_f32 v1, v16, v12, v18
	v_add_co_u32_e32 v44, vcc, s15, v20
	v_cvt_pk_bf16_f32 v1, v1, v193
	v_fmac_f32_e32 v42, v40, v12
	s_nop 0
	v_addc_co_u32_e32 v45, vcc, 0, v21, vcc
	global_store_short v[44:45], v1, off offset:-4096
	v_cvt_pk_bf16_f32 v1, v42, v193
	s_mov_b32 s15, 0x1bd78000
	global_store_short v[32:33], v1, off offset:2048
	v_fmac_f32_e32 v38, v36, v12
	v_cvt_pk_bf16_f32 v1, v38, v193
	v_fmac_f32_e32 v7, v5, v12
	v_add_co_u32_e32 v6, vcc, s15, v20
	global_store_short v[44:45], v1, off
	v_cvt_pk_bf16_f32 v1, v7, v193
	s_nop 0
	v_addc_co_u32_e32 v7, vcc, 0, v21, vcc
	s_mov_b32 s15, 0x1bd79000
	global_store_short v[44:45], v1, off offset:2048
	v_fma_f32 v1, v31, v8, v35
	v_add_co_u32_e32 v32, vcc, s15, v20
	v_cvt_pk_bf16_f32 v1, v1, v193
	v_fmac_f32_e32 v11, v9, v8
	s_nop 0
	v_addc_co_u32_e32 v33, vcc, 0, v21, vcc
	global_store_short v[32:33], v1, off offset:-4096
	v_fma_f32 v1, v27, v8, v29
	v_cvt_pk_bf16_f32 v1, v1, v193
	global_store_short v[6:7], v1, off offset:2048
	v_fma_f32 v1, v15, v8, v25
	v_cvt_pk_bf16_f32 v1, v1, v193
	global_store_short v[32:33], v1, off
	v_cvt_pk_bf16_f32 v1, v11, v193
	v_add_co_u32_e32 v6, vcc, 0x1bd7c000, v20
	global_store_short v[32:33], v1, off offset:2048
	v_fmac_f32_e32 v34, v30, v10
	v_cvt_pk_bf16_f32 v1, v34, v193
	v_addc_co_u32_e32 v7, vcc, 0, v21, vcc
	global_store_short v[6:7], v1, off
	v_fmac_f32_e32 v28, v26, v10
	v_cvt_pk_bf16_f32 v1, v28, v193
	global_store_short v[6:7], v1, off offset:2048
	v_add_co_u32_e32 v6, vcc, 0x1bd7d000, v20
	v_fmac_f32_e32 v24, v14, v10
	v_cvt_pk_bf16_f32 v1, v24, v193
	s_nop 0
	v_addc_co_u32_e32 v7, vcc, 0, v21, vcc
	global_store_short v[6:7], v1, off
	v_fmac_f32_e32 v13, v23, v10
	v_cvt_pk_bf16_f32 v1, v13, v193
	s_nop 1
	global_store_short v[6:7], v1, off offset:2048
	s_branch .LBB0_480

; template <int DIR>
; __device__ __forceinline__ void lru_item(const Params& p, int item, int lane) {
;     ...
;         { const int tn = t + 1 < 72 ? t + 1 : 71; const bf16_t* up = uu + (tile_row0(tn) + r) * 1024 + blk * 128 + 8 * h;
; #pragma unroll
;           for (int s = 0; s < 8; ++s) uf[s] = ld8(up + 16 * s);
;           ui0 = ld8(up + 32 * db); ui1 = ld8(up + 32 * db + 16); }
;         float av[16], bv[16];
; #pragma unroll
;         for (int e = 0; e < 16; e += 2) {
;             const f32x2 xa = (f32x2){Aa[e], Aa[e + 1]} + ba, xi = (f32x2){Ai[e], Ai[e + 1]} + bi, uv = (f32x2){Au[e], Au[e + 1]};
;             const f32x2 ta = xa * -1.4426950408889634f, ti = xi * -1.4426950408889634f;
;             f32x2 da, di; da.x = __builtin_amdgcn_exp2f(ta.x); da.y = __builtin_amdgcn_exp2f(ta.y); di.x = __builtin_amdgcn_exp2f(ti.x); di.y = __builtin_amdgcn_exp2f(ti.y);
;             da = da + 1.f; di = di + 1.f;
;             f32x2 ra, ri; ra.x = __builtin_amdgcn_rcpf(da.x); ra.y = __builtin_amdgcn_rcpf(da.y); ri.x = __builtin_amdgcn_rcpf(di.x); ri.y = __builtin_amdgcn_rcpf(di.y);
;             const f32x2 la = ra * (c8 * 1.4426950408889634f);
;             f32x2 a; a.x = __builtin_amdgcn_exp2f(la.x); a.y = __builtin_amdgcn_exp2f(la.y);
;             f32x2 om = 1.f - a * a; om.x = fmaxf(om.x, 0.f); om.y = fmaxf(om.y, 0.f);
;             f32x2 sq; sq.x = __builtin_amdgcn_sqrtf(om.x); sq.y = __builtin_amdgcn_sqrtf(om.y);
;             const f32x2 b = sq * (ri * uv);
;             const int k0 = DIR ? 15 - e : e, k1 = DIR ? 14 - e : e + 1;
;             av[k0] = a.x; bv[k0] = b.x; av[k1] = a.y; bv[k1] = b.y;
;         }
.LBB0_495:
	s_nop 6
	v_pk_add_f32 v[32:33], v[168:169], v[32:33]
	v_pk_add_f32 v[16:17], v[170:171], v[16:17]
	v_pk_mul_f32 v[32:33], v[32:33], s[90:91] op_sel_hi:[1,0]
	v_pk_mul_f32 v[16:17], v[16:17], s[90:91] op_sel_hi:[1,0]
	v_exp_f32_e32 v32, v32
	v_exp_f32_e32 v33, v33
	v_exp_f32_e32 v182, v16
	v_exp_f32_e32 v183, v17
	v_pk_add_f32 v[34:35], v[168:169], v[34:35]
	v_pk_add_f32 v[32:33], v[32:33], 1.0 op_sel_hi:[1,0]
	v_pk_mul_f32 v[34:35], v[34:35], s[90:91] op_sel_hi:[1,0]
	v_rcp_f32_e32 v32, v32
	v_rcp_f32_e32 v33, v33
	v_exp_f32_e32 v34, v34
	v_exp_f32_e32 v35, v35
	v_pk_add_f32 v[18:19], v[170:171], v[18:19]
	v_pk_mul_f32 v[16:17], v[174:175], v[32:33]
	v_pk_add_f32 v[32:33], v[182:183], 1.0 op_sel_hi:[1,0]
	v_pk_mul_f32 v[18:19], v[18:19], s[90:91] op_sel_hi:[1,0]
	v_rcp_f32_e32 v32, v32
	v_rcp_f32_e32 v33, v33
	v_pk_add_f32 v[36:37], v[168:169], v[36:37]
	v_lshl_add_u64 v[120:121], s[12:13], 0, v[160:161]
	v_pk_mul_f32 v[36:37], v[36:37], s[90:91] op_sel_hi:[1,0]
	v_pk_mul_f32 v[0:1], v[0:1], v[32:33]
	v_pk_add_f32 v[32:33], v[34:35], 1.0 op_sel_hi:[1,0]
	v_exp_f32_e32 v34, v18
	v_rcp_f32_e32 v32, v32
	v_rcp_f32_e32 v33, v33
	v_exp_f32_e32 v35, v19
	v_exp_f32_e32 v36, v36
	v_exp_f32_e32 v37, v37
	v_pk_mul_f32 v[18:19], v[174:175], v[32:33]
	v_pk_add_f32 v[32:33], v[34:35], 1.0 op_sel_hi:[1,0]
	v_exp_f32_e32 v18, v18
	v_exp_f32_e32 v19, v19
	v_rcp_f32_e32 v32, v32
	v_rcp_f32_e32 v33, v33
	v_lshlrev_b64 v[120:121], 11, v[120:121]
	v_pk_fma_f32 v[34:35], v[18:19], v[18:19], 1.0 op_sel_hi:[1,1,0] neg_lo:[1,0,0] neg_hi:[1,0,0]
	v_lshl_add_u64 v[140:141], v[172:173], 0, v[120:121]
	v_max_f32_e32 v34, 0, v34
	v_max_f32_e32 v35, 0, v35
	v_sqrt_f32_e32 v34, v34
	v_sqrt_f32_e32 v35, v35
	v_pk_mul_f32 v[2:3], v[2:3], v[32:33]
	global_load_dwordx4 v[152:155], v[140:141], off
	global_load_dwordx4 v[148:151], v[140:141], off offset:32
	global_load_dwordx4 v[144:147], v[140:141], off offset:64
	global_load_dwordx4 v[136:139], v[140:141], off offset:96
	global_load_dwordx4 v[132:135], v[140:141], off offset:128
	global_load_dwordx4 v[128:131], v[140:141], off offset:160
	global_load_dwordx4 v[124:127], v[140:141], off offset:192
	global_load_dwordx4 v[120:123], v[140:141], off offset:224
	v_lshl_add_u64 v[140:141], v[140:141], 0, s[66:67]
	v_pk_mul_f32 v[32:33], v[2:3], v[34:35]
	v_pk_add_f32 v[2:3], v[170:171], v[20:21]
	v_pk_add_f32 v[20:21], v[36:37], 1.0 op_sel_hi:[1,0]
	v_pk_mul_f32 v[2:3], v[2:3], s[90:91] op_sel_hi:[1,0]
	v_rcp_f32_e32 v20, v20
	v_rcp_f32_e32 v21, v21
	v_exp_f32_e32 v34, v2
	v_exp_f32_e32 v35, v3
	v_pk_add_f32 v[36:37], v[168:169], v[38:39]
	v_pk_mul_f32 v[2:3], v[174:175], v[20:21]
	v_pk_mul_f32 v[36:37], v[36:37], s[90:91] op_sel_hi:[1,0]
	v_pk_add_f32 v[20:21], v[34:35], 1.0 op_sel_hi:[1,0]
	v_exp_f32_e32 v36, v36
	v_rcp_f32_e32 v20, v20
	v_rcp_f32_e32 v21, v21
	v_exp_f32_e32 v37, v37
	v_exp_f32_e32 v2, v2
	v_exp_f32_e32 v3, v3
	v_pk_mul_f32 v[4:5], v[4:5], v[20:21]
	v_pk_add_f32 v[20:21], v[170:171], v[22:23]
	v_pk_add_f32 v[22:23], v[36:37], 1.0 op_sel_hi:[1,0]
	v_pk_fma_f32 v[34:35], v[2:3], v[2:3], 1.0 op_sel_hi:[1,1,0] neg_lo:[1,0,0] neg_hi:[1,0,0]
	v_rcp_f32_e32 v22, v22
	v_rcp_f32_e32 v23, v23
	v_max_f32_e32 v34, 0, v34
	v_max_f32_e32 v35, 0, v35
	v_pk_mul_f32 v[20:21], v[20:21], s[90:91] op_sel_hi:[1,0]
	v_pk_mul_f32 v[22:23], v[174:175], v[22:23]
	v_sqrt_f32_e32 v34, v34
	v_sqrt_f32_e32 v35, v35
	v_exp_f32_e32 v20, v20
	v_exp_f32_e32 v21, v21
	v_exp_f32_e32 v22, v22
	v_exp_f32_e32 v23, v23
	global_load_dwordx4 v[156:159], v[140:141], off
	s_nop 0
	global_load_dwordx4 v[140:143], v[140:141], off offset:32
	v_pk_mul_f32 v[4:5], v[4:5], v[34:35]
	v_pk_add_f32 v[20:21], v[20:21], 1.0 op_sel_hi:[1,0]
	v_pk_fma_f32 v[34:35], v[22:23], v[22:23], 1.0 op_sel_hi:[1,1,0] neg_lo:[1,0,0] neg_hi:[1,0,0]
	v_rcp_f32_e32 v20, v20
	v_rcp_f32_e32 v21, v21
	v_max_f32_e32 v34, 0, v34
	v_max_f32_e32 v35, 0, v35
	v_pk_add_f32 v[36:37], v[168:169], v[40:41]
	v_sqrt_f32_e32 v34, v34
	v_sqrt_f32_e32 v35, v35
	v_pk_mul_f32 v[36:37], v[36:37], s[90:91] op_sel_hi:[1,0]
	v_pk_mul_f32 v[6:7], v[6:7], v[20:21]
	v_exp_f32_e32 v36, v36
	v_exp_f32_e32 v37, v37
	v_pk_mul_f32 v[20:21], v[6:7], v[34:35]
	v_pk_add_f32 v[6:7], v[170:171], v[24:25]
	v_pk_add_f32 v[30:31], v[170:171], v[30:31]
	v_pk_add_f32 v[24:25], v[36:37], 1.0 op_sel_hi:[1,0]
	v_pk_mul_f32 v[6:7], v[6:7], s[90:91] op_sel_hi:[1,0]
	v_rcp_f32_e32 v24, v24
	v_rcp_f32_e32 v25, v25
	v_exp_f32_e32 v34, v6
	v_exp_f32_e32 v35, v7
	v_pk_add_f32 v[36:37], v[168:169], v[42:43]
	v_pk_mul_f32 v[6:7], v[174:175], v[24:25]
	v_pk_mul_f32 v[36:37], v[36:37], s[90:91] op_sel_hi:[1,0]
	v_pk_add_f32 v[24:25], v[34:35], 1.0 op_sel_hi:[1,0]
	v_exp_f32_e32 v36, v36
	v_rcp_f32_e32 v24, v24
	v_rcp_f32_e32 v25, v25
	v_exp_f32_e32 v37, v37
	v_exp_f32_e32 v6, v6
	v_exp_f32_e32 v7, v7
	v_pk_mul_f32 v[8:9], v[8:9], v[24:25]
	v_pk_add_f32 v[24:25], v[170:171], v[26:27]
	v_pk_add_f32 v[26:27], v[36:37], 1.0 op_sel_hi:[1,0]
	v_pk_fma_f32 v[34:35], v[6:7], v[6:7], 1.0 op_sel_hi:[1,1,0] neg_lo:[1,0,0] neg_hi:[1,0,0]
	v_rcp_f32_e32 v26, v26
	v_rcp_f32_e32 v27, v27
	v_max_f32_e32 v34, 0, v34
	v_max_f32_e32 v35, 0, v35
	v_sqrt_f32_e32 v34, v34
	v_sqrt_f32_e32 v35, v35
	v_pk_mul_f32 v[24:25], v[24:25], s[90:91] op_sel_hi:[1,0]
	v_pk_mul_f32 v[26:27], v[174:175], v[26:27]
	v_exp_f32_e32 v24, v24
	v_exp_f32_e32 v25, v25
	v_exp_f32_e32 v40, v26
	v_exp_f32_e32 v41, v27
	v_pk_mul_f32 v[8:9], v[8:9], v[34:35]
	v_pk_add_f32 v[34:35], v[168:169], v[44:45]
	v_pk_add_f32 v[24:25], v[24:25], 1.0 op_sel_hi:[1,0]
	v_pk_mul_f32 v[34:35], v[34:35], s[90:91] op_sel_hi:[1,0]
	v_rcp_f32_e32 v24, v24
	v_rcp_f32_e32 v25, v25
; template <int DIR>
; __device__ __forceinline__ void lru_item(const Params& p, int item, int lane) {
;     ...
;         for (int e = 0; e < 16; e += 2) {
;             const f32x2 xa = (f32x2){Aa[e], Aa[e + 1]} + ba, xi = (f32x2){Ai[e], Ai[e + 1]} + bi, uv = (f32x2){Au[e], Au[e + 1]};
;             const f32x2 ta = xa * -1.4426950408889634f, ti = xi * -1.4426950408889634f;
;             f32x2 da, di; da.x = __builtin_amdgcn_exp2f(ta.x); da.y = __builtin_amdgcn_exp2f(ta.y); di.x = __builtin_amdgcn_exp2f(ti.x); di.y = __builtin_amdgcn_exp2f(ti.y);
;             da = da + 1.f; di = di + 1.f;
;             f32x2 ra, ri; ra.x = __builtin_amdgcn_rcpf(da.x); ra.y = __builtin_amdgcn_rcpf(da.y); ri.x = __builtin_amdgcn_rcpf(di.x); ri.y = __builtin_amdgcn_rcpf(di.y);
;             const f32x2 la = ra * (c8 * 1.4426950408889634f);
;             f32x2 a; a.x = __builtin_amdgcn_exp2f(la.x); a.y = __builtin_amdgcn_exp2f(la.y);
;             f32x2 om = 1.f - a * a; om.x = fmaxf(om.x, 0.f); om.y = fmaxf(om.y, 0.f);
;             f32x2 sq; sq.x = __builtin_amdgcn_sqrtf(om.x); sq.y = __builtin_amdgcn_sqrtf(om.y);
;             const f32x2 b = sq * (ri * uv);
;             const int k0 = DIR ? 15 - e : e, k1 = DIR ? 14 - e : e + 1;
;             av[k0] = a.x; bv[k0] = b.x; av[k1] = a.y; bv[k1] = b.y;
;         }
;         const int hh = DIR ? 1 - h : h;
;         float Ag[4], Bg[4];
; #pragma unroll
;         for (int q = 0; q < 4; q += 2) {
;             f32x2 A = (f32x2){av[4 * q], av[4 * q + 4]}, B = (f32x2){bv[4 * q], bv[4 * q + 4]};
; #pragma unroll
;             for (int k = 1; k < 4; ++k) { const f32x2 ak = (f32x2){av[4 * q + k], av[4 * q + 4 + k]}, bk = (f32x2){bv[4 * q + k], bv[4 * q + 4 + k]};
;                 A = A * ak; B = B * ak + bk; av[4 * q + k] = A.x; av[4 * q + 4 + k] = A.y; bv[4 * q + k] = B.x; bv[4 * q + 4 + k] = B.y; }
;             Ag[q] = A.x; Ag[q + 1] = A.y; Bg[q] = B.x; Bg[q + 1] = B.y;
;         }
;         float Ap[4], Bp[4];
; #pragma unroll
;         for (int q = 0; q < 4; ++q) { Ap[q] = lane_get(Ag[q], lane ^ 32); Bp[q] = lane_get(Bg[q], lane ^ 32); }
;         float st = hst, hs[4];
; #pragma unroll
;         for (int Gi = 0; Gi < 8; ++Gi) {
;             const int q = Gi >> 1; const bool own = (hh == (Gi & 1));
;             const float A = own ? Ag[q] : Ap[q], B = own ? Bg[q] : Bp[q];
;             if (own) hs[q] = st;
	v_exp_f32_e32 v34, v34
	v_exp_f32_e32 v35, v35
	v_pk_fma_f32 v[26:27], v[40:41], v[40:41], 1.0 op_sel_hi:[1,1,0] neg_lo:[1,0,0] neg_hi:[1,0,0]
	v_pk_mul_f32 v[10:11], v[10:11], v[24:25]
	v_max_f32_e32 v26, 0, v26
	v_max_f32_e32 v27, 0, v27
	v_sqrt_f32_e32 v26, v26
	v_sqrt_f32_e32 v27, v27
	v_pk_add_f32 v[24:25], v[34:35], 1.0 op_sel_hi:[1,0]
	v_exp_f32_e32 v16, v16
	v_rcp_f32_e32 v24, v24
	v_rcp_f32_e32 v25, v25
	v_pk_mul_f32 v[42:43], v[10:11], v[26:27]
	v_pk_add_f32 v[10:11], v[170:171], v[28:29]
	v_exp_f32_e32 v17, v17
	v_pk_mul_f32 v[10:11], v[10:11], s[90:91] op_sel_hi:[1,0]
	v_pk_mul_f32 v[30:31], v[30:31], s[90:91] op_sel_hi:[1,0]
	v_exp_f32_e32 v26, v10
	v_exp_f32_e32 v27, v11
	v_pk_mul_f32 v[10:11], v[174:175], v[24:25]
	v_exp_f32_e32 v30, v30
	v_exp_f32_e32 v10, v10
	v_exp_f32_e32 v11, v11
	v_pk_add_f32 v[24:25], v[26:27], 1.0 op_sel_hi:[1,0]
	v_exp_f32_e32 v31, v31
	v_pk_fma_f32 v[182:183], v[16:17], v[16:17], 1.0 op_sel_hi:[1,1,0] neg_lo:[1,0,0] neg_hi:[1,0,0]
	v_pk_fma_f32 v[26:27], v[10:11], v[10:11], 1.0 op_sel_hi:[1,1,0] neg_lo:[1,0,0] neg_hi:[1,0,0]
	v_max_f32_e32 v179, 0, v182
	v_max_f32_e32 v28, 0, v26
	v_max_f32_e32 v29, 0, v27
	v_pk_add_f32 v[26:27], v[168:169], v[46:47]
	v_max_f32_e32 v183, 0, v183
	v_pk_mul_f32 v[26:27], v[26:27], s[90:91] op_sel_hi:[1,0]
	v_sqrt_f32_e32 v182, v179
	v_exp_f32_e32 v26, v26
	v_exp_f32_e32 v27, v27
	v_sqrt_f32_e32 v183, v183
	v_rcp_f32_e32 v24, v24
	v_rcp_f32_e32 v25, v25
	v_pk_add_f32 v[26:27], v[26:27], 1.0 op_sel_hi:[1,0]
	v_sqrt_f32_e32 v28, v28
	v_rcp_f32_e32 v26, v26
	v_rcp_f32_e32 v27, v27
	v_sqrt_f32_e32 v29, v29
	v_pk_mul_f32 v[0:1], v[0:1], v[182:183]
	v_pk_mul_f32 v[12:13], v[12:13], v[24:25]
	v_pk_mul_f32 v[26:27], v[174:175], v[26:27]
	v_mov_b32_e32 v24, v0
	v_exp_f32_e32 v44, v26
	v_exp_f32_e32 v45, v27
	v_pk_add_f32 v[26:27], v[30:31], 1.0 op_sel_hi:[1,0]
	v_mov_b32_e32 v25, v4
	v_rcp_f32_e32 v26, v26
	v_pk_fma_f32 v[30:31], v[44:45], v[44:45], 1.0 op_sel_hi:[1,1,0] neg_lo:[1,0,0] neg_hi:[1,0,0]
	v_rcp_f32_e32 v27, v27
	v_max_f32_e32 v30, 0, v30
	v_max_f32_e32 v31, 0, v31
	v_sqrt_f32_e32 v30, v30
	v_sqrt_f32_e32 v31, v31
	v_pk_mul_f32 v[14:15], v[14:15], v[26:27]
	v_mov_b32_e32 v26, v17
	v_mov_b32_e32 v27, v3
	v_pk_mul_f32 v[46:47], v[14:15], v[30:31]
	v_mov_b32_e32 v14, v16
	v_mov_b32_e32 v15, v2
	v_mov_b32_e32 v30, v1
	v_mov_b32_e32 v31, v5
	v_pk_mul_f32 v[12:13], v[12:13], v[28:29]
	v_pk_mul_f32 v[28:29], v[14:15], v[26:27]
	v_pk_fma_f32 v[30:31], v[26:27], v[24:25], v[30:31]
	v_mov_b32_e32 v14, v18
	v_mov_b32_e32 v15, v22
	v_mov_b32_e32 v24, v32
	v_mov_b32_e32 v25, v20
	v_pk_mul_f32 v[34:35], v[14:15], v[28:29]
	v_pk_fma_f32 v[36:37], v[14:15], v[30:31], v[24:25]
	v_mov_b32_e32 v22, v19
	v_mov_b32_e32 v20, v33
	v_pk_mul_f32 v[32:33], v[22:23], v[34:35]
	v_pk_fma_f32 v[38:39], v[22:23], v[36:37], v[20:21]
	v_mov_b32_e32 v14, v6
	v_mov_b32_e32 v15, v10
	v_mov_b32_e32 v18, v8
	v_mov_b32_e32 v19, v12
	v_mov_b32_e32 v22, v7
	v_mov_b32_e32 v23, v11
	v_mov_b32_e32 v24, v9
	v_mov_b32_e32 v25, v13
	ds_bpermute_b32 v5, v180, v32
	ds_bpermute_b32 v9, v180, v38
	v_pk_mul_f32 v[20:21], v[14:15], v[22:23]
	v_pk_fma_f32 v[22:23], v[22:23], v[18:19], v[24:25]
	v_mov_b32_e32 v14, v40
	v_mov_b32_e32 v15, v44
	v_mov_b32_e32 v18, v42
	v_mov_b32_e32 v19, v46
	v_pk_mul_f32 v[24:25], v[14:15], v[20:21]
	v_pk_fma_f32 v[26:27], v[14:15], v[22:23], v[18:19]
	v_mov_b32_e32 v44, v41
	v_mov_b32_e32 v46, v43
	ds_bpermute_b32 v13, v180, v33
	ds_bpermute_b32 v17, v180, v39
	v_pk_mul_f32 v[14:15], v[44:45], v[24:25]
	v_pk_fma_f32 v[18:19], v[44:45], v[26:27], v[46:47]
	ds_bpermute_b32 v40, v180, v14
	ds_bpermute_b32 v41, v180, v18
	s_waitcnt lgkmcnt(0)
	v_cndmask_b32_e64 v11, v5, v32, s[2:3]
	v_cndmask_b32_e64 v7, v9, v38, s[2:3]
	ds_bpermute_b32 v1, v180, v15
	ds_bpermute_b32 v3, v180, v19
	v_fmac_f32_e32 v7, v178, v11
	v_cndmask_b32_e64 v5, v32, v5, s[2:3]
	v_cndmask_b32_e64 v9, v38, v9, s[2:3]
	v_fmac_f32_e32 v9, v5, v7
	v_cndmask_b32_e64 v5, v13, v33, s[2:3]
	v_cndmask_b32_e64 v11, v17, v39, s[2:3]
	v_fmac_f32_e32 v11, v5, v9
	v_cndmask_b32_e64 v5, v33, v13, s[2:3]
	v_cndmask_b32_e64 v13, v39, v17, s[2:3]
	v_fmac_f32_e32 v13, v5, v11
	v_cndmask_b32_e64 v5, v40, v14, s[2:3]
	v_cndmask_b32_e64 v17, v41, v18, s[2:3]
	v_fmac_f32_e32 v17, v5, v13
	v_cndmask_b32_e64 v5, v14, v40, s[2:3]
	v_cndmask_b32_e64 v40, v18, v41, s[2:3]
	v_fmac_f32_e32 v40, v5, v17
	s_waitcnt lgkmcnt(1)
	v_cndmask_b32_e64 v41, v1, v15, s[2:3]
	s_waitcnt lgkmcnt(0)
	v_cndmask_b32_e64 v5, v3, v19, s[2:3]
	s_cmp_lt_u32 s19, 8
	v_fmac_f32_e32 v5, v41, v40
	s_cbranch_scc1 .LBB0_490
; __device__ __forceinline__ unsigned short f2bf(float f) { return (unsigned short)(cvt_pk_bf16(f, 0.f) & 0xffffu); }
; template <int DIR>
; __device__ __forceinline__ void lru_item(const Params& p, int item, int lane) {
;     ...
;         float st = hst, hs[4];
; #pragma unroll
;         for (int Gi = 0; Gi < 8; ++Gi) {
;             const int q = Gi >> 1; const bool own = (hh == (Gi & 1));
;             const float A = own ? Ag[q] : Ap[q], B = own ? Bg[q] : Bp[q];
;             if (own) hs[q] = st;
;             st = A * st + B;
;         }
;         hst = st;
;         if (!is_ctx) {
;             bf16_t* yr = yl + ((size_t)bl * 2048 + tile * 32) * 1024 + d;
; #pragma unroll
;             for (int e = 0; e < 16; ++e) { const int k = DIR ? 15 - e : e; const float hv = av[k] * hs[k >> 2] + bv[k];
;                 const int tok = (e & 3) + 8 * (e >> 2) + 4 * h; yr[(size_t)tok * 1024] = f2bf(hv); }
;         }
	v_cndmask_b32_e64 v7, v7, v178, s[2:3]
	v_cndmask_b32_e64 v13, v17, v13, s[2:3]
	v_fmac_f32_e32 v0, v16, v7
	v_lshl_add_u64 v[16:17], v[176:177], 0, s[10:11]
	s_mov_b32 s12, 0x17880000
	v_cndmask_b32_e64 v44, v5, v40, s[2:3]
	v_add_co_u32_e32 v40, vcc, s12, v16
	s_mov_b32 s12, 0x17881000
	s_nop 0
	v_addc_co_u32_e32 v41, vcc, 0, v17, vcc
	v_add_co_u32_e32 v42, vcc, s12, v16
	v_cvt_pk_bf16_f32 v0, v0, v193
	s_mov_b32 s12, 0x17884000
	s_nop 0
	v_addc_co_u32_e32 v43, vcc, 0, v17, vcc
	global_store_short v[42:43], v0, off offset:-4096
	v_fma_f32 v0, v28, v7, v30
	v_cvt_pk_bf16_f32 v0, v0, v193
	global_store_short v[40:41], v0, off offset:2048
	v_fma_f32 v0, v34, v7, v36
	v_cvt_pk_bf16_f32 v0, v0, v193
	v_add_co_u32_e32 v40, vcc, s12, v16
	global_store_short v[42:43], v0, off
	v_fma_f32 v0, v32, v7, v38
	v_addc_co_u32_e32 v41, vcc, 0, v17, vcc
	s_mov_b32 s12, 0x17885000
	v_cndmask_b32_e64 v9, v11, v9, s[2:3]
	v_cvt_pk_bf16_f32 v0, v0, v193
	global_store_short v[42:43], v0, off offset:2048
	v_add_co_u32_e32 v42, vcc, s12, v16
	v_fmac_f32_e32 v4, v2, v9
	v_cvt_pk_bf16_f32 v0, v4, v193
	s_nop 0
	v_addc_co_u32_e32 v43, vcc, 0, v17, vcc
	global_store_short v[42:43], v0, off offset:-4096
	v_fmac_f32_e32 v31, v29, v9
	v_cvt_pk_bf16_f32 v0, v31, v193
	s_mov_b32 s12, 0x17888000
	global_store_short v[40:41], v0, off offset:2048
	v_fmac_f32_e32 v37, v35, v9
	v_cvt_pk_bf16_f32 v0, v37, v193
	v_fmac_f32_e32 v8, v6, v13
	v_add_co_u32_e32 v6, vcc, s12, v16
	global_store_short v[42:43], v0, off
	v_fmac_f32_e32 v39, v33, v9
	v_cvt_pk_bf16_f32 v0, v39, v193
	v_addc_co_u32_e32 v7, vcc, 0, v17, vcc
	s_mov_b32 s12, 0x17889000
	global_store_short v[42:43], v0, off offset:2048
	v_cvt_pk_bf16_f32 v0, v8, v193
	v_add_co_u32_e32 v8, vcc, s12, v16
	v_fmac_f32_e32 v12, v10, v44
	s_nop 0
	v_addc_co_u32_e32 v9, vcc, 0, v17, vcc
	global_store_short v[8:9], v0, off offset:-4096
	v_fma_f32 v0, v20, v13, v22
	v_cvt_pk_bf16_f32 v0, v0, v193
	global_store_short v[6:7], v0, off offset:2048
	v_fma_f32 v0, v24, v13, v26
	v_cvt_pk_bf16_f32 v0, v0, v193
	global_store_short v[8:9], v0, off
	v_fma_f32 v0, v14, v13, v18
	v_cvt_pk_bf16_f32 v0, v0, v193
	v_add_co_u32_e32 v6, vcc, 0x1788c000, v16
	global_store_short v[8:9], v0, off offset:2048
	v_cvt_pk_bf16_f32 v0, v12, v193
	s_nop 0
	v_addc_co_u32_e32 v7, vcc, 0, v17, vcc
	global_store_short v[6:7], v0, off
	v_fmac_f32_e32 v23, v21, v44
	v_cvt_pk_bf16_f32 v0, v23, v193
	global_store_short v[6:7], v0, off offset:2048
	v_add_co_u32_e32 v6, vcc, 0x1788d000, v16
	v_fmac_f32_e32 v27, v25, v44
	v_cvt_pk_bf16_f32 v0, v27, v193
	s_nop 0
	v_addc_co_u32_e32 v7, vcc, 0, v17, vcc
	global_store_short v[6:7], v0, off
	v_fma_f32 v0, v15, v44, v19
	v_cvt_pk_bf16_f32 v0, v0, v193
	s_nop 1
	global_store_short v[6:7], v0, off offset:2048
	s_branch .LBB0_490

; __device__ __forceinline__ unsigned cvt_pk_bf16(float lo, float hi) { unsigned r; asm volatile("s_nop 0\n\tv_cvt_pk_bf16_f32 %0, %1, %2\n\ts_nop 1" : "=v"(r) : "v"(lo), "v"(hi)); return r; }
; __device__ __forceinline__ void phase_conv(const Params& p, LAS unsigned char* lds, int wg, int G, int tid) {
;     ...
;         if (fb < 48) {
;             bf16_t* dst = (fb < 32) ? xT + ((size_t)ch * 2048 + feat) * 128 + tq * 8 : bT + ((size_t)ch * 1024 + (feat - 2048)) * 128 + tq * 8;
;             u32x4 a, b; a.x = cvt_pk_bf16(o[0].x, o[1].x); a.y = cvt_pk_bf16(o[2].x, o[3].x); a.z = cvt_pk_bf16(o[4].x, o[5].x); a.w = cvt_pk_bf16(o[6].x, o[7].x);
;             b.x = cvt_pk_bf16(o[0].y, o[1].y); b.y = cvt_pk_bf16(o[2].y, o[3].y); b.z = cvt_pk_bf16(o[4].y, o[5].y); b.w = cvt_pk_bf16(o[6].y, o[7].y);
;             *(u32x4*)dst = a; *(u32x4*)(dst + 128) = b;
;         }
;         if (fb >= 32 && !(is_ctx && fb >= 48 && fb < 64)) {
;             bf16_t* dst = (fb < 48) ? bm + (feat - 2048) : (fb < 64) ? cm + (feat - 3072) : uu + (feat - 4096);
; #pragma unroll
;             for (int k = 0; k < 8; ++k) *(unsigned*)(dst + (row0 + tq * 8 + k) * 1024) = cvt_pk_bf16(o[k].x, o[k].y);
;         }
.LBB0_666:
	s_ashr_i32 s49, s48, 31
	s_cmp_lt_i32 s45, 48
	s_cselect_b64 s[22:23], -1, 0
	s_cmp_gt_i32 s45, 47
	s_cbranch_scc1 .LBB0_668
	s_cmp_lt_i32 s45, 32
	s_cselect_b64 vcc, -1, 0
	s_and_b64 s[52:53], vcc, exec
	s_mov_b32 s41, 0x1f900000
	s_cselect_b32 s41, s41, 0x2d100000
	v_add_u32_e32 v27, 0xfffff800, v26
	s_cselect_b32 s44, 19, 18
	s_add_u32 s41, s94, s41
	v_cndmask_b32_e32 v32, v27, v26, vcc
	s_addc_u32 s46, s95, 0
	s_lshl_b64 s[52:53], s[48:49], s44
	v_ashrrev_i32_e32 v33, 31, v32
	s_add_u32 s52, s41, s52
	s_addc_u32 s53, s46, s53
	v_lshlrev_b64 v[32:33], 8, v[32:33]
	v_lshl_add_u64 v[32:33], s[52:53], 0, v[32:33]
	v_lshl_add_u64 v[44:45], v[22:23], 1, v[32:33]
	v_cvt_pk_bf16_f32 v32, v16, v18
	v_cvt_pk_bf16_f32 v33, v12, v14
	v_cvt_pk_bf16_f32 v34, v28, v40
	v_cvt_pk_bf16_f32 v35, v42, v30
	v_cvt_pk_bf16_f32 v36, v17, v19
	v_cvt_pk_bf16_f32 v37, v13, v15
	v_cvt_pk_bf16_f32 v38, v29, v41
	v_cvt_pk_bf16_f32 v39, v43, v31
	global_store_dwordx4 v[44:45], v[32:35], off
	global_store_dwordx4 v[44:45], v[36:39], off offset:256
.LBB0_668:
	s_cmp_lt_i32 s45, 32
	s_cbranch_scc1 .LBB0_627
	s_and_b32 s41, s45, 0x7ffffff0
	s_cmp_eq_u32 s41, 48
	s_cselect_b64 s[44:45], -1, 0
	s_and_b64 s[20:21], s[20:21], s[44:45]
	s_and_b64 vcc, exec, s[20:21]
	s_cbranch_vccnz .LBB0_627
	s_and_b64 s[20:21], s[50:51], exec
	s_mov_b32 s20, 0x318fe800
	v_mov_b32_e32 v27, v193
	s_cselect_b32 s41, s20, 0x360fe000
	s_and_b64 s[20:21], s[22:23], exec
	v_lshl_add_u64 v[26:27], v[26:27], 1, s[94:95]
	s_cselect_b32 s66, 0x288ff000, s41
	v_lshl_add_u64 v[26:27], v[26:27], 0, s[66:67]
	s_lshl_b64 s[20:21], s[48:49], 18
	v_cvt_pk_bf16_f32 v32, v16, v17
	v_lshl_add_u64 v[16:17], v[26:27], 0, s[20:21]
	v_lshl_add_u64 v[16:17], v[16:17], 0, v[24:25]
	s_movk_i32 s20, 0x1000
	global_store_dword v[16:17], v32, off
	v_cvt_pk_bf16_f32 v18, v18, v19
	global_store_dword v[16:17], v18, off offset:2048
	v_cvt_pk_bf16_f32 v26, v12, v13
	v_add_co_u32_e32 v12, vcc, s20, v16
	s_movk_i32 s20, 0x2000
	s_nop 0
	v_addc_co_u32_e32 v13, vcc, 0, v17, vcc
	v_add_co_u32_e32 v18, vcc, s20, v16
	s_mov_b32 s66, 0x48000
	s_nop 0
	v_addc_co_u32_e32 v19, vcc, 0, v17, vcc
	global_store_dword v[18:19], v26, off offset:-4096
	v_cvt_pk_bf16_f32 v14, v14, v15
	global_store_dword v[12:13], v14, off offset:2048
	v_cvt_pk_bf16_f32 v12, v28, v29
	global_store_dword v[18:19], v12, off
	v_cvt_pk_bf16_f32 v12, v40, v41
	global_store_dword v[18:19], v12, off offset:2048
	v_add_co_u32_e32 v12, vcc, 0x3000, v16
	v_cvt_pk_bf16_f32 v14, v42, v43
	s_nop 1
	v_addc_co_u32_e32 v13, vcc, 0, v17, vcc
	global_store_dword v[12:13], v14, off
	v_cvt_pk_bf16_f32 v14, v30, v31
	s_nop 1
	global_store_dword v[12:13], v14, off offset:2048
	s_branch .LBB0_627

; __device__ __forceinline__ unsigned cvt_pk_bf16(float lo, float hi) { unsigned r; asm volatile("s_nop 0\n\tv_cvt_pk_bf16_f32 %0, %1, %2\n\ts_nop 1" : "=v"(r) : "v"(lo), "v"(hi)); return r; }
; __device__ __forceinline__ void phase_ln0(const Params& p, int g, int gw, int NGW, int lane) {
;     ...
;     for (int row = gw; row < RG; row += NGW) {
;         const int mrow = (row < CGR) ? 32 : g * BG + (row - CGR) / SEQ;
;         const float* sh = mod + (size_t)mrow * MODW; const float* sc = sh + DM;
;         f32x4 v[4]; float s = 0.f;
; #pragma unroll
;         for (int j = 0; j < 4; ++j) { v[j] = nx[j]; s += (v[j].x + v[j].y) + (v[j].z + v[j].w); }
;         if (row + NGW < RG) { const float* src = ln0_src(p, g, row + NGW);
; #pragma unroll
;             for (int j = 0; j < 4; ++j) nx[j] = *(const f32x4*)(src + 4 * lane + 256 * j); }
;         const float mean = wave_sum(s, lane) * (1.f / DM); float s2 = 0.f;
; #pragma unroll
;         for (int j = 0; j < 4; ++j) { v[j] = v[j] - mean; s2 += (v[j].x * v[j].x + v[j].y * v[j].y) + (v[j].z * v[j].z + v[j].w * v[j].w); }
;         const float rstd = __builtin_amdgcn_rsqf(wave_sum(s2, lane) * (1.f / DM) + 1e-6f);
; #pragma unroll
;         for (int j = 0; j < 4; ++j) { const int col = 4 * lane + 256 * j; const f32x4 a = *(const f32x4*)(sc + col), b = *(const f32x4*)(sh + col);
;             const f32x4 o = v[j] * rstd * (a + 1.f) + b; u32x2 w; w.x = cvt_pk_bf16(o.x, o.y); w.y = cvt_pk_bf16(o.z, o.w);
;             *(u32x2*)(h0 + (size_t)row * DM + col) = w; }
.LBB0_679:
	v_add_f32_e32 v44, v12, v13
	v_add_f32_e32 v45, v14, v15
	v_add_f32_e32 v44, v44, v45
	v_add_f32_e32 v45, v8, v9
	v_add_f32_e32 v46, v10, v11
	v_add_f32_e32 v44, 0, v44
	v_add_f32_e32 v45, v45, v46
	v_add_f32_e32 v44, v45, v44
	v_add_f32_e32 v45, v4, v5
	v_add_f32_e32 v46, v6, v7
	v_add_f32_e32 v45, v45, v46
	v_add_f32_e32 v44, v45, v44
	v_add_f32_e32 v45, v0, v1
	v_add_f32_e32 v46, v2, v3
	v_add_f32_e32 v45, v45, v46
	v_add_f32_e32 v44, v45, v44
	ds_bpermute_b32 v45, v34, v44
	s_lshl_b64 s[2:3], s[2:3], 2
	s_add_u32 s2, s94, s2
	s_addc_u32 s3, s95, s3
	s_add_u32 s4, s2, 0x1000
	s_waitcnt lgkmcnt(0)
	v_add_f32_e32 v44, v44, v45
	ds_bpermute_b32 v45, v35, v44
	s_addc_u32 s5, s3, 0
	s_and_b64 vcc, exec, s[0:1]
	v_readlane_b32 s0, v255, 2
	v_readlane_b32 s1, v255, 3
	s_waitcnt lgkmcnt(0)
	v_add_f32_e32 v44, v44, v45
	ds_bpermute_b32 v45, v36, v44
	s_waitcnt lgkmcnt(0)
	v_add_f32_e32 v44, v44, v45
	ds_bpermute_b32 v45, v37, v44
	s_waitcnt lgkmcnt(0)
	v_add_f32_e32 v44, v44, v45
	ds_bpermute_b32 v45, v38, v44
	s_waitcnt lgkmcnt(0)
	v_add_f32_e32 v52, v44, v45
	global_load_dwordx4 v[44:47], v40, s[4:5]
	global_load_dwordx4 v[48:51], v40, s[2:3]
	ds_bpermute_b32 v53, v39, v52
	s_waitcnt lgkmcnt(0)
	v_add_f32_e32 v60, v52, v53
	v_fmac_f32_e32 v13, 0xba800000, v60
	v_fmac_f32_e32 v12, 0xba800000, v60
	v_fmac_f32_e32 v15, 0xba800000, v60
	v_fmac_f32_e32 v14, 0xba800000, v60
	v_pk_mul_f32 v[52:53], v[14:15], v[14:15]
	v_pk_mul_f32 v[54:55], v[12:13], v[12:13]
	v_fmac_f32_e32 v9, 0xba800000, v60
	v_pk_mov_b32 v[56:57], v[54:55], v[52:53] op_sel:[1,0]
	v_mov_b32_e32 v55, v53
	v_fmac_f32_e32 v8, 0xba800000, v60
	v_pk_add_f32 v[52:53], v[56:57], v[54:55]
	v_fmac_f32_e32 v11, 0xba800000, v60
	v_fmac_f32_e32 v10, 0xba800000, v60
	v_pk_add_f32 v[52:53], v[52:53], v[52:53] op_sel_hi:[0,1]
	v_pk_mul_f32 v[54:55], v[10:11], v[10:11]
	v_pk_mul_f32 v[56:57], v[8:9], v[8:9]
	v_fmac_f32_e32 v4, 0xba800000, v60
	v_pk_mov_b32 v[58:59], v[56:57], v[54:55] op_sel:[1,0]
	v_mov_b32_e32 v57, v55
	v_fmac_f32_e32 v5, 0xba800000, v60
	v_fmac_f32_e32 v6, 0xba800000, v60
	v_mul_f32_e32 v52, v4, v4
	v_pk_add_f32 v[54:55], v[58:59], v[56:57]
	v_fmac_f32_e32 v7, 0xba800000, v60
	v_pk_fma_f32 v[56:57], v[4:5], v[4:5], v[52:53] op_sel_hi:[1,1,0]
	v_mul_f32_e32 v52, v6, v6
	v_pk_add_f32 v[54:55], v[54:55], v[54:55] op_sel_hi:[0,1]
	v_pk_fma_f32 v[58:59], v[6:7], v[6:7], v[52:53] op_sel_hi:[1,1,0]
	v_fmac_f32_e32 v3, 0xba800000, v60
	v_fmac_f32_e32 v2, 0xba800000, v60
	v_fmac_f32_e32 v1, 0xba800000, v60
	v_fmac_f32_e32 v0, 0xba800000, v60
	v_mul_f32_e32 v56, v0, v0
	v_mul_f32_e32 v58, v1, v1
	v_mul_f32_e32 v52, v2, v2
	v_mul_f32_e32 v54, v3, v3
	v_pk_add_f32 v[56:57], v[56:57], v[58:59]
	v_pk_add_f32 v[52:53], v[52:53], v[54:55]
	s_waitcnt vmcnt(1)
	v_pk_add_f32 v[44:45], v[44:45], 1.0 op_sel_hi:[1,0]
	v_pk_add_f32 v[52:53], v[56:57], v[52:53]
	v_pk_add_f32 v[46:47], v[46:47], 1.0 op_sel_hi:[1,0]
	v_add_f32_e32 v52, v52, v53
	ds_bpermute_b32 v53, v34, v52
	s_waitcnt lgkmcnt(0)
	v_add_f32_e32 v52, v52, v53
	ds_bpermute_b32 v53, v35, v52
	s_waitcnt lgkmcnt(0)
	v_add_f32_e32 v52, v52, v53
	ds_bpermute_b32 v53, v36, v52
	s_waitcnt lgkmcnt(0)
	v_add_f32_e32 v52, v52, v53
	ds_bpermute_b32 v53, v37, v52
	s_waitcnt lgkmcnt(0)
	v_add_f32_e32 v52, v52, v53
	ds_bpermute_b32 v53, v38, v52
	s_waitcnt lgkmcnt(0)
	v_add_f32_e32 v52, v52, v53
	ds_bpermute_b32 v53, v39, v52
	s_waitcnt lgkmcnt(0)
	v_add_f32_e32 v52, v52, v53
	v_fmamk_f32 v52, v52, 0x3a800000, v238
	v_rsq_f32_e32 v52, v52
	s_nop 0
	v_pk_mul_f32 v[12:13], v[12:13], v[52:53] op_sel_hi:[1,0]
	v_pk_mul_f32 v[14:15], v[14:15], v[52:53] op_sel_hi:[1,0]
	s_waitcnt vmcnt(0)
	v_pk_fma_f32 v[12:13], v[44:45], v[12:13], v[48:49]
	v_pk_fma_f32 v[14:15], v[46:47], v[14:15], v[50:51]
	v_cvt_pk_bf16_f32 v12, v12, v13
	v_pk_mul_f32 v[8:9], v[8:9], v[52:53] op_sel_hi:[1,0]
	v_cvt_pk_bf16_f32 v13, v14, v15
	global_store_dwordx2 v[32:33], v[12:13], off
	global_load_dwordx4 v[12:15], v41, s[4:5]
	s_nop 0
	global_load_dwordx4 v[44:47], v40, s[2:3] offset:1024
	v_pk_mul_f32 v[10:11], v[10:11], v[52:53] op_sel_hi:[1,0]
	v_pk_mul_f32 v[4:5], v[4:5], v[52:53] op_sel_hi:[1,0]
	v_pk_mul_f32 v[6:7], v[6:7], v[52:53] op_sel_hi:[1,0]
	v_pk_mul_f32 v[54:55], v[0:1], v[52:53] op_sel_hi:[1,0]
	v_pk_mul_f32 v[52:53], v[2:3], v[52:53] op_sel_hi:[1,0]
	v_mov_b32_e32 v0, v28
	v_mov_b32_e32 v1, v29
	v_mov_b32_e32 v2, v30
	v_mov_b32_e32 v3, v31
	s_waitcnt vmcnt(1)
	v_pk_add_f32 v[12:13], v[12:13], 1.0 op_sel_hi:[1,0]
	v_pk_add_f32 v[14:15], v[14:15], 1.0 op_sel_hi:[1,0]
	s_waitcnt vmcnt(0)
	v_pk_fma_f32 v[8:9], v[12:13], v[8:9], v[44:45]
	v_pk_fma_f32 v[10:11], v[14:15], v[10:11], v[46:47]
	v_cvt_pk_bf16_f32 v8, v8, v9
	s_nop 0
	v_cvt_pk_bf16_f32 v9, v10, v11
	global_store_dwordx2 v[32:33], v[8:9], off offset:512
	global_load_dwordx4 v[8:11], v42, s[4:5]
	s_nop 0
	global_load_dwordx4 v[12:15], v40, s[2:3] offset:2048
	s_waitcnt vmcnt(1)
	v_pk_add_f32 v[8:9], v[8:9], 1.0 op_sel_hi:[1,0]
	v_pk_add_f32 v[10:11], v[10:11], 1.0 op_sel_hi:[1,0]
	s_waitcnt vmcnt(0)
	v_pk_fma_f32 v[4:5], v[8:9], v[4:5], v[12:13]
	v_pk_fma_f32 v[6:7], v[10:11], v[6:7], v[14:15]
	v_cvt_pk_bf16_f32 v4, v4, v5
	v_mov_b32_e32 v14, v18
	v_cvt_pk_bf16_f32 v5, v6, v7
	global_store_dwordx2 v[32:33], v[4:5], off offset:1024
	global_load_dwordx4 v[44:47], v43, s[4:5]
	global_load_dwordx4 v[48:51], v40, s[2:3] offset:3072
	v_mov_b32_e32 v15, v19
	v_mov_b32_e32 v12, v16
	v_mov_b32_e32 v13, v17
	v_mov_b32_e32 v8, v20
	v_mov_b32_e32 v9, v21
	v_mov_b32_e32 v10, v22
	v_mov_b32_e32 v11, v23
	v_mov_b32_e32 v4, v24
	v_mov_b32_e32 v5, v25
	v_mov_b32_e32 v6, v26
	v_mov_b32_e32 v7, v27
	s_waitcnt vmcnt(1)
	v_pk_add_f32 v[18:19], v[44:45], 1.0 op_sel_hi:[1,0]
	v_pk_add_f32 v[16:17], v[46:47], 1.0 op_sel_hi:[1,0]
	s_waitcnt vmcnt(0)
	v_pk_fma_f32 v[18:19], v[18:19], v[54:55], v[48:49]
	v_pk_fma_f32 v[16:17], v[16:17], v[52:53], v[50:51]
	v_cvt_pk_bf16_f32 v18, v18, v19
	s_nop 0
	v_cvt_pk_bf16_f32 v19, v16, v17
	global_store_dwordx2 v[32:33], v[18:19], off offset:1536
	v_lshl_add_u64 v[32:33], v[32:33], 0, s[0:1]
	s_cbranch_vccnz .LBB0_684

; #define PG8_STAGE(bufoff, gbase, voff) do { _Pragma("unroll") for (int _i = 0; _i < 2; ++_i) \
;         __builtin_amdgcn_global_load_lds((const unsigned*)((const char*)(gbase) + (voff)[_i]), (PG8_LAS unsigned*)(lds + (bufoff) + ldsw + _i * 8192), 16, 0, 0); } while (0)
; #define PG8_LDA(dst, b, h) do { _Pragma("unroll") for (int m = 0; m < 4; ++m) _Pragma("unroll") for (int k = 0; k < 2; ++k) dst[m][k] = *(const PG8_LAS bf16x8*)(lds + PG8_SA(b, h) + aoff + m * 2048 + k * 1024); } while (0)
; #define PG8_LDB(dst, b, h) do { _Pragma("unroll") for (int n = 0; n < 2; ++n) _Pragma("unroll") for (int k = 0; k < 2; ++k) dst[n][k] = *(const PG8_LAS bf16x8*)(lds + PG8_SB(b, h) + boff + n * 2048 + k * 1024); } while (0)
; #define PG8_MMA(ai, bj, At, Bt) do { __builtin_amdgcn_s_setprio(1); _Pragma("unroll") for (int m = 0; m < 4; ++m) _Pragma("unroll") for (int n = 0; n < 2; ++n) _Pragma("unroll") for (int k = 0; k < 2; ++k) \
;         acc[ai][bj][m][n] = __builtin_amdgcn_mfma_f32_16x16x32_bf16(Bt[n][k], At[m][k], acc[ai][bj][m][n], 0, 0, 0); __builtin_amdgcn_s_setprio(0); } while (0)
; #define PG8_WAIT_V(n) asm volatile("s_waitcnt vmcnt(" #n ")" ::: "memory")
; #define PG8_WAIT_L(n) asm volatile("s_waitcnt lgkmcnt(" #n ")" ::: "memory")
; #define PG8_BAR __builtin_amdgcn_s_barrier()
; #define PG8_SCHED __builtin_amdgcn_sched_barrier(0)
; template <class Epi, class Sched>
; __device__ __forceinline__ void gemm_phase(PG8_LAS unsigned char* lds, const Gemm g, const Sched& S, const Epi& E, int tid_in) {
;     ...
;             PG8_LDB(B0, 0, 0); PG8_SCHED; PG8_LDA(At, 0, 0); PG8_STAGE(PG8_SA(1, 1), a1 + hstep, voffA);
;             PG8_WAIT_L(8); PG8_BAR; PG8_WAIT_L(0); PG8_MMA(0, 0, At, B0); PG8_BAR; PG8_SCHED;
;             PG8_LDB(B1, 0, 1); PG8_STAGE(PG8_SB(0, 0), b2, voffB);
;             PG8_BAR; PG8_WAIT_L(0); PG8_MMA(0, 1, At, B1); PG8_BAR;
;             PG8_LDA(At, 0, 1); PG8_STAGE(PG8_SA(0, 0), a2, voffA);
;             PG8_BAR; PG8_WAIT_L(0); PG8_MMA(1, 0, At, B0); PG8_BAR; PG8_SCHED;
;             PG8_STAGE(PG8_SB(0, 1), b2 + hstep, voffB);
;             PG8_WAIT_V(6); PG8_BAR; PG8_MMA(1, 1, At, B1); PG8_BAR;
.LBB0_696:
	s_add_u32 s18, s16, 0xfffc0080
	s_addc_u32 s19, s17, -1
	s_add_i32 s43, 0, 0x10000
	v_add_u32_e32 v154, s43, v143
	ds_read_b128 v[138:141], v154
	ds_read_b128 v[146:149], v154 offset:1024
	ds_read_b128 v[150:153], v154 offset:2048
	ds_read_b128 v[154:157], v154 offset:3072
	s_cmp_eq_u32 s42, 12
	s_cselect_b32 s21, s5, s19
	s_cselect_b32 s20, s7, s18
	s_cselect_b32 s19, s9, s41
	s_cselect_b32 s18, s11, s40
	v_lshl_add_u64 v[190:191], s[16:17], 0, v[134:135]
	s_add_i32 m0, s28, 0xc000
	ds_read_b128 v[158:161], v145
	ds_read_b128 v[162:165], v145 offset:1024
	ds_read_b128 v[166:169], v145 offset:2048
	ds_read_b128 v[170:173], v145 offset:3072
	ds_read_b128 v[174:177], v145 offset:4096
	ds_read_b128 v[178:181], v145 offset:5120
	ds_read_b128 v[182:185], v145 offset:6144
	ds_read_b128 v[186:189], v145 offset:7168
	global_load_lds_dwordx4 v[190:191], off
	v_lshl_add_u64 v[190:191], s[16:17], 0, v[136:137]
	s_add_i32 m0, s28, 0xe000
	s_nop 0
	global_load_lds_dwordx4 v[190:191], off
	s_waitcnt lgkmcnt(8)
	s_barrier
	s_waitcnt lgkmcnt(0)
	s_setprio 1
	s_waitcnt lgkmcnt(0)
	v_mfma_f32_16x16x32_bf16 v[124:127], v[138:141], v[158:161], v[124:127]
	v_mfma_f32_16x16x32_bf16 v[120:123], v[150:153], v[158:161], v[120:123]
	v_mfma_f32_16x16x32_bf16 v[112:115], v[138:141], v[166:169], v[112:115]
	v_mfma_f32_16x16x32_bf16 v[104:107], v[150:153], v[166:169], v[104:107]
	v_mfma_f32_16x16x32_bf16 v[96:99], v[138:141], v[174:177], v[96:99]
	v_mfma_f32_16x16x32_bf16 v[88:91], v[150:153], v[174:177], v[88:91]
	v_mfma_f32_16x16x32_bf16 v[80:83], v[138:141], v[182:185], v[80:83]
	v_mfma_f32_16x16x32_bf16 v[72:75], v[150:153], v[182:185], v[72:75]
	v_mfma_f32_16x16x32_bf16 v[124:127], v[146:149], v[162:165], v[124:127]
	v_mfma_f32_16x16x32_bf16 v[120:123], v[154:157], v[162:165], v[120:123]
	v_mfma_f32_16x16x32_bf16 v[112:115], v[146:149], v[170:173], v[112:115]
	v_mfma_f32_16x16x32_bf16 v[104:107], v[154:157], v[170:173], v[104:107]
	v_mfma_f32_16x16x32_bf16 v[96:99], v[146:149], v[178:181], v[96:99]
	v_mfma_f32_16x16x32_bf16 v[88:91], v[154:157], v[178:181], v[88:91]
	v_mfma_f32_16x16x32_bf16 v[80:83], v[146:149], v[186:189], v[80:83]
	v_mfma_f32_16x16x32_bf16 v[72:75], v[154:157], v[186:189], v[72:75]
	s_setprio 0
	s_barrier
	s_add_i32 s46, 0, 0x14000
	v_add_u32_e32 v190, s46, v143
	s_add_i32 s43, s43, s27
	ds_read_b128 v[200:203], v190
	ds_read_b128 v[204:207], v190 offset:1024
	ds_read_b128 v[208:211], v190 offset:2048
	ds_read_b128 v[212:215], v190 offset:3072
	v_lshl_add_u64 v[190:191], s[18:19], 0, v[192:193]
	s_mov_b32 m0, s43
	v_lshl_add_u64 v[194:195], s[18:19], 0, v[132:133]
	global_load_lds_dwordx4 v[190:191], off
	s_add_i32 m0, s43, 0x2000
	s_nop 0
	global_load_lds_dwordx4 v[194:195], off
	s_barrier
	s_waitcnt lgkmcnt(0)
	s_setprio 1
	s_waitcnt lgkmcnt(0)
	v_mfma_f32_16x16x32_bf16 v[116:119], v[200:203], v[158:161], v[116:119]
	v_mfma_f32_16x16x32_bf16 v[108:111], v[208:211], v[158:161], v[108:111]
	v_mfma_f32_16x16x32_bf16 v[100:103], v[200:203], v[166:169], v[100:103]
	v_mfma_f32_16x16x32_bf16 v[92:95], v[208:211], v[166:169], v[92:95]
	v_mfma_f32_16x16x32_bf16 v[84:87], v[200:203], v[174:177], v[84:87]
	v_mfma_f32_16x16x32_bf16 v[76:79], v[208:211], v[174:177], v[76:79]
	v_mfma_f32_16x16x32_bf16 v[68:71], v[200:203], v[182:185], v[68:71]
	v_mfma_f32_16x16x32_bf16 v[64:67], v[208:211], v[182:185], v[64:67]
	v_mfma_f32_16x16x32_bf16 v[116:119], v[204:207], v[162:165], v[116:119]
	v_mfma_f32_16x16x32_bf16 v[108:111], v[212:215], v[162:165], v[108:111]
	v_mfma_f32_16x16x32_bf16 v[100:103], v[204:207], v[170:173], v[100:103]
	v_mfma_f32_16x16x32_bf16 v[92:95], v[212:215], v[170:173], v[92:95]
	v_mfma_f32_16x16x32_bf16 v[84:87], v[204:207], v[178:181], v[84:87]
	v_mfma_f32_16x16x32_bf16 v[76:79], v[212:215], v[178:181], v[76:79]
	v_mfma_f32_16x16x32_bf16 v[68:71], v[204:207], v[186:189], v[68:71]
	v_mfma_f32_16x16x32_bf16 v[64:67], v[212:215], v[186:189], v[64:67]
	s_setprio 0
	s_mov_b32 m0, s28
	v_lshl_add_u64 v[196:197], s[20:21], 0, v[128:129]
	s_barrier
	ds_read_b128 v[158:161], v145 offset:16384
	ds_read_b128 v[162:165], v145 offset:17408
	ds_read_b128 v[166:169], v145 offset:18432
	ds_read_b128 v[170:173], v145 offset:19456
	ds_read_b128 v[174:177], v145 offset:20480
	ds_read_b128 v[178:181], v145 offset:21504
	ds_read_b128 v[182:185], v145 offset:22528
	ds_read_b128 v[186:189], v145 offset:23552
	global_load_lds_dwordx4 v[196:197], off
	v_lshl_add_u64 v[216:217], s[20:21], 0, v[130:131]
	s_mov_b32 m0, s29
	s_nop 0
	global_load_lds_dwordx4 v[216:217], off
	s_barrier
	s_waitcnt lgkmcnt(0)
	s_setprio 1
	s_waitcnt lgkmcnt(0)
	v_mfma_f32_16x16x32_bf16 v[60:63], v[138:141], v[158:161], v[60:63]
	v_mfma_f32_16x16x32_bf16 v[56:59], v[150:153], v[158:161], v[56:59]
	v_mfma_f32_16x16x32_bf16 v[48:51], v[138:141], v[166:169], v[48:51]
	v_mfma_f32_16x16x32_bf16 v[40:43], v[150:153], v[166:169], v[40:43]
	v_mfma_f32_16x16x32_bf16 v[32:35], v[138:141], v[174:177], v[32:35]
	v_mfma_f32_16x16x32_bf16 v[24:27], v[150:153], v[174:177], v[24:27]
	v_mfma_f32_16x16x32_bf16 v[16:19], v[138:141], v[182:185], v[16:19]
	v_mfma_f32_16x16x32_bf16 v[8:11], v[150:153], v[182:185], v[8:11]
	v_mfma_f32_16x16x32_bf16 v[60:63], v[146:149], v[162:165], v[60:63]
	v_mfma_f32_16x16x32_bf16 v[56:59], v[154:157], v[162:165], v[56:59]
	v_mfma_f32_16x16x32_bf16 v[48:51], v[146:149], v[170:173], v[48:51]
	v_mfma_f32_16x16x32_bf16 v[40:43], v[154:157], v[170:173], v[40:43]
	v_mfma_f32_16x16x32_bf16 v[32:35], v[146:149], v[178:181], v[32:35]
	v_mfma_f32_16x16x32_bf16 v[24:27], v[154:157], v[178:181], v[24:27]
	v_mfma_f32_16x16x32_bf16 v[16:19], v[146:149], v[186:189], v[16:19]
	v_mfma_f32_16x16x32_bf16 v[8:11], v[154:157], v[186:189], v[8:11]
	s_setprio 0
	s_barrier
; #define PG8_STAGE(bufoff, gbase, voff) do { _Pragma("unroll") for (int _i = 0; _i < 2; ++_i) \
;         __builtin_amdgcn_global_load_lds((const unsigned*)((const char*)(gbase) + (voff)[_i]), (PG8_LAS unsigned*)(lds + (bufoff) + ldsw + _i * 8192), 16, 0, 0); } while (0)
; #define PG8_LDA(dst, b, h) do { _Pragma("unroll") for (int m = 0; m < 4; ++m) _Pragma("unroll") for (int k = 0; k < 2; ++k) dst[m][k] = *(const PG8_LAS bf16x8*)(lds + PG8_SA(b, h) + aoff + m * 2048 + k * 1024); } while (0)
; #define PG8_LDB(dst, b, h) do { _Pragma("unroll") for (int n = 0; n < 2; ++n) _Pragma("unroll") for (int k = 0; k < 2; ++k) dst[n][k] = *(const PG8_LAS bf16x8*)(lds + PG8_SB(b, h) + boff + n * 2048 + k * 1024); } while (0)
; #define PG8_MMA(ai, bj, At, Bt) do { __builtin_amdgcn_s_setprio(1); _Pragma("unroll") for (int m = 0; m < 4; ++m) _Pragma("unroll") for (int n = 0; n < 2; ++n) _Pragma("unroll") for (int k = 0; k < 2; ++k) \
;         acc[ai][bj][m][n] = __builtin_amdgcn_mfma_f32_16x16x32_bf16(Bt[n][k], At[m][k], acc[ai][bj][m][n], 0, 0, 0); __builtin_amdgcn_s_setprio(0); } while (0)
; #define PG8_WAIT_V(n) asm volatile("s_waitcnt vmcnt(" #n ")" ::: "memory")
; #define PG8_WAIT_L(n) asm volatile("s_waitcnt lgkmcnt(" #n ")" ::: "memory")
; #define PG8_BAR __builtin_amdgcn_s_barrier()
; #define PG8_SCHED __builtin_amdgcn_sched_barrier(0)
; template <class Epi, class Sched>
; __device__ __forceinline__ void gemm_phase(PG8_LAS unsigned char* lds, const Gemm g, const Sched& S, const Epi& E, int tid_in) {
;     ...
;             PG8_WAIT_V(6); PG8_BAR; PG8_MMA(1, 1, At, B1); PG8_BAR;
;             PG8_LDB(B0, 1, 0); PG8_SCHED; PG8_LDA(At, 1, 0); PG8_STAGE(PG8_SA(0, 1), a2 + hstep, voffA);
;             PG8_WAIT_L(8); PG8_BAR; PG8_WAIT_L(0); PG8_MMA(0, 0, At, B0); PG8_BAR; PG8_SCHED;
;             PG8_LDB(B1, 1, 1); PG8_STAGE(PG8_SB(1, 0), b3, voffB);
;             PG8_BAR; PG8_WAIT_L(0); PG8_MMA(0, 1, At, B1); PG8_BAR;
;             PG8_LDA(At, 1, 1); PG8_STAGE(PG8_SA(1, 0), a3, voffA);
;             PG8_BAR; PG8_WAIT_L(0); PG8_MMA(1, 0, At, B0); PG8_BAR; PG8_SCHED;
	s_add_u32 s44, s18, 0x40000
	s_addc_u32 s45, s19, 0
	s_add_i32 s43, s46, s27
	v_lshl_add_u64 v[138:139], s[44:45], 0, v[192:193]
	s_mov_b32 m0, s43
	s_nop 0
	global_load_lds_dwordx4 v[138:139], off
	v_lshl_add_u64 v[138:139], s[44:45], 0, v[132:133]
	s_add_i32 m0, s43, 0x2000
	s_nop 0
	global_load_lds_dwordx4 v[138:139], off
	s_waitcnt vmcnt(6)
	s_barrier
	s_setprio 1
	v_mfma_f32_16x16x32_bf16 v[52:55], v[200:203], v[158:161], v[52:55]
	v_mfma_f32_16x16x32_bf16 v[44:47], v[208:211], v[158:161], v[44:47]
	v_mfma_f32_16x16x32_bf16 v[36:39], v[200:203], v[166:169], v[36:39]
	v_mfma_f32_16x16x32_bf16 v[28:31], v[208:211], v[166:169], v[28:31]
	v_mfma_f32_16x16x32_bf16 v[20:23], v[200:203], v[174:177], v[20:23]
	v_mfma_f32_16x16x32_bf16 v[12:15], v[208:211], v[174:177], v[12:15]
	v_mfma_f32_16x16x32_bf16 v[4:7], v[200:203], v[182:185], v[4:7]
	v_mfma_f32_16x16x32_bf16 v[0:3], v[208:211], v[182:185], v[0:3]
	v_mfma_f32_16x16x32_bf16 v[52:55], v[204:207], v[162:165], v[52:55]
	v_mfma_f32_16x16x32_bf16 v[44:47], v[212:215], v[162:165], v[44:47]
	v_mfma_f32_16x16x32_bf16 v[36:39], v[204:207], v[170:173], v[36:39]
	v_mfma_f32_16x16x32_bf16 v[28:31], v[212:215], v[170:173], v[28:31]
	v_mfma_f32_16x16x32_bf16 v[20:23], v[204:207], v[178:181], v[20:23]
	v_mfma_f32_16x16x32_bf16 v[12:15], v[212:215], v[178:181], v[12:15]
	v_mfma_f32_16x16x32_bf16 v[4:7], v[204:207], v[186:189], v[4:7]
	v_mfma_f32_16x16x32_bf16 v[0:3], v[212:215], v[186:189], v[0:3]
	s_setprio 0
	s_add_i32 s43, 0, 0x18000
	v_add_u32_e32 v154, s43, v143
	s_barrier
	ds_read_b128 v[138:141], v154
	ds_read_b128 v[146:149], v154 offset:1024
	ds_read_b128 v[150:153], v154 offset:2048
	ds_read_b128 v[154:157], v154 offset:3072
	s_add_u32 s20, s20, 0x40000
	s_addc_u32 s21, s21, 0
	s_mov_b32 m0, s30
	v_lshl_add_u64 v[200:201], s[20:21], 0, v[128:129]
	ds_read_b128 v[158:161], v145 offset:32768
	ds_read_b128 v[162:165], v145 offset:33792
	ds_read_b128 v[166:169], v145 offset:34816
	ds_read_b128 v[170:173], v145 offset:35840
	ds_read_b128 v[174:177], v145 offset:36864
	ds_read_b128 v[178:181], v145 offset:37888
	ds_read_b128 v[182:185], v145 offset:38912
	ds_read_b128 v[186:189], v145 offset:39936
	global_load_lds_dwordx4 v[200:201], off
	v_lshl_add_u64 v[200:201], s[20:21], 0, v[130:131]
	s_mov_b32 m0, s31
	s_nop 0
	global_load_lds_dwordx4 v[200:201], off
	s_waitcnt lgkmcnt(8)
	s_barrier
	s_waitcnt lgkmcnt(0)
	s_setprio 1
	s_waitcnt lgkmcnt(0)
	v_mfma_f32_16x16x32_bf16 v[124:127], v[138:141], v[158:161], v[124:127]
	v_mfma_f32_16x16x32_bf16 v[120:123], v[150:153], v[158:161], v[120:123]
	v_mfma_f32_16x16x32_bf16 v[112:115], v[138:141], v[166:169], v[112:115]
	v_mfma_f32_16x16x32_bf16 v[104:107], v[150:153], v[166:169], v[104:107]
	v_mfma_f32_16x16x32_bf16 v[96:99], v[138:141], v[174:177], v[96:99]
	v_mfma_f32_16x16x32_bf16 v[88:91], v[150:153], v[174:177], v[88:91]
	v_mfma_f32_16x16x32_bf16 v[80:83], v[138:141], v[182:185], v[80:83]
	v_mfma_f32_16x16x32_bf16 v[72:75], v[150:153], v[182:185], v[72:75]
	v_mfma_f32_16x16x32_bf16 v[124:127], v[146:149], v[162:165], v[124:127]
	v_mfma_f32_16x16x32_bf16 v[120:123], v[154:157], v[162:165], v[120:123]
	v_mfma_f32_16x16x32_bf16 v[112:115], v[146:149], v[170:173], v[112:115]
	v_mfma_f32_16x16x32_bf16 v[104:107], v[154:157], v[170:173], v[104:107]
	v_mfma_f32_16x16x32_bf16 v[96:99], v[146:149], v[178:181], v[96:99]
	v_mfma_f32_16x16x32_bf16 v[88:91], v[154:157], v[178:181], v[88:91]
	v_mfma_f32_16x16x32_bf16 v[80:83], v[146:149], v[186:189], v[80:83]
	v_mfma_f32_16x16x32_bf16 v[72:75], v[154:157], v[186:189], v[72:75]
	s_setprio 0
	s_barrier
	s_add_i32 s20, 0, 0x1c000
	s_add_i32 s21, s43, s27
	v_add_u32_e32 v199, s20, v143
	v_lshl_add_u64 v[190:191], v[190:191], 0, s[74:75]
	s_mov_b32 m0, s21
	ds_read_b128 v[200:203], v199
	ds_read_b128 v[204:207], v199 offset:1024
	ds_read_b128 v[208:211], v199 offset:2048
	ds_read_b128 v[212:215], v199 offset:3072
	global_load_lds_dwordx4 v[190:191], off
	v_lshl_add_u64 v[190:191], v[194:195], 0, s[74:75]
	s_add_i32 m0, s21, 0x2000
	s_nop 0
	global_load_lds_dwordx4 v[190:191], off
	s_barrier
	s_waitcnt lgkmcnt(0)
	s_setprio 1
	s_waitcnt lgkmcnt(0)
	v_mfma_f32_16x16x32_bf16 v[116:119], v[200:203], v[158:161], v[116:119]
	v_mfma_f32_16x16x32_bf16 v[108:111], v[208:211], v[158:161], v[108:111]
	v_mfma_f32_16x16x32_bf16 v[100:103], v[200:203], v[166:169], v[100:103]
	v_mfma_f32_16x16x32_bf16 v[92:95], v[208:211], v[166:169], v[92:95]
	v_mfma_f32_16x16x32_bf16 v[84:87], v[200:203], v[174:177], v[84:87]
	v_mfma_f32_16x16x32_bf16 v[76:79], v[208:211], v[174:177], v[76:79]
	v_mfma_f32_16x16x32_bf16 v[68:71], v[200:203], v[182:185], v[68:71]
	v_mfma_f32_16x16x32_bf16 v[64:67], v[208:211], v[182:185], v[64:67]
	v_mfma_f32_16x16x32_bf16 v[116:119], v[204:207], v[162:165], v[116:119]
	v_mfma_f32_16x16x32_bf16 v[108:111], v[212:215], v[162:165], v[108:111]
	v_mfma_f32_16x16x32_bf16 v[100:103], v[204:207], v[170:173], v[100:103]
	v_mfma_f32_16x16x32_bf16 v[92:95], v[212:215], v[170:173], v[92:95]
	v_mfma_f32_16x16x32_bf16 v[84:87], v[204:207], v[178:181], v[84:87]
	v_mfma_f32_16x16x32_bf16 v[76:79], v[212:215], v[178:181], v[76:79]
	v_mfma_f32_16x16x32_bf16 v[68:71], v[204:207], v[186:189], v[68:71]
	v_mfma_f32_16x16x32_bf16 v[64:67], v[212:215], v[186:189], v[64:67]
	s_setprio 0
	s_mov_b32 m0, s36
	v_lshl_add_u64 v[190:191], v[196:197], 0, s[74:75]
	s_barrier
	ds_read_b128 v[158:161], v145 offset:49152
	ds_read_b128 v[162:165], v145 offset:50176
	ds_read_b128 v[166:169], v145 offset:51200
	ds_read_b128 v[170:173], v145 offset:52224
	ds_read_b128 v[174:177], v145 offset:53248
	ds_read_b128 v[178:181], v145 offset:54272
	ds_read_b128 v[182:185], v145 offset:55296
	ds_read_b128 v[186:189], v145 offset:56320
	global_load_lds_dwordx4 v[190:191], off
	v_lshl_add_u64 v[190:191], v[216:217], 0, s[74:75]
	s_mov_b32 m0, s37
	s_nop 0
	global_load_lds_dwordx4 v[190:191], off
	s_barrier
; __device__ __forceinline__ unsigned cvt_pk_bf16(float lo, float hi) { unsigned r; asm volatile("s_nop 0\n\tv_cvt_pk_bf16_f32 %0, %1, %2\n\ts_nop 1" : "=v"(r) : "v"(lo), "v"(hi)); return r; }
; #define PG8_STAGE(bufoff, gbase, voff) do { _Pragma("unroll") for (int _i = 0; _i < 2; ++_i) \
;         __builtin_amdgcn_global_load_lds((const unsigned*)((const char*)(gbase) + (voff)[_i]), (PG8_LAS unsigned*)(lds + (bufoff) + ldsw + _i * 8192), 16, 0, 0); } while (0)
; #define PG8_MMA(ai, bj, At, Bt) do { __builtin_amdgcn_s_setprio(1); _Pragma("unroll") for (int m = 0; m < 4; ++m) _Pragma("unroll") for (int n = 0; n < 2; ++n) _Pragma("unroll") for (int k = 0; k < 2; ++k) \
;         acc[ai][bj][m][n] = __builtin_amdgcn_mfma_f32_16x16x32_bf16(Bt[n][k], At[m][k], acc[ai][bj][m][n], 0, 0, 0); __builtin_amdgcn_s_setprio(0); } while (0)
; #define PG8_WAIT_V(n) asm volatile("s_waitcnt vmcnt(" #n ")" ::: "memory")
; #define PG8_WAIT_L(n) asm volatile("s_waitcnt lgkmcnt(" #n ")" ::: "memory")
; #define PG8_BAR __builtin_amdgcn_s_barrier()
; #define PG8_SCHED __builtin_amdgcn_sched_barrier(0)
; template <class Epi, class Sched>
; __device__ __forceinline__ void gemm_phase(PG8_LAS unsigned char* lds, const Gemm g, const Sched& S, const Epi& E, int tid_in) {
;     ...
;             PG8_BAR; PG8_WAIT_L(0); PG8_MMA(1, 0, At, B0); PG8_BAR; PG8_SCHED;
;             PG8_STAGE(PG8_SB(1, 1), b3 + hstep, voffB);
;             PG8_WAIT_V(6); PG8_BAR; PG8_MMA(1, 1, At, B1); PG8_BAR;
;         }
;     __device__ __forceinline__ void operator()(f32x4 (&acc)[2][2][4][2], const Unit& u, int wr, int wc, int fr, int fq) const {
;         const int row0 = u.pm * 256 + wr * 64 + fr, col0 = u.pn * 256 + wc * 32 + 8 * fq;
; #pragma unroll
;         for (int ai = 0; ai < 2; ++ai)
; #pragma unroll
;             for (int m = 0; m < 4; ++m) { bf16_t* rowp = O + (size_t)(row0 + ai * 128 + m * 16) * ldc + col0;
; #pragma unroll
;                 for (int bj = 0; bj < 2; ++bj) { if (u.pn * 256 + bj * 128 + wc * 32 >= 5184) continue;
;                     const f32x4 v0 = acc[ai][bj][m][0], v1 = acc[ai][bj][m][1];
;                     u32x4 w; w.x = cvt_pk_bf16(v0[0], v0[1]); w.y = cvt_pk_bf16(v0[2], v0[3]); w.z = cvt_pk_bf16(v1[0], v1[1]); w.w = cvt_pk_bf16(v1[2], v1[3]);
;                     *(u32x4*)(rowp + bj * 128) = w; } }
;     }
	s_waitcnt lgkmcnt(0)
	s_setprio 1
	s_waitcnt lgkmcnt(0)
	v_mfma_f32_16x16x32_bf16 v[60:63], v[138:141], v[158:161], v[60:63]
	v_mfma_f32_16x16x32_bf16 v[56:59], v[150:153], v[158:161], v[56:59]
	v_mfma_f32_16x16x32_bf16 v[48:51], v[138:141], v[166:169], v[48:51]
	v_mfma_f32_16x16x32_bf16 v[40:43], v[150:153], v[166:169], v[40:43]
	v_mfma_f32_16x16x32_bf16 v[32:35], v[138:141], v[174:177], v[32:35]
	v_mfma_f32_16x16x32_bf16 v[24:27], v[150:153], v[174:177], v[24:27]
	v_mfma_f32_16x16x32_bf16 v[16:19], v[138:141], v[182:185], v[16:19]
	v_mfma_f32_16x16x32_bf16 v[8:11], v[150:153], v[182:185], v[8:11]
	v_mfma_f32_16x16x32_bf16 v[60:63], v[146:149], v[162:165], v[60:63]
	v_mfma_f32_16x16x32_bf16 v[56:59], v[154:157], v[162:165], v[56:59]
	v_mfma_f32_16x16x32_bf16 v[48:51], v[146:149], v[170:173], v[48:51]
	v_mfma_f32_16x16x32_bf16 v[40:43], v[154:157], v[170:173], v[40:43]
	v_mfma_f32_16x16x32_bf16 v[32:35], v[146:149], v[178:181], v[32:35]
	v_mfma_f32_16x16x32_bf16 v[24:27], v[154:157], v[178:181], v[24:27]
	v_mfma_f32_16x16x32_bf16 v[16:19], v[146:149], v[186:189], v[16:19]
	v_mfma_f32_16x16x32_bf16 v[8:11], v[154:157], v[186:189], v[8:11]
	s_setprio 0
	s_barrier
	s_add_u32 s18, s18, 0x40080
	s_addc_u32 s19, s19, 0
	s_add_i32 s20, s20, s27
	v_lshl_add_u64 v[138:139], s[18:19], 0, v[192:193]
	s_mov_b32 m0, s20
	s_nop 0
	global_load_lds_dwordx4 v[138:139], off
	v_lshl_add_u64 v[138:139], s[18:19], 0, v[132:133]
	s_add_i32 m0, s20, 0x2000
	s_nop 0
	global_load_lds_dwordx4 v[138:139], off
	s_waitcnt vmcnt(6)
	s_barrier
	s_setprio 1
	v_mfma_f32_16x16x32_bf16 v[52:55], v[200:203], v[158:161], v[52:55]
	v_mfma_f32_16x16x32_bf16 v[44:47], v[208:211], v[158:161], v[44:47]
	v_mfma_f32_16x16x32_bf16 v[36:39], v[200:203], v[166:169], v[36:39]
	v_mfma_f32_16x16x32_bf16 v[28:31], v[208:211], v[166:169], v[28:31]
	v_mfma_f32_16x16x32_bf16 v[20:23], v[200:203], v[174:177], v[20:23]
	v_mfma_f32_16x16x32_bf16 v[12:15], v[208:211], v[174:177], v[12:15]
	v_mfma_f32_16x16x32_bf16 v[4:7], v[200:203], v[182:185], v[4:7]
	v_mfma_f32_16x16x32_bf16 v[0:3], v[208:211], v[182:185], v[0:3]
	v_mfma_f32_16x16x32_bf16 v[52:55], v[204:207], v[162:165], v[52:55]
	v_mfma_f32_16x16x32_bf16 v[44:47], v[212:215], v[162:165], v[44:47]
	v_mfma_f32_16x16x32_bf16 v[36:39], v[204:207], v[170:173], v[36:39]
	v_mfma_f32_16x16x32_bf16 v[28:31], v[212:215], v[170:173], v[28:31]
	v_mfma_f32_16x16x32_bf16 v[20:23], v[204:207], v[178:181], v[20:23]
	v_mfma_f32_16x16x32_bf16 v[12:15], v[212:215], v[178:181], v[12:15]
	v_mfma_f32_16x16x32_bf16 v[4:7], v[204:207], v[186:189], v[4:7]
	v_mfma_f32_16x16x32_bf16 v[0:3], v[212:215], v[186:189], v[0:3]
	s_setprio 0
	s_add_i32 s42, s42, 2
	s_add_u32 s16, s16, 0x100
	s_addc_u32 s17, s17, 0
	s_add_u32 s40, s40, 0x100
	s_addc_u32 s41, s41, 0
	s_cmp_gt_u32 s42, 13
	s_barrier
	s_cbranch_scc0 .LBB0_696
	s_lshl_b32 s4, s4, 8
	v_lshl_add_u32 v146, s6, 8, v142
	v_or_b32_e32 v138, s4, v144
	s_or_b32 s4, s4, s33
	v_mov_b64_e32 v[140:141], s[0:1]
	v_ashrrev_i32_e32 v139, 31, v138
	v_mad_i64_i32 v[140:141], s[6:7], v146, s78, v[140:141]
	s_cmpk_lt_i32 s4, 0x1440
	s_cselect_b64 s[6:7], -1, 0
	s_cmpk_gt_i32 s4, 0x143f
	v_lshl_add_u64 v[140:141], v[138:139], 1, v[140:141]
	s_cbranch_scc1 .LBB0_699
	v_cvt_pk_bf16_f32 v124, v124, v125
	v_cvt_pk_bf16_f32 v125, v126, v127
	v_cvt_pk_bf16_f32 v126, v120, v121
	v_cvt_pk_bf16_f32 v127, v122, v123
	s_nop 1
	global_store_dwordx4 v[140:141], v[124:127], off
.LBB0_699:
	s_bitset1_b32 s4, 7
	s_cmpk_lt_i32 s4, 0x1440
	s_cselect_b64 s[16:17], -1, 0
	s_cmpk_gt_i32 s4, 0x143f
	s_cbranch_scc1 .LBB0_701
	s_nop 0
	v_cvt_pk_bf16_f32 v116, v116, v117
	s_nop 0
	v_cvt_pk_bf16_f32 v117, v118, v119
	s_nop 0
	v_cvt_pk_bf16_f32 v118, v108, v109
	s_nop 0
	v_cvt_pk_bf16_f32 v119, v110, v111
	s_nop 1
	global_store_dwordx4 v[140:141], v[116:119], off offset:256
.LBB0_701:
	v_or_b32_e32 v110, 16, v146
	v_mov_b64_e32 v[108:109], s[0:1]
	v_mad_i64_i32 v[108:109], s[4:5], v110, s78, v[108:109]
	v_cndmask_b32_e64 v110, 0, 1, s[6:7]
	v_cmp_ne_u32_e64 s[4:5], 1, v110
	s_andn2_b64 vcc, exec, s[6:7]
	v_lshl_add_u64 v[108:109], v[138:139], 1, v[108:109]
	s_cbranch_vccnz .LBB0_703
	s_nop 0
	v_cvt_pk_bf16_f32 v110, v112, v113
	s_nop 0
	v_cvt_pk_bf16_f32 v111, v114, v115
	s_nop 0
	v_cvt_pk_bf16_f32 v112, v104, v105
	s_nop 0
	v_cvt_pk_bf16_f32 v113, v106, v107
	s_nop 1
	global_store_dwordx4 v[108:109], v[110:113], off
.LBB0_703:
	v_cndmask_b32_e64 v104, 0, 1, s[16:17]
	v_cmp_ne_u32_e64 s[6:7], 1, v104
	s_andn2_b64 vcc, exec, s[16:17]
	s_cbranch_vccnz .LBB0_705
	s_nop 0
	v_cvt_pk_bf16_f32 v100, v100, v101
	s_nop 0
	v_cvt_pk_bf16_f32 v101, v102, v103
	s_nop 0
	v_cvt_pk_bf16_f32 v102, v92, v93
	s_nop 0
	v_cvt_pk_bf16_f32 v103, v94, v95
	s_nop 1
	global_store_dwordx4 v[108:109], v[100:103], off offset:256
; __device__ __forceinline__ unsigned cvt_pk_bf16(float lo, float hi) { unsigned r; asm volatile("s_nop 0\n\tv_cvt_pk_bf16_f32 %0, %1, %2\n\ts_nop 1" : "=v"(r) : "v"(lo), "v"(hi)); return r; }
;     __device__ __forceinline__ void operator()(f32x4 (&acc)[2][2][4][2], const Unit& u, int wr, int wc, int fr, int fq) const {
;         const int row0 = u.pm * 256 + wr * 64 + fr, col0 = u.pn * 256 + wc * 32 + 8 * fq;
; #pragma unroll
;         for (int ai = 0; ai < 2; ++ai)
; #pragma unroll
;             for (int m = 0; m < 4; ++m) { bf16_t* rowp = O + (size_t)(row0 + ai * 128 + m * 16) * ldc + col0;
; #pragma unroll
;                 for (int bj = 0; bj < 2; ++bj) { if (u.pn * 256 + bj * 128 + wc * 32 >= 5184) continue;
;                     const f32x4 v0 = acc[ai][bj][m][0], v1 = acc[ai][bj][m][1];
;                     u32x4 w; w.x = cvt_pk_bf16(v0[0], v0[1]); w.y = cvt_pk_bf16(v0[2], v0[3]); w.z = cvt_pk_bf16(v1[0], v1[1]); w.w = cvt_pk_bf16(v1[2], v1[3]);
;                     *(u32x4*)(rowp + bj * 128) = w; } }
;     }
.LBB0_705:
	v_or_b32_e32 v94, 32, v146
	v_mov_b64_e32 v[92:93], s[0:1]
	v_mad_i64_i32 v[92:93], s[16:17], v94, s78, v[92:93]
	s_and_b64 vcc, exec, s[4:5]
	v_lshl_add_u64 v[92:93], v[138:139], 1, v[92:93]
	s_cbranch_vccnz .LBB0_707
	s_nop 0
	v_cvt_pk_bf16_f32 v94, v96, v97
	s_nop 0
	v_cvt_pk_bf16_f32 v95, v98, v99
	s_nop 0
	v_cvt_pk_bf16_f32 v96, v88, v89
	s_nop 0
	v_cvt_pk_bf16_f32 v97, v90, v91
	s_nop 1
	global_store_dwordx4 v[92:93], v[94:97], off
.LBB0_707:
	s_and_b64 vcc, exec, s[6:7]
	s_cbranch_vccnz .LBB0_709
	s_nop 0
	v_cvt_pk_bf16_f32 v84, v84, v85
	s_nop 0
	v_cvt_pk_bf16_f32 v85, v86, v87
	s_nop 0
	v_cvt_pk_bf16_f32 v86, v76, v77
	s_nop 0
	v_cvt_pk_bf16_f32 v87, v78, v79
	s_nop 1
	global_store_dwordx4 v[92:93], v[84:87], off offset:256
.LBB0_709:
	v_or_b32_e32 v78, 48, v146
	v_mov_b64_e32 v[76:77], s[0:1]
	v_mad_i64_i32 v[76:77], s[16:17], v78, s78, v[76:77]
	s_and_b64 vcc, exec, s[4:5]
	v_lshl_add_u64 v[76:77], v[138:139], 1, v[76:77]
	s_cbranch_vccnz .LBB0_711
	s_nop 0
	v_cvt_pk_bf16_f32 v78, v80, v81
	s_nop 0
	v_cvt_pk_bf16_f32 v79, v82, v83
	s_nop 0
	v_cvt_pk_bf16_f32 v80, v72, v73
	s_nop 0
	v_cvt_pk_bf16_f32 v81, v74, v75
	s_nop 1
	global_store_dwordx4 v[76:77], v[78:81], off
.LBB0_711:
	s_and_b64 vcc, exec, s[6:7]
	s_cbranch_vccnz .LBB0_713
	s_nop 0
	v_cvt_pk_bf16_f32 v68, v68, v69
	s_nop 0
	v_cvt_pk_bf16_f32 v69, v70, v71
	s_nop 0
	v_cvt_pk_bf16_f32 v70, v64, v65
	s_nop 0
	v_cvt_pk_bf16_f32 v71, v66, v67
	s_nop 1
	global_store_dwordx4 v[76:77], v[68:71], off offset:256
.LBB0_713:
	v_add_u32_e32 v66, 0x80, v146
	v_mov_b64_e32 v[64:65], s[0:1]
	v_mad_i64_i32 v[64:65], s[16:17], v66, s78, v[64:65]
	s_and_b64 vcc, exec, s[4:5]
	v_lshl_add_u64 v[64:65], v[138:139], 1, v[64:65]
	s_cbranch_vccnz .LBB0_715
	s_nop 0
	v_cvt_pk_bf16_f32 v60, v60, v61
	s_nop 0
	v_cvt_pk_bf16_f32 v61, v62, v63
	s_nop 0
	v_cvt_pk_bf16_f32 v62, v56, v57
	s_nop 0
	v_cvt_pk_bf16_f32 v63, v58, v59
	s_nop 1
	global_store_dwordx4 v[64:65], v[60:63], off
.LBB0_715:
	s_and_b64 vcc, exec, s[6:7]
	s_cbranch_vccnz .LBB0_717
	s_nop 0
	v_cvt_pk_bf16_f32 v52, v52, v53
	s_nop 0
	v_cvt_pk_bf16_f32 v53, v54, v55
	s_nop 0
	v_cvt_pk_bf16_f32 v54, v44, v45
	s_nop 0
	v_cvt_pk_bf16_f32 v55, v46, v47
	s_nop 1
	global_store_dwordx4 v[64:65], v[52:55], off offset:256
.LBB0_717:
	v_add_u32_e32 v46, 0x90, v146
	v_mov_b64_e32 v[44:45], s[0:1]
	v_mad_i64_i32 v[44:45], s[16:17], v46, s78, v[44:45]
	s_and_b64 vcc, exec, s[4:5]
	v_lshl_add_u64 v[44:45], v[138:139], 1, v[44:45]
	s_cbranch_vccnz .LBB0_719
	s_nop 0
	v_cvt_pk_bf16_f32 v46, v48, v49
	s_nop 0
	v_cvt_pk_bf16_f32 v47, v50, v51
	s_nop 0
	v_cvt_pk_bf16_f32 v48, v40, v41
	s_nop 0
	v_cvt_pk_bf16_f32 v49, v42, v43
	s_nop 1
	global_store_dwordx4 v[44:45], v[46:49], off
.LBB0_719:
	s_and_b64 vcc, exec, s[6:7]
	s_cbranch_vccnz .LBB0_721
	s_nop 0
	v_cvt_pk_bf16_f32 v36, v36, v37
	s_nop 0
	v_cvt_pk_bf16_f32 v37, v38, v39
	s_nop 0
	v_cvt_pk_bf16_f32 v38, v28, v29
	s_nop 0
	v_cvt_pk_bf16_f32 v39, v30, v31
	s_nop 1
	global_store_dwordx4 v[44:45], v[36:39], off offset:256
.LBB0_721:
	v_add_u32_e32 v30, 0xa0, v146
	v_mov_b64_e32 v[28:29], s[0:1]
	v_mad_i64_i32 v[28:29], s[16:17], v30, s78, v[28:29]
	s_and_b64 vcc, exec, s[4:5]
	v_lshl_add_u64 v[28:29], v[138:139], 1, v[28:29]
	s_cbranch_vccnz .LBB0_723
	s_nop 0
	v_cvt_pk_bf16_f32 v30, v32, v33
	s_nop 0
	v_cvt_pk_bf16_f32 v31, v34, v35
	s_nop 0
	v_cvt_pk_bf16_f32 v32, v24, v25
	s_nop 0
	v_cvt_pk_bf16_f32 v33, v26, v27
	s_nop 1
	global_store_dwordx4 v[28:29], v[30:33], off
.LBB0_723:
	s_and_b64 vcc, exec, s[6:7]
	s_cbranch_vccnz .LBB0_725
	s_nop 0
	v_cvt_pk_bf16_f32 v20, v20, v21
	s_nop 0
	v_cvt_pk_bf16_f32 v21, v22, v23
	s_nop 0
	v_cvt_pk_bf16_f32 v22, v12, v13
	s_nop 0
	v_cvt_pk_bf16_f32 v23, v14, v15
	s_nop 1
	global_store_dwordx4 v[28:29], v[20:23], off offset:256
.LBB0_725:
	v_add_u32_e32 v14, 0xb0, v146
	v_mov_b64_e32 v[12:13], s[0:1]
	v_mad_i64_i32 v[12:13], s[16:17], v14, s78, v[12:13]
	s_and_b64 vcc, exec, s[4:5]
	v_lshl_add_u64 v[12:13], v[138:139], 1, v[12:13]
	s_cbranch_vccnz .LBB0_727
	s_nop 0
	v_cvt_pk_bf16_f32 v14, v16, v17
	s_nop 0
	v_cvt_pk_bf16_f32 v15, v18, v19
	s_nop 0
	v_cvt_pk_bf16_f32 v16, v8, v9
	s_nop 0
	v_cvt_pk_bf16_f32 v17, v10, v11
	s_nop 1
	global_store_dwordx4 v[12:13], v[14:17], off
.LBB0_727:
	s_and_b64 vcc, exec, s[6:7]
	s_cbranch_vccnz .LBB0_692
	s_nop 0
	v_cvt_pk_bf16_f32 v4, v4, v5
	s_nop 0
	v_cvt_pk_bf16_f32 v5, v6, v7
	s_nop 0
	v_cvt_pk_bf16_f32 v6, v0, v1
	s_nop 0
	v_cvt_pk_bf16_f32 v7, v2, v3
	s_nop 1
	global_store_dwordx4 v[12:13], v[4:7], off offset:256
	s_branch .LBB0_692

; #define LAS __attribute__((address_space(3)))
; __device__ __forceinline__ unsigned xb_add(unsigned* p, unsigned v) { return __hip_atomic_fetch_add(p, v, __ATOMIC_RELAXED, __HIP_MEMORY_SCOPE_AGENT); }
; __device__ __forceinline__ unsigned xb_xcc_id() { return (unsigned)__builtin_amdgcn_s_getreg((3 << 11) | 20) & 0xFu; }
; __global__ void __launch_bounds__(512) mega(Params p_arg) {
;     extern __shared__ __attribute__((aligned(16))) unsigned char lds_raw[];
;     LAS unsigned char* lds = (LAS unsigned char*)lds_raw;
;     if (threadIdx.x == 0) { volatile LAS unsigned* st = (volatile LAS unsigned*)(lds + ST_OFF); st[0] = 0u; st[1] = 0u; (void)xb_add(&((unsigned*)(p_arg.ws + OFF_BAR))[XB_XCNT(xb_xcc_id())], 1u); }
;     const int wave0 = __builtin_amdgcn_readfirstlane(threadIdx.x >> 6);
	.amdhsa_kernel _Z4mega6Params
		.amdhsa_group_segment_fixed_size 0
		.amdhsa_private_segment_fixed_size 0
		.amdhsa_kernarg_size 528
		.amdhsa_user_sgpr_count 2
		.amdhsa_user_sgpr_dispatch_ptr 0
		.amdhsa_user_sgpr_queue_ptr 0
		.amdhsa_user_sgpr_kernarg_segment_ptr 1
		.amdhsa_user_sgpr_dispatch_id 0
		.amdhsa_user_sgpr_kernarg_preload_length 0
		.amdhsa_user_sgpr_kernarg_preload_offset 0
		.amdhsa_user_sgpr_private_segment_size 0
		.amdhsa_uses_dynamic_stack 0
		.amdhsa_enable_private_segment 0
		.amdhsa_system_sgpr_workgroup_id_x 1
		.amdhsa_system_sgpr_workgroup_id_y 0
		.amdhsa_system_sgpr_workgroup_id_z 0
		.amdhsa_system_sgpr_workgroup_info 0
		.amdhsa_system_vgpr_workitem_id 2
		.amdhsa_next_free_vgpr 256
		.amdhsa_next_free_sgpr 102
		.amdhsa_accum_offset 256
		.amdhsa_reserve_vcc 1
		.amdhsa_float_round_mode_32 0
		.amdhsa_float_round_mode_16_64 0
		.amdhsa_float_denorm_mode_32 3
		.amdhsa_float_denorm_mode_16_64 3
		.amdhsa_dx10_clamp 1
		.amdhsa_ieee_mode 1
		.amdhsa_fp16_overflow 0
		.amdhsa_tg_split 0
		.amdhsa_exception_fp_ieee_invalid_op 0
		.amdhsa_exception_fp_denorm_src 0
		.amdhsa_exception_fp_ieee_div_zero 0
		.amdhsa_exception_fp_ieee_overflow 0
		.amdhsa_exception_fp_ieee_underflow 0
		.amdhsa_exception_fp_ieee_inexact 0
		.amdhsa_exception_int_div_zero 0
	.end_amdhsa_kernel

; #define LAS __attribute__((address_space(3)))
; __device__ __forceinline__ unsigned xb_add(unsigned* p, unsigned v) { return __hip_atomic_fetch_add(p, v, __ATOMIC_RELAXED, __HIP_MEMORY_SCOPE_AGENT); }
; __device__ __forceinline__ unsigned xb_xcc_id() { return (unsigned)__builtin_amdgcn_s_getreg((3 << 11) | 20) & 0xFu; }
; __global__ void __launch_bounds__(512) mega(Params p_arg) {
;     extern __shared__ __attribute__((aligned(16))) unsigned char lds_raw[];
;     LAS unsigned char* lds = (LAS unsigned char*)lds_raw;
;     if (threadIdx.x == 0) { volatile LAS unsigned* st = (volatile LAS unsigned*)(lds + ST_OFF); st[0] = 0u; st[1] = 0u; (void)xb_add(&((unsigned*)(p_arg.ws + OFF_BAR))[XB_XCNT(xb_xcc_id())], 1u); }
;     const int wave0 = __builtin_amdgcn_readfirstlane(threadIdx.x >> 6);
amdhsa.kernels:
  - .agpr_count:     0
    .args:
      - .offset:         0
        .size:           272
        .value_kind:     by_value
      - .offset:         272
        .size:           4
        .value_kind:     hidden_block_count_x
      - .offset:         276
        .size:           4
        .value_kind:     hidden_block_count_y
      - .offset:         280
        .size:           4
        .value_kind:     hidden_block_count_z
      - .offset:         284
        .size:           2
        .value_kind:     hidden_group_size_x
      - .offset:         286
        .size:           2
        .value_kind:     hidden_group_size_y
      - .offset:         288
        .size:           2
        .value_kind:     hidden_group_size_z
      - .offset:         290
        .size:           2
        .value_kind:     hidden_remainder_x
      - .offset:         292
        .size:           2
        .value_kind:     hidden_remainder_y
      - .offset:         294
        .size:           2
        .value_kind:     hidden_remainder_z
      - .offset:         312
        .size:           8
        .value_kind:     hidden_global_offset_x
      - .offset:         320
        .size:           8
        .value_kind:     hidden_global_offset_y
      - .offset:         328
        .size:           8
        .value_kind:     hidden_global_offset_z
      - .offset:         336
        .size:           2
        .value_kind:     hidden_grid_dims
      - .offset:         360
        .size:           8
        .value_kind:     hidden_multigrid_sync_arg
      - .offset:         392
        .size:           4
        .value_kind:     hidden_dynamic_lds_size
    .group_segment_fixed_size: 0
    .kernarg_segment_align: 8
    .kernarg_segment_size: 528
    .language:       OpenCL C
    .language_version:
      - 2
      - 0
    .max_flat_workgroup_size: 512
    .name:           _Z4mega6Params
    .private_segment_fixed_size: 0
    .sgpr_count:     108
    .sgpr_spill_count: 71
    .symbol:         _Z4mega6Params.kd
    .uniform_work_group_size: 1
    .uses_dynamic_stack: false
    .vgpr_count:     256
    .vgpr_spill_count: 0
    .wavefront_size: 64
